# PEER v-phase rewritten by hand: slice-outer token groups, continuous LDS-DMA stream, partials in registers, trickled final norm
# speedup vs baseline: 1.0081x; 1.0081x over previous
; #define LAS __attribute__((address_space(3)))
; __device__ __forceinline__ void peer_v_tokens(int j, const LAS unsigned short* EL, const LAS unsigned char* AL  , const LAS float* ASC  , const LAS int* SAL  , ...
;     ...
;     const int BUF[3] = {vslot(3 * wave), vslot(3 * wave + 1), vslot(3 * wave + 2)};
;     const int g = lane >> 3, j8 = lane & 7, s16 = lane & 15, grp = lane >> 4;
;     *(LAS unsigned long long*)(ldsb + BUF[0] + 8 * s16) = 0xFEDCBA9876543210ull;
;     CFENCE();
;     const v2i cal = TR4(ldsb + BUF[0] + 8 * s16);
;     const int pc = cal.x & 15;
;     asm volatile("s_waitcnt lgkmcnt(0)" ::: "memory");
;     const unsigned cx0 = 16u * (unsigned)(j8 ^ (g >> 1)), cx1 = 16u * (unsigned)(j8 ^ (4 + (g >> 1)));
;     const int fr = (4 * (s16 >> 3) + ((s16 & 7) >> 1)) & 7;
;     int roff[4];
; #pragma unroll
;     for (int r = 0; r < 4; ++r) roff[r] = 128 * s16 + 16 * ((((grp >> 1) + 2 * r)) ^ fr) + 8 * (grp & 1);
;     ...
; #pragma unroll 1
;     for (int it = 0; it < 8; ++it) {
;         const int tl = it * 8 + wave, t = j * 64 + tl;
;         unsigned E[8];
;         { const LAS v4u* ep = (const LAS v4u*)(EL + tl * 128 + 16 * g); const v4u e0 = ep[0], e1 = ep[1];
;           E[0] = e0.x; E[1] = e0.y; E[2] = e0.z; E[3] = e0.w; E[4] = e1.x; E[5] = e1.y; E[6] = e1.z; E[7] = e1.w; }
;         uint2 hv[4]; float4 gv[4];
;         { unsigned ho = (unsigned)t * (D / 4) + (unsigned)lane; asm volatile("" : "+v"(ho)); const uint2* hp = (const uint2*)HB + ho; const float4* gp = (const float4*)fng + lane;
; #pragma unroll
;           for (int jq = 0; jq < 4; ++jq) { hv[jq] = hp[64 * jq]; gv[jq] = gp[64 * jq]; } }
;         VDMA(0, 0); VDMA(1, 1);
; #pragma unroll
;         for (int m = 0; m < 2; ++m) {
;             const int idx = lane + 64 * m, tau = idx >> 4, sr = idx & 15, k = 16 * (sr & 7) + 2 * tau + (sr >> 3);
;             const int aq = (int)*(const LAS signed char*)(AL + tl * 128 + k); const int tq = aq + 8;
;             const unsigned lo = (((unsigned)tq & 15u) ^ 8u) * 0x11111111u, hi = ((unsigned)(tq >> 4) & 15u) * 0x11111111u;
;             typedef unsigned u2v __attribute__((ext_vector_type(2)));
;             u2v l2; l2.x = lo; l2.y = lo; u2v h2; h2.x = hi; h2.y = hi;
;             *(LAS u2v*)(ATL + 8 * idx) = l2; *(LAS u2v*)(ATL + 1024 + 8 * idx) = h2;
;         }
;         const float asc = ASC[tl]; const int sa = SAL[tl];
.LBB0_691:
	s_or_b64 exec, exec, s[10:11]
	v_mov_b32_e32 v18, v1
	s_waitcnt lgkmcnt(0)
	s_barrier
	v_readlane_b32 s70, v235, 50
	v_and_b32_e32 v19, 15, v18
	v_lshlrev_b32_e32 v58, 3, v19
	v_add_u32_e32 v20, s60, v58
	ds_write_b64 v20, v[84:85]
	v_lshrrev_b32_e32 v23, 1, v18
	v_ashrrev_i32_e32 v24, 5, v18
	v_and_b32_e32 v25, 8, v23
	ds_read_b64_tr_b4 v[20:21], v20
	v_lshl_or_b32 v19, v19, 7, v25
	v_bitop3_b32 v25, v23, v24, 7 bitop3:0x6c
	v_lshl_add_u32 v59, v25, 4, v19
	v_add_u32_e32 v25, 2, v24
	v_bitop3_b32 v25, v25, v23, 7 bitop3:0x78
	v_lshl_add_u32 v60, v25, 4, v19
	v_add_u32_e32 v25, 4, v24
	v_add_u32_e32 v24, 6, v24
	s_waitcnt lgkmcnt(0)
	v_ashrrev_i32_e32 v21, 4, v18
	v_bitop3_b32 v25, v25, v23, 7 bitop3:0x78
	v_bitop3_b32 v23, v24, v23, 7 bitop3:0x78
	v_bitop3_b32 v22, v18, v21, 7 bitop3:0x6c
	v_add_u32_e32 v21, 4, v21
	v_lshl_add_u32 v61, v25, 4, v19
	v_lshl_add_u32 v62, v23, 4, v19
	v_and_b32_e32 v19, 15, v20
	v_bitop3_b32 v21, v21, v18, 7 bitop3:0x78
	v_lshlrev_b32_e32 v63, 4, v22
	v_lshlrev_b32_e32 v22, 1, v19
	v_ashrrev_i32_e32 v19, 31, v18
	v_lshlrev_b32_e32 v64, 4, v21
	v_lshlrev_b64 v[20:21], 4, v[18:19]
	v_and_b32_e32 v25, 0x7ffffff0, v18
	v_lshl_add_u64 v[34:35], s[86:87], 0, v[20:21]
	v_lshlrev_b32_e32 v19, 4, v18
	v_lshlrev_b32_e32 v25, 1, v25
	v_lshl_add_u64 v[36:37], s[88:89], 0, v[20:21]
	v_add_u32_e32 v21, 64, v18
	s_waitcnt lgkmcnt(0)
	v_and_b32_e32 v19, 0x70, v19
	v_add3_u32 v65, s58, v22, v25
	v_ashrrev_i32_e32 v20, 3, v18
	v_ashrrev_i32_e32 v22, 3, v21
	v_lshrrev_b32_e32 v23, 3, v18
	v_bfe_u32 v24, v18, 3, 1
	v_and_b32_e32 v20, -2, v20
	v_and_b32_e32 v22, -2, v22
	v_lshlrev_b32_e32 v21, 3, v21
	v_add_u32_e32 v19, s72, v19
	v_lshlrev_b32_e32 v66, 3, v18
	v_add_u32_e32 v67, 0x200000, v63
	v_add_u32_e32 v68, 0x200000, v64
	v_add_u32_e32 v69, 0x400000, v63
	v_add_u32_e32 v70, 0x400000, v64
	v_add_u32_e32 v71, 0x600000, v63
	v_add_u32_e32 v72, 0x600000, v64
	v_add3_u32 v73, v19, v22, v24
	v_add3_u32 v74, v19, v20, v24
	v_lshl_add_u32 v75, v23, 5, s65
	v_add_u32_e32 v76, s73, v18
	s_mov_b32 s12, 0
	v_add_u32_e32 v77, s59, v21
	s_mov_b32 s13, s67
	v_readlane_b32 s71, v235, 51
	s_mov_b32 s76, s60
	s_add_i32 s77, s60, 0x800
	s_mov_b32 s78, s61
	s_add_i32 s79, s61, 0x800
	s_mov_b32 s98, s62
	s_add_i32 s99, s62, 0x800
	v_add_u32_e32 v159, s59, v66
	v_add_u32_e32 v160, s59, v58
	v_add_u32_e32 v154, s58, v66
	v_add_u32_e32 v227, 0x12000, v75
	v_lshlrev_b32_e32 v138, 1, v66
	v_add_u32_e32 v155, 0x11200, v138
	v_add_u32_e32 v156, 0x27400, v138
	global_load_dwordx4 v[210:213], v[34:35], off
	global_load_dwordx4 v[214:217], v[34:35], off offset:1024
	global_load_dwordx4 v[218:221], v[34:35], off offset:2048
	global_load_dwordx4 v[222:225], v[34:35], off offset:3072
	ds_read_b128 v[18:21], v227
	ds_read_b128 v[22:25], v227 offset:16
	v_mov_b32_e32 v138, v74
	ds_read_u8 v139, v138
	v_mov_b32_e32 v141, v73
	ds_read_u8 v140, v141
	v_mov_b32_e32 v150, v63
	v_mov_b32_e32 v151, v64
	s_waitcnt lgkmcnt(0)
	v_and_b32_e32 v78, 0xffff, v18
	v_lshrrev_b32_e32 v79, 16, v18
	v_lshl_add_u32 v78, v78, 7, v150
	v_lshl_add_u32 v79, v79, 7, v151
	s_mov_b32 m0, s76
	s_add_i32 s43, s76, 0x400
	global_load_lds_dwordx4 v78, s[50:51]
	s_mov_b32 m0, s43
	s_nop 0
	global_load_lds_dwordx4 v79, s[50:51]
	v_and_b32_e32 v78, 0xffff, v19
	v_lshrrev_b32_e32 v79, 16, v19
	v_lshl_add_u32 v78, v78, 7, v150
	v_lshl_add_u32 v79, v79, 7, v151
	s_mov_b32 m0, s77
	s_add_i32 s43, s77, 0x400
	global_load_lds_dwordx4 v78, s[50:51]
	s_mov_b32 m0, s43
	s_nop 0
	global_load_lds_dwordx4 v79, s[50:51]
	v_and_b32_e32 v78, 0xffff, v20
	v_lshrrev_b32_e32 v79, 16, v20
	v_lshl_add_u32 v78, v78, 7, v150
	v_lshl_add_u32 v79, v79, 7, v151
	s_mov_b32 m0, s78
	s_add_i32 s43, s78, 0x400
	global_load_lds_dwordx4 v78, s[50:51]
	s_mov_b32 m0, s43
	s_nop 0
	global_load_lds_dwordx4 v79, s[50:51]
	v_and_b32_e32 v78, 0xffff, v21
	v_lshrrev_b32_e32 v79, 16, v21
	v_lshl_add_u32 v78, v78, 7, v150
	v_lshl_add_u32 v79, v79, 7, v151
	s_mov_b32 m0, s79
	s_add_i32 s43, s79, 0x400
	global_load_lds_dwordx4 v78, s[50:51]
	s_mov_b32 m0, s43
	s_nop 0
	global_load_lds_dwordx4 v79, s[50:51]
	v_and_b32_e32 v78, 0xffff, v22
	v_lshrrev_b32_e32 v79, 16, v22
	v_lshl_add_u32 v78, v78, 7, v150
	v_lshl_add_u32 v79, v79, 7, v151
	s_mov_b32 m0, s98
	s_add_i32 s43, s98, 0x400
	global_load_lds_dwordx4 v78, s[50:51]
	s_mov_b32 m0, s43
	s_nop 0
	global_load_lds_dwordx4 v79, s[50:51]
	v_add_u32_e32 v143, 8, v139
	v_and_b32_e32 v142, 15, v143
	v_xor_b32_e32 v142, 8, v142
	v_bfe_u32 v144, v143, 4, 4
	v_mul_lo_u32 v142, v142, s92
	v_mul_lo_u32 v144, v144, s92
	v_mov_b32_e32 v143, v142
	v_mov_b32_e32 v145, v144
	ds_write2st64_b64 v159, v[142:143], v[144:145] offset1:2
	s_waitcnt vmcnt(10)
	ds_write_b128 v155, v[210:213]
	ds_write_b128 v155, v[214:217] offset:1024
	ds_write_b128 v156, v[218:221]
	ds_write_b128 v156, v[222:225] offset:1024
	s_waitcnt vmcnt(8)
	v_add_u32_e32 v54, s76, v59
	v_add_u32_e32 v55, s76, v60
	v_add_u32_e32 v56, s76, v61
	v_add_u32_e32 v57, s76, v62
	ds_read_b64_tr_b4 v[46:47], v160
	ds_read_b64_tr_b4 v[48:49], v160 offset:1024
	ds_read_b64_tr_b4 v[122:123], v54
	ds_read_b64_tr_b4 v[124:125], v55
	ds_read_b64_tr_b4 v[126:127], v56
	ds_read_b64_tr_b4 v[128:129], v57
	v_add_u32_e32 v147, 8, v140
	v_and_b32_e32 v146, 15, v147
	v_xor_b32_e32 v146, 8, v146
	v_bfe_u32 v148, v147, 4, 4
	v_mul_lo_u32 v146, v146, s92
	v_mul_lo_u32 v148, v148, s92
	v_mov_b32_e32 v147, v146
	v_mov_b32_e32 v149, v148
	ds_write2st64_b64 v77, v[146:147], v[148:149] offset1:2
	v_add_u32_e32 v138, 0x400, v74
	ds_read_u8 v139, v138
	v_add_u32_e32 v141, 0x400, v73
	ds_read_u8 v140, v141
	s_mov_b32 s43, s67
	v_mov_b32_e32 v138, s43
	ds_read2st64_b32 v[228:229], v138 offset1:1
	ds_read_b128 v[26:29], v227 offset:2048
	ds_read_b128 v[30:33], v227 offset:2064
	v_mov_b32_e32 v38, 0
	v_mov_b32_e32 v39, 0
	v_mov_b32_e32 v40, 0
	v_mov_b32_e32 v41, 0
	v_mov_b32_e32 v42, 0
	v_mov_b32_e32 v43, 0
	v_mov_b32_e32 v44, 0
	v_mov_b32_e32 v45, 0
	v_and_b32_e32 v78, 0xffff, v23
	v_lshrrev_b32_e32 v79, 16, v23
	v_lshl_add_u32 v78, v78, 7, v150
	v_lshl_add_u32 v79, v79, 7, v151
	s_mov_b32 m0, s99
	s_add_i32 s43, s99, 0x400
	global_load_lds_dwordx4 v78, s[50:51]
	s_mov_b32 m0, s43
	s_nop 0
	global_load_lds_dwordx4 v79, s[50:51]
	s_waitcnt vmcnt(8)
; #define TR4(p_) __builtin_amdgcn_ds_read_tr4_b64_v2i32((LAS v2i*)(p_))
; #define VDMA(st_, k_) do { _Pragma("unroll") for (int i_ = 0; i_ < 4; ++i_) { \
;         const unsigned off_ = (unsigned)((st_) >> 2) * (16384u * 128u) + (PE_ID(E, 4 * ((st_) & 3) + i_) << 7) + ((i_ & 1) ? cx1 : cx0); \
;         __builtin_amdgcn_global_load_lds((const unsigned*)(V4 + off_), (LAS unsigned*)(ldsb + BUF[k_] + 1024 * i_), 16, 0, 0); } } while (0)
; __device__ __forceinline__ void peer_v_tokens(int j, const LAS unsigned short* EL, const LAS unsigned char* AL  , const LAS float* ASC  , const LAS int* SAL  , ...
;     ...
;         for (int st = 0; st < 16; ++st) {
;             const int p = st >> 2, q = st & 3;
;             if (st < 14) VDMA(st + 2, (st + 2) % 3);
;             if (st < 14) asm volatile("s_waitcnt vmcnt(8)" ::: "memory");
;             else if (st == 14) asm volatile("s_waitcnt vmcnt(4)" ::: "memory");
;             else asm volatile("s_waitcnt vmcnt(0)" ::: "memory");
;             if (q == 0) {
; #pragma unroll
;                 for (int r = 0; r < 4; ++r) { accH[r] = 0; accL[r] = 0; } }
; #pragma unroll
;             for (int tp = 0; tp < 2; ++tp) {
;                 const v2i ao = TR4(ATL + (2 * q + tp) * 128 + 8 * s16), ah = TR4(ATL + 1024 + (2 * q + tp) * 128 + 8 * s16);
; #pragma unroll
;                 for (int r = 0; r < 4; ++r) {
;                     const v2i d = TR4(ldsb + BUF[st % 3] + 2048 * tp + roff[r]);
;                     accH[r] = __builtin_amdgcn_sdot8(d.x, ah.x, accH[r], false); accH[r] = __builtin_amdgcn_sdot8(d.y, ah.y, accH[r], false);
;                     accL[r] = __builtin_amdgcn_sdot8(d.x, ao.x, accL[r], false); accL[r] = __builtin_amdgcn_sdot8(d.y, ao.y, accL[r], false);
;                 }
;             }
	v_add_u32_e32 v54, s77, v59
	v_add_u32_e32 v55, s77, v60
	v_add_u32_e32 v56, s77, v61
	v_add_u32_e32 v57, s77, v62
	ds_read_b64_tr_b4 v[50:51], v160 offset:128
	ds_read_b64_tr_b4 v[52:53], v160 offset:1152
	ds_read_b64_tr_b4 v[130:131], v54
	ds_read_b64_tr_b4 v[132:133], v55
	ds_read_b64_tr_b4 v[134:135], v56
	ds_read_b64_tr_b4 v[136:137], v57
	s_waitcnt lgkmcnt(12)
	v_dot8c_i32_i4_e32 v38, v122, v48
	v_dot8c_i32_i4_e32 v39, v122, v46
	v_dot8c_i32_i4_e32 v40, v124, v48
	v_dot8c_i32_i4_e32 v41, v124, v46
	v_dot8c_i32_i4_e32 v42, v126, v48
	v_dot8c_i32_i4_e32 v43, v126, v46
	v_dot8c_i32_i4_e32 v44, v128, v48
	v_dot8c_i32_i4_e32 v45, v128, v46
	v_dot8c_i32_i4_e32 v38, v123, v49
	v_dot8c_i32_i4_e32 v39, v123, v47
	v_dot8c_i32_i4_e32 v40, v125, v49
	v_dot8c_i32_i4_e32 v41, v125, v47
	v_dot8c_i32_i4_e32 v42, v127, v49
	v_dot8c_i32_i4_e32 v43, v127, v47
	v_dot8c_i32_i4_e32 v44, v129, v49
	v_dot8c_i32_i4_e32 v45, v129, v47
	v_and_b32_e32 v78, 0xffff, v24
	v_lshrrev_b32_e32 v79, 16, v24
	v_lshl_add_u32 v78, v78, 7, v150
	v_lshl_add_u32 v79, v79, 7, v151
	s_mov_b32 m0, s76
	s_add_i32 s43, s76, 0x400
	global_load_lds_dwordx4 v78, s[50:51]
	s_mov_b32 m0, s43
	s_nop 0
	global_load_lds_dwordx4 v79, s[50:51]
	s_waitcnt vmcnt(8)
	v_add_u32_e32 v54, s78, v59
	v_add_u32_e32 v55, s78, v60
	v_add_u32_e32 v56, s78, v61
	v_add_u32_e32 v57, s78, v62
	ds_read_b64_tr_b4 v[46:47], v160 offset:256
	ds_read_b64_tr_b4 v[48:49], v160 offset:1280
	ds_read_b64_tr_b4 v[122:123], v54
	ds_read_b64_tr_b4 v[124:125], v55
	ds_read_b64_tr_b4 v[126:127], v56
	ds_read_b64_tr_b4 v[128:129], v57
	s_waitcnt lgkmcnt(6)
	v_dot8c_i32_i4_e32 v38, v130, v52
	v_dot8c_i32_i4_e32 v39, v130, v50
	v_dot8c_i32_i4_e32 v40, v132, v52
	v_dot8c_i32_i4_e32 v41, v132, v50
	v_dot8c_i32_i4_e32 v42, v134, v52
	v_dot8c_i32_i4_e32 v43, v134, v50
	v_dot8c_i32_i4_e32 v44, v136, v52
	v_dot8c_i32_i4_e32 v45, v136, v50
	v_dot8c_i32_i4_e32 v38, v131, v53
	v_dot8c_i32_i4_e32 v39, v131, v51
	v_dot8c_i32_i4_e32 v40, v133, v53
	v_dot8c_i32_i4_e32 v41, v133, v51
	v_dot8c_i32_i4_e32 v42, v135, v53
	v_dot8c_i32_i4_e32 v43, v135, v51
	v_dot8c_i32_i4_e32 v44, v137, v53
	v_dot8c_i32_i4_e32 v45, v137, v51
	v_and_b32_e32 v78, 0xffff, v25
	v_lshrrev_b32_e32 v79, 16, v25
	v_lshl_add_u32 v78, v78, 7, v150
	v_lshl_add_u32 v79, v79, 7, v151
	s_mov_b32 m0, s77
	s_add_i32 s43, s77, 0x400
	global_load_lds_dwordx4 v78, s[50:51]
	s_mov_b32 m0, s43
	s_nop 0
	global_load_lds_dwordx4 v79, s[50:51]
	s_waitcnt vmcnt(8)
	v_add_u32_e32 v54, s79, v59
	v_add_u32_e32 v55, s79, v60
	v_add_u32_e32 v56, s79, v61
	v_add_u32_e32 v57, s79, v62
	ds_read_b64_tr_b4 v[50:51], v160 offset:384
	ds_read_b64_tr_b4 v[52:53], v160 offset:1408
	ds_read_b64_tr_b4 v[130:131], v54
	ds_read_b64_tr_b4 v[132:133], v55
	ds_read_b64_tr_b4 v[134:135], v56
	ds_read_b64_tr_b4 v[136:137], v57
	s_waitcnt lgkmcnt(6)
	v_dot8c_i32_i4_e32 v38, v122, v48
	v_dot8c_i32_i4_e32 v39, v122, v46
	v_dot8c_i32_i4_e32 v40, v124, v48
	v_dot8c_i32_i4_e32 v41, v124, v46
	v_dot8c_i32_i4_e32 v42, v126, v48
	v_dot8c_i32_i4_e32 v43, v126, v46
	v_dot8c_i32_i4_e32 v44, v128, v48
	v_dot8c_i32_i4_e32 v45, v128, v46
	v_dot8c_i32_i4_e32 v38, v123, v49
	v_dot8c_i32_i4_e32 v39, v123, v47
	v_dot8c_i32_i4_e32 v40, v125, v49
	v_dot8c_i32_i4_e32 v41, v125, v47
	v_dot8c_i32_i4_e32 v42, v127, v49
	v_dot8c_i32_i4_e32 v43, v127, v47
	v_dot8c_i32_i4_e32 v44, v129, v49
	v_dot8c_i32_i4_e32 v45, v129, v47
	s_waitcnt lgkmcnt(15)
	v_and_b32_e32 v78, 0xffff, v26
	v_lshrrev_b32_e32 v79, 16, v26
	v_lshl_add_u32 v78, v78, 7, v150
	v_lshl_add_u32 v79, v79, 7, v151
	s_mov_b32 m0, s78
	s_add_i32 s43, s78, 0x400
	global_load_lds_dwordx4 v78, s[50:51]
	s_mov_b32 m0, s43
	s_nop 0
	global_load_lds_dwordx4 v79, s[50:51]
	s_waitcnt vmcnt(8)
	v_add_u32_e32 v54, s98, v59
	v_add_u32_e32 v55, s98, v60
	v_add_u32_e32 v56, s98, v61
	v_add_u32_e32 v57, s98, v62
	ds_read_b64_tr_b4 v[46:47], v160 offset:512
	ds_read_b64_tr_b4 v[48:49], v160 offset:1536
	ds_read_b64_tr_b4 v[122:123], v54
	ds_read_b64_tr_b4 v[124:125], v55
	ds_read_b64_tr_b4 v[126:127], v56
	ds_read_b64_tr_b4 v[128:129], v57
	s_waitcnt lgkmcnt(6)
	v_dot8c_i32_i4_e32 v38, v130, v52
	v_dot8c_i32_i4_e32 v39, v130, v50
	v_dot8c_i32_i4_e32 v40, v132, v52
	v_dot8c_i32_i4_e32 v41, v132, v50
	v_dot8c_i32_i4_e32 v42, v134, v52
	v_dot8c_i32_i4_e32 v43, v134, v50
	v_dot8c_i32_i4_e32 v44, v136, v52
	v_dot8c_i32_i4_e32 v45, v136, v50
	v_dot8c_i32_i4_e32 v38, v131, v53
	v_dot8c_i32_i4_e32 v39, v131, v51
	v_dot8c_i32_i4_e32 v40, v133, v53
	v_dot8c_i32_i4_e32 v41, v133, v51
	v_dot8c_i32_i4_e32 v42, v135, v53
	v_dot8c_i32_i4_e32 v43, v135, v51
	v_dot8c_i32_i4_e32 v44, v137, v53
	v_dot8c_i32_i4_e32 v45, v137, v51
	v_and_b32_e32 v78, 0xffff, v27
	v_lshrrev_b32_e32 v79, 16, v27
	v_lshl_add_u32 v78, v78, 7, v150
	v_lshl_add_u32 v79, v79, 7, v151
	s_mov_b32 m0, s79
	s_add_i32 s43, s79, 0x400
	global_load_lds_dwordx4 v78, s[50:51]
	s_mov_b32 m0, s43
	s_nop 0
	global_load_lds_dwordx4 v79, s[50:51]
	s_waitcnt vmcnt(8)
	v_add_u32_e32 v54, s99, v59
	v_add_u32_e32 v55, s99, v60
	v_add_u32_e32 v56, s99, v61
	v_add_u32_e32 v57, s99, v62
	ds_read_b64_tr_b4 v[50:51], v160 offset:640
	ds_read_b64_tr_b4 v[52:53], v160 offset:1664
	ds_read_b64_tr_b4 v[130:131], v54
	ds_read_b64_tr_b4 v[132:133], v55
	ds_read_b64_tr_b4 v[134:135], v56
	ds_read_b64_tr_b4 v[136:137], v57
	s_waitcnt lgkmcnt(6)
	v_dot8c_i32_i4_e32 v38, v122, v48
	v_dot8c_i32_i4_e32 v39, v122, v46
	v_dot8c_i32_i4_e32 v40, v124, v48
	v_dot8c_i32_i4_e32 v41, v124, v46
	v_dot8c_i32_i4_e32 v42, v126, v48
	v_dot8c_i32_i4_e32 v43, v126, v46
	v_dot8c_i32_i4_e32 v44, v128, v48
	v_dot8c_i32_i4_e32 v45, v128, v46
	v_dot8c_i32_i4_e32 v38, v123, v49
	v_dot8c_i32_i4_e32 v39, v123, v47
	v_dot8c_i32_i4_e32 v40, v125, v49
	v_dot8c_i32_i4_e32 v41, v125, v47
	v_dot8c_i32_i4_e32 v42, v127, v49
	v_dot8c_i32_i4_e32 v43, v127, v47
	v_dot8c_i32_i4_e32 v44, v129, v49
	v_dot8c_i32_i4_e32 v45, v129, v47
	s_waitcnt lgkmcnt(15)
; __device__ __forceinline__ void peer_v_tokens(int j, const LAS unsigned short* EL, const LAS unsigned char* AL  , const LAS float* ASC  , const LAS int* SAL  , ...
;     ...
; #pragma unroll
;         for (int m = 0; m < 2; ++m) {
;             const int idx = lane + 64 * m, tau = idx >> 4, sr = idx & 15, k = 16 * (sr & 7) + 2 * tau + (sr >> 3);
;             const int aq = (int)*(const LAS signed char*)(AL + tl * 128 + k); const int tq = aq + 8;
;             const unsigned lo = (((unsigned)tq & 15u) ^ 8u) * 0x11111111u, hi = ((unsigned)(tq >> 4) & 15u) * 0x11111111u;
;             typedef unsigned u2v __attribute__((ext_vector_type(2)));
;             u2v l2; l2.x = lo; l2.y = lo; u2v h2; h2.x = hi; h2.y = hi;
;             *(LAS u2v*)(ATL + 8 * idx) = l2; *(LAS u2v*)(ATL + 1024 + 8 * idx) = h2;
;         }
;         const float asc = ASC[tl]; const int sa = SAL[tl];
;         CFENCE();
;         int accH[4], accL[4];
; #pragma unroll
;         for (int st = 0; st < 16; ++st) {
;             const int p = st >> 2, q = st & 3;
;             if (st < 14) VDMA(st + 2, (st + 2) % 3);
;             if (st < 14) asm volatile("s_waitcnt vmcnt(8)" ::: "memory");
;             else if (st == 14) asm volatile("s_waitcnt vmcnt(4)" ::: "memory");
;             else asm volatile("s_waitcnt vmcnt(0)" ::: "memory");
;             if (q == 0) {
; #pragma unroll
;                 for (int r = 0; r < 4; ++r) { accH[r] = 0; accL[r] = 0; } }
; #pragma unroll
;             for (int tp = 0; tp < 2; ++tp) {
;                 const v2i ao = TR4(ATL + (2 * q + tp) * 128 + 8 * s16), ah = TR4(ATL + 1024 + (2 * q + tp) * 128 + 8 * s16);
; #pragma unroll
;                 for (int r = 0; r < 4; ++r) {
;                     const v2i d = TR4(ldsb + BUF[st % 3] + 2048 * tp + roff[r]);
;                     accH[r] = __builtin_amdgcn_sdot8(d.x, ah.x, accH[r], false); accH[r] = __builtin_amdgcn_sdot8(d.y, ah.y, accH[r], false);
;                     accL[r] = __builtin_amdgcn_sdot8(d.x, ao.x, accL[r], false); accL[r] = __builtin_amdgcn_sdot8(d.y, ao.y, accL[r], false);
;                 }
;             }
;             asm volatile("s_waitcnt lgkmcnt(0)" ::: "memory");
;             if (q == 3) {
; #pragma unroll
;                 for (int r = 0; r < 4; ++r) STASH[256 * p + 16 * (grp + 4 * r) + pc] = f2bf(asc * (float)(2 * ((accH[r] << 4) + accL[r]) + sa));
;             }
	v_add_u32_e32 v143, 8, v139
	v_and_b32_e32 v142, 15, v143
	v_xor_b32_e32 v142, 8, v142
	v_bfe_u32 v144, v143, 4, 4
	v_mul_lo_u32 v142, v142, s92
	v_mul_lo_u32 v144, v144, s92
	v_mov_b32_e32 v143, v142
	v_mov_b32_e32 v145, v144
	ds_write2st64_b64 v159, v[142:143], v[144:145] offset1:2
	v_and_b32_e32 v78, 0xffff, v28
	v_lshrrev_b32_e32 v79, 16, v28
	v_lshl_add_u32 v78, v78, 7, v150
	v_lshl_add_u32 v79, v79, 7, v151
	s_mov_b32 m0, s98
	s_add_i32 s43, s98, 0x400
	global_load_lds_dwordx4 v78, s[50:51]
	s_mov_b32 m0, s43
	s_nop 0
	global_load_lds_dwordx4 v79, s[50:51]
	s_waitcnt vmcnt(8)
	v_add_u32_e32 v54, s76, v59
	v_add_u32_e32 v55, s76, v60
	v_add_u32_e32 v56, s76, v61
	v_add_u32_e32 v57, s76, v62
	ds_read_b64_tr_b4 v[46:47], v160 offset:768
	ds_read_b64_tr_b4 v[48:49], v160 offset:1792
	ds_read_b64_tr_b4 v[122:123], v54
	ds_read_b64_tr_b4 v[124:125], v55
	ds_read_b64_tr_b4 v[126:127], v56
	ds_read_b64_tr_b4 v[128:129], v57
	s_waitcnt lgkmcnt(7)
	v_dot8c_i32_i4_e32 v38, v130, v52
	v_dot8c_i32_i4_e32 v39, v130, v50
	v_dot8c_i32_i4_e32 v40, v132, v52
	v_dot8c_i32_i4_e32 v41, v132, v50
	v_dot8c_i32_i4_e32 v42, v134, v52
	v_dot8c_i32_i4_e32 v43, v134, v50
	v_dot8c_i32_i4_e32 v44, v136, v52
	v_dot8c_i32_i4_e32 v45, v136, v50
	v_dot8c_i32_i4_e32 v38, v131, v53
	v_dot8c_i32_i4_e32 v39, v131, v51
	v_dot8c_i32_i4_e32 v40, v133, v53
	v_dot8c_i32_i4_e32 v41, v133, v51
	v_dot8c_i32_i4_e32 v42, v135, v53
	v_dot8c_i32_i4_e32 v43, v135, v51
	v_dot8c_i32_i4_e32 v44, v137, v53
	v_dot8c_i32_i4_e32 v45, v137, v51
	v_and_b32_e32 v78, 0xffff, v29
	v_lshrrev_b32_e32 v79, 16, v29
	v_lshl_add_u32 v78, v78, 7, v150
	v_lshl_add_u32 v79, v79, 7, v151
	s_mov_b32 m0, s99
	s_add_i32 s43, s99, 0x400
	global_load_lds_dwordx4 v78, s[50:51]
	s_mov_b32 m0, s43
	s_nop 0
	global_load_lds_dwordx4 v79, s[50:51]
	s_waitcnt vmcnt(8)
	v_add_u32_e32 v54, s77, v59
	v_add_u32_e32 v55, s77, v60
	v_add_u32_e32 v56, s77, v61
	v_add_u32_e32 v57, s77, v62
	ds_read_b64_tr_b4 v[50:51], v160 offset:896
	ds_read_b64_tr_b4 v[52:53], v160 offset:1920
	ds_read_b64_tr_b4 v[130:131], v54
	ds_read_b64_tr_b4 v[132:133], v55
	ds_read_b64_tr_b4 v[134:135], v56
	ds_read_b64_tr_b4 v[136:137], v57
	s_waitcnt lgkmcnt(6)
	v_dot8c_i32_i4_e32 v38, v122, v48
	v_dot8c_i32_i4_e32 v39, v122, v46
	v_dot8c_i32_i4_e32 v40, v124, v48
	v_dot8c_i32_i4_e32 v41, v124, v46
	v_dot8c_i32_i4_e32 v42, v126, v48
	v_dot8c_i32_i4_e32 v43, v126, v46
	v_dot8c_i32_i4_e32 v44, v128, v48
	v_dot8c_i32_i4_e32 v45, v128, v46
	v_dot8c_i32_i4_e32 v38, v123, v49
	v_dot8c_i32_i4_e32 v39, v123, v47
	v_dot8c_i32_i4_e32 v40, v125, v49
	v_dot8c_i32_i4_e32 v41, v125, v47
	v_dot8c_i32_i4_e32 v42, v127, v49
	v_dot8c_i32_i4_e32 v43, v127, v47
	v_dot8c_i32_i4_e32 v44, v129, v49
	v_dot8c_i32_i4_e32 v45, v129, v47
	v_and_b32_e32 v78, 0xffff, v30
	v_lshrrev_b32_e32 v79, 16, v30
	v_lshl_add_u32 v78, v78, 7, v150
	v_lshl_add_u32 v79, v79, 7, v151
	s_mov_b32 m0, s76
	s_add_i32 s43, s76, 0x400
	global_load_lds_dwordx4 v78, s[50:51]
	s_mov_b32 m0, s43
	s_nop 0
	global_load_lds_dwordx4 v79, s[50:51]
	s_waitcnt vmcnt(8)
	v_add_u32_e32 v54, s78, v59
	v_add_u32_e32 v55, s78, v60
	v_add_u32_e32 v56, s78, v61
	v_add_u32_e32 v57, s78, v62
	ds_read_b64_tr_b4 v[46:47], v160
	ds_read_b64_tr_b4 v[48:49], v160 offset:1024
	ds_read_b64_tr_b4 v[122:123], v54
	ds_read_b64_tr_b4 v[124:125], v55
	ds_read_b64_tr_b4 v[126:127], v56
	ds_read_b64_tr_b4 v[128:129], v57
	s_waitcnt lgkmcnt(6)
	v_dot8c_i32_i4_e32 v38, v130, v52
	v_dot8c_i32_i4_e32 v39, v130, v50
	v_dot8c_i32_i4_e32 v40, v132, v52
	v_dot8c_i32_i4_e32 v41, v132, v50
	v_dot8c_i32_i4_e32 v42, v134, v52
	v_dot8c_i32_i4_e32 v43, v134, v50
	v_dot8c_i32_i4_e32 v44, v136, v52
	v_dot8c_i32_i4_e32 v45, v136, v50
	v_dot8c_i32_i4_e32 v38, v131, v53
	v_dot8c_i32_i4_e32 v39, v131, v51
	v_dot8c_i32_i4_e32 v40, v133, v53
	v_dot8c_i32_i4_e32 v41, v133, v51
	v_dot8c_i32_i4_e32 v42, v135, v53
	v_dot8c_i32_i4_e32 v43, v135, v51
	v_dot8c_i32_i4_e32 v44, v137, v53
	v_dot8c_i32_i4_e32 v45, v137, v51
	s_nop 3
	s_waitcnt lgkmcnt(15)
	v_lshlrev_b32_e32 v38, 5, v38
	v_lshlrev_b32_e32 v39, 1, v39
	v_add3_u32 v38, v39, v229, v38
	v_cvt_f32_i32_e32 v38, v38
	v_mul_f32_e32 v38, v228, v38
	v_lshlrev_b32_e32 v40, 5, v40
	v_lshlrev_b32_e32 v41, 1, v41
	v_add3_u32 v40, v41, v229, v40
	v_cvt_f32_i32_e32 v40, v40
	v_mul_f32_e32 v40, v228, v40
	v_lshlrev_b32_e32 v42, 5, v42
	v_lshlrev_b32_e32 v43, 1, v43
	v_add3_u32 v42, v43, v229, v42
	v_cvt_f32_i32_e32 v42, v42
	v_mul_f32_e32 v42, v228, v42
	v_lshlrev_b32_e32 v44, 5, v44
	v_lshlrev_b32_e32 v45, 1, v45
	v_add3_u32 v44, v45, v229, v44
	v_cvt_f32_i32_e32 v44, v44
	v_mul_f32_e32 v44, v228, v44
	v_cvt_pk_bf16_f32 v162, v38, v40
	v_cvt_pk_bf16_f32 v163, v42, v44
	v_add_u32_e32 v147, 8, v140
	v_and_b32_e32 v146, 15, v147
	v_xor_b32_e32 v146, 8, v146
	v_bfe_u32 v148, v147, 4, 4
	v_mul_lo_u32 v146, v146, s92
	v_mul_lo_u32 v148, v148, s92
	v_mov_b32_e32 v147, v146
	v_mov_b32_e32 v149, v148
	ds_write2st64_b64 v77, v[146:147], v[148:149] offset1:2
	v_mov_b32_e32 v138, v74
	ds_read_u8 v139, v138
	v_mov_b32_e32 v141, v73
	ds_read_u8 v140, v141
	s_add_i32 s43, s67, 32
	v_mov_b32_e32 v138, s43
	ds_read2st64_b32 v[228:229], v138 offset1:1
	ds_read_b128 v[18:21], v227
	ds_read_b128 v[22:25], v227 offset:16
	v_add_u32_e32 v152, 0x200000, v63
	v_add_u32_e32 v153, 0x200000, v64
	v_mov_b32_e32 v38, 0
	v_mov_b32_e32 v39, 0
	v_mov_b32_e32 v40, 0
	v_mov_b32_e32 v41, 0
	v_mov_b32_e32 v42, 0
	v_mov_b32_e32 v43, 0
	v_mov_b32_e32 v44, 0
	v_mov_b32_e32 v45, 0
	v_and_b32_e32 v78, 0xffff, v31
	v_lshrrev_b32_e32 v79, 16, v31
	v_lshl_add_u32 v78, v78, 7, v150
	v_lshl_add_u32 v79, v79, 7, v151
	s_mov_b32 m0, s77
	s_add_i32 s43, s77, 0x400
	global_load_lds_dwordx4 v78, s[50:51]
	s_mov_b32 m0, s43
	s_nop 0
	global_load_lds_dwordx4 v79, s[50:51]
	s_waitcnt vmcnt(8)
; #define TR4(p_) __builtin_amdgcn_ds_read_tr4_b64_v2i32((LAS v2i*)(p_))
; #define VDMA(st_, k_) do { _Pragma("unroll") for (int i_ = 0; i_ < 4; ++i_) { \
;         const unsigned off_ = (unsigned)((st_) >> 2) * (16384u * 128u) + (PE_ID(E, 4 * ((st_) & 3) + i_) << 7) + ((i_ & 1) ? cx1 : cx0); \
;         __builtin_amdgcn_global_load_lds((const unsigned*)(V4 + off_), (LAS unsigned*)(ldsb + BUF[k_] + 1024 * i_), 16, 0, 0); } } while (0)
; __device__ __forceinline__ void peer_v_tokens(int j, const LAS unsigned short* EL, const LAS unsigned char* AL  , const LAS float* ASC  , const LAS int* SAL  , ...
;     ...
;         for (int st = 0; st < 16; ++st) {
;             const int p = st >> 2, q = st & 3;
;             if (st < 14) VDMA(st + 2, (st + 2) % 3);
;             if (st < 14) asm volatile("s_waitcnt vmcnt(8)" ::: "memory");
;             else if (st == 14) asm volatile("s_waitcnt vmcnt(4)" ::: "memory");
;             else asm volatile("s_waitcnt vmcnt(0)" ::: "memory");
;             if (q == 0) {
; #pragma unroll
;                 for (int r = 0; r < 4; ++r) { accH[r] = 0; accL[r] = 0; } }
; #pragma unroll
;             for (int tp = 0; tp < 2; ++tp) {
;                 const v2i ao = TR4(ATL + (2 * q + tp) * 128 + 8 * s16), ah = TR4(ATL + 1024 + (2 * q + tp) * 128 + 8 * s16);
; #pragma unroll
;                 for (int r = 0; r < 4; ++r) {
;                     const v2i d = TR4(ldsb + BUF[st % 3] + 2048 * tp + roff[r]);
;                     accH[r] = __builtin_amdgcn_sdot8(d.x, ah.x, accH[r], false); accH[r] = __builtin_amdgcn_sdot8(d.y, ah.y, accH[r], false);
;                     accL[r] = __builtin_amdgcn_sdot8(d.x, ao.x, accL[r], false); accL[r] = __builtin_amdgcn_sdot8(d.y, ao.y, accL[r], false);
;                 }
;             }
	v_add_u32_e32 v54, s79, v59
	v_add_u32_e32 v55, s79, v60
	v_add_u32_e32 v56, s79, v61
	v_add_u32_e32 v57, s79, v62
	ds_read_b64_tr_b4 v[50:51], v160 offset:128
	ds_read_b64_tr_b4 v[52:53], v160 offset:1152
	ds_read_b64_tr_b4 v[130:131], v54
	ds_read_b64_tr_b4 v[132:133], v55
	ds_read_b64_tr_b4 v[134:135], v56
	ds_read_b64_tr_b4 v[136:137], v57
	s_waitcnt lgkmcnt(12)
	v_dot8c_i32_i4_e32 v38, v122, v48
	v_dot8c_i32_i4_e32 v39, v122, v46
	v_dot8c_i32_i4_e32 v40, v124, v48
	v_dot8c_i32_i4_e32 v41, v124, v46
	v_dot8c_i32_i4_e32 v42, v126, v48
	v_dot8c_i32_i4_e32 v43, v126, v46
	v_dot8c_i32_i4_e32 v44, v128, v48
	v_dot8c_i32_i4_e32 v45, v128, v46
	v_dot8c_i32_i4_e32 v38, v123, v49
	v_dot8c_i32_i4_e32 v39, v123, v47
	v_dot8c_i32_i4_e32 v40, v125, v49
	v_dot8c_i32_i4_e32 v41, v125, v47
	v_dot8c_i32_i4_e32 v42, v127, v49
	v_dot8c_i32_i4_e32 v43, v127, v47
	v_dot8c_i32_i4_e32 v44, v129, v49
	v_dot8c_i32_i4_e32 v45, v129, v47
	v_and_b32_e32 v78, 0xffff, v32
	v_lshrrev_b32_e32 v79, 16, v32
	v_lshl_add_u32 v78, v78, 7, v150
	v_lshl_add_u32 v79, v79, 7, v151
	s_mov_b32 m0, s78
	s_add_i32 s43, s78, 0x400
	global_load_lds_dwordx4 v78, s[50:51]
	s_mov_b32 m0, s43
	s_nop 0
	global_load_lds_dwordx4 v79, s[50:51]
	s_waitcnt vmcnt(8)
	v_add_u32_e32 v54, s98, v59
	v_add_u32_e32 v55, s98, v60
	v_add_u32_e32 v56, s98, v61
	v_add_u32_e32 v57, s98, v62
	ds_read_b64_tr_b4 v[46:47], v160 offset:256
	ds_read_b64_tr_b4 v[48:49], v160 offset:1280
	ds_read_b64_tr_b4 v[122:123], v54
	ds_read_b64_tr_b4 v[124:125], v55
	ds_read_b64_tr_b4 v[126:127], v56
	ds_read_b64_tr_b4 v[128:129], v57
	s_waitcnt lgkmcnt(6)
	v_dot8c_i32_i4_e32 v38, v130, v52
	v_dot8c_i32_i4_e32 v39, v130, v50
	v_dot8c_i32_i4_e32 v40, v132, v52
	v_dot8c_i32_i4_e32 v41, v132, v50
	v_dot8c_i32_i4_e32 v42, v134, v52
	v_dot8c_i32_i4_e32 v43, v134, v50
	v_dot8c_i32_i4_e32 v44, v136, v52
	v_dot8c_i32_i4_e32 v45, v136, v50
	v_dot8c_i32_i4_e32 v38, v131, v53
	v_dot8c_i32_i4_e32 v39, v131, v51
	v_dot8c_i32_i4_e32 v40, v133, v53
	v_dot8c_i32_i4_e32 v41, v133, v51
	v_dot8c_i32_i4_e32 v42, v135, v53
	v_dot8c_i32_i4_e32 v43, v135, v51
	v_dot8c_i32_i4_e32 v44, v137, v53
	v_dot8c_i32_i4_e32 v45, v137, v51
	v_and_b32_e32 v78, 0xffff, v33
	v_lshrrev_b32_e32 v79, 16, v33
	v_lshl_add_u32 v78, v78, 7, v150
	v_lshl_add_u32 v79, v79, 7, v151
	s_mov_b32 m0, s79
	s_add_i32 s43, s79, 0x400
	global_load_lds_dwordx4 v78, s[50:51]
	s_mov_b32 m0, s43
	s_nop 0
	global_load_lds_dwordx4 v79, s[50:51]
	s_waitcnt vmcnt(8)
	v_add_u32_e32 v54, s99, v59
	v_add_u32_e32 v55, s99, v60
	v_add_u32_e32 v56, s99, v61
	v_add_u32_e32 v57, s99, v62
	ds_read_b64_tr_b4 v[50:51], v160 offset:384
	ds_read_b64_tr_b4 v[52:53], v160 offset:1408
	ds_read_b64_tr_b4 v[130:131], v54
	ds_read_b64_tr_b4 v[132:133], v55
	ds_read_b64_tr_b4 v[134:135], v56
	ds_read_b64_tr_b4 v[136:137], v57
	s_waitcnt lgkmcnt(6)
	v_dot8c_i32_i4_e32 v38, v122, v48
	v_dot8c_i32_i4_e32 v39, v122, v46
	v_dot8c_i32_i4_e32 v40, v124, v48
	v_dot8c_i32_i4_e32 v41, v124, v46
	v_dot8c_i32_i4_e32 v42, v126, v48
	v_dot8c_i32_i4_e32 v43, v126, v46
	v_dot8c_i32_i4_e32 v44, v128, v48
	v_dot8c_i32_i4_e32 v45, v128, v46
	v_dot8c_i32_i4_e32 v38, v123, v49
	v_dot8c_i32_i4_e32 v39, v123, v47
	v_dot8c_i32_i4_e32 v40, v125, v49
	v_dot8c_i32_i4_e32 v41, v125, v47
	v_dot8c_i32_i4_e32 v42, v127, v49
	v_dot8c_i32_i4_e32 v43, v127, v47
	v_dot8c_i32_i4_e32 v44, v129, v49
	v_dot8c_i32_i4_e32 v45, v129, v47
	s_waitcnt lgkmcnt(15)
	v_and_b32_e32 v78, 0xffff, v18
	v_lshrrev_b32_e32 v79, 16, v18
	v_lshl_add_u32 v78, v78, 7, v152
	v_lshl_add_u32 v79, v79, 7, v153
	s_mov_b32 m0, s98
	s_add_i32 s43, s98, 0x400
	global_load_lds_dwordx4 v78, s[50:51]
	s_mov_b32 m0, s43
	s_nop 0
	global_load_lds_dwordx4 v79, s[50:51]
	s_waitcnt vmcnt(8)
	v_add_u32_e32 v54, s76, v59
	v_add_u32_e32 v55, s76, v60
	v_add_u32_e32 v56, s76, v61
	v_add_u32_e32 v57, s76, v62
	ds_read_b64_tr_b4 v[46:47], v160 offset:512
	ds_read_b64_tr_b4 v[48:49], v160 offset:1536
	ds_read_b64_tr_b4 v[122:123], v54
	ds_read_b64_tr_b4 v[124:125], v55
	ds_read_b64_tr_b4 v[126:127], v56
	ds_read_b64_tr_b4 v[128:129], v57
	s_waitcnt lgkmcnt(6)
	v_dot8c_i32_i4_e32 v38, v130, v52
	v_dot8c_i32_i4_e32 v39, v130, v50
	v_dot8c_i32_i4_e32 v40, v132, v52
	v_dot8c_i32_i4_e32 v41, v132, v50
	v_dot8c_i32_i4_e32 v42, v134, v52
	v_dot8c_i32_i4_e32 v43, v134, v50
	v_dot8c_i32_i4_e32 v44, v136, v52
	v_dot8c_i32_i4_e32 v45, v136, v50
	v_dot8c_i32_i4_e32 v38, v131, v53
	v_dot8c_i32_i4_e32 v39, v131, v51
	v_dot8c_i32_i4_e32 v40, v133, v53
	v_dot8c_i32_i4_e32 v41, v133, v51
	v_dot8c_i32_i4_e32 v42, v135, v53
	v_dot8c_i32_i4_e32 v43, v135, v51
	v_dot8c_i32_i4_e32 v44, v137, v53
	v_dot8c_i32_i4_e32 v45, v137, v51
	v_and_b32_e32 v78, 0xffff, v19
	v_lshrrev_b32_e32 v79, 16, v19
	v_lshl_add_u32 v78, v78, 7, v152
	v_lshl_add_u32 v79, v79, 7, v153
	s_mov_b32 m0, s99
	s_add_i32 s43, s99, 0x400
	global_load_lds_dwordx4 v78, s[50:51]
	s_mov_b32 m0, s43
	s_nop 0
	global_load_lds_dwordx4 v79, s[50:51]
	s_waitcnt vmcnt(8)
	v_add_u32_e32 v54, s77, v59
	v_add_u32_e32 v55, s77, v60
	v_add_u32_e32 v56, s77, v61
	v_add_u32_e32 v57, s77, v62
	ds_read_b64_tr_b4 v[50:51], v160 offset:640
	ds_read_b64_tr_b4 v[52:53], v160 offset:1664
	ds_read_b64_tr_b4 v[130:131], v54
	ds_read_b64_tr_b4 v[132:133], v55
	ds_read_b64_tr_b4 v[134:135], v56
	ds_read_b64_tr_b4 v[136:137], v57
	s_waitcnt lgkmcnt(6)
	v_dot8c_i32_i4_e32 v38, v122, v48
	v_dot8c_i32_i4_e32 v39, v122, v46
	v_dot8c_i32_i4_e32 v40, v124, v48
	v_dot8c_i32_i4_e32 v41, v124, v46
	v_dot8c_i32_i4_e32 v42, v126, v48
	v_dot8c_i32_i4_e32 v43, v126, v46
	v_dot8c_i32_i4_e32 v44, v128, v48
	v_dot8c_i32_i4_e32 v45, v128, v46
	v_dot8c_i32_i4_e32 v38, v123, v49
	v_dot8c_i32_i4_e32 v39, v123, v47
	v_dot8c_i32_i4_e32 v40, v125, v49
	v_dot8c_i32_i4_e32 v41, v125, v47
	v_dot8c_i32_i4_e32 v42, v127, v49
	v_dot8c_i32_i4_e32 v43, v127, v47
	v_dot8c_i32_i4_e32 v44, v129, v49
	v_dot8c_i32_i4_e32 v45, v129, v47
	s_waitcnt lgkmcnt(15)
; __device__ __forceinline__ void peer_v_tokens(int j, const LAS unsigned short* EL, const LAS unsigned char* AL  , const LAS float* ASC  , const LAS int* SAL  , ...
;     ...
; #pragma unroll
;         for (int m = 0; m < 2; ++m) {
;             const int idx = lane + 64 * m, tau = idx >> 4, sr = idx & 15, k = 16 * (sr & 7) + 2 * tau + (sr >> 3);
;             const int aq = (int)*(const LAS signed char*)(AL + tl * 128 + k); const int tq = aq + 8;
;             const unsigned lo = (((unsigned)tq & 15u) ^ 8u) * 0x11111111u, hi = ((unsigned)(tq >> 4) & 15u) * 0x11111111u;
;             typedef unsigned u2v __attribute__((ext_vector_type(2)));
;             u2v l2; l2.x = lo; l2.y = lo; u2v h2; h2.x = hi; h2.y = hi;
;             *(LAS u2v*)(ATL + 8 * idx) = l2; *(LAS u2v*)(ATL + 1024 + 8 * idx) = h2;
;         }
;         const float asc = ASC[tl]; const int sa = SAL[tl];
;         CFENCE();
;         int accH[4], accL[4];
; #pragma unroll
;         for (int st = 0; st < 16; ++st) {
;             const int p = st >> 2, q = st & 3;
;             if (st < 14) VDMA(st + 2, (st + 2) % 3);
;             if (st < 14) asm volatile("s_waitcnt vmcnt(8)" ::: "memory");
;             else if (st == 14) asm volatile("s_waitcnt vmcnt(4)" ::: "memory");
;             else asm volatile("s_waitcnt vmcnt(0)" ::: "memory");
;             if (q == 0) {
; #pragma unroll
;                 for (int r = 0; r < 4; ++r) { accH[r] = 0; accL[r] = 0; } }
; #pragma unroll
;             for (int tp = 0; tp < 2; ++tp) {
;                 const v2i ao = TR4(ATL + (2 * q + tp) * 128 + 8 * s16), ah = TR4(ATL + 1024 + (2 * q + tp) * 128 + 8 * s16);
; #pragma unroll
;                 for (int r = 0; r < 4; ++r) {
;                     const v2i d = TR4(ldsb + BUF[st % 3] + 2048 * tp + roff[r]);
;                     accH[r] = __builtin_amdgcn_sdot8(d.x, ah.x, accH[r], false); accH[r] = __builtin_amdgcn_sdot8(d.y, ah.y, accH[r], false);
;                     accL[r] = __builtin_amdgcn_sdot8(d.x, ao.x, accL[r], false); accL[r] = __builtin_amdgcn_sdot8(d.y, ao.y, accL[r], false);
;                 }
;             }
;             asm volatile("s_waitcnt lgkmcnt(0)" ::: "memory");
;             if (q == 3) {
; #pragma unroll
;                 for (int r = 0; r < 4; ++r) STASH[256 * p + 16 * (grp + 4 * r) + pc] = f2bf(asc * (float)(2 * ((accH[r] << 4) + accL[r]) + sa));
;             }
	v_add_u32_e32 v143, 8, v139
	v_and_b32_e32 v142, 15, v143
	v_xor_b32_e32 v142, 8, v142
	v_bfe_u32 v144, v143, 4, 4
	v_mul_lo_u32 v142, v142, s92
	v_mul_lo_u32 v144, v144, s92
	v_mov_b32_e32 v143, v142
	v_mov_b32_e32 v145, v144
	ds_write2st64_b64 v159, v[142:143], v[144:145] offset1:2
	v_and_b32_e32 v78, 0xffff, v20
	v_lshrrev_b32_e32 v79, 16, v20
	v_lshl_add_u32 v78, v78, 7, v152
	v_lshl_add_u32 v79, v79, 7, v153
	s_mov_b32 m0, s76
	s_add_i32 s43, s76, 0x400
	global_load_lds_dwordx4 v78, s[50:51]
	s_mov_b32 m0, s43
	s_nop 0
	global_load_lds_dwordx4 v79, s[50:51]
	s_waitcnt vmcnt(8)
	v_add_u32_e32 v54, s78, v59
	v_add_u32_e32 v55, s78, v60
	v_add_u32_e32 v56, s78, v61
	v_add_u32_e32 v57, s78, v62
	ds_read_b64_tr_b4 v[46:47], v160 offset:768
	ds_read_b64_tr_b4 v[48:49], v160 offset:1792
	ds_read_b64_tr_b4 v[122:123], v54
	ds_read_b64_tr_b4 v[124:125], v55
	ds_read_b64_tr_b4 v[126:127], v56
	ds_read_b64_tr_b4 v[128:129], v57
	s_waitcnt lgkmcnt(7)
	v_dot8c_i32_i4_e32 v38, v130, v52
	v_dot8c_i32_i4_e32 v39, v130, v50
	v_dot8c_i32_i4_e32 v40, v132, v52
	v_dot8c_i32_i4_e32 v41, v132, v50
	v_dot8c_i32_i4_e32 v42, v134, v52
	v_dot8c_i32_i4_e32 v43, v134, v50
	v_dot8c_i32_i4_e32 v44, v136, v52
	v_dot8c_i32_i4_e32 v45, v136, v50
	v_dot8c_i32_i4_e32 v38, v131, v53
	v_dot8c_i32_i4_e32 v39, v131, v51
	v_dot8c_i32_i4_e32 v40, v133, v53
	v_dot8c_i32_i4_e32 v41, v133, v51
	v_dot8c_i32_i4_e32 v42, v135, v53
	v_dot8c_i32_i4_e32 v43, v135, v51
	v_dot8c_i32_i4_e32 v44, v137, v53
	v_dot8c_i32_i4_e32 v45, v137, v51
	v_and_b32_e32 v78, 0xffff, v21
	v_lshrrev_b32_e32 v79, 16, v21
	v_lshl_add_u32 v78, v78, 7, v152
	v_lshl_add_u32 v79, v79, 7, v153
	s_mov_b32 m0, s77
	s_add_i32 s43, s77, 0x400
	global_load_lds_dwordx4 v78, s[50:51]
	s_mov_b32 m0, s43
	s_nop 0
	global_load_lds_dwordx4 v79, s[50:51]
	s_waitcnt vmcnt(8)
	v_add_u32_e32 v54, s79, v59
	v_add_u32_e32 v55, s79, v60
	v_add_u32_e32 v56, s79, v61
	v_add_u32_e32 v57, s79, v62
	ds_read_b64_tr_b4 v[50:51], v160 offset:896
	ds_read_b64_tr_b4 v[52:53], v160 offset:1920
	ds_read_b64_tr_b4 v[130:131], v54
	ds_read_b64_tr_b4 v[132:133], v55
	ds_read_b64_tr_b4 v[134:135], v56
	ds_read_b64_tr_b4 v[136:137], v57
	s_waitcnt lgkmcnt(6)
	v_dot8c_i32_i4_e32 v38, v122, v48
	v_dot8c_i32_i4_e32 v39, v122, v46
	v_dot8c_i32_i4_e32 v40, v124, v48
	v_dot8c_i32_i4_e32 v41, v124, v46
	v_dot8c_i32_i4_e32 v42, v126, v48
	v_dot8c_i32_i4_e32 v43, v126, v46
	v_dot8c_i32_i4_e32 v44, v128, v48
	v_dot8c_i32_i4_e32 v45, v128, v46
	v_dot8c_i32_i4_e32 v38, v123, v49
	v_dot8c_i32_i4_e32 v39, v123, v47
	v_dot8c_i32_i4_e32 v40, v125, v49
	v_dot8c_i32_i4_e32 v41, v125, v47
	v_dot8c_i32_i4_e32 v42, v127, v49
	v_dot8c_i32_i4_e32 v43, v127, v47
	v_dot8c_i32_i4_e32 v44, v129, v49
	v_dot8c_i32_i4_e32 v45, v129, v47
	v_and_b32_e32 v78, 0xffff, v22
	v_lshrrev_b32_e32 v79, 16, v22
	v_lshl_add_u32 v78, v78, 7, v152
	v_lshl_add_u32 v79, v79, 7, v153
	s_mov_b32 m0, s78
	s_add_i32 s43, s78, 0x400
	global_load_lds_dwordx4 v78, s[50:51]
	s_mov_b32 m0, s43
	s_nop 0
	global_load_lds_dwordx4 v79, s[50:51]
	s_waitcnt vmcnt(8)
	v_add_u32_e32 v54, s98, v59
	v_add_u32_e32 v55, s98, v60
	v_add_u32_e32 v56, s98, v61
	v_add_u32_e32 v57, s98, v62
	ds_read_b64_tr_b4 v[46:47], v160
	ds_read_b64_tr_b4 v[48:49], v160 offset:1024
	ds_read_b64_tr_b4 v[122:123], v54
	ds_read_b64_tr_b4 v[124:125], v55
	ds_read_b64_tr_b4 v[126:127], v56
	ds_read_b64_tr_b4 v[128:129], v57
	s_waitcnt lgkmcnt(6)
	v_dot8c_i32_i4_e32 v38, v130, v52
	v_dot8c_i32_i4_e32 v39, v130, v50
	v_dot8c_i32_i4_e32 v40, v132, v52
	v_dot8c_i32_i4_e32 v41, v132, v50
	v_dot8c_i32_i4_e32 v42, v134, v52
	v_dot8c_i32_i4_e32 v43, v134, v50
	v_dot8c_i32_i4_e32 v44, v136, v52
	v_dot8c_i32_i4_e32 v45, v136, v50
	v_dot8c_i32_i4_e32 v38, v131, v53
	v_dot8c_i32_i4_e32 v39, v131, v51
	v_dot8c_i32_i4_e32 v40, v133, v53
	v_dot8c_i32_i4_e32 v41, v133, v51
	v_dot8c_i32_i4_e32 v42, v135, v53
	v_dot8c_i32_i4_e32 v43, v135, v51
	v_dot8c_i32_i4_e32 v44, v137, v53
	v_dot8c_i32_i4_e32 v45, v137, v51
	s_nop 3
	s_waitcnt lgkmcnt(15)
	v_lshlrev_b32_e32 v38, 5, v38
	v_lshlrev_b32_e32 v39, 1, v39
	v_add3_u32 v38, v39, v229, v38
	v_cvt_f32_i32_e32 v38, v38
	v_mul_f32_e32 v38, v228, v38
	v_lshlrev_b32_e32 v40, 5, v40
	v_lshlrev_b32_e32 v41, 1, v41
	v_add3_u32 v40, v41, v229, v40
	v_cvt_f32_i32_e32 v40, v40
	v_mul_f32_e32 v40, v228, v40
	v_lshlrev_b32_e32 v42, 5, v42
	v_lshlrev_b32_e32 v43, 1, v43
	v_add3_u32 v42, v43, v229, v42
	v_cvt_f32_i32_e32 v42, v42
	v_mul_f32_e32 v42, v228, v42
	v_lshlrev_b32_e32 v44, 5, v44
	v_lshlrev_b32_e32 v45, 1, v45
	v_add3_u32 v44, v45, v229, v44
	v_cvt_f32_i32_e32 v44, v44
	v_mul_f32_e32 v44, v228, v44
	v_cvt_pk_bf16_f32 v170, v38, v40
	v_cvt_pk_bf16_f32 v171, v42, v44
	v_add_u32_e32 v147, 8, v140
	v_and_b32_e32 v146, 15, v147
	v_xor_b32_e32 v146, 8, v146
	v_bfe_u32 v148, v147, 4, 4
	v_mul_lo_u32 v146, v146, s92
	v_mul_lo_u32 v148, v148, s92
	v_mov_b32_e32 v147, v146
	v_mov_b32_e32 v149, v148
	ds_write2st64_b64 v77, v[146:147], v[148:149] offset1:2
	v_add_u32_e32 v138, 0x400, v74
	ds_read_u8 v139, v138
	v_add_u32_e32 v141, 0x400, v73
	ds_read_u8 v140, v141
	s_mov_b32 s43, s67
	v_mov_b32_e32 v138, s43
	ds_read2st64_b32 v[228:229], v138 offset1:1
	ds_read_b128 v[26:29], v227 offset:2048
	ds_read_b128 v[30:33], v227 offset:2064
	v_mov_b32_e32 v38, 0
	v_mov_b32_e32 v39, 0
	v_mov_b32_e32 v40, 0
	v_mov_b32_e32 v41, 0
	v_mov_b32_e32 v42, 0
	v_mov_b32_e32 v43, 0
	v_mov_b32_e32 v44, 0
	v_mov_b32_e32 v45, 0
	v_and_b32_e32 v78, 0xffff, v23
	v_lshrrev_b32_e32 v79, 16, v23
	v_lshl_add_u32 v78, v78, 7, v152
	v_lshl_add_u32 v79, v79, 7, v153
	s_mov_b32 m0, s79
	s_add_i32 s43, s79, 0x400
	global_load_lds_dwordx4 v78, s[50:51]
	s_mov_b32 m0, s43
	s_nop 0
	global_load_lds_dwordx4 v79, s[50:51]
	s_waitcnt vmcnt(8)
; #define TR4(p_) __builtin_amdgcn_ds_read_tr4_b64_v2i32((LAS v2i*)(p_))
; #define VDMA(st_, k_) do { _Pragma("unroll") for (int i_ = 0; i_ < 4; ++i_) { \
;         const unsigned off_ = (unsigned)((st_) >> 2) * (16384u * 128u) + (PE_ID(E, 4 * ((st_) & 3) + i_) << 7) + ((i_ & 1) ? cx1 : cx0); \
;         __builtin_amdgcn_global_load_lds((const unsigned*)(V4 + off_), (LAS unsigned*)(ldsb + BUF[k_] + 1024 * i_), 16, 0, 0); } } while (0)
; __device__ __forceinline__ void peer_v_tokens(int j, const LAS unsigned short* EL, const LAS unsigned char* AL  , const LAS float* ASC  , const LAS int* SAL  , ...
;     ...
;         for (int st = 0; st < 16; ++st) {
;             const int p = st >> 2, q = st & 3;
;             if (st < 14) VDMA(st + 2, (st + 2) % 3);
;             if (st < 14) asm volatile("s_waitcnt vmcnt(8)" ::: "memory");
;             else if (st == 14) asm volatile("s_waitcnt vmcnt(4)" ::: "memory");
;             else asm volatile("s_waitcnt vmcnt(0)" ::: "memory");
;             if (q == 0) {
; #pragma unroll
;                 for (int r = 0; r < 4; ++r) { accH[r] = 0; accL[r] = 0; } }
; #pragma unroll
;             for (int tp = 0; tp < 2; ++tp) {
;                 const v2i ao = TR4(ATL + (2 * q + tp) * 128 + 8 * s16), ah = TR4(ATL + 1024 + (2 * q + tp) * 128 + 8 * s16);
; #pragma unroll
;                 for (int r = 0; r < 4; ++r) {
;                     const v2i d = TR4(ldsb + BUF[st % 3] + 2048 * tp + roff[r]);
;                     accH[r] = __builtin_amdgcn_sdot8(d.x, ah.x, accH[r], false); accH[r] = __builtin_amdgcn_sdot8(d.y, ah.y, accH[r], false);
;                     accL[r] = __builtin_amdgcn_sdot8(d.x, ao.x, accL[r], false); accL[r] = __builtin_amdgcn_sdot8(d.y, ao.y, accL[r], false);
;                 }
;             }
	v_add_u32_e32 v54, s99, v59
	v_add_u32_e32 v55, s99, v60
	v_add_u32_e32 v56, s99, v61
	v_add_u32_e32 v57, s99, v62
	ds_read_b64_tr_b4 v[50:51], v160 offset:128
	ds_read_b64_tr_b4 v[52:53], v160 offset:1152
	ds_read_b64_tr_b4 v[130:131], v54
	ds_read_b64_tr_b4 v[132:133], v55
	ds_read_b64_tr_b4 v[134:135], v56
	ds_read_b64_tr_b4 v[136:137], v57
	s_waitcnt lgkmcnt(12)
	v_dot8c_i32_i4_e32 v38, v122, v48
	v_dot8c_i32_i4_e32 v39, v122, v46
	v_dot8c_i32_i4_e32 v40, v124, v48
	v_dot8c_i32_i4_e32 v41, v124, v46
	v_dot8c_i32_i4_e32 v42, v126, v48
	v_dot8c_i32_i4_e32 v43, v126, v46
	v_dot8c_i32_i4_e32 v44, v128, v48
	v_dot8c_i32_i4_e32 v45, v128, v46
	v_dot8c_i32_i4_e32 v38, v123, v49
	v_dot8c_i32_i4_e32 v39, v123, v47
	v_dot8c_i32_i4_e32 v40, v125, v49
	v_dot8c_i32_i4_e32 v41, v125, v47
	v_dot8c_i32_i4_e32 v42, v127, v49
	v_dot8c_i32_i4_e32 v43, v127, v47
	v_dot8c_i32_i4_e32 v44, v129, v49
	v_dot8c_i32_i4_e32 v45, v129, v47
	v_and_b32_e32 v78, 0xffff, v24
	v_lshrrev_b32_e32 v79, 16, v24
	v_lshl_add_u32 v78, v78, 7, v152
	v_lshl_add_u32 v79, v79, 7, v153
	s_mov_b32 m0, s98
	s_add_i32 s43, s98, 0x400
	global_load_lds_dwordx4 v78, s[50:51]
	s_mov_b32 m0, s43
	s_nop 0
	global_load_lds_dwordx4 v79, s[50:51]
	s_waitcnt vmcnt(8)
	v_add_u32_e32 v54, s76, v59
	v_add_u32_e32 v55, s76, v60
	v_add_u32_e32 v56, s76, v61
	v_add_u32_e32 v57, s76, v62
	ds_read_b64_tr_b4 v[46:47], v160 offset:256
	ds_read_b64_tr_b4 v[48:49], v160 offset:1280
	ds_read_b64_tr_b4 v[122:123], v54
	ds_read_b64_tr_b4 v[124:125], v55
	ds_read_b64_tr_b4 v[126:127], v56
	ds_read_b64_tr_b4 v[128:129], v57
	s_waitcnt lgkmcnt(6)
	v_dot8c_i32_i4_e32 v38, v130, v52
	v_dot8c_i32_i4_e32 v39, v130, v50
	v_dot8c_i32_i4_e32 v40, v132, v52
	v_dot8c_i32_i4_e32 v41, v132, v50
	v_dot8c_i32_i4_e32 v42, v134, v52
	v_dot8c_i32_i4_e32 v43, v134, v50
	v_dot8c_i32_i4_e32 v44, v136, v52
	v_dot8c_i32_i4_e32 v45, v136, v50
	v_dot8c_i32_i4_e32 v38, v131, v53
	v_dot8c_i32_i4_e32 v39, v131, v51
	v_dot8c_i32_i4_e32 v40, v133, v53
	v_dot8c_i32_i4_e32 v41, v133, v51
	v_dot8c_i32_i4_e32 v42, v135, v53
	v_dot8c_i32_i4_e32 v43, v135, v51
	v_dot8c_i32_i4_e32 v44, v137, v53
	v_dot8c_i32_i4_e32 v45, v137, v51
	v_and_b32_e32 v78, 0xffff, v25
	v_lshrrev_b32_e32 v79, 16, v25
	v_lshl_add_u32 v78, v78, 7, v152
	v_lshl_add_u32 v79, v79, 7, v153
	s_mov_b32 m0, s99
	s_add_i32 s43, s99, 0x400
	global_load_lds_dwordx4 v78, s[50:51]
	s_mov_b32 m0, s43
	s_nop 0
	global_load_lds_dwordx4 v79, s[50:51]
	s_waitcnt vmcnt(8)
	v_add_u32_e32 v54, s77, v59
	v_add_u32_e32 v55, s77, v60
	v_add_u32_e32 v56, s77, v61
	v_add_u32_e32 v57, s77, v62
	ds_read_b64_tr_b4 v[50:51], v160 offset:384
	ds_read_b64_tr_b4 v[52:53], v160 offset:1408
	ds_read_b64_tr_b4 v[130:131], v54
	ds_read_b64_tr_b4 v[132:133], v55
	ds_read_b64_tr_b4 v[134:135], v56
	ds_read_b64_tr_b4 v[136:137], v57
	s_waitcnt lgkmcnt(6)
	v_dot8c_i32_i4_e32 v38, v122, v48
	v_dot8c_i32_i4_e32 v39, v122, v46
	v_dot8c_i32_i4_e32 v40, v124, v48
	v_dot8c_i32_i4_e32 v41, v124, v46
	v_dot8c_i32_i4_e32 v42, v126, v48
	v_dot8c_i32_i4_e32 v43, v126, v46
	v_dot8c_i32_i4_e32 v44, v128, v48
	v_dot8c_i32_i4_e32 v45, v128, v46
	v_dot8c_i32_i4_e32 v38, v123, v49
	v_dot8c_i32_i4_e32 v39, v123, v47
	v_dot8c_i32_i4_e32 v40, v125, v49
	v_dot8c_i32_i4_e32 v41, v125, v47
	v_dot8c_i32_i4_e32 v42, v127, v49
	v_dot8c_i32_i4_e32 v43, v127, v47
	v_dot8c_i32_i4_e32 v44, v129, v49
	v_dot8c_i32_i4_e32 v45, v129, v47
	s_waitcnt lgkmcnt(15)
	v_and_b32_e32 v78, 0xffff, v26
	v_lshrrev_b32_e32 v79, 16, v26
	v_lshl_add_u32 v78, v78, 7, v152
	v_lshl_add_u32 v79, v79, 7, v153
	s_mov_b32 m0, s76
	s_add_i32 s43, s76, 0x400
	global_load_lds_dwordx4 v78, s[50:51]
	s_mov_b32 m0, s43
	s_nop 0
	global_load_lds_dwordx4 v79, s[50:51]
	s_waitcnt vmcnt(8)
	v_add_u32_e32 v54, s78, v59
	v_add_u32_e32 v55, s78, v60
	v_add_u32_e32 v56, s78, v61
	v_add_u32_e32 v57, s78, v62
	ds_read_b64_tr_b4 v[46:47], v160 offset:512
	ds_read_b64_tr_b4 v[48:49], v160 offset:1536
	ds_read_b64_tr_b4 v[122:123], v54
	ds_read_b64_tr_b4 v[124:125], v55
	ds_read_b64_tr_b4 v[126:127], v56
	ds_read_b64_tr_b4 v[128:129], v57
	s_waitcnt lgkmcnt(6)
	v_dot8c_i32_i4_e32 v38, v130, v52
	v_dot8c_i32_i4_e32 v39, v130, v50
	v_dot8c_i32_i4_e32 v40, v132, v52
	v_dot8c_i32_i4_e32 v41, v132, v50
	v_dot8c_i32_i4_e32 v42, v134, v52
	v_dot8c_i32_i4_e32 v43, v134, v50
	v_dot8c_i32_i4_e32 v44, v136, v52
	v_dot8c_i32_i4_e32 v45, v136, v50
	v_dot8c_i32_i4_e32 v38, v131, v53
	v_dot8c_i32_i4_e32 v39, v131, v51
	v_dot8c_i32_i4_e32 v40, v133, v53
	v_dot8c_i32_i4_e32 v41, v133, v51
	v_dot8c_i32_i4_e32 v42, v135, v53
	v_dot8c_i32_i4_e32 v43, v135, v51
	v_dot8c_i32_i4_e32 v44, v137, v53
	v_dot8c_i32_i4_e32 v45, v137, v51
	v_and_b32_e32 v78, 0xffff, v27
	v_lshrrev_b32_e32 v79, 16, v27
	v_lshl_add_u32 v78, v78, 7, v152
	v_lshl_add_u32 v79, v79, 7, v153
	s_mov_b32 m0, s77
	s_add_i32 s43, s77, 0x400
	global_load_lds_dwordx4 v78, s[50:51]
	s_mov_b32 m0, s43
	s_nop 0
	global_load_lds_dwordx4 v79, s[50:51]
	s_waitcnt vmcnt(8)
	v_add_u32_e32 v54, s79, v59
	v_add_u32_e32 v55, s79, v60
	v_add_u32_e32 v56, s79, v61
	v_add_u32_e32 v57, s79, v62
	ds_read_b64_tr_b4 v[50:51], v160 offset:640
	ds_read_b64_tr_b4 v[52:53], v160 offset:1664
	ds_read_b64_tr_b4 v[130:131], v54
	ds_read_b64_tr_b4 v[132:133], v55
	ds_read_b64_tr_b4 v[134:135], v56
	ds_read_b64_tr_b4 v[136:137], v57
	s_waitcnt lgkmcnt(6)
	v_dot8c_i32_i4_e32 v38, v122, v48
	v_dot8c_i32_i4_e32 v39, v122, v46
	v_dot8c_i32_i4_e32 v40, v124, v48
	v_dot8c_i32_i4_e32 v41, v124, v46
	v_dot8c_i32_i4_e32 v42, v126, v48
	v_dot8c_i32_i4_e32 v43, v126, v46
	v_dot8c_i32_i4_e32 v44, v128, v48
	v_dot8c_i32_i4_e32 v45, v128, v46
	v_dot8c_i32_i4_e32 v38, v123, v49
	v_dot8c_i32_i4_e32 v39, v123, v47
	v_dot8c_i32_i4_e32 v40, v125, v49
	v_dot8c_i32_i4_e32 v41, v125, v47
	v_dot8c_i32_i4_e32 v42, v127, v49
	v_dot8c_i32_i4_e32 v43, v127, v47
	v_dot8c_i32_i4_e32 v44, v129, v49
	v_dot8c_i32_i4_e32 v45, v129, v47
	s_waitcnt lgkmcnt(15)
; __device__ __forceinline__ void peer_v_tokens(int j, const LAS unsigned short* EL, const LAS unsigned char* AL  , const LAS float* ASC  , const LAS int* SAL  , ...
;     ...
; #pragma unroll
;         for (int m = 0; m < 2; ++m) {
;             const int idx = lane + 64 * m, tau = idx >> 4, sr = idx & 15, k = 16 * (sr & 7) + 2 * tau + (sr >> 3);
;             const int aq = (int)*(const LAS signed char*)(AL + tl * 128 + k); const int tq = aq + 8;
;             const unsigned lo = (((unsigned)tq & 15u) ^ 8u) * 0x11111111u, hi = ((unsigned)(tq >> 4) & 15u) * 0x11111111u;
;             typedef unsigned u2v __attribute__((ext_vector_type(2)));
;             u2v l2; l2.x = lo; l2.y = lo; u2v h2; h2.x = hi; h2.y = hi;
;             *(LAS u2v*)(ATL + 8 * idx) = l2; *(LAS u2v*)(ATL + 1024 + 8 * idx) = h2;
;         }
;         const float asc = ASC[tl]; const int sa = SAL[tl];
;         CFENCE();
;         int accH[4], accL[4];
; #pragma unroll
;         for (int st = 0; st < 16; ++st) {
;             const int p = st >> 2, q = st & 3;
;             if (st < 14) VDMA(st + 2, (st + 2) % 3);
;             if (st < 14) asm volatile("s_waitcnt vmcnt(8)" ::: "memory");
;             else if (st == 14) asm volatile("s_waitcnt vmcnt(4)" ::: "memory");
;             else asm volatile("s_waitcnt vmcnt(0)" ::: "memory");
;             if (q == 0) {
; #pragma unroll
;                 for (int r = 0; r < 4; ++r) { accH[r] = 0; accL[r] = 0; } }
; #pragma unroll
;             for (int tp = 0; tp < 2; ++tp) {
;                 const v2i ao = TR4(ATL + (2 * q + tp) * 128 + 8 * s16), ah = TR4(ATL + 1024 + (2 * q + tp) * 128 + 8 * s16);
; #pragma unroll
;                 for (int r = 0; r < 4; ++r) {
;                     const v2i d = TR4(ldsb + BUF[st % 3] + 2048 * tp + roff[r]);
;                     accH[r] = __builtin_amdgcn_sdot8(d.x, ah.x, accH[r], false); accH[r] = __builtin_amdgcn_sdot8(d.y, ah.y, accH[r], false);
;                     accL[r] = __builtin_amdgcn_sdot8(d.x, ao.x, accL[r], false); accL[r] = __builtin_amdgcn_sdot8(d.y, ao.y, accL[r], false);
;                 }
;             }
;             asm volatile("s_waitcnt lgkmcnt(0)" ::: "memory");
;             if (q == 3) {
; #pragma unroll
;                 for (int r = 0; r < 4; ++r) STASH[256 * p + 16 * (grp + 4 * r) + pc] = f2bf(asc * (float)(2 * ((accH[r] << 4) + accL[r]) + sa));
;             }
	v_add_u32_e32 v143, 8, v139
	v_and_b32_e32 v142, 15, v143
	v_xor_b32_e32 v142, 8, v142
	v_bfe_u32 v144, v143, 4, 4
	v_mul_lo_u32 v142, v142, s92
	v_mul_lo_u32 v144, v144, s92
	v_mov_b32_e32 v143, v142
	v_mov_b32_e32 v145, v144
	ds_write2st64_b64 v159, v[142:143], v[144:145] offset1:2
	v_and_b32_e32 v78, 0xffff, v28
	v_lshrrev_b32_e32 v79, 16, v28
	v_lshl_add_u32 v78, v78, 7, v152
	v_lshl_add_u32 v79, v79, 7, v153
	s_mov_b32 m0, s78
	s_add_i32 s43, s78, 0x400
	global_load_lds_dwordx4 v78, s[50:51]
	s_mov_b32 m0, s43
	s_nop 0
	global_load_lds_dwordx4 v79, s[50:51]
	s_waitcnt vmcnt(8)
	v_add_u32_e32 v54, s98, v59
	v_add_u32_e32 v55, s98, v60
	v_add_u32_e32 v56, s98, v61
	v_add_u32_e32 v57, s98, v62
	ds_read_b64_tr_b4 v[46:47], v160 offset:768
	ds_read_b64_tr_b4 v[48:49], v160 offset:1792
	ds_read_b64_tr_b4 v[122:123], v54
	ds_read_b64_tr_b4 v[124:125], v55
	ds_read_b64_tr_b4 v[126:127], v56
	ds_read_b64_tr_b4 v[128:129], v57
	s_waitcnt lgkmcnt(7)
	v_dot8c_i32_i4_e32 v38, v130, v52
	v_dot8c_i32_i4_e32 v39, v130, v50
	v_dot8c_i32_i4_e32 v40, v132, v52
	v_dot8c_i32_i4_e32 v41, v132, v50
	v_dot8c_i32_i4_e32 v42, v134, v52
	v_dot8c_i32_i4_e32 v43, v134, v50
	v_dot8c_i32_i4_e32 v44, v136, v52
	v_dot8c_i32_i4_e32 v45, v136, v50
	v_dot8c_i32_i4_e32 v38, v131, v53
	v_dot8c_i32_i4_e32 v39, v131, v51
	v_dot8c_i32_i4_e32 v40, v133, v53
	v_dot8c_i32_i4_e32 v41, v133, v51
	v_dot8c_i32_i4_e32 v42, v135, v53
	v_dot8c_i32_i4_e32 v43, v135, v51
	v_dot8c_i32_i4_e32 v44, v137, v53
	v_dot8c_i32_i4_e32 v45, v137, v51
	v_and_b32_e32 v78, 0xffff, v29
	v_lshrrev_b32_e32 v79, 16, v29
	v_lshl_add_u32 v78, v78, 7, v152
	v_lshl_add_u32 v79, v79, 7, v153
	s_mov_b32 m0, s79
	s_add_i32 s43, s79, 0x400
	global_load_lds_dwordx4 v78, s[50:51]
	s_mov_b32 m0, s43
	s_nop 0
	global_load_lds_dwordx4 v79, s[50:51]
	s_waitcnt vmcnt(8)
	v_add_u32_e32 v54, s99, v59
	v_add_u32_e32 v55, s99, v60
	v_add_u32_e32 v56, s99, v61
	v_add_u32_e32 v57, s99, v62
	ds_read_b64_tr_b4 v[50:51], v160 offset:896
	ds_read_b64_tr_b4 v[52:53], v160 offset:1920
	ds_read_b64_tr_b4 v[130:131], v54
	ds_read_b64_tr_b4 v[132:133], v55
	ds_read_b64_tr_b4 v[134:135], v56
	ds_read_b64_tr_b4 v[136:137], v57
	s_waitcnt lgkmcnt(6)
	v_dot8c_i32_i4_e32 v38, v122, v48
	v_dot8c_i32_i4_e32 v39, v122, v46
	v_dot8c_i32_i4_e32 v40, v124, v48
	v_dot8c_i32_i4_e32 v41, v124, v46
	v_dot8c_i32_i4_e32 v42, v126, v48
	v_dot8c_i32_i4_e32 v43, v126, v46
	v_dot8c_i32_i4_e32 v44, v128, v48
	v_dot8c_i32_i4_e32 v45, v128, v46
	v_dot8c_i32_i4_e32 v38, v123, v49
	v_dot8c_i32_i4_e32 v39, v123, v47
	v_dot8c_i32_i4_e32 v40, v125, v49
	v_dot8c_i32_i4_e32 v41, v125, v47
	v_dot8c_i32_i4_e32 v42, v127, v49
	v_dot8c_i32_i4_e32 v43, v127, v47
	v_dot8c_i32_i4_e32 v44, v129, v49
	v_dot8c_i32_i4_e32 v45, v129, v47
	v_and_b32_e32 v78, 0xffff, v30
	v_lshrrev_b32_e32 v79, 16, v30
	v_lshl_add_u32 v78, v78, 7, v152
	v_lshl_add_u32 v79, v79, 7, v153
	s_mov_b32 m0, s98
	s_add_i32 s43, s98, 0x400
	global_load_lds_dwordx4 v78, s[50:51]
	s_mov_b32 m0, s43
	s_nop 0
	global_load_lds_dwordx4 v79, s[50:51]
	s_waitcnt vmcnt(8)
	v_add_u32_e32 v54, s76, v59
	v_add_u32_e32 v55, s76, v60
	v_add_u32_e32 v56, s76, v61
	v_add_u32_e32 v57, s76, v62
	ds_read_b64_tr_b4 v[46:47], v160
	ds_read_b64_tr_b4 v[48:49], v160 offset:1024
	ds_read_b64_tr_b4 v[122:123], v54
	ds_read_b64_tr_b4 v[124:125], v55
	ds_read_b64_tr_b4 v[126:127], v56
	ds_read_b64_tr_b4 v[128:129], v57
	s_waitcnt lgkmcnt(6)
	v_dot8c_i32_i4_e32 v38, v130, v52
	v_dot8c_i32_i4_e32 v39, v130, v50
	v_dot8c_i32_i4_e32 v40, v132, v52
	v_dot8c_i32_i4_e32 v41, v132, v50
	v_dot8c_i32_i4_e32 v42, v134, v52
	v_dot8c_i32_i4_e32 v43, v134, v50
	v_dot8c_i32_i4_e32 v44, v136, v52
	v_dot8c_i32_i4_e32 v45, v136, v50
	v_dot8c_i32_i4_e32 v38, v131, v53
	v_dot8c_i32_i4_e32 v39, v131, v51
	v_dot8c_i32_i4_e32 v40, v133, v53
	v_dot8c_i32_i4_e32 v41, v133, v51
	v_dot8c_i32_i4_e32 v42, v135, v53
	v_dot8c_i32_i4_e32 v43, v135, v51
	v_dot8c_i32_i4_e32 v44, v137, v53
	v_dot8c_i32_i4_e32 v45, v137, v51
	s_nop 3
	s_waitcnt lgkmcnt(15)
	v_lshlrev_b32_e32 v38, 5, v38
	v_lshlrev_b32_e32 v39, 1, v39
	v_add3_u32 v38, v39, v229, v38
	v_cvt_f32_i32_e32 v38, v38
	v_mul_f32_e32 v38, v228, v38
	v_lshlrev_b32_e32 v40, 5, v40
	v_lshlrev_b32_e32 v41, 1, v41
	v_add3_u32 v40, v41, v229, v40
	v_cvt_f32_i32_e32 v40, v40
	v_mul_f32_e32 v40, v228, v40
	v_lshlrev_b32_e32 v42, 5, v42
	v_lshlrev_b32_e32 v43, 1, v43
	v_add3_u32 v42, v43, v229, v42
	v_cvt_f32_i32_e32 v42, v42
	v_mul_f32_e32 v42, v228, v42
	v_lshlrev_b32_e32 v44, 5, v44
	v_lshlrev_b32_e32 v45, 1, v45
	v_add3_u32 v44, v45, v229, v44
	v_cvt_f32_i32_e32 v44, v44
	v_mul_f32_e32 v44, v228, v44
	v_cvt_pk_bf16_f32 v164, v38, v40
	v_cvt_pk_bf16_f32 v165, v42, v44
	v_add_u32_e32 v147, 8, v140
	v_and_b32_e32 v146, 15, v147
	v_xor_b32_e32 v146, 8, v146
	v_bfe_u32 v148, v147, 4, 4
	v_mul_lo_u32 v146, v146, s92
	v_mul_lo_u32 v148, v148, s92
	v_mov_b32_e32 v147, v146
	v_mov_b32_e32 v149, v148
	ds_write2st64_b64 v77, v[146:147], v[148:149] offset1:2
	v_mov_b32_e32 v138, v74
	ds_read_u8 v139, v138
	v_mov_b32_e32 v141, v73
	ds_read_u8 v140, v141
	s_add_i32 s43, s67, 32
	v_mov_b32_e32 v138, s43
	ds_read2st64_b32 v[228:229], v138 offset1:1
	ds_read_b128 v[18:21], v227
	ds_read_b128 v[22:25], v227 offset:16
	v_add_u32_e32 v150, 0x400000, v63
	v_add_u32_e32 v151, 0x400000, v64
	v_mov_b32_e32 v38, 0
	v_mov_b32_e32 v39, 0
	v_mov_b32_e32 v40, 0
	v_mov_b32_e32 v41, 0
	v_mov_b32_e32 v42, 0
	v_mov_b32_e32 v43, 0
	v_mov_b32_e32 v44, 0
	v_mov_b32_e32 v45, 0
	v_and_b32_e32 v78, 0xffff, v31
	v_lshrrev_b32_e32 v79, 16, v31
	v_lshl_add_u32 v78, v78, 7, v152
	v_lshl_add_u32 v79, v79, 7, v153
	s_mov_b32 m0, s99
	s_add_i32 s43, s99, 0x400
	global_load_lds_dwordx4 v78, s[50:51]
	s_mov_b32 m0, s43
	s_nop 0
	global_load_lds_dwordx4 v79, s[50:51]
	s_waitcnt vmcnt(8)
; #define TR4(p_) __builtin_amdgcn_ds_read_tr4_b64_v2i32((LAS v2i*)(p_))
; #define VDMA(st_, k_) do { _Pragma("unroll") for (int i_ = 0; i_ < 4; ++i_) { \
;         const unsigned off_ = (unsigned)((st_) >> 2) * (16384u * 128u) + (PE_ID(E, 4 * ((st_) & 3) + i_) << 7) + ((i_ & 1) ? cx1 : cx0); \
;         __builtin_amdgcn_global_load_lds((const unsigned*)(V4 + off_), (LAS unsigned*)(ldsb + BUF[k_] + 1024 * i_), 16, 0, 0); } } while (0)
; __device__ __forceinline__ void peer_v_tokens(int j, const LAS unsigned short* EL, const LAS unsigned char* AL  , const LAS float* ASC  , const LAS int* SAL  , ...
;     ...
;         for (int st = 0; st < 16; ++st) {
;             const int p = st >> 2, q = st & 3;
;             if (st < 14) VDMA(st + 2, (st + 2) % 3);
;             if (st < 14) asm volatile("s_waitcnt vmcnt(8)" ::: "memory");
;             else if (st == 14) asm volatile("s_waitcnt vmcnt(4)" ::: "memory");
;             else asm volatile("s_waitcnt vmcnt(0)" ::: "memory");
;             if (q == 0) {
; #pragma unroll
;                 for (int r = 0; r < 4; ++r) { accH[r] = 0; accL[r] = 0; } }
; #pragma unroll
;             for (int tp = 0; tp < 2; ++tp) {
;                 const v2i ao = TR4(ATL + (2 * q + tp) * 128 + 8 * s16), ah = TR4(ATL + 1024 + (2 * q + tp) * 128 + 8 * s16);
; #pragma unroll
;                 for (int r = 0; r < 4; ++r) {
;                     const v2i d = TR4(ldsb + BUF[st % 3] + 2048 * tp + roff[r]);
;                     accH[r] = __builtin_amdgcn_sdot8(d.x, ah.x, accH[r], false); accH[r] = __builtin_amdgcn_sdot8(d.y, ah.y, accH[r], false);
;                     accL[r] = __builtin_amdgcn_sdot8(d.x, ao.x, accL[r], false); accL[r] = __builtin_amdgcn_sdot8(d.y, ao.y, accL[r], false);
;                 }
;             }
	v_add_u32_e32 v54, s77, v59
	v_add_u32_e32 v55, s77, v60
	v_add_u32_e32 v56, s77, v61
	v_add_u32_e32 v57, s77, v62
	ds_read_b64_tr_b4 v[50:51], v160 offset:128
	ds_read_b64_tr_b4 v[52:53], v160 offset:1152
	ds_read_b64_tr_b4 v[130:131], v54
	ds_read_b64_tr_b4 v[132:133], v55
	ds_read_b64_tr_b4 v[134:135], v56
	ds_read_b64_tr_b4 v[136:137], v57
	s_waitcnt lgkmcnt(12)
	v_dot8c_i32_i4_e32 v38, v122, v48
	v_dot8c_i32_i4_e32 v39, v122, v46
	v_dot8c_i32_i4_e32 v40, v124, v48
	v_dot8c_i32_i4_e32 v41, v124, v46
	v_dot8c_i32_i4_e32 v42, v126, v48
	v_dot8c_i32_i4_e32 v43, v126, v46
	v_dot8c_i32_i4_e32 v44, v128, v48
	v_dot8c_i32_i4_e32 v45, v128, v46
	v_dot8c_i32_i4_e32 v38, v123, v49
	v_dot8c_i32_i4_e32 v39, v123, v47
	v_dot8c_i32_i4_e32 v40, v125, v49
	v_dot8c_i32_i4_e32 v41, v125, v47
	v_dot8c_i32_i4_e32 v42, v127, v49
	v_dot8c_i32_i4_e32 v43, v127, v47
	v_dot8c_i32_i4_e32 v44, v129, v49
	v_dot8c_i32_i4_e32 v45, v129, v47
	v_and_b32_e32 v78, 0xffff, v32
	v_lshrrev_b32_e32 v79, 16, v32
	v_lshl_add_u32 v78, v78, 7, v152
	v_lshl_add_u32 v79, v79, 7, v153
	s_mov_b32 m0, s76
	s_add_i32 s43, s76, 0x400
	global_load_lds_dwordx4 v78, s[50:51]
	s_mov_b32 m0, s43
	s_nop 0
	global_load_lds_dwordx4 v79, s[50:51]
	s_waitcnt vmcnt(8)
	v_add_u32_e32 v54, s78, v59
	v_add_u32_e32 v55, s78, v60
	v_add_u32_e32 v56, s78, v61
	v_add_u32_e32 v57, s78, v62
	ds_read_b64_tr_b4 v[46:47], v160 offset:256
	ds_read_b64_tr_b4 v[48:49], v160 offset:1280
	ds_read_b64_tr_b4 v[122:123], v54
	ds_read_b64_tr_b4 v[124:125], v55
	ds_read_b64_tr_b4 v[126:127], v56
	ds_read_b64_tr_b4 v[128:129], v57
	s_waitcnt lgkmcnt(6)
	v_dot8c_i32_i4_e32 v38, v130, v52
	v_dot8c_i32_i4_e32 v39, v130, v50
	v_dot8c_i32_i4_e32 v40, v132, v52
	v_dot8c_i32_i4_e32 v41, v132, v50
	v_dot8c_i32_i4_e32 v42, v134, v52
	v_dot8c_i32_i4_e32 v43, v134, v50
	v_dot8c_i32_i4_e32 v44, v136, v52
	v_dot8c_i32_i4_e32 v45, v136, v50
	v_dot8c_i32_i4_e32 v38, v131, v53
	v_dot8c_i32_i4_e32 v39, v131, v51
	v_dot8c_i32_i4_e32 v40, v133, v53
	v_dot8c_i32_i4_e32 v41, v133, v51
	v_dot8c_i32_i4_e32 v42, v135, v53
	v_dot8c_i32_i4_e32 v43, v135, v51
	v_dot8c_i32_i4_e32 v44, v137, v53
	v_dot8c_i32_i4_e32 v45, v137, v51
	v_and_b32_e32 v78, 0xffff, v33
	v_lshrrev_b32_e32 v79, 16, v33
	v_lshl_add_u32 v78, v78, 7, v152
	v_lshl_add_u32 v79, v79, 7, v153
	s_mov_b32 m0, s77
	s_add_i32 s43, s77, 0x400
	global_load_lds_dwordx4 v78, s[50:51]
	s_mov_b32 m0, s43
	s_nop 0
	global_load_lds_dwordx4 v79, s[50:51]
	s_waitcnt vmcnt(8)
	v_add_u32_e32 v54, s79, v59
	v_add_u32_e32 v55, s79, v60
	v_add_u32_e32 v56, s79, v61
	v_add_u32_e32 v57, s79, v62
	ds_read_b64_tr_b4 v[50:51], v160 offset:384
	ds_read_b64_tr_b4 v[52:53], v160 offset:1408
	ds_read_b64_tr_b4 v[130:131], v54
	ds_read_b64_tr_b4 v[132:133], v55
	ds_read_b64_tr_b4 v[134:135], v56
	ds_read_b64_tr_b4 v[136:137], v57
	s_waitcnt lgkmcnt(6)
	v_dot8c_i32_i4_e32 v38, v122, v48
	v_dot8c_i32_i4_e32 v39, v122, v46
	v_dot8c_i32_i4_e32 v40, v124, v48
	v_dot8c_i32_i4_e32 v41, v124, v46
	v_dot8c_i32_i4_e32 v42, v126, v48
	v_dot8c_i32_i4_e32 v43, v126, v46
	v_dot8c_i32_i4_e32 v44, v128, v48
	v_dot8c_i32_i4_e32 v45, v128, v46
	v_dot8c_i32_i4_e32 v38, v123, v49
	v_dot8c_i32_i4_e32 v39, v123, v47
	v_dot8c_i32_i4_e32 v40, v125, v49
	v_dot8c_i32_i4_e32 v41, v125, v47
	v_dot8c_i32_i4_e32 v42, v127, v49
	v_dot8c_i32_i4_e32 v43, v127, v47
	v_dot8c_i32_i4_e32 v44, v129, v49
	v_dot8c_i32_i4_e32 v45, v129, v47
	s_waitcnt lgkmcnt(15)
	v_and_b32_e32 v78, 0xffff, v18
	v_lshrrev_b32_e32 v79, 16, v18
	v_lshl_add_u32 v78, v78, 7, v150
	v_lshl_add_u32 v79, v79, 7, v151
	s_mov_b32 m0, s78
	s_add_i32 s43, s78, 0x400
	global_load_lds_dwordx4 v78, s[50:51]
	s_mov_b32 m0, s43
	s_nop 0
	global_load_lds_dwordx4 v79, s[50:51]
	s_waitcnt vmcnt(8)
	v_add_u32_e32 v54, s98, v59
	v_add_u32_e32 v55, s98, v60
	v_add_u32_e32 v56, s98, v61
	v_add_u32_e32 v57, s98, v62
	ds_read_b64_tr_b4 v[46:47], v160 offset:512
	ds_read_b64_tr_b4 v[48:49], v160 offset:1536
	ds_read_b64_tr_b4 v[122:123], v54
	ds_read_b64_tr_b4 v[124:125], v55
	ds_read_b64_tr_b4 v[126:127], v56
	ds_read_b64_tr_b4 v[128:129], v57
	s_waitcnt lgkmcnt(6)
	v_dot8c_i32_i4_e32 v38, v130, v52
	v_dot8c_i32_i4_e32 v39, v130, v50
	v_dot8c_i32_i4_e32 v40, v132, v52
	v_dot8c_i32_i4_e32 v41, v132, v50
	v_dot8c_i32_i4_e32 v42, v134, v52
	v_dot8c_i32_i4_e32 v43, v134, v50
	v_dot8c_i32_i4_e32 v44, v136, v52
	v_dot8c_i32_i4_e32 v45, v136, v50
	v_dot8c_i32_i4_e32 v38, v131, v53
	v_dot8c_i32_i4_e32 v39, v131, v51
	v_dot8c_i32_i4_e32 v40, v133, v53
	v_dot8c_i32_i4_e32 v41, v133, v51
	v_dot8c_i32_i4_e32 v42, v135, v53
	v_dot8c_i32_i4_e32 v43, v135, v51
	v_dot8c_i32_i4_e32 v44, v137, v53
	v_dot8c_i32_i4_e32 v45, v137, v51
	v_and_b32_e32 v78, 0xffff, v19
	v_lshrrev_b32_e32 v79, 16, v19
	v_lshl_add_u32 v78, v78, 7, v150
	v_lshl_add_u32 v79, v79, 7, v151
	s_mov_b32 m0, s79
	s_add_i32 s43, s79, 0x400
	global_load_lds_dwordx4 v78, s[50:51]
	s_mov_b32 m0, s43
	s_nop 0
	global_load_lds_dwordx4 v79, s[50:51]
	s_waitcnt vmcnt(8)
	v_add_u32_e32 v54, s99, v59
	v_add_u32_e32 v55, s99, v60
	v_add_u32_e32 v56, s99, v61
	v_add_u32_e32 v57, s99, v62
	ds_read_b64_tr_b4 v[50:51], v160 offset:640
	ds_read_b64_tr_b4 v[52:53], v160 offset:1664
	ds_read_b64_tr_b4 v[130:131], v54
	ds_read_b64_tr_b4 v[132:133], v55
	ds_read_b64_tr_b4 v[134:135], v56
	ds_read_b64_tr_b4 v[136:137], v57
	s_waitcnt lgkmcnt(6)
	v_dot8c_i32_i4_e32 v38, v122, v48
	v_dot8c_i32_i4_e32 v39, v122, v46
	v_dot8c_i32_i4_e32 v40, v124, v48
	v_dot8c_i32_i4_e32 v41, v124, v46
	v_dot8c_i32_i4_e32 v42, v126, v48
	v_dot8c_i32_i4_e32 v43, v126, v46
	v_dot8c_i32_i4_e32 v44, v128, v48
	v_dot8c_i32_i4_e32 v45, v128, v46
	v_dot8c_i32_i4_e32 v38, v123, v49
	v_dot8c_i32_i4_e32 v39, v123, v47
	v_dot8c_i32_i4_e32 v40, v125, v49
	v_dot8c_i32_i4_e32 v41, v125, v47
	v_dot8c_i32_i4_e32 v42, v127, v49
	v_dot8c_i32_i4_e32 v43, v127, v47
	v_dot8c_i32_i4_e32 v44, v129, v49
	v_dot8c_i32_i4_e32 v45, v129, v47
	s_waitcnt lgkmcnt(15)
; __device__ __forceinline__ void peer_v_tokens(int j, const LAS unsigned short* EL, const LAS unsigned char* AL  , const LAS float* ASC  , const LAS int* SAL  , ...
;     ...
; #pragma unroll
;         for (int m = 0; m < 2; ++m) {
;             const int idx = lane + 64 * m, tau = idx >> 4, sr = idx & 15, k = 16 * (sr & 7) + 2 * tau + (sr >> 3);
;             const int aq = (int)*(const LAS signed char*)(AL + tl * 128 + k); const int tq = aq + 8;
;             const unsigned lo = (((unsigned)tq & 15u) ^ 8u) * 0x11111111u, hi = ((unsigned)(tq >> 4) & 15u) * 0x11111111u;
;             typedef unsigned u2v __attribute__((ext_vector_type(2)));
;             u2v l2; l2.x = lo; l2.y = lo; u2v h2; h2.x = hi; h2.y = hi;
;             *(LAS u2v*)(ATL + 8 * idx) = l2; *(LAS u2v*)(ATL + 1024 + 8 * idx) = h2;
;         }
;         const float asc = ASC[tl]; const int sa = SAL[tl];
;         CFENCE();
;         int accH[4], accL[4];
; #pragma unroll
;         for (int st = 0; st < 16; ++st) {
;             const int p = st >> 2, q = st & 3;
;             if (st < 14) VDMA(st + 2, (st + 2) % 3);
;             if (st < 14) asm volatile("s_waitcnt vmcnt(8)" ::: "memory");
;             else if (st == 14) asm volatile("s_waitcnt vmcnt(4)" ::: "memory");
;             else asm volatile("s_waitcnt vmcnt(0)" ::: "memory");
;             if (q == 0) {
; #pragma unroll
;                 for (int r = 0; r < 4; ++r) { accH[r] = 0; accL[r] = 0; } }
; #pragma unroll
;             for (int tp = 0; tp < 2; ++tp) {
;                 const v2i ao = TR4(ATL + (2 * q + tp) * 128 + 8 * s16), ah = TR4(ATL + 1024 + (2 * q + tp) * 128 + 8 * s16);
; #pragma unroll
;                 for (int r = 0; r < 4; ++r) {
;                     const v2i d = TR4(ldsb + BUF[st % 3] + 2048 * tp + roff[r]);
;                     accH[r] = __builtin_amdgcn_sdot8(d.x, ah.x, accH[r], false); accH[r] = __builtin_amdgcn_sdot8(d.y, ah.y, accH[r], false);
;                     accL[r] = __builtin_amdgcn_sdot8(d.x, ao.x, accL[r], false); accL[r] = __builtin_amdgcn_sdot8(d.y, ao.y, accL[r], false);
;                 }
;             }
;             asm volatile("s_waitcnt lgkmcnt(0)" ::: "memory");
;             if (q == 3) {
; #pragma unroll
;                 for (int r = 0; r < 4; ++r) STASH[256 * p + 16 * (grp + 4 * r) + pc] = f2bf(asc * (float)(2 * ((accH[r] << 4) + accL[r]) + sa));
;             }
	v_add_u32_e32 v143, 8, v139
	v_and_b32_e32 v142, 15, v143
	v_xor_b32_e32 v142, 8, v142
	v_bfe_u32 v144, v143, 4, 4
	v_mul_lo_u32 v142, v142, s92
	v_mul_lo_u32 v144, v144, s92
	v_mov_b32_e32 v143, v142
	v_mov_b32_e32 v145, v144
	ds_write2st64_b64 v159, v[142:143], v[144:145] offset1:2
	v_and_b32_e32 v78, 0xffff, v20
	v_lshrrev_b32_e32 v79, 16, v20
	v_lshl_add_u32 v78, v78, 7, v150
	v_lshl_add_u32 v79, v79, 7, v151
	s_mov_b32 m0, s98
	s_add_i32 s43, s98, 0x400
	global_load_lds_dwordx4 v78, s[50:51]
	s_mov_b32 m0, s43
	s_nop 0
	global_load_lds_dwordx4 v79, s[50:51]
	s_waitcnt vmcnt(8)
	v_add_u32_e32 v54, s76, v59
	v_add_u32_e32 v55, s76, v60
	v_add_u32_e32 v56, s76, v61
	v_add_u32_e32 v57, s76, v62
	ds_read_b64_tr_b4 v[46:47], v160 offset:768
	ds_read_b64_tr_b4 v[48:49], v160 offset:1792
	ds_read_b64_tr_b4 v[122:123], v54
	ds_read_b64_tr_b4 v[124:125], v55
	ds_read_b64_tr_b4 v[126:127], v56
	ds_read_b64_tr_b4 v[128:129], v57
	s_waitcnt lgkmcnt(7)
	v_dot8c_i32_i4_e32 v38, v130, v52
	v_dot8c_i32_i4_e32 v39, v130, v50
	v_dot8c_i32_i4_e32 v40, v132, v52
	v_dot8c_i32_i4_e32 v41, v132, v50
	v_dot8c_i32_i4_e32 v42, v134, v52
	v_dot8c_i32_i4_e32 v43, v134, v50
	v_dot8c_i32_i4_e32 v44, v136, v52
	v_dot8c_i32_i4_e32 v45, v136, v50
	v_dot8c_i32_i4_e32 v38, v131, v53
	v_dot8c_i32_i4_e32 v39, v131, v51
	v_dot8c_i32_i4_e32 v40, v133, v53
	v_dot8c_i32_i4_e32 v41, v133, v51
	v_dot8c_i32_i4_e32 v42, v135, v53
	v_dot8c_i32_i4_e32 v43, v135, v51
	v_dot8c_i32_i4_e32 v44, v137, v53
	v_dot8c_i32_i4_e32 v45, v137, v51
	v_and_b32_e32 v78, 0xffff, v21
	v_lshrrev_b32_e32 v79, 16, v21
	v_lshl_add_u32 v78, v78, 7, v150
	v_lshl_add_u32 v79, v79, 7, v151
	s_mov_b32 m0, s99
	s_add_i32 s43, s99, 0x400
	global_load_lds_dwordx4 v78, s[50:51]
	s_mov_b32 m0, s43
	s_nop 0
	global_load_lds_dwordx4 v79, s[50:51]
	s_waitcnt vmcnt(8)
	v_add_u32_e32 v54, s77, v59
	v_add_u32_e32 v55, s77, v60
	v_add_u32_e32 v56, s77, v61
	v_add_u32_e32 v57, s77, v62
	ds_read_b64_tr_b4 v[50:51], v160 offset:896
	ds_read_b64_tr_b4 v[52:53], v160 offset:1920
	ds_read_b64_tr_b4 v[130:131], v54
	ds_read_b64_tr_b4 v[132:133], v55
	ds_read_b64_tr_b4 v[134:135], v56
	ds_read_b64_tr_b4 v[136:137], v57
	s_waitcnt lgkmcnt(6)
	v_dot8c_i32_i4_e32 v38, v122, v48
	v_dot8c_i32_i4_e32 v39, v122, v46
	v_dot8c_i32_i4_e32 v40, v124, v48
	v_dot8c_i32_i4_e32 v41, v124, v46
	v_dot8c_i32_i4_e32 v42, v126, v48
	v_dot8c_i32_i4_e32 v43, v126, v46
	v_dot8c_i32_i4_e32 v44, v128, v48
	v_dot8c_i32_i4_e32 v45, v128, v46
	v_dot8c_i32_i4_e32 v38, v123, v49
	v_dot8c_i32_i4_e32 v39, v123, v47
	v_dot8c_i32_i4_e32 v40, v125, v49
	v_dot8c_i32_i4_e32 v41, v125, v47
	v_dot8c_i32_i4_e32 v42, v127, v49
	v_dot8c_i32_i4_e32 v43, v127, v47
	v_dot8c_i32_i4_e32 v44, v129, v49
	v_dot8c_i32_i4_e32 v45, v129, v47
	v_and_b32_e32 v78, 0xffff, v22
	v_lshrrev_b32_e32 v79, 16, v22
	v_lshl_add_u32 v78, v78, 7, v150
	v_lshl_add_u32 v79, v79, 7, v151
	s_mov_b32 m0, s76
	s_add_i32 s43, s76, 0x400
	global_load_lds_dwordx4 v78, s[50:51]
	s_mov_b32 m0, s43
	s_nop 0
	global_load_lds_dwordx4 v79, s[50:51]
	s_waitcnt vmcnt(8)
	v_add_u32_e32 v54, s78, v59
	v_add_u32_e32 v55, s78, v60
	v_add_u32_e32 v56, s78, v61
	v_add_u32_e32 v57, s78, v62
	ds_read_b64_tr_b4 v[46:47], v160
	ds_read_b64_tr_b4 v[48:49], v160 offset:1024
	ds_read_b64_tr_b4 v[122:123], v54
	ds_read_b64_tr_b4 v[124:125], v55
	ds_read_b64_tr_b4 v[126:127], v56
	ds_read_b64_tr_b4 v[128:129], v57
	s_waitcnt lgkmcnt(6)
	v_dot8c_i32_i4_e32 v38, v130, v52
	v_dot8c_i32_i4_e32 v39, v130, v50
	v_dot8c_i32_i4_e32 v40, v132, v52
	v_dot8c_i32_i4_e32 v41, v132, v50
	v_dot8c_i32_i4_e32 v42, v134, v52
	v_dot8c_i32_i4_e32 v43, v134, v50
	v_dot8c_i32_i4_e32 v44, v136, v52
	v_dot8c_i32_i4_e32 v45, v136, v50
	v_dot8c_i32_i4_e32 v38, v131, v53
	v_dot8c_i32_i4_e32 v39, v131, v51
	v_dot8c_i32_i4_e32 v40, v133, v53
	v_dot8c_i32_i4_e32 v41, v133, v51
	v_dot8c_i32_i4_e32 v42, v135, v53
	v_dot8c_i32_i4_e32 v43, v135, v51
	v_dot8c_i32_i4_e32 v44, v137, v53
	v_dot8c_i32_i4_e32 v45, v137, v51
	s_nop 3
	s_waitcnt lgkmcnt(15)
	v_lshlrev_b32_e32 v38, 5, v38
	v_lshlrev_b32_e32 v39, 1, v39
	v_add3_u32 v38, v39, v229, v38
	v_cvt_f32_i32_e32 v38, v38
	v_mul_f32_e32 v38, v228, v38
	v_lshlrev_b32_e32 v40, 5, v40
	v_lshlrev_b32_e32 v41, 1, v41
	v_add3_u32 v40, v41, v229, v40
	v_cvt_f32_i32_e32 v40, v40
	v_mul_f32_e32 v40, v228, v40
	v_lshlrev_b32_e32 v42, 5, v42
	v_lshlrev_b32_e32 v43, 1, v43
	v_add3_u32 v42, v43, v229, v42
	v_cvt_f32_i32_e32 v42, v42
	v_mul_f32_e32 v42, v228, v42
	v_lshlrev_b32_e32 v44, 5, v44
	v_lshlrev_b32_e32 v45, 1, v45
	v_add3_u32 v44, v45, v229, v44
	v_cvt_f32_i32_e32 v44, v44
	v_mul_f32_e32 v44, v228, v44
	v_cvt_pk_bf16_f32 v172, v38, v40
	v_cvt_pk_bf16_f32 v173, v42, v44
	v_add_u32_e32 v147, 8, v140
	v_and_b32_e32 v146, 15, v147
	v_xor_b32_e32 v146, 8, v146
	v_bfe_u32 v148, v147, 4, 4
	v_mul_lo_u32 v146, v146, s92
	v_mul_lo_u32 v148, v148, s92
	v_mov_b32_e32 v147, v146
	v_mov_b32_e32 v149, v148
	ds_write2st64_b64 v77, v[146:147], v[148:149] offset1:2
	v_add_u32_e32 v138, 0x400, v74
	ds_read_u8 v139, v138
	v_add_u32_e32 v141, 0x400, v73
	ds_read_u8 v140, v141
	s_mov_b32 s43, s67
	v_mov_b32_e32 v138, s43
	ds_read2st64_b32 v[228:229], v138 offset1:1
	ds_read_b128 v[26:29], v227 offset:2048
	ds_read_b128 v[30:33], v227 offset:2064
	v_mov_b32_e32 v38, 0
	v_mov_b32_e32 v39, 0
	v_mov_b32_e32 v40, 0
	v_mov_b32_e32 v41, 0
	v_mov_b32_e32 v42, 0
	v_mov_b32_e32 v43, 0
	v_mov_b32_e32 v44, 0
	v_mov_b32_e32 v45, 0
	v_and_b32_e32 v78, 0xffff, v23
	v_lshrrev_b32_e32 v79, 16, v23
	v_lshl_add_u32 v78, v78, 7, v150
	v_lshl_add_u32 v79, v79, 7, v151
	s_mov_b32 m0, s77
	s_add_i32 s43, s77, 0x400
	global_load_lds_dwordx4 v78, s[50:51]
	s_mov_b32 m0, s43
	s_nop 0
	global_load_lds_dwordx4 v79, s[50:51]
	s_waitcnt vmcnt(8)
; #define TR4(p_) __builtin_amdgcn_ds_read_tr4_b64_v2i32((LAS v2i*)(p_))
; #define VDMA(st_, k_) do { _Pragma("unroll") for (int i_ = 0; i_ < 4; ++i_) { \
;         const unsigned off_ = (unsigned)((st_) >> 2) * (16384u * 128u) + (PE_ID(E, 4 * ((st_) & 3) + i_) << 7) + ((i_ & 1) ? cx1 : cx0); \
;         __builtin_amdgcn_global_load_lds((const unsigned*)(V4 + off_), (LAS unsigned*)(ldsb + BUF[k_] + 1024 * i_), 16, 0, 0); } } while (0)
; __device__ __forceinline__ void peer_v_tokens(int j, const LAS unsigned short* EL, const LAS unsigned char* AL  , const LAS float* ASC  , const LAS int* SAL  , ...
;     ...
;         for (int st = 0; st < 16; ++st) {
;             const int p = st >> 2, q = st & 3;
;             if (st < 14) VDMA(st + 2, (st + 2) % 3);
;             if (st < 14) asm volatile("s_waitcnt vmcnt(8)" ::: "memory");
;             else if (st == 14) asm volatile("s_waitcnt vmcnt(4)" ::: "memory");
;             else asm volatile("s_waitcnt vmcnt(0)" ::: "memory");
;             if (q == 0) {
; #pragma unroll
;                 for (int r = 0; r < 4; ++r) { accH[r] = 0; accL[r] = 0; } }
; #pragma unroll
;             for (int tp = 0; tp < 2; ++tp) {
;                 const v2i ao = TR4(ATL + (2 * q + tp) * 128 + 8 * s16), ah = TR4(ATL + 1024 + (2 * q + tp) * 128 + 8 * s16);
; #pragma unroll
;                 for (int r = 0; r < 4; ++r) {
;                     const v2i d = TR4(ldsb + BUF[st % 3] + 2048 * tp + roff[r]);
;                     accH[r] = __builtin_amdgcn_sdot8(d.x, ah.x, accH[r], false); accH[r] = __builtin_amdgcn_sdot8(d.y, ah.y, accH[r], false);
;                     accL[r] = __builtin_amdgcn_sdot8(d.x, ao.x, accL[r], false); accL[r] = __builtin_amdgcn_sdot8(d.y, ao.y, accL[r], false);
;                 }
;             }
	v_add_u32_e32 v54, s79, v59
	v_add_u32_e32 v55, s79, v60
	v_add_u32_e32 v56, s79, v61
	v_add_u32_e32 v57, s79, v62
	ds_read_b64_tr_b4 v[50:51], v160 offset:128
	ds_read_b64_tr_b4 v[52:53], v160 offset:1152
	ds_read_b64_tr_b4 v[130:131], v54
	ds_read_b64_tr_b4 v[132:133], v55
	ds_read_b64_tr_b4 v[134:135], v56
	ds_read_b64_tr_b4 v[136:137], v57
	s_waitcnt lgkmcnt(12)
	v_dot8c_i32_i4_e32 v38, v122, v48
	v_dot8c_i32_i4_e32 v39, v122, v46
	v_dot8c_i32_i4_e32 v40, v124, v48
	v_dot8c_i32_i4_e32 v41, v124, v46
	v_dot8c_i32_i4_e32 v42, v126, v48
	v_dot8c_i32_i4_e32 v43, v126, v46
	v_dot8c_i32_i4_e32 v44, v128, v48
	v_dot8c_i32_i4_e32 v45, v128, v46
	v_dot8c_i32_i4_e32 v38, v123, v49
	v_dot8c_i32_i4_e32 v39, v123, v47
	v_dot8c_i32_i4_e32 v40, v125, v49
	v_dot8c_i32_i4_e32 v41, v125, v47
	v_dot8c_i32_i4_e32 v42, v127, v49
	v_dot8c_i32_i4_e32 v43, v127, v47
	v_dot8c_i32_i4_e32 v44, v129, v49
	v_dot8c_i32_i4_e32 v45, v129, v47
	v_and_b32_e32 v78, 0xffff, v24
	v_lshrrev_b32_e32 v79, 16, v24
	v_lshl_add_u32 v78, v78, 7, v150
	v_lshl_add_u32 v79, v79, 7, v151
	s_mov_b32 m0, s78
	s_add_i32 s43, s78, 0x400
	global_load_lds_dwordx4 v78, s[50:51]
	s_mov_b32 m0, s43
	s_nop 0
	global_load_lds_dwordx4 v79, s[50:51]
	s_waitcnt vmcnt(8)
	v_add_u32_e32 v54, s98, v59
	v_add_u32_e32 v55, s98, v60
	v_add_u32_e32 v56, s98, v61
	v_add_u32_e32 v57, s98, v62
	ds_read_b64_tr_b4 v[46:47], v160 offset:256
	ds_read_b64_tr_b4 v[48:49], v160 offset:1280
	ds_read_b64_tr_b4 v[122:123], v54
	ds_read_b64_tr_b4 v[124:125], v55
	ds_read_b64_tr_b4 v[126:127], v56
	ds_read_b64_tr_b4 v[128:129], v57
	s_waitcnt lgkmcnt(6)
	v_dot8c_i32_i4_e32 v38, v130, v52
	v_dot8c_i32_i4_e32 v39, v130, v50
	v_dot8c_i32_i4_e32 v40, v132, v52
	v_dot8c_i32_i4_e32 v41, v132, v50
	v_dot8c_i32_i4_e32 v42, v134, v52
	v_dot8c_i32_i4_e32 v43, v134, v50
	v_dot8c_i32_i4_e32 v44, v136, v52
	v_dot8c_i32_i4_e32 v45, v136, v50
	v_dot8c_i32_i4_e32 v38, v131, v53
	v_dot8c_i32_i4_e32 v39, v131, v51
	v_dot8c_i32_i4_e32 v40, v133, v53
	v_dot8c_i32_i4_e32 v41, v133, v51
	v_dot8c_i32_i4_e32 v42, v135, v53
	v_dot8c_i32_i4_e32 v43, v135, v51
	v_dot8c_i32_i4_e32 v44, v137, v53
	v_dot8c_i32_i4_e32 v45, v137, v51
	v_and_b32_e32 v78, 0xffff, v25
	v_lshrrev_b32_e32 v79, 16, v25
	v_lshl_add_u32 v78, v78, 7, v150
	v_lshl_add_u32 v79, v79, 7, v151
	s_mov_b32 m0, s79
	s_add_i32 s43, s79, 0x400
	global_load_lds_dwordx4 v78, s[50:51]
	s_mov_b32 m0, s43
	s_nop 0
	global_load_lds_dwordx4 v79, s[50:51]
	s_waitcnt vmcnt(8)
	v_add_u32_e32 v54, s99, v59
	v_add_u32_e32 v55, s99, v60
	v_add_u32_e32 v56, s99, v61
	v_add_u32_e32 v57, s99, v62
	ds_read_b64_tr_b4 v[50:51], v160 offset:384
	ds_read_b64_tr_b4 v[52:53], v160 offset:1408
	ds_read_b64_tr_b4 v[130:131], v54
	ds_read_b64_tr_b4 v[132:133], v55
	ds_read_b64_tr_b4 v[134:135], v56
	ds_read_b64_tr_b4 v[136:137], v57
	s_waitcnt lgkmcnt(6)
	v_dot8c_i32_i4_e32 v38, v122, v48
	v_dot8c_i32_i4_e32 v39, v122, v46
	v_dot8c_i32_i4_e32 v40, v124, v48
	v_dot8c_i32_i4_e32 v41, v124, v46
	v_dot8c_i32_i4_e32 v42, v126, v48
	v_dot8c_i32_i4_e32 v43, v126, v46
	v_dot8c_i32_i4_e32 v44, v128, v48
	v_dot8c_i32_i4_e32 v45, v128, v46
	v_dot8c_i32_i4_e32 v38, v123, v49
	v_dot8c_i32_i4_e32 v39, v123, v47
	v_dot8c_i32_i4_e32 v40, v125, v49
	v_dot8c_i32_i4_e32 v41, v125, v47
	v_dot8c_i32_i4_e32 v42, v127, v49
	v_dot8c_i32_i4_e32 v43, v127, v47
	v_dot8c_i32_i4_e32 v44, v129, v49
	v_dot8c_i32_i4_e32 v45, v129, v47
	s_waitcnt lgkmcnt(15)
	v_and_b32_e32 v78, 0xffff, v26
	v_lshrrev_b32_e32 v79, 16, v26
	v_lshl_add_u32 v78, v78, 7, v150
	v_lshl_add_u32 v79, v79, 7, v151
	s_mov_b32 m0, s98
	s_add_i32 s43, s98, 0x400
	global_load_lds_dwordx4 v78, s[50:51]
	s_mov_b32 m0, s43
	s_nop 0
	global_load_lds_dwordx4 v79, s[50:51]
	s_waitcnt vmcnt(8)
	v_add_u32_e32 v54, s76, v59
	v_add_u32_e32 v55, s76, v60
	v_add_u32_e32 v56, s76, v61
	v_add_u32_e32 v57, s76, v62
	ds_read_b64_tr_b4 v[46:47], v160 offset:512
	ds_read_b64_tr_b4 v[48:49], v160 offset:1536
	ds_read_b64_tr_b4 v[122:123], v54
	ds_read_b64_tr_b4 v[124:125], v55
	ds_read_b64_tr_b4 v[126:127], v56
	ds_read_b64_tr_b4 v[128:129], v57
	s_waitcnt lgkmcnt(6)
	v_dot8c_i32_i4_e32 v38, v130, v52
	v_dot8c_i32_i4_e32 v39, v130, v50
	v_dot8c_i32_i4_e32 v40, v132, v52
	v_dot8c_i32_i4_e32 v41, v132, v50
	v_dot8c_i32_i4_e32 v42, v134, v52
	v_dot8c_i32_i4_e32 v43, v134, v50
	v_dot8c_i32_i4_e32 v44, v136, v52
	v_dot8c_i32_i4_e32 v45, v136, v50
	v_dot8c_i32_i4_e32 v38, v131, v53
	v_dot8c_i32_i4_e32 v39, v131, v51
	v_dot8c_i32_i4_e32 v40, v133, v53
	v_dot8c_i32_i4_e32 v41, v133, v51
	v_dot8c_i32_i4_e32 v42, v135, v53
	v_dot8c_i32_i4_e32 v43, v135, v51
	v_dot8c_i32_i4_e32 v44, v137, v53
	v_dot8c_i32_i4_e32 v45, v137, v51
	v_and_b32_e32 v78, 0xffff, v27
	v_lshrrev_b32_e32 v79, 16, v27
	v_lshl_add_u32 v78, v78, 7, v150
	v_lshl_add_u32 v79, v79, 7, v151
	s_mov_b32 m0, s99
	s_add_i32 s43, s99, 0x400
	global_load_lds_dwordx4 v78, s[50:51]
	s_mov_b32 m0, s43
	s_nop 0
	global_load_lds_dwordx4 v79, s[50:51]
	s_waitcnt vmcnt(8)
	v_add_u32_e32 v54, s77, v59
	v_add_u32_e32 v55, s77, v60
	v_add_u32_e32 v56, s77, v61
	v_add_u32_e32 v57, s77, v62
	ds_read_b64_tr_b4 v[50:51], v160 offset:640
	ds_read_b64_tr_b4 v[52:53], v160 offset:1664
	ds_read_b64_tr_b4 v[130:131], v54
	ds_read_b64_tr_b4 v[132:133], v55
	ds_read_b64_tr_b4 v[134:135], v56
	ds_read_b64_tr_b4 v[136:137], v57
	s_waitcnt lgkmcnt(6)
	v_dot8c_i32_i4_e32 v38, v122, v48
	v_dot8c_i32_i4_e32 v39, v122, v46
	v_dot8c_i32_i4_e32 v40, v124, v48
	v_dot8c_i32_i4_e32 v41, v124, v46
	v_dot8c_i32_i4_e32 v42, v126, v48
	v_dot8c_i32_i4_e32 v43, v126, v46
	v_dot8c_i32_i4_e32 v44, v128, v48
	v_dot8c_i32_i4_e32 v45, v128, v46
	v_dot8c_i32_i4_e32 v38, v123, v49
	v_dot8c_i32_i4_e32 v39, v123, v47
	v_dot8c_i32_i4_e32 v40, v125, v49
	v_dot8c_i32_i4_e32 v41, v125, v47
	v_dot8c_i32_i4_e32 v42, v127, v49
	v_dot8c_i32_i4_e32 v43, v127, v47
	v_dot8c_i32_i4_e32 v44, v129, v49
	v_dot8c_i32_i4_e32 v45, v129, v47
	s_waitcnt lgkmcnt(15)
; __device__ __forceinline__ void peer_v_tokens(int j, const LAS unsigned short* EL, const LAS unsigned char* AL  , const LAS float* ASC  , const LAS int* SAL  , ...
;     ...
; #pragma unroll
;         for (int m = 0; m < 2; ++m) {
;             const int idx = lane + 64 * m, tau = idx >> 4, sr = idx & 15, k = 16 * (sr & 7) + 2 * tau + (sr >> 3);
;             const int aq = (int)*(const LAS signed char*)(AL + tl * 128 + k); const int tq = aq + 8;
;             const unsigned lo = (((unsigned)tq & 15u) ^ 8u) * 0x11111111u, hi = ((unsigned)(tq >> 4) & 15u) * 0x11111111u;
;             typedef unsigned u2v __attribute__((ext_vector_type(2)));
;             u2v l2; l2.x = lo; l2.y = lo; u2v h2; h2.x = hi; h2.y = hi;
;             *(LAS u2v*)(ATL + 8 * idx) = l2; *(LAS u2v*)(ATL + 1024 + 8 * idx) = h2;
;         }
;         const float asc = ASC[tl]; const int sa = SAL[tl];
;         CFENCE();
;         int accH[4], accL[4];
; #pragma unroll
;         for (int st = 0; st < 16; ++st) {
;             const int p = st >> 2, q = st & 3;
;             if (st < 14) VDMA(st + 2, (st + 2) % 3);
;             if (st < 14) asm volatile("s_waitcnt vmcnt(8)" ::: "memory");
;             else if (st == 14) asm volatile("s_waitcnt vmcnt(4)" ::: "memory");
;             else asm volatile("s_waitcnt vmcnt(0)" ::: "memory");
;             if (q == 0) {
; #pragma unroll
;                 for (int r = 0; r < 4; ++r) { accH[r] = 0; accL[r] = 0; } }
; #pragma unroll
;             for (int tp = 0; tp < 2; ++tp) {
;                 const v2i ao = TR4(ATL + (2 * q + tp) * 128 + 8 * s16), ah = TR4(ATL + 1024 + (2 * q + tp) * 128 + 8 * s16);
; #pragma unroll
;                 for (int r = 0; r < 4; ++r) {
;                     const v2i d = TR4(ldsb + BUF[st % 3] + 2048 * tp + roff[r]);
;                     accH[r] = __builtin_amdgcn_sdot8(d.x, ah.x, accH[r], false); accH[r] = __builtin_amdgcn_sdot8(d.y, ah.y, accH[r], false);
;                     accL[r] = __builtin_amdgcn_sdot8(d.x, ao.x, accL[r], false); accL[r] = __builtin_amdgcn_sdot8(d.y, ao.y, accL[r], false);
;                 }
;             }
;             asm volatile("s_waitcnt lgkmcnt(0)" ::: "memory");
;             if (q == 3) {
; #pragma unroll
;                 for (int r = 0; r < 4; ++r) STASH[256 * p + 16 * (grp + 4 * r) + pc] = f2bf(asc * (float)(2 * ((accH[r] << 4) + accL[r]) + sa));
;             }
	v_add_u32_e32 v143, 8, v139
	v_and_b32_e32 v142, 15, v143
	v_xor_b32_e32 v142, 8, v142
	v_bfe_u32 v144, v143, 4, 4
	v_mul_lo_u32 v142, v142, s92
	v_mul_lo_u32 v144, v144, s92
	v_mov_b32_e32 v143, v142
	v_mov_b32_e32 v145, v144
	ds_write2st64_b64 v159, v[142:143], v[144:145] offset1:2
	v_and_b32_e32 v78, 0xffff, v28
	v_lshrrev_b32_e32 v79, 16, v28
	v_lshl_add_u32 v78, v78, 7, v150
	v_lshl_add_u32 v79, v79, 7, v151
	s_mov_b32 m0, s76
	s_add_i32 s43, s76, 0x400
	global_load_lds_dwordx4 v78, s[50:51]
	s_mov_b32 m0, s43
	s_nop 0
	global_load_lds_dwordx4 v79, s[50:51]
	s_waitcnt vmcnt(8)
	v_add_u32_e32 v54, s78, v59
	v_add_u32_e32 v55, s78, v60
	v_add_u32_e32 v56, s78, v61
	v_add_u32_e32 v57, s78, v62
	ds_read_b64_tr_b4 v[46:47], v160 offset:768
	ds_read_b64_tr_b4 v[48:49], v160 offset:1792
	ds_read_b64_tr_b4 v[122:123], v54
	ds_read_b64_tr_b4 v[124:125], v55
	ds_read_b64_tr_b4 v[126:127], v56
	ds_read_b64_tr_b4 v[128:129], v57
	s_waitcnt lgkmcnt(7)
	v_dot8c_i32_i4_e32 v38, v130, v52
	v_dot8c_i32_i4_e32 v39, v130, v50
	v_dot8c_i32_i4_e32 v40, v132, v52
	v_dot8c_i32_i4_e32 v41, v132, v50
	v_dot8c_i32_i4_e32 v42, v134, v52
	v_dot8c_i32_i4_e32 v43, v134, v50
	v_dot8c_i32_i4_e32 v44, v136, v52
	v_dot8c_i32_i4_e32 v45, v136, v50
	v_dot8c_i32_i4_e32 v38, v131, v53
	v_dot8c_i32_i4_e32 v39, v131, v51
	v_dot8c_i32_i4_e32 v40, v133, v53
	v_dot8c_i32_i4_e32 v41, v133, v51
	v_dot8c_i32_i4_e32 v42, v135, v53
	v_dot8c_i32_i4_e32 v43, v135, v51
	v_dot8c_i32_i4_e32 v44, v137, v53
	v_dot8c_i32_i4_e32 v45, v137, v51
	v_and_b32_e32 v78, 0xffff, v29
	v_lshrrev_b32_e32 v79, 16, v29
	v_lshl_add_u32 v78, v78, 7, v150
	v_lshl_add_u32 v79, v79, 7, v151
	s_mov_b32 m0, s77
	s_add_i32 s43, s77, 0x400
	global_load_lds_dwordx4 v78, s[50:51]
	s_mov_b32 m0, s43
	s_nop 0
	global_load_lds_dwordx4 v79, s[50:51]
	s_waitcnt vmcnt(8)
	v_add_u32_e32 v54, s79, v59
	v_add_u32_e32 v55, s79, v60
	v_add_u32_e32 v56, s79, v61
	v_add_u32_e32 v57, s79, v62
	ds_read_b64_tr_b4 v[50:51], v160 offset:896
	ds_read_b64_tr_b4 v[52:53], v160 offset:1920
	ds_read_b64_tr_b4 v[130:131], v54
	ds_read_b64_tr_b4 v[132:133], v55
	ds_read_b64_tr_b4 v[134:135], v56
	ds_read_b64_tr_b4 v[136:137], v57
	s_waitcnt lgkmcnt(6)
	v_dot8c_i32_i4_e32 v38, v122, v48
	v_dot8c_i32_i4_e32 v39, v122, v46
	v_dot8c_i32_i4_e32 v40, v124, v48
	v_dot8c_i32_i4_e32 v41, v124, v46
	v_dot8c_i32_i4_e32 v42, v126, v48
	v_dot8c_i32_i4_e32 v43, v126, v46
	v_dot8c_i32_i4_e32 v44, v128, v48
	v_dot8c_i32_i4_e32 v45, v128, v46
	v_dot8c_i32_i4_e32 v38, v123, v49
	v_dot8c_i32_i4_e32 v39, v123, v47
	v_dot8c_i32_i4_e32 v40, v125, v49
	v_dot8c_i32_i4_e32 v41, v125, v47
	v_dot8c_i32_i4_e32 v42, v127, v49
	v_dot8c_i32_i4_e32 v43, v127, v47
	v_dot8c_i32_i4_e32 v44, v129, v49
	v_dot8c_i32_i4_e32 v45, v129, v47
	v_and_b32_e32 v78, 0xffff, v30
	v_lshrrev_b32_e32 v79, 16, v30
	v_lshl_add_u32 v78, v78, 7, v150
	v_lshl_add_u32 v79, v79, 7, v151
	s_mov_b32 m0, s78
	s_add_i32 s43, s78, 0x400
	global_load_lds_dwordx4 v78, s[50:51]
	s_mov_b32 m0, s43
	s_nop 0
	global_load_lds_dwordx4 v79, s[50:51]
	s_waitcnt vmcnt(8)
	v_add_u32_e32 v54, s98, v59
	v_add_u32_e32 v55, s98, v60
	v_add_u32_e32 v56, s98, v61
	v_add_u32_e32 v57, s98, v62
	ds_read_b64_tr_b4 v[46:47], v160
	ds_read_b64_tr_b4 v[48:49], v160 offset:1024
	ds_read_b64_tr_b4 v[122:123], v54
	ds_read_b64_tr_b4 v[124:125], v55
	ds_read_b64_tr_b4 v[126:127], v56
	ds_read_b64_tr_b4 v[128:129], v57
	s_waitcnt lgkmcnt(6)
	v_dot8c_i32_i4_e32 v38, v130, v52
	v_dot8c_i32_i4_e32 v39, v130, v50
	v_dot8c_i32_i4_e32 v40, v132, v52
	v_dot8c_i32_i4_e32 v41, v132, v50
	v_dot8c_i32_i4_e32 v42, v134, v52
	v_dot8c_i32_i4_e32 v43, v134, v50
	v_dot8c_i32_i4_e32 v44, v136, v52
	v_dot8c_i32_i4_e32 v45, v136, v50
	v_dot8c_i32_i4_e32 v38, v131, v53
	v_dot8c_i32_i4_e32 v39, v131, v51
	v_dot8c_i32_i4_e32 v40, v133, v53
	v_dot8c_i32_i4_e32 v41, v133, v51
	v_dot8c_i32_i4_e32 v42, v135, v53
	v_dot8c_i32_i4_e32 v43, v135, v51
	v_dot8c_i32_i4_e32 v44, v137, v53
	v_dot8c_i32_i4_e32 v45, v137, v51
	s_nop 3
	s_waitcnt lgkmcnt(15)
	v_lshlrev_b32_e32 v38, 5, v38
	v_lshlrev_b32_e32 v39, 1, v39
	v_add3_u32 v38, v39, v229, v38
	v_cvt_f32_i32_e32 v38, v38
	v_mul_f32_e32 v38, v228, v38
	v_lshlrev_b32_e32 v40, 5, v40
	v_lshlrev_b32_e32 v41, 1, v41
	v_add3_u32 v40, v41, v229, v40
	v_cvt_f32_i32_e32 v40, v40
	v_mul_f32_e32 v40, v228, v40
	v_lshlrev_b32_e32 v42, 5, v42
	v_lshlrev_b32_e32 v43, 1, v43
	v_add3_u32 v42, v43, v229, v42
	v_cvt_f32_i32_e32 v42, v42
	v_mul_f32_e32 v42, v228, v42
	v_lshlrev_b32_e32 v44, 5, v44
	v_lshlrev_b32_e32 v45, 1, v45
	v_add3_u32 v44, v45, v229, v44
	v_cvt_f32_i32_e32 v44, v44
	v_mul_f32_e32 v44, v228, v44
	v_cvt_pk_bf16_f32 v166, v38, v40
	v_cvt_pk_bf16_f32 v167, v42, v44
	v_add_u32_e32 v147, 8, v140
	v_and_b32_e32 v146, 15, v147
	v_xor_b32_e32 v146, 8, v146
	v_bfe_u32 v148, v147, 4, 4
	v_mul_lo_u32 v146, v146, s92
	v_mul_lo_u32 v148, v148, s92
	v_mov_b32_e32 v147, v146
	v_mov_b32_e32 v149, v148
	ds_write2st64_b64 v77, v[146:147], v[148:149] offset1:2
	v_mov_b32_e32 v138, v74
	ds_read_u8 v139, v138
	v_mov_b32_e32 v141, v73
	ds_read_u8 v140, v141
	s_add_i32 s43, s67, 32
	v_mov_b32_e32 v138, s43
	ds_read2st64_b32 v[228:229], v138 offset1:1
	ds_read_b128 v[18:21], v227
	ds_read_b128 v[22:25], v227 offset:16
	v_add_u32_e32 v152, 0x600000, v63
	v_add_u32_e32 v153, 0x600000, v64
	v_mov_b32_e32 v38, 0
	v_mov_b32_e32 v39, 0
	v_mov_b32_e32 v40, 0
	v_mov_b32_e32 v41, 0
	v_mov_b32_e32 v42, 0
	v_mov_b32_e32 v43, 0
	v_mov_b32_e32 v44, 0
	v_mov_b32_e32 v45, 0
	v_and_b32_e32 v78, 0xffff, v31
	v_lshrrev_b32_e32 v79, 16, v31
	v_lshl_add_u32 v78, v78, 7, v150
	v_lshl_add_u32 v79, v79, 7, v151
	s_mov_b32 m0, s79
	s_add_i32 s43, s79, 0x400
	global_load_lds_dwordx4 v78, s[50:51]
	s_mov_b32 m0, s43
	s_nop 0
	global_load_lds_dwordx4 v79, s[50:51]
	s_waitcnt vmcnt(8)
; #define TR4(p_) __builtin_amdgcn_ds_read_tr4_b64_v2i32((LAS v2i*)(p_))
; #define VDMA(st_, k_) do { _Pragma("unroll") for (int i_ = 0; i_ < 4; ++i_) { \
;         const unsigned off_ = (unsigned)((st_) >> 2) * (16384u * 128u) + (PE_ID(E, 4 * ((st_) & 3) + i_) << 7) + ((i_ & 1) ? cx1 : cx0); \
;         __builtin_amdgcn_global_load_lds((const unsigned*)(V4 + off_), (LAS unsigned*)(ldsb + BUF[k_] + 1024 * i_), 16, 0, 0); } } while (0)
; __device__ __forceinline__ void peer_v_tokens(int j, const LAS unsigned short* EL, const LAS unsigned char* AL  , const LAS float* ASC  , const LAS int* SAL  , ...
;     ...
;         for (int st = 0; st < 16; ++st) {
;             const int p = st >> 2, q = st & 3;
;             if (st < 14) VDMA(st + 2, (st + 2) % 3);
;             if (st < 14) asm volatile("s_waitcnt vmcnt(8)" ::: "memory");
;             else if (st == 14) asm volatile("s_waitcnt vmcnt(4)" ::: "memory");
;             else asm volatile("s_waitcnt vmcnt(0)" ::: "memory");
;             if (q == 0) {
; #pragma unroll
;                 for (int r = 0; r < 4; ++r) { accH[r] = 0; accL[r] = 0; } }
; #pragma unroll
;             for (int tp = 0; tp < 2; ++tp) {
;                 const v2i ao = TR4(ATL + (2 * q + tp) * 128 + 8 * s16), ah = TR4(ATL + 1024 + (2 * q + tp) * 128 + 8 * s16);
; #pragma unroll
;                 for (int r = 0; r < 4; ++r) {
;                     const v2i d = TR4(ldsb + BUF[st % 3] + 2048 * tp + roff[r]);
;                     accH[r] = __builtin_amdgcn_sdot8(d.x, ah.x, accH[r], false); accH[r] = __builtin_amdgcn_sdot8(d.y, ah.y, accH[r], false);
;                     accL[r] = __builtin_amdgcn_sdot8(d.x, ao.x, accL[r], false); accL[r] = __builtin_amdgcn_sdot8(d.y, ao.y, accL[r], false);
;                 }
;             }
	v_add_u32_e32 v54, s99, v59
	v_add_u32_e32 v55, s99, v60
	v_add_u32_e32 v56, s99, v61
	v_add_u32_e32 v57, s99, v62
	ds_read_b64_tr_b4 v[50:51], v160 offset:128
	ds_read_b64_tr_b4 v[52:53], v160 offset:1152
	ds_read_b64_tr_b4 v[130:131], v54
	ds_read_b64_tr_b4 v[132:133], v55
	ds_read_b64_tr_b4 v[134:135], v56
	ds_read_b64_tr_b4 v[136:137], v57
	s_waitcnt lgkmcnt(12)
	v_dot8c_i32_i4_e32 v38, v122, v48
	v_dot8c_i32_i4_e32 v39, v122, v46
	v_dot8c_i32_i4_e32 v40, v124, v48
	v_dot8c_i32_i4_e32 v41, v124, v46
	v_dot8c_i32_i4_e32 v42, v126, v48
	v_dot8c_i32_i4_e32 v43, v126, v46
	v_dot8c_i32_i4_e32 v44, v128, v48
	v_dot8c_i32_i4_e32 v45, v128, v46
	v_dot8c_i32_i4_e32 v38, v123, v49
	v_dot8c_i32_i4_e32 v39, v123, v47
	v_dot8c_i32_i4_e32 v40, v125, v49
	v_dot8c_i32_i4_e32 v41, v125, v47
	v_dot8c_i32_i4_e32 v42, v127, v49
	v_dot8c_i32_i4_e32 v43, v127, v47
	v_dot8c_i32_i4_e32 v44, v129, v49
	v_dot8c_i32_i4_e32 v45, v129, v47
	v_and_b32_e32 v78, 0xffff, v32
	v_lshrrev_b32_e32 v79, 16, v32
	v_lshl_add_u32 v78, v78, 7, v150
	v_lshl_add_u32 v79, v79, 7, v151
	s_mov_b32 m0, s98
	s_add_i32 s43, s98, 0x400
	global_load_lds_dwordx4 v78, s[50:51]
	s_mov_b32 m0, s43
	s_nop 0
	global_load_lds_dwordx4 v79, s[50:51]
	s_waitcnt vmcnt(8)
	v_add_u32_e32 v54, s76, v59
	v_add_u32_e32 v55, s76, v60
	v_add_u32_e32 v56, s76, v61
	v_add_u32_e32 v57, s76, v62
	ds_read_b64_tr_b4 v[46:47], v160 offset:256
	ds_read_b64_tr_b4 v[48:49], v160 offset:1280
	ds_read_b64_tr_b4 v[122:123], v54
	ds_read_b64_tr_b4 v[124:125], v55
	ds_read_b64_tr_b4 v[126:127], v56
	ds_read_b64_tr_b4 v[128:129], v57
	s_waitcnt lgkmcnt(6)
	v_dot8c_i32_i4_e32 v38, v130, v52
	v_dot8c_i32_i4_e32 v39, v130, v50
	v_dot8c_i32_i4_e32 v40, v132, v52
	v_dot8c_i32_i4_e32 v41, v132, v50
	v_dot8c_i32_i4_e32 v42, v134, v52
	v_dot8c_i32_i4_e32 v43, v134, v50
	v_dot8c_i32_i4_e32 v44, v136, v52
	v_dot8c_i32_i4_e32 v45, v136, v50
	v_dot8c_i32_i4_e32 v38, v131, v53
	v_dot8c_i32_i4_e32 v39, v131, v51
	v_dot8c_i32_i4_e32 v40, v133, v53
	v_dot8c_i32_i4_e32 v41, v133, v51
	v_dot8c_i32_i4_e32 v42, v135, v53
	v_dot8c_i32_i4_e32 v43, v135, v51
	v_dot8c_i32_i4_e32 v44, v137, v53
	v_dot8c_i32_i4_e32 v45, v137, v51
	v_and_b32_e32 v78, 0xffff, v33
	v_lshrrev_b32_e32 v79, 16, v33
	v_lshl_add_u32 v78, v78, 7, v150
	v_lshl_add_u32 v79, v79, 7, v151
	s_mov_b32 m0, s99
	s_add_i32 s43, s99, 0x400
	global_load_lds_dwordx4 v78, s[50:51]
	s_mov_b32 m0, s43
	s_nop 0
	global_load_lds_dwordx4 v79, s[50:51]
	s_waitcnt vmcnt(8)
	v_add_u32_e32 v54, s77, v59
	v_add_u32_e32 v55, s77, v60
	v_add_u32_e32 v56, s77, v61
	v_add_u32_e32 v57, s77, v62
	ds_read_b64_tr_b4 v[50:51], v160 offset:384
	ds_read_b64_tr_b4 v[52:53], v160 offset:1408
	ds_read_b64_tr_b4 v[130:131], v54
	ds_read_b64_tr_b4 v[132:133], v55
	ds_read_b64_tr_b4 v[134:135], v56
	ds_read_b64_tr_b4 v[136:137], v57
	s_waitcnt lgkmcnt(6)
	v_dot8c_i32_i4_e32 v38, v122, v48
	v_dot8c_i32_i4_e32 v39, v122, v46
	v_dot8c_i32_i4_e32 v40, v124, v48
	v_dot8c_i32_i4_e32 v41, v124, v46
	v_dot8c_i32_i4_e32 v42, v126, v48
	v_dot8c_i32_i4_e32 v43, v126, v46
	v_dot8c_i32_i4_e32 v44, v128, v48
	v_dot8c_i32_i4_e32 v45, v128, v46
	v_dot8c_i32_i4_e32 v38, v123, v49
	v_dot8c_i32_i4_e32 v39, v123, v47
	v_dot8c_i32_i4_e32 v40, v125, v49
	v_dot8c_i32_i4_e32 v41, v125, v47
	v_dot8c_i32_i4_e32 v42, v127, v49
	v_dot8c_i32_i4_e32 v43, v127, v47
	v_dot8c_i32_i4_e32 v44, v129, v49
	v_dot8c_i32_i4_e32 v45, v129, v47
	s_waitcnt lgkmcnt(15)
	v_and_b32_e32 v78, 0xffff, v18
	v_lshrrev_b32_e32 v79, 16, v18
	v_lshl_add_u32 v78, v78, 7, v152
	v_lshl_add_u32 v79, v79, 7, v153
	s_mov_b32 m0, s76
	s_add_i32 s43, s76, 0x400
	global_load_lds_dwordx4 v78, s[50:51]
	s_mov_b32 m0, s43
	s_nop 0
	global_load_lds_dwordx4 v79, s[50:51]
	s_waitcnt vmcnt(8)
	v_add_u32_e32 v54, s78, v59
	v_add_u32_e32 v55, s78, v60
	v_add_u32_e32 v56, s78, v61
	v_add_u32_e32 v57, s78, v62
	ds_read_b64_tr_b4 v[46:47], v160 offset:512
	ds_read_b64_tr_b4 v[48:49], v160 offset:1536
	ds_read_b64_tr_b4 v[122:123], v54
	ds_read_b64_tr_b4 v[124:125], v55
	ds_read_b64_tr_b4 v[126:127], v56
	ds_read_b64_tr_b4 v[128:129], v57
	s_waitcnt lgkmcnt(6)
	v_dot8c_i32_i4_e32 v38, v130, v52
	v_dot8c_i32_i4_e32 v39, v130, v50
	v_dot8c_i32_i4_e32 v40, v132, v52
	v_dot8c_i32_i4_e32 v41, v132, v50
	v_dot8c_i32_i4_e32 v42, v134, v52
	v_dot8c_i32_i4_e32 v43, v134, v50
	v_dot8c_i32_i4_e32 v44, v136, v52
	v_dot8c_i32_i4_e32 v45, v136, v50
	v_dot8c_i32_i4_e32 v38, v131, v53
	v_dot8c_i32_i4_e32 v39, v131, v51
	v_dot8c_i32_i4_e32 v40, v133, v53
	v_dot8c_i32_i4_e32 v41, v133, v51
	v_dot8c_i32_i4_e32 v42, v135, v53
	v_dot8c_i32_i4_e32 v43, v135, v51
	v_dot8c_i32_i4_e32 v44, v137, v53
	v_dot8c_i32_i4_e32 v45, v137, v51
	v_and_b32_e32 v78, 0xffff, v19
	v_lshrrev_b32_e32 v79, 16, v19
	v_lshl_add_u32 v78, v78, 7, v152
	v_lshl_add_u32 v79, v79, 7, v153
	s_mov_b32 m0, s77
	s_add_i32 s43, s77, 0x400
	global_load_lds_dwordx4 v78, s[50:51]
	s_mov_b32 m0, s43
	s_nop 0
	global_load_lds_dwordx4 v79, s[50:51]
	s_waitcnt vmcnt(8)
	v_add_u32_e32 v54, s79, v59
	v_add_u32_e32 v55, s79, v60
	v_add_u32_e32 v56, s79, v61
	v_add_u32_e32 v57, s79, v62
	ds_read_b64_tr_b4 v[50:51], v160 offset:640
	ds_read_b64_tr_b4 v[52:53], v160 offset:1664
	ds_read_b64_tr_b4 v[130:131], v54
	ds_read_b64_tr_b4 v[132:133], v55
	ds_read_b64_tr_b4 v[134:135], v56
	ds_read_b64_tr_b4 v[136:137], v57
	s_waitcnt lgkmcnt(6)
	v_dot8c_i32_i4_e32 v38, v122, v48
	v_dot8c_i32_i4_e32 v39, v122, v46
	v_dot8c_i32_i4_e32 v40, v124, v48
	v_dot8c_i32_i4_e32 v41, v124, v46
	v_dot8c_i32_i4_e32 v42, v126, v48
	v_dot8c_i32_i4_e32 v43, v126, v46
	v_dot8c_i32_i4_e32 v44, v128, v48
	v_dot8c_i32_i4_e32 v45, v128, v46
	v_dot8c_i32_i4_e32 v38, v123, v49
	v_dot8c_i32_i4_e32 v39, v123, v47
	v_dot8c_i32_i4_e32 v40, v125, v49
	v_dot8c_i32_i4_e32 v41, v125, v47
	v_dot8c_i32_i4_e32 v42, v127, v49
	v_dot8c_i32_i4_e32 v43, v127, v47
	v_dot8c_i32_i4_e32 v44, v129, v49
	v_dot8c_i32_i4_e32 v45, v129, v47
	s_waitcnt lgkmcnt(15)
; __device__ __forceinline__ void peer_v_tokens(int j, const LAS unsigned short* EL, const LAS unsigned char* AL  , const LAS float* ASC  , const LAS int* SAL  , ...
;     ...
; #pragma unroll
;         for (int m = 0; m < 2; ++m) {
;             const int idx = lane + 64 * m, tau = idx >> 4, sr = idx & 15, k = 16 * (sr & 7) + 2 * tau + (sr >> 3);
;             const int aq = (int)*(const LAS signed char*)(AL + tl * 128 + k); const int tq = aq + 8;
;             const unsigned lo = (((unsigned)tq & 15u) ^ 8u) * 0x11111111u, hi = ((unsigned)(tq >> 4) & 15u) * 0x11111111u;
;             typedef unsigned u2v __attribute__((ext_vector_type(2)));
;             u2v l2; l2.x = lo; l2.y = lo; u2v h2; h2.x = hi; h2.y = hi;
;             *(LAS u2v*)(ATL + 8 * idx) = l2; *(LAS u2v*)(ATL + 1024 + 8 * idx) = h2;
;         }
;         const float asc = ASC[tl]; const int sa = SAL[tl];
;         CFENCE();
;         int accH[4], accL[4];
; #pragma unroll
;         for (int st = 0; st < 16; ++st) {
;             const int p = st >> 2, q = st & 3;
;             if (st < 14) VDMA(st + 2, (st + 2) % 3);
;             if (st < 14) asm volatile("s_waitcnt vmcnt(8)" ::: "memory");
;             else if (st == 14) asm volatile("s_waitcnt vmcnt(4)" ::: "memory");
;             else asm volatile("s_waitcnt vmcnt(0)" ::: "memory");
;             if (q == 0) {
; #pragma unroll
;                 for (int r = 0; r < 4; ++r) { accH[r] = 0; accL[r] = 0; } }
; #pragma unroll
;             for (int tp = 0; tp < 2; ++tp) {
;                 const v2i ao = TR4(ATL + (2 * q + tp) * 128 + 8 * s16), ah = TR4(ATL + 1024 + (2 * q + tp) * 128 + 8 * s16);
; #pragma unroll
;                 for (int r = 0; r < 4; ++r) {
;                     const v2i d = TR4(ldsb + BUF[st % 3] + 2048 * tp + roff[r]);
;                     accH[r] = __builtin_amdgcn_sdot8(d.x, ah.x, accH[r], false); accH[r] = __builtin_amdgcn_sdot8(d.y, ah.y, accH[r], false);
;                     accL[r] = __builtin_amdgcn_sdot8(d.x, ao.x, accL[r], false); accL[r] = __builtin_amdgcn_sdot8(d.y, ao.y, accL[r], false);
;                 }
;             }
;             asm volatile("s_waitcnt lgkmcnt(0)" ::: "memory");
;             if (q == 3) {
; #pragma unroll
;                 for (int r = 0; r < 4; ++r) STASH[256 * p + 16 * (grp + 4 * r) + pc] = f2bf(asc * (float)(2 * ((accH[r] << 4) + accL[r]) + sa));
;             }
	v_add_u32_e32 v143, 8, v139
	v_and_b32_e32 v142, 15, v143
	v_xor_b32_e32 v142, 8, v142
	v_bfe_u32 v144, v143, 4, 4
	v_mul_lo_u32 v142, v142, s92
	v_mul_lo_u32 v144, v144, s92
	v_mov_b32_e32 v143, v142
	v_mov_b32_e32 v145, v144
	ds_write2st64_b64 v159, v[142:143], v[144:145] offset1:2
	v_and_b32_e32 v78, 0xffff, v20
	v_lshrrev_b32_e32 v79, 16, v20
	v_lshl_add_u32 v78, v78, 7, v152
	v_lshl_add_u32 v79, v79, 7, v153
	s_mov_b32 m0, s78
	s_add_i32 s43, s78, 0x400
	global_load_lds_dwordx4 v78, s[50:51]
	s_mov_b32 m0, s43
	s_nop 0
	global_load_lds_dwordx4 v79, s[50:51]
	s_waitcnt vmcnt(8)
	v_add_u32_e32 v54, s98, v59
	v_add_u32_e32 v55, s98, v60
	v_add_u32_e32 v56, s98, v61
	v_add_u32_e32 v57, s98, v62
	ds_read_b64_tr_b4 v[46:47], v160 offset:768
	ds_read_b64_tr_b4 v[48:49], v160 offset:1792
	ds_read_b64_tr_b4 v[122:123], v54
	ds_read_b64_tr_b4 v[124:125], v55
	ds_read_b64_tr_b4 v[126:127], v56
	ds_read_b64_tr_b4 v[128:129], v57
	s_waitcnt lgkmcnt(7)
	v_dot8c_i32_i4_e32 v38, v130, v52
	v_dot8c_i32_i4_e32 v39, v130, v50
	v_dot8c_i32_i4_e32 v40, v132, v52
	v_dot8c_i32_i4_e32 v41, v132, v50
	v_dot8c_i32_i4_e32 v42, v134, v52
	v_dot8c_i32_i4_e32 v43, v134, v50
	v_dot8c_i32_i4_e32 v44, v136, v52
	v_dot8c_i32_i4_e32 v45, v136, v50
	v_dot8c_i32_i4_e32 v38, v131, v53
	v_dot8c_i32_i4_e32 v39, v131, v51
	v_dot8c_i32_i4_e32 v40, v133, v53
	v_dot8c_i32_i4_e32 v41, v133, v51
	v_dot8c_i32_i4_e32 v42, v135, v53
	v_dot8c_i32_i4_e32 v43, v135, v51
	v_dot8c_i32_i4_e32 v44, v137, v53
	v_dot8c_i32_i4_e32 v45, v137, v51
	v_and_b32_e32 v78, 0xffff, v21
	v_lshrrev_b32_e32 v79, 16, v21
	v_lshl_add_u32 v78, v78, 7, v152
	v_lshl_add_u32 v79, v79, 7, v153
	s_mov_b32 m0, s79
	s_add_i32 s43, s79, 0x400
	global_load_lds_dwordx4 v78, s[50:51]
	s_mov_b32 m0, s43
	s_nop 0
	global_load_lds_dwordx4 v79, s[50:51]
	s_waitcnt vmcnt(8)
	v_add_u32_e32 v54, s99, v59
	v_add_u32_e32 v55, s99, v60
	v_add_u32_e32 v56, s99, v61
	v_add_u32_e32 v57, s99, v62
	ds_read_b64_tr_b4 v[50:51], v160 offset:896
	ds_read_b64_tr_b4 v[52:53], v160 offset:1920
	ds_read_b64_tr_b4 v[130:131], v54
	ds_read_b64_tr_b4 v[132:133], v55
	ds_read_b64_tr_b4 v[134:135], v56
	ds_read_b64_tr_b4 v[136:137], v57
	s_waitcnt lgkmcnt(6)
	v_dot8c_i32_i4_e32 v38, v122, v48
	v_dot8c_i32_i4_e32 v39, v122, v46
	v_dot8c_i32_i4_e32 v40, v124, v48
	v_dot8c_i32_i4_e32 v41, v124, v46
	v_dot8c_i32_i4_e32 v42, v126, v48
	v_dot8c_i32_i4_e32 v43, v126, v46
	v_dot8c_i32_i4_e32 v44, v128, v48
	v_dot8c_i32_i4_e32 v45, v128, v46
	v_dot8c_i32_i4_e32 v38, v123, v49
	v_dot8c_i32_i4_e32 v39, v123, v47
	v_dot8c_i32_i4_e32 v40, v125, v49
	v_dot8c_i32_i4_e32 v41, v125, v47
	v_dot8c_i32_i4_e32 v42, v127, v49
	v_dot8c_i32_i4_e32 v43, v127, v47
	v_dot8c_i32_i4_e32 v44, v129, v49
	v_dot8c_i32_i4_e32 v45, v129, v47
	v_and_b32_e32 v78, 0xffff, v22
	v_lshrrev_b32_e32 v79, 16, v22
	v_lshl_add_u32 v78, v78, 7, v152
	v_lshl_add_u32 v79, v79, 7, v153
	s_mov_b32 m0, s98
	s_add_i32 s43, s98, 0x400
	global_load_lds_dwordx4 v78, s[50:51]
	s_mov_b32 m0, s43
	s_nop 0
	global_load_lds_dwordx4 v79, s[50:51]
	s_waitcnt vmcnt(8)
	v_add_u32_e32 v54, s76, v59
	v_add_u32_e32 v55, s76, v60
	v_add_u32_e32 v56, s76, v61
	v_add_u32_e32 v57, s76, v62
	ds_read_b64_tr_b4 v[46:47], v160
	ds_read_b64_tr_b4 v[48:49], v160 offset:1024
	ds_read_b64_tr_b4 v[122:123], v54
	ds_read_b64_tr_b4 v[124:125], v55
	ds_read_b64_tr_b4 v[126:127], v56
	ds_read_b64_tr_b4 v[128:129], v57
	s_waitcnt lgkmcnt(6)
	v_dot8c_i32_i4_e32 v38, v130, v52
	v_dot8c_i32_i4_e32 v39, v130, v50
	v_dot8c_i32_i4_e32 v40, v132, v52
	v_dot8c_i32_i4_e32 v41, v132, v50
	v_dot8c_i32_i4_e32 v42, v134, v52
	v_dot8c_i32_i4_e32 v43, v134, v50
	v_dot8c_i32_i4_e32 v44, v136, v52
	v_dot8c_i32_i4_e32 v45, v136, v50
	v_dot8c_i32_i4_e32 v38, v131, v53
	v_dot8c_i32_i4_e32 v39, v131, v51
	v_dot8c_i32_i4_e32 v40, v133, v53
	v_dot8c_i32_i4_e32 v41, v133, v51
	v_dot8c_i32_i4_e32 v42, v135, v53
	v_dot8c_i32_i4_e32 v43, v135, v51
	v_dot8c_i32_i4_e32 v44, v137, v53
	v_dot8c_i32_i4_e32 v45, v137, v51
	s_nop 3
	s_waitcnt lgkmcnt(15)
	v_lshlrev_b32_e32 v38, 5, v38
	v_lshlrev_b32_e32 v39, 1, v39
	v_add3_u32 v38, v39, v229, v38
	v_cvt_f32_i32_e32 v38, v38
	v_mul_f32_e32 v38, v228, v38
	v_lshlrev_b32_e32 v40, 5, v40
	v_lshlrev_b32_e32 v41, 1, v41
	v_add3_u32 v40, v41, v229, v40
	v_cvt_f32_i32_e32 v40, v40
	v_mul_f32_e32 v40, v228, v40
	v_lshlrev_b32_e32 v42, 5, v42
	v_lshlrev_b32_e32 v43, 1, v43
	v_add3_u32 v42, v43, v229, v42
	v_cvt_f32_i32_e32 v42, v42
	v_mul_f32_e32 v42, v228, v42
	v_lshlrev_b32_e32 v44, 5, v44
	v_lshlrev_b32_e32 v45, 1, v45
	v_add3_u32 v44, v45, v229, v44
	v_cvt_f32_i32_e32 v44, v44
	v_mul_f32_e32 v44, v228, v44
	v_cvt_pk_bf16_f32 v174, v38, v40
	v_cvt_pk_bf16_f32 v175, v42, v44
	v_add_u32_e32 v147, 8, v140
	v_and_b32_e32 v146, 15, v147
	v_xor_b32_e32 v146, 8, v146
	v_bfe_u32 v148, v147, 4, 4
	v_mul_lo_u32 v146, v146, s92
	v_mul_lo_u32 v148, v148, s92
	v_mov_b32_e32 v147, v146
	v_mov_b32_e32 v149, v148
	ds_write2st64_b64 v77, v[146:147], v[148:149] offset1:2
	v_add_u32_e32 v138, 0x400, v74
	ds_read_u8 v139, v138
	v_add_u32_e32 v141, 0x400, v73
	ds_read_u8 v140, v141
	s_mov_b32 s43, s67
	v_mov_b32_e32 v138, s43
	ds_read2st64_b32 v[228:229], v138 offset1:1
	ds_read_b128 v[26:29], v227 offset:2048
	ds_read_b128 v[30:33], v227 offset:2064
	v_mov_b32_e32 v38, 0
	v_mov_b32_e32 v39, 0
	v_mov_b32_e32 v40, 0
	v_mov_b32_e32 v41, 0
	v_mov_b32_e32 v42, 0
	v_mov_b32_e32 v43, 0
	v_mov_b32_e32 v44, 0
	v_mov_b32_e32 v45, 0
	v_and_b32_e32 v78, 0xffff, v23
	v_lshrrev_b32_e32 v79, 16, v23
	v_lshl_add_u32 v78, v78, 7, v152
	v_lshl_add_u32 v79, v79, 7, v153
	s_mov_b32 m0, s99
	s_add_i32 s43, s99, 0x400
	global_load_lds_dwordx4 v78, s[50:51]
	s_mov_b32 m0, s43
	s_nop 0
	global_load_lds_dwordx4 v79, s[50:51]
	s_waitcnt vmcnt(8)
; #define TR4(p_) __builtin_amdgcn_ds_read_tr4_b64_v2i32((LAS v2i*)(p_))
; #define VDMA(st_, k_) do { _Pragma("unroll") for (int i_ = 0; i_ < 4; ++i_) { \
;         const unsigned off_ = (unsigned)((st_) >> 2) * (16384u * 128u) + (PE_ID(E, 4 * ((st_) & 3) + i_) << 7) + ((i_ & 1) ? cx1 : cx0); \
;         __builtin_amdgcn_global_load_lds((const unsigned*)(V4 + off_), (LAS unsigned*)(ldsb + BUF[k_] + 1024 * i_), 16, 0, 0); } } while (0)
; __device__ __forceinline__ void peer_v_tokens(int j, const LAS unsigned short* EL, const LAS unsigned char* AL  , const LAS float* ASC  , const LAS int* SAL  , ...
;     ...
;         for (int st = 0; st < 16; ++st) {
;             const int p = st >> 2, q = st & 3;
;             if (st < 14) VDMA(st + 2, (st + 2) % 3);
;             if (st < 14) asm volatile("s_waitcnt vmcnt(8)" ::: "memory");
;             else if (st == 14) asm volatile("s_waitcnt vmcnt(4)" ::: "memory");
;             else asm volatile("s_waitcnt vmcnt(0)" ::: "memory");
;             if (q == 0) {
; #pragma unroll
;                 for (int r = 0; r < 4; ++r) { accH[r] = 0; accL[r] = 0; } }
; #pragma unroll
;             for (int tp = 0; tp < 2; ++tp) {
;                 const v2i ao = TR4(ATL + (2 * q + tp) * 128 + 8 * s16), ah = TR4(ATL + 1024 + (2 * q + tp) * 128 + 8 * s16);
; #pragma unroll
;                 for (int r = 0; r < 4; ++r) {
;                     const v2i d = TR4(ldsb + BUF[st % 3] + 2048 * tp + roff[r]);
;                     accH[r] = __builtin_amdgcn_sdot8(d.x, ah.x, accH[r], false); accH[r] = __builtin_amdgcn_sdot8(d.y, ah.y, accH[r], false);
;                     accL[r] = __builtin_amdgcn_sdot8(d.x, ao.x, accL[r], false); accL[r] = __builtin_amdgcn_sdot8(d.y, ao.y, accL[r], false);
;                 }
;             }
	v_add_u32_e32 v54, s77, v59
	v_add_u32_e32 v55, s77, v60
	v_add_u32_e32 v56, s77, v61
	v_add_u32_e32 v57, s77, v62
	ds_read_b64_tr_b4 v[50:51], v160 offset:128
	ds_read_b64_tr_b4 v[52:53], v160 offset:1152
	ds_read_b64_tr_b4 v[130:131], v54
	ds_read_b64_tr_b4 v[132:133], v55
	ds_read_b64_tr_b4 v[134:135], v56
	ds_read_b64_tr_b4 v[136:137], v57
	s_waitcnt lgkmcnt(12)
	v_dot8c_i32_i4_e32 v38, v122, v48
	v_dot8c_i32_i4_e32 v39, v122, v46
	v_dot8c_i32_i4_e32 v40, v124, v48
	v_dot8c_i32_i4_e32 v41, v124, v46
	v_dot8c_i32_i4_e32 v42, v126, v48
	v_dot8c_i32_i4_e32 v43, v126, v46
	v_dot8c_i32_i4_e32 v44, v128, v48
	v_dot8c_i32_i4_e32 v45, v128, v46
	v_dot8c_i32_i4_e32 v38, v123, v49
	v_dot8c_i32_i4_e32 v39, v123, v47
	v_dot8c_i32_i4_e32 v40, v125, v49
	v_dot8c_i32_i4_e32 v41, v125, v47
	v_dot8c_i32_i4_e32 v42, v127, v49
	v_dot8c_i32_i4_e32 v43, v127, v47
	v_dot8c_i32_i4_e32 v44, v129, v49
	v_dot8c_i32_i4_e32 v45, v129, v47
	v_and_b32_e32 v78, 0xffff, v24
	v_lshrrev_b32_e32 v79, 16, v24
	v_lshl_add_u32 v78, v78, 7, v152
	v_lshl_add_u32 v79, v79, 7, v153
	s_mov_b32 m0, s76
	s_add_i32 s43, s76, 0x400
	global_load_lds_dwordx4 v78, s[50:51]
	s_mov_b32 m0, s43
	s_nop 0
	global_load_lds_dwordx4 v79, s[50:51]
	s_waitcnt vmcnt(8)
	v_add_u32_e32 v54, s78, v59
	v_add_u32_e32 v55, s78, v60
	v_add_u32_e32 v56, s78, v61
	v_add_u32_e32 v57, s78, v62
	ds_read_b64_tr_b4 v[46:47], v160 offset:256
	ds_read_b64_tr_b4 v[48:49], v160 offset:1280
	ds_read_b64_tr_b4 v[122:123], v54
	ds_read_b64_tr_b4 v[124:125], v55
	ds_read_b64_tr_b4 v[126:127], v56
	ds_read_b64_tr_b4 v[128:129], v57
	s_waitcnt lgkmcnt(6)
	v_dot8c_i32_i4_e32 v38, v130, v52
	v_dot8c_i32_i4_e32 v39, v130, v50
	v_dot8c_i32_i4_e32 v40, v132, v52
	v_dot8c_i32_i4_e32 v41, v132, v50
	v_dot8c_i32_i4_e32 v42, v134, v52
	v_dot8c_i32_i4_e32 v43, v134, v50
	v_dot8c_i32_i4_e32 v44, v136, v52
	v_dot8c_i32_i4_e32 v45, v136, v50
	v_dot8c_i32_i4_e32 v38, v131, v53
	v_dot8c_i32_i4_e32 v39, v131, v51
	v_dot8c_i32_i4_e32 v40, v133, v53
	v_dot8c_i32_i4_e32 v41, v133, v51
	v_dot8c_i32_i4_e32 v42, v135, v53
	v_dot8c_i32_i4_e32 v43, v135, v51
	v_dot8c_i32_i4_e32 v44, v137, v53
	v_dot8c_i32_i4_e32 v45, v137, v51
	v_and_b32_e32 v78, 0xffff, v25
	v_lshrrev_b32_e32 v79, 16, v25
	v_lshl_add_u32 v78, v78, 7, v152
	v_lshl_add_u32 v79, v79, 7, v153
	s_mov_b32 m0, s77
	s_add_i32 s43, s77, 0x400
	global_load_lds_dwordx4 v78, s[50:51]
	s_mov_b32 m0, s43
	s_nop 0
	global_load_lds_dwordx4 v79, s[50:51]
	s_waitcnt vmcnt(8)
	v_add_u32_e32 v54, s79, v59
	v_add_u32_e32 v55, s79, v60
	v_add_u32_e32 v56, s79, v61
	v_add_u32_e32 v57, s79, v62
	ds_read_b64_tr_b4 v[50:51], v160 offset:384
	ds_read_b64_tr_b4 v[52:53], v160 offset:1408
	ds_read_b64_tr_b4 v[130:131], v54
	ds_read_b64_tr_b4 v[132:133], v55
	ds_read_b64_tr_b4 v[134:135], v56
	ds_read_b64_tr_b4 v[136:137], v57
	s_waitcnt lgkmcnt(6)
	v_dot8c_i32_i4_e32 v38, v122, v48
	v_dot8c_i32_i4_e32 v39, v122, v46
	v_dot8c_i32_i4_e32 v40, v124, v48
	v_dot8c_i32_i4_e32 v41, v124, v46
	v_dot8c_i32_i4_e32 v42, v126, v48
	v_dot8c_i32_i4_e32 v43, v126, v46
	v_dot8c_i32_i4_e32 v44, v128, v48
	v_dot8c_i32_i4_e32 v45, v128, v46
	v_dot8c_i32_i4_e32 v38, v123, v49
	v_dot8c_i32_i4_e32 v39, v123, v47
	v_dot8c_i32_i4_e32 v40, v125, v49
	v_dot8c_i32_i4_e32 v41, v125, v47
	v_dot8c_i32_i4_e32 v42, v127, v49
	v_dot8c_i32_i4_e32 v43, v127, v47
	v_dot8c_i32_i4_e32 v44, v129, v49
	v_dot8c_i32_i4_e32 v45, v129, v47
	s_waitcnt lgkmcnt(15)
	v_and_b32_e32 v78, 0xffff, v26
	v_lshrrev_b32_e32 v79, 16, v26
	v_lshl_add_u32 v78, v78, 7, v152
	v_lshl_add_u32 v79, v79, 7, v153
	s_mov_b32 m0, s78
	s_add_i32 s43, s78, 0x400
	global_load_lds_dwordx4 v78, s[50:51]
	s_mov_b32 m0, s43
	s_nop 0
	global_load_lds_dwordx4 v79, s[50:51]
	s_waitcnt vmcnt(8)
	v_add_u32_e32 v54, s98, v59
	v_add_u32_e32 v55, s98, v60
	v_add_u32_e32 v56, s98, v61
	v_add_u32_e32 v57, s98, v62
	ds_read_b64_tr_b4 v[46:47], v160 offset:512
	ds_read_b64_tr_b4 v[48:49], v160 offset:1536
	ds_read_b64_tr_b4 v[122:123], v54
	ds_read_b64_tr_b4 v[124:125], v55
	ds_read_b64_tr_b4 v[126:127], v56
	ds_read_b64_tr_b4 v[128:129], v57
	s_waitcnt lgkmcnt(6)
	v_dot8c_i32_i4_e32 v38, v130, v52
	v_dot8c_i32_i4_e32 v39, v130, v50
	v_dot8c_i32_i4_e32 v40, v132, v52
	v_dot8c_i32_i4_e32 v41, v132, v50
	v_dot8c_i32_i4_e32 v42, v134, v52
	v_dot8c_i32_i4_e32 v43, v134, v50
	v_dot8c_i32_i4_e32 v44, v136, v52
	v_dot8c_i32_i4_e32 v45, v136, v50
	v_dot8c_i32_i4_e32 v38, v131, v53
	v_dot8c_i32_i4_e32 v39, v131, v51
	v_dot8c_i32_i4_e32 v40, v133, v53
	v_dot8c_i32_i4_e32 v41, v133, v51
	v_dot8c_i32_i4_e32 v42, v135, v53
	v_dot8c_i32_i4_e32 v43, v135, v51
	v_dot8c_i32_i4_e32 v44, v137, v53
	v_dot8c_i32_i4_e32 v45, v137, v51
	v_and_b32_e32 v78, 0xffff, v27
	v_lshrrev_b32_e32 v79, 16, v27
	v_lshl_add_u32 v78, v78, 7, v152
	v_lshl_add_u32 v79, v79, 7, v153
	s_mov_b32 m0, s79
	s_add_i32 s43, s79, 0x400
	global_load_lds_dwordx4 v78, s[50:51]
	s_mov_b32 m0, s43
	s_nop 0
	global_load_lds_dwordx4 v79, s[50:51]
	s_waitcnt vmcnt(8)
	v_add_u32_e32 v54, s99, v59
	v_add_u32_e32 v55, s99, v60
	v_add_u32_e32 v56, s99, v61
	v_add_u32_e32 v57, s99, v62
	ds_read_b64_tr_b4 v[50:51], v160 offset:640
	ds_read_b64_tr_b4 v[52:53], v160 offset:1664
	ds_read_b64_tr_b4 v[130:131], v54
	ds_read_b64_tr_b4 v[132:133], v55
	ds_read_b64_tr_b4 v[134:135], v56
	ds_read_b64_tr_b4 v[136:137], v57
	s_waitcnt lgkmcnt(6)
	v_dot8c_i32_i4_e32 v38, v122, v48
	v_dot8c_i32_i4_e32 v39, v122, v46
	v_dot8c_i32_i4_e32 v40, v124, v48
	v_dot8c_i32_i4_e32 v41, v124, v46
	v_dot8c_i32_i4_e32 v42, v126, v48
	v_dot8c_i32_i4_e32 v43, v126, v46
	v_dot8c_i32_i4_e32 v44, v128, v48
	v_dot8c_i32_i4_e32 v45, v128, v46
	v_dot8c_i32_i4_e32 v38, v123, v49
	v_dot8c_i32_i4_e32 v39, v123, v47
	v_dot8c_i32_i4_e32 v40, v125, v49
	v_dot8c_i32_i4_e32 v41, v125, v47
	v_dot8c_i32_i4_e32 v42, v127, v49
	v_dot8c_i32_i4_e32 v43, v127, v47
	v_dot8c_i32_i4_e32 v44, v129, v49
	v_dot8c_i32_i4_e32 v45, v129, v47
	s_waitcnt lgkmcnt(15)
; __device__ __forceinline__ void peer_v_tokens(int j, const LAS unsigned short* EL, const LAS unsigned char* AL  , const LAS float* ASC  , const LAS int* SAL  , ...
;     ...
; #pragma unroll
;         for (int m = 0; m < 2; ++m) {
;             const int idx = lane + 64 * m, tau = idx >> 4, sr = idx & 15, k = 16 * (sr & 7) + 2 * tau + (sr >> 3);
;             const int aq = (int)*(const LAS signed char*)(AL + tl * 128 + k); const int tq = aq + 8;
;             const unsigned lo = (((unsigned)tq & 15u) ^ 8u) * 0x11111111u, hi = ((unsigned)(tq >> 4) & 15u) * 0x11111111u;
;             typedef unsigned u2v __attribute__((ext_vector_type(2)));
;             u2v l2; l2.x = lo; l2.y = lo; u2v h2; h2.x = hi; h2.y = hi;
;             *(LAS u2v*)(ATL + 8 * idx) = l2; *(LAS u2v*)(ATL + 1024 + 8 * idx) = h2;
;         }
;         const float asc = ASC[tl]; const int sa = SAL[tl];
;         CFENCE();
;         int accH[4], accL[4];
; #pragma unroll
;         for (int st = 0; st < 16; ++st) {
;             const int p = st >> 2, q = st & 3;
;             if (st < 14) VDMA(st + 2, (st + 2) % 3);
;             if (st < 14) asm volatile("s_waitcnt vmcnt(8)" ::: "memory");
;             else if (st == 14) asm volatile("s_waitcnt vmcnt(4)" ::: "memory");
;             else asm volatile("s_waitcnt vmcnt(0)" ::: "memory");
;             if (q == 0) {
; #pragma unroll
;                 for (int r = 0; r < 4; ++r) { accH[r] = 0; accL[r] = 0; } }
; #pragma unroll
;             for (int tp = 0; tp < 2; ++tp) {
;                 const v2i ao = TR4(ATL + (2 * q + tp) * 128 + 8 * s16), ah = TR4(ATL + 1024 + (2 * q + tp) * 128 + 8 * s16);
; #pragma unroll
;                 for (int r = 0; r < 4; ++r) {
;                     const v2i d = TR4(ldsb + BUF[st % 3] + 2048 * tp + roff[r]);
;                     accH[r] = __builtin_amdgcn_sdot8(d.x, ah.x, accH[r], false); accH[r] = __builtin_amdgcn_sdot8(d.y, ah.y, accH[r], false);
;                     accL[r] = __builtin_amdgcn_sdot8(d.x, ao.x, accL[r], false); accL[r] = __builtin_amdgcn_sdot8(d.y, ao.y, accL[r], false);
;                 }
;             }
;             asm volatile("s_waitcnt lgkmcnt(0)" ::: "memory");
;             if (q == 3) {
; #pragma unroll
;                 for (int r = 0; r < 4; ++r) STASH[256 * p + 16 * (grp + 4 * r) + pc] = f2bf(asc * (float)(2 * ((accH[r] << 4) + accL[r]) + sa));
;             }
	v_add_u32_e32 v143, 8, v139
	v_and_b32_e32 v142, 15, v143
	v_xor_b32_e32 v142, 8, v142
	v_bfe_u32 v144, v143, 4, 4
	v_mul_lo_u32 v142, v142, s92
	v_mul_lo_u32 v144, v144, s92
	v_mov_b32_e32 v143, v142
	v_mov_b32_e32 v145, v144
	ds_write2st64_b64 v159, v[142:143], v[144:145] offset1:2
	v_and_b32_e32 v78, 0xffff, v28
	v_lshrrev_b32_e32 v79, 16, v28
	v_lshl_add_u32 v78, v78, 7, v152
	v_lshl_add_u32 v79, v79, 7, v153
	s_mov_b32 m0, s98
	s_add_i32 s43, s98, 0x400
	global_load_lds_dwordx4 v78, s[50:51]
	s_mov_b32 m0, s43
	s_nop 0
	global_load_lds_dwordx4 v79, s[50:51]
	s_waitcnt vmcnt(8)
	v_add_u32_e32 v54, s76, v59
	v_add_u32_e32 v55, s76, v60
	v_add_u32_e32 v56, s76, v61
	v_add_u32_e32 v57, s76, v62
	ds_read_b64_tr_b4 v[46:47], v160 offset:768
	ds_read_b64_tr_b4 v[48:49], v160 offset:1792
	ds_read_b64_tr_b4 v[122:123], v54
	ds_read_b64_tr_b4 v[124:125], v55
	ds_read_b64_tr_b4 v[126:127], v56
	ds_read_b64_tr_b4 v[128:129], v57
	s_waitcnt lgkmcnt(7)
	v_dot8c_i32_i4_e32 v38, v130, v52
	v_dot8c_i32_i4_e32 v39, v130, v50
	v_dot8c_i32_i4_e32 v40, v132, v52
	v_dot8c_i32_i4_e32 v41, v132, v50
	v_dot8c_i32_i4_e32 v42, v134, v52
	v_dot8c_i32_i4_e32 v43, v134, v50
	v_dot8c_i32_i4_e32 v44, v136, v52
	v_dot8c_i32_i4_e32 v45, v136, v50
	v_dot8c_i32_i4_e32 v38, v131, v53
	v_dot8c_i32_i4_e32 v39, v131, v51
	v_dot8c_i32_i4_e32 v40, v133, v53
	v_dot8c_i32_i4_e32 v41, v133, v51
	v_dot8c_i32_i4_e32 v42, v135, v53
	v_dot8c_i32_i4_e32 v43, v135, v51
	v_dot8c_i32_i4_e32 v44, v137, v53
	v_dot8c_i32_i4_e32 v45, v137, v51
	v_and_b32_e32 v78, 0xffff, v29
	v_lshrrev_b32_e32 v79, 16, v29
	v_lshl_add_u32 v78, v78, 7, v152
	v_lshl_add_u32 v79, v79, 7, v153
	s_mov_b32 m0, s99
	s_add_i32 s43, s99, 0x400
	global_load_lds_dwordx4 v78, s[50:51]
	s_mov_b32 m0, s43
	s_nop 0
	global_load_lds_dwordx4 v79, s[50:51]
	s_waitcnt vmcnt(8)
	v_add_u32_e32 v54, s77, v59
	v_add_u32_e32 v55, s77, v60
	v_add_u32_e32 v56, s77, v61
	v_add_u32_e32 v57, s77, v62
	ds_read_b64_tr_b4 v[50:51], v160 offset:896
	ds_read_b64_tr_b4 v[52:53], v160 offset:1920
	ds_read_b64_tr_b4 v[130:131], v54
	ds_read_b64_tr_b4 v[132:133], v55
	ds_read_b64_tr_b4 v[134:135], v56
	ds_read_b64_tr_b4 v[136:137], v57
	s_waitcnt lgkmcnt(6)
	v_dot8c_i32_i4_e32 v38, v122, v48
	v_dot8c_i32_i4_e32 v39, v122, v46
	v_dot8c_i32_i4_e32 v40, v124, v48
	v_dot8c_i32_i4_e32 v41, v124, v46
	v_dot8c_i32_i4_e32 v42, v126, v48
	v_dot8c_i32_i4_e32 v43, v126, v46
	v_dot8c_i32_i4_e32 v44, v128, v48
	v_dot8c_i32_i4_e32 v45, v128, v46
	v_dot8c_i32_i4_e32 v38, v123, v49
	v_dot8c_i32_i4_e32 v39, v123, v47
	v_dot8c_i32_i4_e32 v40, v125, v49
	v_dot8c_i32_i4_e32 v41, v125, v47
	v_dot8c_i32_i4_e32 v42, v127, v49
	v_dot8c_i32_i4_e32 v43, v127, v47
	v_dot8c_i32_i4_e32 v44, v129, v49
	v_dot8c_i32_i4_e32 v45, v129, v47
	v_and_b32_e32 v78, 0xffff, v30
	v_lshrrev_b32_e32 v79, 16, v30
	v_lshl_add_u32 v78, v78, 7, v152
	v_lshl_add_u32 v79, v79, 7, v153
	s_mov_b32 m0, s76
	s_add_i32 s43, s76, 0x400
	global_load_lds_dwordx4 v78, s[50:51]
	s_mov_b32 m0, s43
	s_nop 0
	global_load_lds_dwordx4 v79, s[50:51]
	s_waitcnt vmcnt(8)
	v_add_u32_e32 v54, s78, v59
	v_add_u32_e32 v55, s78, v60
	v_add_u32_e32 v56, s78, v61
	v_add_u32_e32 v57, s78, v62
	ds_read_b64_tr_b4 v[46:47], v160
	ds_read_b64_tr_b4 v[48:49], v160 offset:1024
	ds_read_b64_tr_b4 v[122:123], v54
	ds_read_b64_tr_b4 v[124:125], v55
	ds_read_b64_tr_b4 v[126:127], v56
	ds_read_b64_tr_b4 v[128:129], v57
	s_waitcnt lgkmcnt(6)
	v_dot8c_i32_i4_e32 v38, v130, v52
	v_dot8c_i32_i4_e32 v39, v130, v50
	v_dot8c_i32_i4_e32 v40, v132, v52
	v_dot8c_i32_i4_e32 v41, v132, v50
	v_dot8c_i32_i4_e32 v42, v134, v52
	v_dot8c_i32_i4_e32 v43, v134, v50
	v_dot8c_i32_i4_e32 v44, v136, v52
	v_dot8c_i32_i4_e32 v45, v136, v50
	v_dot8c_i32_i4_e32 v38, v131, v53
	v_dot8c_i32_i4_e32 v39, v131, v51
	v_dot8c_i32_i4_e32 v40, v133, v53
	v_dot8c_i32_i4_e32 v41, v133, v51
	v_dot8c_i32_i4_e32 v42, v135, v53
	v_dot8c_i32_i4_e32 v43, v135, v51
	v_dot8c_i32_i4_e32 v44, v137, v53
	v_dot8c_i32_i4_e32 v45, v137, v51
	s_nop 3
	s_waitcnt lgkmcnt(15)
	v_lshlrev_b32_e32 v38, 5, v38
	v_lshlrev_b32_e32 v39, 1, v39
	v_add3_u32 v38, v39, v229, v38
	v_cvt_f32_i32_e32 v38, v38
	v_mul_f32_e32 v38, v228, v38
	v_lshlrev_b32_e32 v40, 5, v40
	v_lshlrev_b32_e32 v41, 1, v41
	v_add3_u32 v40, v41, v229, v40
	v_cvt_f32_i32_e32 v40, v40
	v_mul_f32_e32 v40, v228, v40
	v_lshlrev_b32_e32 v42, 5, v42
	v_lshlrev_b32_e32 v43, 1, v43
	v_add3_u32 v42, v43, v229, v42
	v_cvt_f32_i32_e32 v42, v42
	v_mul_f32_e32 v42, v228, v42
	v_lshlrev_b32_e32 v44, 5, v44
	v_lshlrev_b32_e32 v45, 1, v45
	v_add3_u32 v44, v45, v229, v44
	v_cvt_f32_i32_e32 v44, v44
	v_mul_f32_e32 v44, v228, v44
	v_cvt_pk_bf16_f32 v168, v38, v40
	v_cvt_pk_bf16_f32 v169, v42, v44
	s_add_i32 s43, s40, 0
	s_lshl_b32 s43, s43, 11
	v_add_u32_e32 v138, s43, v66
	global_load_dwordx2 v[194:195], v138, s[70:71]
	global_load_dwordx2 v[196:197], v138, s[70:71] offset:512
	global_load_dwordx2 v[198:199], v138, s[70:71] offset:1024
	global_load_dwordx2 v[200:201], v138, s[70:71] offset:1536
	v_add_u32_e32 v147, 8, v140
	v_and_b32_e32 v146, 15, v147
	v_xor_b32_e32 v146, 8, v146
	v_bfe_u32 v148, v147, 4, 4
	v_mul_lo_u32 v146, v146, s92
	v_mul_lo_u32 v148, v148, s92
	v_mov_b32_e32 v147, v146
	v_mov_b32_e32 v149, v148
	ds_write2st64_b64 v77, v[146:147], v[148:149] offset1:2
	v_add_u32_e32 v138, 0x800, v74
	ds_read_u8 v139, v138
	v_add_u32_e32 v141, 0x800, v73
	ds_read_u8 v140, v141
	s_add_i32 s43, s67, 32
	v_mov_b32_e32 v138, s43
	ds_read2st64_b32 v[228:229], v138 offset1:1
	ds_read_b128 v[18:21], v227 offset:4096
	ds_read_b128 v[22:25], v227 offset:4112
	v_mov_b32_e32 v150, v63
	v_mov_b32_e32 v151, v64
	v_mov_b32_e32 v38, 0
	v_mov_b32_e32 v39, 0
	v_mov_b32_e32 v40, 0
	v_mov_b32_e32 v41, 0
	v_mov_b32_e32 v42, 0
	v_mov_b32_e32 v43, 0
	v_mov_b32_e32 v44, 0
	v_mov_b32_e32 v45, 0
	v_and_b32_e32 v78, 0xffff, v31
	v_lshrrev_b32_e32 v79, 16, v31
	v_lshl_add_u32 v78, v78, 7, v152
	v_lshl_add_u32 v79, v79, 7, v153
	s_mov_b32 m0, s77
	s_add_i32 s43, s77, 0x400
	global_load_lds_dwordx4 v78, s[50:51]
	s_mov_b32 m0, s43
	s_nop 0
	global_load_lds_dwordx4 v79, s[50:51]
	s_waitcnt vmcnt(12)
; #define TR4(p_) __builtin_amdgcn_ds_read_tr4_b64_v2i32((LAS v2i*)(p_))
; #define VDMA(st_, k_) do { _Pragma("unroll") for (int i_ = 0; i_ < 4; ++i_) { \
;         const unsigned off_ = (unsigned)((st_) >> 2) * (16384u * 128u) + (PE_ID(E, 4 * ((st_) & 3) + i_) << 7) + ((i_ & 1) ? cx1 : cx0); \
;         __builtin_amdgcn_global_load_lds((const unsigned*)(V4 + off_), (LAS unsigned*)(ldsb + BUF[k_] + 1024 * i_), 16, 0, 0); } } while (0)
; __device__ __forceinline__ void peer_v_tokens(int j, const LAS unsigned short* EL, const LAS unsigned char* AL  , const LAS float* ASC  , const LAS int* SAL  , ...
;     ...
;         for (int st = 0; st < 16; ++st) {
;             const int p = st >> 2, q = st & 3;
;             if (st < 14) VDMA(st + 2, (st + 2) % 3);
;             if (st < 14) asm volatile("s_waitcnt vmcnt(8)" ::: "memory");
;             else if (st == 14) asm volatile("s_waitcnt vmcnt(4)" ::: "memory");
;             else asm volatile("s_waitcnt vmcnt(0)" ::: "memory");
;             if (q == 0) {
; #pragma unroll
;                 for (int r = 0; r < 4; ++r) { accH[r] = 0; accL[r] = 0; } }
; #pragma unroll
;             for (int tp = 0; tp < 2; ++tp) {
;                 const v2i ao = TR4(ATL + (2 * q + tp) * 128 + 8 * s16), ah = TR4(ATL + 1024 + (2 * q + tp) * 128 + 8 * s16);
; #pragma unroll
;                 for (int r = 0; r < 4; ++r) {
;                     const v2i d = TR4(ldsb + BUF[st % 3] + 2048 * tp + roff[r]);
;                     accH[r] = __builtin_amdgcn_sdot8(d.x, ah.x, accH[r], false); accH[r] = __builtin_amdgcn_sdot8(d.y, ah.y, accH[r], false);
;                     accL[r] = __builtin_amdgcn_sdot8(d.x, ao.x, accL[r], false); accL[r] = __builtin_amdgcn_sdot8(d.y, ao.y, accL[r], false);
;                 }
;             }
	v_add_u32_e32 v54, s79, v59
	v_add_u32_e32 v55, s79, v60
	v_add_u32_e32 v56, s79, v61
	v_add_u32_e32 v57, s79, v62
	ds_read_b64_tr_b4 v[50:51], v160 offset:128
	ds_read_b64_tr_b4 v[52:53], v160 offset:1152
	ds_read_b64_tr_b4 v[130:131], v54
	ds_read_b64_tr_b4 v[132:133], v55
	ds_read_b64_tr_b4 v[134:135], v56
	ds_read_b64_tr_b4 v[136:137], v57
	s_waitcnt lgkmcnt(12)
	v_dot8c_i32_i4_e32 v38, v122, v48
	v_dot8c_i32_i4_e32 v39, v122, v46
	v_dot8c_i32_i4_e32 v40, v124, v48
	v_dot8c_i32_i4_e32 v41, v124, v46
	v_dot8c_i32_i4_e32 v42, v126, v48
	v_dot8c_i32_i4_e32 v43, v126, v46
	v_dot8c_i32_i4_e32 v44, v128, v48
	v_dot8c_i32_i4_e32 v45, v128, v46
	v_dot8c_i32_i4_e32 v38, v123, v49
	v_dot8c_i32_i4_e32 v39, v123, v47
	v_dot8c_i32_i4_e32 v40, v125, v49
	v_dot8c_i32_i4_e32 v41, v125, v47
	v_dot8c_i32_i4_e32 v42, v127, v49
	v_dot8c_i32_i4_e32 v43, v127, v47
	v_dot8c_i32_i4_e32 v44, v129, v49
	v_dot8c_i32_i4_e32 v45, v129, v47
	v_and_b32_e32 v78, 0xffff, v32
	v_lshrrev_b32_e32 v79, 16, v32
	v_lshl_add_u32 v78, v78, 7, v152
	v_lshl_add_u32 v79, v79, 7, v153
	s_mov_b32 m0, s78
	s_add_i32 s43, s78, 0x400
	global_load_lds_dwordx4 v78, s[50:51]
	s_mov_b32 m0, s43
	s_nop 0
	global_load_lds_dwordx4 v79, s[50:51]
	s_waitcnt vmcnt(12)
	v_add_u32_e32 v54, s98, v59
	v_add_u32_e32 v55, s98, v60
	v_add_u32_e32 v56, s98, v61
	v_add_u32_e32 v57, s98, v62
	ds_read_b64_tr_b4 v[46:47], v160 offset:256
	ds_read_b64_tr_b4 v[48:49], v160 offset:1280
	ds_read_b64_tr_b4 v[122:123], v54
	ds_read_b64_tr_b4 v[124:125], v55
	ds_read_b64_tr_b4 v[126:127], v56
	ds_read_b64_tr_b4 v[128:129], v57
	s_waitcnt lgkmcnt(6)
	v_dot8c_i32_i4_e32 v38, v130, v52
	v_dot8c_i32_i4_e32 v39, v130, v50
	v_dot8c_i32_i4_e32 v40, v132, v52
	v_dot8c_i32_i4_e32 v41, v132, v50
	v_dot8c_i32_i4_e32 v42, v134, v52
	v_dot8c_i32_i4_e32 v43, v134, v50
	v_dot8c_i32_i4_e32 v44, v136, v52
	v_dot8c_i32_i4_e32 v45, v136, v50
	v_dot8c_i32_i4_e32 v38, v131, v53
	v_dot8c_i32_i4_e32 v39, v131, v51
	v_dot8c_i32_i4_e32 v40, v133, v53
	v_dot8c_i32_i4_e32 v41, v133, v51
	v_dot8c_i32_i4_e32 v42, v135, v53
	v_dot8c_i32_i4_e32 v43, v135, v51
	v_dot8c_i32_i4_e32 v44, v137, v53
	v_dot8c_i32_i4_e32 v45, v137, v51
	v_and_b32_e32 v78, 0xffff, v33
	v_lshrrev_b32_e32 v79, 16, v33
	v_lshl_add_u32 v78, v78, 7, v152
	v_lshl_add_u32 v79, v79, 7, v153
	s_mov_b32 m0, s79
	s_add_i32 s43, s79, 0x400
	global_load_lds_dwordx4 v78, s[50:51]
	s_mov_b32 m0, s43
	s_nop 0
	global_load_lds_dwordx4 v79, s[50:51]
	s_waitcnt vmcnt(12)
	v_add_u32_e32 v54, s99, v59
	v_add_u32_e32 v55, s99, v60
	v_add_u32_e32 v56, s99, v61
	v_add_u32_e32 v57, s99, v62
	ds_read_b64_tr_b4 v[50:51], v160 offset:384
	ds_read_b64_tr_b4 v[52:53], v160 offset:1408
	ds_read_b64_tr_b4 v[130:131], v54
	ds_read_b64_tr_b4 v[132:133], v55
	ds_read_b64_tr_b4 v[134:135], v56
	ds_read_b64_tr_b4 v[136:137], v57
	s_waitcnt lgkmcnt(6)
	v_dot8c_i32_i4_e32 v38, v122, v48
	v_dot8c_i32_i4_e32 v39, v122, v46
	v_dot8c_i32_i4_e32 v40, v124, v48
	v_dot8c_i32_i4_e32 v41, v124, v46
	v_dot8c_i32_i4_e32 v42, v126, v48
	v_dot8c_i32_i4_e32 v43, v126, v46
	v_dot8c_i32_i4_e32 v44, v128, v48
	v_dot8c_i32_i4_e32 v45, v128, v46
	v_dot8c_i32_i4_e32 v38, v123, v49
	v_dot8c_i32_i4_e32 v39, v123, v47
	v_dot8c_i32_i4_e32 v40, v125, v49
	v_dot8c_i32_i4_e32 v41, v125, v47
	v_dot8c_i32_i4_e32 v42, v127, v49
	v_dot8c_i32_i4_e32 v43, v127, v47
	v_dot8c_i32_i4_e32 v44, v129, v49
	v_dot8c_i32_i4_e32 v45, v129, v47
	s_waitcnt lgkmcnt(15)
	v_and_b32_e32 v78, 0xffff, v18
	v_lshrrev_b32_e32 v79, 16, v18
	v_lshl_add_u32 v78, v78, 7, v150
	v_lshl_add_u32 v79, v79, 7, v151
	s_mov_b32 m0, s98
	s_add_i32 s43, s98, 0x400
	global_load_lds_dwordx4 v78, s[50:51]
	s_mov_b32 m0, s43
	s_nop 0
	global_load_lds_dwordx4 v79, s[50:51]
	s_waitcnt vmcnt(12)
	v_add_u32_e32 v54, s76, v59
	v_add_u32_e32 v55, s76, v60
	v_add_u32_e32 v56, s76, v61
	v_add_u32_e32 v57, s76, v62
	ds_read_b64_tr_b4 v[46:47], v160 offset:512
	ds_read_b64_tr_b4 v[48:49], v160 offset:1536
	ds_read_b64_tr_b4 v[122:123], v54
	ds_read_b64_tr_b4 v[124:125], v55
	ds_read_b64_tr_b4 v[126:127], v56
	ds_read_b64_tr_b4 v[128:129], v57
	s_waitcnt lgkmcnt(6)
	v_dot8c_i32_i4_e32 v38, v130, v52
	v_dot8c_i32_i4_e32 v39, v130, v50
	v_dot8c_i32_i4_e32 v40, v132, v52
	v_dot8c_i32_i4_e32 v41, v132, v50
	v_dot8c_i32_i4_e32 v42, v134, v52
	v_dot8c_i32_i4_e32 v43, v134, v50
	v_dot8c_i32_i4_e32 v44, v136, v52
	v_dot8c_i32_i4_e32 v45, v136, v50
	v_dot8c_i32_i4_e32 v38, v131, v53
	v_dot8c_i32_i4_e32 v39, v131, v51
	v_dot8c_i32_i4_e32 v40, v133, v53
	v_dot8c_i32_i4_e32 v41, v133, v51
	v_dot8c_i32_i4_e32 v42, v135, v53
	v_dot8c_i32_i4_e32 v43, v135, v51
	v_dot8c_i32_i4_e32 v44, v137, v53
	v_dot8c_i32_i4_e32 v45, v137, v51
	v_and_b32_e32 v78, 0xffff, v19
	v_lshrrev_b32_e32 v79, 16, v19
	v_lshl_add_u32 v78, v78, 7, v150
	v_lshl_add_u32 v79, v79, 7, v151
	s_mov_b32 m0, s99
	s_add_i32 s43, s99, 0x400
	global_load_lds_dwordx4 v78, s[50:51]
	s_mov_b32 m0, s43
	s_nop 0
	global_load_lds_dwordx4 v79, s[50:51]
	s_waitcnt vmcnt(8)
	v_add_u32_e32 v54, s77, v59
	v_add_u32_e32 v55, s77, v60
	v_add_u32_e32 v56, s77, v61
	v_add_u32_e32 v57, s77, v62
	ds_read_b64_tr_b4 v[50:51], v160 offset:640
	ds_read_b64_tr_b4 v[52:53], v160 offset:1664
	ds_read_b64_tr_b4 v[130:131], v54
	ds_read_b64_tr_b4 v[132:133], v55
	ds_read_b64_tr_b4 v[134:135], v56
	ds_read_b64_tr_b4 v[136:137], v57
	s_waitcnt lgkmcnt(6)
	v_dot8c_i32_i4_e32 v38, v122, v48
	v_dot8c_i32_i4_e32 v39, v122, v46
	v_dot8c_i32_i4_e32 v40, v124, v48
	v_dot8c_i32_i4_e32 v41, v124, v46
	v_dot8c_i32_i4_e32 v42, v126, v48
	v_dot8c_i32_i4_e32 v43, v126, v46
	v_dot8c_i32_i4_e32 v44, v128, v48
	v_dot8c_i32_i4_e32 v45, v128, v46
	v_dot8c_i32_i4_e32 v38, v123, v49
	v_dot8c_i32_i4_e32 v39, v123, v47
	v_dot8c_i32_i4_e32 v40, v125, v49
	v_dot8c_i32_i4_e32 v41, v125, v47
	v_dot8c_i32_i4_e32 v42, v127, v49
	v_dot8c_i32_i4_e32 v43, v127, v47
	v_dot8c_i32_i4_e32 v44, v129, v49
	v_dot8c_i32_i4_e32 v45, v129, v47
	s_waitcnt lgkmcnt(15)
; __device__ __forceinline__ void peer_v_tokens(int j, const LAS unsigned short* EL, const LAS unsigned char* AL  , const LAS float* ASC  , const LAS int* SAL  , ...
;     ...
; #pragma unroll
;         for (int m = 0; m < 2; ++m) {
;             const int idx = lane + 64 * m, tau = idx >> 4, sr = idx & 15, k = 16 * (sr & 7) + 2 * tau + (sr >> 3);
;             const int aq = (int)*(const LAS signed char*)(AL + tl * 128 + k); const int tq = aq + 8;
;             const unsigned lo = (((unsigned)tq & 15u) ^ 8u) * 0x11111111u, hi = ((unsigned)(tq >> 4) & 15u) * 0x11111111u;
;             typedef unsigned u2v __attribute__((ext_vector_type(2)));
;             u2v l2; l2.x = lo; l2.y = lo; u2v h2; h2.x = hi; h2.y = hi;
;             *(LAS u2v*)(ATL + 8 * idx) = l2; *(LAS u2v*)(ATL + 1024 + 8 * idx) = h2;
;         }
;         const float asc = ASC[tl]; const int sa = SAL[tl];
;         CFENCE();
;         int accH[4], accL[4];
; #pragma unroll
;         for (int st = 0; st < 16; ++st) {
;             const int p = st >> 2, q = st & 3;
;             if (st < 14) VDMA(st + 2, (st + 2) % 3);
;             if (st < 14) asm volatile("s_waitcnt vmcnt(8)" ::: "memory");
;             else if (st == 14) asm volatile("s_waitcnt vmcnt(4)" ::: "memory");
;             else asm volatile("s_waitcnt vmcnt(0)" ::: "memory");
;             if (q == 0) {
; #pragma unroll
;                 for (int r = 0; r < 4; ++r) { accH[r] = 0; accL[r] = 0; } }
; #pragma unroll
;             for (int tp = 0; tp < 2; ++tp) {
;                 const v2i ao = TR4(ATL + (2 * q + tp) * 128 + 8 * s16), ah = TR4(ATL + 1024 + (2 * q + tp) * 128 + 8 * s16);
; #pragma unroll
;                 for (int r = 0; r < 4; ++r) {
;                     const v2i d = TR4(ldsb + BUF[st % 3] + 2048 * tp + roff[r]);
;                     accH[r] = __builtin_amdgcn_sdot8(d.x, ah.x, accH[r], false); accH[r] = __builtin_amdgcn_sdot8(d.y, ah.y, accH[r], false);
;                     accL[r] = __builtin_amdgcn_sdot8(d.x, ao.x, accL[r], false); accL[r] = __builtin_amdgcn_sdot8(d.y, ao.y, accL[r], false);
;                 }
;             }
;             asm volatile("s_waitcnt lgkmcnt(0)" ::: "memory");
;             if (q == 3) {
; #pragma unroll
;                 for (int r = 0; r < 4; ++r) STASH[256 * p + 16 * (grp + 4 * r) + pc] = f2bf(asc * (float)(2 * ((accH[r] << 4) + accL[r]) + sa));
;             }
	v_add_u32_e32 v143, 8, v139
	v_and_b32_e32 v142, 15, v143
	v_xor_b32_e32 v142, 8, v142
	v_bfe_u32 v144, v143, 4, 4
	v_mul_lo_u32 v142, v142, s92
	v_mul_lo_u32 v144, v144, s92
	v_mov_b32_e32 v143, v142
	v_mov_b32_e32 v145, v144
	ds_write2st64_b64 v159, v[142:143], v[144:145] offset1:2
	v_and_b32_e32 v78, 0xffff, v20
	v_lshrrev_b32_e32 v79, 16, v20
	v_lshl_add_u32 v78, v78, 7, v150
	v_lshl_add_u32 v79, v79, 7, v151
	s_mov_b32 m0, s76
	s_add_i32 s43, s76, 0x400
	global_load_lds_dwordx4 v78, s[50:51]
	s_mov_b32 m0, s43
	s_nop 0
	global_load_lds_dwordx4 v79, s[50:51]
	s_waitcnt vmcnt(8)
	v_add_u32_e32 v54, s78, v59
	v_add_u32_e32 v55, s78, v60
	v_add_u32_e32 v56, s78, v61
	v_add_u32_e32 v57, s78, v62
	ds_read_b64_tr_b4 v[46:47], v160 offset:768
	ds_read_b64_tr_b4 v[48:49], v160 offset:1792
	ds_read_b64_tr_b4 v[122:123], v54
	ds_read_b64_tr_b4 v[124:125], v55
	ds_read_b64_tr_b4 v[126:127], v56
	ds_read_b64_tr_b4 v[128:129], v57
	s_waitcnt lgkmcnt(7)
	v_dot8c_i32_i4_e32 v38, v130, v52
	v_dot8c_i32_i4_e32 v39, v130, v50
	v_dot8c_i32_i4_e32 v40, v132, v52
	v_dot8c_i32_i4_e32 v41, v132, v50
	v_dot8c_i32_i4_e32 v42, v134, v52
	v_dot8c_i32_i4_e32 v43, v134, v50
	v_dot8c_i32_i4_e32 v44, v136, v52
	v_dot8c_i32_i4_e32 v45, v136, v50
	v_dot8c_i32_i4_e32 v38, v131, v53
	v_dot8c_i32_i4_e32 v39, v131, v51
	v_dot8c_i32_i4_e32 v40, v133, v53
	v_dot8c_i32_i4_e32 v41, v133, v51
	v_dot8c_i32_i4_e32 v42, v135, v53
	v_dot8c_i32_i4_e32 v43, v135, v51
	v_dot8c_i32_i4_e32 v44, v137, v53
	v_dot8c_i32_i4_e32 v45, v137, v51
	v_and_b32_e32 v78, 0xffff, v21
	v_lshrrev_b32_e32 v79, 16, v21
	v_lshl_add_u32 v78, v78, 7, v150
	v_lshl_add_u32 v79, v79, 7, v151
	s_mov_b32 m0, s77
	s_add_i32 s43, s77, 0x400
	global_load_lds_dwordx4 v78, s[50:51]
	s_mov_b32 m0, s43
	s_nop 0
	global_load_lds_dwordx4 v79, s[50:51]
	s_waitcnt vmcnt(8)
	v_add_u32_e32 v54, s79, v59
	v_add_u32_e32 v55, s79, v60
	v_add_u32_e32 v56, s79, v61
	v_add_u32_e32 v57, s79, v62
	ds_read_b64_tr_b4 v[50:51], v160 offset:896
	ds_read_b64_tr_b4 v[52:53], v160 offset:1920
	ds_read_b64_tr_b4 v[130:131], v54
	ds_read_b64_tr_b4 v[132:133], v55
	ds_read_b64_tr_b4 v[134:135], v56
	ds_read_b64_tr_b4 v[136:137], v57
	s_waitcnt lgkmcnt(6)
	v_dot8c_i32_i4_e32 v38, v122, v48
	v_dot8c_i32_i4_e32 v39, v122, v46
	v_dot8c_i32_i4_e32 v40, v124, v48
	v_dot8c_i32_i4_e32 v41, v124, v46
	v_dot8c_i32_i4_e32 v42, v126, v48
	v_dot8c_i32_i4_e32 v43, v126, v46
	v_dot8c_i32_i4_e32 v44, v128, v48
	v_dot8c_i32_i4_e32 v45, v128, v46
	v_dot8c_i32_i4_e32 v38, v123, v49
	v_dot8c_i32_i4_e32 v39, v123, v47
	v_dot8c_i32_i4_e32 v40, v125, v49
	v_dot8c_i32_i4_e32 v41, v125, v47
	v_dot8c_i32_i4_e32 v42, v127, v49
	v_dot8c_i32_i4_e32 v43, v127, v47
	v_dot8c_i32_i4_e32 v44, v129, v49
	v_dot8c_i32_i4_e32 v45, v129, v47
	v_and_b32_e32 v78, 0xffff, v22
	v_lshrrev_b32_e32 v79, 16, v22
	v_lshl_add_u32 v78, v78, 7, v150
	v_lshl_add_u32 v79, v79, 7, v151
	s_mov_b32 m0, s78
	s_add_i32 s43, s78, 0x400
	global_load_lds_dwordx4 v78, s[50:51]
	s_mov_b32 m0, s43
	s_nop 0
	global_load_lds_dwordx4 v79, s[50:51]
	s_waitcnt vmcnt(8)
	v_add_u32_e32 v54, s98, v59
	v_add_u32_e32 v55, s98, v60
	v_add_u32_e32 v56, s98, v61
	v_add_u32_e32 v57, s98, v62
	ds_read_b64_tr_b4 v[46:47], v160
	ds_read_b64_tr_b4 v[48:49], v160 offset:1024
	ds_read_b64_tr_b4 v[122:123], v54
	ds_read_b64_tr_b4 v[124:125], v55
	ds_read_b64_tr_b4 v[126:127], v56
	ds_read_b64_tr_b4 v[128:129], v57
	s_waitcnt lgkmcnt(6)
	v_dot8c_i32_i4_e32 v38, v130, v52
	v_dot8c_i32_i4_e32 v39, v130, v50
	v_dot8c_i32_i4_e32 v40, v132, v52
	v_dot8c_i32_i4_e32 v41, v132, v50
	v_dot8c_i32_i4_e32 v42, v134, v52
	v_dot8c_i32_i4_e32 v43, v134, v50
	v_dot8c_i32_i4_e32 v44, v136, v52
	v_dot8c_i32_i4_e32 v45, v136, v50
	v_dot8c_i32_i4_e32 v38, v131, v53
	v_dot8c_i32_i4_e32 v39, v131, v51
	v_dot8c_i32_i4_e32 v40, v133, v53
	v_dot8c_i32_i4_e32 v41, v133, v51
	v_dot8c_i32_i4_e32 v42, v135, v53
	v_dot8c_i32_i4_e32 v43, v135, v51
	v_dot8c_i32_i4_e32 v44, v137, v53
	v_dot8c_i32_i4_e32 v45, v137, v51
	s_nop 3
	s_waitcnt lgkmcnt(15)
	v_lshlrev_b32_e32 v38, 5, v38
	v_lshlrev_b32_e32 v39, 1, v39
	v_add3_u32 v38, v39, v229, v38
	v_cvt_f32_i32_e32 v38, v38
	v_mul_f32_e32 v38, v228, v38
	v_lshlrev_b32_e32 v40, 5, v40
	v_lshlrev_b32_e32 v41, 1, v41
	v_add3_u32 v40, v41, v229, v40
	v_cvt_f32_i32_e32 v40, v40
	v_mul_f32_e32 v40, v228, v40
	v_lshlrev_b32_e32 v42, 5, v42
	v_lshlrev_b32_e32 v43, 1, v43
	v_add3_u32 v42, v43, v229, v42
	v_cvt_f32_i32_e32 v42, v42
	v_mul_f32_e32 v42, v228, v42
	v_lshlrev_b32_e32 v44, 5, v44
	v_lshlrev_b32_e32 v45, 1, v45
	v_add3_u32 v44, v45, v229, v44
	v_cvt_f32_i32_e32 v44, v44
	v_mul_f32_e32 v44, v228, v44
	v_cvt_pk_bf16_f32 v176, v38, v40
	v_cvt_pk_bf16_f32 v177, v42, v44
	v_add_u32_e32 v147, 8, v140
	v_and_b32_e32 v146, 15, v147
	v_xor_b32_e32 v146, 8, v146
	v_bfe_u32 v148, v147, 4, 4
	v_mul_lo_u32 v146, v146, s92
	v_mul_lo_u32 v148, v148, s92
	v_mov_b32_e32 v147, v146
	v_mov_b32_e32 v149, v148
	ds_write2st64_b64 v77, v[146:147], v[148:149] offset1:2
	v_add_u32_e32 v138, 0xc00, v74
	ds_read_u8 v139, v138
	v_add_u32_e32 v141, 0xc00, v73
	ds_read_u8 v140, v141
	s_add_i32 s43, s67, 64
	v_mov_b32_e32 v138, s43
	ds_read2st64_b32 v[228:229], v138 offset1:1
	ds_read_b128 v[26:29], v227 offset:6144
	ds_read_b128 v[30:33], v227 offset:6160
	v_mov_b32_e32 v38, 0
	v_mov_b32_e32 v39, 0
	v_mov_b32_e32 v40, 0
	v_mov_b32_e32 v41, 0
	v_mov_b32_e32 v42, 0
	v_mov_b32_e32 v43, 0
	v_mov_b32_e32 v44, 0
	v_mov_b32_e32 v45, 0
	v_and_b32_e32 v78, 0xffff, v23
	v_lshrrev_b32_e32 v79, 16, v23
	v_lshl_add_u32 v78, v78, 7, v150
	v_lshl_add_u32 v79, v79, 7, v151
	s_mov_b32 m0, s79
	s_add_i32 s43, s79, 0x400
	global_load_lds_dwordx4 v78, s[50:51]
	s_mov_b32 m0, s43
	s_nop 0
	global_load_lds_dwordx4 v79, s[50:51]
	s_waitcnt vmcnt(8)
; #define LAS __attribute__((address_space(3)))
; __device__ __forceinline__ bf16 f2bf(float f) { return (bf16)f2bfu(f); }
; #define TR4(p_) __builtin_amdgcn_ds_read_tr4_b64_v2i32((LAS v2i*)(p_))
; #define CFENCE() asm volatile("" ::: "memory")
; __device__ __forceinline__ void peer_v_tokens(int j, const LAS unsigned short* EL, const LAS unsigned char* AL  , const LAS float* ASC  , const LAS int* SAL  , ...
;     ...
;         for (int st = 0; st < 16; ++st) {
;             const int p = st >> 2, q = st & 3;
;             if (st < 14) VDMA(st + 2, (st + 2) % 3);
;             if (st < 14) asm volatile("s_waitcnt vmcnt(8)" ::: "memory");
;             else if (st == 14) asm volatile("s_waitcnt vmcnt(4)" ::: "memory");
;             else asm volatile("s_waitcnt vmcnt(0)" ::: "memory");
;             if (q == 0) {
; #pragma unroll
;                 for (int r = 0; r < 4; ++r) { accH[r] = 0; accL[r] = 0; } }
; #pragma unroll
;             for (int tp = 0; tp < 2; ++tp) {
;                 const v2i ao = TR4(ATL + (2 * q + tp) * 128 + 8 * s16), ah = TR4(ATL + 1024 + (2 * q + tp) * 128 + 8 * s16);
; #pragma unroll
;                 for (int r = 0; r < 4; ++r) {
;                     const v2i d = TR4(ldsb + BUF[st % 3] + 2048 * tp + roff[r]);
;                     accH[r] = __builtin_amdgcn_sdot8(d.x, ah.x, accH[r], false); accH[r] = __builtin_amdgcn_sdot8(d.y, ah.y, accH[r], false);
;                     accL[r] = __builtin_amdgcn_sdot8(d.x, ao.x, accL[r], false); accL[r] = __builtin_amdgcn_sdot8(d.y, ao.y, accL[r], false);
;                 }
;             }
;             asm volatile("s_waitcnt lgkmcnt(0)" ::: "memory");
;             if (q == 3) {
; #pragma unroll
;                 for (int r = 0; r < 4; ++r) STASH[256 * p + 16 * (grp + 4 * r) + pc] = f2bf(asc * (float)(2 * ((accH[r] << 4) + accL[r]) + sa));
;             }
;         }
;         CFENCE();
;         {
;             float4 v[4]; float ss = 0.f;
; #pragma unroll
;             for (int jq = 0; jq < 4; ++jq) { typedef unsigned u2v __attribute__((ext_vector_type(2))); const u2v pw = *(const LAS u2v*)(STASH + 4 * lane + 256 * jq); const uint2 hw = hv[jq];
	v_add_u32_e32 v54, s99, v59
	v_add_u32_e32 v55, s99, v60
	v_add_u32_e32 v56, s99, v61
	v_add_u32_e32 v57, s99, v62
	ds_read_b64_tr_b4 v[50:51], v160 offset:128
	ds_read_b64_tr_b4 v[52:53], v160 offset:1152
	ds_read_b64_tr_b4 v[130:131], v54
	ds_read_b64_tr_b4 v[132:133], v55
	ds_read_b64_tr_b4 v[134:135], v56
	ds_read_b64_tr_b4 v[136:137], v57
	s_waitcnt lgkmcnt(12)
	v_dot8c_i32_i4_e32 v38, v122, v48
	v_dot8c_i32_i4_e32 v39, v122, v46
	v_dot8c_i32_i4_e32 v40, v124, v48
	v_dot8c_i32_i4_e32 v41, v124, v46
	v_dot8c_i32_i4_e32 v42, v126, v48
	v_dot8c_i32_i4_e32 v43, v126, v46
	v_dot8c_i32_i4_e32 v44, v128, v48
	v_dot8c_i32_i4_e32 v45, v128, v46
	v_dot8c_i32_i4_e32 v38, v123, v49
	v_dot8c_i32_i4_e32 v39, v123, v47
	v_dot8c_i32_i4_e32 v40, v125, v49
	v_dot8c_i32_i4_e32 v41, v125, v47
	v_dot8c_i32_i4_e32 v42, v127, v49
	v_dot8c_i32_i4_e32 v43, v127, v47
	v_dot8c_i32_i4_e32 v44, v129, v49
	v_dot8c_i32_i4_e32 v45, v129, v47
	v_and_b32_e32 v78, 0xffff, v24
	v_lshrrev_b32_e32 v79, 16, v24
	v_lshl_add_u32 v78, v78, 7, v150
	v_lshl_add_u32 v79, v79, 7, v151
	s_mov_b32 m0, s98
	s_add_i32 s43, s98, 0x400
	global_load_lds_dwordx4 v78, s[50:51]
	s_mov_b32 m0, s43
	s_nop 0
	global_load_lds_dwordx4 v79, s[50:51]
	s_waitcnt vmcnt(8)
	v_add_u32_e32 v54, s76, v59
	v_add_u32_e32 v55, s76, v60
	v_add_u32_e32 v56, s76, v61
	v_add_u32_e32 v57, s76, v62
	ds_read_b64_tr_b4 v[46:47], v160 offset:256
	ds_read_b64_tr_b4 v[48:49], v160 offset:1280
	ds_read_b64_tr_b4 v[122:123], v54
	ds_read_b64_tr_b4 v[124:125], v55
	ds_read_b64_tr_b4 v[126:127], v56
	ds_read_b64_tr_b4 v[128:129], v57
	s_waitcnt lgkmcnt(6)
	v_dot8c_i32_i4_e32 v38, v130, v52
	v_dot8c_i32_i4_e32 v39, v130, v50
	v_dot8c_i32_i4_e32 v40, v132, v52
	v_dot8c_i32_i4_e32 v41, v132, v50
	v_dot8c_i32_i4_e32 v42, v134, v52
	v_dot8c_i32_i4_e32 v43, v134, v50
	v_dot8c_i32_i4_e32 v44, v136, v52
	v_dot8c_i32_i4_e32 v45, v136, v50
	v_dot8c_i32_i4_e32 v38, v131, v53
	v_dot8c_i32_i4_e32 v39, v131, v51
	v_dot8c_i32_i4_e32 v40, v133, v53
	v_dot8c_i32_i4_e32 v41, v133, v51
	v_dot8c_i32_i4_e32 v42, v135, v53
	v_dot8c_i32_i4_e32 v43, v135, v51
	v_dot8c_i32_i4_e32 v44, v137, v53
	v_dot8c_i32_i4_e32 v45, v137, v51
	ds_write_b16 v65, v162
	ds_write_b16_d16_hi v65, v162 offset:128
	ds_write_b16 v65, v163 offset:256
	ds_write_b16_d16_hi v65, v163 offset:384
	ds_write_b16 v65, v164 offset:512
	ds_write_b16_d16_hi v65, v164 offset:640
	ds_write_b16 v65, v165 offset:768
	ds_write_b16_d16_hi v65, v165 offset:896
	ds_write_b16 v65, v166 offset:1024
	ds_write_b16_d16_hi v65, v166 offset:1152
	ds_write_b16 v65, v167 offset:1280
	ds_write_b16_d16_hi v65, v167 offset:1408
	ds_write_b16 v65, v168 offset:1536
	ds_write_b16_d16_hi v65, v168 offset:1664
	ds_write_b16 v65, v169 offset:1792
	ds_write_b16_d16_hi v65, v169 offset:1920
	ds_read_b64 v[202:203], v154
	ds_read_b64 v[204:205], v154 offset:512
	ds_read_b64 v[206:207], v154 offset:1024
	ds_read_b64 v[208:209], v154 offset:1536
	v_and_b32_e32 v78, 0xffff, v25
	v_lshrrev_b32_e32 v79, 16, v25
	v_lshl_add_u32 v78, v78, 7, v150
	v_lshl_add_u32 v79, v79, 7, v151
	s_mov_b32 m0, s99
	s_add_i32 s43, s99, 0x400
	global_load_lds_dwordx4 v78, s[50:51]
	s_mov_b32 m0, s43
	s_nop 0
	global_load_lds_dwordx4 v79, s[50:51]
	s_waitcnt vmcnt(8)
	v_add_u32_e32 v54, s77, v59
	v_add_u32_e32 v55, s77, v60
	v_add_u32_e32 v56, s77, v61
	v_add_u32_e32 v57, s77, v62
	ds_read_b64_tr_b4 v[50:51], v160 offset:384
	ds_read_b64_tr_b4 v[52:53], v160 offset:1408
	ds_read_b64_tr_b4 v[130:131], v54
	ds_read_b64_tr_b4 v[132:133], v55
	ds_read_b64_tr_b4 v[134:135], v56
	ds_read_b64_tr_b4 v[136:137], v57
	s_waitcnt lgkmcnt(15)
	v_dot8c_i32_i4_e32 v38, v122, v48
	v_dot8c_i32_i4_e32 v39, v122, v46
	v_dot8c_i32_i4_e32 v40, v124, v48
	v_dot8c_i32_i4_e32 v41, v124, v46
	v_dot8c_i32_i4_e32 v42, v126, v48
	v_dot8c_i32_i4_e32 v43, v126, v46
	v_dot8c_i32_i4_e32 v44, v128, v48
	v_dot8c_i32_i4_e32 v45, v128, v46
	v_dot8c_i32_i4_e32 v38, v123, v49
	v_dot8c_i32_i4_e32 v39, v123, v47
	v_dot8c_i32_i4_e32 v40, v125, v49
	v_dot8c_i32_i4_e32 v41, v125, v47
	v_dot8c_i32_i4_e32 v42, v127, v49
	v_dot8c_i32_i4_e32 v43, v127, v47
	v_dot8c_i32_i4_e32 v44, v129, v49
	v_dot8c_i32_i4_e32 v45, v129, v47
	s_waitcnt lgkmcnt(15)
	v_and_b32_e32 v78, 0xffff, v26
	v_lshrrev_b32_e32 v79, 16, v26
	v_lshl_add_u32 v78, v78, 7, v150
	v_lshl_add_u32 v79, v79, 7, v151
	s_mov_b32 m0, s76
	s_add_i32 s43, s76, 0x400
	global_load_lds_dwordx4 v78, s[50:51]
	s_mov_b32 m0, s43
	s_nop 0
	global_load_lds_dwordx4 v79, s[50:51]
	s_waitcnt vmcnt(8)
	v_add_u32_e32 v54, s78, v59
	v_add_u32_e32 v55, s78, v60
	v_add_u32_e32 v56, s78, v61
	v_add_u32_e32 v57, s78, v62
	ds_read_b64_tr_b4 v[46:47], v160 offset:512
	ds_read_b64_tr_b4 v[48:49], v160 offset:1536
	ds_read_b64_tr_b4 v[122:123], v54
	ds_read_b64_tr_b4 v[124:125], v55
	ds_read_b64_tr_b4 v[126:127], v56
	ds_read_b64_tr_b4 v[128:129], v57
	s_waitcnt lgkmcnt(6)
	v_dot8c_i32_i4_e32 v38, v130, v52
	v_dot8c_i32_i4_e32 v39, v130, v50
	v_dot8c_i32_i4_e32 v40, v132, v52
	v_dot8c_i32_i4_e32 v41, v132, v50
	v_dot8c_i32_i4_e32 v42, v134, v52
	v_dot8c_i32_i4_e32 v43, v134, v50
	v_dot8c_i32_i4_e32 v44, v136, v52
	v_dot8c_i32_i4_e32 v45, v136, v50
	v_dot8c_i32_i4_e32 v38, v131, v53
	v_dot8c_i32_i4_e32 v39, v131, v51
	v_dot8c_i32_i4_e32 v40, v133, v53
	v_dot8c_i32_i4_e32 v41, v133, v51
	v_dot8c_i32_i4_e32 v42, v135, v53
	v_dot8c_i32_i4_e32 v43, v135, v51
	v_dot8c_i32_i4_e32 v44, v137, v53
	v_dot8c_i32_i4_e32 v45, v137, v51
	v_and_b32_e32 v78, 0xffff, v27
	v_lshrrev_b32_e32 v79, 16, v27
	v_lshl_add_u32 v78, v78, 7, v150
	v_lshl_add_u32 v79, v79, 7, v151
	s_mov_b32 m0, s77
	s_add_i32 s43, s77, 0x400
	global_load_lds_dwordx4 v78, s[50:51]
	s_mov_b32 m0, s43
	s_nop 0
	global_load_lds_dwordx4 v79, s[50:51]
	s_waitcnt vmcnt(8)
; #define LAS __attribute__((address_space(3)))
; #define TR4(p_) __builtin_amdgcn_ds_read_tr4_b64_v2i32((LAS v2i*)(p_))
; __device__ __forceinline__ void peer_v_tokens(int j, const LAS unsigned short* EL, const LAS unsigned char* AL  , const LAS float* ASC  , const LAS int* SAL  , ...
;     ...
; #pragma unroll
;         for (int m = 0; m < 2; ++m) {
;             const int idx = lane + 64 * m, tau = idx >> 4, sr = idx & 15, k = 16 * (sr & 7) + 2 * tau + (sr >> 3);
;             const int aq = (int)*(const LAS signed char*)(AL + tl * 128 + k); const int tq = aq + 8;
;             const unsigned lo = (((unsigned)tq & 15u) ^ 8u) * 0x11111111u, hi = ((unsigned)(tq >> 4) & 15u) * 0x11111111u;
;             typedef unsigned u2v __attribute__((ext_vector_type(2)));
;             u2v l2; l2.x = lo; l2.y = lo; u2v h2; h2.x = hi; h2.y = hi;
;             *(LAS u2v*)(ATL + 8 * idx) = l2; *(LAS u2v*)(ATL + 1024 + 8 * idx) = h2;
;         }
;     ...
;         for (int st = 0; st < 16; ++st) {
;             const int p = st >> 2, q = st & 3;
;             if (st < 14) VDMA(st + 2, (st + 2) % 3);
;             if (st < 14) asm volatile("s_waitcnt vmcnt(8)" ::: "memory");
;             else if (st == 14) asm volatile("s_waitcnt vmcnt(4)" ::: "memory");
;             else asm volatile("s_waitcnt vmcnt(0)" ::: "memory");
;             if (q == 0) {
; #pragma unroll
;                 for (int r = 0; r < 4; ++r) { accH[r] = 0; accL[r] = 0; } }
; #pragma unroll
;             for (int tp = 0; tp < 2; ++tp) {
;                 const v2i ao = TR4(ATL + (2 * q + tp) * 128 + 8 * s16), ah = TR4(ATL + 1024 + (2 * q + tp) * 128 + 8 * s16);
; #pragma unroll
;                 for (int r = 0; r < 4; ++r) {
;                     const v2i d = TR4(ldsb + BUF[st % 3] + 2048 * tp + roff[r]);
;                     accH[r] = __builtin_amdgcn_sdot8(d.x, ah.x, accH[r], false); accH[r] = __builtin_amdgcn_sdot8(d.y, ah.y, accH[r], false);
;                     accL[r] = __builtin_amdgcn_sdot8(d.x, ao.x, accL[r], false); accL[r] = __builtin_amdgcn_sdot8(d.y, ao.y, accL[r], false);
;                 }
;             }
	v_add_u32_e32 v54, s79, v59
	v_add_u32_e32 v55, s79, v60
	v_add_u32_e32 v56, s79, v61
	v_add_u32_e32 v57, s79, v62
	ds_read_b64_tr_b4 v[50:51], v160 offset:640
	ds_read_b64_tr_b4 v[52:53], v160 offset:1664
	ds_read_b64_tr_b4 v[130:131], v54
	ds_read_b64_tr_b4 v[132:133], v55
	ds_read_b64_tr_b4 v[134:135], v56
	ds_read_b64_tr_b4 v[136:137], v57
	s_waitcnt lgkmcnt(6)
	v_dot8c_i32_i4_e32 v38, v122, v48
	v_dot8c_i32_i4_e32 v39, v122, v46
	v_dot8c_i32_i4_e32 v40, v124, v48
	v_dot8c_i32_i4_e32 v41, v124, v46
	v_dot8c_i32_i4_e32 v42, v126, v48
	v_dot8c_i32_i4_e32 v43, v126, v46
	v_dot8c_i32_i4_e32 v44, v128, v48
	v_dot8c_i32_i4_e32 v45, v128, v46
	v_dot8c_i32_i4_e32 v38, v123, v49
	v_dot8c_i32_i4_e32 v39, v123, v47
	v_dot8c_i32_i4_e32 v40, v125, v49
	v_dot8c_i32_i4_e32 v41, v125, v47
	v_dot8c_i32_i4_e32 v42, v127, v49
	v_dot8c_i32_i4_e32 v43, v127, v47
	v_dot8c_i32_i4_e32 v44, v129, v49
	v_dot8c_i32_i4_e32 v45, v129, v47
	s_waitcnt lgkmcnt(15)
	v_add_u32_e32 v143, 8, v139
	v_and_b32_e32 v142, 15, v143
	v_xor_b32_e32 v142, 8, v142
	v_bfe_u32 v144, v143, 4, 4
	v_mul_lo_u32 v142, v142, s92
	v_mul_lo_u32 v144, v144, s92
	v_mov_b32_e32 v143, v142
	v_mov_b32_e32 v145, v144
	ds_write2st64_b64 v159, v[142:143], v[144:145] offset1:2
	v_and_b32_e32 v78, 0xffff, v28
	v_lshrrev_b32_e32 v79, 16, v28
	v_lshl_add_u32 v78, v78, 7, v150
	v_lshl_add_u32 v79, v79, 7, v151
	s_mov_b32 m0, s78
	s_add_i32 s43, s78, 0x400
	global_load_lds_dwordx4 v78, s[50:51]
	s_mov_b32 m0, s43
	s_nop 0
	global_load_lds_dwordx4 v79, s[50:51]
	s_waitcnt vmcnt(8)
	v_add_u32_e32 v54, s98, v59
	v_add_u32_e32 v55, s98, v60
	v_add_u32_e32 v56, s98, v61
	v_add_u32_e32 v57, s98, v62
	ds_read_b64_tr_b4 v[46:47], v160 offset:768
	ds_read_b64_tr_b4 v[48:49], v160 offset:1792
	ds_read_b64_tr_b4 v[122:123], v54
	ds_read_b64_tr_b4 v[124:125], v55
	ds_read_b64_tr_b4 v[126:127], v56
	ds_read_b64_tr_b4 v[128:129], v57
	s_waitcnt lgkmcnt(7)
	v_dot8c_i32_i4_e32 v38, v130, v52
	v_dot8c_i32_i4_e32 v39, v130, v50
	v_dot8c_i32_i4_e32 v40, v132, v52
	v_dot8c_i32_i4_e32 v41, v132, v50
	v_dot8c_i32_i4_e32 v42, v134, v52
	v_dot8c_i32_i4_e32 v43, v134, v50
	v_dot8c_i32_i4_e32 v44, v136, v52
	v_dot8c_i32_i4_e32 v45, v136, v50
	v_dot8c_i32_i4_e32 v38, v131, v53
	v_dot8c_i32_i4_e32 v39, v131, v51
	v_dot8c_i32_i4_e32 v40, v133, v53
	v_dot8c_i32_i4_e32 v41, v133, v51
	v_dot8c_i32_i4_e32 v42, v135, v53
	v_dot8c_i32_i4_e32 v43, v135, v51
	v_dot8c_i32_i4_e32 v44, v137, v53
	v_dot8c_i32_i4_e32 v45, v137, v51
	v_and_b32_e32 v78, 0xffff, v29
	v_lshrrev_b32_e32 v79, 16, v29
	v_lshl_add_u32 v78, v78, 7, v150
	v_lshl_add_u32 v79, v79, 7, v151
	s_mov_b32 m0, s79
	s_add_i32 s43, s79, 0x400
	global_load_lds_dwordx4 v78, s[50:51]
	s_mov_b32 m0, s43
	s_nop 0
	global_load_lds_dwordx4 v79, s[50:51]
	s_waitcnt vmcnt(8)
	v_add_u32_e32 v54, s99, v59
	v_add_u32_e32 v55, s99, v60
	v_add_u32_e32 v56, s99, v61
	v_add_u32_e32 v57, s99, v62
	ds_read_b64_tr_b4 v[50:51], v160 offset:896
	ds_read_b64_tr_b4 v[52:53], v160 offset:1920
	ds_read_b64_tr_b4 v[130:131], v54
	ds_read_b64_tr_b4 v[132:133], v55
	ds_read_b64_tr_b4 v[134:135], v56
	ds_read_b64_tr_b4 v[136:137], v57
	s_waitcnt lgkmcnt(6)
	v_dot8c_i32_i4_e32 v38, v122, v48
	v_dot8c_i32_i4_e32 v39, v122, v46
	v_dot8c_i32_i4_e32 v40, v124, v48
	v_dot8c_i32_i4_e32 v41, v124, v46
	v_dot8c_i32_i4_e32 v42, v126, v48
	v_dot8c_i32_i4_e32 v43, v126, v46
	v_dot8c_i32_i4_e32 v44, v128, v48
	v_dot8c_i32_i4_e32 v45, v128, v46
	v_dot8c_i32_i4_e32 v38, v123, v49
	v_dot8c_i32_i4_e32 v39, v123, v47
	v_dot8c_i32_i4_e32 v40, v125, v49
	v_dot8c_i32_i4_e32 v41, v125, v47
	v_dot8c_i32_i4_e32 v42, v127, v49
	v_dot8c_i32_i4_e32 v43, v127, v47
	v_dot8c_i32_i4_e32 v44, v129, v49
	v_dot8c_i32_i4_e32 v45, v129, v47
	v_and_b32_e32 v78, 0xffff, v30
	v_lshrrev_b32_e32 v79, 16, v30
	v_lshl_add_u32 v78, v78, 7, v150
	v_lshl_add_u32 v79, v79, 7, v151
	s_mov_b32 m0, s98
	s_add_i32 s43, s98, 0x400
	global_load_lds_dwordx4 v78, s[50:51]
	s_mov_b32 m0, s43
	s_nop 0
	global_load_lds_dwordx4 v79, s[50:51]
	s_waitcnt vmcnt(8)
	v_add_u32_e32 v54, s76, v59
	v_add_u32_e32 v55, s76, v60
	v_add_u32_e32 v56, s76, v61
	v_add_u32_e32 v57, s76, v62
	ds_read_b64_tr_b4 v[46:47], v160
	ds_read_b64_tr_b4 v[48:49], v160 offset:1024
	ds_read_b64_tr_b4 v[122:123], v54
	ds_read_b64_tr_b4 v[124:125], v55
	ds_read_b64_tr_b4 v[126:127], v56
	ds_read_b64_tr_b4 v[128:129], v57
	s_waitcnt lgkmcnt(6)
	v_dot8c_i32_i4_e32 v38, v130, v52
	v_dot8c_i32_i4_e32 v39, v130, v50
	v_dot8c_i32_i4_e32 v40, v132, v52
	v_dot8c_i32_i4_e32 v41, v132, v50
	v_dot8c_i32_i4_e32 v42, v134, v52
	v_dot8c_i32_i4_e32 v43, v134, v50
	v_dot8c_i32_i4_e32 v44, v136, v52
	v_dot8c_i32_i4_e32 v45, v136, v50
	v_dot8c_i32_i4_e32 v38, v131, v53
	v_dot8c_i32_i4_e32 v39, v131, v51
	v_dot8c_i32_i4_e32 v40, v133, v53
	v_dot8c_i32_i4_e32 v41, v133, v51
	v_dot8c_i32_i4_e32 v42, v135, v53
	v_dot8c_i32_i4_e32 v43, v135, v51
	v_dot8c_i32_i4_e32 v44, v137, v53
	v_dot8c_i32_i4_e32 v45, v137, v51
	s_nop 3
	s_waitcnt lgkmcnt(15)
; #define LAS __attribute__((address_space(3)))
; __device__ __forceinline__ bf16 f2bf(float f) { return (bf16)f2bfu(f); }
; #define CFENCE() asm volatile("" ::: "memory")
; __device__ __forceinline__ void peer_v_tokens(int j, const LAS unsigned short* EL, const LAS unsigned char* AL  , const LAS float* ASC  , const LAS int* SAL  , ...
;     ...
;             if (q == 3) {
; #pragma unroll
;                 for (int r = 0; r < 4; ++r) STASH[256 * p + 16 * (grp + 4 * r) + pc] = f2bf(asc * (float)(2 * ((accH[r] << 4) + accL[r]) + sa));
;             }
;         }
;         CFENCE();
;         {
;             float4 v[4]; float ss = 0.f;
; #pragma unroll
;             for (int jq = 0; jq < 4; ++jq) { typedef unsigned u2v __attribute__((ext_vector_type(2))); const u2v pw = *(const LAS u2v*)(STASH + 4 * lane + 256 * jq); const uint2 hw = hv[jq];
;                 v[jq] = make_float4(__uint_as_float(hw.x << 16) + __uint_as_float(pw.x << 16), __uint_as_float(hw.x & 0xffff0000u) + __uint_as_float(pw.x & 0xffff0000u),
;                                     __uint_as_float(hw.y << 16) + __uint_as_float(pw.y << 16), __uint_as_float(hw.y & 0xffff0000u) + __uint_as_float(pw.y & 0xffff0000u));
;                 ss += v[jq].x * v[jq].x + v[jq].y * v[jq].y + v[jq].z * v[jq].z + v[jq].w * v[jq].w; }
;             ss = wave_sum(ss);
;             const float r3 = rsqrtf(ss * (1.f / D) + EPS);
	v_lshlrev_b32_e32 v38, 5, v38
	v_lshlrev_b32_e32 v39, 1, v39
	v_add3_u32 v38, v39, v229, v38
	v_cvt_f32_i32_e32 v38, v38
	v_mul_f32_e32 v38, v228, v38
	v_lshlrev_b32_e32 v40, 5, v40
	v_lshlrev_b32_e32 v41, 1, v41
	v_add3_u32 v40, v41, v229, v40
	v_cvt_f32_i32_e32 v40, v40
	v_mul_f32_e32 v40, v228, v40
	v_lshlrev_b32_e32 v42, 5, v42
	v_lshlrev_b32_e32 v43, 1, v43
	v_add3_u32 v42, v43, v229, v42
	v_cvt_f32_i32_e32 v42, v42
	v_mul_f32_e32 v42, v228, v42
	v_lshlrev_b32_e32 v44, 5, v44
	v_lshlrev_b32_e32 v45, 1, v45
	v_add3_u32 v44, v45, v229, v44
	v_cvt_f32_i32_e32 v44, v44
	v_mul_f32_e32 v44, v228, v44
	v_cvt_pk_bf16_f32 v178, v38, v40
	v_cvt_pk_bf16_f32 v179, v42, v44
	v_add_u32_e32 v147, 8, v140
	v_and_b32_e32 v146, 15, v147
	v_xor_b32_e32 v146, 8, v146
	v_bfe_u32 v148, v147, 4, 4
	v_mul_lo_u32 v146, v146, s92
	v_mul_lo_u32 v148, v148, s92
	v_mov_b32_e32 v147, v146
	v_mov_b32_e32 v149, v148
	ds_write2st64_b64 v77, v[146:147], v[148:149] offset1:2
	v_add_u32_e32 v138, 0x800, v74
	ds_read_u8 v139, v138
	v_add_u32_e32 v141, 0x800, v73
	ds_read_u8 v140, v141
	s_add_i32 s43, s67, 96
	v_mov_b32_e32 v138, s43
	ds_read2st64_b32 v[228:229], v138 offset1:1
	ds_read_b128 v[18:21], v227 offset:4096
	ds_read_b128 v[22:25], v227 offset:4112
	v_add_u32_e32 v152, 0x200000, v63
	v_add_u32_e32 v153, 0x200000, v64
	v_mov_b32_e32 v38, 0
	v_mov_b32_e32 v39, 0
	v_mov_b32_e32 v40, 0
	v_mov_b32_e32 v41, 0
	v_mov_b32_e32 v42, 0
	v_mov_b32_e32 v43, 0
	v_mov_b32_e32 v44, 0
	v_mov_b32_e32 v45, 0
	v_and_b32_e32 v78, 0xffff, v31
	v_lshrrev_b32_e32 v79, 16, v31
	v_lshl_add_u32 v78, v78, 7, v150
	v_lshl_add_u32 v79, v79, 7, v151
	s_mov_b32 m0, s99
	s_add_i32 s43, s99, 0x400
	global_load_lds_dwordx4 v78, s[50:51]
	s_mov_b32 m0, s43
	s_nop 0
	global_load_lds_dwordx4 v79, s[50:51]
	s_waitcnt vmcnt(8)
	v_add_u32_e32 v54, s77, v59
	v_add_u32_e32 v55, s77, v60
	v_add_u32_e32 v56, s77, v61
	v_add_u32_e32 v57, s77, v62
	ds_read_b64_tr_b4 v[50:51], v160 offset:128
	ds_read_b64_tr_b4 v[52:53], v160 offset:1152
	ds_read_b64_tr_b4 v[130:131], v54
	ds_read_b64_tr_b4 v[132:133], v55
	ds_read_b64_tr_b4 v[134:135], v56
	ds_read_b64_tr_b4 v[136:137], v57
	s_waitcnt lgkmcnt(12)
	s_waitcnt vmcnt(34) lgkmcnt(15)
	v_lshlrev_b32_e32 v210, 16, v194
	v_and_b32_e32 v211, 0xffff0000, v194
	v_lshlrev_b32_e32 v142, 16, v202
	v_and_b32_e32 v143, 0xffff0000, v202
	v_add_f32_e32 v210, v210, v142
	v_add_f32_e32 v211, v211, v143
	v_lshlrev_b32_e32 v212, 16, v195
	v_and_b32_e32 v213, 0xffff0000, v195
	v_lshlrev_b32_e32 v142, 16, v203
	v_and_b32_e32 v143, 0xffff0000, v203
	v_add_f32_e32 v212, v212, v142
	v_add_f32_e32 v213, v213, v143
	v_lshlrev_b32_e32 v214, 16, v196
	v_and_b32_e32 v215, 0xffff0000, v196
	v_lshlrev_b32_e32 v142, 16, v204
	v_and_b32_e32 v143, 0xffff0000, v204
	v_add_f32_e32 v214, v214, v142
	v_add_f32_e32 v215, v215, v143
	v_lshlrev_b32_e32 v216, 16, v197
	v_and_b32_e32 v217, 0xffff0000, v197
	v_lshlrev_b32_e32 v142, 16, v205
	v_and_b32_e32 v143, 0xffff0000, v205
	v_add_f32_e32 v216, v216, v142
	v_add_f32_e32 v217, v217, v143
	v_lshlrev_b32_e32 v218, 16, v198
	v_and_b32_e32 v219, 0xffff0000, v198
	v_lshlrev_b32_e32 v142, 16, v206
	v_and_b32_e32 v143, 0xffff0000, v206
	v_add_f32_e32 v218, v218, v142
	v_add_f32_e32 v219, v219, v143
	v_lshlrev_b32_e32 v220, 16, v199
	v_and_b32_e32 v221, 0xffff0000, v199
	v_lshlrev_b32_e32 v142, 16, v207
	v_and_b32_e32 v143, 0xffff0000, v207
	v_add_f32_e32 v220, v220, v142
	v_add_f32_e32 v221, v221, v143
	v_lshlrev_b32_e32 v222, 16, v200
	v_and_b32_e32 v223, 0xffff0000, v200
	v_lshlrev_b32_e32 v142, 16, v208
	v_and_b32_e32 v143, 0xffff0000, v208
	v_add_f32_e32 v222, v222, v142
	v_add_f32_e32 v223, v223, v143
	v_lshlrev_b32_e32 v224, 16, v201
	v_and_b32_e32 v225, 0xffff0000, v201
	v_lshlrev_b32_e32 v142, 16, v209
	v_and_b32_e32 v143, 0xffff0000, v209
	v_add_f32_e32 v224, v224, v142
	v_add_f32_e32 v225, v225, v143
	v_mov_b32_e32 v144, 0
	v_mul_f32_e32 v145, v210, v210
	v_fmac_f32_e32 v145, v211, v211
	v_fmac_f32_e32 v145, v212, v212
	v_fmac_f32_e32 v145, v213, v213
	v_add_f32_e32 v144, v144, v145
	v_mul_f32_e32 v145, v214, v214
	v_fmac_f32_e32 v145, v215, v215
	v_fmac_f32_e32 v145, v216, v216
	v_fmac_f32_e32 v145, v217, v217
	v_add_f32_e32 v144, v144, v145
	v_mul_f32_e32 v145, v218, v218
	v_fmac_f32_e32 v145, v219, v219
	v_fmac_f32_e32 v145, v220, v220
	v_fmac_f32_e32 v145, v221, v221
	v_add_f32_e32 v144, v144, v145
	v_mul_f32_e32 v145, v222, v222
	v_fmac_f32_e32 v145, v223, v223
	v_fmac_f32_e32 v145, v224, v224
	v_fmac_f32_e32 v145, v225, v225
	v_add_f32_e32 v144, v144, v145
	s_nop 1
	v_add_f32_dpp v144, v144, v144 quad_perm:[1,0,3,2] row_mask:0xf bank_mask:0xf bound_ctrl:1
	s_nop 1
	v_add_f32_dpp v144, v144, v144 quad_perm:[2,3,0,1] row_mask:0xf bank_mask:0xf bound_ctrl:1
	s_nop 1
	v_add_f32_dpp v144, v144, v144 row_half_mirror row_mask:0xf bank_mask:0xf bound_ctrl:1
	s_nop 1
	v_add_f32_dpp v144, v144, v144 row_mirror row_mask:0xf bank_mask:0xf bound_ctrl:1
	s_nop 1
	v_readlane_b32 s10, v144, 0
	v_readlane_b32 s11, v144, 16
	v_readlane_b32 s14, v144, 32
	v_readlane_b32 s15, v144, 48
	s_nop 3
	v_mov_b32_e32 v144, s11
	v_mov_b32_e32 v145, s15
	v_add_f32_e32 v144, s10, v144
	v_add_f32_e32 v145, s14, v145
	v_add_f32_e32 v144, v144, v145
	v_fmamk_f32 v144, v144, 0x3a800000, v111
	v_rsq_f32_e32 v144, v144
	s_nop 0
	v_mul_f32_e32 v210, v210, v144
	v_mul_f32_e32 v211, v211, v144
	v_mul_f32_e32 v212, v212, v144
	v_mul_f32_e32 v213, v213, v144
	v_mul_f32_e32 v214, v214, v144
	v_mul_f32_e32 v215, v215, v144
	v_mul_f32_e32 v216, v216, v144
	v_mul_f32_e32 v217, v217, v144
	v_mul_f32_e32 v218, v218, v144
	v_mul_f32_e32 v219, v219, v144
	v_mul_f32_e32 v220, v220, v144
	v_mul_f32_e32 v221, v221, v144
	v_mul_f32_e32 v222, v222, v144
	v_mul_f32_e32 v223, v223, v144
	v_mul_f32_e32 v224, v224, v144
	v_mul_f32_e32 v225, v225, v144
	v_dot8c_i32_i4_e32 v38, v122, v48
	v_dot8c_i32_i4_e32 v39, v122, v46
	v_dot8c_i32_i4_e32 v40, v124, v48
	v_dot8c_i32_i4_e32 v41, v124, v46
	v_dot8c_i32_i4_e32 v42, v126, v48
	v_dot8c_i32_i4_e32 v43, v126, v46
	v_dot8c_i32_i4_e32 v44, v128, v48
	v_dot8c_i32_i4_e32 v45, v128, v46
	v_dot8c_i32_i4_e32 v38, v123, v49
	v_dot8c_i32_i4_e32 v39, v123, v47
	v_dot8c_i32_i4_e32 v40, v125, v49
	v_dot8c_i32_i4_e32 v41, v125, v47
	v_dot8c_i32_i4_e32 v42, v127, v49
	v_dot8c_i32_i4_e32 v43, v127, v47
	v_dot8c_i32_i4_e32 v44, v129, v49
	v_dot8c_i32_i4_e32 v45, v129, v47
	v_and_b32_e32 v78, 0xffff, v32
	v_lshrrev_b32_e32 v79, 16, v32
	v_lshl_add_u32 v78, v78, 7, v150
	v_lshl_add_u32 v79, v79, 7, v151
	s_mov_b32 m0, s76
	s_add_i32 s43, s76, 0x400
	global_load_lds_dwordx4 v78, s[50:51]
	s_mov_b32 m0, s43
	s_nop 0
	global_load_lds_dwordx4 v79, s[50:51]
	s_waitcnt vmcnt(8)
; #define TR4(p_) __builtin_amdgcn_ds_read_tr4_b64_v2i32((LAS v2i*)(p_))
; #define VDMA(st_, k_) do { _Pragma("unroll") for (int i_ = 0; i_ < 4; ++i_) { \
;         const unsigned off_ = (unsigned)((st_) >> 2) * (16384u * 128u) + (PE_ID(E, 4 * ((st_) & 3) + i_) << 7) + ((i_ & 1) ? cx1 : cx0); \
;         __builtin_amdgcn_global_load_lds((const unsigned*)(V4 + off_), (LAS unsigned*)(ldsb + BUF[k_] + 1024 * i_), 16, 0, 0); } } while (0)
; __device__ __forceinline__ void peer_v_tokens(int j, const LAS unsigned short* EL, const LAS unsigned char* AL  , const LAS float* ASC  , const LAS int* SAL  , ...
;     ...
;             if (st < 14) VDMA(st + 2, (st + 2) % 3);
;             if (st < 14) asm volatile("s_waitcnt vmcnt(8)" ::: "memory");
;             else if (st == 14) asm volatile("s_waitcnt vmcnt(4)" ::: "memory");
;             else asm volatile("s_waitcnt vmcnt(0)" ::: "memory");
;             if (q == 0) {
; #pragma unroll
;                 for (int r = 0; r < 4; ++r) { accH[r] = 0; accL[r] = 0; } }
; #pragma unroll
;             for (int tp = 0; tp < 2; ++tp) {
;                 const v2i ao = TR4(ATL + (2 * q + tp) * 128 + 8 * s16), ah = TR4(ATL + 1024 + (2 * q + tp) * 128 + 8 * s16);
; #pragma unroll
;                 for (int r = 0; r < 4; ++r) {
;                     const v2i d = TR4(ldsb + BUF[st % 3] + 2048 * tp + roff[r]);
;                     accH[r] = __builtin_amdgcn_sdot8(d.x, ah.x, accH[r], false); accH[r] = __builtin_amdgcn_sdot8(d.y, ah.y, accH[r], false);
;                     accL[r] = __builtin_amdgcn_sdot8(d.x, ao.x, accL[r], false); accL[r] = __builtin_amdgcn_sdot8(d.y, ao.y, accL[r], false);
;                 }
	v_add_u32_e32 v54, s78, v59
	v_add_u32_e32 v55, s78, v60
	v_add_u32_e32 v56, s78, v61
	v_add_u32_e32 v57, s78, v62
	ds_read_b64_tr_b4 v[46:47], v160 offset:256
	ds_read_b64_tr_b4 v[48:49], v160 offset:1280
	ds_read_b64_tr_b4 v[122:123], v54
	ds_read_b64_tr_b4 v[124:125], v55
	ds_read_b64_tr_b4 v[126:127], v56
	ds_read_b64_tr_b4 v[128:129], v57
	s_waitcnt lgkmcnt(6)
	v_dot8c_i32_i4_e32 v38, v130, v52
	v_dot8c_i32_i4_e32 v39, v130, v50
	v_dot8c_i32_i4_e32 v40, v132, v52
	v_dot8c_i32_i4_e32 v41, v132, v50
	v_dot8c_i32_i4_e32 v42, v134, v52
	v_dot8c_i32_i4_e32 v43, v134, v50
	v_dot8c_i32_i4_e32 v44, v136, v52
	v_dot8c_i32_i4_e32 v45, v136, v50
	v_dot8c_i32_i4_e32 v38, v131, v53
	v_dot8c_i32_i4_e32 v39, v131, v51
	v_dot8c_i32_i4_e32 v40, v133, v53
	v_dot8c_i32_i4_e32 v41, v133, v51
	v_dot8c_i32_i4_e32 v42, v135, v53
	v_dot8c_i32_i4_e32 v43, v135, v51
	v_dot8c_i32_i4_e32 v44, v137, v53
	v_dot8c_i32_i4_e32 v45, v137, v51
	v_and_b32_e32 v78, 0xffff, v33
	v_lshrrev_b32_e32 v79, 16, v33
	v_lshl_add_u32 v78, v78, 7, v150
	v_lshl_add_u32 v79, v79, 7, v151
	s_mov_b32 m0, s77
	s_add_i32 s43, s77, 0x400
	global_load_lds_dwordx4 v78, s[50:51]
	s_mov_b32 m0, s43
	s_nop 0
	global_load_lds_dwordx4 v79, s[50:51]
	s_waitcnt vmcnt(8)
	v_add_u32_e32 v54, s79, v59
	v_add_u32_e32 v55, s79, v60
	v_add_u32_e32 v56, s79, v61
	v_add_u32_e32 v57, s79, v62
	ds_read_b64_tr_b4 v[50:51], v160 offset:384
	ds_read_b64_tr_b4 v[52:53], v160 offset:1408
	ds_read_b64_tr_b4 v[130:131], v54
	ds_read_b64_tr_b4 v[132:133], v55
	ds_read_b64_tr_b4 v[134:135], v56
	ds_read_b64_tr_b4 v[136:137], v57
	s_waitcnt lgkmcnt(6)
	v_dot8c_i32_i4_e32 v38, v122, v48
	v_dot8c_i32_i4_e32 v39, v122, v46
	v_dot8c_i32_i4_e32 v40, v124, v48
	v_dot8c_i32_i4_e32 v41, v124, v46
	v_dot8c_i32_i4_e32 v42, v126, v48
	v_dot8c_i32_i4_e32 v43, v126, v46
	v_dot8c_i32_i4_e32 v44, v128, v48
	v_dot8c_i32_i4_e32 v45, v128, v46
	v_dot8c_i32_i4_e32 v38, v123, v49
	v_dot8c_i32_i4_e32 v39, v123, v47
	v_dot8c_i32_i4_e32 v40, v125, v49
	v_dot8c_i32_i4_e32 v41, v125, v47
	v_dot8c_i32_i4_e32 v42, v127, v49
	v_dot8c_i32_i4_e32 v43, v127, v47
	v_dot8c_i32_i4_e32 v44, v129, v49
	v_dot8c_i32_i4_e32 v45, v129, v47
	s_waitcnt lgkmcnt(15)
	v_and_b32_e32 v78, 0xffff, v18
	v_lshrrev_b32_e32 v79, 16, v18
	v_lshl_add_u32 v78, v78, 7, v152
	v_lshl_add_u32 v79, v79, 7, v153
	s_mov_b32 m0, s78
	s_add_i32 s43, s78, 0x400
	global_load_lds_dwordx4 v78, s[50:51]
	s_mov_b32 m0, s43
	s_nop 0
	global_load_lds_dwordx4 v79, s[50:51]
	s_waitcnt vmcnt(8)
	v_add_u32_e32 v54, s98, v59
	v_add_u32_e32 v55, s98, v60
	v_add_u32_e32 v56, s98, v61
	v_add_u32_e32 v57, s98, v62
	ds_read_b64_tr_b4 v[46:47], v160 offset:512
	ds_read_b64_tr_b4 v[48:49], v160 offset:1536
	ds_read_b64_tr_b4 v[122:123], v54
	ds_read_b64_tr_b4 v[124:125], v55
	ds_read_b64_tr_b4 v[126:127], v56
	ds_read_b64_tr_b4 v[128:129], v57
	s_waitcnt lgkmcnt(6)
	v_dot8c_i32_i4_e32 v38, v130, v52
	v_dot8c_i32_i4_e32 v39, v130, v50
	v_dot8c_i32_i4_e32 v40, v132, v52
	v_dot8c_i32_i4_e32 v41, v132, v50
	v_dot8c_i32_i4_e32 v42, v134, v52
	v_dot8c_i32_i4_e32 v43, v134, v50
	v_dot8c_i32_i4_e32 v44, v136, v52
	v_dot8c_i32_i4_e32 v45, v136, v50
	v_dot8c_i32_i4_e32 v38, v131, v53
	v_dot8c_i32_i4_e32 v39, v131, v51
	v_dot8c_i32_i4_e32 v40, v133, v53
	v_dot8c_i32_i4_e32 v41, v133, v51
	v_dot8c_i32_i4_e32 v42, v135, v53
	v_dot8c_i32_i4_e32 v43, v135, v51
	v_dot8c_i32_i4_e32 v44, v137, v53
	v_dot8c_i32_i4_e32 v45, v137, v51
	v_and_b32_e32 v78, 0xffff, v19
	v_lshrrev_b32_e32 v79, 16, v19
	v_lshl_add_u32 v78, v78, 7, v152
	v_lshl_add_u32 v79, v79, 7, v153
	s_mov_b32 m0, s79
	s_add_i32 s43, s79, 0x400
	global_load_lds_dwordx4 v78, s[50:51]
	s_mov_b32 m0, s43
	s_nop 0
	global_load_lds_dwordx4 v79, s[50:51]
	s_waitcnt vmcnt(8)
	v_add_u32_e32 v54, s99, v59
	v_add_u32_e32 v55, s99, v60
	v_add_u32_e32 v56, s99, v61
	v_add_u32_e32 v57, s99, v62
	ds_read_b64_tr_b4 v[50:51], v160 offset:640
	ds_read_b64_tr_b4 v[52:53], v160 offset:1664
	ds_read_b64_tr_b4 v[130:131], v54
	ds_read_b64_tr_b4 v[132:133], v55
	ds_read_b64_tr_b4 v[134:135], v56
	ds_read_b64_tr_b4 v[136:137], v57
	s_waitcnt lgkmcnt(6)
	v_dot8c_i32_i4_e32 v38, v122, v48
	v_dot8c_i32_i4_e32 v39, v122, v46
	v_dot8c_i32_i4_e32 v40, v124, v48
	v_dot8c_i32_i4_e32 v41, v124, v46
	v_dot8c_i32_i4_e32 v42, v126, v48
	v_dot8c_i32_i4_e32 v43, v126, v46
	v_dot8c_i32_i4_e32 v44, v128, v48
	v_dot8c_i32_i4_e32 v45, v128, v46
	v_dot8c_i32_i4_e32 v38, v123, v49
	v_dot8c_i32_i4_e32 v39, v123, v47
	v_dot8c_i32_i4_e32 v40, v125, v49
	v_dot8c_i32_i4_e32 v41, v125, v47
	v_dot8c_i32_i4_e32 v42, v127, v49
	v_dot8c_i32_i4_e32 v43, v127, v47
	v_dot8c_i32_i4_e32 v44, v129, v49
	v_dot8c_i32_i4_e32 v45, v129, v47
	s_waitcnt lgkmcnt(15)
	v_add_u32_e32 v143, 8, v139
	v_and_b32_e32 v142, 15, v143
	v_xor_b32_e32 v142, 8, v142
	v_bfe_u32 v144, v143, 4, 4
	v_mul_lo_u32 v142, v142, s92
	v_mul_lo_u32 v144, v144, s92
	v_mov_b32_e32 v143, v142
	v_mov_b32_e32 v145, v144
	ds_write2st64_b64 v159, v[142:143], v[144:145] offset1:2
	v_and_b32_e32 v78, 0xffff, v20
	v_lshrrev_b32_e32 v79, 16, v20
	v_lshl_add_u32 v78, v78, 7, v152
	v_lshl_add_u32 v79, v79, 7, v153
	s_mov_b32 m0, s98
	s_add_i32 s43, s98, 0x400
	global_load_lds_dwordx4 v78, s[50:51]
	s_mov_b32 m0, s43
	s_nop 0
	global_load_lds_dwordx4 v79, s[50:51]
	s_waitcnt vmcnt(8)
	v_add_u32_e32 v54, s76, v59
	v_add_u32_e32 v55, s76, v60
	v_add_u32_e32 v56, s76, v61
	v_add_u32_e32 v57, s76, v62
	ds_read_b64_tr_b4 v[46:47], v160 offset:768
	ds_read_b64_tr_b4 v[48:49], v160 offset:1792
	ds_read_b64_tr_b4 v[122:123], v54
	ds_read_b64_tr_b4 v[124:125], v55
	ds_read_b64_tr_b4 v[126:127], v56
	ds_read_b64_tr_b4 v[128:129], v57
	s_waitcnt lgkmcnt(7)
; #define LAS __attribute__((address_space(3)))
; __device__ __forceinline__ void peer_v_tokens(int j, const LAS unsigned short* EL, const LAS unsigned char* AL  , const LAS float* ASC  , const LAS int* SAL  , ...
;     ...
;         { const LAS v4u* ep = (const LAS v4u*)(EL + tl * 128 + 16 * g); const v4u e0 = ep[0], e1 = ep[1];
;           E[0] = e0.x; E[1] = e0.y; E[2] = e0.z; E[3] = e0.w; E[4] = e1.x; E[5] = e1.y; E[6] = e1.z; E[7] = e1.w; }
;         uint2 hv[4]; float4 gv[4];
;         { unsigned ho = (unsigned)t * (D / 4) + (unsigned)lane; asm volatile("" : "+v"(ho)); const uint2* hp = (const uint2*)HB + ho; const float4* gp = (const float4*)fng + lane;
; #pragma unroll
;           for (int jq = 0; jq < 4; ++jq) { hv[jq] = hp[64 * jq]; gv[jq] = gp[64 * jq]; } }
;         VDMA(0, 0); VDMA(1, 1);
; #pragma unroll
;         for (int m = 0; m < 2; ++m) {
;             const int idx = lane + 64 * m, tau = idx >> 4, sr = idx & 15, k = 16 * (sr & 7) + 2 * tau + (sr >> 3);
;     ...
;         for (int st = 0; st < 16; ++st) {
;             const int p = st >> 2, q = st & 3;
;             if (st < 14) VDMA(st + 2, (st + 2) % 3);
;             if (st < 14) asm volatile("s_waitcnt vmcnt(8)" ::: "memory");
;             else if (st == 14) asm volatile("s_waitcnt vmcnt(4)" ::: "memory");
;             else asm volatile("s_waitcnt vmcnt(0)" ::: "memory");
;             if (q == 0) {
; #pragma unroll
;                 for (int r = 0; r < 4; ++r) { accH[r] = 0; accL[r] = 0; } }
; #pragma unroll
;             for (int tp = 0; tp < 2; ++tp) {
;                 const v2i ao = TR4(ATL + (2 * q + tp) * 128 + 8 * s16), ah = TR4(ATL + 1024 + (2 * q + tp) * 128 + 8 * s16);
; #pragma unroll
;                 for (int r = 0; r < 4; ++r) {
;                     const v2i d = TR4(ldsb + BUF[st % 3] + 2048 * tp + roff[r]);
;                     accH[r] = __builtin_amdgcn_sdot8(d.x, ah.x, accH[r], false); accH[r] = __builtin_amdgcn_sdot8(d.y, ah.y, accH[r], false);
;                     accL[r] = __builtin_amdgcn_sdot8(d.x, ao.x, accL[r], false); accL[r] = __builtin_amdgcn_sdot8(d.y, ao.y, accL[r], false);
;                 }
;             }
;             asm volatile("s_waitcnt lgkmcnt(0)" ::: "memory");
;             if (q == 3) {
; #pragma unroll
;                 for (int r = 0; r < 4; ++r) STASH[256 * p + 16 * (grp + 4 * r) + pc] = f2bf(asc * (float)(2 * ((accH[r] << 4) + accL[r]) + sa));
	v_dot8c_i32_i4_e32 v38, v130, v52
	v_dot8c_i32_i4_e32 v39, v130, v50
	v_dot8c_i32_i4_e32 v40, v132, v52
	v_dot8c_i32_i4_e32 v41, v132, v50
	v_dot8c_i32_i4_e32 v42, v134, v52
	v_dot8c_i32_i4_e32 v43, v134, v50
	v_dot8c_i32_i4_e32 v44, v136, v52
	v_dot8c_i32_i4_e32 v45, v136, v50
	v_dot8c_i32_i4_e32 v38, v131, v53
	v_dot8c_i32_i4_e32 v39, v131, v51
	v_dot8c_i32_i4_e32 v40, v133, v53
	v_dot8c_i32_i4_e32 v41, v133, v51
	v_dot8c_i32_i4_e32 v42, v135, v53
	v_dot8c_i32_i4_e32 v43, v135, v51
	v_dot8c_i32_i4_e32 v44, v137, v53
	v_dot8c_i32_i4_e32 v45, v137, v51
	v_and_b32_e32 v78, 0xffff, v21
	v_lshrrev_b32_e32 v79, 16, v21
	v_lshl_add_u32 v78, v78, 7, v152
	v_lshl_add_u32 v79, v79, 7, v153
	s_mov_b32 m0, s99
	s_add_i32 s43, s99, 0x400
	global_load_lds_dwordx4 v78, s[50:51]
	s_mov_b32 m0, s43
	s_nop 0
	global_load_lds_dwordx4 v79, s[50:51]
	s_waitcnt vmcnt(8)
	v_add_u32_e32 v54, s77, v59
	v_add_u32_e32 v55, s77, v60
	v_add_u32_e32 v56, s77, v61
	v_add_u32_e32 v57, s77, v62
	ds_read_b64_tr_b4 v[50:51], v160 offset:896
	ds_read_b64_tr_b4 v[52:53], v160 offset:1920
	ds_read_b64_tr_b4 v[130:131], v54
	ds_read_b64_tr_b4 v[132:133], v55
	ds_read_b64_tr_b4 v[134:135], v56
	ds_read_b64_tr_b4 v[136:137], v57
	s_waitcnt lgkmcnt(6)
	v_dot8c_i32_i4_e32 v38, v122, v48
	v_dot8c_i32_i4_e32 v39, v122, v46
	v_dot8c_i32_i4_e32 v40, v124, v48
	v_dot8c_i32_i4_e32 v41, v124, v46
	v_dot8c_i32_i4_e32 v42, v126, v48
	v_dot8c_i32_i4_e32 v43, v126, v46
	v_dot8c_i32_i4_e32 v44, v128, v48
	v_dot8c_i32_i4_e32 v45, v128, v46
	v_dot8c_i32_i4_e32 v38, v123, v49
	v_dot8c_i32_i4_e32 v39, v123, v47
	v_dot8c_i32_i4_e32 v40, v125, v49
	v_dot8c_i32_i4_e32 v41, v125, v47
	v_dot8c_i32_i4_e32 v42, v127, v49
	v_dot8c_i32_i4_e32 v43, v127, v47
	v_dot8c_i32_i4_e32 v44, v129, v49
	v_dot8c_i32_i4_e32 v45, v129, v47
	v_and_b32_e32 v78, 0xffff, v22
	v_lshrrev_b32_e32 v79, 16, v22
	v_lshl_add_u32 v78, v78, 7, v152
	v_lshl_add_u32 v79, v79, 7, v153
	s_mov_b32 m0, s76
	s_add_i32 s43, s76, 0x400
	global_load_lds_dwordx4 v78, s[50:51]
	s_mov_b32 m0, s43
	s_nop 0
	global_load_lds_dwordx4 v79, s[50:51]
	s_waitcnt vmcnt(8)
	v_add_u32_e32 v54, s78, v59
	v_add_u32_e32 v55, s78, v60
	v_add_u32_e32 v56, s78, v61
	v_add_u32_e32 v57, s78, v62
	ds_read_b64_tr_b4 v[46:47], v160
	ds_read_b64_tr_b4 v[48:49], v160 offset:1024
	ds_read_b64_tr_b4 v[122:123], v54
	ds_read_b64_tr_b4 v[124:125], v55
	ds_read_b64_tr_b4 v[126:127], v56
	ds_read_b64_tr_b4 v[128:129], v57
	s_waitcnt lgkmcnt(6)
	v_dot8c_i32_i4_e32 v38, v130, v52
	v_dot8c_i32_i4_e32 v39, v130, v50
	v_dot8c_i32_i4_e32 v40, v132, v52
	v_dot8c_i32_i4_e32 v41, v132, v50
	v_dot8c_i32_i4_e32 v42, v134, v52
	v_dot8c_i32_i4_e32 v43, v134, v50
	v_dot8c_i32_i4_e32 v44, v136, v52
	v_dot8c_i32_i4_e32 v45, v136, v50
	v_dot8c_i32_i4_e32 v38, v131, v53
	v_dot8c_i32_i4_e32 v39, v131, v51
	v_dot8c_i32_i4_e32 v40, v133, v53
	v_dot8c_i32_i4_e32 v41, v133, v51
	v_dot8c_i32_i4_e32 v42, v135, v53
	v_dot8c_i32_i4_e32 v43, v135, v51
	v_dot8c_i32_i4_e32 v44, v137, v53
	v_dot8c_i32_i4_e32 v45, v137, v51
	s_nop 3
	s_waitcnt lgkmcnt(15)
	v_lshlrev_b32_e32 v38, 5, v38
	v_lshlrev_b32_e32 v39, 1, v39
	v_add3_u32 v38, v39, v229, v38
	v_cvt_f32_i32_e32 v38, v38
	v_mul_f32_e32 v38, v228, v38
	v_lshlrev_b32_e32 v40, 5, v40
	v_lshlrev_b32_e32 v41, 1, v41
	v_add3_u32 v40, v41, v229, v40
	v_cvt_f32_i32_e32 v40, v40
	v_mul_f32_e32 v40, v228, v40
	v_lshlrev_b32_e32 v42, 5, v42
	v_lshlrev_b32_e32 v43, 1, v43
	v_add3_u32 v42, v43, v229, v42
	v_cvt_f32_i32_e32 v42, v42
	v_mul_f32_e32 v42, v228, v42
	v_lshlrev_b32_e32 v44, 5, v44
	v_lshlrev_b32_e32 v45, 1, v45
	v_add3_u32 v44, v45, v229, v44
	v_cvt_f32_i32_e32 v44, v44
	v_mul_f32_e32 v44, v228, v44
	v_cvt_pk_bf16_f32 v186, v38, v40
	v_cvt_pk_bf16_f32 v187, v42, v44
	ds_read_b128 v[252:255], v155
	s_add_i32 s44, s40, 0
	s_ashr_i32 s45, s44, 31
	s_lshl_b64 s[44:45], s[44:45], 12
	v_lshl_add_u64 v[80:81], v[36:37], 0, s[44:45]
	s_waitcnt lgkmcnt(0)
	v_mul_f32_e32 v210, v210, v252
	v_mul_f32_e32 v211, v211, v253
	v_mul_f32_e32 v212, v212, v254
	v_mul_f32_e32 v213, v213, v255
	global_store_dwordx4 v[80:81], v[210:213], off nt
	s_add_i32 s43, s40, 8
	s_lshl_b32 s43, s43, 11
	v_add_u32_e32 v138, s43, v66
	global_load_dwordx2 v[194:195], v138, s[70:71]
	global_load_dwordx2 v[196:197], v138, s[70:71] offset:512
	global_load_dwordx2 v[198:199], v138, s[70:71] offset:1024
	global_load_dwordx2 v[200:201], v138, s[70:71] offset:1536
	v_add_u32_e32 v147, 8, v140
	v_and_b32_e32 v146, 15, v147
	v_xor_b32_e32 v146, 8, v146
	v_bfe_u32 v148, v147, 4, 4
	v_mul_lo_u32 v146, v146, s92
	v_mul_lo_u32 v148, v148, s92
	v_mov_b32_e32 v147, v146
	v_mov_b32_e32 v149, v148
	ds_write2st64_b64 v77, v[146:147], v[148:149] offset1:2
	v_add_u32_e32 v138, 0xc00, v74
	ds_read_u8 v139, v138
	v_add_u32_e32 v141, 0xc00, v73
	ds_read_u8 v140, v141
	s_add_i32 s43, s67, 64
	v_mov_b32_e32 v138, s43
	ds_read2st64_b32 v[228:229], v138 offset1:1
	ds_read_b128 v[26:29], v227 offset:6144
	ds_read_b128 v[30:33], v227 offset:6160
	v_mov_b32_e32 v38, 0
	v_mov_b32_e32 v39, 0
	v_mov_b32_e32 v40, 0
	v_mov_b32_e32 v41, 0
	v_mov_b32_e32 v42, 0
	v_mov_b32_e32 v43, 0
	v_mov_b32_e32 v44, 0
	v_mov_b32_e32 v45, 0
	v_and_b32_e32 v78, 0xffff, v23
	v_lshrrev_b32_e32 v79, 16, v23
	v_lshl_add_u32 v78, v78, 7, v152
	v_lshl_add_u32 v79, v79, 7, v153
	s_mov_b32 m0, s77
	s_add_i32 s43, s77, 0x400
	global_load_lds_dwordx4 v78, s[50:51]
	s_mov_b32 m0, s43
	s_nop 0
	global_load_lds_dwordx4 v79, s[50:51]
	s_waitcnt vmcnt(13)
	v_add_u32_e32 v54, s79, v59
	v_add_u32_e32 v55, s79, v60
	v_add_u32_e32 v56, s79, v61
	v_add_u32_e32 v57, s79, v62
	ds_read_b64_tr_b4 v[50:51], v160 offset:128
	ds_read_b64_tr_b4 v[52:53], v160 offset:1152
	ds_read_b64_tr_b4 v[130:131], v54
	ds_read_b64_tr_b4 v[132:133], v55
	ds_read_b64_tr_b4 v[134:135], v56
	ds_read_b64_tr_b4 v[136:137], v57
	s_waitcnt lgkmcnt(13)
; #define TR4(p_) __builtin_amdgcn_ds_read_tr4_b64_v2i32((LAS v2i*)(p_))
; #define VDMA(st_, k_) do { _Pragma("unroll") for (int i_ = 0; i_ < 4; ++i_) { \
;         const unsigned off_ = (unsigned)((st_) >> 2) * (16384u * 128u) + (PE_ID(E, 4 * ((st_) & 3) + i_) << 7) + ((i_ & 1) ? cx1 : cx0); \
;         __builtin_amdgcn_global_load_lds((const unsigned*)(V4 + off_), (LAS unsigned*)(ldsb + BUF[k_] + 1024 * i_), 16, 0, 0); } } while (0)
; __device__ __forceinline__ void peer_v_tokens(int j, const LAS unsigned short* EL, const LAS unsigned char* AL  , const LAS float* ASC  , const LAS int* SAL  , ...
;     ...
;             if (st < 14) VDMA(st + 2, (st + 2) % 3);
;             if (st < 14) asm volatile("s_waitcnt vmcnt(8)" ::: "memory");
;             else if (st == 14) asm volatile("s_waitcnt vmcnt(4)" ::: "memory");
;             else asm volatile("s_waitcnt vmcnt(0)" ::: "memory");
;             if (q == 0) {
; #pragma unroll
;                 for (int r = 0; r < 4; ++r) { accH[r] = 0; accL[r] = 0; } }
; #pragma unroll
;             for (int tp = 0; tp < 2; ++tp) {
;                 const v2i ao = TR4(ATL + (2 * q + tp) * 128 + 8 * s16), ah = TR4(ATL + 1024 + (2 * q + tp) * 128 + 8 * s16);
; #pragma unroll
;                 for (int r = 0; r < 4; ++r) {
;                     const v2i d = TR4(ldsb + BUF[st % 3] + 2048 * tp + roff[r]);
;                     accH[r] = __builtin_amdgcn_sdot8(d.x, ah.x, accH[r], false); accH[r] = __builtin_amdgcn_sdot8(d.y, ah.y, accH[r], false);
;                     accL[r] = __builtin_amdgcn_sdot8(d.x, ao.x, accL[r], false); accL[r] = __builtin_amdgcn_sdot8(d.y, ao.y, accL[r], false);
;                 }
	v_dot8c_i32_i4_e32 v38, v122, v48
	v_dot8c_i32_i4_e32 v39, v122, v46
	v_dot8c_i32_i4_e32 v40, v124, v48
	v_dot8c_i32_i4_e32 v41, v124, v46
	v_dot8c_i32_i4_e32 v42, v126, v48
	v_dot8c_i32_i4_e32 v43, v126, v46
	v_dot8c_i32_i4_e32 v44, v128, v48
	v_dot8c_i32_i4_e32 v45, v128, v46
	v_dot8c_i32_i4_e32 v38, v123, v49
	v_dot8c_i32_i4_e32 v39, v123, v47
	v_dot8c_i32_i4_e32 v40, v125, v49
	v_dot8c_i32_i4_e32 v41, v125, v47
	v_dot8c_i32_i4_e32 v42, v127, v49
	v_dot8c_i32_i4_e32 v43, v127, v47
	v_dot8c_i32_i4_e32 v44, v129, v49
	v_dot8c_i32_i4_e32 v45, v129, v47
	v_and_b32_e32 v78, 0xffff, v24
	v_lshrrev_b32_e32 v79, 16, v24
	v_lshl_add_u32 v78, v78, 7, v152
	v_lshl_add_u32 v79, v79, 7, v153
	s_mov_b32 m0, s78
	s_add_i32 s43, s78, 0x400
	global_load_lds_dwordx4 v78, s[50:51]
	s_mov_b32 m0, s43
	s_nop 0
	global_load_lds_dwordx4 v79, s[50:51]
	s_waitcnt vmcnt(13)
	v_add_u32_e32 v54, s98, v59
	v_add_u32_e32 v55, s98, v60
	v_add_u32_e32 v56, s98, v61
	v_add_u32_e32 v57, s98, v62
	ds_read_b64_tr_b4 v[46:47], v160 offset:256
	ds_read_b64_tr_b4 v[48:49], v160 offset:1280
	ds_read_b64_tr_b4 v[122:123], v54
	ds_read_b64_tr_b4 v[124:125], v55
	ds_read_b64_tr_b4 v[126:127], v56
	ds_read_b64_tr_b4 v[128:129], v57
	s_waitcnt lgkmcnt(6)
	v_dot8c_i32_i4_e32 v38, v130, v52
	v_dot8c_i32_i4_e32 v39, v130, v50
	v_dot8c_i32_i4_e32 v40, v132, v52
	v_dot8c_i32_i4_e32 v41, v132, v50
	v_dot8c_i32_i4_e32 v42, v134, v52
	v_dot8c_i32_i4_e32 v43, v134, v50
	v_dot8c_i32_i4_e32 v44, v136, v52
	v_dot8c_i32_i4_e32 v45, v136, v50
	v_dot8c_i32_i4_e32 v38, v131, v53
	v_dot8c_i32_i4_e32 v39, v131, v51
	v_dot8c_i32_i4_e32 v40, v133, v53
	v_dot8c_i32_i4_e32 v41, v133, v51
	v_dot8c_i32_i4_e32 v42, v135, v53
	v_dot8c_i32_i4_e32 v43, v135, v51
	v_dot8c_i32_i4_e32 v44, v137, v53
	v_dot8c_i32_i4_e32 v45, v137, v51
	v_and_b32_e32 v78, 0xffff, v25
	v_lshrrev_b32_e32 v79, 16, v25
	v_lshl_add_u32 v78, v78, 7, v152
	v_lshl_add_u32 v79, v79, 7, v153
	s_mov_b32 m0, s79
	s_add_i32 s43, s79, 0x400
	global_load_lds_dwordx4 v78, s[50:51]
	s_mov_b32 m0, s43
	s_nop 0
	global_load_lds_dwordx4 v79, s[50:51]
	s_waitcnt vmcnt(13)
	v_add_u32_e32 v54, s99, v59
	v_add_u32_e32 v55, s99, v60
	v_add_u32_e32 v56, s99, v61
	v_add_u32_e32 v57, s99, v62
	ds_read_b64_tr_b4 v[50:51], v160 offset:384
	ds_read_b64_tr_b4 v[52:53], v160 offset:1408
	ds_read_b64_tr_b4 v[130:131], v54
	ds_read_b64_tr_b4 v[132:133], v55
	ds_read_b64_tr_b4 v[134:135], v56
	ds_read_b64_tr_b4 v[136:137], v57
	s_waitcnt lgkmcnt(6)
	v_dot8c_i32_i4_e32 v38, v122, v48
	v_dot8c_i32_i4_e32 v39, v122, v46
	v_dot8c_i32_i4_e32 v40, v124, v48
	v_dot8c_i32_i4_e32 v41, v124, v46
	v_dot8c_i32_i4_e32 v42, v126, v48
	v_dot8c_i32_i4_e32 v43, v126, v46
	v_dot8c_i32_i4_e32 v44, v128, v48
	v_dot8c_i32_i4_e32 v45, v128, v46
	v_dot8c_i32_i4_e32 v38, v123, v49
	v_dot8c_i32_i4_e32 v39, v123, v47
	v_dot8c_i32_i4_e32 v40, v125, v49
	v_dot8c_i32_i4_e32 v41, v125, v47
	v_dot8c_i32_i4_e32 v42, v127, v49
	v_dot8c_i32_i4_e32 v43, v127, v47
	v_dot8c_i32_i4_e32 v44, v129, v49
	v_dot8c_i32_i4_e32 v45, v129, v47
	s_waitcnt lgkmcnt(15)
	v_and_b32_e32 v78, 0xffff, v26
	v_lshrrev_b32_e32 v79, 16, v26
	v_lshl_add_u32 v78, v78, 7, v152
	v_lshl_add_u32 v79, v79, 7, v153
	s_mov_b32 m0, s98
	s_add_i32 s43, s98, 0x400
	global_load_lds_dwordx4 v78, s[50:51]
	s_mov_b32 m0, s43
	s_nop 0
	global_load_lds_dwordx4 v79, s[50:51]
	s_waitcnt vmcnt(13)
	v_add_u32_e32 v54, s76, v59
	v_add_u32_e32 v55, s76, v60
	v_add_u32_e32 v56, s76, v61
	v_add_u32_e32 v57, s76, v62
	ds_read_b64_tr_b4 v[46:47], v160 offset:512
	ds_read_b64_tr_b4 v[48:49], v160 offset:1536
	ds_read_b64_tr_b4 v[122:123], v54
	ds_read_b64_tr_b4 v[124:125], v55
	ds_read_b64_tr_b4 v[126:127], v56
	ds_read_b64_tr_b4 v[128:129], v57
	s_waitcnt lgkmcnt(6)
	v_dot8c_i32_i4_e32 v38, v130, v52
	v_dot8c_i32_i4_e32 v39, v130, v50
	v_dot8c_i32_i4_e32 v40, v132, v52
	v_dot8c_i32_i4_e32 v41, v132, v50
	v_dot8c_i32_i4_e32 v42, v134, v52
	v_dot8c_i32_i4_e32 v43, v134, v50
	v_dot8c_i32_i4_e32 v44, v136, v52
	v_dot8c_i32_i4_e32 v45, v136, v50
	v_dot8c_i32_i4_e32 v38, v131, v53
	v_dot8c_i32_i4_e32 v39, v131, v51
	v_dot8c_i32_i4_e32 v40, v133, v53
	v_dot8c_i32_i4_e32 v41, v133, v51
	v_dot8c_i32_i4_e32 v42, v135, v53
	v_dot8c_i32_i4_e32 v43, v135, v51
	v_dot8c_i32_i4_e32 v44, v137, v53
	v_dot8c_i32_i4_e32 v45, v137, v51
	v_and_b32_e32 v78, 0xffff, v27
	v_lshrrev_b32_e32 v79, 16, v27
	v_lshl_add_u32 v78, v78, 7, v152
	v_lshl_add_u32 v79, v79, 7, v153
	s_mov_b32 m0, s99
	s_add_i32 s43, s99, 0x400
	global_load_lds_dwordx4 v78, s[50:51]
	s_mov_b32 m0, s43
	s_nop 0
	global_load_lds_dwordx4 v79, s[50:51]
	s_waitcnt vmcnt(8)
	v_add_u32_e32 v54, s77, v59
	v_add_u32_e32 v55, s77, v60
	v_add_u32_e32 v56, s77, v61
	v_add_u32_e32 v57, s77, v62
	ds_read_b64_tr_b4 v[50:51], v160 offset:640
	ds_read_b64_tr_b4 v[52:53], v160 offset:1664
	ds_read_b64_tr_b4 v[130:131], v54
	ds_read_b64_tr_b4 v[132:133], v55
	ds_read_b64_tr_b4 v[134:135], v56
	ds_read_b64_tr_b4 v[136:137], v57
	s_waitcnt lgkmcnt(6)
	v_dot8c_i32_i4_e32 v38, v122, v48
	v_dot8c_i32_i4_e32 v39, v122, v46
	v_dot8c_i32_i4_e32 v40, v124, v48
	v_dot8c_i32_i4_e32 v41, v124, v46
	v_dot8c_i32_i4_e32 v42, v126, v48
	v_dot8c_i32_i4_e32 v43, v126, v46
	v_dot8c_i32_i4_e32 v44, v128, v48
	v_dot8c_i32_i4_e32 v45, v128, v46
	v_dot8c_i32_i4_e32 v38, v123, v49
	v_dot8c_i32_i4_e32 v39, v123, v47
	v_dot8c_i32_i4_e32 v40, v125, v49
	v_dot8c_i32_i4_e32 v41, v125, v47
	v_dot8c_i32_i4_e32 v42, v127, v49
	v_dot8c_i32_i4_e32 v43, v127, v47
	v_dot8c_i32_i4_e32 v44, v129, v49
	v_dot8c_i32_i4_e32 v45, v129, v47
	s_waitcnt lgkmcnt(15)
; #define LAS __attribute__((address_space(3)))
; __device__ __forceinline__ void peer_v_tokens(int j, const LAS unsigned short* EL, const LAS unsigned char* AL  , const LAS float* ASC  , const LAS int* SAL  , ...
;     ...
;         { const LAS v4u* ep = (const LAS v4u*)(EL + tl * 128 + 16 * g); const v4u e0 = ep[0], e1 = ep[1];
;           E[0] = e0.x; E[1] = e0.y; E[2] = e0.z; E[3] = e0.w; E[4] = e1.x; E[5] = e1.y; E[6] = e1.z; E[7] = e1.w; }
;         uint2 hv[4]; float4 gv[4];
;         { unsigned ho = (unsigned)t * (D / 4) + (unsigned)lane; asm volatile("" : "+v"(ho)); const uint2* hp = (const uint2*)HB + ho; const float4* gp = (const float4*)fng + lane;
; #pragma unroll
;           for (int jq = 0; jq < 4; ++jq) { hv[jq] = hp[64 * jq]; gv[jq] = gp[64 * jq]; } }
;         VDMA(0, 0); VDMA(1, 1);
; #pragma unroll
;         for (int m = 0; m < 2; ++m) {
;             const int idx = lane + 64 * m, tau = idx >> 4, sr = idx & 15, k = 16 * (sr & 7) + 2 * tau + (sr >> 3);
;     ...
;         for (int st = 0; st < 16; ++st) {
;             const int p = st >> 2, q = st & 3;
;             if (st < 14) VDMA(st + 2, (st + 2) % 3);
;             if (st < 14) asm volatile("s_waitcnt vmcnt(8)" ::: "memory");
;             else if (st == 14) asm volatile("s_waitcnt vmcnt(4)" ::: "memory");
;             else asm volatile("s_waitcnt vmcnt(0)" ::: "memory");
;             if (q == 0) {
; #pragma unroll
;                 for (int r = 0; r < 4; ++r) { accH[r] = 0; accL[r] = 0; } }
; #pragma unroll
;             for (int tp = 0; tp < 2; ++tp) {
;                 const v2i ao = TR4(ATL + (2 * q + tp) * 128 + 8 * s16), ah = TR4(ATL + 1024 + (2 * q + tp) * 128 + 8 * s16);
; #pragma unroll
;                 for (int r = 0; r < 4; ++r) {
;                     const v2i d = TR4(ldsb + BUF[st % 3] + 2048 * tp + roff[r]);
;                     accH[r] = __builtin_amdgcn_sdot8(d.x, ah.x, accH[r], false); accH[r] = __builtin_amdgcn_sdot8(d.y, ah.y, accH[r], false);
;                     accL[r] = __builtin_amdgcn_sdot8(d.x, ao.x, accL[r], false); accL[r] = __builtin_amdgcn_sdot8(d.y, ao.y, accL[r], false);
;                 }
;             }
;             asm volatile("s_waitcnt lgkmcnt(0)" ::: "memory");
;             if (q == 3) {
; #pragma unroll
;                 for (int r = 0; r < 4; ++r) STASH[256 * p + 16 * (grp + 4 * r) + pc] = f2bf(asc * (float)(2 * ((accH[r] << 4) + accL[r]) + sa));
	v_add_u32_e32 v143, 8, v139
	v_and_b32_e32 v142, 15, v143
	v_xor_b32_e32 v142, 8, v142
	v_bfe_u32 v144, v143, 4, 4
	v_mul_lo_u32 v142, v142, s92
	v_mul_lo_u32 v144, v144, s92
	v_mov_b32_e32 v143, v142
	v_mov_b32_e32 v145, v144
	ds_write2st64_b64 v159, v[142:143], v[144:145] offset1:2
	v_and_b32_e32 v78, 0xffff, v28
	v_lshrrev_b32_e32 v79, 16, v28
	v_lshl_add_u32 v78, v78, 7, v152
	v_lshl_add_u32 v79, v79, 7, v153
	s_mov_b32 m0, s76
	s_add_i32 s43, s76, 0x400
	global_load_lds_dwordx4 v78, s[50:51]
	s_mov_b32 m0, s43
	s_nop 0
	global_load_lds_dwordx4 v79, s[50:51]
	s_waitcnt vmcnt(8)
	v_add_u32_e32 v54, s78, v59
	v_add_u32_e32 v55, s78, v60
	v_add_u32_e32 v56, s78, v61
	v_add_u32_e32 v57, s78, v62
	ds_read_b64_tr_b4 v[46:47], v160 offset:768
	ds_read_b64_tr_b4 v[48:49], v160 offset:1792
	ds_read_b64_tr_b4 v[122:123], v54
	ds_read_b64_tr_b4 v[124:125], v55
	ds_read_b64_tr_b4 v[126:127], v56
	ds_read_b64_tr_b4 v[128:129], v57
	s_waitcnt lgkmcnt(7)
	v_dot8c_i32_i4_e32 v38, v130, v52
	v_dot8c_i32_i4_e32 v39, v130, v50
	v_dot8c_i32_i4_e32 v40, v132, v52
	v_dot8c_i32_i4_e32 v41, v132, v50
	v_dot8c_i32_i4_e32 v42, v134, v52
	v_dot8c_i32_i4_e32 v43, v134, v50
	v_dot8c_i32_i4_e32 v44, v136, v52
	v_dot8c_i32_i4_e32 v45, v136, v50
	v_dot8c_i32_i4_e32 v38, v131, v53
	v_dot8c_i32_i4_e32 v39, v131, v51
	v_dot8c_i32_i4_e32 v40, v133, v53
	v_dot8c_i32_i4_e32 v41, v133, v51
	v_dot8c_i32_i4_e32 v42, v135, v53
	v_dot8c_i32_i4_e32 v43, v135, v51
	v_dot8c_i32_i4_e32 v44, v137, v53
	v_dot8c_i32_i4_e32 v45, v137, v51
	v_and_b32_e32 v78, 0xffff, v29
	v_lshrrev_b32_e32 v79, 16, v29
	v_lshl_add_u32 v78, v78, 7, v152
	v_lshl_add_u32 v79, v79, 7, v153
	s_mov_b32 m0, s77
	s_add_i32 s43, s77, 0x400
	global_load_lds_dwordx4 v78, s[50:51]
	s_mov_b32 m0, s43
	s_nop 0
	global_load_lds_dwordx4 v79, s[50:51]
	s_waitcnt vmcnt(8)
	v_add_u32_e32 v54, s79, v59
	v_add_u32_e32 v55, s79, v60
	v_add_u32_e32 v56, s79, v61
	v_add_u32_e32 v57, s79, v62
	ds_read_b64_tr_b4 v[50:51], v160 offset:896
	ds_read_b64_tr_b4 v[52:53], v160 offset:1920
	ds_read_b64_tr_b4 v[130:131], v54
	ds_read_b64_tr_b4 v[132:133], v55
	ds_read_b64_tr_b4 v[134:135], v56
	ds_read_b64_tr_b4 v[136:137], v57
	s_waitcnt lgkmcnt(6)
	v_dot8c_i32_i4_e32 v38, v122, v48
	v_dot8c_i32_i4_e32 v39, v122, v46
	v_dot8c_i32_i4_e32 v40, v124, v48
	v_dot8c_i32_i4_e32 v41, v124, v46
	v_dot8c_i32_i4_e32 v42, v126, v48
	v_dot8c_i32_i4_e32 v43, v126, v46
	v_dot8c_i32_i4_e32 v44, v128, v48
	v_dot8c_i32_i4_e32 v45, v128, v46
	v_dot8c_i32_i4_e32 v38, v123, v49
	v_dot8c_i32_i4_e32 v39, v123, v47
	v_dot8c_i32_i4_e32 v40, v125, v49
	v_dot8c_i32_i4_e32 v41, v125, v47
	v_dot8c_i32_i4_e32 v42, v127, v49
	v_dot8c_i32_i4_e32 v43, v127, v47
	v_dot8c_i32_i4_e32 v44, v129, v49
	v_dot8c_i32_i4_e32 v45, v129, v47
	v_and_b32_e32 v78, 0xffff, v30
	v_lshrrev_b32_e32 v79, 16, v30
	v_lshl_add_u32 v78, v78, 7, v152
	v_lshl_add_u32 v79, v79, 7, v153
	s_mov_b32 m0, s78
	s_add_i32 s43, s78, 0x400
	global_load_lds_dwordx4 v78, s[50:51]
	s_mov_b32 m0, s43
	s_nop 0
	global_load_lds_dwordx4 v79, s[50:51]
	s_waitcnt vmcnt(8)
	v_add_u32_e32 v54, s98, v59
	v_add_u32_e32 v55, s98, v60
	v_add_u32_e32 v56, s98, v61
	v_add_u32_e32 v57, s98, v62
	ds_read_b64_tr_b4 v[46:47], v160
	ds_read_b64_tr_b4 v[48:49], v160 offset:1024
	ds_read_b64_tr_b4 v[122:123], v54
	ds_read_b64_tr_b4 v[124:125], v55
	ds_read_b64_tr_b4 v[126:127], v56
	ds_read_b64_tr_b4 v[128:129], v57
	s_waitcnt lgkmcnt(6)
	v_dot8c_i32_i4_e32 v38, v130, v52
	v_dot8c_i32_i4_e32 v39, v130, v50
	v_dot8c_i32_i4_e32 v40, v132, v52
	v_dot8c_i32_i4_e32 v41, v132, v50
	v_dot8c_i32_i4_e32 v42, v134, v52
	v_dot8c_i32_i4_e32 v43, v134, v50
	v_dot8c_i32_i4_e32 v44, v136, v52
	v_dot8c_i32_i4_e32 v45, v136, v50
	v_dot8c_i32_i4_e32 v38, v131, v53
	v_dot8c_i32_i4_e32 v39, v131, v51
	v_dot8c_i32_i4_e32 v40, v133, v53
	v_dot8c_i32_i4_e32 v41, v133, v51
	v_dot8c_i32_i4_e32 v42, v135, v53
	v_dot8c_i32_i4_e32 v43, v135, v51
	v_dot8c_i32_i4_e32 v44, v137, v53
	v_dot8c_i32_i4_e32 v45, v137, v51
	s_nop 3
	s_waitcnt lgkmcnt(15)
	v_lshlrev_b32_e32 v38, 5, v38
	v_lshlrev_b32_e32 v39, 1, v39
	v_add3_u32 v38, v39, v229, v38
	v_cvt_f32_i32_e32 v38, v38
	v_mul_f32_e32 v38, v228, v38
	v_lshlrev_b32_e32 v40, 5, v40
	v_lshlrev_b32_e32 v41, 1, v41
	v_add3_u32 v40, v41, v229, v40
	v_cvt_f32_i32_e32 v40, v40
	v_mul_f32_e32 v40, v228, v40
	v_lshlrev_b32_e32 v42, 5, v42
	v_lshlrev_b32_e32 v43, 1, v43
	v_add3_u32 v42, v43, v229, v42
	v_cvt_f32_i32_e32 v42, v42
	v_mul_f32_e32 v42, v228, v42
	v_lshlrev_b32_e32 v44, 5, v44
	v_lshlrev_b32_e32 v45, 1, v45
	v_add3_u32 v44, v45, v229, v44
	v_cvt_f32_i32_e32 v44, v44
	v_mul_f32_e32 v44, v228, v44
	v_cvt_pk_bf16_f32 v180, v38, v40
	v_cvt_pk_bf16_f32 v181, v42, v44
	ds_read_b128 v[252:255], v155 offset:1024
	s_add_i32 s44, s40, 0
	s_ashr_i32 s45, s44, 31
	s_lshl_b64 s[44:45], s[44:45], 12
	v_lshl_add_u64 v[80:81], v[36:37], 0, s[44:45]
	s_waitcnt lgkmcnt(0)
	v_mul_f32_e32 v214, v214, v252
	v_mul_f32_e32 v215, v215, v253
	v_mul_f32_e32 v216, v216, v254
	v_mul_f32_e32 v217, v217, v255
	global_store_dwordx4 v[80:81], v[214:217], off offset:1024 nt
	v_add_u32_e32 v147, 8, v140
	v_and_b32_e32 v146, 15, v147
	v_xor_b32_e32 v146, 8, v146
	v_bfe_u32 v148, v147, 4, 4
	v_mul_lo_u32 v146, v146, s92
	v_mul_lo_u32 v148, v148, s92
	v_mov_b32_e32 v147, v146
	v_mov_b32_e32 v149, v148
	ds_write2st64_b64 v77, v[146:147], v[148:149] offset1:2
	v_add_u32_e32 v138, 0x800, v74
	ds_read_u8 v139, v138
	v_add_u32_e32 v141, 0x800, v73
	ds_read_u8 v140, v141
	s_add_i32 s43, s67, 96
	v_mov_b32_e32 v138, s43
	ds_read2st64_b32 v[228:229], v138 offset1:1
	ds_read_b128 v[18:21], v227 offset:4096
	ds_read_b128 v[22:25], v227 offset:4112
	v_add_u32_e32 v150, 0x400000, v63
	v_add_u32_e32 v151, 0x400000, v64
	v_mov_b32_e32 v38, 0
	v_mov_b32_e32 v39, 0
	v_mov_b32_e32 v40, 0
	v_mov_b32_e32 v41, 0
	v_mov_b32_e32 v42, 0
	v_mov_b32_e32 v43, 0
	v_mov_b32_e32 v44, 0
	v_mov_b32_e32 v45, 0
	v_and_b32_e32 v78, 0xffff, v31
	v_lshrrev_b32_e32 v79, 16, v31
	v_lshl_add_u32 v78, v78, 7, v152
	v_lshl_add_u32 v79, v79, 7, v153
	s_mov_b32 m0, s79
	s_add_i32 s43, s79, 0x400
	global_load_lds_dwordx4 v78, s[50:51]
	s_mov_b32 m0, s43
	s_nop 0
	global_load_lds_dwordx4 v79, s[50:51]
	s_waitcnt vmcnt(9)
; #define LAS __attribute__((address_space(3)))
; __device__ __forceinline__ bf16 f2bf(float f) { return (bf16)f2bfu(f); }
; #define TR4(p_) __builtin_amdgcn_ds_read_tr4_b64_v2i32((LAS v2i*)(p_))
; #define CFENCE() asm volatile("" ::: "memory")
; __device__ __forceinline__ void peer_v_tokens(int j, const LAS unsigned short* EL, const LAS unsigned char* AL  , const LAS float* ASC  , const LAS int* SAL  , ...
;     ...
;         for (int st = 0; st < 16; ++st) {
;             const int p = st >> 2, q = st & 3;
;             if (st < 14) VDMA(st + 2, (st + 2) % 3);
;             if (st < 14) asm volatile("s_waitcnt vmcnt(8)" ::: "memory");
;             else if (st == 14) asm volatile("s_waitcnt vmcnt(4)" ::: "memory");
;             else asm volatile("s_waitcnt vmcnt(0)" ::: "memory");
;             if (q == 0) {
; #pragma unroll
;                 for (int r = 0; r < 4; ++r) { accH[r] = 0; accL[r] = 0; } }
; #pragma unroll
;             for (int tp = 0; tp < 2; ++tp) {
;                 const v2i ao = TR4(ATL + (2 * q + tp) * 128 + 8 * s16), ah = TR4(ATL + 1024 + (2 * q + tp) * 128 + 8 * s16);
; #pragma unroll
;                 for (int r = 0; r < 4; ++r) {
;                     const v2i d = TR4(ldsb + BUF[st % 3] + 2048 * tp + roff[r]);
;                     accH[r] = __builtin_amdgcn_sdot8(d.x, ah.x, accH[r], false); accH[r] = __builtin_amdgcn_sdot8(d.y, ah.y, accH[r], false);
;                     accL[r] = __builtin_amdgcn_sdot8(d.x, ao.x, accL[r], false); accL[r] = __builtin_amdgcn_sdot8(d.y, ao.y, accL[r], false);
;                 }
;             }
;             asm volatile("s_waitcnt lgkmcnt(0)" ::: "memory");
;             if (q == 3) {
; #pragma unroll
;                 for (int r = 0; r < 4; ++r) STASH[256 * p + 16 * (grp + 4 * r) + pc] = f2bf(asc * (float)(2 * ((accH[r] << 4) + accL[r]) + sa));
;             }
;         }
;         CFENCE();
;         {
;             float4 v[4]; float ss = 0.f;
; #pragma unroll
;             for (int jq = 0; jq < 4; ++jq) { typedef unsigned u2v __attribute__((ext_vector_type(2))); const u2v pw = *(const LAS u2v*)(STASH + 4 * lane + 256 * jq); const uint2 hw = hv[jq];
	v_add_u32_e32 v54, s99, v59
	v_add_u32_e32 v55, s99, v60
	v_add_u32_e32 v56, s99, v61
	v_add_u32_e32 v57, s99, v62
	ds_read_b64_tr_b4 v[50:51], v160 offset:128
	ds_read_b64_tr_b4 v[52:53], v160 offset:1152
	ds_read_b64_tr_b4 v[130:131], v54
	ds_read_b64_tr_b4 v[132:133], v55
	ds_read_b64_tr_b4 v[134:135], v56
	ds_read_b64_tr_b4 v[136:137], v57
	s_waitcnt lgkmcnt(13)
	v_dot8c_i32_i4_e32 v38, v122, v48
	v_dot8c_i32_i4_e32 v39, v122, v46
	v_dot8c_i32_i4_e32 v40, v124, v48
	v_dot8c_i32_i4_e32 v41, v124, v46
	v_dot8c_i32_i4_e32 v42, v126, v48
	v_dot8c_i32_i4_e32 v43, v126, v46
	v_dot8c_i32_i4_e32 v44, v128, v48
	v_dot8c_i32_i4_e32 v45, v128, v46
	v_dot8c_i32_i4_e32 v38, v123, v49
	v_dot8c_i32_i4_e32 v39, v123, v47
	v_dot8c_i32_i4_e32 v40, v125, v49
	v_dot8c_i32_i4_e32 v41, v125, v47
	v_dot8c_i32_i4_e32 v42, v127, v49
	v_dot8c_i32_i4_e32 v43, v127, v47
	v_dot8c_i32_i4_e32 v44, v129, v49
	v_dot8c_i32_i4_e32 v45, v129, v47
	v_and_b32_e32 v78, 0xffff, v32
	v_lshrrev_b32_e32 v79, 16, v32
	v_lshl_add_u32 v78, v78, 7, v152
	v_lshl_add_u32 v79, v79, 7, v153
	s_mov_b32 m0, s98
	s_add_i32 s43, s98, 0x400
	global_load_lds_dwordx4 v78, s[50:51]
	s_mov_b32 m0, s43
	s_nop 0
	global_load_lds_dwordx4 v79, s[50:51]
	s_waitcnt vmcnt(9)
	v_add_u32_e32 v54, s76, v59
	v_add_u32_e32 v55, s76, v60
	v_add_u32_e32 v56, s76, v61
	v_add_u32_e32 v57, s76, v62
	ds_read_b64_tr_b4 v[46:47], v160 offset:256
	ds_read_b64_tr_b4 v[48:49], v160 offset:1280
	ds_read_b64_tr_b4 v[122:123], v54
	ds_read_b64_tr_b4 v[124:125], v55
	ds_read_b64_tr_b4 v[126:127], v56
	ds_read_b64_tr_b4 v[128:129], v57
	s_waitcnt lgkmcnt(6)
	v_dot8c_i32_i4_e32 v38, v130, v52
	v_dot8c_i32_i4_e32 v39, v130, v50
	v_dot8c_i32_i4_e32 v40, v132, v52
	v_dot8c_i32_i4_e32 v41, v132, v50
	v_dot8c_i32_i4_e32 v42, v134, v52
	v_dot8c_i32_i4_e32 v43, v134, v50
	v_dot8c_i32_i4_e32 v44, v136, v52
	v_dot8c_i32_i4_e32 v45, v136, v50
	v_dot8c_i32_i4_e32 v38, v131, v53
	v_dot8c_i32_i4_e32 v39, v131, v51
	v_dot8c_i32_i4_e32 v40, v133, v53
	v_dot8c_i32_i4_e32 v41, v133, v51
	v_dot8c_i32_i4_e32 v42, v135, v53
	v_dot8c_i32_i4_e32 v43, v135, v51
	v_dot8c_i32_i4_e32 v44, v137, v53
	v_dot8c_i32_i4_e32 v45, v137, v51
	ds_write_b16 v65, v170
	ds_write_b16_d16_hi v65, v170 offset:128
	ds_write_b16 v65, v171 offset:256
	ds_write_b16_d16_hi v65, v171 offset:384
	ds_write_b16 v65, v172 offset:512
	ds_write_b16_d16_hi v65, v172 offset:640
	ds_write_b16 v65, v173 offset:768
	ds_write_b16_d16_hi v65, v173 offset:896
	ds_write_b16 v65, v174 offset:1024
	ds_write_b16_d16_hi v65, v174 offset:1152
	ds_write_b16 v65, v175 offset:1280
	ds_write_b16_d16_hi v65, v175 offset:1408
	ds_write_b16 v65, v176 offset:1536
	ds_write_b16_d16_hi v65, v176 offset:1664
	ds_write_b16 v65, v177 offset:1792
	ds_write_b16_d16_hi v65, v177 offset:1920
	ds_read_b64 v[202:203], v154
	ds_read_b64 v[204:205], v154 offset:512
	ds_read_b64 v[206:207], v154 offset:1024
	ds_read_b64 v[208:209], v154 offset:1536
	v_and_b32_e32 v78, 0xffff, v33
	v_lshrrev_b32_e32 v79, 16, v33
	v_lshl_add_u32 v78, v78, 7, v152
	v_lshl_add_u32 v79, v79, 7, v153
	s_mov_b32 m0, s99
	s_add_i32 s43, s99, 0x400
	global_load_lds_dwordx4 v78, s[50:51]
	s_mov_b32 m0, s43
	s_nop 0
	global_load_lds_dwordx4 v79, s[50:51]
	s_waitcnt vmcnt(9)
	v_add_u32_e32 v54, s77, v59
	v_add_u32_e32 v55, s77, v60
	v_add_u32_e32 v56, s77, v61
	v_add_u32_e32 v57, s77, v62
	ds_read_b64_tr_b4 v[50:51], v160 offset:384
	ds_read_b64_tr_b4 v[52:53], v160 offset:1408
	ds_read_b64_tr_b4 v[130:131], v54
	ds_read_b64_tr_b4 v[132:133], v55
	ds_read_b64_tr_b4 v[134:135], v56
	ds_read_b64_tr_b4 v[136:137], v57
	s_waitcnt lgkmcnt(15)
	v_dot8c_i32_i4_e32 v38, v122, v48
	v_dot8c_i32_i4_e32 v39, v122, v46
	v_dot8c_i32_i4_e32 v40, v124, v48
	v_dot8c_i32_i4_e32 v41, v124, v46
	v_dot8c_i32_i4_e32 v42, v126, v48
	v_dot8c_i32_i4_e32 v43, v126, v46
	v_dot8c_i32_i4_e32 v44, v128, v48
	v_dot8c_i32_i4_e32 v45, v128, v46
	v_dot8c_i32_i4_e32 v38, v123, v49
	v_dot8c_i32_i4_e32 v39, v123, v47
	v_dot8c_i32_i4_e32 v40, v125, v49
	v_dot8c_i32_i4_e32 v41, v125, v47
	v_dot8c_i32_i4_e32 v42, v127, v49
	v_dot8c_i32_i4_e32 v43, v127, v47
	v_dot8c_i32_i4_e32 v44, v129, v49
	v_dot8c_i32_i4_e32 v45, v129, v47
	s_waitcnt lgkmcnt(15)
	v_and_b32_e32 v78, 0xffff, v18
	v_lshrrev_b32_e32 v79, 16, v18
	v_lshl_add_u32 v78, v78, 7, v150
	v_lshl_add_u32 v79, v79, 7, v151
	s_mov_b32 m0, s76
	s_add_i32 s43, s76, 0x400
	global_load_lds_dwordx4 v78, s[50:51]
	s_mov_b32 m0, s43
	s_nop 0
	global_load_lds_dwordx4 v79, s[50:51]
	s_waitcnt vmcnt(9)
	v_add_u32_e32 v54, s78, v59
	v_add_u32_e32 v55, s78, v60
	v_add_u32_e32 v56, s78, v61
	v_add_u32_e32 v57, s78, v62
	ds_read_b64_tr_b4 v[46:47], v160 offset:512
	ds_read_b64_tr_b4 v[48:49], v160 offset:1536
	ds_read_b64_tr_b4 v[122:123], v54
	ds_read_b64_tr_b4 v[124:125], v55
	ds_read_b64_tr_b4 v[126:127], v56
	ds_read_b64_tr_b4 v[128:129], v57
	s_waitcnt lgkmcnt(6)
	v_dot8c_i32_i4_e32 v38, v130, v52
	v_dot8c_i32_i4_e32 v39, v130, v50
	v_dot8c_i32_i4_e32 v40, v132, v52
	v_dot8c_i32_i4_e32 v41, v132, v50
	v_dot8c_i32_i4_e32 v42, v134, v52
	v_dot8c_i32_i4_e32 v43, v134, v50
	v_dot8c_i32_i4_e32 v44, v136, v52
	v_dot8c_i32_i4_e32 v45, v136, v50
	v_dot8c_i32_i4_e32 v38, v131, v53
	v_dot8c_i32_i4_e32 v39, v131, v51
	v_dot8c_i32_i4_e32 v40, v133, v53
	v_dot8c_i32_i4_e32 v41, v133, v51
	v_dot8c_i32_i4_e32 v42, v135, v53
	v_dot8c_i32_i4_e32 v43, v135, v51
	v_dot8c_i32_i4_e32 v44, v137, v53
	v_dot8c_i32_i4_e32 v45, v137, v51
	v_and_b32_e32 v78, 0xffff, v19
	v_lshrrev_b32_e32 v79, 16, v19
	v_lshl_add_u32 v78, v78, 7, v150
	v_lshl_add_u32 v79, v79, 7, v151
	s_mov_b32 m0, s77
	s_add_i32 s43, s77, 0x400
	global_load_lds_dwordx4 v78, s[50:51]
	s_mov_b32 m0, s43
	s_nop 0
	global_load_lds_dwordx4 v79, s[50:51]
	s_waitcnt vmcnt(8)
; __device__ __forceinline__ bf16 f2bf(float f) { return (bf16)f2bfu(f); }
; #define TR4(p_) __builtin_amdgcn_ds_read_tr4_b64_v2i32((LAS v2i*)(p_))
; #define VDMA(st_, k_) do { _Pragma("unroll") for (int i_ = 0; i_ < 4; ++i_) { \
;         const unsigned off_ = (unsigned)((st_) >> 2) * (16384u * 128u) + (PE_ID(E, 4 * ((st_) & 3) + i_) << 7) + ((i_ & 1) ? cx1 : cx0); \
;         __builtin_amdgcn_global_load_lds((const unsigned*)(V4 + off_), (LAS unsigned*)(ldsb + BUF[k_] + 1024 * i_), 16, 0, 0); } } while (0)
; __device__ __forceinline__ void peer_v_tokens(int j, const LAS unsigned short* EL, const LAS unsigned char* AL  , const LAS float* ASC  , const LAS int* SAL  , ...
;     ...
;         for (int st = 0; st < 16; ++st) {
;             const int p = st >> 2, q = st & 3;
;             if (st < 14) VDMA(st + 2, (st + 2) % 3);
;             if (st < 14) asm volatile("s_waitcnt vmcnt(8)" ::: "memory");
;             else if (st == 14) asm volatile("s_waitcnt vmcnt(4)" ::: "memory");
;             else asm volatile("s_waitcnt vmcnt(0)" ::: "memory");
;             if (q == 0) {
; #pragma unroll
;                 for (int r = 0; r < 4; ++r) { accH[r] = 0; accL[r] = 0; } }
; #pragma unroll
;             for (int tp = 0; tp < 2; ++tp) {
;                 const v2i ao = TR4(ATL + (2 * q + tp) * 128 + 8 * s16), ah = TR4(ATL + 1024 + (2 * q + tp) * 128 + 8 * s16);
; #pragma unroll
;                 for (int r = 0; r < 4; ++r) {
;                     const v2i d = TR4(ldsb + BUF[st % 3] + 2048 * tp + roff[r]);
;                     accH[r] = __builtin_amdgcn_sdot8(d.x, ah.x, accH[r], false); accH[r] = __builtin_amdgcn_sdot8(d.y, ah.y, accH[r], false);
;                     accL[r] = __builtin_amdgcn_sdot8(d.x, ao.x, accL[r], false); accL[r] = __builtin_amdgcn_sdot8(d.y, ao.y, accL[r], false);
;                 }
;             }
;             asm volatile("s_waitcnt lgkmcnt(0)" ::: "memory");
;             if (q == 3) {
; #pragma unroll
;                 for (int r = 0; r < 4; ++r) STASH[256 * p + 16 * (grp + 4 * r) + pc] = f2bf(asc * (float)(2 * ((accH[r] << 4) + accL[r]) + sa));
	v_add_u32_e32 v54, s79, v59
	v_add_u32_e32 v55, s79, v60
	v_add_u32_e32 v56, s79, v61
	v_add_u32_e32 v57, s79, v62
	ds_read_b64_tr_b4 v[50:51], v160 offset:640
	ds_read_b64_tr_b4 v[52:53], v160 offset:1664
	ds_read_b64_tr_b4 v[130:131], v54
	ds_read_b64_tr_b4 v[132:133], v55
	ds_read_b64_tr_b4 v[134:135], v56
	ds_read_b64_tr_b4 v[136:137], v57
	s_waitcnt lgkmcnt(6)
	v_dot8c_i32_i4_e32 v38, v122, v48
	v_dot8c_i32_i4_e32 v39, v122, v46
	v_dot8c_i32_i4_e32 v40, v124, v48
	v_dot8c_i32_i4_e32 v41, v124, v46
	v_dot8c_i32_i4_e32 v42, v126, v48
	v_dot8c_i32_i4_e32 v43, v126, v46
	v_dot8c_i32_i4_e32 v44, v128, v48
	v_dot8c_i32_i4_e32 v45, v128, v46
	v_dot8c_i32_i4_e32 v38, v123, v49
	v_dot8c_i32_i4_e32 v39, v123, v47
	v_dot8c_i32_i4_e32 v40, v125, v49
	v_dot8c_i32_i4_e32 v41, v125, v47
	v_dot8c_i32_i4_e32 v42, v127, v49
	v_dot8c_i32_i4_e32 v43, v127, v47
	v_dot8c_i32_i4_e32 v44, v129, v49
	v_dot8c_i32_i4_e32 v45, v129, v47
	s_waitcnt lgkmcnt(15)
	v_add_u32_e32 v143, 8, v139
	v_and_b32_e32 v142, 15, v143
	v_xor_b32_e32 v142, 8, v142
	v_bfe_u32 v144, v143, 4, 4
	v_mul_lo_u32 v142, v142, s92
	v_mul_lo_u32 v144, v144, s92
	v_mov_b32_e32 v143, v142
	v_mov_b32_e32 v145, v144
	ds_write2st64_b64 v159, v[142:143], v[144:145] offset1:2
	v_and_b32_e32 v78, 0xffff, v20
	v_lshrrev_b32_e32 v79, 16, v20
	v_lshl_add_u32 v78, v78, 7, v150
	v_lshl_add_u32 v79, v79, 7, v151
	s_mov_b32 m0, s78
	s_add_i32 s43, s78, 0x400
	global_load_lds_dwordx4 v78, s[50:51]
	s_mov_b32 m0, s43
	s_nop 0
	global_load_lds_dwordx4 v79, s[50:51]
	s_waitcnt vmcnt(8)
	v_add_u32_e32 v54, s98, v59
	v_add_u32_e32 v55, s98, v60
	v_add_u32_e32 v56, s98, v61
	v_add_u32_e32 v57, s98, v62
	ds_read_b64_tr_b4 v[46:47], v160 offset:768
	ds_read_b64_tr_b4 v[48:49], v160 offset:1792
	ds_read_b64_tr_b4 v[122:123], v54
	ds_read_b64_tr_b4 v[124:125], v55
	ds_read_b64_tr_b4 v[126:127], v56
	ds_read_b64_tr_b4 v[128:129], v57
	s_waitcnt lgkmcnt(7)
	v_dot8c_i32_i4_e32 v38, v130, v52
	v_dot8c_i32_i4_e32 v39, v130, v50
	v_dot8c_i32_i4_e32 v40, v132, v52
	v_dot8c_i32_i4_e32 v41, v132, v50
	v_dot8c_i32_i4_e32 v42, v134, v52
	v_dot8c_i32_i4_e32 v43, v134, v50
	v_dot8c_i32_i4_e32 v44, v136, v52
	v_dot8c_i32_i4_e32 v45, v136, v50
	v_dot8c_i32_i4_e32 v38, v131, v53
	v_dot8c_i32_i4_e32 v39, v131, v51
	v_dot8c_i32_i4_e32 v40, v133, v53
	v_dot8c_i32_i4_e32 v41, v133, v51
	v_dot8c_i32_i4_e32 v42, v135, v53
	v_dot8c_i32_i4_e32 v43, v135, v51
	v_dot8c_i32_i4_e32 v44, v137, v53
	v_dot8c_i32_i4_e32 v45, v137, v51
	v_and_b32_e32 v78, 0xffff, v21
	v_lshrrev_b32_e32 v79, 16, v21
	v_lshl_add_u32 v78, v78, 7, v150
	v_lshl_add_u32 v79, v79, 7, v151
	s_mov_b32 m0, s79
	s_add_i32 s43, s79, 0x400
	global_load_lds_dwordx4 v78, s[50:51]
	s_mov_b32 m0, s43
	s_nop 0
	global_load_lds_dwordx4 v79, s[50:51]
	s_waitcnt vmcnt(8)
	v_add_u32_e32 v54, s99, v59
	v_add_u32_e32 v55, s99, v60
	v_add_u32_e32 v56, s99, v61
	v_add_u32_e32 v57, s99, v62
	ds_read_b64_tr_b4 v[50:51], v160 offset:896
	ds_read_b64_tr_b4 v[52:53], v160 offset:1920
	ds_read_b64_tr_b4 v[130:131], v54
	ds_read_b64_tr_b4 v[132:133], v55
	ds_read_b64_tr_b4 v[134:135], v56
	ds_read_b64_tr_b4 v[136:137], v57
	s_waitcnt lgkmcnt(6)
	v_dot8c_i32_i4_e32 v38, v122, v48
	v_dot8c_i32_i4_e32 v39, v122, v46
	v_dot8c_i32_i4_e32 v40, v124, v48
	v_dot8c_i32_i4_e32 v41, v124, v46
	v_dot8c_i32_i4_e32 v42, v126, v48
	v_dot8c_i32_i4_e32 v43, v126, v46
	v_dot8c_i32_i4_e32 v44, v128, v48
	v_dot8c_i32_i4_e32 v45, v128, v46
	v_dot8c_i32_i4_e32 v38, v123, v49
	v_dot8c_i32_i4_e32 v39, v123, v47
	v_dot8c_i32_i4_e32 v40, v125, v49
	v_dot8c_i32_i4_e32 v41, v125, v47
	v_dot8c_i32_i4_e32 v42, v127, v49
	v_dot8c_i32_i4_e32 v43, v127, v47
	v_dot8c_i32_i4_e32 v44, v129, v49
	v_dot8c_i32_i4_e32 v45, v129, v47
	v_and_b32_e32 v78, 0xffff, v22
	v_lshrrev_b32_e32 v79, 16, v22
	v_lshl_add_u32 v78, v78, 7, v150
	v_lshl_add_u32 v79, v79, 7, v151
	s_mov_b32 m0, s98
	s_add_i32 s43, s98, 0x400
	global_load_lds_dwordx4 v78, s[50:51]
	s_mov_b32 m0, s43
	s_nop 0
	global_load_lds_dwordx4 v79, s[50:51]
	s_waitcnt vmcnt(8)
	v_add_u32_e32 v54, s76, v59
	v_add_u32_e32 v55, s76, v60
	v_add_u32_e32 v56, s76, v61
	v_add_u32_e32 v57, s76, v62
	ds_read_b64_tr_b4 v[46:47], v160
	ds_read_b64_tr_b4 v[48:49], v160 offset:1024
	ds_read_b64_tr_b4 v[122:123], v54
	ds_read_b64_tr_b4 v[124:125], v55
	ds_read_b64_tr_b4 v[126:127], v56
	ds_read_b64_tr_b4 v[128:129], v57
	s_waitcnt lgkmcnt(6)
	v_dot8c_i32_i4_e32 v38, v130, v52
	v_dot8c_i32_i4_e32 v39, v130, v50
	v_dot8c_i32_i4_e32 v40, v132, v52
	v_dot8c_i32_i4_e32 v41, v132, v50
	v_dot8c_i32_i4_e32 v42, v134, v52
	v_dot8c_i32_i4_e32 v43, v134, v50
	v_dot8c_i32_i4_e32 v44, v136, v52
	v_dot8c_i32_i4_e32 v45, v136, v50
	v_dot8c_i32_i4_e32 v38, v131, v53
	v_dot8c_i32_i4_e32 v39, v131, v51
	v_dot8c_i32_i4_e32 v40, v133, v53
	v_dot8c_i32_i4_e32 v41, v133, v51
	v_dot8c_i32_i4_e32 v42, v135, v53
	v_dot8c_i32_i4_e32 v43, v135, v51
	v_dot8c_i32_i4_e32 v44, v137, v53
	v_dot8c_i32_i4_e32 v45, v137, v51
	s_nop 3
	s_waitcnt lgkmcnt(15)
	v_lshlrev_b32_e32 v38, 5, v38
	v_lshlrev_b32_e32 v39, 1, v39
	v_add3_u32 v38, v39, v229, v38
	v_cvt_f32_i32_e32 v38, v38
	v_mul_f32_e32 v38, v228, v38
	v_lshlrev_b32_e32 v40, 5, v40
	v_lshlrev_b32_e32 v41, 1, v41
	v_add3_u32 v40, v41, v229, v40
	v_cvt_f32_i32_e32 v40, v40
	v_mul_f32_e32 v40, v228, v40
	v_lshlrev_b32_e32 v42, 5, v42
	v_lshlrev_b32_e32 v43, 1, v43
	v_add3_u32 v42, v43, v229, v42
	v_cvt_f32_i32_e32 v42, v42
	v_mul_f32_e32 v42, v228, v42
	v_lshlrev_b32_e32 v44, 5, v44
	v_lshlrev_b32_e32 v45, 1, v45
	v_add3_u32 v44, v45, v229, v44
	v_cvt_f32_i32_e32 v44, v44
	v_mul_f32_e32 v44, v228, v44
	v_cvt_pk_bf16_f32 v188, v38, v40
	v_cvt_pk_bf16_f32 v189, v42, v44
	ds_read_b128 v[252:255], v156
	s_add_i32 s44, s40, 0
	s_ashr_i32 s45, s44, 31
	s_lshl_b64 s[44:45], s[44:45], 12
	v_lshl_add_u64 v[80:81], v[36:37], 0, s[44:45]
	s_waitcnt lgkmcnt(0)
; #define LAS __attribute__((address_space(3)))
; __device__ __forceinline__ void peer_v_tokens(int j, const LAS unsigned short* EL, const LAS unsigned char* AL  , const LAS float* ASC  , const LAS int* SAL  , ...
;     ...
;             if (st < 14) VDMA(st + 2, (st + 2) % 3);
;             if (st < 14) asm volatile("s_waitcnt vmcnt(8)" ::: "memory");
;             else if (st == 14) asm volatile("s_waitcnt vmcnt(4)" ::: "memory");
;             else asm volatile("s_waitcnt vmcnt(0)" ::: "memory");
;             if (q == 0) {
; #pragma unroll
;                 for (int r = 0; r < 4; ++r) { accH[r] = 0; accL[r] = 0; } }
; #pragma unroll
;             for (int tp = 0; tp < 2; ++tp) {
;                 const v2i ao = TR4(ATL + (2 * q + tp) * 128 + 8 * s16), ah = TR4(ATL + 1024 + (2 * q + tp) * 128 + 8 * s16);
; #pragma unroll
;                 for (int r = 0; r < 4; ++r) {
;                     const v2i d = TR4(ldsb + BUF[st % 3] + 2048 * tp + roff[r]);
;                     accH[r] = __builtin_amdgcn_sdot8(d.x, ah.x, accH[r], false); accH[r] = __builtin_amdgcn_sdot8(d.y, ah.y, accH[r], false);
;                     accL[r] = __builtin_amdgcn_sdot8(d.x, ao.x, accL[r], false); accL[r] = __builtin_amdgcn_sdot8(d.y, ao.y, accL[r], false);
;                 }
;             }
;             asm volatile("s_waitcnt lgkmcnt(0)" ::: "memory");
;             if (q == 3) {
; #pragma unroll
;                 for (int r = 0; r < 4; ++r) STASH[256 * p + 16 * (grp + 4 * r) + pc] = f2bf(asc * (float)(2 * ((accH[r] << 4) + accL[r]) + sa));
;             }
;         }
;         CFENCE();
;         {
;             float4 v[4]; float ss = 0.f;
; #pragma unroll
;             for (int jq = 0; jq < 4; ++jq) { typedef unsigned u2v __attribute__((ext_vector_type(2))); const u2v pw = *(const LAS u2v*)(STASH + 4 * lane + 256 * jq); const uint2 hw = hv[jq];
;                 v[jq] = make_float4(__uint_as_float(hw.x << 16) + __uint_as_float(pw.x << 16), __uint_as_float(hw.x & 0xffff0000u) + __uint_as_float(pw.x & 0xffff0000u),
;                                     __uint_as_float(hw.y << 16) + __uint_as_float(pw.y << 16), __uint_as_float(hw.y & 0xffff0000u) + __uint_as_float(pw.y & 0xffff0000u));
;                 ss += v[jq].x * v[jq].x + v[jq].y * v[jq].y + v[jq].z * v[jq].z + v[jq].w * v[jq].w; }
;             ss = wave_sum(ss);
;             const float r3 = rsqrtf(ss * (1.f / D) + EPS);
	v_mul_f32_e32 v218, v218, v252
	v_mul_f32_e32 v219, v219, v253
	v_mul_f32_e32 v220, v220, v254
	v_mul_f32_e32 v221, v221, v255
	global_store_dwordx4 v[80:81], v[218:221], off offset:2048 nt
	v_add_u32_e32 v147, 8, v140
	v_and_b32_e32 v146, 15, v147
	v_xor_b32_e32 v146, 8, v146
	v_bfe_u32 v148, v147, 4, 4
	v_mul_lo_u32 v146, v146, s92
	v_mul_lo_u32 v148, v148, s92
	v_mov_b32_e32 v147, v146
	v_mov_b32_e32 v149, v148
	ds_write2st64_b64 v77, v[146:147], v[148:149] offset1:2
	v_add_u32_e32 v138, 0xc00, v74
	ds_read_u8 v139, v138
	v_add_u32_e32 v141, 0xc00, v73
	ds_read_u8 v140, v141
	s_add_i32 s43, s67, 64
	v_mov_b32_e32 v138, s43
	ds_read2st64_b32 v[228:229], v138 offset1:1
	ds_read_b128 v[26:29], v227 offset:6144
	ds_read_b128 v[30:33], v227 offset:6160
	v_mov_b32_e32 v38, 0
	v_mov_b32_e32 v39, 0
	v_mov_b32_e32 v40, 0
	v_mov_b32_e32 v41, 0
	v_mov_b32_e32 v42, 0
	v_mov_b32_e32 v43, 0
	v_mov_b32_e32 v44, 0
	v_mov_b32_e32 v45, 0
	v_and_b32_e32 v78, 0xffff, v23
	v_lshrrev_b32_e32 v79, 16, v23
	v_lshl_add_u32 v78, v78, 7, v150
	v_lshl_add_u32 v79, v79, 7, v151
	s_mov_b32 m0, s99
	s_add_i32 s43, s99, 0x400
	global_load_lds_dwordx4 v78, s[50:51]
	s_mov_b32 m0, s43
	s_nop 0
	global_load_lds_dwordx4 v79, s[50:51]
	s_waitcnt vmcnt(9)
	v_add_u32_e32 v54, s77, v59
	v_add_u32_e32 v55, s77, v60
	v_add_u32_e32 v56, s77, v61
	v_add_u32_e32 v57, s77, v62
	ds_read_b64_tr_b4 v[50:51], v160 offset:128
	ds_read_b64_tr_b4 v[52:53], v160 offset:1152
	ds_read_b64_tr_b4 v[130:131], v54
	ds_read_b64_tr_b4 v[132:133], v55
	ds_read_b64_tr_b4 v[134:135], v56
	ds_read_b64_tr_b4 v[136:137], v57
	s_waitcnt lgkmcnt(13)
	s_waitcnt vmcnt(36) lgkmcnt(15)
	v_lshlrev_b32_e32 v236, 16, v194
	v_and_b32_e32 v237, 0xffff0000, v194
	v_lshlrev_b32_e32 v142, 16, v202
	v_and_b32_e32 v143, 0xffff0000, v202
	v_add_f32_e32 v236, v236, v142
	v_add_f32_e32 v237, v237, v143
	v_lshlrev_b32_e32 v238, 16, v195
	v_and_b32_e32 v239, 0xffff0000, v195
	v_lshlrev_b32_e32 v142, 16, v203
	v_and_b32_e32 v143, 0xffff0000, v203
	v_add_f32_e32 v238, v238, v142
	v_add_f32_e32 v239, v239, v143
	v_lshlrev_b32_e32 v240, 16, v196
	v_and_b32_e32 v241, 0xffff0000, v196
	v_lshlrev_b32_e32 v142, 16, v204
	v_and_b32_e32 v143, 0xffff0000, v204
	v_add_f32_e32 v240, v240, v142
	v_add_f32_e32 v241, v241, v143
	v_lshlrev_b32_e32 v242, 16, v197
	v_and_b32_e32 v243, 0xffff0000, v197
	v_lshlrev_b32_e32 v142, 16, v205
	v_and_b32_e32 v143, 0xffff0000, v205
	v_add_f32_e32 v242, v242, v142
	v_add_f32_e32 v243, v243, v143
	v_lshlrev_b32_e32 v244, 16, v198
	v_and_b32_e32 v245, 0xffff0000, v198
	v_lshlrev_b32_e32 v142, 16, v206
	v_and_b32_e32 v143, 0xffff0000, v206
	v_add_f32_e32 v244, v244, v142
	v_add_f32_e32 v245, v245, v143
	v_lshlrev_b32_e32 v246, 16, v199
	v_and_b32_e32 v247, 0xffff0000, v199
	v_lshlrev_b32_e32 v142, 16, v207
	v_and_b32_e32 v143, 0xffff0000, v207
	v_add_f32_e32 v246, v246, v142
	v_add_f32_e32 v247, v247, v143
	v_lshlrev_b32_e32 v248, 16, v200
	v_and_b32_e32 v249, 0xffff0000, v200
	v_lshlrev_b32_e32 v142, 16, v208
	v_and_b32_e32 v143, 0xffff0000, v208
	v_add_f32_e32 v248, v248, v142
	v_add_f32_e32 v249, v249, v143
	v_lshlrev_b32_e32 v250, 16, v201
	v_and_b32_e32 v251, 0xffff0000, v201
	v_lshlrev_b32_e32 v142, 16, v209
	v_and_b32_e32 v143, 0xffff0000, v209
	v_add_f32_e32 v250, v250, v142
	v_add_f32_e32 v251, v251, v143
	v_mov_b32_e32 v144, 0
	v_mul_f32_e32 v145, v236, v236
	v_fmac_f32_e32 v145, v237, v237
	v_fmac_f32_e32 v145, v238, v238
	v_fmac_f32_e32 v145, v239, v239
	v_add_f32_e32 v144, v144, v145
	v_mul_f32_e32 v145, v240, v240
	v_fmac_f32_e32 v145, v241, v241
	v_fmac_f32_e32 v145, v242, v242
	v_fmac_f32_e32 v145, v243, v243
	v_add_f32_e32 v144, v144, v145
	v_mul_f32_e32 v145, v244, v244
	v_fmac_f32_e32 v145, v245, v245
	v_fmac_f32_e32 v145, v246, v246
	v_fmac_f32_e32 v145, v247, v247
	v_add_f32_e32 v144, v144, v145
	v_mul_f32_e32 v145, v248, v248
	v_fmac_f32_e32 v145, v249, v249
	v_fmac_f32_e32 v145, v250, v250
	v_fmac_f32_e32 v145, v251, v251
	v_add_f32_e32 v144, v144, v145
	s_nop 1
	v_add_f32_dpp v144, v144, v144 quad_perm:[1,0,3,2] row_mask:0xf bank_mask:0xf bound_ctrl:1
	s_nop 1
	v_add_f32_dpp v144, v144, v144 quad_perm:[2,3,0,1] row_mask:0xf bank_mask:0xf bound_ctrl:1
	s_nop 1
	v_add_f32_dpp v144, v144, v144 row_half_mirror row_mask:0xf bank_mask:0xf bound_ctrl:1
	s_nop 1
	v_add_f32_dpp v144, v144, v144 row_mirror row_mask:0xf bank_mask:0xf bound_ctrl:1
	s_nop 1
	v_readlane_b32 s10, v144, 0
	v_readlane_b32 s11, v144, 16
	v_readlane_b32 s14, v144, 32
	v_readlane_b32 s15, v144, 48
	s_nop 3
	v_mov_b32_e32 v144, s11
	v_mov_b32_e32 v145, s15
	v_add_f32_e32 v144, s10, v144
	v_add_f32_e32 v145, s14, v145
	v_add_f32_e32 v144, v144, v145
	v_fmamk_f32 v144, v144, 0x3a800000, v111
	v_rsq_f32_e32 v144, v144
	s_nop 0
	v_mul_f32_e32 v236, v236, v144
	v_mul_f32_e32 v237, v237, v144
	v_mul_f32_e32 v238, v238, v144
	v_mul_f32_e32 v239, v239, v144
	v_mul_f32_e32 v240, v240, v144
	v_mul_f32_e32 v241, v241, v144
	v_mul_f32_e32 v242, v242, v144
	v_mul_f32_e32 v243, v243, v144
	v_mul_f32_e32 v244, v244, v144
	v_mul_f32_e32 v245, v245, v144
	v_mul_f32_e32 v246, v246, v144
	v_mul_f32_e32 v247, v247, v144
	v_mul_f32_e32 v248, v248, v144
	v_mul_f32_e32 v249, v249, v144
	v_mul_f32_e32 v250, v250, v144
	v_mul_f32_e32 v251, v251, v144
	v_dot8c_i32_i4_e32 v38, v122, v48
	v_dot8c_i32_i4_e32 v39, v122, v46
	v_dot8c_i32_i4_e32 v40, v124, v48
	v_dot8c_i32_i4_e32 v41, v124, v46
	v_dot8c_i32_i4_e32 v42, v126, v48
	v_dot8c_i32_i4_e32 v43, v126, v46
	v_dot8c_i32_i4_e32 v44, v128, v48
	v_dot8c_i32_i4_e32 v45, v128, v46
	v_dot8c_i32_i4_e32 v38, v123, v49
	v_dot8c_i32_i4_e32 v39, v123, v47
	v_dot8c_i32_i4_e32 v40, v125, v49
	v_dot8c_i32_i4_e32 v41, v125, v47
	v_dot8c_i32_i4_e32 v42, v127, v49
	v_dot8c_i32_i4_e32 v43, v127, v47
	v_dot8c_i32_i4_e32 v44, v129, v49
	v_dot8c_i32_i4_e32 v45, v129, v47
	v_and_b32_e32 v78, 0xffff, v24
	v_lshrrev_b32_e32 v79, 16, v24
	v_lshl_add_u32 v78, v78, 7, v150
	v_lshl_add_u32 v79, v79, 7, v151
	s_mov_b32 m0, s76
	s_add_i32 s43, s76, 0x400
	global_load_lds_dwordx4 v78, s[50:51]
	s_mov_b32 m0, s43
	s_nop 0
	global_load_lds_dwordx4 v79, s[50:51]
	s_waitcnt vmcnt(9)
; #define TR4(p_) __builtin_amdgcn_ds_read_tr4_b64_v2i32((LAS v2i*)(p_))
; #define VDMA(st_, k_) do { _Pragma("unroll") for (int i_ = 0; i_ < 4; ++i_) { \
;         const unsigned off_ = (unsigned)((st_) >> 2) * (16384u * 128u) + (PE_ID(E, 4 * ((st_) & 3) + i_) << 7) + ((i_ & 1) ? cx1 : cx0); \
;         __builtin_amdgcn_global_load_lds((const unsigned*)(V4 + off_), (LAS unsigned*)(ldsb + BUF[k_] + 1024 * i_), 16, 0, 0); } } while (0)
; __device__ __forceinline__ void peer_v_tokens(int j, const LAS unsigned short* EL, const LAS unsigned char* AL  , const LAS float* ASC  , const LAS int* SAL  , ...
;     ...
;             if (st < 14) VDMA(st + 2, (st + 2) % 3);
;             if (st < 14) asm volatile("s_waitcnt vmcnt(8)" ::: "memory");
;             else if (st == 14) asm volatile("s_waitcnt vmcnt(4)" ::: "memory");
;             else asm volatile("s_waitcnt vmcnt(0)" ::: "memory");
;             if (q == 0) {
; #pragma unroll
;                 for (int r = 0; r < 4; ++r) { accH[r] = 0; accL[r] = 0; } }
; #pragma unroll
;             for (int tp = 0; tp < 2; ++tp) {
;                 const v2i ao = TR4(ATL + (2 * q + tp) * 128 + 8 * s16), ah = TR4(ATL + 1024 + (2 * q + tp) * 128 + 8 * s16);
; #pragma unroll
;                 for (int r = 0; r < 4; ++r) {
;                     const v2i d = TR4(ldsb + BUF[st % 3] + 2048 * tp + roff[r]);
;                     accH[r] = __builtin_amdgcn_sdot8(d.x, ah.x, accH[r], false); accH[r] = __builtin_amdgcn_sdot8(d.y, ah.y, accH[r], false);
;                     accL[r] = __builtin_amdgcn_sdot8(d.x, ao.x, accL[r], false); accL[r] = __builtin_amdgcn_sdot8(d.y, ao.y, accL[r], false);
;                 }
	v_add_u32_e32 v54, s78, v59
	v_add_u32_e32 v55, s78, v60
	v_add_u32_e32 v56, s78, v61
	v_add_u32_e32 v57, s78, v62
	ds_read_b64_tr_b4 v[46:47], v160 offset:256
	ds_read_b64_tr_b4 v[48:49], v160 offset:1280
	ds_read_b64_tr_b4 v[122:123], v54
	ds_read_b64_tr_b4 v[124:125], v55
	ds_read_b64_tr_b4 v[126:127], v56
	ds_read_b64_tr_b4 v[128:129], v57
	s_waitcnt lgkmcnt(6)
	v_dot8c_i32_i4_e32 v38, v130, v52
	v_dot8c_i32_i4_e32 v39, v130, v50
	v_dot8c_i32_i4_e32 v40, v132, v52
	v_dot8c_i32_i4_e32 v41, v132, v50
	v_dot8c_i32_i4_e32 v42, v134, v52
	v_dot8c_i32_i4_e32 v43, v134, v50
	v_dot8c_i32_i4_e32 v44, v136, v52
	v_dot8c_i32_i4_e32 v45, v136, v50
	v_dot8c_i32_i4_e32 v38, v131, v53
	v_dot8c_i32_i4_e32 v39, v131, v51
	v_dot8c_i32_i4_e32 v40, v133, v53
	v_dot8c_i32_i4_e32 v41, v133, v51
	v_dot8c_i32_i4_e32 v42, v135, v53
	v_dot8c_i32_i4_e32 v43, v135, v51
	v_dot8c_i32_i4_e32 v44, v137, v53
	v_dot8c_i32_i4_e32 v45, v137, v51
	v_and_b32_e32 v78, 0xffff, v25
	v_lshrrev_b32_e32 v79, 16, v25
	v_lshl_add_u32 v78, v78, 7, v150
	v_lshl_add_u32 v79, v79, 7, v151
	s_mov_b32 m0, s77
	s_add_i32 s43, s77, 0x400
	global_load_lds_dwordx4 v78, s[50:51]
	s_mov_b32 m0, s43
	s_nop 0
	global_load_lds_dwordx4 v79, s[50:51]
	s_waitcnt vmcnt(9)
	v_add_u32_e32 v54, s79, v59
	v_add_u32_e32 v55, s79, v60
	v_add_u32_e32 v56, s79, v61
	v_add_u32_e32 v57, s79, v62
	ds_read_b64_tr_b4 v[50:51], v160 offset:384
	ds_read_b64_tr_b4 v[52:53], v160 offset:1408
	ds_read_b64_tr_b4 v[130:131], v54
	ds_read_b64_tr_b4 v[132:133], v55
	ds_read_b64_tr_b4 v[134:135], v56
	ds_read_b64_tr_b4 v[136:137], v57
	s_waitcnt lgkmcnt(6)
	v_dot8c_i32_i4_e32 v38, v122, v48
	v_dot8c_i32_i4_e32 v39, v122, v46
	v_dot8c_i32_i4_e32 v40, v124, v48
	v_dot8c_i32_i4_e32 v41, v124, v46
	v_dot8c_i32_i4_e32 v42, v126, v48
	v_dot8c_i32_i4_e32 v43, v126, v46
	v_dot8c_i32_i4_e32 v44, v128, v48
	v_dot8c_i32_i4_e32 v45, v128, v46
	v_dot8c_i32_i4_e32 v38, v123, v49
	v_dot8c_i32_i4_e32 v39, v123, v47
	v_dot8c_i32_i4_e32 v40, v125, v49
	v_dot8c_i32_i4_e32 v41, v125, v47
	v_dot8c_i32_i4_e32 v42, v127, v49
	v_dot8c_i32_i4_e32 v43, v127, v47
	v_dot8c_i32_i4_e32 v44, v129, v49
	v_dot8c_i32_i4_e32 v45, v129, v47
	s_waitcnt lgkmcnt(15)
	v_and_b32_e32 v78, 0xffff, v26
	v_lshrrev_b32_e32 v79, 16, v26
	v_lshl_add_u32 v78, v78, 7, v150
	v_lshl_add_u32 v79, v79, 7, v151
	s_mov_b32 m0, s78
	s_add_i32 s43, s78, 0x400
	global_load_lds_dwordx4 v78, s[50:51]
	s_mov_b32 m0, s43
	s_nop 0
	global_load_lds_dwordx4 v79, s[50:51]
	s_waitcnt vmcnt(9)
	v_add_u32_e32 v54, s98, v59
	v_add_u32_e32 v55, s98, v60
	v_add_u32_e32 v56, s98, v61
	v_add_u32_e32 v57, s98, v62
	ds_read_b64_tr_b4 v[46:47], v160 offset:512
	ds_read_b64_tr_b4 v[48:49], v160 offset:1536
	ds_read_b64_tr_b4 v[122:123], v54
	ds_read_b64_tr_b4 v[124:125], v55
	ds_read_b64_tr_b4 v[126:127], v56
	ds_read_b64_tr_b4 v[128:129], v57
	s_waitcnt lgkmcnt(6)
	v_dot8c_i32_i4_e32 v38, v130, v52
	v_dot8c_i32_i4_e32 v39, v130, v50
	v_dot8c_i32_i4_e32 v40, v132, v52
	v_dot8c_i32_i4_e32 v41, v132, v50
	v_dot8c_i32_i4_e32 v42, v134, v52
	v_dot8c_i32_i4_e32 v43, v134, v50
	v_dot8c_i32_i4_e32 v44, v136, v52
	v_dot8c_i32_i4_e32 v45, v136, v50
	v_dot8c_i32_i4_e32 v38, v131, v53
	v_dot8c_i32_i4_e32 v39, v131, v51
	v_dot8c_i32_i4_e32 v40, v133, v53
	v_dot8c_i32_i4_e32 v41, v133, v51
	v_dot8c_i32_i4_e32 v42, v135, v53
	v_dot8c_i32_i4_e32 v43, v135, v51
	v_dot8c_i32_i4_e32 v44, v137, v53
	v_dot8c_i32_i4_e32 v45, v137, v51
	v_and_b32_e32 v78, 0xffff, v27
	v_lshrrev_b32_e32 v79, 16, v27
	v_lshl_add_u32 v78, v78, 7, v150
	v_lshl_add_u32 v79, v79, 7, v151
	s_mov_b32 m0, s79
	s_add_i32 s43, s79, 0x400
	global_load_lds_dwordx4 v78, s[50:51]
	s_mov_b32 m0, s43
	s_nop 0
	global_load_lds_dwordx4 v79, s[50:51]
	s_waitcnt vmcnt(8)
	v_add_u32_e32 v54, s99, v59
	v_add_u32_e32 v55, s99, v60
	v_add_u32_e32 v56, s99, v61
	v_add_u32_e32 v57, s99, v62
	ds_read_b64_tr_b4 v[50:51], v160 offset:640
	ds_read_b64_tr_b4 v[52:53], v160 offset:1664
	ds_read_b64_tr_b4 v[130:131], v54
	ds_read_b64_tr_b4 v[132:133], v55
	ds_read_b64_tr_b4 v[134:135], v56
	ds_read_b64_tr_b4 v[136:137], v57
	s_waitcnt lgkmcnt(6)
	v_dot8c_i32_i4_e32 v38, v122, v48
	v_dot8c_i32_i4_e32 v39, v122, v46
	v_dot8c_i32_i4_e32 v40, v124, v48
	v_dot8c_i32_i4_e32 v41, v124, v46
	v_dot8c_i32_i4_e32 v42, v126, v48
	v_dot8c_i32_i4_e32 v43, v126, v46
	v_dot8c_i32_i4_e32 v44, v128, v48
	v_dot8c_i32_i4_e32 v45, v128, v46
	v_dot8c_i32_i4_e32 v38, v123, v49
	v_dot8c_i32_i4_e32 v39, v123, v47
	v_dot8c_i32_i4_e32 v40, v125, v49
	v_dot8c_i32_i4_e32 v41, v125, v47
	v_dot8c_i32_i4_e32 v42, v127, v49
	v_dot8c_i32_i4_e32 v43, v127, v47
	v_dot8c_i32_i4_e32 v44, v129, v49
	v_dot8c_i32_i4_e32 v45, v129, v47
	s_waitcnt lgkmcnt(15)
	v_add_u32_e32 v143, 8, v139
	v_and_b32_e32 v142, 15, v143
	v_xor_b32_e32 v142, 8, v142
	v_bfe_u32 v144, v143, 4, 4
	v_mul_lo_u32 v142, v142, s92
	v_mul_lo_u32 v144, v144, s92
	v_mov_b32_e32 v143, v142
	v_mov_b32_e32 v145, v144
	ds_write2st64_b64 v159, v[142:143], v[144:145] offset1:2
	v_and_b32_e32 v78, 0xffff, v28
	v_lshrrev_b32_e32 v79, 16, v28
	v_lshl_add_u32 v78, v78, 7, v150
	v_lshl_add_u32 v79, v79, 7, v151
	s_mov_b32 m0, s98
	s_add_i32 s43, s98, 0x400
	global_load_lds_dwordx4 v78, s[50:51]
	s_mov_b32 m0, s43
	s_nop 0
	global_load_lds_dwordx4 v79, s[50:51]
	s_waitcnt vmcnt(8)
	v_add_u32_e32 v54, s76, v59
	v_add_u32_e32 v55, s76, v60
	v_add_u32_e32 v56, s76, v61
	v_add_u32_e32 v57, s76, v62
	ds_read_b64_tr_b4 v[46:47], v160 offset:768
	ds_read_b64_tr_b4 v[48:49], v160 offset:1792
	ds_read_b64_tr_b4 v[122:123], v54
	ds_read_b64_tr_b4 v[124:125], v55
	ds_read_b64_tr_b4 v[126:127], v56
	ds_read_b64_tr_b4 v[128:129], v57
	s_waitcnt lgkmcnt(7)
; #define LAS __attribute__((address_space(3)))
; __device__ __forceinline__ void peer_v_tokens(int j, const LAS unsigned short* EL, const LAS unsigned char* AL  , const LAS float* ASC  , const LAS int* SAL  , ...
;     ...
;         { const LAS v4u* ep = (const LAS v4u*)(EL + tl * 128 + 16 * g); const v4u e0 = ep[0], e1 = ep[1];
;           E[0] = e0.x; E[1] = e0.y; E[2] = e0.z; E[3] = e0.w; E[4] = e1.x; E[5] = e1.y; E[6] = e1.z; E[7] = e1.w; }
;         uint2 hv[4]; float4 gv[4];
;         { unsigned ho = (unsigned)t * (D / 4) + (unsigned)lane; asm volatile("" : "+v"(ho)); const uint2* hp = (const uint2*)HB + ho; const float4* gp = (const float4*)fng + lane;
; #pragma unroll
;           for (int jq = 0; jq < 4; ++jq) { hv[jq] = hp[64 * jq]; gv[jq] = gp[64 * jq]; } }
;         VDMA(0, 0); VDMA(1, 1);
; #pragma unroll
;         for (int m = 0; m < 2; ++m) {
;             const int idx = lane + 64 * m, tau = idx >> 4, sr = idx & 15, k = 16 * (sr & 7) + 2 * tau + (sr >> 3);
;     ...
;         for (int st = 0; st < 16; ++st) {
;             const int p = st >> 2, q = st & 3;
;             if (st < 14) VDMA(st + 2, (st + 2) % 3);
;             if (st < 14) asm volatile("s_waitcnt vmcnt(8)" ::: "memory");
;             else if (st == 14) asm volatile("s_waitcnt vmcnt(4)" ::: "memory");
;             else asm volatile("s_waitcnt vmcnt(0)" ::: "memory");
;             if (q == 0) {
; #pragma unroll
;                 for (int r = 0; r < 4; ++r) { accH[r] = 0; accL[r] = 0; } }
; #pragma unroll
;             for (int tp = 0; tp < 2; ++tp) {
;                 const v2i ao = TR4(ATL + (2 * q + tp) * 128 + 8 * s16), ah = TR4(ATL + 1024 + (2 * q + tp) * 128 + 8 * s16);
; #pragma unroll
;                 for (int r = 0; r < 4; ++r) {
;                     const v2i d = TR4(ldsb + BUF[st % 3] + 2048 * tp + roff[r]);
;                     accH[r] = __builtin_amdgcn_sdot8(d.x, ah.x, accH[r], false); accH[r] = __builtin_amdgcn_sdot8(d.y, ah.y, accH[r], false);
;                     accL[r] = __builtin_amdgcn_sdot8(d.x, ao.x, accL[r], false); accL[r] = __builtin_amdgcn_sdot8(d.y, ao.y, accL[r], false);
;                 }
;             }
;             asm volatile("s_waitcnt lgkmcnt(0)" ::: "memory");
;             if (q == 3) {
; #pragma unroll
;                 for (int r = 0; r < 4; ++r) STASH[256 * p + 16 * (grp + 4 * r) + pc] = f2bf(asc * (float)(2 * ((accH[r] << 4) + accL[r]) + sa));
	v_dot8c_i32_i4_e32 v38, v130, v52
	v_dot8c_i32_i4_e32 v39, v130, v50
	v_dot8c_i32_i4_e32 v40, v132, v52
	v_dot8c_i32_i4_e32 v41, v132, v50
	v_dot8c_i32_i4_e32 v42, v134, v52
	v_dot8c_i32_i4_e32 v43, v134, v50
	v_dot8c_i32_i4_e32 v44, v136, v52
	v_dot8c_i32_i4_e32 v45, v136, v50
	v_dot8c_i32_i4_e32 v38, v131, v53
	v_dot8c_i32_i4_e32 v39, v131, v51
	v_dot8c_i32_i4_e32 v40, v133, v53
	v_dot8c_i32_i4_e32 v41, v133, v51
	v_dot8c_i32_i4_e32 v42, v135, v53
	v_dot8c_i32_i4_e32 v43, v135, v51
	v_dot8c_i32_i4_e32 v44, v137, v53
	v_dot8c_i32_i4_e32 v45, v137, v51
	v_and_b32_e32 v78, 0xffff, v29
	v_lshrrev_b32_e32 v79, 16, v29
	v_lshl_add_u32 v78, v78, 7, v150
	v_lshl_add_u32 v79, v79, 7, v151
	s_mov_b32 m0, s99
	s_add_i32 s43, s99, 0x400
	global_load_lds_dwordx4 v78, s[50:51]
	s_mov_b32 m0, s43
	s_nop 0
	global_load_lds_dwordx4 v79, s[50:51]
	s_waitcnt vmcnt(8)
	v_add_u32_e32 v54, s77, v59
	v_add_u32_e32 v55, s77, v60
	v_add_u32_e32 v56, s77, v61
	v_add_u32_e32 v57, s77, v62
	ds_read_b64_tr_b4 v[50:51], v160 offset:896
	ds_read_b64_tr_b4 v[52:53], v160 offset:1920
	ds_read_b64_tr_b4 v[130:131], v54
	ds_read_b64_tr_b4 v[132:133], v55
	ds_read_b64_tr_b4 v[134:135], v56
	ds_read_b64_tr_b4 v[136:137], v57
	s_waitcnt lgkmcnt(6)
	v_dot8c_i32_i4_e32 v38, v122, v48
	v_dot8c_i32_i4_e32 v39, v122, v46
	v_dot8c_i32_i4_e32 v40, v124, v48
	v_dot8c_i32_i4_e32 v41, v124, v46
	v_dot8c_i32_i4_e32 v42, v126, v48
	v_dot8c_i32_i4_e32 v43, v126, v46
	v_dot8c_i32_i4_e32 v44, v128, v48
	v_dot8c_i32_i4_e32 v45, v128, v46
	v_dot8c_i32_i4_e32 v38, v123, v49
	v_dot8c_i32_i4_e32 v39, v123, v47
	v_dot8c_i32_i4_e32 v40, v125, v49
	v_dot8c_i32_i4_e32 v41, v125, v47
	v_dot8c_i32_i4_e32 v42, v127, v49
	v_dot8c_i32_i4_e32 v43, v127, v47
	v_dot8c_i32_i4_e32 v44, v129, v49
	v_dot8c_i32_i4_e32 v45, v129, v47
	v_and_b32_e32 v78, 0xffff, v30
	v_lshrrev_b32_e32 v79, 16, v30
	v_lshl_add_u32 v78, v78, 7, v150
	v_lshl_add_u32 v79, v79, 7, v151
	s_mov_b32 m0, s76
	s_add_i32 s43, s76, 0x400
	global_load_lds_dwordx4 v78, s[50:51]
	s_mov_b32 m0, s43
	s_nop 0
	global_load_lds_dwordx4 v79, s[50:51]
	s_waitcnt vmcnt(8)
	v_add_u32_e32 v54, s78, v59
	v_add_u32_e32 v55, s78, v60
	v_add_u32_e32 v56, s78, v61
	v_add_u32_e32 v57, s78, v62
	ds_read_b64_tr_b4 v[46:47], v160
	ds_read_b64_tr_b4 v[48:49], v160 offset:1024
	ds_read_b64_tr_b4 v[122:123], v54
	ds_read_b64_tr_b4 v[124:125], v55
	ds_read_b64_tr_b4 v[126:127], v56
	ds_read_b64_tr_b4 v[128:129], v57
	s_waitcnt lgkmcnt(6)
	v_dot8c_i32_i4_e32 v38, v130, v52
	v_dot8c_i32_i4_e32 v39, v130, v50
	v_dot8c_i32_i4_e32 v40, v132, v52
	v_dot8c_i32_i4_e32 v41, v132, v50
	v_dot8c_i32_i4_e32 v42, v134, v52
	v_dot8c_i32_i4_e32 v43, v134, v50
	v_dot8c_i32_i4_e32 v44, v136, v52
	v_dot8c_i32_i4_e32 v45, v136, v50
	v_dot8c_i32_i4_e32 v38, v131, v53
	v_dot8c_i32_i4_e32 v39, v131, v51
	v_dot8c_i32_i4_e32 v40, v133, v53
	v_dot8c_i32_i4_e32 v41, v133, v51
	v_dot8c_i32_i4_e32 v42, v135, v53
	v_dot8c_i32_i4_e32 v43, v135, v51
	v_dot8c_i32_i4_e32 v44, v137, v53
	v_dot8c_i32_i4_e32 v45, v137, v51
	s_nop 3
	s_waitcnt lgkmcnt(15)
	v_lshlrev_b32_e32 v38, 5, v38
	v_lshlrev_b32_e32 v39, 1, v39
	v_add3_u32 v38, v39, v229, v38
	v_cvt_f32_i32_e32 v38, v38
	v_mul_f32_e32 v38, v228, v38
	v_lshlrev_b32_e32 v40, 5, v40
	v_lshlrev_b32_e32 v41, 1, v41
	v_add3_u32 v40, v41, v229, v40
	v_cvt_f32_i32_e32 v40, v40
	v_mul_f32_e32 v40, v228, v40
	v_lshlrev_b32_e32 v42, 5, v42
	v_lshlrev_b32_e32 v43, 1, v43
	v_add3_u32 v42, v43, v229, v42
	v_cvt_f32_i32_e32 v42, v42
	v_mul_f32_e32 v42, v228, v42
	v_lshlrev_b32_e32 v44, 5, v44
	v_lshlrev_b32_e32 v45, 1, v45
	v_add3_u32 v44, v45, v229, v44
	v_cvt_f32_i32_e32 v44, v44
	v_mul_f32_e32 v44, v228, v44
	v_cvt_pk_bf16_f32 v182, v38, v40
	v_cvt_pk_bf16_f32 v183, v42, v44
	ds_read_b128 v[252:255], v156 offset:1024
	s_add_i32 s44, s40, 0
	s_ashr_i32 s45, s44, 31
	s_lshl_b64 s[44:45], s[44:45], 12
	v_lshl_add_u64 v[80:81], v[36:37], 0, s[44:45]
	s_waitcnt lgkmcnt(0)
	v_mul_f32_e32 v222, v222, v252
	v_mul_f32_e32 v223, v223, v253
	v_mul_f32_e32 v224, v224, v254
	v_mul_f32_e32 v225, v225, v255
	global_store_dwordx4 v[80:81], v[222:225], off offset:3072 nt
	ds_read_b128 v[252:255], v155
	s_add_i32 s44, s40, 8
	s_ashr_i32 s45, s44, 31
	s_lshl_b64 s[44:45], s[44:45], 12
	v_lshl_add_u64 v[80:81], v[36:37], 0, s[44:45]
	s_waitcnt lgkmcnt(0)
	v_mul_f32_e32 v236, v236, v252
	v_mul_f32_e32 v237, v237, v253
	v_mul_f32_e32 v238, v238, v254
	v_mul_f32_e32 v239, v239, v255
	global_store_dwordx4 v[80:81], v[236:239], off nt
	v_add_u32_e32 v147, 8, v140
	v_and_b32_e32 v146, 15, v147
	v_xor_b32_e32 v146, 8, v146
	v_bfe_u32 v148, v147, 4, 4
	v_mul_lo_u32 v146, v146, s92
	v_mul_lo_u32 v148, v148, s92
	v_mov_b32_e32 v147, v146
	v_mov_b32_e32 v149, v148
	ds_write2st64_b64 v77, v[146:147], v[148:149] offset1:2
	v_add_u32_e32 v138, 0x800, v74
	ds_read_u8 v139, v138
	v_add_u32_e32 v141, 0x800, v73
	ds_read_u8 v140, v141
	s_add_i32 s43, s67, 96
	v_mov_b32_e32 v138, s43
	ds_read2st64_b32 v[228:229], v138 offset1:1
	ds_read_b128 v[18:21], v227 offset:4096
	ds_read_b128 v[22:25], v227 offset:4112
	v_add_u32_e32 v152, 0x600000, v63
	v_add_u32_e32 v153, 0x600000, v64
	v_mov_b32_e32 v38, 0
	v_mov_b32_e32 v39, 0
	v_mov_b32_e32 v40, 0
	v_mov_b32_e32 v41, 0
	v_mov_b32_e32 v42, 0
	v_mov_b32_e32 v43, 0
	v_mov_b32_e32 v44, 0
	v_mov_b32_e32 v45, 0
	v_and_b32_e32 v78, 0xffff, v31
	v_lshrrev_b32_e32 v79, 16, v31
	v_lshl_add_u32 v78, v78, 7, v150
	v_lshl_add_u32 v79, v79, 7, v151
	s_mov_b32 m0, s77
	s_add_i32 s43, s77, 0x400
	global_load_lds_dwordx4 v78, s[50:51]
	s_mov_b32 m0, s43
	s_nop 0
	global_load_lds_dwordx4 v79, s[50:51]
	s_waitcnt vmcnt(10)
; #define TR4(p_) __builtin_amdgcn_ds_read_tr4_b64_v2i32((LAS v2i*)(p_))
; #define VDMA(st_, k_) do { _Pragma("unroll") for (int i_ = 0; i_ < 4; ++i_) { \
;         const unsigned off_ = (unsigned)((st_) >> 2) * (16384u * 128u) + (PE_ID(E, 4 * ((st_) & 3) + i_) << 7) + ((i_ & 1) ? cx1 : cx0); \
;         __builtin_amdgcn_global_load_lds((const unsigned*)(V4 + off_), (LAS unsigned*)(ldsb + BUF[k_] + 1024 * i_), 16, 0, 0); } } while (0)
; __device__ __forceinline__ void peer_v_tokens(int j, const LAS unsigned short* EL, const LAS unsigned char* AL  , const LAS float* ASC  , const LAS int* SAL  , ...
;     ...
;             if (st < 14) VDMA(st + 2, (st + 2) % 3);
;             if (st < 14) asm volatile("s_waitcnt vmcnt(8)" ::: "memory");
;             else if (st == 14) asm volatile("s_waitcnt vmcnt(4)" ::: "memory");
;             else asm volatile("s_waitcnt vmcnt(0)" ::: "memory");
;             if (q == 0) {
; #pragma unroll
;                 for (int r = 0; r < 4; ++r) { accH[r] = 0; accL[r] = 0; } }
; #pragma unroll
;             for (int tp = 0; tp < 2; ++tp) {
;                 const v2i ao = TR4(ATL + (2 * q + tp) * 128 + 8 * s16), ah = TR4(ATL + 1024 + (2 * q + tp) * 128 + 8 * s16);
; #pragma unroll
;                 for (int r = 0; r < 4; ++r) {
;                     const v2i d = TR4(ldsb + BUF[st % 3] + 2048 * tp + roff[r]);
;                     accH[r] = __builtin_amdgcn_sdot8(d.x, ah.x, accH[r], false); accH[r] = __builtin_amdgcn_sdot8(d.y, ah.y, accH[r], false);
;                     accL[r] = __builtin_amdgcn_sdot8(d.x, ao.x, accL[r], false); accL[r] = __builtin_amdgcn_sdot8(d.y, ao.y, accL[r], false);
;                 }
	v_add_u32_e32 v54, s79, v59
	v_add_u32_e32 v55, s79, v60
	v_add_u32_e32 v56, s79, v61
	v_add_u32_e32 v57, s79, v62
	ds_read_b64_tr_b4 v[50:51], v160 offset:128
	ds_read_b64_tr_b4 v[52:53], v160 offset:1152
	ds_read_b64_tr_b4 v[130:131], v54
	ds_read_b64_tr_b4 v[132:133], v55
	ds_read_b64_tr_b4 v[134:135], v56
	ds_read_b64_tr_b4 v[136:137], v57
	s_waitcnt lgkmcnt(14)
	v_dot8c_i32_i4_e32 v38, v122, v48
	v_dot8c_i32_i4_e32 v39, v122, v46
	v_dot8c_i32_i4_e32 v40, v124, v48
	v_dot8c_i32_i4_e32 v41, v124, v46
	v_dot8c_i32_i4_e32 v42, v126, v48
	v_dot8c_i32_i4_e32 v43, v126, v46
	v_dot8c_i32_i4_e32 v44, v128, v48
	v_dot8c_i32_i4_e32 v45, v128, v46
	v_dot8c_i32_i4_e32 v38, v123, v49
	v_dot8c_i32_i4_e32 v39, v123, v47
	v_dot8c_i32_i4_e32 v40, v125, v49
	v_dot8c_i32_i4_e32 v41, v125, v47
	v_dot8c_i32_i4_e32 v42, v127, v49
	v_dot8c_i32_i4_e32 v43, v127, v47
	v_dot8c_i32_i4_e32 v44, v129, v49
	v_dot8c_i32_i4_e32 v45, v129, v47
	v_and_b32_e32 v78, 0xffff, v32
	v_lshrrev_b32_e32 v79, 16, v32
	v_lshl_add_u32 v78, v78, 7, v150
	v_lshl_add_u32 v79, v79, 7, v151
	s_mov_b32 m0, s78
	s_add_i32 s43, s78, 0x400
	global_load_lds_dwordx4 v78, s[50:51]
	s_mov_b32 m0, s43
	s_nop 0
	global_load_lds_dwordx4 v79, s[50:51]
	s_waitcnt vmcnt(10)
	v_add_u32_e32 v54, s98, v59
	v_add_u32_e32 v55, s98, v60
	v_add_u32_e32 v56, s98, v61
	v_add_u32_e32 v57, s98, v62
	ds_read_b64_tr_b4 v[46:47], v160 offset:256
	ds_read_b64_tr_b4 v[48:49], v160 offset:1280
	ds_read_b64_tr_b4 v[122:123], v54
	ds_read_b64_tr_b4 v[124:125], v55
	ds_read_b64_tr_b4 v[126:127], v56
	ds_read_b64_tr_b4 v[128:129], v57
	s_waitcnt lgkmcnt(6)
	v_dot8c_i32_i4_e32 v38, v130, v52
	v_dot8c_i32_i4_e32 v39, v130, v50
	v_dot8c_i32_i4_e32 v40, v132, v52
	v_dot8c_i32_i4_e32 v41, v132, v50
	v_dot8c_i32_i4_e32 v42, v134, v52
	v_dot8c_i32_i4_e32 v43, v134, v50
	v_dot8c_i32_i4_e32 v44, v136, v52
	v_dot8c_i32_i4_e32 v45, v136, v50
	v_dot8c_i32_i4_e32 v38, v131, v53
	v_dot8c_i32_i4_e32 v39, v131, v51
	v_dot8c_i32_i4_e32 v40, v133, v53
	v_dot8c_i32_i4_e32 v41, v133, v51
	v_dot8c_i32_i4_e32 v42, v135, v53
	v_dot8c_i32_i4_e32 v43, v135, v51
	v_dot8c_i32_i4_e32 v44, v137, v53
	v_dot8c_i32_i4_e32 v45, v137, v51
	v_and_b32_e32 v78, 0xffff, v33
	v_lshrrev_b32_e32 v79, 16, v33
	v_lshl_add_u32 v78, v78, 7, v150
	v_lshl_add_u32 v79, v79, 7, v151
	s_mov_b32 m0, s79
	s_add_i32 s43, s79, 0x400
	global_load_lds_dwordx4 v78, s[50:51]
	s_mov_b32 m0, s43
	s_nop 0
	global_load_lds_dwordx4 v79, s[50:51]
	s_waitcnt vmcnt(10)
	v_add_u32_e32 v54, s99, v59
	v_add_u32_e32 v55, s99, v60
	v_add_u32_e32 v56, s99, v61
	v_add_u32_e32 v57, s99, v62
	ds_read_b64_tr_b4 v[50:51], v160 offset:384
	ds_read_b64_tr_b4 v[52:53], v160 offset:1408
	ds_read_b64_tr_b4 v[130:131], v54
	ds_read_b64_tr_b4 v[132:133], v55
	ds_read_b64_tr_b4 v[134:135], v56
	ds_read_b64_tr_b4 v[136:137], v57
	s_waitcnt lgkmcnt(6)
	v_dot8c_i32_i4_e32 v38, v122, v48
	v_dot8c_i32_i4_e32 v39, v122, v46
	v_dot8c_i32_i4_e32 v40, v124, v48
	v_dot8c_i32_i4_e32 v41, v124, v46
	v_dot8c_i32_i4_e32 v42, v126, v48
	v_dot8c_i32_i4_e32 v43, v126, v46
	v_dot8c_i32_i4_e32 v44, v128, v48
	v_dot8c_i32_i4_e32 v45, v128, v46
	v_dot8c_i32_i4_e32 v38, v123, v49
	v_dot8c_i32_i4_e32 v39, v123, v47
	v_dot8c_i32_i4_e32 v40, v125, v49
	v_dot8c_i32_i4_e32 v41, v125, v47
	v_dot8c_i32_i4_e32 v42, v127, v49
	v_dot8c_i32_i4_e32 v43, v127, v47
	v_dot8c_i32_i4_e32 v44, v129, v49
	v_dot8c_i32_i4_e32 v45, v129, v47
	s_waitcnt lgkmcnt(15)
	v_and_b32_e32 v78, 0xffff, v18
	v_lshrrev_b32_e32 v79, 16, v18
	v_lshl_add_u32 v78, v78, 7, v152
	v_lshl_add_u32 v79, v79, 7, v153
	s_mov_b32 m0, s98
	s_add_i32 s43, s98, 0x400
	global_load_lds_dwordx4 v78, s[50:51]
	s_mov_b32 m0, s43
	s_nop 0
	global_load_lds_dwordx4 v79, s[50:51]
	s_waitcnt vmcnt(10)
	v_add_u32_e32 v54, s76, v59
	v_add_u32_e32 v55, s76, v60
	v_add_u32_e32 v56, s76, v61
	v_add_u32_e32 v57, s76, v62
	ds_read_b64_tr_b4 v[46:47], v160 offset:512
	ds_read_b64_tr_b4 v[48:49], v160 offset:1536
	ds_read_b64_tr_b4 v[122:123], v54
	ds_read_b64_tr_b4 v[124:125], v55
	ds_read_b64_tr_b4 v[126:127], v56
	ds_read_b64_tr_b4 v[128:129], v57
	s_waitcnt lgkmcnt(6)
	v_dot8c_i32_i4_e32 v38, v130, v52
	v_dot8c_i32_i4_e32 v39, v130, v50
	v_dot8c_i32_i4_e32 v40, v132, v52
	v_dot8c_i32_i4_e32 v41, v132, v50
	v_dot8c_i32_i4_e32 v42, v134, v52
	v_dot8c_i32_i4_e32 v43, v134, v50
	v_dot8c_i32_i4_e32 v44, v136, v52
	v_dot8c_i32_i4_e32 v45, v136, v50
	v_dot8c_i32_i4_e32 v38, v131, v53
	v_dot8c_i32_i4_e32 v39, v131, v51
	v_dot8c_i32_i4_e32 v40, v133, v53
	v_dot8c_i32_i4_e32 v41, v133, v51
	v_dot8c_i32_i4_e32 v42, v135, v53
	v_dot8c_i32_i4_e32 v43, v135, v51
	v_dot8c_i32_i4_e32 v44, v137, v53
	v_dot8c_i32_i4_e32 v45, v137, v51
	v_and_b32_e32 v78, 0xffff, v19
	v_lshrrev_b32_e32 v79, 16, v19
	v_lshl_add_u32 v78, v78, 7, v152
	v_lshl_add_u32 v79, v79, 7, v153
	s_mov_b32 m0, s99
	s_add_i32 s43, s99, 0x400
	global_load_lds_dwordx4 v78, s[50:51]
	s_mov_b32 m0, s43
	s_nop 0
	global_load_lds_dwordx4 v79, s[50:51]
	s_waitcnt vmcnt(8)
	v_add_u32_e32 v54, s77, v59
	v_add_u32_e32 v55, s77, v60
	v_add_u32_e32 v56, s77, v61
	v_add_u32_e32 v57, s77, v62
	ds_read_b64_tr_b4 v[50:51], v160 offset:640
	ds_read_b64_tr_b4 v[52:53], v160 offset:1664
	ds_read_b64_tr_b4 v[130:131], v54
	ds_read_b64_tr_b4 v[132:133], v55
	ds_read_b64_tr_b4 v[134:135], v56
	ds_read_b64_tr_b4 v[136:137], v57
	s_waitcnt lgkmcnt(6)
	v_dot8c_i32_i4_e32 v38, v122, v48
	v_dot8c_i32_i4_e32 v39, v122, v46
	v_dot8c_i32_i4_e32 v40, v124, v48
	v_dot8c_i32_i4_e32 v41, v124, v46
	v_dot8c_i32_i4_e32 v42, v126, v48
	v_dot8c_i32_i4_e32 v43, v126, v46
	v_dot8c_i32_i4_e32 v44, v128, v48
	v_dot8c_i32_i4_e32 v45, v128, v46
	v_dot8c_i32_i4_e32 v38, v123, v49
	v_dot8c_i32_i4_e32 v39, v123, v47
	v_dot8c_i32_i4_e32 v40, v125, v49
	v_dot8c_i32_i4_e32 v41, v125, v47
	v_dot8c_i32_i4_e32 v42, v127, v49
	v_dot8c_i32_i4_e32 v43, v127, v47
	v_dot8c_i32_i4_e32 v44, v129, v49
	v_dot8c_i32_i4_e32 v45, v129, v47
	s_waitcnt lgkmcnt(15)
; #define LAS __attribute__((address_space(3)))
; __device__ __forceinline__ void peer_v_tokens(int j, const LAS unsigned short* EL, const LAS unsigned char* AL  , const LAS float* ASC  , const LAS int* SAL  , ...
;     ...
;         { const LAS v4u* ep = (const LAS v4u*)(EL + tl * 128 + 16 * g); const v4u e0 = ep[0], e1 = ep[1];
;           E[0] = e0.x; E[1] = e0.y; E[2] = e0.z; E[3] = e0.w; E[4] = e1.x; E[5] = e1.y; E[6] = e1.z; E[7] = e1.w; }
;         uint2 hv[4]; float4 gv[4];
;         { unsigned ho = (unsigned)t * (D / 4) + (unsigned)lane; asm volatile("" : "+v"(ho)); const uint2* hp = (const uint2*)HB + ho; const float4* gp = (const float4*)fng + lane;
; #pragma unroll
;           for (int jq = 0; jq < 4; ++jq) { hv[jq] = hp[64 * jq]; gv[jq] = gp[64 * jq]; } }
;         VDMA(0, 0); VDMA(1, 1);
; #pragma unroll
;         for (int m = 0; m < 2; ++m) {
;             const int idx = lane + 64 * m, tau = idx >> 4, sr = idx & 15, k = 16 * (sr & 7) + 2 * tau + (sr >> 3);
;     ...
;         for (int st = 0; st < 16; ++st) {
;             const int p = st >> 2, q = st & 3;
;             if (st < 14) VDMA(st + 2, (st + 2) % 3);
;             if (st < 14) asm volatile("s_waitcnt vmcnt(8)" ::: "memory");
;             else if (st == 14) asm volatile("s_waitcnt vmcnt(4)" ::: "memory");
;             else asm volatile("s_waitcnt vmcnt(0)" ::: "memory");
;             if (q == 0) {
; #pragma unroll
;                 for (int r = 0; r < 4; ++r) { accH[r] = 0; accL[r] = 0; } }
; #pragma unroll
;             for (int tp = 0; tp < 2; ++tp) {
;                 const v2i ao = TR4(ATL + (2 * q + tp) * 128 + 8 * s16), ah = TR4(ATL + 1024 + (2 * q + tp) * 128 + 8 * s16);
; #pragma unroll
;                 for (int r = 0; r < 4; ++r) {
;                     const v2i d = TR4(ldsb + BUF[st % 3] + 2048 * tp + roff[r]);
;                     accH[r] = __builtin_amdgcn_sdot8(d.x, ah.x, accH[r], false); accH[r] = __builtin_amdgcn_sdot8(d.y, ah.y, accH[r], false);
;                     accL[r] = __builtin_amdgcn_sdot8(d.x, ao.x, accL[r], false); accL[r] = __builtin_amdgcn_sdot8(d.y, ao.y, accL[r], false);
;                 }
;             }
;             asm volatile("s_waitcnt lgkmcnt(0)" ::: "memory");
;             if (q == 3) {
; #pragma unroll
;                 for (int r = 0; r < 4; ++r) STASH[256 * p + 16 * (grp + 4 * r) + pc] = f2bf(asc * (float)(2 * ((accH[r] << 4) + accL[r]) + sa));
	v_add_u32_e32 v143, 8, v139
	v_and_b32_e32 v142, 15, v143
	v_xor_b32_e32 v142, 8, v142
	v_bfe_u32 v144, v143, 4, 4
	v_mul_lo_u32 v142, v142, s92
	v_mul_lo_u32 v144, v144, s92
	v_mov_b32_e32 v143, v142
	v_mov_b32_e32 v145, v144
	ds_write2st64_b64 v159, v[142:143], v[144:145] offset1:2
	v_and_b32_e32 v78, 0xffff, v20
	v_lshrrev_b32_e32 v79, 16, v20
	v_lshl_add_u32 v78, v78, 7, v152
	v_lshl_add_u32 v79, v79, 7, v153
	s_mov_b32 m0, s76
	s_add_i32 s43, s76, 0x400
	global_load_lds_dwordx4 v78, s[50:51]
	s_mov_b32 m0, s43
	s_nop 0
	global_load_lds_dwordx4 v79, s[50:51]
	s_waitcnt vmcnt(8)
	v_add_u32_e32 v54, s78, v59
	v_add_u32_e32 v55, s78, v60
	v_add_u32_e32 v56, s78, v61
	v_add_u32_e32 v57, s78, v62
	ds_read_b64_tr_b4 v[46:47], v160 offset:768
	ds_read_b64_tr_b4 v[48:49], v160 offset:1792
	ds_read_b64_tr_b4 v[122:123], v54
	ds_read_b64_tr_b4 v[124:125], v55
	ds_read_b64_tr_b4 v[126:127], v56
	ds_read_b64_tr_b4 v[128:129], v57
	s_waitcnt lgkmcnt(7)
	v_dot8c_i32_i4_e32 v38, v130, v52
	v_dot8c_i32_i4_e32 v39, v130, v50
	v_dot8c_i32_i4_e32 v40, v132, v52
	v_dot8c_i32_i4_e32 v41, v132, v50
	v_dot8c_i32_i4_e32 v42, v134, v52
	v_dot8c_i32_i4_e32 v43, v134, v50
	v_dot8c_i32_i4_e32 v44, v136, v52
	v_dot8c_i32_i4_e32 v45, v136, v50
	v_dot8c_i32_i4_e32 v38, v131, v53
	v_dot8c_i32_i4_e32 v39, v131, v51
	v_dot8c_i32_i4_e32 v40, v133, v53
	v_dot8c_i32_i4_e32 v41, v133, v51
	v_dot8c_i32_i4_e32 v42, v135, v53
	v_dot8c_i32_i4_e32 v43, v135, v51
	v_dot8c_i32_i4_e32 v44, v137, v53
	v_dot8c_i32_i4_e32 v45, v137, v51
	v_and_b32_e32 v78, 0xffff, v21
	v_lshrrev_b32_e32 v79, 16, v21
	v_lshl_add_u32 v78, v78, 7, v152
	v_lshl_add_u32 v79, v79, 7, v153
	s_mov_b32 m0, s77
	s_add_i32 s43, s77, 0x400
	global_load_lds_dwordx4 v78, s[50:51]
	s_mov_b32 m0, s43
	s_nop 0
	global_load_lds_dwordx4 v79, s[50:51]
	s_waitcnt vmcnt(8)
	v_add_u32_e32 v54, s79, v59
	v_add_u32_e32 v55, s79, v60
	v_add_u32_e32 v56, s79, v61
	v_add_u32_e32 v57, s79, v62
	ds_read_b64_tr_b4 v[50:51], v160 offset:896
	ds_read_b64_tr_b4 v[52:53], v160 offset:1920
	ds_read_b64_tr_b4 v[130:131], v54
	ds_read_b64_tr_b4 v[132:133], v55
	ds_read_b64_tr_b4 v[134:135], v56
	ds_read_b64_tr_b4 v[136:137], v57
	s_waitcnt lgkmcnt(6)
	v_dot8c_i32_i4_e32 v38, v122, v48
	v_dot8c_i32_i4_e32 v39, v122, v46
	v_dot8c_i32_i4_e32 v40, v124, v48
	v_dot8c_i32_i4_e32 v41, v124, v46
	v_dot8c_i32_i4_e32 v42, v126, v48
	v_dot8c_i32_i4_e32 v43, v126, v46
	v_dot8c_i32_i4_e32 v44, v128, v48
	v_dot8c_i32_i4_e32 v45, v128, v46
	v_dot8c_i32_i4_e32 v38, v123, v49
	v_dot8c_i32_i4_e32 v39, v123, v47
	v_dot8c_i32_i4_e32 v40, v125, v49
	v_dot8c_i32_i4_e32 v41, v125, v47
	v_dot8c_i32_i4_e32 v42, v127, v49
	v_dot8c_i32_i4_e32 v43, v127, v47
	v_dot8c_i32_i4_e32 v44, v129, v49
	v_dot8c_i32_i4_e32 v45, v129, v47
	v_and_b32_e32 v78, 0xffff, v22
	v_lshrrev_b32_e32 v79, 16, v22
	v_lshl_add_u32 v78, v78, 7, v152
	v_lshl_add_u32 v79, v79, 7, v153
	s_mov_b32 m0, s78
	s_add_i32 s43, s78, 0x400
	global_load_lds_dwordx4 v78, s[50:51]
	s_mov_b32 m0, s43
	s_nop 0
	global_load_lds_dwordx4 v79, s[50:51]
	s_waitcnt vmcnt(8)
	v_add_u32_e32 v54, s98, v59
	v_add_u32_e32 v55, s98, v60
	v_add_u32_e32 v56, s98, v61
	v_add_u32_e32 v57, s98, v62
	ds_read_b64_tr_b4 v[46:47], v160
	ds_read_b64_tr_b4 v[48:49], v160 offset:1024
	ds_read_b64_tr_b4 v[122:123], v54
	ds_read_b64_tr_b4 v[124:125], v55
	ds_read_b64_tr_b4 v[126:127], v56
	ds_read_b64_tr_b4 v[128:129], v57
	s_waitcnt lgkmcnt(6)
	v_dot8c_i32_i4_e32 v38, v130, v52
	v_dot8c_i32_i4_e32 v39, v130, v50
	v_dot8c_i32_i4_e32 v40, v132, v52
	v_dot8c_i32_i4_e32 v41, v132, v50
	v_dot8c_i32_i4_e32 v42, v134, v52
	v_dot8c_i32_i4_e32 v43, v134, v50
	v_dot8c_i32_i4_e32 v44, v136, v52
	v_dot8c_i32_i4_e32 v45, v136, v50
	v_dot8c_i32_i4_e32 v38, v131, v53
	v_dot8c_i32_i4_e32 v39, v131, v51
	v_dot8c_i32_i4_e32 v40, v133, v53
	v_dot8c_i32_i4_e32 v41, v133, v51
	v_dot8c_i32_i4_e32 v42, v135, v53
	v_dot8c_i32_i4_e32 v43, v135, v51
	v_dot8c_i32_i4_e32 v44, v137, v53
	v_dot8c_i32_i4_e32 v45, v137, v51
	s_nop 3
	s_waitcnt lgkmcnt(15)
	v_lshlrev_b32_e32 v38, 5, v38
	v_lshlrev_b32_e32 v39, 1, v39
	v_add3_u32 v38, v39, v229, v38
	v_cvt_f32_i32_e32 v38, v38
	v_mul_f32_e32 v38, v228, v38
	v_lshlrev_b32_e32 v40, 5, v40
	v_lshlrev_b32_e32 v41, 1, v41
	v_add3_u32 v40, v41, v229, v40
	v_cvt_f32_i32_e32 v40, v40
	v_mul_f32_e32 v40, v228, v40
	v_lshlrev_b32_e32 v42, 5, v42
	v_lshlrev_b32_e32 v43, 1, v43
	v_add3_u32 v42, v43, v229, v42
	v_cvt_f32_i32_e32 v42, v42
	v_mul_f32_e32 v42, v228, v42
	v_lshlrev_b32_e32 v44, 5, v44
	v_lshlrev_b32_e32 v45, 1, v45
	v_add3_u32 v44, v45, v229, v44
	v_cvt_f32_i32_e32 v44, v44
	v_mul_f32_e32 v44, v228, v44
	v_cvt_pk_bf16_f32 v190, v38, v40
	v_cvt_pk_bf16_f32 v191, v42, v44
	ds_read_b128 v[252:255], v155 offset:1024
	s_add_i32 s44, s40, 8
	s_ashr_i32 s45, s44, 31
	s_lshl_b64 s[44:45], s[44:45], 12
	v_lshl_add_u64 v[80:81], v[36:37], 0, s[44:45]
	s_waitcnt lgkmcnt(0)
	v_mul_f32_e32 v240, v240, v252
	v_mul_f32_e32 v241, v241, v253
	v_mul_f32_e32 v242, v242, v254
	v_mul_f32_e32 v243, v243, v255
	global_store_dwordx4 v[80:81], v[240:243], off offset:1024 nt
	v_add_u32_e32 v147, 8, v140
	v_and_b32_e32 v146, 15, v147
	v_xor_b32_e32 v146, 8, v146
	v_bfe_u32 v148, v147, 4, 4
	v_mul_lo_u32 v146, v146, s92
	v_mul_lo_u32 v148, v148, s92
	v_mov_b32_e32 v147, v146
	v_mov_b32_e32 v149, v148
	ds_write2st64_b64 v77, v[146:147], v[148:149] offset1:2
	v_add_u32_e32 v138, 0xc00, v74
	ds_read_u8 v139, v138
	v_add_u32_e32 v141, 0xc00, v73
	ds_read_u8 v140, v141
	s_add_i32 s43, s67, 64
	v_mov_b32_e32 v138, s43
	ds_read2st64_b32 v[228:229], v138 offset1:1
	ds_read_b128 v[26:29], v227 offset:6144
	ds_read_b128 v[30:33], v227 offset:6160
	v_mov_b32_e32 v38, 0
	v_mov_b32_e32 v39, 0
	v_mov_b32_e32 v40, 0
	v_mov_b32_e32 v41, 0
	v_mov_b32_e32 v42, 0
	v_mov_b32_e32 v43, 0
	v_mov_b32_e32 v44, 0
	v_mov_b32_e32 v45, 0
	v_and_b32_e32 v78, 0xffff, v23
	v_lshrrev_b32_e32 v79, 16, v23
	v_lshl_add_u32 v78, v78, 7, v152
	v_lshl_add_u32 v79, v79, 7, v153
	s_mov_b32 m0, s79
	s_add_i32 s43, s79, 0x400
	global_load_lds_dwordx4 v78, s[50:51]
	s_mov_b32 m0, s43
	s_nop 0
	global_load_lds_dwordx4 v79, s[50:51]
	s_waitcnt vmcnt(9)
; #define TR4(p_) __builtin_amdgcn_ds_read_tr4_b64_v2i32((LAS v2i*)(p_))
; #define VDMA(st_, k_) do { _Pragma("unroll") for (int i_ = 0; i_ < 4; ++i_) { \
;         const unsigned off_ = (unsigned)((st_) >> 2) * (16384u * 128u) + (PE_ID(E, 4 * ((st_) & 3) + i_) << 7) + ((i_ & 1) ? cx1 : cx0); \
;         __builtin_amdgcn_global_load_lds((const unsigned*)(V4 + off_), (LAS unsigned*)(ldsb + BUF[k_] + 1024 * i_), 16, 0, 0); } } while (0)
; __device__ __forceinline__ void peer_v_tokens(int j, const LAS unsigned short* EL, const LAS unsigned char* AL  , const LAS float* ASC  , const LAS int* SAL  , ...
;     ...
;             if (st < 14) VDMA(st + 2, (st + 2) % 3);
;             if (st < 14) asm volatile("s_waitcnt vmcnt(8)" ::: "memory");
;             else if (st == 14) asm volatile("s_waitcnt vmcnt(4)" ::: "memory");
;             else asm volatile("s_waitcnt vmcnt(0)" ::: "memory");
;             if (q == 0) {
; #pragma unroll
;                 for (int r = 0; r < 4; ++r) { accH[r] = 0; accL[r] = 0; } }
; #pragma unroll
;             for (int tp = 0; tp < 2; ++tp) {
;                 const v2i ao = TR4(ATL + (2 * q + tp) * 128 + 8 * s16), ah = TR4(ATL + 1024 + (2 * q + tp) * 128 + 8 * s16);
; #pragma unroll
;                 for (int r = 0; r < 4; ++r) {
;                     const v2i d = TR4(ldsb + BUF[st % 3] + 2048 * tp + roff[r]);
;                     accH[r] = __builtin_amdgcn_sdot8(d.x, ah.x, accH[r], false); accH[r] = __builtin_amdgcn_sdot8(d.y, ah.y, accH[r], false);
;                     accL[r] = __builtin_amdgcn_sdot8(d.x, ao.x, accL[r], false); accL[r] = __builtin_amdgcn_sdot8(d.y, ao.y, accL[r], false);
;                 }
	v_add_u32_e32 v54, s99, v59
	v_add_u32_e32 v55, s99, v60
	v_add_u32_e32 v56, s99, v61
	v_add_u32_e32 v57, s99, v62
	ds_read_b64_tr_b4 v[50:51], v160 offset:128
	ds_read_b64_tr_b4 v[52:53], v160 offset:1152
	ds_read_b64_tr_b4 v[130:131], v54
	ds_read_b64_tr_b4 v[132:133], v55
	ds_read_b64_tr_b4 v[134:135], v56
	ds_read_b64_tr_b4 v[136:137], v57
	s_waitcnt lgkmcnt(13)
	v_dot8c_i32_i4_e32 v38, v122, v48
	v_dot8c_i32_i4_e32 v39, v122, v46
	v_dot8c_i32_i4_e32 v40, v124, v48
	v_dot8c_i32_i4_e32 v41, v124, v46
	v_dot8c_i32_i4_e32 v42, v126, v48
	v_dot8c_i32_i4_e32 v43, v126, v46
	v_dot8c_i32_i4_e32 v44, v128, v48
	v_dot8c_i32_i4_e32 v45, v128, v46
	v_dot8c_i32_i4_e32 v38, v123, v49
	v_dot8c_i32_i4_e32 v39, v123, v47
	v_dot8c_i32_i4_e32 v40, v125, v49
	v_dot8c_i32_i4_e32 v41, v125, v47
	v_dot8c_i32_i4_e32 v42, v127, v49
	v_dot8c_i32_i4_e32 v43, v127, v47
	v_dot8c_i32_i4_e32 v44, v129, v49
	v_dot8c_i32_i4_e32 v45, v129, v47
	v_and_b32_e32 v78, 0xffff, v24
	v_lshrrev_b32_e32 v79, 16, v24
	v_lshl_add_u32 v78, v78, 7, v152
	v_lshl_add_u32 v79, v79, 7, v153
	s_mov_b32 m0, s98
	s_add_i32 s43, s98, 0x400
	global_load_lds_dwordx4 v78, s[50:51]
	s_mov_b32 m0, s43
	s_nop 0
	global_load_lds_dwordx4 v79, s[50:51]
	s_waitcnt vmcnt(9)
	v_add_u32_e32 v54, s76, v59
	v_add_u32_e32 v55, s76, v60
	v_add_u32_e32 v56, s76, v61
	v_add_u32_e32 v57, s76, v62
	ds_read_b64_tr_b4 v[46:47], v160 offset:256
	ds_read_b64_tr_b4 v[48:49], v160 offset:1280
	ds_read_b64_tr_b4 v[122:123], v54
	ds_read_b64_tr_b4 v[124:125], v55
	ds_read_b64_tr_b4 v[126:127], v56
	ds_read_b64_tr_b4 v[128:129], v57
	s_waitcnt lgkmcnt(6)
	v_dot8c_i32_i4_e32 v38, v130, v52
	v_dot8c_i32_i4_e32 v39, v130, v50
	v_dot8c_i32_i4_e32 v40, v132, v52
	v_dot8c_i32_i4_e32 v41, v132, v50
	v_dot8c_i32_i4_e32 v42, v134, v52
	v_dot8c_i32_i4_e32 v43, v134, v50
	v_dot8c_i32_i4_e32 v44, v136, v52
	v_dot8c_i32_i4_e32 v45, v136, v50
	v_dot8c_i32_i4_e32 v38, v131, v53
	v_dot8c_i32_i4_e32 v39, v131, v51
	v_dot8c_i32_i4_e32 v40, v133, v53
	v_dot8c_i32_i4_e32 v41, v133, v51
	v_dot8c_i32_i4_e32 v42, v135, v53
	v_dot8c_i32_i4_e32 v43, v135, v51
	v_dot8c_i32_i4_e32 v44, v137, v53
	v_dot8c_i32_i4_e32 v45, v137, v51
	v_and_b32_e32 v78, 0xffff, v25
	v_lshrrev_b32_e32 v79, 16, v25
	v_lshl_add_u32 v78, v78, 7, v152
	v_lshl_add_u32 v79, v79, 7, v153
	s_mov_b32 m0, s99
	s_add_i32 s43, s99, 0x400
	global_load_lds_dwordx4 v78, s[50:51]
	s_mov_b32 m0, s43
	s_nop 0
	global_load_lds_dwordx4 v79, s[50:51]
	s_waitcnt vmcnt(9)
	v_add_u32_e32 v54, s77, v59
	v_add_u32_e32 v55, s77, v60
	v_add_u32_e32 v56, s77, v61
	v_add_u32_e32 v57, s77, v62
	ds_read_b64_tr_b4 v[50:51], v160 offset:384
	ds_read_b64_tr_b4 v[52:53], v160 offset:1408
	ds_read_b64_tr_b4 v[130:131], v54
	ds_read_b64_tr_b4 v[132:133], v55
	ds_read_b64_tr_b4 v[134:135], v56
	ds_read_b64_tr_b4 v[136:137], v57
	s_waitcnt lgkmcnt(6)
	v_dot8c_i32_i4_e32 v38, v122, v48
	v_dot8c_i32_i4_e32 v39, v122, v46
	v_dot8c_i32_i4_e32 v40, v124, v48
	v_dot8c_i32_i4_e32 v41, v124, v46
	v_dot8c_i32_i4_e32 v42, v126, v48
	v_dot8c_i32_i4_e32 v43, v126, v46
	v_dot8c_i32_i4_e32 v44, v128, v48
	v_dot8c_i32_i4_e32 v45, v128, v46
	v_dot8c_i32_i4_e32 v38, v123, v49
	v_dot8c_i32_i4_e32 v39, v123, v47
	v_dot8c_i32_i4_e32 v40, v125, v49
	v_dot8c_i32_i4_e32 v41, v125, v47
	v_dot8c_i32_i4_e32 v42, v127, v49
	v_dot8c_i32_i4_e32 v43, v127, v47
	v_dot8c_i32_i4_e32 v44, v129, v49
	v_dot8c_i32_i4_e32 v45, v129, v47
	s_waitcnt lgkmcnt(15)
	v_and_b32_e32 v78, 0xffff, v26
	v_lshrrev_b32_e32 v79, 16, v26
	v_lshl_add_u32 v78, v78, 7, v152
	v_lshl_add_u32 v79, v79, 7, v153
	s_mov_b32 m0, s76
	s_add_i32 s43, s76, 0x400
	global_load_lds_dwordx4 v78, s[50:51]
	s_mov_b32 m0, s43
	s_nop 0
	global_load_lds_dwordx4 v79, s[50:51]
	s_waitcnt vmcnt(9)
	v_add_u32_e32 v54, s78, v59
	v_add_u32_e32 v55, s78, v60
	v_add_u32_e32 v56, s78, v61
	v_add_u32_e32 v57, s78, v62
	ds_read_b64_tr_b4 v[46:47], v160 offset:512
	ds_read_b64_tr_b4 v[48:49], v160 offset:1536
	ds_read_b64_tr_b4 v[122:123], v54
	ds_read_b64_tr_b4 v[124:125], v55
	ds_read_b64_tr_b4 v[126:127], v56
	ds_read_b64_tr_b4 v[128:129], v57
	s_waitcnt lgkmcnt(6)
	v_dot8c_i32_i4_e32 v38, v130, v52
	v_dot8c_i32_i4_e32 v39, v130, v50
	v_dot8c_i32_i4_e32 v40, v132, v52
	v_dot8c_i32_i4_e32 v41, v132, v50
	v_dot8c_i32_i4_e32 v42, v134, v52
	v_dot8c_i32_i4_e32 v43, v134, v50
	v_dot8c_i32_i4_e32 v44, v136, v52
	v_dot8c_i32_i4_e32 v45, v136, v50
	v_dot8c_i32_i4_e32 v38, v131, v53
	v_dot8c_i32_i4_e32 v39, v131, v51
	v_dot8c_i32_i4_e32 v40, v133, v53
	v_dot8c_i32_i4_e32 v41, v133, v51
	v_dot8c_i32_i4_e32 v42, v135, v53
	v_dot8c_i32_i4_e32 v43, v135, v51
	v_dot8c_i32_i4_e32 v44, v137, v53
	v_dot8c_i32_i4_e32 v45, v137, v51
	v_and_b32_e32 v78, 0xffff, v27
	v_lshrrev_b32_e32 v79, 16, v27
	v_lshl_add_u32 v78, v78, 7, v152
	v_lshl_add_u32 v79, v79, 7, v153
	s_mov_b32 m0, s77
	s_add_i32 s43, s77, 0x400
	global_load_lds_dwordx4 v78, s[50:51]
	s_mov_b32 m0, s43
	s_nop 0
	global_load_lds_dwordx4 v79, s[50:51]
	s_waitcnt vmcnt(8)
	v_add_u32_e32 v54, s79, v59
	v_add_u32_e32 v55, s79, v60
	v_add_u32_e32 v56, s79, v61
	v_add_u32_e32 v57, s79, v62
	ds_read_b64_tr_b4 v[50:51], v160 offset:640
	ds_read_b64_tr_b4 v[52:53], v160 offset:1664
	ds_read_b64_tr_b4 v[130:131], v54
	ds_read_b64_tr_b4 v[132:133], v55
	ds_read_b64_tr_b4 v[134:135], v56
	ds_read_b64_tr_b4 v[136:137], v57
	s_waitcnt lgkmcnt(6)
	v_dot8c_i32_i4_e32 v38, v122, v48
	v_dot8c_i32_i4_e32 v39, v122, v46
	v_dot8c_i32_i4_e32 v40, v124, v48
	v_dot8c_i32_i4_e32 v41, v124, v46
	v_dot8c_i32_i4_e32 v42, v126, v48
	v_dot8c_i32_i4_e32 v43, v126, v46
	v_dot8c_i32_i4_e32 v44, v128, v48
	v_dot8c_i32_i4_e32 v45, v128, v46
	v_dot8c_i32_i4_e32 v38, v123, v49
	v_dot8c_i32_i4_e32 v39, v123, v47
	v_dot8c_i32_i4_e32 v40, v125, v49
	v_dot8c_i32_i4_e32 v41, v125, v47
	v_dot8c_i32_i4_e32 v42, v127, v49
	v_dot8c_i32_i4_e32 v43, v127, v47
	v_dot8c_i32_i4_e32 v44, v129, v49
	v_dot8c_i32_i4_e32 v45, v129, v47
	s_waitcnt lgkmcnt(15)
; __device__ __forceinline__ bf16 f2bf(float f) { return (bf16)f2bfu(f); }
; #define TR4(p_) __builtin_amdgcn_ds_read_tr4_b64_v2i32((LAS v2i*)(p_))
; #define VDMA(st_, k_) do { _Pragma("unroll") for (int i_ = 0; i_ < 4; ++i_) { \
;         const unsigned off_ = (unsigned)((st_) >> 2) * (16384u * 128u) + (PE_ID(E, 4 * ((st_) & 3) + i_) << 7) + ((i_ & 1) ? cx1 : cx0); \
;         __builtin_amdgcn_global_load_lds((const unsigned*)(V4 + off_), (LAS unsigned*)(ldsb + BUF[k_] + 1024 * i_), 16, 0, 0); } } while (0)
; __device__ __forceinline__ void peer_v_tokens(int j, const LAS unsigned short* EL, const LAS unsigned char* AL  , const LAS float* ASC  , const LAS int* SAL  , ...
;     ...
;         for (int st = 0; st < 16; ++st) {
;             const int p = st >> 2, q = st & 3;
;             if (st < 14) VDMA(st + 2, (st + 2) % 3);
;             if (st < 14) asm volatile("s_waitcnt vmcnt(8)" ::: "memory");
;             else if (st == 14) asm volatile("s_waitcnt vmcnt(4)" ::: "memory");
;             else asm volatile("s_waitcnt vmcnt(0)" ::: "memory");
;             if (q == 0) {
; #pragma unroll
;                 for (int r = 0; r < 4; ++r) { accH[r] = 0; accL[r] = 0; } }
; #pragma unroll
;             for (int tp = 0; tp < 2; ++tp) {
;                 const v2i ao = TR4(ATL + (2 * q + tp) * 128 + 8 * s16), ah = TR4(ATL + 1024 + (2 * q + tp) * 128 + 8 * s16);
; #pragma unroll
;                 for (int r = 0; r < 4; ++r) {
;                     const v2i d = TR4(ldsb + BUF[st % 3] + 2048 * tp + roff[r]);
;                     accH[r] = __builtin_amdgcn_sdot8(d.x, ah.x, accH[r], false); accH[r] = __builtin_amdgcn_sdot8(d.y, ah.y, accH[r], false);
;                     accL[r] = __builtin_amdgcn_sdot8(d.x, ao.x, accL[r], false); accL[r] = __builtin_amdgcn_sdot8(d.y, ao.y, accL[r], false);
;                 }
;             }
;             asm volatile("s_waitcnt lgkmcnt(0)" ::: "memory");
;             if (q == 3) {
; #pragma unroll
;                 for (int r = 0; r < 4; ++r) STASH[256 * p + 16 * (grp + 4 * r) + pc] = f2bf(asc * (float)(2 * ((accH[r] << 4) + accL[r]) + sa));
	v_add_u32_e32 v143, 8, v139
	v_and_b32_e32 v142, 15, v143
	v_xor_b32_e32 v142, 8, v142
	v_bfe_u32 v144, v143, 4, 4
	v_mul_lo_u32 v142, v142, s92
	v_mul_lo_u32 v144, v144, s92
	v_mov_b32_e32 v143, v142
	v_mov_b32_e32 v145, v144
	ds_write2st64_b64 v159, v[142:143], v[144:145] offset1:2
	v_and_b32_e32 v78, 0xffff, v28
	v_lshrrev_b32_e32 v79, 16, v28
	v_lshl_add_u32 v78, v78, 7, v152
	v_lshl_add_u32 v79, v79, 7, v153
	s_mov_b32 m0, s78
	s_add_i32 s43, s78, 0x400
	global_load_lds_dwordx4 v78, s[50:51]
	s_mov_b32 m0, s43
	s_nop 0
	global_load_lds_dwordx4 v79, s[50:51]
	s_waitcnt vmcnt(8)
	v_add_u32_e32 v54, s98, v59
	v_add_u32_e32 v55, s98, v60
	v_add_u32_e32 v56, s98, v61
	v_add_u32_e32 v57, s98, v62
	ds_read_b64_tr_b4 v[46:47], v160 offset:768
	ds_read_b64_tr_b4 v[48:49], v160 offset:1792
	ds_read_b64_tr_b4 v[122:123], v54
	ds_read_b64_tr_b4 v[124:125], v55
	ds_read_b64_tr_b4 v[126:127], v56
	ds_read_b64_tr_b4 v[128:129], v57
	s_waitcnt lgkmcnt(7)
	v_dot8c_i32_i4_e32 v38, v130, v52
	v_dot8c_i32_i4_e32 v39, v130, v50
	v_dot8c_i32_i4_e32 v40, v132, v52
	v_dot8c_i32_i4_e32 v41, v132, v50
	v_dot8c_i32_i4_e32 v42, v134, v52
	v_dot8c_i32_i4_e32 v43, v134, v50
	v_dot8c_i32_i4_e32 v44, v136, v52
	v_dot8c_i32_i4_e32 v45, v136, v50
	v_dot8c_i32_i4_e32 v38, v131, v53
	v_dot8c_i32_i4_e32 v39, v131, v51
	v_dot8c_i32_i4_e32 v40, v133, v53
	v_dot8c_i32_i4_e32 v41, v133, v51
	v_dot8c_i32_i4_e32 v42, v135, v53
	v_dot8c_i32_i4_e32 v43, v135, v51
	v_dot8c_i32_i4_e32 v44, v137, v53
	v_dot8c_i32_i4_e32 v45, v137, v51
	v_and_b32_e32 v78, 0xffff, v29
	v_lshrrev_b32_e32 v79, 16, v29
	v_lshl_add_u32 v78, v78, 7, v152
	v_lshl_add_u32 v79, v79, 7, v153
	s_mov_b32 m0, s79
	s_add_i32 s43, s79, 0x400
	global_load_lds_dwordx4 v78, s[50:51]
	s_mov_b32 m0, s43
	s_nop 0
	global_load_lds_dwordx4 v79, s[50:51]
	s_waitcnt vmcnt(8)
	v_add_u32_e32 v54, s99, v59
	v_add_u32_e32 v55, s99, v60
	v_add_u32_e32 v56, s99, v61
	v_add_u32_e32 v57, s99, v62
	ds_read_b64_tr_b4 v[50:51], v160 offset:896
	ds_read_b64_tr_b4 v[52:53], v160 offset:1920
	ds_read_b64_tr_b4 v[130:131], v54
	ds_read_b64_tr_b4 v[132:133], v55
	ds_read_b64_tr_b4 v[134:135], v56
	ds_read_b64_tr_b4 v[136:137], v57
	s_waitcnt lgkmcnt(6)
	v_dot8c_i32_i4_e32 v38, v122, v48
	v_dot8c_i32_i4_e32 v39, v122, v46
	v_dot8c_i32_i4_e32 v40, v124, v48
	v_dot8c_i32_i4_e32 v41, v124, v46
	v_dot8c_i32_i4_e32 v42, v126, v48
	v_dot8c_i32_i4_e32 v43, v126, v46
	v_dot8c_i32_i4_e32 v44, v128, v48
	v_dot8c_i32_i4_e32 v45, v128, v46
	v_dot8c_i32_i4_e32 v38, v123, v49
	v_dot8c_i32_i4_e32 v39, v123, v47
	v_dot8c_i32_i4_e32 v40, v125, v49
	v_dot8c_i32_i4_e32 v41, v125, v47
	v_dot8c_i32_i4_e32 v42, v127, v49
	v_dot8c_i32_i4_e32 v43, v127, v47
	v_dot8c_i32_i4_e32 v44, v129, v49
	v_dot8c_i32_i4_e32 v45, v129, v47
	v_and_b32_e32 v78, 0xffff, v30
	v_lshrrev_b32_e32 v79, 16, v30
	v_lshl_add_u32 v78, v78, 7, v152
	v_lshl_add_u32 v79, v79, 7, v153
	s_mov_b32 m0, s98
	s_add_i32 s43, s98, 0x400
	global_load_lds_dwordx4 v78, s[50:51]
	s_mov_b32 m0, s43
	s_nop 0
	global_load_lds_dwordx4 v79, s[50:51]
	s_waitcnt vmcnt(8)
	v_add_u32_e32 v54, s76, v59
	v_add_u32_e32 v55, s76, v60
	v_add_u32_e32 v56, s76, v61
	v_add_u32_e32 v57, s76, v62
	ds_read_b64_tr_b4 v[46:47], v160
	ds_read_b64_tr_b4 v[48:49], v160 offset:1024
	ds_read_b64_tr_b4 v[122:123], v54
	ds_read_b64_tr_b4 v[124:125], v55
	ds_read_b64_tr_b4 v[126:127], v56
	ds_read_b64_tr_b4 v[128:129], v57
	s_waitcnt lgkmcnt(6)
	v_dot8c_i32_i4_e32 v38, v130, v52
	v_dot8c_i32_i4_e32 v39, v130, v50
	v_dot8c_i32_i4_e32 v40, v132, v52
	v_dot8c_i32_i4_e32 v41, v132, v50
	v_dot8c_i32_i4_e32 v42, v134, v52
	v_dot8c_i32_i4_e32 v43, v134, v50
	v_dot8c_i32_i4_e32 v44, v136, v52
	v_dot8c_i32_i4_e32 v45, v136, v50
	v_dot8c_i32_i4_e32 v38, v131, v53
	v_dot8c_i32_i4_e32 v39, v131, v51
	v_dot8c_i32_i4_e32 v40, v133, v53
	v_dot8c_i32_i4_e32 v41, v133, v51
	v_dot8c_i32_i4_e32 v42, v135, v53
	v_dot8c_i32_i4_e32 v43, v135, v51
	v_dot8c_i32_i4_e32 v44, v137, v53
	v_dot8c_i32_i4_e32 v45, v137, v51
	s_nop 3
	s_waitcnt lgkmcnt(15)
	v_lshlrev_b32_e32 v38, 5, v38
	v_lshlrev_b32_e32 v39, 1, v39
	v_add3_u32 v38, v39, v229, v38
	v_cvt_f32_i32_e32 v38, v38
	v_mul_f32_e32 v38, v228, v38
	v_lshlrev_b32_e32 v40, 5, v40
	v_lshlrev_b32_e32 v41, 1, v41
	v_add3_u32 v40, v41, v229, v40
	v_cvt_f32_i32_e32 v40, v40
	v_mul_f32_e32 v40, v228, v40
	v_lshlrev_b32_e32 v42, 5, v42
	v_lshlrev_b32_e32 v43, 1, v43
	v_add3_u32 v42, v43, v229, v42
	v_cvt_f32_i32_e32 v42, v42
	v_mul_f32_e32 v42, v228, v42
	v_lshlrev_b32_e32 v44, 5, v44
	v_lshlrev_b32_e32 v45, 1, v45
	v_add3_u32 v44, v45, v229, v44
	v_cvt_f32_i32_e32 v44, v44
	v_mul_f32_e32 v44, v228, v44
	v_cvt_pk_bf16_f32 v184, v38, v40
	v_cvt_pk_bf16_f32 v185, v42, v44
	ds_read_b128 v[252:255], v156
	s_add_i32 s44, s40, 8
	s_ashr_i32 s45, s44, 31
	s_lshl_b64 s[44:45], s[44:45], 12
	v_lshl_add_u64 v[80:81], v[36:37], 0, s[44:45]
	s_waitcnt lgkmcnt(0)
; __device__ __forceinline__ void peer_v_tokens(int j, const LAS unsigned short* EL, const LAS unsigned char* AL  , const LAS float* ASC  , const LAS int* SAL  , ...
;     ...
;         { const LAS v4u* ep = (const LAS v4u*)(EL + tl * 128 + 16 * g); const v4u e0 = ep[0], e1 = ep[1];
;           E[0] = e0.x; E[1] = e0.y; E[2] = e0.z; E[3] = e0.w; E[4] = e1.x; E[5] = e1.y; E[6] = e1.z; E[7] = e1.w; }
;         uint2 hv[4]; float4 gv[4];
;         { unsigned ho = (unsigned)t * (D / 4) + (unsigned)lane; asm volatile("" : "+v"(ho)); const uint2* hp = (const uint2*)HB + ho; const float4* gp = (const float4*)fng + lane;
; #pragma unroll
;           for (int jq = 0; jq < 4; ++jq) { hv[jq] = hp[64 * jq]; gv[jq] = gp[64 * jq]; } }
;         VDMA(0, 0); VDMA(1, 1);
; #pragma unroll
;         for (int m = 0; m < 2; ++m) {
;             const int idx = lane + 64 * m, tau = idx >> 4, sr = idx & 15, k = 16 * (sr & 7) + 2 * tau + (sr >> 3);
;             const int aq = (int)*(const LAS signed char*)(AL + tl * 128 + k); const int tq = aq + 8;
;             const unsigned lo = (((unsigned)tq & 15u) ^ 8u) * 0x11111111u, hi = ((unsigned)(tq >> 4) & 15u) * 0x11111111u;
;             typedef unsigned u2v __attribute__((ext_vector_type(2)));
;             u2v l2; l2.x = lo; l2.y = lo; u2v h2; h2.x = hi; h2.y = hi;
;             *(LAS u2v*)(ATL + 8 * idx) = l2; *(LAS u2v*)(ATL + 1024 + 8 * idx) = h2;
;         }
;         const float asc = ASC[tl]; const int sa = SAL[tl];
;         CFENCE();
;         int accH[4], accL[4];
; #pragma unroll
;         for (int st = 0; st < 16; ++st) {
;             const int p = st >> 2, q = st & 3;
;             if (st < 14) VDMA(st + 2, (st + 2) % 3);
;             if (st < 14) asm volatile("s_waitcnt vmcnt(8)" ::: "memory");
;             else if (st == 14) asm volatile("s_waitcnt vmcnt(4)" ::: "memory");
;             else asm volatile("s_waitcnt vmcnt(0)" ::: "memory");
;             if (q == 0) {
; #pragma unroll
;                 for (int r = 0; r < 4; ++r) { accH[r] = 0; accL[r] = 0; } }
; #pragma unroll
;             for (int tp = 0; tp < 2; ++tp) {
;                 const v2i ao = TR4(ATL + (2 * q + tp) * 128 + 8 * s16), ah = TR4(ATL + 1024 + (2 * q + tp) * 128 + 8 * s16);
; #pragma unroll
;                 for (int r = 0; r < 4; ++r) {
;                     const v2i d = TR4(ldsb + BUF[st % 3] + 2048 * tp + roff[r]);
	v_mul_f32_e32 v244, v244, v252
	v_mul_f32_e32 v245, v245, v253
	v_mul_f32_e32 v246, v246, v254
	v_mul_f32_e32 v247, v247, v255
	global_store_dwordx4 v[80:81], v[244:247], off offset:2048 nt
	s_add_i32 s43, s40, 16
	s_lshl_b32 s43, s43, 11
	v_add_u32_e32 v138, s43, v66
	global_load_dwordx2 v[194:195], v138, s[70:71]
	global_load_dwordx2 v[196:197], v138, s[70:71] offset:512
	global_load_dwordx2 v[198:199], v138, s[70:71] offset:1024
	global_load_dwordx2 v[200:201], v138, s[70:71] offset:1536
	v_add_u32_e32 v147, 8, v140
	v_and_b32_e32 v146, 15, v147
	v_xor_b32_e32 v146, 8, v146
	v_bfe_u32 v148, v147, 4, 4
	v_mul_lo_u32 v146, v146, s92
	v_mul_lo_u32 v148, v148, s92
	v_mov_b32_e32 v147, v146
	v_mov_b32_e32 v149, v148
	ds_write2st64_b64 v77, v[146:147], v[148:149] offset1:2
	v_add_u32_e32 v138, 0x1000, v74
	ds_read_u8 v139, v138
	v_add_u32_e32 v141, 0x1000, v73
	ds_read_u8 v140, v141
	s_add_i32 s43, s67, 96
	v_mov_b32_e32 v138, s43
	ds_read2st64_b32 v[228:229], v138 offset1:1
	ds_read_b128 v[18:21], v227 offset:8192
	ds_read_b128 v[22:25], v227 offset:8208
	v_mov_b32_e32 v150, v63
	v_mov_b32_e32 v151, v64
	v_mov_b32_e32 v38, 0
	v_mov_b32_e32 v39, 0
	v_mov_b32_e32 v40, 0
	v_mov_b32_e32 v41, 0
	v_mov_b32_e32 v42, 0
	v_mov_b32_e32 v43, 0
	v_mov_b32_e32 v44, 0
	v_mov_b32_e32 v45, 0
	v_and_b32_e32 v78, 0xffff, v31
	v_lshrrev_b32_e32 v79, 16, v31
	v_lshl_add_u32 v78, v78, 7, v152
	v_lshl_add_u32 v79, v79, 7, v153
	s_mov_b32 m0, s99
	s_add_i32 s43, s99, 0x400
	global_load_lds_dwordx4 v78, s[50:51]
	s_mov_b32 m0, s43
	s_nop 0
	global_load_lds_dwordx4 v79, s[50:51]
	s_waitcnt vmcnt(13)
	v_add_u32_e32 v54, s77, v59
	v_add_u32_e32 v55, s77, v60
	v_add_u32_e32 v56, s77, v61
	v_add_u32_e32 v57, s77, v62
	ds_read_b64_tr_b4 v[50:51], v160 offset:128
	ds_read_b64_tr_b4 v[52:53], v160 offset:1152
	ds_read_b64_tr_b4 v[130:131], v54
	ds_read_b64_tr_b4 v[132:133], v55
	ds_read_b64_tr_b4 v[134:135], v56
	ds_read_b64_tr_b4 v[136:137], v57
	s_waitcnt lgkmcnt(13)
	v_dot8c_i32_i4_e32 v38, v122, v48
	v_dot8c_i32_i4_e32 v39, v122, v46
	v_dot8c_i32_i4_e32 v40, v124, v48
	v_dot8c_i32_i4_e32 v41, v124, v46
	v_dot8c_i32_i4_e32 v42, v126, v48
	v_dot8c_i32_i4_e32 v43, v126, v46
	v_dot8c_i32_i4_e32 v44, v128, v48
	v_dot8c_i32_i4_e32 v45, v128, v46
	v_dot8c_i32_i4_e32 v38, v123, v49
	v_dot8c_i32_i4_e32 v39, v123, v47
	v_dot8c_i32_i4_e32 v40, v125, v49
	v_dot8c_i32_i4_e32 v41, v125, v47
	v_dot8c_i32_i4_e32 v42, v127, v49
	v_dot8c_i32_i4_e32 v43, v127, v47
	v_dot8c_i32_i4_e32 v44, v129, v49
	v_dot8c_i32_i4_e32 v45, v129, v47
	v_and_b32_e32 v78, 0xffff, v32
	v_lshrrev_b32_e32 v79, 16, v32
	v_lshl_add_u32 v78, v78, 7, v152
	v_lshl_add_u32 v79, v79, 7, v153
	s_mov_b32 m0, s76
	s_add_i32 s43, s76, 0x400
	global_load_lds_dwordx4 v78, s[50:51]
	s_mov_b32 m0, s43
	s_nop 0
	global_load_lds_dwordx4 v79, s[50:51]
	s_waitcnt vmcnt(13)
	v_add_u32_e32 v54, s78, v59
	v_add_u32_e32 v55, s78, v60
	v_add_u32_e32 v56, s78, v61
	v_add_u32_e32 v57, s78, v62
	ds_read_b64_tr_b4 v[46:47], v160 offset:256
	ds_read_b64_tr_b4 v[48:49], v160 offset:1280
	ds_read_b64_tr_b4 v[122:123], v54
	ds_read_b64_tr_b4 v[124:125], v55
	ds_read_b64_tr_b4 v[126:127], v56
	ds_read_b64_tr_b4 v[128:129], v57
	s_waitcnt lgkmcnt(6)
	v_dot8c_i32_i4_e32 v38, v130, v52
	v_dot8c_i32_i4_e32 v39, v130, v50
	v_dot8c_i32_i4_e32 v40, v132, v52
	v_dot8c_i32_i4_e32 v41, v132, v50
	v_dot8c_i32_i4_e32 v42, v134, v52
	v_dot8c_i32_i4_e32 v43, v134, v50
	v_dot8c_i32_i4_e32 v44, v136, v52
	v_dot8c_i32_i4_e32 v45, v136, v50
	v_dot8c_i32_i4_e32 v38, v131, v53
	v_dot8c_i32_i4_e32 v39, v131, v51
	v_dot8c_i32_i4_e32 v40, v133, v53
	v_dot8c_i32_i4_e32 v41, v133, v51
	v_dot8c_i32_i4_e32 v42, v135, v53
	v_dot8c_i32_i4_e32 v43, v135, v51
	v_dot8c_i32_i4_e32 v44, v137, v53
	v_dot8c_i32_i4_e32 v45, v137, v51
	v_and_b32_e32 v78, 0xffff, v33
	v_lshrrev_b32_e32 v79, 16, v33
	v_lshl_add_u32 v78, v78, 7, v152
	v_lshl_add_u32 v79, v79, 7, v153
	s_mov_b32 m0, s77
	s_add_i32 s43, s77, 0x400
	global_load_lds_dwordx4 v78, s[50:51]
	s_mov_b32 m0, s43
	s_nop 0
	global_load_lds_dwordx4 v79, s[50:51]
	s_waitcnt vmcnt(13)
	v_add_u32_e32 v54, s79, v59
	v_add_u32_e32 v55, s79, v60
	v_add_u32_e32 v56, s79, v61
	v_add_u32_e32 v57, s79, v62
	ds_read_b64_tr_b4 v[50:51], v160 offset:384
	ds_read_b64_tr_b4 v[52:53], v160 offset:1408
	ds_read_b64_tr_b4 v[130:131], v54
	ds_read_b64_tr_b4 v[132:133], v55
	ds_read_b64_tr_b4 v[134:135], v56
	ds_read_b64_tr_b4 v[136:137], v57
	s_waitcnt lgkmcnt(6)
	v_dot8c_i32_i4_e32 v38, v122, v48
	v_dot8c_i32_i4_e32 v39, v122, v46
	v_dot8c_i32_i4_e32 v40, v124, v48
	v_dot8c_i32_i4_e32 v41, v124, v46
	v_dot8c_i32_i4_e32 v42, v126, v48
	v_dot8c_i32_i4_e32 v43, v126, v46
	v_dot8c_i32_i4_e32 v44, v128, v48
	v_dot8c_i32_i4_e32 v45, v128, v46
	v_dot8c_i32_i4_e32 v38, v123, v49
	v_dot8c_i32_i4_e32 v39, v123, v47
	v_dot8c_i32_i4_e32 v40, v125, v49
	v_dot8c_i32_i4_e32 v41, v125, v47
	v_dot8c_i32_i4_e32 v42, v127, v49
	v_dot8c_i32_i4_e32 v43, v127, v47
	v_dot8c_i32_i4_e32 v44, v129, v49
	v_dot8c_i32_i4_e32 v45, v129, v47
	s_waitcnt lgkmcnt(15)
	v_and_b32_e32 v78, 0xffff, v18
	v_lshrrev_b32_e32 v79, 16, v18
	v_lshl_add_u32 v78, v78, 7, v150
	v_lshl_add_u32 v79, v79, 7, v151
	s_mov_b32 m0, s78
	s_add_i32 s43, s78, 0x400
	global_load_lds_dwordx4 v78, s[50:51]
	s_mov_b32 m0, s43
	s_nop 0
	global_load_lds_dwordx4 v79, s[50:51]
	s_waitcnt vmcnt(13)
	v_add_u32_e32 v54, s98, v59
	v_add_u32_e32 v55, s98, v60
	v_add_u32_e32 v56, s98, v61
	v_add_u32_e32 v57, s98, v62
	ds_read_b64_tr_b4 v[46:47], v160 offset:512
	ds_read_b64_tr_b4 v[48:49], v160 offset:1536
	ds_read_b64_tr_b4 v[122:123], v54
	ds_read_b64_tr_b4 v[124:125], v55
	ds_read_b64_tr_b4 v[126:127], v56
	ds_read_b64_tr_b4 v[128:129], v57
	s_waitcnt lgkmcnt(6)
; #define TR4(p_) __builtin_amdgcn_ds_read_tr4_b64_v2i32((LAS v2i*)(p_))
; #define VDMA(st_, k_) do { _Pragma("unroll") for (int i_ = 0; i_ < 4; ++i_) { \
;         const unsigned off_ = (unsigned)((st_) >> 2) * (16384u * 128u) + (PE_ID(E, 4 * ((st_) & 3) + i_) << 7) + ((i_ & 1) ? cx1 : cx0); \
;         __builtin_amdgcn_global_load_lds((const unsigned*)(V4 + off_), (LAS unsigned*)(ldsb + BUF[k_] + 1024 * i_), 16, 0, 0); } } while (0)
; __device__ __forceinline__ void peer_v_tokens(int j, const LAS unsigned short* EL, const LAS unsigned char* AL  , const LAS float* ASC  , const LAS int* SAL  , ...
;     ...
;             if (st < 14) VDMA(st + 2, (st + 2) % 3);
;             if (st < 14) asm volatile("s_waitcnt vmcnt(8)" ::: "memory");
;             else if (st == 14) asm volatile("s_waitcnt vmcnt(4)" ::: "memory");
;             else asm volatile("s_waitcnt vmcnt(0)" ::: "memory");
;             if (q == 0) {
; #pragma unroll
;                 for (int r = 0; r < 4; ++r) { accH[r] = 0; accL[r] = 0; } }
; #pragma unroll
;             for (int tp = 0; tp < 2; ++tp) {
;                 const v2i ao = TR4(ATL + (2 * q + tp) * 128 + 8 * s16), ah = TR4(ATL + 1024 + (2 * q + tp) * 128 + 8 * s16);
; #pragma unroll
;                 for (int r = 0; r < 4; ++r) {
;                     const v2i d = TR4(ldsb + BUF[st % 3] + 2048 * tp + roff[r]);
;                     accH[r] = __builtin_amdgcn_sdot8(d.x, ah.x, accH[r], false); accH[r] = __builtin_amdgcn_sdot8(d.y, ah.y, accH[r], false);
;                     accL[r] = __builtin_amdgcn_sdot8(d.x, ao.x, accL[r], false); accL[r] = __builtin_amdgcn_sdot8(d.y, ao.y, accL[r], false);
;                 }
	v_dot8c_i32_i4_e32 v38, v130, v52
	v_dot8c_i32_i4_e32 v39, v130, v50
	v_dot8c_i32_i4_e32 v40, v132, v52
	v_dot8c_i32_i4_e32 v41, v132, v50
	v_dot8c_i32_i4_e32 v42, v134, v52
	v_dot8c_i32_i4_e32 v43, v134, v50
	v_dot8c_i32_i4_e32 v44, v136, v52
	v_dot8c_i32_i4_e32 v45, v136, v50
	v_dot8c_i32_i4_e32 v38, v131, v53
	v_dot8c_i32_i4_e32 v39, v131, v51
	v_dot8c_i32_i4_e32 v40, v133, v53
	v_dot8c_i32_i4_e32 v41, v133, v51
	v_dot8c_i32_i4_e32 v42, v135, v53
	v_dot8c_i32_i4_e32 v43, v135, v51
	v_dot8c_i32_i4_e32 v44, v137, v53
	v_dot8c_i32_i4_e32 v45, v137, v51
	v_and_b32_e32 v78, 0xffff, v19
	v_lshrrev_b32_e32 v79, 16, v19
	v_lshl_add_u32 v78, v78, 7, v150
	v_lshl_add_u32 v79, v79, 7, v151
	s_mov_b32 m0, s79
	s_add_i32 s43, s79, 0x400
	global_load_lds_dwordx4 v78, s[50:51]
	s_mov_b32 m0, s43
	s_nop 0
	global_load_lds_dwordx4 v79, s[50:51]
	s_waitcnt vmcnt(8)
	v_add_u32_e32 v54, s99, v59
	v_add_u32_e32 v55, s99, v60
	v_add_u32_e32 v56, s99, v61
	v_add_u32_e32 v57, s99, v62
	ds_read_b64_tr_b4 v[50:51], v160 offset:640
	ds_read_b64_tr_b4 v[52:53], v160 offset:1664
	ds_read_b64_tr_b4 v[130:131], v54
	ds_read_b64_tr_b4 v[132:133], v55
	ds_read_b64_tr_b4 v[134:135], v56
	ds_read_b64_tr_b4 v[136:137], v57
	s_waitcnt lgkmcnt(6)
	v_dot8c_i32_i4_e32 v38, v122, v48
	v_dot8c_i32_i4_e32 v39, v122, v46
	v_dot8c_i32_i4_e32 v40, v124, v48
	v_dot8c_i32_i4_e32 v41, v124, v46
	v_dot8c_i32_i4_e32 v42, v126, v48
	v_dot8c_i32_i4_e32 v43, v126, v46
	v_dot8c_i32_i4_e32 v44, v128, v48
	v_dot8c_i32_i4_e32 v45, v128, v46
	v_dot8c_i32_i4_e32 v38, v123, v49
	v_dot8c_i32_i4_e32 v39, v123, v47
	v_dot8c_i32_i4_e32 v40, v125, v49
	v_dot8c_i32_i4_e32 v41, v125, v47
	v_dot8c_i32_i4_e32 v42, v127, v49
	v_dot8c_i32_i4_e32 v43, v127, v47
	v_dot8c_i32_i4_e32 v44, v129, v49
	v_dot8c_i32_i4_e32 v45, v129, v47
	s_waitcnt lgkmcnt(15)
	v_add_u32_e32 v143, 8, v139
	v_and_b32_e32 v142, 15, v143
	v_xor_b32_e32 v142, 8, v142
	v_bfe_u32 v144, v143, 4, 4
	v_mul_lo_u32 v142, v142, s92
	v_mul_lo_u32 v144, v144, s92
	v_mov_b32_e32 v143, v142
	v_mov_b32_e32 v145, v144
	ds_write2st64_b64 v159, v[142:143], v[144:145] offset1:2
	v_and_b32_e32 v78, 0xffff, v20
	v_lshrrev_b32_e32 v79, 16, v20
	v_lshl_add_u32 v78, v78, 7, v150
	v_lshl_add_u32 v79, v79, 7, v151
	s_mov_b32 m0, s98
	s_add_i32 s43, s98, 0x400
	global_load_lds_dwordx4 v78, s[50:51]
	s_mov_b32 m0, s43
	s_nop 0
	global_load_lds_dwordx4 v79, s[50:51]
	s_waitcnt vmcnt(8)
	v_add_u32_e32 v54, s76, v59
	v_add_u32_e32 v55, s76, v60
	v_add_u32_e32 v56, s76, v61
	v_add_u32_e32 v57, s76, v62
	ds_read_b64_tr_b4 v[46:47], v160 offset:768
	ds_read_b64_tr_b4 v[48:49], v160 offset:1792
	ds_read_b64_tr_b4 v[122:123], v54
	ds_read_b64_tr_b4 v[124:125], v55
	ds_read_b64_tr_b4 v[126:127], v56
	ds_read_b64_tr_b4 v[128:129], v57
	s_waitcnt lgkmcnt(7)
	v_dot8c_i32_i4_e32 v38, v130, v52
	v_dot8c_i32_i4_e32 v39, v130, v50
	v_dot8c_i32_i4_e32 v40, v132, v52
	v_dot8c_i32_i4_e32 v41, v132, v50
	v_dot8c_i32_i4_e32 v42, v134, v52
	v_dot8c_i32_i4_e32 v43, v134, v50
	v_dot8c_i32_i4_e32 v44, v136, v52
	v_dot8c_i32_i4_e32 v45, v136, v50
	v_dot8c_i32_i4_e32 v38, v131, v53
	v_dot8c_i32_i4_e32 v39, v131, v51
	v_dot8c_i32_i4_e32 v40, v133, v53
	v_dot8c_i32_i4_e32 v41, v133, v51
	v_dot8c_i32_i4_e32 v42, v135, v53
	v_dot8c_i32_i4_e32 v43, v135, v51
	v_dot8c_i32_i4_e32 v44, v137, v53
	v_dot8c_i32_i4_e32 v45, v137, v51
	v_and_b32_e32 v78, 0xffff, v21
	v_lshrrev_b32_e32 v79, 16, v21
	v_lshl_add_u32 v78, v78, 7, v150
	v_lshl_add_u32 v79, v79, 7, v151
	s_mov_b32 m0, s99
	s_add_i32 s43, s99, 0x400
	global_load_lds_dwordx4 v78, s[50:51]
	s_mov_b32 m0, s43
	s_nop 0
	global_load_lds_dwordx4 v79, s[50:51]
	s_waitcnt vmcnt(8)
	v_add_u32_e32 v54, s77, v59
	v_add_u32_e32 v55, s77, v60
	v_add_u32_e32 v56, s77, v61
	v_add_u32_e32 v57, s77, v62
	ds_read_b64_tr_b4 v[50:51], v160 offset:896
	ds_read_b64_tr_b4 v[52:53], v160 offset:1920
	ds_read_b64_tr_b4 v[130:131], v54
	ds_read_b64_tr_b4 v[132:133], v55
	ds_read_b64_tr_b4 v[134:135], v56
	ds_read_b64_tr_b4 v[136:137], v57
	s_waitcnt lgkmcnt(6)
	v_dot8c_i32_i4_e32 v38, v122, v48
	v_dot8c_i32_i4_e32 v39, v122, v46
	v_dot8c_i32_i4_e32 v40, v124, v48
	v_dot8c_i32_i4_e32 v41, v124, v46
	v_dot8c_i32_i4_e32 v42, v126, v48
	v_dot8c_i32_i4_e32 v43, v126, v46
	v_dot8c_i32_i4_e32 v44, v128, v48
	v_dot8c_i32_i4_e32 v45, v128, v46
	v_dot8c_i32_i4_e32 v38, v123, v49
	v_dot8c_i32_i4_e32 v39, v123, v47
	v_dot8c_i32_i4_e32 v40, v125, v49
	v_dot8c_i32_i4_e32 v41, v125, v47
	v_dot8c_i32_i4_e32 v42, v127, v49
	v_dot8c_i32_i4_e32 v43, v127, v47
	v_dot8c_i32_i4_e32 v44, v129, v49
	v_dot8c_i32_i4_e32 v45, v129, v47
	v_and_b32_e32 v78, 0xffff, v22
	v_lshrrev_b32_e32 v79, 16, v22
	v_lshl_add_u32 v78, v78, 7, v150
	v_lshl_add_u32 v79, v79, 7, v151
	s_mov_b32 m0, s76
	s_add_i32 s43, s76, 0x400
	global_load_lds_dwordx4 v78, s[50:51]
	s_mov_b32 m0, s43
	s_nop 0
	global_load_lds_dwordx4 v79, s[50:51]
	s_waitcnt vmcnt(8)
	v_add_u32_e32 v54, s78, v59
	v_add_u32_e32 v55, s78, v60
	v_add_u32_e32 v56, s78, v61
	v_add_u32_e32 v57, s78, v62
	ds_read_b64_tr_b4 v[46:47], v160
	ds_read_b64_tr_b4 v[48:49], v160 offset:1024
	ds_read_b64_tr_b4 v[122:123], v54
	ds_read_b64_tr_b4 v[124:125], v55
	ds_read_b64_tr_b4 v[126:127], v56
	ds_read_b64_tr_b4 v[128:129], v57
	s_waitcnt lgkmcnt(6)
	v_dot8c_i32_i4_e32 v38, v130, v52
	v_dot8c_i32_i4_e32 v39, v130, v50
	v_dot8c_i32_i4_e32 v40, v132, v52
	v_dot8c_i32_i4_e32 v41, v132, v50
	v_dot8c_i32_i4_e32 v42, v134, v52
	v_dot8c_i32_i4_e32 v43, v134, v50
	v_dot8c_i32_i4_e32 v44, v136, v52
	v_dot8c_i32_i4_e32 v45, v136, v50
	v_dot8c_i32_i4_e32 v38, v131, v53
	v_dot8c_i32_i4_e32 v39, v131, v51
	v_dot8c_i32_i4_e32 v40, v133, v53
	v_dot8c_i32_i4_e32 v41, v133, v51
	v_dot8c_i32_i4_e32 v42, v135, v53
	v_dot8c_i32_i4_e32 v43, v135, v51
	v_dot8c_i32_i4_e32 v44, v137, v53
	v_dot8c_i32_i4_e32 v45, v137, v51
	s_nop 3
	s_waitcnt lgkmcnt(15)
; __device__ __forceinline__ void peer_v_tokens(int j, const LAS unsigned short* EL, const LAS unsigned char* AL  , const LAS float* ASC  , const LAS int* SAL  , ...
;     ...
;         { const LAS v4u* ep = (const LAS v4u*)(EL + tl * 128 + 16 * g); const v4u e0 = ep[0], e1 = ep[1];
;           E[0] = e0.x; E[1] = e0.y; E[2] = e0.z; E[3] = e0.w; E[4] = e1.x; E[5] = e1.y; E[6] = e1.z; E[7] = e1.w; }
;         uint2 hv[4]; float4 gv[4];
;         { unsigned ho = (unsigned)t * (D / 4) + (unsigned)lane; asm volatile("" : "+v"(ho)); const uint2* hp = (const uint2*)HB + ho; const float4* gp = (const float4*)fng + lane;
; #pragma unroll
;           for (int jq = 0; jq < 4; ++jq) { hv[jq] = hp[64 * jq]; gv[jq] = gp[64 * jq]; } }
;         VDMA(0, 0); VDMA(1, 1);
; #pragma unroll
;         for (int m = 0; m < 2; ++m) {
;             const int idx = lane + 64 * m, tau = idx >> 4, sr = idx & 15, k = 16 * (sr & 7) + 2 * tau + (sr >> 3);
;             const int aq = (int)*(const LAS signed char*)(AL + tl * 128 + k); const int tq = aq + 8;
;             const unsigned lo = (((unsigned)tq & 15u) ^ 8u) * 0x11111111u, hi = ((unsigned)(tq >> 4) & 15u) * 0x11111111u;
;             typedef unsigned u2v __attribute__((ext_vector_type(2)));
;             u2v l2; l2.x = lo; l2.y = lo; u2v h2; h2.x = hi; h2.y = hi;
;             *(LAS u2v*)(ATL + 8 * idx) = l2; *(LAS u2v*)(ATL + 1024 + 8 * idx) = h2;
;         }
;         const float asc = ASC[tl]; const int sa = SAL[tl];
;         CFENCE();
;         int accH[4], accL[4];
; #pragma unroll
;         for (int st = 0; st < 16; ++st) {
;             const int p = st >> 2, q = st & 3;
;             if (st < 14) VDMA(st + 2, (st + 2) % 3);
;             if (st < 14) asm volatile("s_waitcnt vmcnt(8)" ::: "memory");
;             else if (st == 14) asm volatile("s_waitcnt vmcnt(4)" ::: "memory");
;             else asm volatile("s_waitcnt vmcnt(0)" ::: "memory");
;             if (q == 0) {
; #pragma unroll
;                 for (int r = 0; r < 4; ++r) { accH[r] = 0; accL[r] = 0; } }
; #pragma unroll
;             for (int tp = 0; tp < 2; ++tp) {
;                 const v2i ao = TR4(ATL + (2 * q + tp) * 128 + 8 * s16), ah = TR4(ATL + 1024 + (2 * q + tp) * 128 + 8 * s16);
; #pragma unroll
;                 for (int r = 0; r < 4; ++r) {
;                     const v2i d = TR4(ldsb + BUF[st % 3] + 2048 * tp + roff[r]);
	v_lshlrev_b32_e32 v38, 5, v38
	v_lshlrev_b32_e32 v39, 1, v39
	v_add3_u32 v38, v39, v229, v38
	v_cvt_f32_i32_e32 v38, v38
	v_mul_f32_e32 v38, v228, v38
	v_lshlrev_b32_e32 v40, 5, v40
	v_lshlrev_b32_e32 v41, 1, v41
	v_add3_u32 v40, v41, v229, v40
	v_cvt_f32_i32_e32 v40, v40
	v_mul_f32_e32 v40, v228, v40
	v_lshlrev_b32_e32 v42, 5, v42
	v_lshlrev_b32_e32 v43, 1, v43
	v_add3_u32 v42, v43, v229, v42
	v_cvt_f32_i32_e32 v42, v42
	v_mul_f32_e32 v42, v228, v42
	v_lshlrev_b32_e32 v44, 5, v44
	v_lshlrev_b32_e32 v45, 1, v45
	v_add3_u32 v44, v45, v229, v44
	v_cvt_f32_i32_e32 v44, v44
	v_mul_f32_e32 v44, v228, v44
	v_cvt_pk_bf16_f32 v192, v38, v40
	v_cvt_pk_bf16_f32 v193, v42, v44
	ds_read_b128 v[252:255], v156 offset:1024
	s_add_i32 s44, s40, 8
	s_ashr_i32 s45, s44, 31
	s_lshl_b64 s[44:45], s[44:45], 12
	v_lshl_add_u64 v[80:81], v[36:37], 0, s[44:45]
	s_waitcnt lgkmcnt(0)
	v_mul_f32_e32 v248, v248, v252
	v_mul_f32_e32 v249, v249, v253
	v_mul_f32_e32 v250, v250, v254
	v_mul_f32_e32 v251, v251, v255
	global_store_dwordx4 v[80:81], v[248:251], off offset:3072 nt
	v_add_u32_e32 v147, 8, v140
	v_and_b32_e32 v146, 15, v147
	v_xor_b32_e32 v146, 8, v146
	v_bfe_u32 v148, v147, 4, 4
	v_mul_lo_u32 v146, v146, s92
	v_mul_lo_u32 v148, v148, s92
	v_mov_b32_e32 v147, v146
	v_mov_b32_e32 v149, v148
	ds_write2st64_b64 v77, v[146:147], v[148:149] offset1:2
	v_add_u32_e32 v138, 0x1400, v74
	ds_read_u8 v139, v138
	v_add_u32_e32 v141, 0x1400, v73
	ds_read_u8 v140, v141
	s_add_i32 s43, s67, 128
	v_mov_b32_e32 v138, s43
	ds_read2st64_b32 v[228:229], v138 offset1:1
	ds_read_b128 v[26:29], v227 offset:10240
	ds_read_b128 v[30:33], v227 offset:10256
	v_mov_b32_e32 v38, 0
	v_mov_b32_e32 v39, 0
	v_mov_b32_e32 v40, 0
	v_mov_b32_e32 v41, 0
	v_mov_b32_e32 v42, 0
	v_mov_b32_e32 v43, 0
	v_mov_b32_e32 v44, 0
	v_mov_b32_e32 v45, 0
	v_and_b32_e32 v78, 0xffff, v23
	v_lshrrev_b32_e32 v79, 16, v23
	v_lshl_add_u32 v78, v78, 7, v150
	v_lshl_add_u32 v79, v79, 7, v151
	s_mov_b32 m0, s77
	s_add_i32 s43, s77, 0x400
	global_load_lds_dwordx4 v78, s[50:51]
	s_mov_b32 m0, s43
	s_nop 0
	global_load_lds_dwordx4 v79, s[50:51]
	s_waitcnt vmcnt(9)
	v_add_u32_e32 v54, s79, v59
	v_add_u32_e32 v55, s79, v60
	v_add_u32_e32 v56, s79, v61
	v_add_u32_e32 v57, s79, v62
	ds_read_b64_tr_b4 v[50:51], v160 offset:128
	ds_read_b64_tr_b4 v[52:53], v160 offset:1152
	ds_read_b64_tr_b4 v[130:131], v54
	ds_read_b64_tr_b4 v[132:133], v55
	ds_read_b64_tr_b4 v[134:135], v56
	ds_read_b64_tr_b4 v[136:137], v57
	s_waitcnt lgkmcnt(13)
	v_dot8c_i32_i4_e32 v38, v122, v48
	v_dot8c_i32_i4_e32 v39, v122, v46
	v_dot8c_i32_i4_e32 v40, v124, v48
	v_dot8c_i32_i4_e32 v41, v124, v46
	v_dot8c_i32_i4_e32 v42, v126, v48
	v_dot8c_i32_i4_e32 v43, v126, v46
	v_dot8c_i32_i4_e32 v44, v128, v48
	v_dot8c_i32_i4_e32 v45, v128, v46
	v_dot8c_i32_i4_e32 v38, v123, v49
	v_dot8c_i32_i4_e32 v39, v123, v47
	v_dot8c_i32_i4_e32 v40, v125, v49
	v_dot8c_i32_i4_e32 v41, v125, v47
	v_dot8c_i32_i4_e32 v42, v127, v49
	v_dot8c_i32_i4_e32 v43, v127, v47
	v_dot8c_i32_i4_e32 v44, v129, v49
	v_dot8c_i32_i4_e32 v45, v129, v47
	v_and_b32_e32 v78, 0xffff, v24
	v_lshrrev_b32_e32 v79, 16, v24
	v_lshl_add_u32 v78, v78, 7, v150
	v_lshl_add_u32 v79, v79, 7, v151
	s_mov_b32 m0, s78
	s_add_i32 s43, s78, 0x400
	global_load_lds_dwordx4 v78, s[50:51]
	s_mov_b32 m0, s43
	s_nop 0
	global_load_lds_dwordx4 v79, s[50:51]
	s_waitcnt vmcnt(9)
	v_add_u32_e32 v54, s98, v59
	v_add_u32_e32 v55, s98, v60
	v_add_u32_e32 v56, s98, v61
	v_add_u32_e32 v57, s98, v62
	ds_read_b64_tr_b4 v[46:47], v160 offset:256
	ds_read_b64_tr_b4 v[48:49], v160 offset:1280
	ds_read_b64_tr_b4 v[122:123], v54
	ds_read_b64_tr_b4 v[124:125], v55
	ds_read_b64_tr_b4 v[126:127], v56
	ds_read_b64_tr_b4 v[128:129], v57
	s_waitcnt lgkmcnt(6)
	v_dot8c_i32_i4_e32 v38, v130, v52
	v_dot8c_i32_i4_e32 v39, v130, v50
	v_dot8c_i32_i4_e32 v40, v132, v52
	v_dot8c_i32_i4_e32 v41, v132, v50
	v_dot8c_i32_i4_e32 v42, v134, v52
	v_dot8c_i32_i4_e32 v43, v134, v50
	v_dot8c_i32_i4_e32 v44, v136, v52
	v_dot8c_i32_i4_e32 v45, v136, v50
	v_dot8c_i32_i4_e32 v38, v131, v53
	v_dot8c_i32_i4_e32 v39, v131, v51
	v_dot8c_i32_i4_e32 v40, v133, v53
	v_dot8c_i32_i4_e32 v41, v133, v51
	v_dot8c_i32_i4_e32 v42, v135, v53
	v_dot8c_i32_i4_e32 v43, v135, v51
	v_dot8c_i32_i4_e32 v44, v137, v53
	v_dot8c_i32_i4_e32 v45, v137, v51
	ds_write_b16 v65, v178
	ds_write_b16_d16_hi v65, v178 offset:128
	ds_write_b16 v65, v179 offset:256
	ds_write_b16_d16_hi v65, v179 offset:384
	ds_write_b16 v65, v180 offset:512
	ds_write_b16_d16_hi v65, v180 offset:640
	ds_write_b16 v65, v181 offset:768
	ds_write_b16_d16_hi v65, v181 offset:896
	ds_write_b16 v65, v182 offset:1024
	ds_write_b16_d16_hi v65, v182 offset:1152
	ds_write_b16 v65, v183 offset:1280
	ds_write_b16_d16_hi v65, v183 offset:1408
	ds_write_b16 v65, v184 offset:1536
	ds_write_b16_d16_hi v65, v184 offset:1664
	ds_write_b16 v65, v185 offset:1792
	ds_write_b16_d16_hi v65, v185 offset:1920
	ds_read_b64 v[202:203], v154
	ds_read_b64 v[204:205], v154 offset:512
	ds_read_b64 v[206:207], v154 offset:1024
	ds_read_b64 v[208:209], v154 offset:1536
	v_and_b32_e32 v78, 0xffff, v25
	v_lshrrev_b32_e32 v79, 16, v25
	v_lshl_add_u32 v78, v78, 7, v150
	v_lshl_add_u32 v79, v79, 7, v151
	s_mov_b32 m0, s79
	s_add_i32 s43, s79, 0x400
	global_load_lds_dwordx4 v78, s[50:51]
	s_mov_b32 m0, s43
	s_nop 0
	global_load_lds_dwordx4 v79, s[50:51]
	s_waitcnt vmcnt(9)
	v_add_u32_e32 v54, s99, v59
	v_add_u32_e32 v55, s99, v60
	v_add_u32_e32 v56, s99, v61
	v_add_u32_e32 v57, s99, v62
	ds_read_b64_tr_b4 v[50:51], v160 offset:384
	ds_read_b64_tr_b4 v[52:53], v160 offset:1408
	ds_read_b64_tr_b4 v[130:131], v54
	ds_read_b64_tr_b4 v[132:133], v55
	ds_read_b64_tr_b4 v[134:135], v56
	ds_read_b64_tr_b4 v[136:137], v57
	s_waitcnt lgkmcnt(15)
; #define TR4(p_) __builtin_amdgcn_ds_read_tr4_b64_v2i32((LAS v2i*)(p_))
; #define VDMA(st_, k_) do { _Pragma("unroll") for (int i_ = 0; i_ < 4; ++i_) { \
;         const unsigned off_ = (unsigned)((st_) >> 2) * (16384u * 128u) + (PE_ID(E, 4 * ((st_) & 3) + i_) << 7) + ((i_ & 1) ? cx1 : cx0); \
;         __builtin_amdgcn_global_load_lds((const unsigned*)(V4 + off_), (LAS unsigned*)(ldsb + BUF[k_] + 1024 * i_), 16, 0, 0); } } while (0)
; __device__ __forceinline__ void peer_v_tokens(int j, const LAS unsigned short* EL, const LAS unsigned char* AL  , const LAS float* ASC  , const LAS int* SAL  , ...
;     ...
;             if (st < 14) VDMA(st + 2, (st + 2) % 3);
;             if (st < 14) asm volatile("s_waitcnt vmcnt(8)" ::: "memory");
;             else if (st == 14) asm volatile("s_waitcnt vmcnt(4)" ::: "memory");
;             else asm volatile("s_waitcnt vmcnt(0)" ::: "memory");
;             if (q == 0) {
; #pragma unroll
;                 for (int r = 0; r < 4; ++r) { accH[r] = 0; accL[r] = 0; } }
; #pragma unroll
;             for (int tp = 0; tp < 2; ++tp) {
;                 const v2i ao = TR4(ATL + (2 * q + tp) * 128 + 8 * s16), ah = TR4(ATL + 1024 + (2 * q + tp) * 128 + 8 * s16);
; #pragma unroll
;                 for (int r = 0; r < 4; ++r) {
;                     const v2i d = TR4(ldsb + BUF[st % 3] + 2048 * tp + roff[r]);
;                     accH[r] = __builtin_amdgcn_sdot8(d.x, ah.x, accH[r], false); accH[r] = __builtin_amdgcn_sdot8(d.y, ah.y, accH[r], false);
;                     accL[r] = __builtin_amdgcn_sdot8(d.x, ao.x, accL[r], false); accL[r] = __builtin_amdgcn_sdot8(d.y, ao.y, accL[r], false);
;                 }
	v_dot8c_i32_i4_e32 v38, v122, v48
	v_dot8c_i32_i4_e32 v39, v122, v46
	v_dot8c_i32_i4_e32 v40, v124, v48
	v_dot8c_i32_i4_e32 v41, v124, v46
	v_dot8c_i32_i4_e32 v42, v126, v48
	v_dot8c_i32_i4_e32 v43, v126, v46
	v_dot8c_i32_i4_e32 v44, v128, v48
	v_dot8c_i32_i4_e32 v45, v128, v46
	v_dot8c_i32_i4_e32 v38, v123, v49
	v_dot8c_i32_i4_e32 v39, v123, v47
	v_dot8c_i32_i4_e32 v40, v125, v49
	v_dot8c_i32_i4_e32 v41, v125, v47
	v_dot8c_i32_i4_e32 v42, v127, v49
	v_dot8c_i32_i4_e32 v43, v127, v47
	v_dot8c_i32_i4_e32 v44, v129, v49
	v_dot8c_i32_i4_e32 v45, v129, v47
	s_waitcnt lgkmcnt(15)
	v_and_b32_e32 v78, 0xffff, v26
	v_lshrrev_b32_e32 v79, 16, v26
	v_lshl_add_u32 v78, v78, 7, v150
	v_lshl_add_u32 v79, v79, 7, v151
	s_mov_b32 m0, s98
	s_add_i32 s43, s98, 0x400
	global_load_lds_dwordx4 v78, s[50:51]
	s_mov_b32 m0, s43
	s_nop 0
	global_load_lds_dwordx4 v79, s[50:51]
	s_waitcnt vmcnt(9)
	v_add_u32_e32 v54, s76, v59
	v_add_u32_e32 v55, s76, v60
	v_add_u32_e32 v56, s76, v61
	v_add_u32_e32 v57, s76, v62
	ds_read_b64_tr_b4 v[46:47], v160 offset:512
	ds_read_b64_tr_b4 v[48:49], v160 offset:1536
	ds_read_b64_tr_b4 v[122:123], v54
	ds_read_b64_tr_b4 v[124:125], v55
	ds_read_b64_tr_b4 v[126:127], v56
	ds_read_b64_tr_b4 v[128:129], v57
	s_waitcnt lgkmcnt(6)
	v_dot8c_i32_i4_e32 v38, v130, v52
	v_dot8c_i32_i4_e32 v39, v130, v50
	v_dot8c_i32_i4_e32 v40, v132, v52
	v_dot8c_i32_i4_e32 v41, v132, v50
	v_dot8c_i32_i4_e32 v42, v134, v52
	v_dot8c_i32_i4_e32 v43, v134, v50
	v_dot8c_i32_i4_e32 v44, v136, v52
	v_dot8c_i32_i4_e32 v45, v136, v50
	v_dot8c_i32_i4_e32 v38, v131, v53
	v_dot8c_i32_i4_e32 v39, v131, v51
	v_dot8c_i32_i4_e32 v40, v133, v53
	v_dot8c_i32_i4_e32 v41, v133, v51
	v_dot8c_i32_i4_e32 v42, v135, v53
	v_dot8c_i32_i4_e32 v43, v135, v51
	v_dot8c_i32_i4_e32 v44, v137, v53
	v_dot8c_i32_i4_e32 v45, v137, v51
	v_and_b32_e32 v78, 0xffff, v27
	v_lshrrev_b32_e32 v79, 16, v27
	v_lshl_add_u32 v78, v78, 7, v150
	v_lshl_add_u32 v79, v79, 7, v151
	s_mov_b32 m0, s99
	s_add_i32 s43, s99, 0x400
	global_load_lds_dwordx4 v78, s[50:51]
	s_mov_b32 m0, s43
	s_nop 0
	global_load_lds_dwordx4 v79, s[50:51]
	s_waitcnt vmcnt(8)
	v_add_u32_e32 v54, s77, v59
	v_add_u32_e32 v55, s77, v60
	v_add_u32_e32 v56, s77, v61
	v_add_u32_e32 v57, s77, v62
	ds_read_b64_tr_b4 v[50:51], v160 offset:640
	ds_read_b64_tr_b4 v[52:53], v160 offset:1664
	ds_read_b64_tr_b4 v[130:131], v54
	ds_read_b64_tr_b4 v[132:133], v55
	ds_read_b64_tr_b4 v[134:135], v56
	ds_read_b64_tr_b4 v[136:137], v57
	s_waitcnt lgkmcnt(6)
	v_dot8c_i32_i4_e32 v38, v122, v48
	v_dot8c_i32_i4_e32 v39, v122, v46
	v_dot8c_i32_i4_e32 v40, v124, v48
	v_dot8c_i32_i4_e32 v41, v124, v46
	v_dot8c_i32_i4_e32 v42, v126, v48
	v_dot8c_i32_i4_e32 v43, v126, v46
	v_dot8c_i32_i4_e32 v44, v128, v48
	v_dot8c_i32_i4_e32 v45, v128, v46
	v_dot8c_i32_i4_e32 v38, v123, v49
	v_dot8c_i32_i4_e32 v39, v123, v47
	v_dot8c_i32_i4_e32 v40, v125, v49
	v_dot8c_i32_i4_e32 v41, v125, v47
	v_dot8c_i32_i4_e32 v42, v127, v49
	v_dot8c_i32_i4_e32 v43, v127, v47
	v_dot8c_i32_i4_e32 v44, v129, v49
	v_dot8c_i32_i4_e32 v45, v129, v47
	s_waitcnt lgkmcnt(15)
	v_add_u32_e32 v143, 8, v139
	v_and_b32_e32 v142, 15, v143
	v_xor_b32_e32 v142, 8, v142
	v_bfe_u32 v144, v143, 4, 4
	v_mul_lo_u32 v142, v142, s92
	v_mul_lo_u32 v144, v144, s92
	v_mov_b32_e32 v143, v142
	v_mov_b32_e32 v145, v144
	ds_write2st64_b64 v159, v[142:143], v[144:145] offset1:2
	v_and_b32_e32 v78, 0xffff, v28
	v_lshrrev_b32_e32 v79, 16, v28
	v_lshl_add_u32 v78, v78, 7, v150
	v_lshl_add_u32 v79, v79, 7, v151
	s_mov_b32 m0, s76
	s_add_i32 s43, s76, 0x400
	global_load_lds_dwordx4 v78, s[50:51]
	s_mov_b32 m0, s43
	s_nop 0
	global_load_lds_dwordx4 v79, s[50:51]
	s_waitcnt vmcnt(8)
	v_add_u32_e32 v54, s78, v59
	v_add_u32_e32 v55, s78, v60
	v_add_u32_e32 v56, s78, v61
	v_add_u32_e32 v57, s78, v62
	ds_read_b64_tr_b4 v[46:47], v160 offset:768
	ds_read_b64_tr_b4 v[48:49], v160 offset:1792
	ds_read_b64_tr_b4 v[122:123], v54
	ds_read_b64_tr_b4 v[124:125], v55
	ds_read_b64_tr_b4 v[126:127], v56
	ds_read_b64_tr_b4 v[128:129], v57
	s_waitcnt lgkmcnt(7)
	v_dot8c_i32_i4_e32 v38, v130, v52
	v_dot8c_i32_i4_e32 v39, v130, v50
	v_dot8c_i32_i4_e32 v40, v132, v52
	v_dot8c_i32_i4_e32 v41, v132, v50
	v_dot8c_i32_i4_e32 v42, v134, v52
	v_dot8c_i32_i4_e32 v43, v134, v50
	v_dot8c_i32_i4_e32 v44, v136, v52
	v_dot8c_i32_i4_e32 v45, v136, v50
	v_dot8c_i32_i4_e32 v38, v131, v53
	v_dot8c_i32_i4_e32 v39, v131, v51
	v_dot8c_i32_i4_e32 v40, v133, v53
	v_dot8c_i32_i4_e32 v41, v133, v51
	v_dot8c_i32_i4_e32 v42, v135, v53
	v_dot8c_i32_i4_e32 v43, v135, v51
	v_dot8c_i32_i4_e32 v44, v137, v53
	v_dot8c_i32_i4_e32 v45, v137, v51
	v_and_b32_e32 v78, 0xffff, v29
	v_lshrrev_b32_e32 v79, 16, v29
	v_lshl_add_u32 v78, v78, 7, v150
	v_lshl_add_u32 v79, v79, 7, v151
	s_mov_b32 m0, s77
	s_add_i32 s43, s77, 0x400
	global_load_lds_dwordx4 v78, s[50:51]
	s_mov_b32 m0, s43
	s_nop 0
	global_load_lds_dwordx4 v79, s[50:51]
	s_waitcnt vmcnt(8)
	v_add_u32_e32 v54, s79, v59
	v_add_u32_e32 v55, s79, v60
	v_add_u32_e32 v56, s79, v61
	v_add_u32_e32 v57, s79, v62
	ds_read_b64_tr_b4 v[50:51], v160 offset:896
	ds_read_b64_tr_b4 v[52:53], v160 offset:1920
	ds_read_b64_tr_b4 v[130:131], v54
	ds_read_b64_tr_b4 v[132:133], v55
	ds_read_b64_tr_b4 v[134:135], v56
	ds_read_b64_tr_b4 v[136:137], v57
	s_waitcnt lgkmcnt(6)
; __device__ __forceinline__ void peer_v_tokens(int j, const LAS unsigned short* EL, const LAS unsigned char* AL  , const LAS float* ASC  , const LAS int* SAL  , ...
;     ...
;         for (int st = 0; st < 16; ++st) {
;             const int p = st >> 2, q = st & 3;
;             if (st < 14) VDMA(st + 2, (st + 2) % 3);
;             if (st < 14) asm volatile("s_waitcnt vmcnt(8)" ::: "memory");
;             else if (st == 14) asm volatile("s_waitcnt vmcnt(4)" ::: "memory");
;             else asm volatile("s_waitcnt vmcnt(0)" ::: "memory");
;             if (q == 0) {
; #pragma unroll
;                 for (int r = 0; r < 4; ++r) { accH[r] = 0; accL[r] = 0; } }
; #pragma unroll
;             for (int tp = 0; tp < 2; ++tp) {
;                 const v2i ao = TR4(ATL + (2 * q + tp) * 128 + 8 * s16), ah = TR4(ATL + 1024 + (2 * q + tp) * 128 + 8 * s16);
; #pragma unroll
;                 for (int r = 0; r < 4; ++r) {
;                     const v2i d = TR4(ldsb + BUF[st % 3] + 2048 * tp + roff[r]);
;                     accH[r] = __builtin_amdgcn_sdot8(d.x, ah.x, accH[r], false); accH[r] = __builtin_amdgcn_sdot8(d.y, ah.y, accH[r], false);
;                     accL[r] = __builtin_amdgcn_sdot8(d.x, ao.x, accL[r], false); accL[r] = __builtin_amdgcn_sdot8(d.y, ao.y, accL[r], false);
;                 }
;             }
;             asm volatile("s_waitcnt lgkmcnt(0)" ::: "memory");
;             if (q == 3) {
; #pragma unroll
;                 for (int r = 0; r < 4; ++r) STASH[256 * p + 16 * (grp + 4 * r) + pc] = f2bf(asc * (float)(2 * ((accH[r] << 4) + accL[r]) + sa));
;             }
;         }
;         CFENCE();
;         {
;             float4 v[4]; float ss = 0.f;
; #pragma unroll
;             for (int jq = 0; jq < 4; ++jq) { typedef unsigned u2v __attribute__((ext_vector_type(2))); const u2v pw = *(const LAS u2v*)(STASH + 4 * lane + 256 * jq); const uint2 hw = hv[jq];
;                 v[jq] = make_float4(__uint_as_float(hw.x << 16) + __uint_as_float(pw.x << 16), __uint_as_float(hw.x & 0xffff0000u) + __uint_as_float(pw.x & 0xffff0000u),
;                                     __uint_as_float(hw.y << 16) + __uint_as_float(pw.y << 16), __uint_as_float(hw.y & 0xffff0000u) + __uint_as_float(pw.y & 0xffff0000u));
;                 ss += v[jq].x * v[jq].x + v[jq].y * v[jq].y + v[jq].z * v[jq].z + v[jq].w * v[jq].w; }
;             ss = wave_sum(ss);
	v_dot8c_i32_i4_e32 v38, v122, v48
	v_dot8c_i32_i4_e32 v39, v122, v46
	v_dot8c_i32_i4_e32 v40, v124, v48
	v_dot8c_i32_i4_e32 v41, v124, v46
	v_dot8c_i32_i4_e32 v42, v126, v48
	v_dot8c_i32_i4_e32 v43, v126, v46
	v_dot8c_i32_i4_e32 v44, v128, v48
	v_dot8c_i32_i4_e32 v45, v128, v46
	v_dot8c_i32_i4_e32 v38, v123, v49
	v_dot8c_i32_i4_e32 v39, v123, v47
	v_dot8c_i32_i4_e32 v40, v125, v49
	v_dot8c_i32_i4_e32 v41, v125, v47
	v_dot8c_i32_i4_e32 v42, v127, v49
	v_dot8c_i32_i4_e32 v43, v127, v47
	v_dot8c_i32_i4_e32 v44, v129, v49
	v_dot8c_i32_i4_e32 v45, v129, v47
	v_and_b32_e32 v78, 0xffff, v30
	v_lshrrev_b32_e32 v79, 16, v30
	v_lshl_add_u32 v78, v78, 7, v150
	v_lshl_add_u32 v79, v79, 7, v151
	s_mov_b32 m0, s78
	s_add_i32 s43, s78, 0x400
	global_load_lds_dwordx4 v78, s[50:51]
	s_mov_b32 m0, s43
	s_nop 0
	global_load_lds_dwordx4 v79, s[50:51]
	s_waitcnt vmcnt(8)
	v_add_u32_e32 v54, s98, v59
	v_add_u32_e32 v55, s98, v60
	v_add_u32_e32 v56, s98, v61
	v_add_u32_e32 v57, s98, v62
	ds_read_b64_tr_b4 v[46:47], v160
	ds_read_b64_tr_b4 v[48:49], v160 offset:1024
	ds_read_b64_tr_b4 v[122:123], v54
	ds_read_b64_tr_b4 v[124:125], v55
	ds_read_b64_tr_b4 v[126:127], v56
	ds_read_b64_tr_b4 v[128:129], v57
	s_waitcnt lgkmcnt(6)
	v_dot8c_i32_i4_e32 v38, v130, v52
	v_dot8c_i32_i4_e32 v39, v130, v50
	v_dot8c_i32_i4_e32 v40, v132, v52
	v_dot8c_i32_i4_e32 v41, v132, v50
	v_dot8c_i32_i4_e32 v42, v134, v52
	v_dot8c_i32_i4_e32 v43, v134, v50
	v_dot8c_i32_i4_e32 v44, v136, v52
	v_dot8c_i32_i4_e32 v45, v136, v50
	v_dot8c_i32_i4_e32 v38, v131, v53
	v_dot8c_i32_i4_e32 v39, v131, v51
	v_dot8c_i32_i4_e32 v40, v133, v53
	v_dot8c_i32_i4_e32 v41, v133, v51
	v_dot8c_i32_i4_e32 v42, v135, v53
	v_dot8c_i32_i4_e32 v43, v135, v51
	v_dot8c_i32_i4_e32 v44, v137, v53
	v_dot8c_i32_i4_e32 v45, v137, v51
	s_nop 3
	s_waitcnt lgkmcnt(15)
	v_lshlrev_b32_e32 v38, 5, v38
	v_lshlrev_b32_e32 v39, 1, v39
	v_add3_u32 v38, v39, v229, v38
	v_cvt_f32_i32_e32 v38, v38
	v_mul_f32_e32 v38, v228, v38
	v_lshlrev_b32_e32 v40, 5, v40
	v_lshlrev_b32_e32 v41, 1, v41
	v_add3_u32 v40, v41, v229, v40
	v_cvt_f32_i32_e32 v40, v40
	v_mul_f32_e32 v40, v228, v40
	v_lshlrev_b32_e32 v42, 5, v42
	v_lshlrev_b32_e32 v43, 1, v43
	v_add3_u32 v42, v43, v229, v42
	v_cvt_f32_i32_e32 v42, v42
	v_mul_f32_e32 v42, v228, v42
	v_lshlrev_b32_e32 v44, 5, v44
	v_lshlrev_b32_e32 v45, 1, v45
	v_add3_u32 v44, v45, v229, v44
	v_cvt_f32_i32_e32 v44, v44
	v_mul_f32_e32 v44, v228, v44
	v_cvt_pk_bf16_f32 v162, v38, v40
	v_cvt_pk_bf16_f32 v163, v42, v44
	v_add_u32_e32 v147, 8, v140
	v_and_b32_e32 v146, 15, v147
	v_xor_b32_e32 v146, 8, v146
	v_bfe_u32 v148, v147, 4, 4
	v_mul_lo_u32 v146, v146, s92
	v_mul_lo_u32 v148, v148, s92
	v_mov_b32_e32 v147, v146
	v_mov_b32_e32 v149, v148
	ds_write2st64_b64 v77, v[146:147], v[148:149] offset1:2
	v_add_u32_e32 v138, 0x1000, v74
	ds_read_u8 v139, v138
	v_add_u32_e32 v141, 0x1000, v73
	ds_read_u8 v140, v141
	s_add_i32 s43, s67, 160
	v_mov_b32_e32 v138, s43
	ds_read2st64_b32 v[228:229], v138 offset1:1
	ds_read_b128 v[18:21], v227 offset:8192
	ds_read_b128 v[22:25], v227 offset:8208
	v_add_u32_e32 v152, 0x200000, v63
	v_add_u32_e32 v153, 0x200000, v64
	v_mov_b32_e32 v38, 0
	v_mov_b32_e32 v39, 0
	v_mov_b32_e32 v40, 0
	v_mov_b32_e32 v41, 0
	v_mov_b32_e32 v42, 0
	v_mov_b32_e32 v43, 0
	v_mov_b32_e32 v44, 0
	v_mov_b32_e32 v45, 0
	v_and_b32_e32 v78, 0xffff, v31
	v_lshrrev_b32_e32 v79, 16, v31
	v_lshl_add_u32 v78, v78, 7, v150
	v_lshl_add_u32 v79, v79, 7, v151
	s_mov_b32 m0, s79
	s_add_i32 s43, s79, 0x400
	global_load_lds_dwordx4 v78, s[50:51]
	s_mov_b32 m0, s43
	s_nop 0
	global_load_lds_dwordx4 v79, s[50:51]
	s_waitcnt vmcnt(8)
	v_add_u32_e32 v54, s99, v59
	v_add_u32_e32 v55, s99, v60
	v_add_u32_e32 v56, s99, v61
	v_add_u32_e32 v57, s99, v62
	ds_read_b64_tr_b4 v[50:51], v160 offset:128
	ds_read_b64_tr_b4 v[52:53], v160 offset:1152
	ds_read_b64_tr_b4 v[130:131], v54
	ds_read_b64_tr_b4 v[132:133], v55
	ds_read_b64_tr_b4 v[134:135], v56
	ds_read_b64_tr_b4 v[136:137], v57
	s_waitcnt lgkmcnt(12)
	s_waitcnt vmcnt(35) lgkmcnt(15)
	v_lshlrev_b32_e32 v210, 16, v194
	v_and_b32_e32 v211, 0xffff0000, v194
	v_lshlrev_b32_e32 v142, 16, v202
	v_and_b32_e32 v143, 0xffff0000, v202
	v_add_f32_e32 v210, v210, v142
	v_add_f32_e32 v211, v211, v143
	v_lshlrev_b32_e32 v212, 16, v195
	v_and_b32_e32 v213, 0xffff0000, v195
	v_lshlrev_b32_e32 v142, 16, v203
	v_and_b32_e32 v143, 0xffff0000, v203
	v_add_f32_e32 v212, v212, v142
	v_add_f32_e32 v213, v213, v143
	v_lshlrev_b32_e32 v214, 16, v196
	v_and_b32_e32 v215, 0xffff0000, v196
	v_lshlrev_b32_e32 v142, 16, v204
	v_and_b32_e32 v143, 0xffff0000, v204
	v_add_f32_e32 v214, v214, v142
	v_add_f32_e32 v215, v215, v143
	v_lshlrev_b32_e32 v216, 16, v197
	v_and_b32_e32 v217, 0xffff0000, v197
	v_lshlrev_b32_e32 v142, 16, v205
	v_and_b32_e32 v143, 0xffff0000, v205
	v_add_f32_e32 v216, v216, v142
	v_add_f32_e32 v217, v217, v143
	v_lshlrev_b32_e32 v218, 16, v198
	v_and_b32_e32 v219, 0xffff0000, v198
	v_lshlrev_b32_e32 v142, 16, v206
	v_and_b32_e32 v143, 0xffff0000, v206
	v_add_f32_e32 v218, v218, v142
	v_add_f32_e32 v219, v219, v143
	v_lshlrev_b32_e32 v220, 16, v199
	v_and_b32_e32 v221, 0xffff0000, v199
	v_lshlrev_b32_e32 v142, 16, v207
	v_and_b32_e32 v143, 0xffff0000, v207
	v_add_f32_e32 v220, v220, v142
	v_add_f32_e32 v221, v221, v143
	v_lshlrev_b32_e32 v222, 16, v200
	v_and_b32_e32 v223, 0xffff0000, v200
	v_lshlrev_b32_e32 v142, 16, v208
	v_and_b32_e32 v143, 0xffff0000, v208
	v_add_f32_e32 v222, v222, v142
	v_add_f32_e32 v223, v223, v143
	v_lshlrev_b32_e32 v224, 16, v201
	v_and_b32_e32 v225, 0xffff0000, v201
	v_lshlrev_b32_e32 v142, 16, v209
	v_and_b32_e32 v143, 0xffff0000, v209
	v_add_f32_e32 v224, v224, v142
; #define LAS __attribute__((address_space(3)))
; #define TR4(p_) __builtin_amdgcn_ds_read_tr4_b64_v2i32((LAS v2i*)(p_))
; __device__ __forceinline__ void peer_v_tokens(int j, const LAS unsigned short* EL, const LAS unsigned char* AL  , const LAS float* ASC  , const LAS int* SAL  , ...
;     ...
;             if (st < 14) VDMA(st + 2, (st + 2) % 3);
;             if (st < 14) asm volatile("s_waitcnt vmcnt(8)" ::: "memory");
;             else if (st == 14) asm volatile("s_waitcnt vmcnt(4)" ::: "memory");
;             else asm volatile("s_waitcnt vmcnt(0)" ::: "memory");
;             if (q == 0) {
; #pragma unroll
;                 for (int r = 0; r < 4; ++r) { accH[r] = 0; accL[r] = 0; } }
; #pragma unroll
;             for (int tp = 0; tp < 2; ++tp) {
;                 const v2i ao = TR4(ATL + (2 * q + tp) * 128 + 8 * s16), ah = TR4(ATL + 1024 + (2 * q + tp) * 128 + 8 * s16);
; #pragma unroll
;                 for (int r = 0; r < 4; ++r) {
;                     const v2i d = TR4(ldsb + BUF[st % 3] + 2048 * tp + roff[r]);
;                     accH[r] = __builtin_amdgcn_sdot8(d.x, ah.x, accH[r], false); accH[r] = __builtin_amdgcn_sdot8(d.y, ah.y, accH[r], false);
;                     accL[r] = __builtin_amdgcn_sdot8(d.x, ao.x, accL[r], false); accL[r] = __builtin_amdgcn_sdot8(d.y, ao.y, accL[r], false);
;                 }
;     ...
;         {
;             float4 v[4]; float ss = 0.f;
; #pragma unroll
;             for (int jq = 0; jq < 4; ++jq) { typedef unsigned u2v __attribute__((ext_vector_type(2))); const u2v pw = *(const LAS u2v*)(STASH + 4 * lane + 256 * jq); const uint2 hw = hv[jq];
;                 v[jq] = make_float4(__uint_as_float(hw.x << 16) + __uint_as_float(pw.x << 16), __uint_as_float(hw.x & 0xffff0000u) + __uint_as_float(pw.x & 0xffff0000u),
;                                     __uint_as_float(hw.y << 16) + __uint_as_float(pw.y << 16), __uint_as_float(hw.y & 0xffff0000u) + __uint_as_float(pw.y & 0xffff0000u));
;                 ss += v[jq].x * v[jq].x + v[jq].y * v[jq].y + v[jq].z * v[jq].z + v[jq].w * v[jq].w; }
;             ss = wave_sum(ss);
;             const float r3 = rsqrtf(ss * (1.f / D) + EPS);
	v_add_f32_e32 v225, v225, v143
	v_mov_b32_e32 v144, 0
	v_mul_f32_e32 v145, v210, v210
	v_fmac_f32_e32 v145, v211, v211
	v_fmac_f32_e32 v145, v212, v212
	v_fmac_f32_e32 v145, v213, v213
	v_add_f32_e32 v144, v144, v145
	v_mul_f32_e32 v145, v214, v214
	v_fmac_f32_e32 v145, v215, v215
	v_fmac_f32_e32 v145, v216, v216
	v_fmac_f32_e32 v145, v217, v217
	v_add_f32_e32 v144, v144, v145
	v_mul_f32_e32 v145, v218, v218
	v_fmac_f32_e32 v145, v219, v219
	v_fmac_f32_e32 v145, v220, v220
	v_fmac_f32_e32 v145, v221, v221
	v_add_f32_e32 v144, v144, v145
	v_mul_f32_e32 v145, v222, v222
	v_fmac_f32_e32 v145, v223, v223
	v_fmac_f32_e32 v145, v224, v224
	v_fmac_f32_e32 v145, v225, v225
	v_add_f32_e32 v144, v144, v145
	s_nop 1
	v_add_f32_dpp v144, v144, v144 quad_perm:[1,0,3,2] row_mask:0xf bank_mask:0xf bound_ctrl:1
	s_nop 1
	v_add_f32_dpp v144, v144, v144 quad_perm:[2,3,0,1] row_mask:0xf bank_mask:0xf bound_ctrl:1
	s_nop 1
	v_add_f32_dpp v144, v144, v144 row_half_mirror row_mask:0xf bank_mask:0xf bound_ctrl:1
	s_nop 1
	v_add_f32_dpp v144, v144, v144 row_mirror row_mask:0xf bank_mask:0xf bound_ctrl:1
	s_nop 1
	v_readlane_b32 s10, v144, 0
	v_readlane_b32 s11, v144, 16
	v_readlane_b32 s14, v144, 32
	v_readlane_b32 s15, v144, 48
	s_nop 3
	v_mov_b32_e32 v144, s11
	v_mov_b32_e32 v145, s15
	v_add_f32_e32 v144, s10, v144
	v_add_f32_e32 v145, s14, v145
	v_add_f32_e32 v144, v144, v145
	v_fmamk_f32 v144, v144, 0x3a800000, v111
	v_rsq_f32_e32 v144, v144
	s_nop 0
	v_mul_f32_e32 v210, v210, v144
	v_mul_f32_e32 v211, v211, v144
	v_mul_f32_e32 v212, v212, v144
	v_mul_f32_e32 v213, v213, v144
	v_mul_f32_e32 v214, v214, v144
	v_mul_f32_e32 v215, v215, v144
	v_mul_f32_e32 v216, v216, v144
	v_mul_f32_e32 v217, v217, v144
	v_mul_f32_e32 v218, v218, v144
	v_mul_f32_e32 v219, v219, v144
	v_mul_f32_e32 v220, v220, v144
	v_mul_f32_e32 v221, v221, v144
	v_mul_f32_e32 v222, v222, v144
	v_mul_f32_e32 v223, v223, v144
	v_mul_f32_e32 v224, v224, v144
	v_mul_f32_e32 v225, v225, v144
	v_dot8c_i32_i4_e32 v38, v122, v48
	v_dot8c_i32_i4_e32 v39, v122, v46
	v_dot8c_i32_i4_e32 v40, v124, v48
	v_dot8c_i32_i4_e32 v41, v124, v46
	v_dot8c_i32_i4_e32 v42, v126, v48
	v_dot8c_i32_i4_e32 v43, v126, v46
	v_dot8c_i32_i4_e32 v44, v128, v48
	v_dot8c_i32_i4_e32 v45, v128, v46
	v_dot8c_i32_i4_e32 v38, v123, v49
	v_dot8c_i32_i4_e32 v39, v123, v47
	v_dot8c_i32_i4_e32 v40, v125, v49
	v_dot8c_i32_i4_e32 v41, v125, v47
	v_dot8c_i32_i4_e32 v42, v127, v49
	v_dot8c_i32_i4_e32 v43, v127, v47
	v_dot8c_i32_i4_e32 v44, v129, v49
	v_dot8c_i32_i4_e32 v45, v129, v47
	v_and_b32_e32 v78, 0xffff, v32
	v_lshrrev_b32_e32 v79, 16, v32
	v_lshl_add_u32 v78, v78, 7, v150
	v_lshl_add_u32 v79, v79, 7, v151
	s_mov_b32 m0, s98
	s_add_i32 s43, s98, 0x400
	global_load_lds_dwordx4 v78, s[50:51]
	s_mov_b32 m0, s43
	s_nop 0
	global_load_lds_dwordx4 v79, s[50:51]
	s_waitcnt vmcnt(8)
	v_add_u32_e32 v54, s76, v59
	v_add_u32_e32 v55, s76, v60
	v_add_u32_e32 v56, s76, v61
	v_add_u32_e32 v57, s76, v62
	ds_read_b64_tr_b4 v[46:47], v160 offset:256
	ds_read_b64_tr_b4 v[48:49], v160 offset:1280
	ds_read_b64_tr_b4 v[122:123], v54
	ds_read_b64_tr_b4 v[124:125], v55
	ds_read_b64_tr_b4 v[126:127], v56
	ds_read_b64_tr_b4 v[128:129], v57
	s_waitcnt lgkmcnt(6)
	v_dot8c_i32_i4_e32 v38, v130, v52
	v_dot8c_i32_i4_e32 v39, v130, v50
	v_dot8c_i32_i4_e32 v40, v132, v52
	v_dot8c_i32_i4_e32 v41, v132, v50
	v_dot8c_i32_i4_e32 v42, v134, v52
	v_dot8c_i32_i4_e32 v43, v134, v50
	v_dot8c_i32_i4_e32 v44, v136, v52
	v_dot8c_i32_i4_e32 v45, v136, v50
	v_dot8c_i32_i4_e32 v38, v131, v53
	v_dot8c_i32_i4_e32 v39, v131, v51
	v_dot8c_i32_i4_e32 v40, v133, v53
	v_dot8c_i32_i4_e32 v41, v133, v51
	v_dot8c_i32_i4_e32 v42, v135, v53
	v_dot8c_i32_i4_e32 v43, v135, v51
	v_dot8c_i32_i4_e32 v44, v137, v53
	v_dot8c_i32_i4_e32 v45, v137, v51
	v_and_b32_e32 v78, 0xffff, v33
	v_lshrrev_b32_e32 v79, 16, v33
	v_lshl_add_u32 v78, v78, 7, v150
	v_lshl_add_u32 v79, v79, 7, v151
	s_mov_b32 m0, s99
	s_add_i32 s43, s99, 0x400
	global_load_lds_dwordx4 v78, s[50:51]
	s_mov_b32 m0, s43
	s_nop 0
	global_load_lds_dwordx4 v79, s[50:51]
	s_waitcnt vmcnt(8)
	v_add_u32_e32 v54, s77, v59
	v_add_u32_e32 v55, s77, v60
	v_add_u32_e32 v56, s77, v61
	v_add_u32_e32 v57, s77, v62
	ds_read_b64_tr_b4 v[50:51], v160 offset:384
	ds_read_b64_tr_b4 v[52:53], v160 offset:1408
	ds_read_b64_tr_b4 v[130:131], v54
	ds_read_b64_tr_b4 v[132:133], v55
	ds_read_b64_tr_b4 v[134:135], v56
	ds_read_b64_tr_b4 v[136:137], v57
	s_waitcnt lgkmcnt(6)
	v_dot8c_i32_i4_e32 v38, v122, v48
	v_dot8c_i32_i4_e32 v39, v122, v46
	v_dot8c_i32_i4_e32 v40, v124, v48
	v_dot8c_i32_i4_e32 v41, v124, v46
	v_dot8c_i32_i4_e32 v42, v126, v48
	v_dot8c_i32_i4_e32 v43, v126, v46
	v_dot8c_i32_i4_e32 v44, v128, v48
	v_dot8c_i32_i4_e32 v45, v128, v46
	v_dot8c_i32_i4_e32 v38, v123, v49
	v_dot8c_i32_i4_e32 v39, v123, v47
	v_dot8c_i32_i4_e32 v40, v125, v49
	v_dot8c_i32_i4_e32 v41, v125, v47
	v_dot8c_i32_i4_e32 v42, v127, v49
	v_dot8c_i32_i4_e32 v43, v127, v47
	v_dot8c_i32_i4_e32 v44, v129, v49
	v_dot8c_i32_i4_e32 v45, v129, v47
	s_waitcnt lgkmcnt(15)
	v_and_b32_e32 v78, 0xffff, v18
	v_lshrrev_b32_e32 v79, 16, v18
	v_lshl_add_u32 v78, v78, 7, v152
	v_lshl_add_u32 v79, v79, 7, v153
	s_mov_b32 m0, s76
	s_add_i32 s43, s76, 0x400
	global_load_lds_dwordx4 v78, s[50:51]
	s_mov_b32 m0, s43
	s_nop 0
	global_load_lds_dwordx4 v79, s[50:51]
	s_waitcnt vmcnt(8)
	v_add_u32_e32 v54, s78, v59
	v_add_u32_e32 v55, s78, v60
	v_add_u32_e32 v56, s78, v61
	v_add_u32_e32 v57, s78, v62
	ds_read_b64_tr_b4 v[46:47], v160 offset:512
	ds_read_b64_tr_b4 v[48:49], v160 offset:1536
	ds_read_b64_tr_b4 v[122:123], v54
	ds_read_b64_tr_b4 v[124:125], v55
	ds_read_b64_tr_b4 v[126:127], v56
	ds_read_b64_tr_b4 v[128:129], v57
	s_waitcnt lgkmcnt(6)
; #define TR4(p_) __builtin_amdgcn_ds_read_tr4_b64_v2i32((LAS v2i*)(p_))
; #define VDMA(st_, k_) do { _Pragma("unroll") for (int i_ = 0; i_ < 4; ++i_) { \
;         const unsigned off_ = (unsigned)((st_) >> 2) * (16384u * 128u) + (PE_ID(E, 4 * ((st_) & 3) + i_) << 7) + ((i_ & 1) ? cx1 : cx0); \
;         __builtin_amdgcn_global_load_lds((const unsigned*)(V4 + off_), (LAS unsigned*)(ldsb + BUF[k_] + 1024 * i_), 16, 0, 0); } } while (0)
; __device__ __forceinline__ void peer_v_tokens(int j, const LAS unsigned short* EL, const LAS unsigned char* AL  , const LAS float* ASC  , const LAS int* SAL  , ...
;     ...
;             if (st < 14) VDMA(st + 2, (st + 2) % 3);
;             if (st < 14) asm volatile("s_waitcnt vmcnt(8)" ::: "memory");
;             else if (st == 14) asm volatile("s_waitcnt vmcnt(4)" ::: "memory");
;             else asm volatile("s_waitcnt vmcnt(0)" ::: "memory");
;             if (q == 0) {
; #pragma unroll
;                 for (int r = 0; r < 4; ++r) { accH[r] = 0; accL[r] = 0; } }
; #pragma unroll
;             for (int tp = 0; tp < 2; ++tp) {
;                 const v2i ao = TR4(ATL + (2 * q + tp) * 128 + 8 * s16), ah = TR4(ATL + 1024 + (2 * q + tp) * 128 + 8 * s16);
; #pragma unroll
;                 for (int r = 0; r < 4; ++r) {
;                     const v2i d = TR4(ldsb + BUF[st % 3] + 2048 * tp + roff[r]);
;                     accH[r] = __builtin_amdgcn_sdot8(d.x, ah.x, accH[r], false); accH[r] = __builtin_amdgcn_sdot8(d.y, ah.y, accH[r], false);
;                     accL[r] = __builtin_amdgcn_sdot8(d.x, ao.x, accL[r], false); accL[r] = __builtin_amdgcn_sdot8(d.y, ao.y, accL[r], false);
;                 }
	v_dot8c_i32_i4_e32 v38, v130, v52
	v_dot8c_i32_i4_e32 v39, v130, v50
	v_dot8c_i32_i4_e32 v40, v132, v52
	v_dot8c_i32_i4_e32 v41, v132, v50
	v_dot8c_i32_i4_e32 v42, v134, v52
	v_dot8c_i32_i4_e32 v43, v134, v50
	v_dot8c_i32_i4_e32 v44, v136, v52
	v_dot8c_i32_i4_e32 v45, v136, v50
	v_dot8c_i32_i4_e32 v38, v131, v53
	v_dot8c_i32_i4_e32 v39, v131, v51
	v_dot8c_i32_i4_e32 v40, v133, v53
	v_dot8c_i32_i4_e32 v41, v133, v51
	v_dot8c_i32_i4_e32 v42, v135, v53
	v_dot8c_i32_i4_e32 v43, v135, v51
	v_dot8c_i32_i4_e32 v44, v137, v53
	v_dot8c_i32_i4_e32 v45, v137, v51
	v_and_b32_e32 v78, 0xffff, v19
	v_lshrrev_b32_e32 v79, 16, v19
	v_lshl_add_u32 v78, v78, 7, v152
	v_lshl_add_u32 v79, v79, 7, v153
	s_mov_b32 m0, s77
	s_add_i32 s43, s77, 0x400
	global_load_lds_dwordx4 v78, s[50:51]
	s_mov_b32 m0, s43
	s_nop 0
	global_load_lds_dwordx4 v79, s[50:51]
	s_waitcnt vmcnt(8)
	v_add_u32_e32 v54, s79, v59
	v_add_u32_e32 v55, s79, v60
	v_add_u32_e32 v56, s79, v61
	v_add_u32_e32 v57, s79, v62
	ds_read_b64_tr_b4 v[50:51], v160 offset:640
	ds_read_b64_tr_b4 v[52:53], v160 offset:1664
	ds_read_b64_tr_b4 v[130:131], v54
	ds_read_b64_tr_b4 v[132:133], v55
	ds_read_b64_tr_b4 v[134:135], v56
	ds_read_b64_tr_b4 v[136:137], v57
	s_waitcnt lgkmcnt(6)
	v_dot8c_i32_i4_e32 v38, v122, v48
	v_dot8c_i32_i4_e32 v39, v122, v46
	v_dot8c_i32_i4_e32 v40, v124, v48
	v_dot8c_i32_i4_e32 v41, v124, v46
	v_dot8c_i32_i4_e32 v42, v126, v48
	v_dot8c_i32_i4_e32 v43, v126, v46
	v_dot8c_i32_i4_e32 v44, v128, v48
	v_dot8c_i32_i4_e32 v45, v128, v46
	v_dot8c_i32_i4_e32 v38, v123, v49
	v_dot8c_i32_i4_e32 v39, v123, v47
	v_dot8c_i32_i4_e32 v40, v125, v49
	v_dot8c_i32_i4_e32 v41, v125, v47
	v_dot8c_i32_i4_e32 v42, v127, v49
	v_dot8c_i32_i4_e32 v43, v127, v47
	v_dot8c_i32_i4_e32 v44, v129, v49
	v_dot8c_i32_i4_e32 v45, v129, v47
	s_waitcnt lgkmcnt(15)
	v_add_u32_e32 v143, 8, v139
	v_and_b32_e32 v142, 15, v143
	v_xor_b32_e32 v142, 8, v142
	v_bfe_u32 v144, v143, 4, 4
	v_mul_lo_u32 v142, v142, s92
	v_mul_lo_u32 v144, v144, s92
	v_mov_b32_e32 v143, v142
	v_mov_b32_e32 v145, v144
	ds_write2st64_b64 v159, v[142:143], v[144:145] offset1:2
	v_and_b32_e32 v78, 0xffff, v20
	v_lshrrev_b32_e32 v79, 16, v20
	v_lshl_add_u32 v78, v78, 7, v152
	v_lshl_add_u32 v79, v79, 7, v153
	s_mov_b32 m0, s78
	s_add_i32 s43, s78, 0x400
	global_load_lds_dwordx4 v78, s[50:51]
	s_mov_b32 m0, s43
	s_nop 0
	global_load_lds_dwordx4 v79, s[50:51]
	s_waitcnt vmcnt(8)
	v_add_u32_e32 v54, s98, v59
	v_add_u32_e32 v55, s98, v60
	v_add_u32_e32 v56, s98, v61
	v_add_u32_e32 v57, s98, v62
	ds_read_b64_tr_b4 v[46:47], v160 offset:768
	ds_read_b64_tr_b4 v[48:49], v160 offset:1792
	ds_read_b64_tr_b4 v[122:123], v54
	ds_read_b64_tr_b4 v[124:125], v55
	ds_read_b64_tr_b4 v[126:127], v56
	ds_read_b64_tr_b4 v[128:129], v57
	s_waitcnt lgkmcnt(7)
	v_dot8c_i32_i4_e32 v38, v130, v52
	v_dot8c_i32_i4_e32 v39, v130, v50
	v_dot8c_i32_i4_e32 v40, v132, v52
	v_dot8c_i32_i4_e32 v41, v132, v50
	v_dot8c_i32_i4_e32 v42, v134, v52
	v_dot8c_i32_i4_e32 v43, v134, v50
	v_dot8c_i32_i4_e32 v44, v136, v52
	v_dot8c_i32_i4_e32 v45, v136, v50
	v_dot8c_i32_i4_e32 v38, v131, v53
	v_dot8c_i32_i4_e32 v39, v131, v51
	v_dot8c_i32_i4_e32 v40, v133, v53
	v_dot8c_i32_i4_e32 v41, v133, v51
	v_dot8c_i32_i4_e32 v42, v135, v53
	v_dot8c_i32_i4_e32 v43, v135, v51
	v_dot8c_i32_i4_e32 v44, v137, v53
	v_dot8c_i32_i4_e32 v45, v137, v51
	v_and_b32_e32 v78, 0xffff, v21
	v_lshrrev_b32_e32 v79, 16, v21
	v_lshl_add_u32 v78, v78, 7, v152
	v_lshl_add_u32 v79, v79, 7, v153
	s_mov_b32 m0, s79
	s_add_i32 s43, s79, 0x400
	global_load_lds_dwordx4 v78, s[50:51]
	s_mov_b32 m0, s43
	s_nop 0
	global_load_lds_dwordx4 v79, s[50:51]
	s_waitcnt vmcnt(8)
	v_add_u32_e32 v54, s99, v59
	v_add_u32_e32 v55, s99, v60
	v_add_u32_e32 v56, s99, v61
	v_add_u32_e32 v57, s99, v62
	ds_read_b64_tr_b4 v[50:51], v160 offset:896
	ds_read_b64_tr_b4 v[52:53], v160 offset:1920
	ds_read_b64_tr_b4 v[130:131], v54
	ds_read_b64_tr_b4 v[132:133], v55
	ds_read_b64_tr_b4 v[134:135], v56
	ds_read_b64_tr_b4 v[136:137], v57
	s_waitcnt lgkmcnt(6)
	v_dot8c_i32_i4_e32 v38, v122, v48
	v_dot8c_i32_i4_e32 v39, v122, v46
	v_dot8c_i32_i4_e32 v40, v124, v48
	v_dot8c_i32_i4_e32 v41, v124, v46
	v_dot8c_i32_i4_e32 v42, v126, v48
	v_dot8c_i32_i4_e32 v43, v126, v46
	v_dot8c_i32_i4_e32 v44, v128, v48
	v_dot8c_i32_i4_e32 v45, v128, v46
	v_dot8c_i32_i4_e32 v38, v123, v49
	v_dot8c_i32_i4_e32 v39, v123, v47
	v_dot8c_i32_i4_e32 v40, v125, v49
	v_dot8c_i32_i4_e32 v41, v125, v47
	v_dot8c_i32_i4_e32 v42, v127, v49
	v_dot8c_i32_i4_e32 v43, v127, v47
	v_dot8c_i32_i4_e32 v44, v129, v49
	v_dot8c_i32_i4_e32 v45, v129, v47
	v_and_b32_e32 v78, 0xffff, v22
	v_lshrrev_b32_e32 v79, 16, v22
	v_lshl_add_u32 v78, v78, 7, v152
	v_lshl_add_u32 v79, v79, 7, v153
	s_mov_b32 m0, s98
	s_add_i32 s43, s98, 0x400
	global_load_lds_dwordx4 v78, s[50:51]
	s_mov_b32 m0, s43
	s_nop 0
	global_load_lds_dwordx4 v79, s[50:51]
	s_waitcnt vmcnt(8)
	v_add_u32_e32 v54, s76, v59
	v_add_u32_e32 v55, s76, v60
	v_add_u32_e32 v56, s76, v61
	v_add_u32_e32 v57, s76, v62
	ds_read_b64_tr_b4 v[46:47], v160
	ds_read_b64_tr_b4 v[48:49], v160 offset:1024
	ds_read_b64_tr_b4 v[122:123], v54
	ds_read_b64_tr_b4 v[124:125], v55
	ds_read_b64_tr_b4 v[126:127], v56
	ds_read_b64_tr_b4 v[128:129], v57
	s_waitcnt lgkmcnt(6)
	v_dot8c_i32_i4_e32 v38, v130, v52
	v_dot8c_i32_i4_e32 v39, v130, v50
	v_dot8c_i32_i4_e32 v40, v132, v52
	v_dot8c_i32_i4_e32 v41, v132, v50
	v_dot8c_i32_i4_e32 v42, v134, v52
	v_dot8c_i32_i4_e32 v43, v134, v50
	v_dot8c_i32_i4_e32 v44, v136, v52
	v_dot8c_i32_i4_e32 v45, v136, v50
	v_dot8c_i32_i4_e32 v38, v131, v53
	v_dot8c_i32_i4_e32 v39, v131, v51
	v_dot8c_i32_i4_e32 v40, v133, v53
	v_dot8c_i32_i4_e32 v41, v133, v51
	v_dot8c_i32_i4_e32 v42, v135, v53
	v_dot8c_i32_i4_e32 v43, v135, v51
	v_dot8c_i32_i4_e32 v44, v137, v53
	v_dot8c_i32_i4_e32 v45, v137, v51
	s_nop 3
	s_waitcnt lgkmcnt(15)
; __device__ __forceinline__ void peer_v_tokens(int j, const LAS unsigned short* EL, const LAS unsigned char* AL  , const LAS float* ASC  , const LAS int* SAL  , ...
;     ...
; #pragma unroll 1
;     for (int it = 0; it < 8; ++it) {
;         const int tl = it * 8 + wave, t = j * 64 + tl;
;         unsigned E[8];
;         { const LAS v4u* ep = (const LAS v4u*)(EL + tl * 128 + 16 * g); const v4u e0 = ep[0], e1 = ep[1];
;           E[0] = e0.x; E[1] = e0.y; E[2] = e0.z; E[3] = e0.w; E[4] = e1.x; E[5] = e1.y; E[6] = e1.z; E[7] = e1.w; }
;         uint2 hv[4]; float4 gv[4];
;         { unsigned ho = (unsigned)t * (D / 4) + (unsigned)lane; asm volatile("" : "+v"(ho)); const uint2* hp = (const uint2*)HB + ho; const float4* gp = (const float4*)fng + lane;
; #pragma unroll
;           for (int jq = 0; jq < 4; ++jq) { hv[jq] = hp[64 * jq]; gv[jq] = gp[64 * jq]; } }
;         VDMA(0, 0); VDMA(1, 1);
; #pragma unroll
;         for (int m = 0; m < 2; ++m) {
;             const int idx = lane + 64 * m, tau = idx >> 4, sr = idx & 15, k = 16 * (sr & 7) + 2 * tau + (sr >> 3);
;             const int aq = (int)*(const LAS signed char*)(AL + tl * 128 + k); const int tq = aq + 8;
;             const unsigned lo = (((unsigned)tq & 15u) ^ 8u) * 0x11111111u, hi = ((unsigned)(tq >> 4) & 15u) * 0x11111111u;
;             typedef unsigned u2v __attribute__((ext_vector_type(2)));
;             u2v l2; l2.x = lo; l2.y = lo; u2v h2; h2.x = hi; h2.y = hi;
;             *(LAS u2v*)(ATL + 8 * idx) = l2; *(LAS u2v*)(ATL + 1024 + 8 * idx) = h2;
;         }
;         const float asc = ASC[tl]; const int sa = SAL[tl];
;         CFENCE();
;         int accH[4], accL[4];
; #pragma unroll
;         for (int st = 0; st < 16; ++st) {
;             const int p = st >> 2, q = st & 3;
;             if (st < 14) VDMA(st + 2, (st + 2) % 3);
;             if (st < 14) asm volatile("s_waitcnt vmcnt(8)" ::: "memory");
;             else if (st == 14) asm volatile("s_waitcnt vmcnt(4)" ::: "memory");
;             else asm volatile("s_waitcnt vmcnt(0)" ::: "memory");
;             if (q == 0) {
; #pragma unroll
;                 for (int r = 0; r < 4; ++r) { accH[r] = 0; accL[r] = 0; } }
; #pragma unroll
;             for (int tp = 0; tp < 2; ++tp) {
;                 const v2i ao = TR4(ATL + (2 * q + tp) * 128 + 8 * s16), ah = TR4(ATL + 1024 + (2 * q + tp) * 128 + 8 * s16);
; #pragma unroll
	v_lshlrev_b32_e32 v38, 5, v38
	v_lshlrev_b32_e32 v39, 1, v39
	v_add3_u32 v38, v39, v229, v38
	v_cvt_f32_i32_e32 v38, v38
	v_mul_f32_e32 v38, v228, v38
	v_lshlrev_b32_e32 v40, 5, v40
	v_lshlrev_b32_e32 v41, 1, v41
	v_add3_u32 v40, v41, v229, v40
	v_cvt_f32_i32_e32 v40, v40
	v_mul_f32_e32 v40, v228, v40
	v_lshlrev_b32_e32 v42, 5, v42
	v_lshlrev_b32_e32 v43, 1, v43
	v_add3_u32 v42, v43, v229, v42
	v_cvt_f32_i32_e32 v42, v42
	v_mul_f32_e32 v42, v228, v42
	v_lshlrev_b32_e32 v44, 5, v44
	v_lshlrev_b32_e32 v45, 1, v45
	v_add3_u32 v44, v45, v229, v44
	v_cvt_f32_i32_e32 v44, v44
	v_mul_f32_e32 v44, v228, v44
	v_cvt_pk_bf16_f32 v170, v38, v40
	v_cvt_pk_bf16_f32 v171, v42, v44
	ds_read_b128 v[252:255], v155
	s_add_i32 s44, s40, 16
	s_ashr_i32 s45, s44, 31
	s_lshl_b64 s[44:45], s[44:45], 12
	v_lshl_add_u64 v[80:81], v[36:37], 0, s[44:45]
	s_waitcnt lgkmcnt(0)
	v_mul_f32_e32 v210, v210, v252
	v_mul_f32_e32 v211, v211, v253
	v_mul_f32_e32 v212, v212, v254
	v_mul_f32_e32 v213, v213, v255
	global_store_dwordx4 v[80:81], v[210:213], off nt
	s_add_i32 s43, s40, 24
	s_lshl_b32 s43, s43, 11
	v_add_u32_e32 v138, s43, v66
	global_load_dwordx2 v[194:195], v138, s[70:71]
	global_load_dwordx2 v[196:197], v138, s[70:71] offset:512
	global_load_dwordx2 v[198:199], v138, s[70:71] offset:1024
	global_load_dwordx2 v[200:201], v138, s[70:71] offset:1536
	v_add_u32_e32 v147, 8, v140
	v_and_b32_e32 v146, 15, v147
	v_xor_b32_e32 v146, 8, v146
	v_bfe_u32 v148, v147, 4, 4
	v_mul_lo_u32 v146, v146, s92
	v_mul_lo_u32 v148, v148, s92
	v_mov_b32_e32 v147, v146
	v_mov_b32_e32 v149, v148
	ds_write2st64_b64 v77, v[146:147], v[148:149] offset1:2
	v_add_u32_e32 v138, 0x1400, v74
	ds_read_u8 v139, v138
	v_add_u32_e32 v141, 0x1400, v73
	ds_read_u8 v140, v141
	s_add_i32 s43, s67, 128
	v_mov_b32_e32 v138, s43
	ds_read2st64_b32 v[228:229], v138 offset1:1
	ds_read_b128 v[26:29], v227 offset:10240
	ds_read_b128 v[30:33], v227 offset:10256
	v_mov_b32_e32 v38, 0
	v_mov_b32_e32 v39, 0
	v_mov_b32_e32 v40, 0
	v_mov_b32_e32 v41, 0
	v_mov_b32_e32 v42, 0
	v_mov_b32_e32 v43, 0
	v_mov_b32_e32 v44, 0
	v_mov_b32_e32 v45, 0
	v_and_b32_e32 v78, 0xffff, v23
	v_lshrrev_b32_e32 v79, 16, v23
	v_lshl_add_u32 v78, v78, 7, v152
	v_lshl_add_u32 v79, v79, 7, v153
	s_mov_b32 m0, s99
	s_add_i32 s43, s99, 0x400
	global_load_lds_dwordx4 v78, s[50:51]
	s_mov_b32 m0, s43
	s_nop 0
	global_load_lds_dwordx4 v79, s[50:51]
	s_waitcnt vmcnt(13)
	v_add_u32_e32 v54, s77, v59
	v_add_u32_e32 v55, s77, v60
	v_add_u32_e32 v56, s77, v61
	v_add_u32_e32 v57, s77, v62
	ds_read_b64_tr_b4 v[50:51], v160 offset:128
	ds_read_b64_tr_b4 v[52:53], v160 offset:1152
	ds_read_b64_tr_b4 v[130:131], v54
	ds_read_b64_tr_b4 v[132:133], v55
	ds_read_b64_tr_b4 v[134:135], v56
	ds_read_b64_tr_b4 v[136:137], v57
	s_waitcnt lgkmcnt(13)
	v_dot8c_i32_i4_e32 v38, v122, v48
	v_dot8c_i32_i4_e32 v39, v122, v46
	v_dot8c_i32_i4_e32 v40, v124, v48
	v_dot8c_i32_i4_e32 v41, v124, v46
	v_dot8c_i32_i4_e32 v42, v126, v48
	v_dot8c_i32_i4_e32 v43, v126, v46
	v_dot8c_i32_i4_e32 v44, v128, v48
	v_dot8c_i32_i4_e32 v45, v128, v46
	v_dot8c_i32_i4_e32 v38, v123, v49
	v_dot8c_i32_i4_e32 v39, v123, v47
	v_dot8c_i32_i4_e32 v40, v125, v49
	v_dot8c_i32_i4_e32 v41, v125, v47
	v_dot8c_i32_i4_e32 v42, v127, v49
	v_dot8c_i32_i4_e32 v43, v127, v47
	v_dot8c_i32_i4_e32 v44, v129, v49
	v_dot8c_i32_i4_e32 v45, v129, v47
	v_and_b32_e32 v78, 0xffff, v24
	v_lshrrev_b32_e32 v79, 16, v24
	v_lshl_add_u32 v78, v78, 7, v152
	v_lshl_add_u32 v79, v79, 7, v153
	s_mov_b32 m0, s76
	s_add_i32 s43, s76, 0x400
	global_load_lds_dwordx4 v78, s[50:51]
	s_mov_b32 m0, s43
	s_nop 0
	global_load_lds_dwordx4 v79, s[50:51]
	s_waitcnt vmcnt(13)
	v_add_u32_e32 v54, s78, v59
	v_add_u32_e32 v55, s78, v60
	v_add_u32_e32 v56, s78, v61
	v_add_u32_e32 v57, s78, v62
	ds_read_b64_tr_b4 v[46:47], v160 offset:256
	ds_read_b64_tr_b4 v[48:49], v160 offset:1280
	ds_read_b64_tr_b4 v[122:123], v54
	ds_read_b64_tr_b4 v[124:125], v55
	ds_read_b64_tr_b4 v[126:127], v56
	ds_read_b64_tr_b4 v[128:129], v57
	s_waitcnt lgkmcnt(6)
	v_dot8c_i32_i4_e32 v38, v130, v52
	v_dot8c_i32_i4_e32 v39, v130, v50
	v_dot8c_i32_i4_e32 v40, v132, v52
	v_dot8c_i32_i4_e32 v41, v132, v50
	v_dot8c_i32_i4_e32 v42, v134, v52
	v_dot8c_i32_i4_e32 v43, v134, v50
	v_dot8c_i32_i4_e32 v44, v136, v52
	v_dot8c_i32_i4_e32 v45, v136, v50
	v_dot8c_i32_i4_e32 v38, v131, v53
	v_dot8c_i32_i4_e32 v39, v131, v51
	v_dot8c_i32_i4_e32 v40, v133, v53
	v_dot8c_i32_i4_e32 v41, v133, v51
	v_dot8c_i32_i4_e32 v42, v135, v53
	v_dot8c_i32_i4_e32 v43, v135, v51
	v_dot8c_i32_i4_e32 v44, v137, v53
	v_dot8c_i32_i4_e32 v45, v137, v51
	v_and_b32_e32 v78, 0xffff, v25
	v_lshrrev_b32_e32 v79, 16, v25
	v_lshl_add_u32 v78, v78, 7, v152
	v_lshl_add_u32 v79, v79, 7, v153
	s_mov_b32 m0, s77
	s_add_i32 s43, s77, 0x400
	global_load_lds_dwordx4 v78, s[50:51]
	s_mov_b32 m0, s43
	s_nop 0
	global_load_lds_dwordx4 v79, s[50:51]
	s_waitcnt vmcnt(13)
	v_add_u32_e32 v54, s79, v59
	v_add_u32_e32 v55, s79, v60
	v_add_u32_e32 v56, s79, v61
	v_add_u32_e32 v57, s79, v62
	ds_read_b64_tr_b4 v[50:51], v160 offset:384
	ds_read_b64_tr_b4 v[52:53], v160 offset:1408
	ds_read_b64_tr_b4 v[130:131], v54
	ds_read_b64_tr_b4 v[132:133], v55
	ds_read_b64_tr_b4 v[134:135], v56
	ds_read_b64_tr_b4 v[136:137], v57
	s_waitcnt lgkmcnt(6)
	v_dot8c_i32_i4_e32 v38, v122, v48
	v_dot8c_i32_i4_e32 v39, v122, v46
	v_dot8c_i32_i4_e32 v40, v124, v48
	v_dot8c_i32_i4_e32 v41, v124, v46
	v_dot8c_i32_i4_e32 v42, v126, v48
	v_dot8c_i32_i4_e32 v43, v126, v46
	v_dot8c_i32_i4_e32 v44, v128, v48
	v_dot8c_i32_i4_e32 v45, v128, v46
	v_dot8c_i32_i4_e32 v38, v123, v49
	v_dot8c_i32_i4_e32 v39, v123, v47
	v_dot8c_i32_i4_e32 v40, v125, v49
	v_dot8c_i32_i4_e32 v41, v125, v47
	v_dot8c_i32_i4_e32 v42, v127, v49
	v_dot8c_i32_i4_e32 v43, v127, v47
	v_dot8c_i32_i4_e32 v44, v129, v49
	v_dot8c_i32_i4_e32 v45, v129, v47
	s_waitcnt lgkmcnt(15)
; #define LAS __attribute__((address_space(3)))
; #define TR4(p_) __builtin_amdgcn_ds_read_tr4_b64_v2i32((LAS v2i*)(p_))
; __device__ __forceinline__ void peer_v_tokens(int j, const LAS unsigned short* EL, const LAS unsigned char* AL  , const LAS float* ASC  , const LAS int* SAL  , ...
;     ...
;         for (int m = 0; m < 2; ++m) {
;             const int idx = lane + 64 * m, tau = idx >> 4, sr = idx & 15, k = 16 * (sr & 7) + 2 * tau + (sr >> 3);
;             const int aq = (int)*(const LAS signed char*)(AL + tl * 128 + k); const int tq = aq + 8;
;             const unsigned lo = (((unsigned)tq & 15u) ^ 8u) * 0x11111111u, hi = ((unsigned)(tq >> 4) & 15u) * 0x11111111u;
;             typedef unsigned u2v __attribute__((ext_vector_type(2)));
;             u2v l2; l2.x = lo; l2.y = lo; u2v h2; h2.x = hi; h2.y = hi;
;             *(LAS u2v*)(ATL + 8 * idx) = l2; *(LAS u2v*)(ATL + 1024 + 8 * idx) = h2;
;         }
;     ...
;         for (int st = 0; st < 16; ++st) {
;             const int p = st >> 2, q = st & 3;
;             if (st < 14) VDMA(st + 2, (st + 2) % 3);
;             if (st < 14) asm volatile("s_waitcnt vmcnt(8)" ::: "memory");
;             else if (st == 14) asm volatile("s_waitcnt vmcnt(4)" ::: "memory");
;             else asm volatile("s_waitcnt vmcnt(0)" ::: "memory");
;             if (q == 0) {
; #pragma unroll
;                 for (int r = 0; r < 4; ++r) { accH[r] = 0; accL[r] = 0; } }
; #pragma unroll
;             for (int tp = 0; tp < 2; ++tp) {
;                 const v2i ao = TR4(ATL + (2 * q + tp) * 128 + 8 * s16), ah = TR4(ATL + 1024 + (2 * q + tp) * 128 + 8 * s16);
; #pragma unroll
;                 for (int r = 0; r < 4; ++r) {
;                     const v2i d = TR4(ldsb + BUF[st % 3] + 2048 * tp + roff[r]);
;                     accH[r] = __builtin_amdgcn_sdot8(d.x, ah.x, accH[r], false); accH[r] = __builtin_amdgcn_sdot8(d.y, ah.y, accH[r], false);
;                     accL[r] = __builtin_amdgcn_sdot8(d.x, ao.x, accL[r], false); accL[r] = __builtin_amdgcn_sdot8(d.y, ao.y, accL[r], false);
;                 }
;             }
	v_and_b32_e32 v78, 0xffff, v26
	v_lshrrev_b32_e32 v79, 16, v26
	v_lshl_add_u32 v78, v78, 7, v152
	v_lshl_add_u32 v79, v79, 7, v153
	s_mov_b32 m0, s78
	s_add_i32 s43, s78, 0x400
	global_load_lds_dwordx4 v78, s[50:51]
	s_mov_b32 m0, s43
	s_nop 0
	global_load_lds_dwordx4 v79, s[50:51]
	s_waitcnt vmcnt(13)
	v_add_u32_e32 v54, s98, v59
	v_add_u32_e32 v55, s98, v60
	v_add_u32_e32 v56, s98, v61
	v_add_u32_e32 v57, s98, v62
	ds_read_b64_tr_b4 v[46:47], v160 offset:512
	ds_read_b64_tr_b4 v[48:49], v160 offset:1536
	ds_read_b64_tr_b4 v[122:123], v54
	ds_read_b64_tr_b4 v[124:125], v55
	ds_read_b64_tr_b4 v[126:127], v56
	ds_read_b64_tr_b4 v[128:129], v57
	s_waitcnt lgkmcnt(6)
	v_dot8c_i32_i4_e32 v38, v130, v52
	v_dot8c_i32_i4_e32 v39, v130, v50
	v_dot8c_i32_i4_e32 v40, v132, v52
	v_dot8c_i32_i4_e32 v41, v132, v50
	v_dot8c_i32_i4_e32 v42, v134, v52
	v_dot8c_i32_i4_e32 v43, v134, v50
	v_dot8c_i32_i4_e32 v44, v136, v52
	v_dot8c_i32_i4_e32 v45, v136, v50
	v_dot8c_i32_i4_e32 v38, v131, v53
	v_dot8c_i32_i4_e32 v39, v131, v51
	v_dot8c_i32_i4_e32 v40, v133, v53
	v_dot8c_i32_i4_e32 v41, v133, v51
	v_dot8c_i32_i4_e32 v42, v135, v53
	v_dot8c_i32_i4_e32 v43, v135, v51
	v_dot8c_i32_i4_e32 v44, v137, v53
	v_dot8c_i32_i4_e32 v45, v137, v51
	v_and_b32_e32 v78, 0xffff, v27
	v_lshrrev_b32_e32 v79, 16, v27
	v_lshl_add_u32 v78, v78, 7, v152
	v_lshl_add_u32 v79, v79, 7, v153
	s_mov_b32 m0, s79
	s_add_i32 s43, s79, 0x400
	global_load_lds_dwordx4 v78, s[50:51]
	s_mov_b32 m0, s43
	s_nop 0
	global_load_lds_dwordx4 v79, s[50:51]
	s_waitcnt vmcnt(8)
	v_add_u32_e32 v54, s99, v59
	v_add_u32_e32 v55, s99, v60
	v_add_u32_e32 v56, s99, v61
	v_add_u32_e32 v57, s99, v62
	ds_read_b64_tr_b4 v[50:51], v160 offset:640
	ds_read_b64_tr_b4 v[52:53], v160 offset:1664
	ds_read_b64_tr_b4 v[130:131], v54
	ds_read_b64_tr_b4 v[132:133], v55
	ds_read_b64_tr_b4 v[134:135], v56
	ds_read_b64_tr_b4 v[136:137], v57
	s_waitcnt lgkmcnt(6)
	v_dot8c_i32_i4_e32 v38, v122, v48
	v_dot8c_i32_i4_e32 v39, v122, v46
	v_dot8c_i32_i4_e32 v40, v124, v48
	v_dot8c_i32_i4_e32 v41, v124, v46
	v_dot8c_i32_i4_e32 v42, v126, v48
	v_dot8c_i32_i4_e32 v43, v126, v46
	v_dot8c_i32_i4_e32 v44, v128, v48
	v_dot8c_i32_i4_e32 v45, v128, v46
	v_dot8c_i32_i4_e32 v38, v123, v49
	v_dot8c_i32_i4_e32 v39, v123, v47
	v_dot8c_i32_i4_e32 v40, v125, v49
	v_dot8c_i32_i4_e32 v41, v125, v47
	v_dot8c_i32_i4_e32 v42, v127, v49
	v_dot8c_i32_i4_e32 v43, v127, v47
	v_dot8c_i32_i4_e32 v44, v129, v49
	v_dot8c_i32_i4_e32 v45, v129, v47
	s_waitcnt lgkmcnt(15)
	v_add_u32_e32 v143, 8, v139
	v_and_b32_e32 v142, 15, v143
	v_xor_b32_e32 v142, 8, v142
	v_bfe_u32 v144, v143, 4, 4
	v_mul_lo_u32 v142, v142, s92
	v_mul_lo_u32 v144, v144, s92
	v_mov_b32_e32 v143, v142
	v_mov_b32_e32 v145, v144
	ds_write2st64_b64 v159, v[142:143], v[144:145] offset1:2
	v_and_b32_e32 v78, 0xffff, v28
	v_lshrrev_b32_e32 v79, 16, v28
	v_lshl_add_u32 v78, v78, 7, v152
	v_lshl_add_u32 v79, v79, 7, v153
	s_mov_b32 m0, s98
	s_add_i32 s43, s98, 0x400
	global_load_lds_dwordx4 v78, s[50:51]
	s_mov_b32 m0, s43
	s_nop 0
	global_load_lds_dwordx4 v79, s[50:51]
	s_waitcnt vmcnt(8)
	v_add_u32_e32 v54, s76, v59
	v_add_u32_e32 v55, s76, v60
	v_add_u32_e32 v56, s76, v61
	v_add_u32_e32 v57, s76, v62
	ds_read_b64_tr_b4 v[46:47], v160 offset:768
	ds_read_b64_tr_b4 v[48:49], v160 offset:1792
	ds_read_b64_tr_b4 v[122:123], v54
	ds_read_b64_tr_b4 v[124:125], v55
	ds_read_b64_tr_b4 v[126:127], v56
	ds_read_b64_tr_b4 v[128:129], v57
	s_waitcnt lgkmcnt(7)
	v_dot8c_i32_i4_e32 v38, v130, v52
	v_dot8c_i32_i4_e32 v39, v130, v50
	v_dot8c_i32_i4_e32 v40, v132, v52
	v_dot8c_i32_i4_e32 v41, v132, v50
	v_dot8c_i32_i4_e32 v42, v134, v52
	v_dot8c_i32_i4_e32 v43, v134, v50
	v_dot8c_i32_i4_e32 v44, v136, v52
	v_dot8c_i32_i4_e32 v45, v136, v50
	v_dot8c_i32_i4_e32 v38, v131, v53
	v_dot8c_i32_i4_e32 v39, v131, v51
	v_dot8c_i32_i4_e32 v40, v133, v53
	v_dot8c_i32_i4_e32 v41, v133, v51
	v_dot8c_i32_i4_e32 v42, v135, v53
	v_dot8c_i32_i4_e32 v43, v135, v51
	v_dot8c_i32_i4_e32 v44, v137, v53
	v_dot8c_i32_i4_e32 v45, v137, v51
	v_and_b32_e32 v78, 0xffff, v29
	v_lshrrev_b32_e32 v79, 16, v29
	v_lshl_add_u32 v78, v78, 7, v152
	v_lshl_add_u32 v79, v79, 7, v153
	s_mov_b32 m0, s99
	s_add_i32 s43, s99, 0x400
	global_load_lds_dwordx4 v78, s[50:51]
	s_mov_b32 m0, s43
	s_nop 0
	global_load_lds_dwordx4 v79, s[50:51]
	s_waitcnt vmcnt(8)
	v_add_u32_e32 v54, s77, v59
	v_add_u32_e32 v55, s77, v60
	v_add_u32_e32 v56, s77, v61
	v_add_u32_e32 v57, s77, v62
	ds_read_b64_tr_b4 v[50:51], v160 offset:896
	ds_read_b64_tr_b4 v[52:53], v160 offset:1920
	ds_read_b64_tr_b4 v[130:131], v54
	ds_read_b64_tr_b4 v[132:133], v55
	ds_read_b64_tr_b4 v[134:135], v56
	ds_read_b64_tr_b4 v[136:137], v57
	s_waitcnt lgkmcnt(6)
	v_dot8c_i32_i4_e32 v38, v122, v48
	v_dot8c_i32_i4_e32 v39, v122, v46
	v_dot8c_i32_i4_e32 v40, v124, v48
	v_dot8c_i32_i4_e32 v41, v124, v46
	v_dot8c_i32_i4_e32 v42, v126, v48
	v_dot8c_i32_i4_e32 v43, v126, v46
	v_dot8c_i32_i4_e32 v44, v128, v48
	v_dot8c_i32_i4_e32 v45, v128, v46
	v_dot8c_i32_i4_e32 v38, v123, v49
	v_dot8c_i32_i4_e32 v39, v123, v47
	v_dot8c_i32_i4_e32 v40, v125, v49
	v_dot8c_i32_i4_e32 v41, v125, v47
	v_dot8c_i32_i4_e32 v42, v127, v49
	v_dot8c_i32_i4_e32 v43, v127, v47
	v_dot8c_i32_i4_e32 v44, v129, v49
	v_dot8c_i32_i4_e32 v45, v129, v47
	v_and_b32_e32 v78, 0xffff, v30
	v_lshrrev_b32_e32 v79, 16, v30
	v_lshl_add_u32 v78, v78, 7, v152
	v_lshl_add_u32 v79, v79, 7, v153
	s_mov_b32 m0, s76
	s_add_i32 s43, s76, 0x400
	global_load_lds_dwordx4 v78, s[50:51]
	s_mov_b32 m0, s43
	s_nop 0
	global_load_lds_dwordx4 v79, s[50:51]
	s_waitcnt vmcnt(8)
; __device__ __forceinline__ void peer_v_tokens(int j, const LAS unsigned short* EL, const LAS unsigned char* AL  , const LAS float* ASC  , const LAS int* SAL  , ...
;     ...
; #pragma unroll 1
;     for (int it = 0; it < 8; ++it) {
;         const int tl = it * 8 + wave, t = j * 64 + tl;
;         unsigned E[8];
;         { const LAS v4u* ep = (const LAS v4u*)(EL + tl * 128 + 16 * g); const v4u e0 = ep[0], e1 = ep[1];
;           E[0] = e0.x; E[1] = e0.y; E[2] = e0.z; E[3] = e0.w; E[4] = e1.x; E[5] = e1.y; E[6] = e1.z; E[7] = e1.w; }
;         uint2 hv[4]; float4 gv[4];
;         { unsigned ho = (unsigned)t * (D / 4) + (unsigned)lane; asm volatile("" : "+v"(ho)); const uint2* hp = (const uint2*)HB + ho; const float4* gp = (const float4*)fng + lane;
; #pragma unroll
;           for (int jq = 0; jq < 4; ++jq) { hv[jq] = hp[64 * jq]; gv[jq] = gp[64 * jq]; } }
;         VDMA(0, 0); VDMA(1, 1);
; #pragma unroll
;         for (int m = 0; m < 2; ++m) {
;             const int idx = lane + 64 * m, tau = idx >> 4, sr = idx & 15, k = 16 * (sr & 7) + 2 * tau + (sr >> 3);
;             const int aq = (int)*(const LAS signed char*)(AL + tl * 128 + k); const int tq = aq + 8;
;             const unsigned lo = (((unsigned)tq & 15u) ^ 8u) * 0x11111111u, hi = ((unsigned)(tq >> 4) & 15u) * 0x11111111u;
;             typedef unsigned u2v __attribute__((ext_vector_type(2)));
;             u2v l2; l2.x = lo; l2.y = lo; u2v h2; h2.x = hi; h2.y = hi;
;             *(LAS u2v*)(ATL + 8 * idx) = l2; *(LAS u2v*)(ATL + 1024 + 8 * idx) = h2;
;         }
;         const float asc = ASC[tl]; const int sa = SAL[tl];
;         CFENCE();
;         int accH[4], accL[4];
; #pragma unroll
;         for (int st = 0; st < 16; ++st) {
;             const int p = st >> 2, q = st & 3;
;             if (st < 14) VDMA(st + 2, (st + 2) % 3);
;             if (st < 14) asm volatile("s_waitcnt vmcnt(8)" ::: "memory");
;             else if (st == 14) asm volatile("s_waitcnt vmcnt(4)" ::: "memory");
;             else asm volatile("s_waitcnt vmcnt(0)" ::: "memory");
;             if (q == 0) {
; #pragma unroll
;                 for (int r = 0; r < 4; ++r) { accH[r] = 0; accL[r] = 0; } }
; #pragma unroll
;             for (int tp = 0; tp < 2; ++tp) {
;                 const v2i ao = TR4(ATL + (2 * q + tp) * 128 + 8 * s16), ah = TR4(ATL + 1024 + (2 * q + tp) * 128 + 8 * s16);
; #pragma unroll
	v_add_u32_e32 v54, s78, v59
	v_add_u32_e32 v55, s78, v60
	v_add_u32_e32 v56, s78, v61
	v_add_u32_e32 v57, s78, v62
	ds_read_b64_tr_b4 v[46:47], v160
	ds_read_b64_tr_b4 v[48:49], v160 offset:1024
	ds_read_b64_tr_b4 v[122:123], v54
	ds_read_b64_tr_b4 v[124:125], v55
	ds_read_b64_tr_b4 v[126:127], v56
	ds_read_b64_tr_b4 v[128:129], v57
	s_waitcnt lgkmcnt(6)
	v_dot8c_i32_i4_e32 v38, v130, v52
	v_dot8c_i32_i4_e32 v39, v130, v50
	v_dot8c_i32_i4_e32 v40, v132, v52
	v_dot8c_i32_i4_e32 v41, v132, v50
	v_dot8c_i32_i4_e32 v42, v134, v52
	v_dot8c_i32_i4_e32 v43, v134, v50
	v_dot8c_i32_i4_e32 v44, v136, v52
	v_dot8c_i32_i4_e32 v45, v136, v50
	v_dot8c_i32_i4_e32 v38, v131, v53
	v_dot8c_i32_i4_e32 v39, v131, v51
	v_dot8c_i32_i4_e32 v40, v133, v53
	v_dot8c_i32_i4_e32 v41, v133, v51
	v_dot8c_i32_i4_e32 v42, v135, v53
	v_dot8c_i32_i4_e32 v43, v135, v51
	v_dot8c_i32_i4_e32 v44, v137, v53
	v_dot8c_i32_i4_e32 v45, v137, v51
	s_nop 3
	s_waitcnt lgkmcnt(15)
	v_lshlrev_b32_e32 v38, 5, v38
	v_lshlrev_b32_e32 v39, 1, v39
	v_add3_u32 v38, v39, v229, v38
	v_cvt_f32_i32_e32 v38, v38
	v_mul_f32_e32 v38, v228, v38
	v_lshlrev_b32_e32 v40, 5, v40
	v_lshlrev_b32_e32 v41, 1, v41
	v_add3_u32 v40, v41, v229, v40
	v_cvt_f32_i32_e32 v40, v40
	v_mul_f32_e32 v40, v228, v40
	v_lshlrev_b32_e32 v42, 5, v42
	v_lshlrev_b32_e32 v43, 1, v43
	v_add3_u32 v42, v43, v229, v42
	v_cvt_f32_i32_e32 v42, v42
	v_mul_f32_e32 v42, v228, v42
	v_lshlrev_b32_e32 v44, 5, v44
	v_lshlrev_b32_e32 v45, 1, v45
	v_add3_u32 v44, v45, v229, v44
	v_cvt_f32_i32_e32 v44, v44
	v_mul_f32_e32 v44, v228, v44
	v_cvt_pk_bf16_f32 v164, v38, v40
	v_cvt_pk_bf16_f32 v165, v42, v44
	ds_read_b128 v[252:255], v155 offset:1024
	s_add_i32 s44, s40, 16
	s_ashr_i32 s45, s44, 31
	s_lshl_b64 s[44:45], s[44:45], 12
	v_lshl_add_u64 v[80:81], v[36:37], 0, s[44:45]
	s_waitcnt lgkmcnt(0)
	v_mul_f32_e32 v214, v214, v252
	v_mul_f32_e32 v215, v215, v253
	v_mul_f32_e32 v216, v216, v254
	v_mul_f32_e32 v217, v217, v255
	global_store_dwordx4 v[80:81], v[214:217], off offset:1024 nt
	v_add_u32_e32 v147, 8, v140
	v_and_b32_e32 v146, 15, v147
	v_xor_b32_e32 v146, 8, v146
	v_bfe_u32 v148, v147, 4, 4
	v_mul_lo_u32 v146, v146, s92
	v_mul_lo_u32 v148, v148, s92
	v_mov_b32_e32 v147, v146
	v_mov_b32_e32 v149, v148
	ds_write2st64_b64 v77, v[146:147], v[148:149] offset1:2
	v_add_u32_e32 v138, 0x1000, v74
	ds_read_u8 v139, v138
	v_add_u32_e32 v141, 0x1000, v73
	ds_read_u8 v140, v141
	s_add_i32 s43, s67, 160
	v_mov_b32_e32 v138, s43
	ds_read2st64_b32 v[228:229], v138 offset1:1
	ds_read_b128 v[18:21], v227 offset:8192
	ds_read_b128 v[22:25], v227 offset:8208
	v_add_u32_e32 v150, 0x400000, v63
	v_add_u32_e32 v151, 0x400000, v64
	v_mov_b32_e32 v38, 0
	v_mov_b32_e32 v39, 0
	v_mov_b32_e32 v40, 0
	v_mov_b32_e32 v41, 0
	v_mov_b32_e32 v42, 0
	v_mov_b32_e32 v43, 0
	v_mov_b32_e32 v44, 0
	v_mov_b32_e32 v45, 0
	v_and_b32_e32 v78, 0xffff, v31
	v_lshrrev_b32_e32 v79, 16, v31
	v_lshl_add_u32 v78, v78, 7, v152
	v_lshl_add_u32 v79, v79, 7, v153
	s_mov_b32 m0, s77
	s_add_i32 s43, s77, 0x400
	global_load_lds_dwordx4 v78, s[50:51]
	s_mov_b32 m0, s43
	s_nop 0
	global_load_lds_dwordx4 v79, s[50:51]
	s_waitcnt vmcnt(9)
	v_add_u32_e32 v54, s79, v59
	v_add_u32_e32 v55, s79, v60
	v_add_u32_e32 v56, s79, v61
	v_add_u32_e32 v57, s79, v62
	ds_read_b64_tr_b4 v[50:51], v160 offset:128
	ds_read_b64_tr_b4 v[52:53], v160 offset:1152
	ds_read_b64_tr_b4 v[130:131], v54
	ds_read_b64_tr_b4 v[132:133], v55
	ds_read_b64_tr_b4 v[134:135], v56
	ds_read_b64_tr_b4 v[136:137], v57
	s_waitcnt lgkmcnt(13)
	v_dot8c_i32_i4_e32 v38, v122, v48
	v_dot8c_i32_i4_e32 v39, v122, v46
	v_dot8c_i32_i4_e32 v40, v124, v48
	v_dot8c_i32_i4_e32 v41, v124, v46
	v_dot8c_i32_i4_e32 v42, v126, v48
	v_dot8c_i32_i4_e32 v43, v126, v46
	v_dot8c_i32_i4_e32 v44, v128, v48
	v_dot8c_i32_i4_e32 v45, v128, v46
	v_dot8c_i32_i4_e32 v38, v123, v49
	v_dot8c_i32_i4_e32 v39, v123, v47
	v_dot8c_i32_i4_e32 v40, v125, v49
	v_dot8c_i32_i4_e32 v41, v125, v47
	v_dot8c_i32_i4_e32 v42, v127, v49
	v_dot8c_i32_i4_e32 v43, v127, v47
	v_dot8c_i32_i4_e32 v44, v129, v49
	v_dot8c_i32_i4_e32 v45, v129, v47
	v_and_b32_e32 v78, 0xffff, v32
	v_lshrrev_b32_e32 v79, 16, v32
	v_lshl_add_u32 v78, v78, 7, v152
	v_lshl_add_u32 v79, v79, 7, v153
	s_mov_b32 m0, s78
	s_add_i32 s43, s78, 0x400
	global_load_lds_dwordx4 v78, s[50:51]
	s_mov_b32 m0, s43
	s_nop 0
	global_load_lds_dwordx4 v79, s[50:51]
	s_waitcnt vmcnt(9)
	v_add_u32_e32 v54, s98, v59
	v_add_u32_e32 v55, s98, v60
	v_add_u32_e32 v56, s98, v61
	v_add_u32_e32 v57, s98, v62
	ds_read_b64_tr_b4 v[46:47], v160 offset:256
	ds_read_b64_tr_b4 v[48:49], v160 offset:1280
	ds_read_b64_tr_b4 v[122:123], v54
	ds_read_b64_tr_b4 v[124:125], v55
	ds_read_b64_tr_b4 v[126:127], v56
	ds_read_b64_tr_b4 v[128:129], v57
	s_waitcnt lgkmcnt(6)
	v_dot8c_i32_i4_e32 v38, v130, v52
	v_dot8c_i32_i4_e32 v39, v130, v50
	v_dot8c_i32_i4_e32 v40, v132, v52
	v_dot8c_i32_i4_e32 v41, v132, v50
	v_dot8c_i32_i4_e32 v42, v134, v52
	v_dot8c_i32_i4_e32 v43, v134, v50
	v_dot8c_i32_i4_e32 v44, v136, v52
	v_dot8c_i32_i4_e32 v45, v136, v50
	v_dot8c_i32_i4_e32 v38, v131, v53
	v_dot8c_i32_i4_e32 v39, v131, v51
	v_dot8c_i32_i4_e32 v40, v133, v53
	v_dot8c_i32_i4_e32 v41, v133, v51
	v_dot8c_i32_i4_e32 v42, v135, v53
	v_dot8c_i32_i4_e32 v43, v135, v51
	v_dot8c_i32_i4_e32 v44, v137, v53
	v_dot8c_i32_i4_e32 v45, v137, v51
	ds_write_b16 v65, v186
	ds_write_b16_d16_hi v65, v186 offset:128
	ds_write_b16 v65, v187 offset:256
	ds_write_b16_d16_hi v65, v187 offset:384
	ds_write_b16 v65, v188 offset:512
	ds_write_b16_d16_hi v65, v188 offset:640
	ds_write_b16 v65, v189 offset:768
	ds_write_b16_d16_hi v65, v189 offset:896
	ds_write_b16 v65, v190 offset:1024
	ds_write_b16_d16_hi v65, v190 offset:1152
	ds_write_b16 v65, v191 offset:1280
	ds_write_b16_d16_hi v65, v191 offset:1408
	ds_write_b16 v65, v192 offset:1536
	ds_write_b16_d16_hi v65, v192 offset:1664
	ds_write_b16 v65, v193 offset:1792
	ds_write_b16_d16_hi v65, v193 offset:1920
	ds_read_b64 v[202:203], v154
	ds_read_b64 v[204:205], v154 offset:512
	ds_read_b64 v[206:207], v154 offset:1024
	ds_read_b64 v[208:209], v154 offset:1536
	v_and_b32_e32 v78, 0xffff, v33
	v_lshrrev_b32_e32 v79, 16, v33
	v_lshl_add_u32 v78, v78, 7, v152
	v_lshl_add_u32 v79, v79, 7, v153
	s_mov_b32 m0, s79
	s_add_i32 s43, s79, 0x400
	global_load_lds_dwordx4 v78, s[50:51]
	s_mov_b32 m0, s43
	s_nop 0
	global_load_lds_dwordx4 v79, s[50:51]
	s_waitcnt vmcnt(9)
; #define LAS __attribute__((address_space(3)))
; #define TR4(p_) __builtin_amdgcn_ds_read_tr4_b64_v2i32((LAS v2i*)(p_))
; #define CFENCE() asm volatile("" ::: "memory")
; __device__ __forceinline__ void peer_v_tokens(int j, const LAS unsigned short* EL, const LAS unsigned char* AL  , const LAS float* ASC  , const LAS int* SAL  , ...
;     ...
;         for (int m = 0; m < 2; ++m) {
;             const int idx = lane + 64 * m, tau = idx >> 4, sr = idx & 15, k = 16 * (sr & 7) + 2 * tau + (sr >> 3);
;             const int aq = (int)*(const LAS signed char*)(AL + tl * 128 + k); const int tq = aq + 8;
;             const unsigned lo = (((unsigned)tq & 15u) ^ 8u) * 0x11111111u, hi = ((unsigned)(tq >> 4) & 15u) * 0x11111111u;
;             typedef unsigned u2v __attribute__((ext_vector_type(2)));
;             u2v l2; l2.x = lo; l2.y = lo; u2v h2; h2.x = hi; h2.y = hi;
;             *(LAS u2v*)(ATL + 8 * idx) = l2; *(LAS u2v*)(ATL + 1024 + 8 * idx) = h2;
;         }
;         const float asc = ASC[tl]; const int sa = SAL[tl];
;         CFENCE();
;         int accH[4], accL[4];
; #pragma unroll
;         for (int st = 0; st < 16; ++st) {
;             const int p = st >> 2, q = st & 3;
;             if (st < 14) VDMA(st + 2, (st + 2) % 3);
;             if (st < 14) asm volatile("s_waitcnt vmcnt(8)" ::: "memory");
;             else if (st == 14) asm volatile("s_waitcnt vmcnt(4)" ::: "memory");
;             else asm volatile("s_waitcnt vmcnt(0)" ::: "memory");
;             if (q == 0) {
; #pragma unroll
;                 for (int r = 0; r < 4; ++r) { accH[r] = 0; accL[r] = 0; } }
; #pragma unroll
;             for (int tp = 0; tp < 2; ++tp) {
;                 const v2i ao = TR4(ATL + (2 * q + tp) * 128 + 8 * s16), ah = TR4(ATL + 1024 + (2 * q + tp) * 128 + 8 * s16);
; #pragma unroll
;                 for (int r = 0; r < 4; ++r) {
;                     const v2i d = TR4(ldsb + BUF[st % 3] + 2048 * tp + roff[r]);
;                     accH[r] = __builtin_amdgcn_sdot8(d.x, ah.x, accH[r], false); accH[r] = __builtin_amdgcn_sdot8(d.y, ah.y, accH[r], false);
;                     accL[r] = __builtin_amdgcn_sdot8(d.x, ao.x, accL[r], false); accL[r] = __builtin_amdgcn_sdot8(d.y, ao.y, accL[r], false);
;                 }
;             }
	v_add_u32_e32 v54, s99, v59
	v_add_u32_e32 v55, s99, v60
	v_add_u32_e32 v56, s99, v61
	v_add_u32_e32 v57, s99, v62
	ds_read_b64_tr_b4 v[50:51], v160 offset:384
	ds_read_b64_tr_b4 v[52:53], v160 offset:1408
	ds_read_b64_tr_b4 v[130:131], v54
	ds_read_b64_tr_b4 v[132:133], v55
	ds_read_b64_tr_b4 v[134:135], v56
	ds_read_b64_tr_b4 v[136:137], v57
	s_waitcnt lgkmcnt(15)
	v_dot8c_i32_i4_e32 v38, v122, v48
	v_dot8c_i32_i4_e32 v39, v122, v46
	v_dot8c_i32_i4_e32 v40, v124, v48
	v_dot8c_i32_i4_e32 v41, v124, v46
	v_dot8c_i32_i4_e32 v42, v126, v48
	v_dot8c_i32_i4_e32 v43, v126, v46
	v_dot8c_i32_i4_e32 v44, v128, v48
	v_dot8c_i32_i4_e32 v45, v128, v46
	v_dot8c_i32_i4_e32 v38, v123, v49
	v_dot8c_i32_i4_e32 v39, v123, v47
	v_dot8c_i32_i4_e32 v40, v125, v49
	v_dot8c_i32_i4_e32 v41, v125, v47
	v_dot8c_i32_i4_e32 v42, v127, v49
	v_dot8c_i32_i4_e32 v43, v127, v47
	v_dot8c_i32_i4_e32 v44, v129, v49
	v_dot8c_i32_i4_e32 v45, v129, v47
	s_waitcnt lgkmcnt(15)
	v_and_b32_e32 v78, 0xffff, v18
	v_lshrrev_b32_e32 v79, 16, v18
	v_lshl_add_u32 v78, v78, 7, v150
	v_lshl_add_u32 v79, v79, 7, v151
	s_mov_b32 m0, s98
	s_add_i32 s43, s98, 0x400
	global_load_lds_dwordx4 v78, s[50:51]
	s_mov_b32 m0, s43
	s_nop 0
	global_load_lds_dwordx4 v79, s[50:51]
	s_waitcnt vmcnt(9)
	v_add_u32_e32 v54, s76, v59
	v_add_u32_e32 v55, s76, v60
	v_add_u32_e32 v56, s76, v61
	v_add_u32_e32 v57, s76, v62
	ds_read_b64_tr_b4 v[46:47], v160 offset:512
	ds_read_b64_tr_b4 v[48:49], v160 offset:1536
	ds_read_b64_tr_b4 v[122:123], v54
	ds_read_b64_tr_b4 v[124:125], v55
	ds_read_b64_tr_b4 v[126:127], v56
	ds_read_b64_tr_b4 v[128:129], v57
	s_waitcnt lgkmcnt(6)
	v_dot8c_i32_i4_e32 v38, v130, v52
	v_dot8c_i32_i4_e32 v39, v130, v50
	v_dot8c_i32_i4_e32 v40, v132, v52
	v_dot8c_i32_i4_e32 v41, v132, v50
	v_dot8c_i32_i4_e32 v42, v134, v52
	v_dot8c_i32_i4_e32 v43, v134, v50
	v_dot8c_i32_i4_e32 v44, v136, v52
	v_dot8c_i32_i4_e32 v45, v136, v50
	v_dot8c_i32_i4_e32 v38, v131, v53
	v_dot8c_i32_i4_e32 v39, v131, v51
	v_dot8c_i32_i4_e32 v40, v133, v53
	v_dot8c_i32_i4_e32 v41, v133, v51
	v_dot8c_i32_i4_e32 v42, v135, v53
	v_dot8c_i32_i4_e32 v43, v135, v51
	v_dot8c_i32_i4_e32 v44, v137, v53
	v_dot8c_i32_i4_e32 v45, v137, v51
	v_and_b32_e32 v78, 0xffff, v19
	v_lshrrev_b32_e32 v79, 16, v19
	v_lshl_add_u32 v78, v78, 7, v150
	v_lshl_add_u32 v79, v79, 7, v151
	s_mov_b32 m0, s99
	s_add_i32 s43, s99, 0x400
	global_load_lds_dwordx4 v78, s[50:51]
	s_mov_b32 m0, s43
	s_nop 0
	global_load_lds_dwordx4 v79, s[50:51]
	s_waitcnt vmcnt(8)
	v_add_u32_e32 v54, s77, v59
	v_add_u32_e32 v55, s77, v60
	v_add_u32_e32 v56, s77, v61
	v_add_u32_e32 v57, s77, v62
	ds_read_b64_tr_b4 v[50:51], v160 offset:640
	ds_read_b64_tr_b4 v[52:53], v160 offset:1664
	ds_read_b64_tr_b4 v[130:131], v54
	ds_read_b64_tr_b4 v[132:133], v55
	ds_read_b64_tr_b4 v[134:135], v56
	ds_read_b64_tr_b4 v[136:137], v57
	s_waitcnt lgkmcnt(6)
	v_dot8c_i32_i4_e32 v38, v122, v48
	v_dot8c_i32_i4_e32 v39, v122, v46
	v_dot8c_i32_i4_e32 v40, v124, v48
	v_dot8c_i32_i4_e32 v41, v124, v46
	v_dot8c_i32_i4_e32 v42, v126, v48
	v_dot8c_i32_i4_e32 v43, v126, v46
	v_dot8c_i32_i4_e32 v44, v128, v48
	v_dot8c_i32_i4_e32 v45, v128, v46
	v_dot8c_i32_i4_e32 v38, v123, v49
	v_dot8c_i32_i4_e32 v39, v123, v47
	v_dot8c_i32_i4_e32 v40, v125, v49
	v_dot8c_i32_i4_e32 v41, v125, v47
	v_dot8c_i32_i4_e32 v42, v127, v49
	v_dot8c_i32_i4_e32 v43, v127, v47
	v_dot8c_i32_i4_e32 v44, v129, v49
	v_dot8c_i32_i4_e32 v45, v129, v47
	s_waitcnt lgkmcnt(15)
	v_add_u32_e32 v143, 8, v139
	v_and_b32_e32 v142, 15, v143
	v_xor_b32_e32 v142, 8, v142
	v_bfe_u32 v144, v143, 4, 4
	v_mul_lo_u32 v142, v142, s92
	v_mul_lo_u32 v144, v144, s92
	v_mov_b32_e32 v143, v142
	v_mov_b32_e32 v145, v144
	ds_write2st64_b64 v159, v[142:143], v[144:145] offset1:2
	v_and_b32_e32 v78, 0xffff, v20
	v_lshrrev_b32_e32 v79, 16, v20
	v_lshl_add_u32 v78, v78, 7, v150
	v_lshl_add_u32 v79, v79, 7, v151
	s_mov_b32 m0, s76
	s_add_i32 s43, s76, 0x400
	global_load_lds_dwordx4 v78, s[50:51]
	s_mov_b32 m0, s43
	s_nop 0
	global_load_lds_dwordx4 v79, s[50:51]
	s_waitcnt vmcnt(8)
	v_add_u32_e32 v54, s78, v59
	v_add_u32_e32 v55, s78, v60
	v_add_u32_e32 v56, s78, v61
	v_add_u32_e32 v57, s78, v62
	ds_read_b64_tr_b4 v[46:47], v160 offset:768
	ds_read_b64_tr_b4 v[48:49], v160 offset:1792
	ds_read_b64_tr_b4 v[122:123], v54
	ds_read_b64_tr_b4 v[124:125], v55
	ds_read_b64_tr_b4 v[126:127], v56
	ds_read_b64_tr_b4 v[128:129], v57
	s_waitcnt lgkmcnt(7)
	v_dot8c_i32_i4_e32 v38, v130, v52
	v_dot8c_i32_i4_e32 v39, v130, v50
	v_dot8c_i32_i4_e32 v40, v132, v52
	v_dot8c_i32_i4_e32 v41, v132, v50
	v_dot8c_i32_i4_e32 v42, v134, v52
	v_dot8c_i32_i4_e32 v43, v134, v50
	v_dot8c_i32_i4_e32 v44, v136, v52
	v_dot8c_i32_i4_e32 v45, v136, v50
	v_dot8c_i32_i4_e32 v38, v131, v53
	v_dot8c_i32_i4_e32 v39, v131, v51
	v_dot8c_i32_i4_e32 v40, v133, v53
	v_dot8c_i32_i4_e32 v41, v133, v51
	v_dot8c_i32_i4_e32 v42, v135, v53
	v_dot8c_i32_i4_e32 v43, v135, v51
	v_dot8c_i32_i4_e32 v44, v137, v53
	v_dot8c_i32_i4_e32 v45, v137, v51
	v_and_b32_e32 v78, 0xffff, v21
	v_lshrrev_b32_e32 v79, 16, v21
	v_lshl_add_u32 v78, v78, 7, v150
	v_lshl_add_u32 v79, v79, 7, v151
	s_mov_b32 m0, s77
	s_add_i32 s43, s77, 0x400
	global_load_lds_dwordx4 v78, s[50:51]
	s_mov_b32 m0, s43
	s_nop 0
	global_load_lds_dwordx4 v79, s[50:51]
	s_waitcnt vmcnt(8)
	v_add_u32_e32 v54, s79, v59
	v_add_u32_e32 v55, s79, v60
	v_add_u32_e32 v56, s79, v61
	v_add_u32_e32 v57, s79, v62
	ds_read_b64_tr_b4 v[50:51], v160 offset:896
	ds_read_b64_tr_b4 v[52:53], v160 offset:1920
	ds_read_b64_tr_b4 v[130:131], v54
	ds_read_b64_tr_b4 v[132:133], v55
	ds_read_b64_tr_b4 v[134:135], v56
	ds_read_b64_tr_b4 v[136:137], v57
	s_waitcnt lgkmcnt(6)
; __device__ __forceinline__ void peer_v_tokens(int j, const LAS unsigned short* EL, const LAS unsigned char* AL  , const LAS float* ASC  , const LAS int* SAL  , ...
;     ...
; #pragma unroll 1
;     for (int it = 0; it < 8; ++it) {
;         const int tl = it * 8 + wave, t = j * 64 + tl;
;         unsigned E[8];
;         { const LAS v4u* ep = (const LAS v4u*)(EL + tl * 128 + 16 * g); const v4u e0 = ep[0], e1 = ep[1];
;           E[0] = e0.x; E[1] = e0.y; E[2] = e0.z; E[3] = e0.w; E[4] = e1.x; E[5] = e1.y; E[6] = e1.z; E[7] = e1.w; }
;         uint2 hv[4]; float4 gv[4];
;         { unsigned ho = (unsigned)t * (D / 4) + (unsigned)lane; asm volatile("" : "+v"(ho)); const uint2* hp = (const uint2*)HB + ho; const float4* gp = (const float4*)fng + lane;
; #pragma unroll
;           for (int jq = 0; jq < 4; ++jq) { hv[jq] = hp[64 * jq]; gv[jq] = gp[64 * jq]; } }
;         VDMA(0, 0); VDMA(1, 1);
; #pragma unroll
;         for (int m = 0; m < 2; ++m) {
;             const int idx = lane + 64 * m, tau = idx >> 4, sr = idx & 15, k = 16 * (sr & 7) + 2 * tau + (sr >> 3);
;             const int aq = (int)*(const LAS signed char*)(AL + tl * 128 + k); const int tq = aq + 8;
;             const unsigned lo = (((unsigned)tq & 15u) ^ 8u) * 0x11111111u, hi = ((unsigned)(tq >> 4) & 15u) * 0x11111111u;
;             typedef unsigned u2v __attribute__((ext_vector_type(2)));
;             u2v l2; l2.x = lo; l2.y = lo; u2v h2; h2.x = hi; h2.y = hi;
;             *(LAS u2v*)(ATL + 8 * idx) = l2; *(LAS u2v*)(ATL + 1024 + 8 * idx) = h2;
;         }
;         const float asc = ASC[tl]; const int sa = SAL[tl];
;         CFENCE();
;         int accH[4], accL[4];
; #pragma unroll
;         for (int st = 0; st < 16; ++st) {
;             const int p = st >> 2, q = st & 3;
;             if (st < 14) VDMA(st + 2, (st + 2) % 3);
;             if (st < 14) asm volatile("s_waitcnt vmcnt(8)" ::: "memory");
;             else if (st == 14) asm volatile("s_waitcnt vmcnt(4)" ::: "memory");
;             else asm volatile("s_waitcnt vmcnt(0)" ::: "memory");
;             if (q == 0) {
; #pragma unroll
;                 for (int r = 0; r < 4; ++r) { accH[r] = 0; accL[r] = 0; } }
; #pragma unroll
;             for (int tp = 0; tp < 2; ++tp) {
;                 const v2i ao = TR4(ATL + (2 * q + tp) * 128 + 8 * s16), ah = TR4(ATL + 1024 + (2 * q + tp) * 128 + 8 * s16);
; #pragma unroll
	v_dot8c_i32_i4_e32 v38, v122, v48
	v_dot8c_i32_i4_e32 v39, v122, v46
	v_dot8c_i32_i4_e32 v40, v124, v48
	v_dot8c_i32_i4_e32 v41, v124, v46
	v_dot8c_i32_i4_e32 v42, v126, v48
	v_dot8c_i32_i4_e32 v43, v126, v46
	v_dot8c_i32_i4_e32 v44, v128, v48
	v_dot8c_i32_i4_e32 v45, v128, v46
	v_dot8c_i32_i4_e32 v38, v123, v49
	v_dot8c_i32_i4_e32 v39, v123, v47
	v_dot8c_i32_i4_e32 v40, v125, v49
	v_dot8c_i32_i4_e32 v41, v125, v47
	v_dot8c_i32_i4_e32 v42, v127, v49
	v_dot8c_i32_i4_e32 v43, v127, v47
	v_dot8c_i32_i4_e32 v44, v129, v49
	v_dot8c_i32_i4_e32 v45, v129, v47
	v_and_b32_e32 v78, 0xffff, v22
	v_lshrrev_b32_e32 v79, 16, v22
	v_lshl_add_u32 v78, v78, 7, v150
	v_lshl_add_u32 v79, v79, 7, v151
	s_mov_b32 m0, s78
	s_add_i32 s43, s78, 0x400
	global_load_lds_dwordx4 v78, s[50:51]
	s_mov_b32 m0, s43
	s_nop 0
	global_load_lds_dwordx4 v79, s[50:51]
	s_waitcnt vmcnt(8)
	v_add_u32_e32 v54, s98, v59
	v_add_u32_e32 v55, s98, v60
	v_add_u32_e32 v56, s98, v61
	v_add_u32_e32 v57, s98, v62
	ds_read_b64_tr_b4 v[46:47], v160
	ds_read_b64_tr_b4 v[48:49], v160 offset:1024
	ds_read_b64_tr_b4 v[122:123], v54
	ds_read_b64_tr_b4 v[124:125], v55
	ds_read_b64_tr_b4 v[126:127], v56
	ds_read_b64_tr_b4 v[128:129], v57
	s_waitcnt lgkmcnt(6)
	v_dot8c_i32_i4_e32 v38, v130, v52
	v_dot8c_i32_i4_e32 v39, v130, v50
	v_dot8c_i32_i4_e32 v40, v132, v52
	v_dot8c_i32_i4_e32 v41, v132, v50
	v_dot8c_i32_i4_e32 v42, v134, v52
	v_dot8c_i32_i4_e32 v43, v134, v50
	v_dot8c_i32_i4_e32 v44, v136, v52
	v_dot8c_i32_i4_e32 v45, v136, v50
	v_dot8c_i32_i4_e32 v38, v131, v53
	v_dot8c_i32_i4_e32 v39, v131, v51
	v_dot8c_i32_i4_e32 v40, v133, v53
	v_dot8c_i32_i4_e32 v41, v133, v51
	v_dot8c_i32_i4_e32 v42, v135, v53
	v_dot8c_i32_i4_e32 v43, v135, v51
	v_dot8c_i32_i4_e32 v44, v137, v53
	v_dot8c_i32_i4_e32 v45, v137, v51
	s_nop 3
	s_waitcnt lgkmcnt(15)
	v_lshlrev_b32_e32 v38, 5, v38
	v_lshlrev_b32_e32 v39, 1, v39
	v_add3_u32 v38, v39, v229, v38
	v_cvt_f32_i32_e32 v38, v38
	v_mul_f32_e32 v38, v228, v38
	v_lshlrev_b32_e32 v40, 5, v40
	v_lshlrev_b32_e32 v41, 1, v41
	v_add3_u32 v40, v41, v229, v40
	v_cvt_f32_i32_e32 v40, v40
	v_mul_f32_e32 v40, v228, v40
	v_lshlrev_b32_e32 v42, 5, v42
	v_lshlrev_b32_e32 v43, 1, v43
	v_add3_u32 v42, v43, v229, v42
	v_cvt_f32_i32_e32 v42, v42
	v_mul_f32_e32 v42, v228, v42
	v_lshlrev_b32_e32 v44, 5, v44
	v_lshlrev_b32_e32 v45, 1, v45
	v_add3_u32 v44, v45, v229, v44
	v_cvt_f32_i32_e32 v44, v44
	v_mul_f32_e32 v44, v228, v44
	v_cvt_pk_bf16_f32 v172, v38, v40
	v_cvt_pk_bf16_f32 v173, v42, v44
	ds_read_b128 v[252:255], v156
	s_add_i32 s44, s40, 16
	s_ashr_i32 s45, s44, 31
	s_lshl_b64 s[44:45], s[44:45], 12
	v_lshl_add_u64 v[80:81], v[36:37], 0, s[44:45]
	s_waitcnt lgkmcnt(0)
	v_mul_f32_e32 v218, v218, v252
	v_mul_f32_e32 v219, v219, v253
	v_mul_f32_e32 v220, v220, v254
	v_mul_f32_e32 v221, v221, v255
	global_store_dwordx4 v[80:81], v[218:221], off offset:2048 nt
	v_add_u32_e32 v147, 8, v140
	v_and_b32_e32 v146, 15, v147
	v_xor_b32_e32 v146, 8, v146
	v_bfe_u32 v148, v147, 4, 4
	v_mul_lo_u32 v146, v146, s92
	v_mul_lo_u32 v148, v148, s92
	v_mov_b32_e32 v147, v146
	v_mov_b32_e32 v149, v148
	ds_write2st64_b64 v77, v[146:147], v[148:149] offset1:2
	v_add_u32_e32 v138, 0x1400, v74
	ds_read_u8 v139, v138
	v_add_u32_e32 v141, 0x1400, v73
	ds_read_u8 v140, v141
	s_add_i32 s43, s67, 128
	v_mov_b32_e32 v138, s43
	ds_read2st64_b32 v[228:229], v138 offset1:1
	ds_read_b128 v[26:29], v227 offset:10240
	ds_read_b128 v[30:33], v227 offset:10256
	v_mov_b32_e32 v38, 0
	v_mov_b32_e32 v39, 0
	v_mov_b32_e32 v40, 0
	v_mov_b32_e32 v41, 0
	v_mov_b32_e32 v42, 0
	v_mov_b32_e32 v43, 0
	v_mov_b32_e32 v44, 0
	v_mov_b32_e32 v45, 0
	v_and_b32_e32 v78, 0xffff, v23
	v_lshrrev_b32_e32 v79, 16, v23
	v_lshl_add_u32 v78, v78, 7, v150
	v_lshl_add_u32 v79, v79, 7, v151
	s_mov_b32 m0, s79
	s_add_i32 s43, s79, 0x400
	global_load_lds_dwordx4 v78, s[50:51]
	s_mov_b32 m0, s43
	s_nop 0
	global_load_lds_dwordx4 v79, s[50:51]
	s_waitcnt vmcnt(9)
	v_add_u32_e32 v54, s99, v59
	v_add_u32_e32 v55, s99, v60
	v_add_u32_e32 v56, s99, v61
	v_add_u32_e32 v57, s99, v62
	ds_read_b64_tr_b4 v[50:51], v160 offset:128
	ds_read_b64_tr_b4 v[52:53], v160 offset:1152
	ds_read_b64_tr_b4 v[130:131], v54
	ds_read_b64_tr_b4 v[132:133], v55
	ds_read_b64_tr_b4 v[134:135], v56
	ds_read_b64_tr_b4 v[136:137], v57
	s_waitcnt lgkmcnt(13)
	s_waitcnt vmcnt(36) lgkmcnt(15)
; #define LAS __attribute__((address_space(3)))
; #define TR4(p_) __builtin_amdgcn_ds_read_tr4_b64_v2i32((LAS v2i*)(p_))
; __device__ __forceinline__ void peer_v_tokens(int j, const LAS unsigned short* EL, const LAS unsigned char* AL  , const LAS float* ASC  , const LAS int* SAL  , ...
;     ...
;         for (int st = 0; st < 16; ++st) {
;             const int p = st >> 2, q = st & 3;
;             if (st < 14) VDMA(st + 2, (st + 2) % 3);
;             if (st < 14) asm volatile("s_waitcnt vmcnt(8)" ::: "memory");
;             else if (st == 14) asm volatile("s_waitcnt vmcnt(4)" ::: "memory");
;             else asm volatile("s_waitcnt vmcnt(0)" ::: "memory");
;             if (q == 0) {
; #pragma unroll
;                 for (int r = 0; r < 4; ++r) { accH[r] = 0; accL[r] = 0; } }
; #pragma unroll
;             for (int tp = 0; tp < 2; ++tp) {
;                 const v2i ao = TR4(ATL + (2 * q + tp) * 128 + 8 * s16), ah = TR4(ATL + 1024 + (2 * q + tp) * 128 + 8 * s16);
; #pragma unroll
;                 for (int r = 0; r < 4; ++r) {
;                     const v2i d = TR4(ldsb + BUF[st % 3] + 2048 * tp + roff[r]);
;                     accH[r] = __builtin_amdgcn_sdot8(d.x, ah.x, accH[r], false); accH[r] = __builtin_amdgcn_sdot8(d.y, ah.y, accH[r], false);
;                     accL[r] = __builtin_amdgcn_sdot8(d.x, ao.x, accL[r], false); accL[r] = __builtin_amdgcn_sdot8(d.y, ao.y, accL[r], false);
;                 }
;             }
;     ...
;         {
;             float4 v[4]; float ss = 0.f;
; #pragma unroll
;             for (int jq = 0; jq < 4; ++jq) { typedef unsigned u2v __attribute__((ext_vector_type(2))); const u2v pw = *(const LAS u2v*)(STASH + 4 * lane + 256 * jq); const uint2 hw = hv[jq];
;                 v[jq] = make_float4(__uint_as_float(hw.x << 16) + __uint_as_float(pw.x << 16), __uint_as_float(hw.x & 0xffff0000u) + __uint_as_float(pw.x & 0xffff0000u),
;                                     __uint_as_float(hw.y << 16) + __uint_as_float(pw.y << 16), __uint_as_float(hw.y & 0xffff0000u) + __uint_as_float(pw.y & 0xffff0000u));
;                 ss += v[jq].x * v[jq].x + v[jq].y * v[jq].y + v[jq].z * v[jq].z + v[jq].w * v[jq].w; }
;             ss = wave_sum(ss);
;             const float r3 = rsqrtf(ss * (1.f / D) + EPS);
	v_lshlrev_b32_e32 v236, 16, v194
	v_and_b32_e32 v237, 0xffff0000, v194
	v_lshlrev_b32_e32 v142, 16, v202
	v_and_b32_e32 v143, 0xffff0000, v202
	v_add_f32_e32 v236, v236, v142
	v_add_f32_e32 v237, v237, v143
	v_lshlrev_b32_e32 v238, 16, v195
	v_and_b32_e32 v239, 0xffff0000, v195
	v_lshlrev_b32_e32 v142, 16, v203
	v_and_b32_e32 v143, 0xffff0000, v203
	v_add_f32_e32 v238, v238, v142
	v_add_f32_e32 v239, v239, v143
	v_lshlrev_b32_e32 v240, 16, v196
	v_and_b32_e32 v241, 0xffff0000, v196
	v_lshlrev_b32_e32 v142, 16, v204
	v_and_b32_e32 v143, 0xffff0000, v204
	v_add_f32_e32 v240, v240, v142
	v_add_f32_e32 v241, v241, v143
	v_lshlrev_b32_e32 v242, 16, v197
	v_and_b32_e32 v243, 0xffff0000, v197
	v_lshlrev_b32_e32 v142, 16, v205
	v_and_b32_e32 v143, 0xffff0000, v205
	v_add_f32_e32 v242, v242, v142
	v_add_f32_e32 v243, v243, v143
	v_lshlrev_b32_e32 v244, 16, v198
	v_and_b32_e32 v245, 0xffff0000, v198
	v_lshlrev_b32_e32 v142, 16, v206
	v_and_b32_e32 v143, 0xffff0000, v206
	v_add_f32_e32 v244, v244, v142
	v_add_f32_e32 v245, v245, v143
	v_lshlrev_b32_e32 v246, 16, v199
	v_and_b32_e32 v247, 0xffff0000, v199
	v_lshlrev_b32_e32 v142, 16, v207
	v_and_b32_e32 v143, 0xffff0000, v207
	v_add_f32_e32 v246, v246, v142
	v_add_f32_e32 v247, v247, v143
	v_lshlrev_b32_e32 v248, 16, v200
	v_and_b32_e32 v249, 0xffff0000, v200
	v_lshlrev_b32_e32 v142, 16, v208
	v_and_b32_e32 v143, 0xffff0000, v208
	v_add_f32_e32 v248, v248, v142
	v_add_f32_e32 v249, v249, v143
	v_lshlrev_b32_e32 v250, 16, v201
	v_and_b32_e32 v251, 0xffff0000, v201
	v_lshlrev_b32_e32 v142, 16, v209
	v_and_b32_e32 v143, 0xffff0000, v209
	v_add_f32_e32 v250, v250, v142
	v_add_f32_e32 v251, v251, v143
	v_mov_b32_e32 v144, 0
	v_mul_f32_e32 v145, v236, v236
	v_fmac_f32_e32 v145, v237, v237
	v_fmac_f32_e32 v145, v238, v238
	v_fmac_f32_e32 v145, v239, v239
	v_add_f32_e32 v144, v144, v145
	v_mul_f32_e32 v145, v240, v240
	v_fmac_f32_e32 v145, v241, v241
	v_fmac_f32_e32 v145, v242, v242
	v_fmac_f32_e32 v145, v243, v243
	v_add_f32_e32 v144, v144, v145
	v_mul_f32_e32 v145, v244, v244
	v_fmac_f32_e32 v145, v245, v245
	v_fmac_f32_e32 v145, v246, v246
	v_fmac_f32_e32 v145, v247, v247
	v_add_f32_e32 v144, v144, v145
	v_mul_f32_e32 v145, v248, v248
	v_fmac_f32_e32 v145, v249, v249
	v_fmac_f32_e32 v145, v250, v250
	v_fmac_f32_e32 v145, v251, v251
	v_add_f32_e32 v144, v144, v145
	s_nop 1
	v_add_f32_dpp v144, v144, v144 quad_perm:[1,0,3,2] row_mask:0xf bank_mask:0xf bound_ctrl:1
	s_nop 1
	v_add_f32_dpp v144, v144, v144 quad_perm:[2,3,0,1] row_mask:0xf bank_mask:0xf bound_ctrl:1
	s_nop 1
	v_add_f32_dpp v144, v144, v144 row_half_mirror row_mask:0xf bank_mask:0xf bound_ctrl:1
	s_nop 1
	v_add_f32_dpp v144, v144, v144 row_mirror row_mask:0xf bank_mask:0xf bound_ctrl:1
	s_nop 1
	v_readlane_b32 s10, v144, 0
	v_readlane_b32 s11, v144, 16
	v_readlane_b32 s14, v144, 32
	v_readlane_b32 s15, v144, 48
	s_nop 3
	v_mov_b32_e32 v144, s11
	v_mov_b32_e32 v145, s15
	v_add_f32_e32 v144, s10, v144
	v_add_f32_e32 v145, s14, v145
	v_add_f32_e32 v144, v144, v145
	v_fmamk_f32 v144, v144, 0x3a800000, v111
	v_rsq_f32_e32 v144, v144
	s_nop 0
	v_mul_f32_e32 v236, v236, v144
	v_mul_f32_e32 v237, v237, v144
	v_mul_f32_e32 v238, v238, v144
	v_mul_f32_e32 v239, v239, v144
	v_mul_f32_e32 v240, v240, v144
	v_mul_f32_e32 v241, v241, v144
	v_mul_f32_e32 v242, v242, v144
	v_mul_f32_e32 v243, v243, v144
	v_mul_f32_e32 v244, v244, v144
	v_mul_f32_e32 v245, v245, v144
	v_mul_f32_e32 v246, v246, v144
	v_mul_f32_e32 v247, v247, v144
	v_mul_f32_e32 v248, v248, v144
	v_mul_f32_e32 v249, v249, v144
	v_mul_f32_e32 v250, v250, v144
	v_mul_f32_e32 v251, v251, v144
	v_dot8c_i32_i4_e32 v38, v122, v48
	v_dot8c_i32_i4_e32 v39, v122, v46
	v_dot8c_i32_i4_e32 v40, v124, v48
	v_dot8c_i32_i4_e32 v41, v124, v46
	v_dot8c_i32_i4_e32 v42, v126, v48
	v_dot8c_i32_i4_e32 v43, v126, v46
	v_dot8c_i32_i4_e32 v44, v128, v48
	v_dot8c_i32_i4_e32 v45, v128, v46
	v_dot8c_i32_i4_e32 v38, v123, v49
	v_dot8c_i32_i4_e32 v39, v123, v47
	v_dot8c_i32_i4_e32 v40, v125, v49
	v_dot8c_i32_i4_e32 v41, v125, v47
	v_dot8c_i32_i4_e32 v42, v127, v49
	v_dot8c_i32_i4_e32 v43, v127, v47
	v_dot8c_i32_i4_e32 v44, v129, v49
	v_dot8c_i32_i4_e32 v45, v129, v47
	v_and_b32_e32 v78, 0xffff, v24
	v_lshrrev_b32_e32 v79, 16, v24
	v_lshl_add_u32 v78, v78, 7, v150
	v_lshl_add_u32 v79, v79, 7, v151
	s_mov_b32 m0, s98
	s_add_i32 s43, s98, 0x400
	global_load_lds_dwordx4 v78, s[50:51]
	s_mov_b32 m0, s43
	s_nop 0
	global_load_lds_dwordx4 v79, s[50:51]
	s_waitcnt vmcnt(9)
	v_add_u32_e32 v54, s76, v59
	v_add_u32_e32 v55, s76, v60
	v_add_u32_e32 v56, s76, v61
	v_add_u32_e32 v57, s76, v62
	ds_read_b64_tr_b4 v[46:47], v160 offset:256
	ds_read_b64_tr_b4 v[48:49], v160 offset:1280
	ds_read_b64_tr_b4 v[122:123], v54
	ds_read_b64_tr_b4 v[124:125], v55
	ds_read_b64_tr_b4 v[126:127], v56
	ds_read_b64_tr_b4 v[128:129], v57
	s_waitcnt lgkmcnt(6)
	v_dot8c_i32_i4_e32 v38, v130, v52
	v_dot8c_i32_i4_e32 v39, v130, v50
	v_dot8c_i32_i4_e32 v40, v132, v52
	v_dot8c_i32_i4_e32 v41, v132, v50
	v_dot8c_i32_i4_e32 v42, v134, v52
	v_dot8c_i32_i4_e32 v43, v134, v50
	v_dot8c_i32_i4_e32 v44, v136, v52
	v_dot8c_i32_i4_e32 v45, v136, v50
	v_dot8c_i32_i4_e32 v38, v131, v53
	v_dot8c_i32_i4_e32 v39, v131, v51
	v_dot8c_i32_i4_e32 v40, v133, v53
	v_dot8c_i32_i4_e32 v41, v133, v51
	v_dot8c_i32_i4_e32 v42, v135, v53
	v_dot8c_i32_i4_e32 v43, v135, v51
	v_dot8c_i32_i4_e32 v44, v137, v53
	v_dot8c_i32_i4_e32 v45, v137, v51
	v_and_b32_e32 v78, 0xffff, v25
	v_lshrrev_b32_e32 v79, 16, v25
	v_lshl_add_u32 v78, v78, 7, v150
	v_lshl_add_u32 v79, v79, 7, v151
	s_mov_b32 m0, s99
	s_add_i32 s43, s99, 0x400
	global_load_lds_dwordx4 v78, s[50:51]
	s_mov_b32 m0, s43
	s_nop 0
	global_load_lds_dwordx4 v79, s[50:51]
	s_waitcnt vmcnt(9)
; #define LAS __attribute__((address_space(3)))
; #define TR4(p_) __builtin_amdgcn_ds_read_tr4_b64_v2i32((LAS v2i*)(p_))
; #define CFENCE() asm volatile("" ::: "memory")
; __device__ __forceinline__ void peer_v_tokens(int j, const LAS unsigned short* EL, const LAS unsigned char* AL  , const LAS float* ASC  , const LAS int* SAL  , ...
;     ...
;         for (int m = 0; m < 2; ++m) {
;             const int idx = lane + 64 * m, tau = idx >> 4, sr = idx & 15, k = 16 * (sr & 7) + 2 * tau + (sr >> 3);
;             const int aq = (int)*(const LAS signed char*)(AL + tl * 128 + k); const int tq = aq + 8;
;             const unsigned lo = (((unsigned)tq & 15u) ^ 8u) * 0x11111111u, hi = ((unsigned)(tq >> 4) & 15u) * 0x11111111u;
;             typedef unsigned u2v __attribute__((ext_vector_type(2)));
;             u2v l2; l2.x = lo; l2.y = lo; u2v h2; h2.x = hi; h2.y = hi;
;             *(LAS u2v*)(ATL + 8 * idx) = l2; *(LAS u2v*)(ATL + 1024 + 8 * idx) = h2;
;         }
;         const float asc = ASC[tl]; const int sa = SAL[tl];
;         CFENCE();
;         int accH[4], accL[4];
; #pragma unroll
;         for (int st = 0; st < 16; ++st) {
;             const int p = st >> 2, q = st & 3;
;             if (st < 14) VDMA(st + 2, (st + 2) % 3);
;             if (st < 14) asm volatile("s_waitcnt vmcnt(8)" ::: "memory");
;             else if (st == 14) asm volatile("s_waitcnt vmcnt(4)" ::: "memory");
;             else asm volatile("s_waitcnt vmcnt(0)" ::: "memory");
;             if (q == 0) {
; #pragma unroll
;                 for (int r = 0; r < 4; ++r) { accH[r] = 0; accL[r] = 0; } }
; #pragma unroll
;             for (int tp = 0; tp < 2; ++tp) {
;                 const v2i ao = TR4(ATL + (2 * q + tp) * 128 + 8 * s16), ah = TR4(ATL + 1024 + (2 * q + tp) * 128 + 8 * s16);
; #pragma unroll
;                 for (int r = 0; r < 4; ++r) {
;                     const v2i d = TR4(ldsb + BUF[st % 3] + 2048 * tp + roff[r]);
;                     accH[r] = __builtin_amdgcn_sdot8(d.x, ah.x, accH[r], false); accH[r] = __builtin_amdgcn_sdot8(d.y, ah.y, accH[r], false);
;                     accL[r] = __builtin_amdgcn_sdot8(d.x, ao.x, accL[r], false); accL[r] = __builtin_amdgcn_sdot8(d.y, ao.y, accL[r], false);
;                 }
;             }
	v_add_u32_e32 v54, s77, v59
	v_add_u32_e32 v55, s77, v60
	v_add_u32_e32 v56, s77, v61
	v_add_u32_e32 v57, s77, v62
	ds_read_b64_tr_b4 v[50:51], v160 offset:384
	ds_read_b64_tr_b4 v[52:53], v160 offset:1408
	ds_read_b64_tr_b4 v[130:131], v54
	ds_read_b64_tr_b4 v[132:133], v55
	ds_read_b64_tr_b4 v[134:135], v56
	ds_read_b64_tr_b4 v[136:137], v57
	s_waitcnt lgkmcnt(6)
	v_dot8c_i32_i4_e32 v38, v122, v48
	v_dot8c_i32_i4_e32 v39, v122, v46
	v_dot8c_i32_i4_e32 v40, v124, v48
	v_dot8c_i32_i4_e32 v41, v124, v46
	v_dot8c_i32_i4_e32 v42, v126, v48
	v_dot8c_i32_i4_e32 v43, v126, v46
	v_dot8c_i32_i4_e32 v44, v128, v48
	v_dot8c_i32_i4_e32 v45, v128, v46
	v_dot8c_i32_i4_e32 v38, v123, v49
	v_dot8c_i32_i4_e32 v39, v123, v47
	v_dot8c_i32_i4_e32 v40, v125, v49
	v_dot8c_i32_i4_e32 v41, v125, v47
	v_dot8c_i32_i4_e32 v42, v127, v49
	v_dot8c_i32_i4_e32 v43, v127, v47
	v_dot8c_i32_i4_e32 v44, v129, v49
	v_dot8c_i32_i4_e32 v45, v129, v47
	s_waitcnt lgkmcnt(15)
	v_and_b32_e32 v78, 0xffff, v26
	v_lshrrev_b32_e32 v79, 16, v26
	v_lshl_add_u32 v78, v78, 7, v150
	v_lshl_add_u32 v79, v79, 7, v151
	s_mov_b32 m0, s76
	s_add_i32 s43, s76, 0x400
	global_load_lds_dwordx4 v78, s[50:51]
	s_mov_b32 m0, s43
	s_nop 0
	global_load_lds_dwordx4 v79, s[50:51]
	s_waitcnt vmcnt(9)
	v_add_u32_e32 v54, s78, v59
	v_add_u32_e32 v55, s78, v60
	v_add_u32_e32 v56, s78, v61
	v_add_u32_e32 v57, s78, v62
	ds_read_b64_tr_b4 v[46:47], v160 offset:512
	ds_read_b64_tr_b4 v[48:49], v160 offset:1536
	ds_read_b64_tr_b4 v[122:123], v54
	ds_read_b64_tr_b4 v[124:125], v55
	ds_read_b64_tr_b4 v[126:127], v56
	ds_read_b64_tr_b4 v[128:129], v57
	s_waitcnt lgkmcnt(6)
	v_dot8c_i32_i4_e32 v38, v130, v52
	v_dot8c_i32_i4_e32 v39, v130, v50
	v_dot8c_i32_i4_e32 v40, v132, v52
	v_dot8c_i32_i4_e32 v41, v132, v50
	v_dot8c_i32_i4_e32 v42, v134, v52
	v_dot8c_i32_i4_e32 v43, v134, v50
	v_dot8c_i32_i4_e32 v44, v136, v52
	v_dot8c_i32_i4_e32 v45, v136, v50
	v_dot8c_i32_i4_e32 v38, v131, v53
	v_dot8c_i32_i4_e32 v39, v131, v51
	v_dot8c_i32_i4_e32 v40, v133, v53
	v_dot8c_i32_i4_e32 v41, v133, v51
	v_dot8c_i32_i4_e32 v42, v135, v53
	v_dot8c_i32_i4_e32 v43, v135, v51
	v_dot8c_i32_i4_e32 v44, v137, v53
	v_dot8c_i32_i4_e32 v45, v137, v51
	v_and_b32_e32 v78, 0xffff, v27
	v_lshrrev_b32_e32 v79, 16, v27
	v_lshl_add_u32 v78, v78, 7, v150
	v_lshl_add_u32 v79, v79, 7, v151
	s_mov_b32 m0, s77
	s_add_i32 s43, s77, 0x400
	global_load_lds_dwordx4 v78, s[50:51]
	s_mov_b32 m0, s43
	s_nop 0
	global_load_lds_dwordx4 v79, s[50:51]
	s_waitcnt vmcnt(8)
	v_add_u32_e32 v54, s79, v59
	v_add_u32_e32 v55, s79, v60
	v_add_u32_e32 v56, s79, v61
	v_add_u32_e32 v57, s79, v62
	ds_read_b64_tr_b4 v[50:51], v160 offset:640
	ds_read_b64_tr_b4 v[52:53], v160 offset:1664
	ds_read_b64_tr_b4 v[130:131], v54
	ds_read_b64_tr_b4 v[132:133], v55
	ds_read_b64_tr_b4 v[134:135], v56
	ds_read_b64_tr_b4 v[136:137], v57
	s_waitcnt lgkmcnt(6)
	v_dot8c_i32_i4_e32 v38, v122, v48
	v_dot8c_i32_i4_e32 v39, v122, v46
	v_dot8c_i32_i4_e32 v40, v124, v48
	v_dot8c_i32_i4_e32 v41, v124, v46
	v_dot8c_i32_i4_e32 v42, v126, v48
	v_dot8c_i32_i4_e32 v43, v126, v46
	v_dot8c_i32_i4_e32 v44, v128, v48
	v_dot8c_i32_i4_e32 v45, v128, v46
	v_dot8c_i32_i4_e32 v38, v123, v49
	v_dot8c_i32_i4_e32 v39, v123, v47
	v_dot8c_i32_i4_e32 v40, v125, v49
	v_dot8c_i32_i4_e32 v41, v125, v47
	v_dot8c_i32_i4_e32 v42, v127, v49
	v_dot8c_i32_i4_e32 v43, v127, v47
	v_dot8c_i32_i4_e32 v44, v129, v49
	v_dot8c_i32_i4_e32 v45, v129, v47
	s_waitcnt lgkmcnt(15)
	v_add_u32_e32 v143, 8, v139
	v_and_b32_e32 v142, 15, v143
	v_xor_b32_e32 v142, 8, v142
	v_bfe_u32 v144, v143, 4, 4
	v_mul_lo_u32 v142, v142, s92
	v_mul_lo_u32 v144, v144, s92
	v_mov_b32_e32 v143, v142
	v_mov_b32_e32 v145, v144
	ds_write2st64_b64 v159, v[142:143], v[144:145] offset1:2
	v_and_b32_e32 v78, 0xffff, v28
	v_lshrrev_b32_e32 v79, 16, v28
	v_lshl_add_u32 v78, v78, 7, v150
	v_lshl_add_u32 v79, v79, 7, v151
	s_mov_b32 m0, s78
	s_add_i32 s43, s78, 0x400
	global_load_lds_dwordx4 v78, s[50:51]
	s_mov_b32 m0, s43
	s_nop 0
	global_load_lds_dwordx4 v79, s[50:51]
	s_waitcnt vmcnt(8)
	v_add_u32_e32 v54, s98, v59
	v_add_u32_e32 v55, s98, v60
	v_add_u32_e32 v56, s98, v61
	v_add_u32_e32 v57, s98, v62
	ds_read_b64_tr_b4 v[46:47], v160 offset:768
	ds_read_b64_tr_b4 v[48:49], v160 offset:1792
	ds_read_b64_tr_b4 v[122:123], v54
	ds_read_b64_tr_b4 v[124:125], v55
	ds_read_b64_tr_b4 v[126:127], v56
	ds_read_b64_tr_b4 v[128:129], v57
	s_waitcnt lgkmcnt(7)
	v_dot8c_i32_i4_e32 v38, v130, v52
	v_dot8c_i32_i4_e32 v39, v130, v50
	v_dot8c_i32_i4_e32 v40, v132, v52
	v_dot8c_i32_i4_e32 v41, v132, v50
	v_dot8c_i32_i4_e32 v42, v134, v52
	v_dot8c_i32_i4_e32 v43, v134, v50
	v_dot8c_i32_i4_e32 v44, v136, v52
	v_dot8c_i32_i4_e32 v45, v136, v50
	v_dot8c_i32_i4_e32 v38, v131, v53
	v_dot8c_i32_i4_e32 v39, v131, v51
	v_dot8c_i32_i4_e32 v40, v133, v53
	v_dot8c_i32_i4_e32 v41, v133, v51
	v_dot8c_i32_i4_e32 v42, v135, v53
	v_dot8c_i32_i4_e32 v43, v135, v51
	v_dot8c_i32_i4_e32 v44, v137, v53
	v_dot8c_i32_i4_e32 v45, v137, v51
	v_and_b32_e32 v78, 0xffff, v29
	v_lshrrev_b32_e32 v79, 16, v29
	v_lshl_add_u32 v78, v78, 7, v150
	v_lshl_add_u32 v79, v79, 7, v151
	s_mov_b32 m0, s79
	s_add_i32 s43, s79, 0x400
	global_load_lds_dwordx4 v78, s[50:51]
	s_mov_b32 m0, s43
	s_nop 0
	global_load_lds_dwordx4 v79, s[50:51]
	s_waitcnt vmcnt(8)
	v_add_u32_e32 v54, s99, v59
	v_add_u32_e32 v55, s99, v60
	v_add_u32_e32 v56, s99, v61
	v_add_u32_e32 v57, s99, v62
	ds_read_b64_tr_b4 v[50:51], v160 offset:896
	ds_read_b64_tr_b4 v[52:53], v160 offset:1920
	ds_read_b64_tr_b4 v[130:131], v54
	ds_read_b64_tr_b4 v[132:133], v55
	ds_read_b64_tr_b4 v[134:135], v56
	ds_read_b64_tr_b4 v[136:137], v57
	s_waitcnt lgkmcnt(6)
; __device__ __forceinline__ void peer_v_tokens(int j, const LAS unsigned short* EL, const LAS unsigned char* AL  , const LAS float* ASC  , const LAS int* SAL  , ...
;     ...
; #pragma unroll 1
;     for (int it = 0; it < 8; ++it) {
;         const int tl = it * 8 + wave, t = j * 64 + tl;
;         unsigned E[8];
;         { const LAS v4u* ep = (const LAS v4u*)(EL + tl * 128 + 16 * g); const v4u e0 = ep[0], e1 = ep[1];
;           E[0] = e0.x; E[1] = e0.y; E[2] = e0.z; E[3] = e0.w; E[4] = e1.x; E[5] = e1.y; E[6] = e1.z; E[7] = e1.w; }
;         uint2 hv[4]; float4 gv[4];
;         { unsigned ho = (unsigned)t * (D / 4) + (unsigned)lane; asm volatile("" : "+v"(ho)); const uint2* hp = (const uint2*)HB + ho; const float4* gp = (const float4*)fng + lane;
; #pragma unroll
;           for (int jq = 0; jq < 4; ++jq) { hv[jq] = hp[64 * jq]; gv[jq] = gp[64 * jq]; } }
;         VDMA(0, 0); VDMA(1, 1);
; #pragma unroll
;         for (int m = 0; m < 2; ++m) {
;             const int idx = lane + 64 * m, tau = idx >> 4, sr = idx & 15, k = 16 * (sr & 7) + 2 * tau + (sr >> 3);
;             const int aq = (int)*(const LAS signed char*)(AL + tl * 128 + k); const int tq = aq + 8;
;             const unsigned lo = (((unsigned)tq & 15u) ^ 8u) * 0x11111111u, hi = ((unsigned)(tq >> 4) & 15u) * 0x11111111u;
;             typedef unsigned u2v __attribute__((ext_vector_type(2)));
;             u2v l2; l2.x = lo; l2.y = lo; u2v h2; h2.x = hi; h2.y = hi;
;             *(LAS u2v*)(ATL + 8 * idx) = l2; *(LAS u2v*)(ATL + 1024 + 8 * idx) = h2;
;         }
;         const float asc = ASC[tl]; const int sa = SAL[tl];
;         CFENCE();
;         int accH[4], accL[4];
; #pragma unroll
;         for (int st = 0; st < 16; ++st) {
;             const int p = st >> 2, q = st & 3;
;             if (st < 14) VDMA(st + 2, (st + 2) % 3);
;             if (st < 14) asm volatile("s_waitcnt vmcnt(8)" ::: "memory");
;             else if (st == 14) asm volatile("s_waitcnt vmcnt(4)" ::: "memory");
;             else asm volatile("s_waitcnt vmcnt(0)" ::: "memory");
;             if (q == 0) {
; #pragma unroll
;                 for (int r = 0; r < 4; ++r) { accH[r] = 0; accL[r] = 0; } }
; #pragma unroll
;             for (int tp = 0; tp < 2; ++tp) {
;                 const v2i ao = TR4(ATL + (2 * q + tp) * 128 + 8 * s16), ah = TR4(ATL + 1024 + (2 * q + tp) * 128 + 8 * s16);
; #pragma unroll
	v_dot8c_i32_i4_e32 v38, v122, v48
	v_dot8c_i32_i4_e32 v39, v122, v46
	v_dot8c_i32_i4_e32 v40, v124, v48
	v_dot8c_i32_i4_e32 v41, v124, v46
	v_dot8c_i32_i4_e32 v42, v126, v48
	v_dot8c_i32_i4_e32 v43, v126, v46
	v_dot8c_i32_i4_e32 v44, v128, v48
	v_dot8c_i32_i4_e32 v45, v128, v46
	v_dot8c_i32_i4_e32 v38, v123, v49
	v_dot8c_i32_i4_e32 v39, v123, v47
	v_dot8c_i32_i4_e32 v40, v125, v49
	v_dot8c_i32_i4_e32 v41, v125, v47
	v_dot8c_i32_i4_e32 v42, v127, v49
	v_dot8c_i32_i4_e32 v43, v127, v47
	v_dot8c_i32_i4_e32 v44, v129, v49
	v_dot8c_i32_i4_e32 v45, v129, v47
	v_and_b32_e32 v78, 0xffff, v30
	v_lshrrev_b32_e32 v79, 16, v30
	v_lshl_add_u32 v78, v78, 7, v150
	v_lshl_add_u32 v79, v79, 7, v151
	s_mov_b32 m0, s98
	s_add_i32 s43, s98, 0x400
	global_load_lds_dwordx4 v78, s[50:51]
	s_mov_b32 m0, s43
	s_nop 0
	global_load_lds_dwordx4 v79, s[50:51]
	s_waitcnt vmcnt(8)
	v_add_u32_e32 v54, s76, v59
	v_add_u32_e32 v55, s76, v60
	v_add_u32_e32 v56, s76, v61
	v_add_u32_e32 v57, s76, v62
	ds_read_b64_tr_b4 v[46:47], v160
	ds_read_b64_tr_b4 v[48:49], v160 offset:1024
	ds_read_b64_tr_b4 v[122:123], v54
	ds_read_b64_tr_b4 v[124:125], v55
	ds_read_b64_tr_b4 v[126:127], v56
	ds_read_b64_tr_b4 v[128:129], v57
	s_waitcnt lgkmcnt(6)
	v_dot8c_i32_i4_e32 v38, v130, v52
	v_dot8c_i32_i4_e32 v39, v130, v50
	v_dot8c_i32_i4_e32 v40, v132, v52
	v_dot8c_i32_i4_e32 v41, v132, v50
	v_dot8c_i32_i4_e32 v42, v134, v52
	v_dot8c_i32_i4_e32 v43, v134, v50
	v_dot8c_i32_i4_e32 v44, v136, v52
	v_dot8c_i32_i4_e32 v45, v136, v50
	v_dot8c_i32_i4_e32 v38, v131, v53
	v_dot8c_i32_i4_e32 v39, v131, v51
	v_dot8c_i32_i4_e32 v40, v133, v53
	v_dot8c_i32_i4_e32 v41, v133, v51
	v_dot8c_i32_i4_e32 v42, v135, v53
	v_dot8c_i32_i4_e32 v43, v135, v51
	v_dot8c_i32_i4_e32 v44, v137, v53
	v_dot8c_i32_i4_e32 v45, v137, v51
	s_nop 3
	s_waitcnt lgkmcnt(15)
	v_lshlrev_b32_e32 v38, 5, v38
	v_lshlrev_b32_e32 v39, 1, v39
	v_add3_u32 v38, v39, v229, v38
	v_cvt_f32_i32_e32 v38, v38
	v_mul_f32_e32 v38, v228, v38
	v_lshlrev_b32_e32 v40, 5, v40
	v_lshlrev_b32_e32 v41, 1, v41
	v_add3_u32 v40, v41, v229, v40
	v_cvt_f32_i32_e32 v40, v40
	v_mul_f32_e32 v40, v228, v40
	v_lshlrev_b32_e32 v42, 5, v42
	v_lshlrev_b32_e32 v43, 1, v43
	v_add3_u32 v42, v43, v229, v42
	v_cvt_f32_i32_e32 v42, v42
	v_mul_f32_e32 v42, v228, v42
	v_lshlrev_b32_e32 v44, 5, v44
	v_lshlrev_b32_e32 v45, 1, v45
	v_add3_u32 v44, v45, v229, v44
	v_cvt_f32_i32_e32 v44, v44
	v_mul_f32_e32 v44, v228, v44
	v_cvt_pk_bf16_f32 v166, v38, v40
	v_cvt_pk_bf16_f32 v167, v42, v44
	ds_read_b128 v[252:255], v156 offset:1024
	s_add_i32 s44, s40, 16
	s_ashr_i32 s45, s44, 31
	s_lshl_b64 s[44:45], s[44:45], 12
	v_lshl_add_u64 v[80:81], v[36:37], 0, s[44:45]
	s_waitcnt lgkmcnt(0)
	v_mul_f32_e32 v222, v222, v252
	v_mul_f32_e32 v223, v223, v253
	v_mul_f32_e32 v224, v224, v254
	v_mul_f32_e32 v225, v225, v255
	global_store_dwordx4 v[80:81], v[222:225], off offset:3072 nt
	ds_read_b128 v[252:255], v155
	s_add_i32 s44, s40, 24
	s_ashr_i32 s45, s44, 31
	s_lshl_b64 s[44:45], s[44:45], 12
	v_lshl_add_u64 v[80:81], v[36:37], 0, s[44:45]
	s_waitcnt lgkmcnt(0)
	v_mul_f32_e32 v236, v236, v252
	v_mul_f32_e32 v237, v237, v253
	v_mul_f32_e32 v238, v238, v254
	v_mul_f32_e32 v239, v239, v255
	global_store_dwordx4 v[80:81], v[236:239], off nt
	v_add_u32_e32 v147, 8, v140
	v_and_b32_e32 v146, 15, v147
	v_xor_b32_e32 v146, 8, v146
	v_bfe_u32 v148, v147, 4, 4
	v_mul_lo_u32 v146, v146, s92
	v_mul_lo_u32 v148, v148, s92
	v_mov_b32_e32 v147, v146
	v_mov_b32_e32 v149, v148
	ds_write2st64_b64 v77, v[146:147], v[148:149] offset1:2
	v_add_u32_e32 v138, 0x1000, v74
	ds_read_u8 v139, v138
	v_add_u32_e32 v141, 0x1000, v73
	ds_read_u8 v140, v141
	s_add_i32 s43, s67, 160
	v_mov_b32_e32 v138, s43
	ds_read2st64_b32 v[228:229], v138 offset1:1
	ds_read_b128 v[18:21], v227 offset:8192
	ds_read_b128 v[22:25], v227 offset:8208
	v_add_u32_e32 v152, 0x600000, v63
	v_add_u32_e32 v153, 0x600000, v64
	v_mov_b32_e32 v38, 0
	v_mov_b32_e32 v39, 0
	v_mov_b32_e32 v40, 0
	v_mov_b32_e32 v41, 0
	v_mov_b32_e32 v42, 0
	v_mov_b32_e32 v43, 0
	v_mov_b32_e32 v44, 0
	v_mov_b32_e32 v45, 0
	v_and_b32_e32 v78, 0xffff, v31
	v_lshrrev_b32_e32 v79, 16, v31
	v_lshl_add_u32 v78, v78, 7, v150
	v_lshl_add_u32 v79, v79, 7, v151
	s_mov_b32 m0, s99
	s_add_i32 s43, s99, 0x400
	global_load_lds_dwordx4 v78, s[50:51]
	s_mov_b32 m0, s43
	s_nop 0
	global_load_lds_dwordx4 v79, s[50:51]
	s_waitcnt vmcnt(10)
	v_add_u32_e32 v54, s77, v59
	v_add_u32_e32 v55, s77, v60
	v_add_u32_e32 v56, s77, v61
	v_add_u32_e32 v57, s77, v62
	ds_read_b64_tr_b4 v[50:51], v160 offset:128
	ds_read_b64_tr_b4 v[52:53], v160 offset:1152
	ds_read_b64_tr_b4 v[130:131], v54
	ds_read_b64_tr_b4 v[132:133], v55
	ds_read_b64_tr_b4 v[134:135], v56
	ds_read_b64_tr_b4 v[136:137], v57
	s_waitcnt lgkmcnt(14)
	v_dot8c_i32_i4_e32 v38, v122, v48
	v_dot8c_i32_i4_e32 v39, v122, v46
	v_dot8c_i32_i4_e32 v40, v124, v48
	v_dot8c_i32_i4_e32 v41, v124, v46
	v_dot8c_i32_i4_e32 v42, v126, v48
	v_dot8c_i32_i4_e32 v43, v126, v46
	v_dot8c_i32_i4_e32 v44, v128, v48
	v_dot8c_i32_i4_e32 v45, v128, v46
	v_dot8c_i32_i4_e32 v38, v123, v49
	v_dot8c_i32_i4_e32 v39, v123, v47
	v_dot8c_i32_i4_e32 v40, v125, v49
	v_dot8c_i32_i4_e32 v41, v125, v47
	v_dot8c_i32_i4_e32 v42, v127, v49
	v_dot8c_i32_i4_e32 v43, v127, v47
	v_dot8c_i32_i4_e32 v44, v129, v49
	v_dot8c_i32_i4_e32 v45, v129, v47
	v_and_b32_e32 v78, 0xffff, v32
	v_lshrrev_b32_e32 v79, 16, v32
	v_lshl_add_u32 v78, v78, 7, v150
	v_lshl_add_u32 v79, v79, 7, v151
	s_mov_b32 m0, s76
	s_add_i32 s43, s76, 0x400
	global_load_lds_dwordx4 v78, s[50:51]
	s_mov_b32 m0, s43
	s_nop 0
	global_load_lds_dwordx4 v79, s[50:51]
	s_waitcnt vmcnt(10)
; #define LAS __attribute__((address_space(3)))
; #define TR4(p_) __builtin_amdgcn_ds_read_tr4_b64_v2i32((LAS v2i*)(p_))
; #define CFENCE() asm volatile("" ::: "memory")
; __device__ __forceinline__ void peer_v_tokens(int j, const LAS unsigned short* EL, const LAS unsigned char* AL  , const LAS float* ASC  , const LAS int* SAL  , ...
;     ...
;         for (int m = 0; m < 2; ++m) {
;             const int idx = lane + 64 * m, tau = idx >> 4, sr = idx & 15, k = 16 * (sr & 7) + 2 * tau + (sr >> 3);
;             const int aq = (int)*(const LAS signed char*)(AL + tl * 128 + k); const int tq = aq + 8;
;             const unsigned lo = (((unsigned)tq & 15u) ^ 8u) * 0x11111111u, hi = ((unsigned)(tq >> 4) & 15u) * 0x11111111u;
;             typedef unsigned u2v __attribute__((ext_vector_type(2)));
;             u2v l2; l2.x = lo; l2.y = lo; u2v h2; h2.x = hi; h2.y = hi;
;             *(LAS u2v*)(ATL + 8 * idx) = l2; *(LAS u2v*)(ATL + 1024 + 8 * idx) = h2;
;         }
;         const float asc = ASC[tl]; const int sa = SAL[tl];
;         CFENCE();
;         int accH[4], accL[4];
; #pragma unroll
;         for (int st = 0; st < 16; ++st) {
;             const int p = st >> 2, q = st & 3;
;             if (st < 14) VDMA(st + 2, (st + 2) % 3);
;             if (st < 14) asm volatile("s_waitcnt vmcnt(8)" ::: "memory");
;             else if (st == 14) asm volatile("s_waitcnt vmcnt(4)" ::: "memory");
;             else asm volatile("s_waitcnt vmcnt(0)" ::: "memory");
;             if (q == 0) {
; #pragma unroll
;                 for (int r = 0; r < 4; ++r) { accH[r] = 0; accL[r] = 0; } }
; #pragma unroll
;             for (int tp = 0; tp < 2; ++tp) {
;                 const v2i ao = TR4(ATL + (2 * q + tp) * 128 + 8 * s16), ah = TR4(ATL + 1024 + (2 * q + tp) * 128 + 8 * s16);
; #pragma unroll
;                 for (int r = 0; r < 4; ++r) {
;                     const v2i d = TR4(ldsb + BUF[st % 3] + 2048 * tp + roff[r]);
;                     accH[r] = __builtin_amdgcn_sdot8(d.x, ah.x, accH[r], false); accH[r] = __builtin_amdgcn_sdot8(d.y, ah.y, accH[r], false);
;                     accL[r] = __builtin_amdgcn_sdot8(d.x, ao.x, accL[r], false); accL[r] = __builtin_amdgcn_sdot8(d.y, ao.y, accL[r], false);
;                 }
;             }
	v_add_u32_e32 v54, s78, v59
	v_add_u32_e32 v55, s78, v60
	v_add_u32_e32 v56, s78, v61
	v_add_u32_e32 v57, s78, v62
	ds_read_b64_tr_b4 v[46:47], v160 offset:256
	ds_read_b64_tr_b4 v[48:49], v160 offset:1280
	ds_read_b64_tr_b4 v[122:123], v54
	ds_read_b64_tr_b4 v[124:125], v55
	ds_read_b64_tr_b4 v[126:127], v56
	ds_read_b64_tr_b4 v[128:129], v57
	s_waitcnt lgkmcnt(6)
	v_dot8c_i32_i4_e32 v38, v130, v52
	v_dot8c_i32_i4_e32 v39, v130, v50
	v_dot8c_i32_i4_e32 v40, v132, v52
	v_dot8c_i32_i4_e32 v41, v132, v50
	v_dot8c_i32_i4_e32 v42, v134, v52
	v_dot8c_i32_i4_e32 v43, v134, v50
	v_dot8c_i32_i4_e32 v44, v136, v52
	v_dot8c_i32_i4_e32 v45, v136, v50
	v_dot8c_i32_i4_e32 v38, v131, v53
	v_dot8c_i32_i4_e32 v39, v131, v51
	v_dot8c_i32_i4_e32 v40, v133, v53
	v_dot8c_i32_i4_e32 v41, v133, v51
	v_dot8c_i32_i4_e32 v42, v135, v53
	v_dot8c_i32_i4_e32 v43, v135, v51
	v_dot8c_i32_i4_e32 v44, v137, v53
	v_dot8c_i32_i4_e32 v45, v137, v51
	v_and_b32_e32 v78, 0xffff, v33
	v_lshrrev_b32_e32 v79, 16, v33
	v_lshl_add_u32 v78, v78, 7, v150
	v_lshl_add_u32 v79, v79, 7, v151
	s_mov_b32 m0, s77
	s_add_i32 s43, s77, 0x400
	global_load_lds_dwordx4 v78, s[50:51]
	s_mov_b32 m0, s43
	s_nop 0
	global_load_lds_dwordx4 v79, s[50:51]
	s_waitcnt vmcnt(10)
	v_add_u32_e32 v54, s79, v59
	v_add_u32_e32 v55, s79, v60
	v_add_u32_e32 v56, s79, v61
	v_add_u32_e32 v57, s79, v62
	ds_read_b64_tr_b4 v[50:51], v160 offset:384
	ds_read_b64_tr_b4 v[52:53], v160 offset:1408
	ds_read_b64_tr_b4 v[130:131], v54
	ds_read_b64_tr_b4 v[132:133], v55
	ds_read_b64_tr_b4 v[134:135], v56
	ds_read_b64_tr_b4 v[136:137], v57
	s_waitcnt lgkmcnt(6)
	v_dot8c_i32_i4_e32 v38, v122, v48
	v_dot8c_i32_i4_e32 v39, v122, v46
	v_dot8c_i32_i4_e32 v40, v124, v48
	v_dot8c_i32_i4_e32 v41, v124, v46
	v_dot8c_i32_i4_e32 v42, v126, v48
	v_dot8c_i32_i4_e32 v43, v126, v46
	v_dot8c_i32_i4_e32 v44, v128, v48
	v_dot8c_i32_i4_e32 v45, v128, v46
	v_dot8c_i32_i4_e32 v38, v123, v49
	v_dot8c_i32_i4_e32 v39, v123, v47
	v_dot8c_i32_i4_e32 v40, v125, v49
	v_dot8c_i32_i4_e32 v41, v125, v47
	v_dot8c_i32_i4_e32 v42, v127, v49
	v_dot8c_i32_i4_e32 v43, v127, v47
	v_dot8c_i32_i4_e32 v44, v129, v49
	v_dot8c_i32_i4_e32 v45, v129, v47
	s_waitcnt lgkmcnt(15)
	v_and_b32_e32 v78, 0xffff, v18
	v_lshrrev_b32_e32 v79, 16, v18
	v_lshl_add_u32 v78, v78, 7, v152
	v_lshl_add_u32 v79, v79, 7, v153
	s_mov_b32 m0, s78
	s_add_i32 s43, s78, 0x400
	global_load_lds_dwordx4 v78, s[50:51]
	s_mov_b32 m0, s43
	s_nop 0
	global_load_lds_dwordx4 v79, s[50:51]
	s_waitcnt vmcnt(10)
	v_add_u32_e32 v54, s98, v59
	v_add_u32_e32 v55, s98, v60
	v_add_u32_e32 v56, s98, v61
	v_add_u32_e32 v57, s98, v62
	ds_read_b64_tr_b4 v[46:47], v160 offset:512
	ds_read_b64_tr_b4 v[48:49], v160 offset:1536
	ds_read_b64_tr_b4 v[122:123], v54
	ds_read_b64_tr_b4 v[124:125], v55
	ds_read_b64_tr_b4 v[126:127], v56
	ds_read_b64_tr_b4 v[128:129], v57
	s_waitcnt lgkmcnt(6)
	v_dot8c_i32_i4_e32 v38, v130, v52
	v_dot8c_i32_i4_e32 v39, v130, v50
	v_dot8c_i32_i4_e32 v40, v132, v52
	v_dot8c_i32_i4_e32 v41, v132, v50
	v_dot8c_i32_i4_e32 v42, v134, v52
	v_dot8c_i32_i4_e32 v43, v134, v50
	v_dot8c_i32_i4_e32 v44, v136, v52
	v_dot8c_i32_i4_e32 v45, v136, v50
	v_dot8c_i32_i4_e32 v38, v131, v53
	v_dot8c_i32_i4_e32 v39, v131, v51
	v_dot8c_i32_i4_e32 v40, v133, v53
	v_dot8c_i32_i4_e32 v41, v133, v51
	v_dot8c_i32_i4_e32 v42, v135, v53
	v_dot8c_i32_i4_e32 v43, v135, v51
	v_dot8c_i32_i4_e32 v44, v137, v53
	v_dot8c_i32_i4_e32 v45, v137, v51
	v_and_b32_e32 v78, 0xffff, v19
	v_lshrrev_b32_e32 v79, 16, v19
	v_lshl_add_u32 v78, v78, 7, v152
	v_lshl_add_u32 v79, v79, 7, v153
	s_mov_b32 m0, s79
	s_add_i32 s43, s79, 0x400
	global_load_lds_dwordx4 v78, s[50:51]
	s_mov_b32 m0, s43
	s_nop 0
	global_load_lds_dwordx4 v79, s[50:51]
	s_waitcnt vmcnt(8)
	v_add_u32_e32 v54, s99, v59
	v_add_u32_e32 v55, s99, v60
	v_add_u32_e32 v56, s99, v61
	v_add_u32_e32 v57, s99, v62
	ds_read_b64_tr_b4 v[50:51], v160 offset:640
	ds_read_b64_tr_b4 v[52:53], v160 offset:1664
	ds_read_b64_tr_b4 v[130:131], v54
	ds_read_b64_tr_b4 v[132:133], v55
	ds_read_b64_tr_b4 v[134:135], v56
	ds_read_b64_tr_b4 v[136:137], v57
	s_waitcnt lgkmcnt(6)
	v_dot8c_i32_i4_e32 v38, v122, v48
	v_dot8c_i32_i4_e32 v39, v122, v46
	v_dot8c_i32_i4_e32 v40, v124, v48
	v_dot8c_i32_i4_e32 v41, v124, v46
	v_dot8c_i32_i4_e32 v42, v126, v48
	v_dot8c_i32_i4_e32 v43, v126, v46
	v_dot8c_i32_i4_e32 v44, v128, v48
	v_dot8c_i32_i4_e32 v45, v128, v46
	v_dot8c_i32_i4_e32 v38, v123, v49
	v_dot8c_i32_i4_e32 v39, v123, v47
	v_dot8c_i32_i4_e32 v40, v125, v49
	v_dot8c_i32_i4_e32 v41, v125, v47
	v_dot8c_i32_i4_e32 v42, v127, v49
	v_dot8c_i32_i4_e32 v43, v127, v47
	v_dot8c_i32_i4_e32 v44, v129, v49
	v_dot8c_i32_i4_e32 v45, v129, v47
	s_waitcnt lgkmcnt(15)
	v_add_u32_e32 v143, 8, v139
	v_and_b32_e32 v142, 15, v143
	v_xor_b32_e32 v142, 8, v142
	v_bfe_u32 v144, v143, 4, 4
	v_mul_lo_u32 v142, v142, s92
	v_mul_lo_u32 v144, v144, s92
	v_mov_b32_e32 v143, v142
	v_mov_b32_e32 v145, v144
	ds_write2st64_b64 v159, v[142:143], v[144:145] offset1:2
	v_and_b32_e32 v78, 0xffff, v20
	v_lshrrev_b32_e32 v79, 16, v20
	v_lshl_add_u32 v78, v78, 7, v152
	v_lshl_add_u32 v79, v79, 7, v153
	s_mov_b32 m0, s98
	s_add_i32 s43, s98, 0x400
	global_load_lds_dwordx4 v78, s[50:51]
	s_mov_b32 m0, s43
	s_nop 0
	global_load_lds_dwordx4 v79, s[50:51]
	s_waitcnt vmcnt(8)
	v_add_u32_e32 v54, s76, v59
	v_add_u32_e32 v55, s76, v60
	v_add_u32_e32 v56, s76, v61
	v_add_u32_e32 v57, s76, v62
	ds_read_b64_tr_b4 v[46:47], v160 offset:768
	ds_read_b64_tr_b4 v[48:49], v160 offset:1792
	ds_read_b64_tr_b4 v[122:123], v54
	ds_read_b64_tr_b4 v[124:125], v55
	ds_read_b64_tr_b4 v[126:127], v56
	ds_read_b64_tr_b4 v[128:129], v57
	s_waitcnt lgkmcnt(7)
; __device__ __forceinline__ void peer_v_tokens(int j, const LAS unsigned short* EL, const LAS unsigned char* AL  , const LAS float* ASC  , const LAS int* SAL  , ...
;     ...
; #pragma unroll 1
;     for (int it = 0; it < 8; ++it) {
;         const int tl = it * 8 + wave, t = j * 64 + tl;
;         unsigned E[8];
;         { const LAS v4u* ep = (const LAS v4u*)(EL + tl * 128 + 16 * g); const v4u e0 = ep[0], e1 = ep[1];
;           E[0] = e0.x; E[1] = e0.y; E[2] = e0.z; E[3] = e0.w; E[4] = e1.x; E[5] = e1.y; E[6] = e1.z; E[7] = e1.w; }
;         uint2 hv[4]; float4 gv[4];
;         { unsigned ho = (unsigned)t * (D / 4) + (unsigned)lane; asm volatile("" : "+v"(ho)); const uint2* hp = (const uint2*)HB + ho; const float4* gp = (const float4*)fng + lane;
; #pragma unroll
;           for (int jq = 0; jq < 4; ++jq) { hv[jq] = hp[64 * jq]; gv[jq] = gp[64 * jq]; } }
;         VDMA(0, 0); VDMA(1, 1);
; #pragma unroll
;         for (int m = 0; m < 2; ++m) {
;             const int idx = lane + 64 * m, tau = idx >> 4, sr = idx & 15, k = 16 * (sr & 7) + 2 * tau + (sr >> 3);
;             const int aq = (int)*(const LAS signed char*)(AL + tl * 128 + k); const int tq = aq + 8;
;             const unsigned lo = (((unsigned)tq & 15u) ^ 8u) * 0x11111111u, hi = ((unsigned)(tq >> 4) & 15u) * 0x11111111u;
;             typedef unsigned u2v __attribute__((ext_vector_type(2)));
;             u2v l2; l2.x = lo; l2.y = lo; u2v h2; h2.x = hi; h2.y = hi;
;             *(LAS u2v*)(ATL + 8 * idx) = l2; *(LAS u2v*)(ATL + 1024 + 8 * idx) = h2;
;         }
;         const float asc = ASC[tl]; const int sa = SAL[tl];
;         CFENCE();
;         int accH[4], accL[4];
; #pragma unroll
;         for (int st = 0; st < 16; ++st) {
;             const int p = st >> 2, q = st & 3;
;             if (st < 14) VDMA(st + 2, (st + 2) % 3);
;             if (st < 14) asm volatile("s_waitcnt vmcnt(8)" ::: "memory");
;             else if (st == 14) asm volatile("s_waitcnt vmcnt(4)" ::: "memory");
;             else asm volatile("s_waitcnt vmcnt(0)" ::: "memory");
;             if (q == 0) {
; #pragma unroll
;                 for (int r = 0; r < 4; ++r) { accH[r] = 0; accL[r] = 0; } }
; #pragma unroll
;             for (int tp = 0; tp < 2; ++tp) {
;                 const v2i ao = TR4(ATL + (2 * q + tp) * 128 + 8 * s16), ah = TR4(ATL + 1024 + (2 * q + tp) * 128 + 8 * s16);
; #pragma unroll
	v_dot8c_i32_i4_e32 v38, v130, v52
	v_dot8c_i32_i4_e32 v39, v130, v50
	v_dot8c_i32_i4_e32 v40, v132, v52
	v_dot8c_i32_i4_e32 v41, v132, v50
	v_dot8c_i32_i4_e32 v42, v134, v52
	v_dot8c_i32_i4_e32 v43, v134, v50
	v_dot8c_i32_i4_e32 v44, v136, v52
	v_dot8c_i32_i4_e32 v45, v136, v50
	v_dot8c_i32_i4_e32 v38, v131, v53
	v_dot8c_i32_i4_e32 v39, v131, v51
	v_dot8c_i32_i4_e32 v40, v133, v53
	v_dot8c_i32_i4_e32 v41, v133, v51
	v_dot8c_i32_i4_e32 v42, v135, v53
	v_dot8c_i32_i4_e32 v43, v135, v51
	v_dot8c_i32_i4_e32 v44, v137, v53
	v_dot8c_i32_i4_e32 v45, v137, v51
	v_and_b32_e32 v78, 0xffff, v21
	v_lshrrev_b32_e32 v79, 16, v21
	v_lshl_add_u32 v78, v78, 7, v152
	v_lshl_add_u32 v79, v79, 7, v153
	s_mov_b32 m0, s99
	s_add_i32 s43, s99, 0x400
	global_load_lds_dwordx4 v78, s[50:51]
	s_mov_b32 m0, s43
	s_nop 0
	global_load_lds_dwordx4 v79, s[50:51]
	s_waitcnt vmcnt(8)
	v_add_u32_e32 v54, s77, v59
	v_add_u32_e32 v55, s77, v60
	v_add_u32_e32 v56, s77, v61
	v_add_u32_e32 v57, s77, v62
	ds_read_b64_tr_b4 v[50:51], v160 offset:896
	ds_read_b64_tr_b4 v[52:53], v160 offset:1920
	ds_read_b64_tr_b4 v[130:131], v54
	ds_read_b64_tr_b4 v[132:133], v55
	ds_read_b64_tr_b4 v[134:135], v56
	ds_read_b64_tr_b4 v[136:137], v57
	s_waitcnt lgkmcnt(6)
	v_dot8c_i32_i4_e32 v38, v122, v48
	v_dot8c_i32_i4_e32 v39, v122, v46
	v_dot8c_i32_i4_e32 v40, v124, v48
	v_dot8c_i32_i4_e32 v41, v124, v46
	v_dot8c_i32_i4_e32 v42, v126, v48
	v_dot8c_i32_i4_e32 v43, v126, v46
	v_dot8c_i32_i4_e32 v44, v128, v48
	v_dot8c_i32_i4_e32 v45, v128, v46
	v_dot8c_i32_i4_e32 v38, v123, v49
	v_dot8c_i32_i4_e32 v39, v123, v47
	v_dot8c_i32_i4_e32 v40, v125, v49
	v_dot8c_i32_i4_e32 v41, v125, v47
	v_dot8c_i32_i4_e32 v42, v127, v49
	v_dot8c_i32_i4_e32 v43, v127, v47
	v_dot8c_i32_i4_e32 v44, v129, v49
	v_dot8c_i32_i4_e32 v45, v129, v47
	v_and_b32_e32 v78, 0xffff, v22
	v_lshrrev_b32_e32 v79, 16, v22
	v_lshl_add_u32 v78, v78, 7, v152
	v_lshl_add_u32 v79, v79, 7, v153
	s_mov_b32 m0, s76
	s_add_i32 s43, s76, 0x400
	global_load_lds_dwordx4 v78, s[50:51]
	s_mov_b32 m0, s43
	s_nop 0
	global_load_lds_dwordx4 v79, s[50:51]
	s_waitcnt vmcnt(8)
	v_add_u32_e32 v54, s78, v59
	v_add_u32_e32 v55, s78, v60
	v_add_u32_e32 v56, s78, v61
	v_add_u32_e32 v57, s78, v62
	ds_read_b64_tr_b4 v[46:47], v160
	ds_read_b64_tr_b4 v[48:49], v160 offset:1024
	ds_read_b64_tr_b4 v[122:123], v54
	ds_read_b64_tr_b4 v[124:125], v55
	ds_read_b64_tr_b4 v[126:127], v56
	ds_read_b64_tr_b4 v[128:129], v57
	s_waitcnt lgkmcnt(6)
	v_dot8c_i32_i4_e32 v38, v130, v52
	v_dot8c_i32_i4_e32 v39, v130, v50
	v_dot8c_i32_i4_e32 v40, v132, v52
	v_dot8c_i32_i4_e32 v41, v132, v50
	v_dot8c_i32_i4_e32 v42, v134, v52
	v_dot8c_i32_i4_e32 v43, v134, v50
	v_dot8c_i32_i4_e32 v44, v136, v52
	v_dot8c_i32_i4_e32 v45, v136, v50
	v_dot8c_i32_i4_e32 v38, v131, v53
	v_dot8c_i32_i4_e32 v39, v131, v51
	v_dot8c_i32_i4_e32 v40, v133, v53
	v_dot8c_i32_i4_e32 v41, v133, v51
	v_dot8c_i32_i4_e32 v42, v135, v53
	v_dot8c_i32_i4_e32 v43, v135, v51
	v_dot8c_i32_i4_e32 v44, v137, v53
	v_dot8c_i32_i4_e32 v45, v137, v51
	s_nop 3
	s_waitcnt lgkmcnt(15)
	v_lshlrev_b32_e32 v38, 5, v38
	v_lshlrev_b32_e32 v39, 1, v39
	v_add3_u32 v38, v39, v229, v38
	v_cvt_f32_i32_e32 v38, v38
	v_mul_f32_e32 v38, v228, v38
	v_lshlrev_b32_e32 v40, 5, v40
	v_lshlrev_b32_e32 v41, 1, v41
	v_add3_u32 v40, v41, v229, v40
	v_cvt_f32_i32_e32 v40, v40
	v_mul_f32_e32 v40, v228, v40
	v_lshlrev_b32_e32 v42, 5, v42
	v_lshlrev_b32_e32 v43, 1, v43
	v_add3_u32 v42, v43, v229, v42
	v_cvt_f32_i32_e32 v42, v42
	v_mul_f32_e32 v42, v228, v42
	v_lshlrev_b32_e32 v44, 5, v44
	v_lshlrev_b32_e32 v45, 1, v45
	v_add3_u32 v44, v45, v229, v44
	v_cvt_f32_i32_e32 v44, v44
	v_mul_f32_e32 v44, v228, v44
	v_cvt_pk_bf16_f32 v174, v38, v40
	v_cvt_pk_bf16_f32 v175, v42, v44
	ds_read_b128 v[252:255], v155 offset:1024
	s_add_i32 s44, s40, 24
	s_ashr_i32 s45, s44, 31
	s_lshl_b64 s[44:45], s[44:45], 12
	v_lshl_add_u64 v[80:81], v[36:37], 0, s[44:45]
	s_waitcnt lgkmcnt(0)
	v_mul_f32_e32 v240, v240, v252
	v_mul_f32_e32 v241, v241, v253
	v_mul_f32_e32 v242, v242, v254
	v_mul_f32_e32 v243, v243, v255
	global_store_dwordx4 v[80:81], v[240:243], off offset:1024 nt
	v_add_u32_e32 v147, 8, v140
	v_and_b32_e32 v146, 15, v147
	v_xor_b32_e32 v146, 8, v146
	v_bfe_u32 v148, v147, 4, 4
	v_mul_lo_u32 v146, v146, s92
	v_mul_lo_u32 v148, v148, s92
	v_mov_b32_e32 v147, v146
	v_mov_b32_e32 v149, v148
	ds_write2st64_b64 v77, v[146:147], v[148:149] offset1:2
	v_add_u32_e32 v138, 0x1400, v74
	ds_read_u8 v139, v138
	v_add_u32_e32 v141, 0x1400, v73
	ds_read_u8 v140, v141
	s_add_i32 s43, s67, 128
	v_mov_b32_e32 v138, s43
	ds_read2st64_b32 v[228:229], v138 offset1:1
	ds_read_b128 v[26:29], v227 offset:10240
	ds_read_b128 v[30:33], v227 offset:10256
	v_mov_b32_e32 v38, 0
	v_mov_b32_e32 v39, 0
	v_mov_b32_e32 v40, 0
	v_mov_b32_e32 v41, 0
	v_mov_b32_e32 v42, 0
	v_mov_b32_e32 v43, 0
	v_mov_b32_e32 v44, 0
	v_mov_b32_e32 v45, 0
	v_and_b32_e32 v78, 0xffff, v23
	v_lshrrev_b32_e32 v79, 16, v23
	v_lshl_add_u32 v78, v78, 7, v152
	v_lshl_add_u32 v79, v79, 7, v153
	s_mov_b32 m0, s77
	s_add_i32 s43, s77, 0x400
	global_load_lds_dwordx4 v78, s[50:51]
	s_mov_b32 m0, s43
	s_nop 0
	global_load_lds_dwordx4 v79, s[50:51]
	s_waitcnt vmcnt(9)
	v_add_u32_e32 v54, s79, v59
	v_add_u32_e32 v55, s79, v60
	v_add_u32_e32 v56, s79, v61
	v_add_u32_e32 v57, s79, v62
	ds_read_b64_tr_b4 v[50:51], v160 offset:128
	ds_read_b64_tr_b4 v[52:53], v160 offset:1152
	ds_read_b64_tr_b4 v[130:131], v54
	ds_read_b64_tr_b4 v[132:133], v55
	ds_read_b64_tr_b4 v[134:135], v56
	ds_read_b64_tr_b4 v[136:137], v57
	s_waitcnt lgkmcnt(13)
; #define TR4(p_) __builtin_amdgcn_ds_read_tr4_b64_v2i32((LAS v2i*)(p_))
; #define VDMA(st_, k_) do { _Pragma("unroll") for (int i_ = 0; i_ < 4; ++i_) { \
;         const unsigned off_ = (unsigned)((st_) >> 2) * (16384u * 128u) + (PE_ID(E, 4 * ((st_) & 3) + i_) << 7) + ((i_ & 1) ? cx1 : cx0); \
;         __builtin_amdgcn_global_load_lds((const unsigned*)(V4 + off_), (LAS unsigned*)(ldsb + BUF[k_] + 1024 * i_), 16, 0, 0); } } while (0)
; __device__ __forceinline__ void peer_v_tokens(int j, const LAS unsigned short* EL, const LAS unsigned char* AL  , const LAS float* ASC  , const LAS int* SAL  , ...
;     ...
;         for (int st = 0; st < 16; ++st) {
;             const int p = st >> 2, q = st & 3;
;             if (st < 14) VDMA(st + 2, (st + 2) % 3);
;             if (st < 14) asm volatile("s_waitcnt vmcnt(8)" ::: "memory");
;             else if (st == 14) asm volatile("s_waitcnt vmcnt(4)" ::: "memory");
;             else asm volatile("s_waitcnt vmcnt(0)" ::: "memory");
;             if (q == 0) {
; #pragma unroll
;                 for (int r = 0; r < 4; ++r) { accH[r] = 0; accL[r] = 0; } }
; #pragma unroll
;             for (int tp = 0; tp < 2; ++tp) {
;                 const v2i ao = TR4(ATL + (2 * q + tp) * 128 + 8 * s16), ah = TR4(ATL + 1024 + (2 * q + tp) * 128 + 8 * s16);
; #pragma unroll
;                 for (int r = 0; r < 4; ++r) {
;                     const v2i d = TR4(ldsb + BUF[st % 3] + 2048 * tp + roff[r]);
;                     accH[r] = __builtin_amdgcn_sdot8(d.x, ah.x, accH[r], false); accH[r] = __builtin_amdgcn_sdot8(d.y, ah.y, accH[r], false);
;                     accL[r] = __builtin_amdgcn_sdot8(d.x, ao.x, accL[r], false); accL[r] = __builtin_amdgcn_sdot8(d.y, ao.y, accL[r], false);
;                 }
;             }
	v_dot8c_i32_i4_e32 v38, v122, v48
	v_dot8c_i32_i4_e32 v39, v122, v46
	v_dot8c_i32_i4_e32 v40, v124, v48
	v_dot8c_i32_i4_e32 v41, v124, v46
	v_dot8c_i32_i4_e32 v42, v126, v48
	v_dot8c_i32_i4_e32 v43, v126, v46
	v_dot8c_i32_i4_e32 v44, v128, v48
	v_dot8c_i32_i4_e32 v45, v128, v46
	v_dot8c_i32_i4_e32 v38, v123, v49
	v_dot8c_i32_i4_e32 v39, v123, v47
	v_dot8c_i32_i4_e32 v40, v125, v49
	v_dot8c_i32_i4_e32 v41, v125, v47
	v_dot8c_i32_i4_e32 v42, v127, v49
	v_dot8c_i32_i4_e32 v43, v127, v47
	v_dot8c_i32_i4_e32 v44, v129, v49
	v_dot8c_i32_i4_e32 v45, v129, v47
	v_and_b32_e32 v78, 0xffff, v24
	v_lshrrev_b32_e32 v79, 16, v24
	v_lshl_add_u32 v78, v78, 7, v152
	v_lshl_add_u32 v79, v79, 7, v153
	s_mov_b32 m0, s78
	s_add_i32 s43, s78, 0x400
	global_load_lds_dwordx4 v78, s[50:51]
	s_mov_b32 m0, s43
	s_nop 0
	global_load_lds_dwordx4 v79, s[50:51]
	s_waitcnt vmcnt(9)
	v_add_u32_e32 v54, s98, v59
	v_add_u32_e32 v55, s98, v60
	v_add_u32_e32 v56, s98, v61
	v_add_u32_e32 v57, s98, v62
	ds_read_b64_tr_b4 v[46:47], v160 offset:256
	ds_read_b64_tr_b4 v[48:49], v160 offset:1280
	ds_read_b64_tr_b4 v[122:123], v54
	ds_read_b64_tr_b4 v[124:125], v55
	ds_read_b64_tr_b4 v[126:127], v56
	ds_read_b64_tr_b4 v[128:129], v57
	s_waitcnt lgkmcnt(6)
	v_dot8c_i32_i4_e32 v38, v130, v52
	v_dot8c_i32_i4_e32 v39, v130, v50
	v_dot8c_i32_i4_e32 v40, v132, v52
	v_dot8c_i32_i4_e32 v41, v132, v50
	v_dot8c_i32_i4_e32 v42, v134, v52
	v_dot8c_i32_i4_e32 v43, v134, v50
	v_dot8c_i32_i4_e32 v44, v136, v52
	v_dot8c_i32_i4_e32 v45, v136, v50
	v_dot8c_i32_i4_e32 v38, v131, v53
	v_dot8c_i32_i4_e32 v39, v131, v51
	v_dot8c_i32_i4_e32 v40, v133, v53
	v_dot8c_i32_i4_e32 v41, v133, v51
	v_dot8c_i32_i4_e32 v42, v135, v53
	v_dot8c_i32_i4_e32 v43, v135, v51
	v_dot8c_i32_i4_e32 v44, v137, v53
	v_dot8c_i32_i4_e32 v45, v137, v51
	v_and_b32_e32 v78, 0xffff, v25
	v_lshrrev_b32_e32 v79, 16, v25
	v_lshl_add_u32 v78, v78, 7, v152
	v_lshl_add_u32 v79, v79, 7, v153
	s_mov_b32 m0, s79
	s_add_i32 s43, s79, 0x400
	global_load_lds_dwordx4 v78, s[50:51]
	s_mov_b32 m0, s43
	s_nop 0
	global_load_lds_dwordx4 v79, s[50:51]
	s_waitcnt vmcnt(9)
	v_add_u32_e32 v54, s99, v59
	v_add_u32_e32 v55, s99, v60
	v_add_u32_e32 v56, s99, v61
	v_add_u32_e32 v57, s99, v62
	ds_read_b64_tr_b4 v[50:51], v160 offset:384
	ds_read_b64_tr_b4 v[52:53], v160 offset:1408
	ds_read_b64_tr_b4 v[130:131], v54
	ds_read_b64_tr_b4 v[132:133], v55
	ds_read_b64_tr_b4 v[134:135], v56
	ds_read_b64_tr_b4 v[136:137], v57
	s_waitcnt lgkmcnt(6)
	v_dot8c_i32_i4_e32 v38, v122, v48
	v_dot8c_i32_i4_e32 v39, v122, v46
	v_dot8c_i32_i4_e32 v40, v124, v48
	v_dot8c_i32_i4_e32 v41, v124, v46
	v_dot8c_i32_i4_e32 v42, v126, v48
	v_dot8c_i32_i4_e32 v43, v126, v46
	v_dot8c_i32_i4_e32 v44, v128, v48
	v_dot8c_i32_i4_e32 v45, v128, v46
	v_dot8c_i32_i4_e32 v38, v123, v49
	v_dot8c_i32_i4_e32 v39, v123, v47
	v_dot8c_i32_i4_e32 v40, v125, v49
	v_dot8c_i32_i4_e32 v41, v125, v47
	v_dot8c_i32_i4_e32 v42, v127, v49
	v_dot8c_i32_i4_e32 v43, v127, v47
	v_dot8c_i32_i4_e32 v44, v129, v49
	v_dot8c_i32_i4_e32 v45, v129, v47
	s_waitcnt lgkmcnt(15)
	v_and_b32_e32 v78, 0xffff, v26
	v_lshrrev_b32_e32 v79, 16, v26
	v_lshl_add_u32 v78, v78, 7, v152
	v_lshl_add_u32 v79, v79, 7, v153
	s_mov_b32 m0, s98
	s_add_i32 s43, s98, 0x400
	global_load_lds_dwordx4 v78, s[50:51]
	s_mov_b32 m0, s43
	s_nop 0
	global_load_lds_dwordx4 v79, s[50:51]
	s_waitcnt vmcnt(9)
	v_add_u32_e32 v54, s76, v59
	v_add_u32_e32 v55, s76, v60
	v_add_u32_e32 v56, s76, v61
	v_add_u32_e32 v57, s76, v62
	ds_read_b64_tr_b4 v[46:47], v160 offset:512
	ds_read_b64_tr_b4 v[48:49], v160 offset:1536
	ds_read_b64_tr_b4 v[122:123], v54
	ds_read_b64_tr_b4 v[124:125], v55
	ds_read_b64_tr_b4 v[126:127], v56
	ds_read_b64_tr_b4 v[128:129], v57
	s_waitcnt lgkmcnt(6)
	v_dot8c_i32_i4_e32 v38, v130, v52
	v_dot8c_i32_i4_e32 v39, v130, v50
	v_dot8c_i32_i4_e32 v40, v132, v52
	v_dot8c_i32_i4_e32 v41, v132, v50
	v_dot8c_i32_i4_e32 v42, v134, v52
	v_dot8c_i32_i4_e32 v43, v134, v50
	v_dot8c_i32_i4_e32 v44, v136, v52
	v_dot8c_i32_i4_e32 v45, v136, v50
	v_dot8c_i32_i4_e32 v38, v131, v53
	v_dot8c_i32_i4_e32 v39, v131, v51
	v_dot8c_i32_i4_e32 v40, v133, v53
	v_dot8c_i32_i4_e32 v41, v133, v51
	v_dot8c_i32_i4_e32 v42, v135, v53
	v_dot8c_i32_i4_e32 v43, v135, v51
	v_dot8c_i32_i4_e32 v44, v137, v53
	v_dot8c_i32_i4_e32 v45, v137, v51
	v_and_b32_e32 v78, 0xffff, v27
	v_lshrrev_b32_e32 v79, 16, v27
	v_lshl_add_u32 v78, v78, 7, v152
	v_lshl_add_u32 v79, v79, 7, v153
	s_mov_b32 m0, s99
	s_add_i32 s43, s99, 0x400
	global_load_lds_dwordx4 v78, s[50:51]
	s_mov_b32 m0, s43
	s_nop 0
	global_load_lds_dwordx4 v79, s[50:51]
	s_waitcnt vmcnt(8)
	v_add_u32_e32 v54, s77, v59
	v_add_u32_e32 v55, s77, v60
	v_add_u32_e32 v56, s77, v61
	v_add_u32_e32 v57, s77, v62
	ds_read_b64_tr_b4 v[50:51], v160 offset:640
	ds_read_b64_tr_b4 v[52:53], v160 offset:1664
	ds_read_b64_tr_b4 v[130:131], v54
	ds_read_b64_tr_b4 v[132:133], v55
	ds_read_b64_tr_b4 v[134:135], v56
	ds_read_b64_tr_b4 v[136:137], v57
	s_waitcnt lgkmcnt(6)
	v_dot8c_i32_i4_e32 v38, v122, v48
	v_dot8c_i32_i4_e32 v39, v122, v46
	v_dot8c_i32_i4_e32 v40, v124, v48
	v_dot8c_i32_i4_e32 v41, v124, v46
	v_dot8c_i32_i4_e32 v42, v126, v48
	v_dot8c_i32_i4_e32 v43, v126, v46
	v_dot8c_i32_i4_e32 v44, v128, v48
	v_dot8c_i32_i4_e32 v45, v128, v46
	v_dot8c_i32_i4_e32 v38, v123, v49
	v_dot8c_i32_i4_e32 v39, v123, v47
	v_dot8c_i32_i4_e32 v40, v125, v49
	v_dot8c_i32_i4_e32 v41, v125, v47
	v_dot8c_i32_i4_e32 v42, v127, v49
	v_dot8c_i32_i4_e32 v43, v127, v47
	v_dot8c_i32_i4_e32 v44, v129, v49
	v_dot8c_i32_i4_e32 v45, v129, v47
	s_waitcnt lgkmcnt(15)
; __device__ __forceinline__ void peer_v_tokens(int j, const LAS unsigned short* EL, const LAS unsigned char* AL  , const LAS float* ASC  , const LAS int* SAL  , ...
;     ...
;         for (int m = 0; m < 2; ++m) {
;             const int idx = lane + 64 * m, tau = idx >> 4, sr = idx & 15, k = 16 * (sr & 7) + 2 * tau + (sr >> 3);
;             const int aq = (int)*(const LAS signed char*)(AL + tl * 128 + k); const int tq = aq + 8;
;             const unsigned lo = (((unsigned)tq & 15u) ^ 8u) * 0x11111111u, hi = ((unsigned)(tq >> 4) & 15u) * 0x11111111u;
;             typedef unsigned u2v __attribute__((ext_vector_type(2)));
;             u2v l2; l2.x = lo; l2.y = lo; u2v h2; h2.x = hi; h2.y = hi;
;             *(LAS u2v*)(ATL + 8 * idx) = l2; *(LAS u2v*)(ATL + 1024 + 8 * idx) = h2;
;         }
;         const float asc = ASC[tl]; const int sa = SAL[tl];
;         CFENCE();
;         int accH[4], accL[4];
; #pragma unroll
;         for (int st = 0; st < 16; ++st) {
;             const int p = st >> 2, q = st & 3;
;             if (st < 14) VDMA(st + 2, (st + 2) % 3);
;             if (st < 14) asm volatile("s_waitcnt vmcnt(8)" ::: "memory");
;             else if (st == 14) asm volatile("s_waitcnt vmcnt(4)" ::: "memory");
;             else asm volatile("s_waitcnt vmcnt(0)" ::: "memory");
;             if (q == 0) {
; #pragma unroll
;                 for (int r = 0; r < 4; ++r) { accH[r] = 0; accL[r] = 0; } }
; #pragma unroll
;             for (int tp = 0; tp < 2; ++tp) {
;                 const v2i ao = TR4(ATL + (2 * q + tp) * 128 + 8 * s16), ah = TR4(ATL + 1024 + (2 * q + tp) * 128 + 8 * s16);
; #pragma unroll
;                 for (int r = 0; r < 4; ++r) {
;                     const v2i d = TR4(ldsb + BUF[st % 3] + 2048 * tp + roff[r]);
;                     accH[r] = __builtin_amdgcn_sdot8(d.x, ah.x, accH[r], false); accH[r] = __builtin_amdgcn_sdot8(d.y, ah.y, accH[r], false);
;                     accL[r] = __builtin_amdgcn_sdot8(d.x, ao.x, accL[r], false); accL[r] = __builtin_amdgcn_sdot8(d.y, ao.y, accL[r], false);
;                 }
;             }
;             asm volatile("s_waitcnt lgkmcnt(0)" ::: "memory");
;             if (q == 3) {
; #pragma unroll
;                 for (int r = 0; r < 4; ++r) STASH[256 * p + 16 * (grp + 4 * r) + pc] = f2bf(asc * (float)(2 * ((accH[r] << 4) + accL[r]) + sa));
;             }
;         }
	v_add_u32_e32 v143, 8, v139
	v_and_b32_e32 v142, 15, v143
	v_xor_b32_e32 v142, 8, v142
	v_bfe_u32 v144, v143, 4, 4
	v_mul_lo_u32 v142, v142, s92
	v_mul_lo_u32 v144, v144, s92
	v_mov_b32_e32 v143, v142
	v_mov_b32_e32 v145, v144
	ds_write2st64_b64 v159, v[142:143], v[144:145] offset1:2
	v_and_b32_e32 v78, 0xffff, v28
	v_lshrrev_b32_e32 v79, 16, v28
	v_lshl_add_u32 v78, v78, 7, v152
	v_lshl_add_u32 v79, v79, 7, v153
	s_mov_b32 m0, s76
	s_add_i32 s43, s76, 0x400
	global_load_lds_dwordx4 v78, s[50:51]
	s_mov_b32 m0, s43
	s_nop 0
	global_load_lds_dwordx4 v79, s[50:51]
	s_waitcnt vmcnt(8)
	v_add_u32_e32 v54, s78, v59
	v_add_u32_e32 v55, s78, v60
	v_add_u32_e32 v56, s78, v61
	v_add_u32_e32 v57, s78, v62
	ds_read_b64_tr_b4 v[46:47], v160 offset:768
	ds_read_b64_tr_b4 v[48:49], v160 offset:1792
	ds_read_b64_tr_b4 v[122:123], v54
	ds_read_b64_tr_b4 v[124:125], v55
	ds_read_b64_tr_b4 v[126:127], v56
	ds_read_b64_tr_b4 v[128:129], v57
	s_waitcnt lgkmcnt(7)
	v_dot8c_i32_i4_e32 v38, v130, v52
	v_dot8c_i32_i4_e32 v39, v130, v50
	v_dot8c_i32_i4_e32 v40, v132, v52
	v_dot8c_i32_i4_e32 v41, v132, v50
	v_dot8c_i32_i4_e32 v42, v134, v52
	v_dot8c_i32_i4_e32 v43, v134, v50
	v_dot8c_i32_i4_e32 v44, v136, v52
	v_dot8c_i32_i4_e32 v45, v136, v50
	v_dot8c_i32_i4_e32 v38, v131, v53
	v_dot8c_i32_i4_e32 v39, v131, v51
	v_dot8c_i32_i4_e32 v40, v133, v53
	v_dot8c_i32_i4_e32 v41, v133, v51
	v_dot8c_i32_i4_e32 v42, v135, v53
	v_dot8c_i32_i4_e32 v43, v135, v51
	v_dot8c_i32_i4_e32 v44, v137, v53
	v_dot8c_i32_i4_e32 v45, v137, v51
	v_and_b32_e32 v78, 0xffff, v29
	v_lshrrev_b32_e32 v79, 16, v29
	v_lshl_add_u32 v78, v78, 7, v152
	v_lshl_add_u32 v79, v79, 7, v153
	s_mov_b32 m0, s77
	s_add_i32 s43, s77, 0x400
	global_load_lds_dwordx4 v78, s[50:51]
	s_mov_b32 m0, s43
	s_nop 0
	global_load_lds_dwordx4 v79, s[50:51]
	s_waitcnt vmcnt(8)
	v_add_u32_e32 v54, s79, v59
	v_add_u32_e32 v55, s79, v60
	v_add_u32_e32 v56, s79, v61
	v_add_u32_e32 v57, s79, v62
	ds_read_b64_tr_b4 v[50:51], v160 offset:896
	ds_read_b64_tr_b4 v[52:53], v160 offset:1920
	ds_read_b64_tr_b4 v[130:131], v54
	ds_read_b64_tr_b4 v[132:133], v55
	ds_read_b64_tr_b4 v[134:135], v56
	ds_read_b64_tr_b4 v[136:137], v57
	s_waitcnt lgkmcnt(6)
	v_dot8c_i32_i4_e32 v38, v122, v48
	v_dot8c_i32_i4_e32 v39, v122, v46
	v_dot8c_i32_i4_e32 v40, v124, v48
	v_dot8c_i32_i4_e32 v41, v124, v46
	v_dot8c_i32_i4_e32 v42, v126, v48
	v_dot8c_i32_i4_e32 v43, v126, v46
	v_dot8c_i32_i4_e32 v44, v128, v48
	v_dot8c_i32_i4_e32 v45, v128, v46
	v_dot8c_i32_i4_e32 v38, v123, v49
	v_dot8c_i32_i4_e32 v39, v123, v47
	v_dot8c_i32_i4_e32 v40, v125, v49
	v_dot8c_i32_i4_e32 v41, v125, v47
	v_dot8c_i32_i4_e32 v42, v127, v49
	v_dot8c_i32_i4_e32 v43, v127, v47
	v_dot8c_i32_i4_e32 v44, v129, v49
	v_dot8c_i32_i4_e32 v45, v129, v47
	v_and_b32_e32 v78, 0xffff, v30
	v_lshrrev_b32_e32 v79, 16, v30
	v_lshl_add_u32 v78, v78, 7, v152
	v_lshl_add_u32 v79, v79, 7, v153
	s_mov_b32 m0, s78
	s_add_i32 s43, s78, 0x400
	global_load_lds_dwordx4 v78, s[50:51]
	s_mov_b32 m0, s43
	s_nop 0
	global_load_lds_dwordx4 v79, s[50:51]
	s_waitcnt vmcnt(8)
	v_add_u32_e32 v54, s98, v59
	v_add_u32_e32 v55, s98, v60
	v_add_u32_e32 v56, s98, v61
	v_add_u32_e32 v57, s98, v62
	ds_read_b64_tr_b4 v[46:47], v160
	ds_read_b64_tr_b4 v[48:49], v160 offset:1024
	ds_read_b64_tr_b4 v[122:123], v54
	ds_read_b64_tr_b4 v[124:125], v55
	ds_read_b64_tr_b4 v[126:127], v56
	ds_read_b64_tr_b4 v[128:129], v57
	s_waitcnt lgkmcnt(6)
	v_dot8c_i32_i4_e32 v38, v130, v52
	v_dot8c_i32_i4_e32 v39, v130, v50
	v_dot8c_i32_i4_e32 v40, v132, v52
	v_dot8c_i32_i4_e32 v41, v132, v50
	v_dot8c_i32_i4_e32 v42, v134, v52
	v_dot8c_i32_i4_e32 v43, v134, v50
	v_dot8c_i32_i4_e32 v44, v136, v52
	v_dot8c_i32_i4_e32 v45, v136, v50
	v_dot8c_i32_i4_e32 v38, v131, v53
	v_dot8c_i32_i4_e32 v39, v131, v51
	v_dot8c_i32_i4_e32 v40, v133, v53
	v_dot8c_i32_i4_e32 v41, v133, v51
	v_dot8c_i32_i4_e32 v42, v135, v53
	v_dot8c_i32_i4_e32 v43, v135, v51
	v_dot8c_i32_i4_e32 v44, v137, v53
	v_dot8c_i32_i4_e32 v45, v137, v51
	s_nop 3
	s_waitcnt lgkmcnt(15)
	v_lshlrev_b32_e32 v38, 5, v38
	v_lshlrev_b32_e32 v39, 1, v39
	v_add3_u32 v38, v39, v229, v38
	v_cvt_f32_i32_e32 v38, v38
	v_mul_f32_e32 v38, v228, v38
	v_lshlrev_b32_e32 v40, 5, v40
	v_lshlrev_b32_e32 v41, 1, v41
	v_add3_u32 v40, v41, v229, v40
	v_cvt_f32_i32_e32 v40, v40
	v_mul_f32_e32 v40, v228, v40
	v_lshlrev_b32_e32 v42, 5, v42
	v_lshlrev_b32_e32 v43, 1, v43
	v_add3_u32 v42, v43, v229, v42
	v_cvt_f32_i32_e32 v42, v42
	v_mul_f32_e32 v42, v228, v42
	v_lshlrev_b32_e32 v44, 5, v44
	v_lshlrev_b32_e32 v45, 1, v45
	v_add3_u32 v44, v45, v229, v44
	v_cvt_f32_i32_e32 v44, v44
	v_mul_f32_e32 v44, v228, v44
	v_cvt_pk_bf16_f32 v168, v38, v40
	v_cvt_pk_bf16_f32 v169, v42, v44
	ds_read_b128 v[252:255], v156
	s_add_i32 s44, s40, 24
	s_ashr_i32 s45, s44, 31
	s_lshl_b64 s[44:45], s[44:45], 12
	v_lshl_add_u64 v[80:81], v[36:37], 0, s[44:45]
	s_waitcnt lgkmcnt(0)
; __device__ __forceinline__ void peer_v_tokens(int j, const LAS unsigned short* EL, const LAS unsigned char* AL  , const LAS float* ASC  , const LAS int* SAL  , ...
;     ...
;         { const LAS v4u* ep = (const LAS v4u*)(EL + tl * 128 + 16 * g); const v4u e0 = ep[0], e1 = ep[1];
;           E[0] = e0.x; E[1] = e0.y; E[2] = e0.z; E[3] = e0.w; E[4] = e1.x; E[5] = e1.y; E[6] = e1.z; E[7] = e1.w; }
;         uint2 hv[4]; float4 gv[4];
;         { unsigned ho = (unsigned)t * (D / 4) + (unsigned)lane; asm volatile("" : "+v"(ho)); const uint2* hp = (const uint2*)HB + ho; const float4* gp = (const float4*)fng + lane;
; #pragma unroll
;           for (int jq = 0; jq < 4; ++jq) { hv[jq] = hp[64 * jq]; gv[jq] = gp[64 * jq]; } }
;         VDMA(0, 0); VDMA(1, 1);
; #pragma unroll
;         for (int m = 0; m < 2; ++m) {
;             const int idx = lane + 64 * m, tau = idx >> 4, sr = idx & 15, k = 16 * (sr & 7) + 2 * tau + (sr >> 3);
;             const int aq = (int)*(const LAS signed char*)(AL + tl * 128 + k); const int tq = aq + 8;
;             const unsigned lo = (((unsigned)tq & 15u) ^ 8u) * 0x11111111u, hi = ((unsigned)(tq >> 4) & 15u) * 0x11111111u;
;             typedef unsigned u2v __attribute__((ext_vector_type(2)));
;             u2v l2; l2.x = lo; l2.y = lo; u2v h2; h2.x = hi; h2.y = hi;
;             *(LAS u2v*)(ATL + 8 * idx) = l2; *(LAS u2v*)(ATL + 1024 + 8 * idx) = h2;
;         }
;         const float asc = ASC[tl]; const int sa = SAL[tl];
;         CFENCE();
;         int accH[4], accL[4];
; #pragma unroll
;         for (int st = 0; st < 16; ++st) {
;             const int p = st >> 2, q = st & 3;
;             if (st < 14) VDMA(st + 2, (st + 2) % 3);
;             if (st < 14) asm volatile("s_waitcnt vmcnt(8)" ::: "memory");
;             else if (st == 14) asm volatile("s_waitcnt vmcnt(4)" ::: "memory");
;             else asm volatile("s_waitcnt vmcnt(0)" ::: "memory");
;             if (q == 0) {
; #pragma unroll
;                 for (int r = 0; r < 4; ++r) { accH[r] = 0; accL[r] = 0; } }
; #pragma unroll
;             for (int tp = 0; tp < 2; ++tp) {
;                 const v2i ao = TR4(ATL + (2 * q + tp) * 128 + 8 * s16), ah = TR4(ATL + 1024 + (2 * q + tp) * 128 + 8 * s16);
; #pragma unroll
;                 for (int r = 0; r < 4; ++r) {
;                     const v2i d = TR4(ldsb + BUF[st % 3] + 2048 * tp + roff[r]);
	v_mul_f32_e32 v244, v244, v252
	v_mul_f32_e32 v245, v245, v253
	v_mul_f32_e32 v246, v246, v254
	v_mul_f32_e32 v247, v247, v255
	global_store_dwordx4 v[80:81], v[244:247], off offset:2048 nt
	s_add_i32 s43, s40, 32
	s_lshl_b32 s43, s43, 11
	v_add_u32_e32 v138, s43, v66
	global_load_dwordx2 v[194:195], v138, s[70:71]
	global_load_dwordx2 v[196:197], v138, s[70:71] offset:512
	global_load_dwordx2 v[198:199], v138, s[70:71] offset:1024
	global_load_dwordx2 v[200:201], v138, s[70:71] offset:1536
	v_add_u32_e32 v147, 8, v140
	v_and_b32_e32 v146, 15, v147
	v_xor_b32_e32 v146, 8, v146
	v_bfe_u32 v148, v147, 4, 4
	v_mul_lo_u32 v146, v146, s92
	v_mul_lo_u32 v148, v148, s92
	v_mov_b32_e32 v147, v146
	v_mov_b32_e32 v149, v148
	ds_write2st64_b64 v77, v[146:147], v[148:149] offset1:2
	v_add_u32_e32 v138, 0x1800, v74
	ds_read_u8 v139, v138
	v_add_u32_e32 v141, 0x1800, v73
	ds_read_u8 v140, v141
	s_add_i32 s43, s67, 160
	v_mov_b32_e32 v138, s43
	ds_read2st64_b32 v[228:229], v138 offset1:1
	ds_read_b128 v[18:21], v227 offset:12288
	ds_read_b128 v[22:25], v227 offset:12304
	v_mov_b32_e32 v150, v63
	v_mov_b32_e32 v151, v64
	v_mov_b32_e32 v38, 0
	v_mov_b32_e32 v39, 0
	v_mov_b32_e32 v40, 0
	v_mov_b32_e32 v41, 0
	v_mov_b32_e32 v42, 0
	v_mov_b32_e32 v43, 0
	v_mov_b32_e32 v44, 0
	v_mov_b32_e32 v45, 0
	v_and_b32_e32 v78, 0xffff, v31
	v_lshrrev_b32_e32 v79, 16, v31
	v_lshl_add_u32 v78, v78, 7, v152
	v_lshl_add_u32 v79, v79, 7, v153
	s_mov_b32 m0, s79
	s_add_i32 s43, s79, 0x400
	global_load_lds_dwordx4 v78, s[50:51]
	s_mov_b32 m0, s43
	s_nop 0
	global_load_lds_dwordx4 v79, s[50:51]
	s_waitcnt vmcnt(13)
	v_add_u32_e32 v54, s99, v59
	v_add_u32_e32 v55, s99, v60
	v_add_u32_e32 v56, s99, v61
	v_add_u32_e32 v57, s99, v62
	ds_read_b64_tr_b4 v[50:51], v160 offset:128
	ds_read_b64_tr_b4 v[52:53], v160 offset:1152
	ds_read_b64_tr_b4 v[130:131], v54
	ds_read_b64_tr_b4 v[132:133], v55
	ds_read_b64_tr_b4 v[134:135], v56
	ds_read_b64_tr_b4 v[136:137], v57
	s_waitcnt lgkmcnt(13)
	v_dot8c_i32_i4_e32 v38, v122, v48
	v_dot8c_i32_i4_e32 v39, v122, v46
	v_dot8c_i32_i4_e32 v40, v124, v48
	v_dot8c_i32_i4_e32 v41, v124, v46
	v_dot8c_i32_i4_e32 v42, v126, v48
	v_dot8c_i32_i4_e32 v43, v126, v46
	v_dot8c_i32_i4_e32 v44, v128, v48
	v_dot8c_i32_i4_e32 v45, v128, v46
	v_dot8c_i32_i4_e32 v38, v123, v49
	v_dot8c_i32_i4_e32 v39, v123, v47
	v_dot8c_i32_i4_e32 v40, v125, v49
	v_dot8c_i32_i4_e32 v41, v125, v47
	v_dot8c_i32_i4_e32 v42, v127, v49
	v_dot8c_i32_i4_e32 v43, v127, v47
	v_dot8c_i32_i4_e32 v44, v129, v49
	v_dot8c_i32_i4_e32 v45, v129, v47
	v_and_b32_e32 v78, 0xffff, v32
	v_lshrrev_b32_e32 v79, 16, v32
	v_lshl_add_u32 v78, v78, 7, v152
	v_lshl_add_u32 v79, v79, 7, v153
	s_mov_b32 m0, s98
	s_add_i32 s43, s98, 0x400
	global_load_lds_dwordx4 v78, s[50:51]
	s_mov_b32 m0, s43
	s_nop 0
	global_load_lds_dwordx4 v79, s[50:51]
	s_waitcnt vmcnt(13)
	v_add_u32_e32 v54, s76, v59
	v_add_u32_e32 v55, s76, v60
	v_add_u32_e32 v56, s76, v61
	v_add_u32_e32 v57, s76, v62
	ds_read_b64_tr_b4 v[46:47], v160 offset:256
	ds_read_b64_tr_b4 v[48:49], v160 offset:1280
	ds_read_b64_tr_b4 v[122:123], v54
	ds_read_b64_tr_b4 v[124:125], v55
	ds_read_b64_tr_b4 v[126:127], v56
	ds_read_b64_tr_b4 v[128:129], v57
	s_waitcnt lgkmcnt(6)
	v_dot8c_i32_i4_e32 v38, v130, v52
	v_dot8c_i32_i4_e32 v39, v130, v50
	v_dot8c_i32_i4_e32 v40, v132, v52
	v_dot8c_i32_i4_e32 v41, v132, v50
	v_dot8c_i32_i4_e32 v42, v134, v52
	v_dot8c_i32_i4_e32 v43, v134, v50
	v_dot8c_i32_i4_e32 v44, v136, v52
	v_dot8c_i32_i4_e32 v45, v136, v50
	v_dot8c_i32_i4_e32 v38, v131, v53
	v_dot8c_i32_i4_e32 v39, v131, v51
	v_dot8c_i32_i4_e32 v40, v133, v53
	v_dot8c_i32_i4_e32 v41, v133, v51
	v_dot8c_i32_i4_e32 v42, v135, v53
	v_dot8c_i32_i4_e32 v43, v135, v51
	v_dot8c_i32_i4_e32 v44, v137, v53
	v_dot8c_i32_i4_e32 v45, v137, v51
	v_and_b32_e32 v78, 0xffff, v33
	v_lshrrev_b32_e32 v79, 16, v33
	v_lshl_add_u32 v78, v78, 7, v152
	v_lshl_add_u32 v79, v79, 7, v153
	s_mov_b32 m0, s99
	s_add_i32 s43, s99, 0x400
	global_load_lds_dwordx4 v78, s[50:51]
	s_mov_b32 m0, s43
	s_nop 0
	global_load_lds_dwordx4 v79, s[50:51]
	s_waitcnt vmcnt(13)
	v_add_u32_e32 v54, s77, v59
	v_add_u32_e32 v55, s77, v60
	v_add_u32_e32 v56, s77, v61
	v_add_u32_e32 v57, s77, v62
	ds_read_b64_tr_b4 v[50:51], v160 offset:384
	ds_read_b64_tr_b4 v[52:53], v160 offset:1408
	ds_read_b64_tr_b4 v[130:131], v54
	ds_read_b64_tr_b4 v[132:133], v55
	ds_read_b64_tr_b4 v[134:135], v56
	ds_read_b64_tr_b4 v[136:137], v57
	s_waitcnt lgkmcnt(6)
	v_dot8c_i32_i4_e32 v38, v122, v48
	v_dot8c_i32_i4_e32 v39, v122, v46
	v_dot8c_i32_i4_e32 v40, v124, v48
	v_dot8c_i32_i4_e32 v41, v124, v46
	v_dot8c_i32_i4_e32 v42, v126, v48
	v_dot8c_i32_i4_e32 v43, v126, v46
	v_dot8c_i32_i4_e32 v44, v128, v48
	v_dot8c_i32_i4_e32 v45, v128, v46
	v_dot8c_i32_i4_e32 v38, v123, v49
	v_dot8c_i32_i4_e32 v39, v123, v47
	v_dot8c_i32_i4_e32 v40, v125, v49
	v_dot8c_i32_i4_e32 v41, v125, v47
	v_dot8c_i32_i4_e32 v42, v127, v49
	v_dot8c_i32_i4_e32 v43, v127, v47
	v_dot8c_i32_i4_e32 v44, v129, v49
	v_dot8c_i32_i4_e32 v45, v129, v47
	s_waitcnt lgkmcnt(15)
	v_and_b32_e32 v78, 0xffff, v18
	v_lshrrev_b32_e32 v79, 16, v18
	v_lshl_add_u32 v78, v78, 7, v150
	v_lshl_add_u32 v79, v79, 7, v151
	s_mov_b32 m0, s76
	s_add_i32 s43, s76, 0x400
	global_load_lds_dwordx4 v78, s[50:51]
	s_mov_b32 m0, s43
	s_nop 0
	global_load_lds_dwordx4 v79, s[50:51]
	s_waitcnt vmcnt(13)
	v_add_u32_e32 v54, s78, v59
	v_add_u32_e32 v55, s78, v60
	v_add_u32_e32 v56, s78, v61
	v_add_u32_e32 v57, s78, v62
	ds_read_b64_tr_b4 v[46:47], v160 offset:512
	ds_read_b64_tr_b4 v[48:49], v160 offset:1536
	ds_read_b64_tr_b4 v[122:123], v54
	ds_read_b64_tr_b4 v[124:125], v55
	ds_read_b64_tr_b4 v[126:127], v56
	ds_read_b64_tr_b4 v[128:129], v57
	s_waitcnt lgkmcnt(6)
; #define LAS __attribute__((address_space(3)))
; #define TR4(p_) __builtin_amdgcn_ds_read_tr4_b64_v2i32((LAS v2i*)(p_))
; #define CFENCE() asm volatile("" ::: "memory")
; __device__ __forceinline__ void peer_v_tokens(int j, const LAS unsigned short* EL, const LAS unsigned char* AL  , const LAS float* ASC  , const LAS int* SAL  , ...
;     ...
;         for (int m = 0; m < 2; ++m) {
;             const int idx = lane + 64 * m, tau = idx >> 4, sr = idx & 15, k = 16 * (sr & 7) + 2 * tau + (sr >> 3);
;             const int aq = (int)*(const LAS signed char*)(AL + tl * 128 + k); const int tq = aq + 8;
;             const unsigned lo = (((unsigned)tq & 15u) ^ 8u) * 0x11111111u, hi = ((unsigned)(tq >> 4) & 15u) * 0x11111111u;
;             typedef unsigned u2v __attribute__((ext_vector_type(2)));
;             u2v l2; l2.x = lo; l2.y = lo; u2v h2; h2.x = hi; h2.y = hi;
;             *(LAS u2v*)(ATL + 8 * idx) = l2; *(LAS u2v*)(ATL + 1024 + 8 * idx) = h2;
;         }
;         const float asc = ASC[tl]; const int sa = SAL[tl];
;         CFENCE();
;         int accH[4], accL[4];
; #pragma unroll
;         for (int st = 0; st < 16; ++st) {
;             const int p = st >> 2, q = st & 3;
;             if (st < 14) VDMA(st + 2, (st + 2) % 3);
;             if (st < 14) asm volatile("s_waitcnt vmcnt(8)" ::: "memory");
;             else if (st == 14) asm volatile("s_waitcnt vmcnt(4)" ::: "memory");
;             else asm volatile("s_waitcnt vmcnt(0)" ::: "memory");
;             if (q == 0) {
; #pragma unroll
;                 for (int r = 0; r < 4; ++r) { accH[r] = 0; accL[r] = 0; } }
; #pragma unroll
;             for (int tp = 0; tp < 2; ++tp) {
;                 const v2i ao = TR4(ATL + (2 * q + tp) * 128 + 8 * s16), ah = TR4(ATL + 1024 + (2 * q + tp) * 128 + 8 * s16);
; #pragma unroll
;                 for (int r = 0; r < 4; ++r) {
;                     const v2i d = TR4(ldsb + BUF[st % 3] + 2048 * tp + roff[r]);
;                     accH[r] = __builtin_amdgcn_sdot8(d.x, ah.x, accH[r], false); accH[r] = __builtin_amdgcn_sdot8(d.y, ah.y, accH[r], false);
;                     accL[r] = __builtin_amdgcn_sdot8(d.x, ao.x, accL[r], false); accL[r] = __builtin_amdgcn_sdot8(d.y, ao.y, accL[r], false);
;                 }
;             }
	v_dot8c_i32_i4_e32 v38, v130, v52
	v_dot8c_i32_i4_e32 v39, v130, v50
	v_dot8c_i32_i4_e32 v40, v132, v52
	v_dot8c_i32_i4_e32 v41, v132, v50
	v_dot8c_i32_i4_e32 v42, v134, v52
	v_dot8c_i32_i4_e32 v43, v134, v50
	v_dot8c_i32_i4_e32 v44, v136, v52
	v_dot8c_i32_i4_e32 v45, v136, v50
	v_dot8c_i32_i4_e32 v38, v131, v53
	v_dot8c_i32_i4_e32 v39, v131, v51
	v_dot8c_i32_i4_e32 v40, v133, v53
	v_dot8c_i32_i4_e32 v41, v133, v51
	v_dot8c_i32_i4_e32 v42, v135, v53
	v_dot8c_i32_i4_e32 v43, v135, v51
	v_dot8c_i32_i4_e32 v44, v137, v53
	v_dot8c_i32_i4_e32 v45, v137, v51
	v_and_b32_e32 v78, 0xffff, v19
	v_lshrrev_b32_e32 v79, 16, v19
	v_lshl_add_u32 v78, v78, 7, v150
	v_lshl_add_u32 v79, v79, 7, v151
	s_mov_b32 m0, s77
	s_add_i32 s43, s77, 0x400
	global_load_lds_dwordx4 v78, s[50:51]
	s_mov_b32 m0, s43
	s_nop 0
	global_load_lds_dwordx4 v79, s[50:51]
	s_waitcnt vmcnt(8)
	v_add_u32_e32 v54, s79, v59
	v_add_u32_e32 v55, s79, v60
	v_add_u32_e32 v56, s79, v61
	v_add_u32_e32 v57, s79, v62
	ds_read_b64_tr_b4 v[50:51], v160 offset:640
	ds_read_b64_tr_b4 v[52:53], v160 offset:1664
	ds_read_b64_tr_b4 v[130:131], v54
	ds_read_b64_tr_b4 v[132:133], v55
	ds_read_b64_tr_b4 v[134:135], v56
	ds_read_b64_tr_b4 v[136:137], v57
	s_waitcnt lgkmcnt(6)
	v_dot8c_i32_i4_e32 v38, v122, v48
	v_dot8c_i32_i4_e32 v39, v122, v46
	v_dot8c_i32_i4_e32 v40, v124, v48
	v_dot8c_i32_i4_e32 v41, v124, v46
	v_dot8c_i32_i4_e32 v42, v126, v48
	v_dot8c_i32_i4_e32 v43, v126, v46
	v_dot8c_i32_i4_e32 v44, v128, v48
	v_dot8c_i32_i4_e32 v45, v128, v46
	v_dot8c_i32_i4_e32 v38, v123, v49
	v_dot8c_i32_i4_e32 v39, v123, v47
	v_dot8c_i32_i4_e32 v40, v125, v49
	v_dot8c_i32_i4_e32 v41, v125, v47
	v_dot8c_i32_i4_e32 v42, v127, v49
	v_dot8c_i32_i4_e32 v43, v127, v47
	v_dot8c_i32_i4_e32 v44, v129, v49
	v_dot8c_i32_i4_e32 v45, v129, v47
	s_waitcnt lgkmcnt(15)
	v_add_u32_e32 v143, 8, v139
	v_and_b32_e32 v142, 15, v143
	v_xor_b32_e32 v142, 8, v142
	v_bfe_u32 v144, v143, 4, 4
	v_mul_lo_u32 v142, v142, s92
	v_mul_lo_u32 v144, v144, s92
	v_mov_b32_e32 v143, v142
	v_mov_b32_e32 v145, v144
	ds_write2st64_b64 v159, v[142:143], v[144:145] offset1:2
	v_and_b32_e32 v78, 0xffff, v20
	v_lshrrev_b32_e32 v79, 16, v20
	v_lshl_add_u32 v78, v78, 7, v150
	v_lshl_add_u32 v79, v79, 7, v151
	s_mov_b32 m0, s78
	s_add_i32 s43, s78, 0x400
	global_load_lds_dwordx4 v78, s[50:51]
	s_mov_b32 m0, s43
	s_nop 0
	global_load_lds_dwordx4 v79, s[50:51]
	s_waitcnt vmcnt(8)
	v_add_u32_e32 v54, s98, v59
	v_add_u32_e32 v55, s98, v60
	v_add_u32_e32 v56, s98, v61
	v_add_u32_e32 v57, s98, v62
	ds_read_b64_tr_b4 v[46:47], v160 offset:768
	ds_read_b64_tr_b4 v[48:49], v160 offset:1792
	ds_read_b64_tr_b4 v[122:123], v54
	ds_read_b64_tr_b4 v[124:125], v55
	ds_read_b64_tr_b4 v[126:127], v56
	ds_read_b64_tr_b4 v[128:129], v57
	s_waitcnt lgkmcnt(7)
	v_dot8c_i32_i4_e32 v38, v130, v52
	v_dot8c_i32_i4_e32 v39, v130, v50
	v_dot8c_i32_i4_e32 v40, v132, v52
	v_dot8c_i32_i4_e32 v41, v132, v50
	v_dot8c_i32_i4_e32 v42, v134, v52
	v_dot8c_i32_i4_e32 v43, v134, v50
	v_dot8c_i32_i4_e32 v44, v136, v52
	v_dot8c_i32_i4_e32 v45, v136, v50
	v_dot8c_i32_i4_e32 v38, v131, v53
	v_dot8c_i32_i4_e32 v39, v131, v51
	v_dot8c_i32_i4_e32 v40, v133, v53
	v_dot8c_i32_i4_e32 v41, v133, v51
	v_dot8c_i32_i4_e32 v42, v135, v53
	v_dot8c_i32_i4_e32 v43, v135, v51
	v_dot8c_i32_i4_e32 v44, v137, v53
	v_dot8c_i32_i4_e32 v45, v137, v51
	v_and_b32_e32 v78, 0xffff, v21
	v_lshrrev_b32_e32 v79, 16, v21
	v_lshl_add_u32 v78, v78, 7, v150
	v_lshl_add_u32 v79, v79, 7, v151
	s_mov_b32 m0, s79
	s_add_i32 s43, s79, 0x400
	global_load_lds_dwordx4 v78, s[50:51]
	s_mov_b32 m0, s43
	s_nop 0
	global_load_lds_dwordx4 v79, s[50:51]
	s_waitcnt vmcnt(8)
	v_add_u32_e32 v54, s99, v59
	v_add_u32_e32 v55, s99, v60
	v_add_u32_e32 v56, s99, v61
	v_add_u32_e32 v57, s99, v62
	ds_read_b64_tr_b4 v[50:51], v160 offset:896
	ds_read_b64_tr_b4 v[52:53], v160 offset:1920
	ds_read_b64_tr_b4 v[130:131], v54
	ds_read_b64_tr_b4 v[132:133], v55
	ds_read_b64_tr_b4 v[134:135], v56
	ds_read_b64_tr_b4 v[136:137], v57
	s_waitcnt lgkmcnt(6)
	v_dot8c_i32_i4_e32 v38, v122, v48
	v_dot8c_i32_i4_e32 v39, v122, v46
	v_dot8c_i32_i4_e32 v40, v124, v48
	v_dot8c_i32_i4_e32 v41, v124, v46
	v_dot8c_i32_i4_e32 v42, v126, v48
	v_dot8c_i32_i4_e32 v43, v126, v46
	v_dot8c_i32_i4_e32 v44, v128, v48
	v_dot8c_i32_i4_e32 v45, v128, v46
	v_dot8c_i32_i4_e32 v38, v123, v49
	v_dot8c_i32_i4_e32 v39, v123, v47
	v_dot8c_i32_i4_e32 v40, v125, v49
	v_dot8c_i32_i4_e32 v41, v125, v47
	v_dot8c_i32_i4_e32 v42, v127, v49
	v_dot8c_i32_i4_e32 v43, v127, v47
	v_dot8c_i32_i4_e32 v44, v129, v49
	v_dot8c_i32_i4_e32 v45, v129, v47
	v_and_b32_e32 v78, 0xffff, v22
	v_lshrrev_b32_e32 v79, 16, v22
	v_lshl_add_u32 v78, v78, 7, v150
	v_lshl_add_u32 v79, v79, 7, v151
	s_mov_b32 m0, s98
	s_add_i32 s43, s98, 0x400
	global_load_lds_dwordx4 v78, s[50:51]
	s_mov_b32 m0, s43
	s_nop 0
	global_load_lds_dwordx4 v79, s[50:51]
	s_waitcnt vmcnt(8)
	v_add_u32_e32 v54, s76, v59
	v_add_u32_e32 v55, s76, v60
	v_add_u32_e32 v56, s76, v61
	v_add_u32_e32 v57, s76, v62
	ds_read_b64_tr_b4 v[46:47], v160
	ds_read_b64_tr_b4 v[48:49], v160 offset:1024
	ds_read_b64_tr_b4 v[122:123], v54
	ds_read_b64_tr_b4 v[124:125], v55
	ds_read_b64_tr_b4 v[126:127], v56
	ds_read_b64_tr_b4 v[128:129], v57
	s_waitcnt lgkmcnt(6)
	v_dot8c_i32_i4_e32 v38, v130, v52
	v_dot8c_i32_i4_e32 v39, v130, v50
	v_dot8c_i32_i4_e32 v40, v132, v52
	v_dot8c_i32_i4_e32 v41, v132, v50
	v_dot8c_i32_i4_e32 v42, v134, v52
	v_dot8c_i32_i4_e32 v43, v134, v50
	v_dot8c_i32_i4_e32 v44, v136, v52
	v_dot8c_i32_i4_e32 v45, v136, v50
	v_dot8c_i32_i4_e32 v38, v131, v53
	v_dot8c_i32_i4_e32 v39, v131, v51
	v_dot8c_i32_i4_e32 v40, v133, v53
	v_dot8c_i32_i4_e32 v41, v133, v51
	v_dot8c_i32_i4_e32 v42, v135, v53
	v_dot8c_i32_i4_e32 v43, v135, v51
	v_dot8c_i32_i4_e32 v44, v137, v53
	v_dot8c_i32_i4_e32 v45, v137, v51
	s_nop 3
	s_waitcnt lgkmcnt(15)
; __device__ __forceinline__ void peer_v_tokens(int j, const LAS unsigned short* EL, const LAS unsigned char* AL  , const LAS float* ASC  , const LAS int* SAL  , ...
;     ...
; #pragma unroll 1
;     for (int it = 0; it < 8; ++it) {
;         const int tl = it * 8 + wave, t = j * 64 + tl;
;         unsigned E[8];
;         { const LAS v4u* ep = (const LAS v4u*)(EL + tl * 128 + 16 * g); const v4u e0 = ep[0], e1 = ep[1];
;           E[0] = e0.x; E[1] = e0.y; E[2] = e0.z; E[3] = e0.w; E[4] = e1.x; E[5] = e1.y; E[6] = e1.z; E[7] = e1.w; }
;         uint2 hv[4]; float4 gv[4];
;         { unsigned ho = (unsigned)t * (D / 4) + (unsigned)lane; asm volatile("" : "+v"(ho)); const uint2* hp = (const uint2*)HB + ho; const float4* gp = (const float4*)fng + lane;
; #pragma unroll
;           for (int jq = 0; jq < 4; ++jq) { hv[jq] = hp[64 * jq]; gv[jq] = gp[64 * jq]; } }
;         VDMA(0, 0); VDMA(1, 1);
; #pragma unroll
;         for (int m = 0; m < 2; ++m) {
;             const int idx = lane + 64 * m, tau = idx >> 4, sr = idx & 15, k = 16 * (sr & 7) + 2 * tau + (sr >> 3);
;             const int aq = (int)*(const LAS signed char*)(AL + tl * 128 + k); const int tq = aq + 8;
;             const unsigned lo = (((unsigned)tq & 15u) ^ 8u) * 0x11111111u, hi = ((unsigned)(tq >> 4) & 15u) * 0x11111111u;
;             typedef unsigned u2v __attribute__((ext_vector_type(2)));
;             u2v l2; l2.x = lo; l2.y = lo; u2v h2; h2.x = hi; h2.y = hi;
;             *(LAS u2v*)(ATL + 8 * idx) = l2; *(LAS u2v*)(ATL + 1024 + 8 * idx) = h2;
;         }
;         const float asc = ASC[tl]; const int sa = SAL[tl];
;         CFENCE();
;         int accH[4], accL[4];
; #pragma unroll
;         for (int st = 0; st < 16; ++st) {
;             const int p = st >> 2, q = st & 3;
;             if (st < 14) VDMA(st + 2, (st + 2) % 3);
;             if (st < 14) asm volatile("s_waitcnt vmcnt(8)" ::: "memory");
;             else if (st == 14) asm volatile("s_waitcnt vmcnt(4)" ::: "memory");
;             else asm volatile("s_waitcnt vmcnt(0)" ::: "memory");
;             if (q == 0) {
; #pragma unroll
;                 for (int r = 0; r < 4; ++r) { accH[r] = 0; accL[r] = 0; } }
; #pragma unroll
;             for (int tp = 0; tp < 2; ++tp) {
;                 const v2i ao = TR4(ATL + (2 * q + tp) * 128 + 8 * s16), ah = TR4(ATL + 1024 + (2 * q + tp) * 128 + 8 * s16);
; #pragma unroll
	v_lshlrev_b32_e32 v38, 5, v38
	v_lshlrev_b32_e32 v39, 1, v39
	v_add3_u32 v38, v39, v229, v38
	v_cvt_f32_i32_e32 v38, v38
	v_mul_f32_e32 v38, v228, v38
	v_lshlrev_b32_e32 v40, 5, v40
	v_lshlrev_b32_e32 v41, 1, v41
	v_add3_u32 v40, v41, v229, v40
	v_cvt_f32_i32_e32 v40, v40
	v_mul_f32_e32 v40, v228, v40
	v_lshlrev_b32_e32 v42, 5, v42
	v_lshlrev_b32_e32 v43, 1, v43
	v_add3_u32 v42, v43, v229, v42
	v_cvt_f32_i32_e32 v42, v42
	v_mul_f32_e32 v42, v228, v42
	v_lshlrev_b32_e32 v44, 5, v44
	v_lshlrev_b32_e32 v45, 1, v45
	v_add3_u32 v44, v45, v229, v44
	v_cvt_f32_i32_e32 v44, v44
	v_mul_f32_e32 v44, v228, v44
	v_cvt_pk_bf16_f32 v176, v38, v40
	v_cvt_pk_bf16_f32 v177, v42, v44
	ds_read_b128 v[252:255], v156 offset:1024
	s_add_i32 s44, s40, 24
	s_ashr_i32 s45, s44, 31
	s_lshl_b64 s[44:45], s[44:45], 12
	v_lshl_add_u64 v[80:81], v[36:37], 0, s[44:45]
	s_waitcnt lgkmcnt(0)
	v_mul_f32_e32 v248, v248, v252
	v_mul_f32_e32 v249, v249, v253
	v_mul_f32_e32 v250, v250, v254
	v_mul_f32_e32 v251, v251, v255
	global_store_dwordx4 v[80:81], v[248:251], off offset:3072 nt
	v_add_u32_e32 v147, 8, v140
	v_and_b32_e32 v146, 15, v147
	v_xor_b32_e32 v146, 8, v146
	v_bfe_u32 v148, v147, 4, 4
	v_mul_lo_u32 v146, v146, s92
	v_mul_lo_u32 v148, v148, s92
	v_mov_b32_e32 v147, v146
	v_mov_b32_e32 v149, v148
	ds_write2st64_b64 v77, v[146:147], v[148:149] offset1:2
	v_add_u32_e32 v138, 0x1c00, v74
	ds_read_u8 v139, v138
	v_add_u32_e32 v141, 0x1c00, v73
	ds_read_u8 v140, v141
	s_add_i32 s43, s67, 192
	v_mov_b32_e32 v138, s43
	ds_read2st64_b32 v[228:229], v138 offset1:1
	ds_read_b128 v[26:29], v227 offset:14336
	ds_read_b128 v[30:33], v227 offset:14352
	v_mov_b32_e32 v38, 0
	v_mov_b32_e32 v39, 0
	v_mov_b32_e32 v40, 0
	v_mov_b32_e32 v41, 0
	v_mov_b32_e32 v42, 0
	v_mov_b32_e32 v43, 0
	v_mov_b32_e32 v44, 0
	v_mov_b32_e32 v45, 0
	v_and_b32_e32 v78, 0xffff, v23
	v_lshrrev_b32_e32 v79, 16, v23
	v_lshl_add_u32 v78, v78, 7, v150
	v_lshl_add_u32 v79, v79, 7, v151
	s_mov_b32 m0, s99
	s_add_i32 s43, s99, 0x400
	global_load_lds_dwordx4 v78, s[50:51]
	s_mov_b32 m0, s43
	s_nop 0
	global_load_lds_dwordx4 v79, s[50:51]
	s_waitcnt vmcnt(9)
	v_add_u32_e32 v54, s77, v59
	v_add_u32_e32 v55, s77, v60
	v_add_u32_e32 v56, s77, v61
	v_add_u32_e32 v57, s77, v62
	ds_read_b64_tr_b4 v[50:51], v160 offset:128
	ds_read_b64_tr_b4 v[52:53], v160 offset:1152
	ds_read_b64_tr_b4 v[130:131], v54
	ds_read_b64_tr_b4 v[132:133], v55
	ds_read_b64_tr_b4 v[134:135], v56
	ds_read_b64_tr_b4 v[136:137], v57
	s_waitcnt lgkmcnt(13)
	v_dot8c_i32_i4_e32 v38, v122, v48
	v_dot8c_i32_i4_e32 v39, v122, v46
	v_dot8c_i32_i4_e32 v40, v124, v48
	v_dot8c_i32_i4_e32 v41, v124, v46
	v_dot8c_i32_i4_e32 v42, v126, v48
	v_dot8c_i32_i4_e32 v43, v126, v46
	v_dot8c_i32_i4_e32 v44, v128, v48
	v_dot8c_i32_i4_e32 v45, v128, v46
	v_dot8c_i32_i4_e32 v38, v123, v49
	v_dot8c_i32_i4_e32 v39, v123, v47
	v_dot8c_i32_i4_e32 v40, v125, v49
	v_dot8c_i32_i4_e32 v41, v125, v47
	v_dot8c_i32_i4_e32 v42, v127, v49
	v_dot8c_i32_i4_e32 v43, v127, v47
	v_dot8c_i32_i4_e32 v44, v129, v49
	v_dot8c_i32_i4_e32 v45, v129, v47
	v_and_b32_e32 v78, 0xffff, v24
	v_lshrrev_b32_e32 v79, 16, v24
	v_lshl_add_u32 v78, v78, 7, v150
	v_lshl_add_u32 v79, v79, 7, v151
	s_mov_b32 m0, s76
	s_add_i32 s43, s76, 0x400
	global_load_lds_dwordx4 v78, s[50:51]
	s_mov_b32 m0, s43
	s_nop 0
	global_load_lds_dwordx4 v79, s[50:51]
	s_waitcnt vmcnt(9)
	v_add_u32_e32 v54, s78, v59
	v_add_u32_e32 v55, s78, v60
	v_add_u32_e32 v56, s78, v61
	v_add_u32_e32 v57, s78, v62
	ds_read_b64_tr_b4 v[46:47], v160 offset:256
	ds_read_b64_tr_b4 v[48:49], v160 offset:1280
	ds_read_b64_tr_b4 v[122:123], v54
	ds_read_b64_tr_b4 v[124:125], v55
	ds_read_b64_tr_b4 v[126:127], v56
	ds_read_b64_tr_b4 v[128:129], v57
	s_waitcnt lgkmcnt(6)
	v_dot8c_i32_i4_e32 v38, v130, v52
	v_dot8c_i32_i4_e32 v39, v130, v50
	v_dot8c_i32_i4_e32 v40, v132, v52
	v_dot8c_i32_i4_e32 v41, v132, v50
	v_dot8c_i32_i4_e32 v42, v134, v52
	v_dot8c_i32_i4_e32 v43, v134, v50
	v_dot8c_i32_i4_e32 v44, v136, v52
	v_dot8c_i32_i4_e32 v45, v136, v50
	v_dot8c_i32_i4_e32 v38, v131, v53
	v_dot8c_i32_i4_e32 v39, v131, v51
	v_dot8c_i32_i4_e32 v40, v133, v53
	v_dot8c_i32_i4_e32 v41, v133, v51
	v_dot8c_i32_i4_e32 v42, v135, v53
	v_dot8c_i32_i4_e32 v43, v135, v51
	v_dot8c_i32_i4_e32 v44, v137, v53
	v_dot8c_i32_i4_e32 v45, v137, v51
	ds_write_b16 v65, v162
	ds_write_b16_d16_hi v65, v162 offset:128
	ds_write_b16 v65, v163 offset:256
	ds_write_b16_d16_hi v65, v163 offset:384
	ds_write_b16 v65, v164 offset:512
	ds_write_b16_d16_hi v65, v164 offset:640
	ds_write_b16 v65, v165 offset:768
	ds_write_b16_d16_hi v65, v165 offset:896
	ds_write_b16 v65, v166 offset:1024
	ds_write_b16_d16_hi v65, v166 offset:1152
	ds_write_b16 v65, v167 offset:1280
	ds_write_b16_d16_hi v65, v167 offset:1408
	ds_write_b16 v65, v168 offset:1536
	ds_write_b16_d16_hi v65, v168 offset:1664
	ds_write_b16 v65, v169 offset:1792
	ds_write_b16_d16_hi v65, v169 offset:1920
	ds_read_b64 v[202:203], v154
	ds_read_b64 v[204:205], v154 offset:512
	ds_read_b64 v[206:207], v154 offset:1024
	ds_read_b64 v[208:209], v154 offset:1536
	v_and_b32_e32 v78, 0xffff, v25
	v_lshrrev_b32_e32 v79, 16, v25
	v_lshl_add_u32 v78, v78, 7, v150
	v_lshl_add_u32 v79, v79, 7, v151
	s_mov_b32 m0, s77
	s_add_i32 s43, s77, 0x400
	global_load_lds_dwordx4 v78, s[50:51]
	s_mov_b32 m0, s43
	s_nop 0
	global_load_lds_dwordx4 v79, s[50:51]
	s_waitcnt vmcnt(9)
	v_add_u32_e32 v54, s79, v59
	v_add_u32_e32 v55, s79, v60
	v_add_u32_e32 v56, s79, v61
	v_add_u32_e32 v57, s79, v62
	ds_read_b64_tr_b4 v[50:51], v160 offset:384
	ds_read_b64_tr_b4 v[52:53], v160 offset:1408
	ds_read_b64_tr_b4 v[130:131], v54
	ds_read_b64_tr_b4 v[132:133], v55
	ds_read_b64_tr_b4 v[134:135], v56
	ds_read_b64_tr_b4 v[136:137], v57
	s_waitcnt lgkmcnt(15)
; #define LAS __attribute__((address_space(3)))
; #define TR4(p_) __builtin_amdgcn_ds_read_tr4_b64_v2i32((LAS v2i*)(p_))
; #define CFENCE() asm volatile("" ::: "memory")
; __device__ __forceinline__ void peer_v_tokens(int j, const LAS unsigned short* EL, const LAS unsigned char* AL  , const LAS float* ASC  , const LAS int* SAL  , ...
;     ...
;         for (int m = 0; m < 2; ++m) {
;             const int idx = lane + 64 * m, tau = idx >> 4, sr = idx & 15, k = 16 * (sr & 7) + 2 * tau + (sr >> 3);
;             const int aq = (int)*(const LAS signed char*)(AL + tl * 128 + k); const int tq = aq + 8;
;             const unsigned lo = (((unsigned)tq & 15u) ^ 8u) * 0x11111111u, hi = ((unsigned)(tq >> 4) & 15u) * 0x11111111u;
;             typedef unsigned u2v __attribute__((ext_vector_type(2)));
;             u2v l2; l2.x = lo; l2.y = lo; u2v h2; h2.x = hi; h2.y = hi;
;             *(LAS u2v*)(ATL + 8 * idx) = l2; *(LAS u2v*)(ATL + 1024 + 8 * idx) = h2;
;         }
;         const float asc = ASC[tl]; const int sa = SAL[tl];
;         CFENCE();
;         int accH[4], accL[4];
; #pragma unroll
;         for (int st = 0; st < 16; ++st) {
;             const int p = st >> 2, q = st & 3;
;             if (st < 14) VDMA(st + 2, (st + 2) % 3);
;             if (st < 14) asm volatile("s_waitcnt vmcnt(8)" ::: "memory");
;             else if (st == 14) asm volatile("s_waitcnt vmcnt(4)" ::: "memory");
;             else asm volatile("s_waitcnt vmcnt(0)" ::: "memory");
;             if (q == 0) {
; #pragma unroll
;                 for (int r = 0; r < 4; ++r) { accH[r] = 0; accL[r] = 0; } }
; #pragma unroll
;             for (int tp = 0; tp < 2; ++tp) {
;                 const v2i ao = TR4(ATL + (2 * q + tp) * 128 + 8 * s16), ah = TR4(ATL + 1024 + (2 * q + tp) * 128 + 8 * s16);
; #pragma unroll
;                 for (int r = 0; r < 4; ++r) {
;                     const v2i d = TR4(ldsb + BUF[st % 3] + 2048 * tp + roff[r]);
;                     accH[r] = __builtin_amdgcn_sdot8(d.x, ah.x, accH[r], false); accH[r] = __builtin_amdgcn_sdot8(d.y, ah.y, accH[r], false);
;                     accL[r] = __builtin_amdgcn_sdot8(d.x, ao.x, accL[r], false); accL[r] = __builtin_amdgcn_sdot8(d.y, ao.y, accL[r], false);
;                 }
;             }
	v_dot8c_i32_i4_e32 v38, v122, v48
	v_dot8c_i32_i4_e32 v39, v122, v46
	v_dot8c_i32_i4_e32 v40, v124, v48
	v_dot8c_i32_i4_e32 v41, v124, v46
	v_dot8c_i32_i4_e32 v42, v126, v48
	v_dot8c_i32_i4_e32 v43, v126, v46
	v_dot8c_i32_i4_e32 v44, v128, v48
	v_dot8c_i32_i4_e32 v45, v128, v46
	v_dot8c_i32_i4_e32 v38, v123, v49
	v_dot8c_i32_i4_e32 v39, v123, v47
	v_dot8c_i32_i4_e32 v40, v125, v49
	v_dot8c_i32_i4_e32 v41, v125, v47
	v_dot8c_i32_i4_e32 v42, v127, v49
	v_dot8c_i32_i4_e32 v43, v127, v47
	v_dot8c_i32_i4_e32 v44, v129, v49
	v_dot8c_i32_i4_e32 v45, v129, v47
	s_waitcnt lgkmcnt(15)
	v_and_b32_e32 v78, 0xffff, v26
	v_lshrrev_b32_e32 v79, 16, v26
	v_lshl_add_u32 v78, v78, 7, v150
	v_lshl_add_u32 v79, v79, 7, v151
	s_mov_b32 m0, s78
	s_add_i32 s43, s78, 0x400
	global_load_lds_dwordx4 v78, s[50:51]
	s_mov_b32 m0, s43
	s_nop 0
	global_load_lds_dwordx4 v79, s[50:51]
	s_waitcnt vmcnt(9)
	v_add_u32_e32 v54, s98, v59
	v_add_u32_e32 v55, s98, v60
	v_add_u32_e32 v56, s98, v61
	v_add_u32_e32 v57, s98, v62
	ds_read_b64_tr_b4 v[46:47], v160 offset:512
	ds_read_b64_tr_b4 v[48:49], v160 offset:1536
	ds_read_b64_tr_b4 v[122:123], v54
	ds_read_b64_tr_b4 v[124:125], v55
	ds_read_b64_tr_b4 v[126:127], v56
	ds_read_b64_tr_b4 v[128:129], v57
	s_waitcnt lgkmcnt(6)
	v_dot8c_i32_i4_e32 v38, v130, v52
	v_dot8c_i32_i4_e32 v39, v130, v50
	v_dot8c_i32_i4_e32 v40, v132, v52
	v_dot8c_i32_i4_e32 v41, v132, v50
	v_dot8c_i32_i4_e32 v42, v134, v52
	v_dot8c_i32_i4_e32 v43, v134, v50
	v_dot8c_i32_i4_e32 v44, v136, v52
	v_dot8c_i32_i4_e32 v45, v136, v50
	v_dot8c_i32_i4_e32 v38, v131, v53
	v_dot8c_i32_i4_e32 v39, v131, v51
	v_dot8c_i32_i4_e32 v40, v133, v53
	v_dot8c_i32_i4_e32 v41, v133, v51
	v_dot8c_i32_i4_e32 v42, v135, v53
	v_dot8c_i32_i4_e32 v43, v135, v51
	v_dot8c_i32_i4_e32 v44, v137, v53
	v_dot8c_i32_i4_e32 v45, v137, v51
	v_and_b32_e32 v78, 0xffff, v27
	v_lshrrev_b32_e32 v79, 16, v27
	v_lshl_add_u32 v78, v78, 7, v150
	v_lshl_add_u32 v79, v79, 7, v151
	s_mov_b32 m0, s79
	s_add_i32 s43, s79, 0x400
	global_load_lds_dwordx4 v78, s[50:51]
	s_mov_b32 m0, s43
	s_nop 0
	global_load_lds_dwordx4 v79, s[50:51]
	s_waitcnt vmcnt(8)
	v_add_u32_e32 v54, s99, v59
	v_add_u32_e32 v55, s99, v60
	v_add_u32_e32 v56, s99, v61
	v_add_u32_e32 v57, s99, v62
	ds_read_b64_tr_b4 v[50:51], v160 offset:640
	ds_read_b64_tr_b4 v[52:53], v160 offset:1664
	ds_read_b64_tr_b4 v[130:131], v54
	ds_read_b64_tr_b4 v[132:133], v55
	ds_read_b64_tr_b4 v[134:135], v56
	ds_read_b64_tr_b4 v[136:137], v57
	s_waitcnt lgkmcnt(6)
	v_dot8c_i32_i4_e32 v38, v122, v48
	v_dot8c_i32_i4_e32 v39, v122, v46
	v_dot8c_i32_i4_e32 v40, v124, v48
	v_dot8c_i32_i4_e32 v41, v124, v46
	v_dot8c_i32_i4_e32 v42, v126, v48
	v_dot8c_i32_i4_e32 v43, v126, v46
	v_dot8c_i32_i4_e32 v44, v128, v48
	v_dot8c_i32_i4_e32 v45, v128, v46
	v_dot8c_i32_i4_e32 v38, v123, v49
	v_dot8c_i32_i4_e32 v39, v123, v47
	v_dot8c_i32_i4_e32 v40, v125, v49
	v_dot8c_i32_i4_e32 v41, v125, v47
	v_dot8c_i32_i4_e32 v42, v127, v49
	v_dot8c_i32_i4_e32 v43, v127, v47
	v_dot8c_i32_i4_e32 v44, v129, v49
	v_dot8c_i32_i4_e32 v45, v129, v47
	s_waitcnt lgkmcnt(15)
	v_add_u32_e32 v143, 8, v139
	v_and_b32_e32 v142, 15, v143
	v_xor_b32_e32 v142, 8, v142
	v_bfe_u32 v144, v143, 4, 4
	v_mul_lo_u32 v142, v142, s92
	v_mul_lo_u32 v144, v144, s92
	v_mov_b32_e32 v143, v142
	v_mov_b32_e32 v145, v144
	ds_write2st64_b64 v159, v[142:143], v[144:145] offset1:2
	v_and_b32_e32 v78, 0xffff, v28
	v_lshrrev_b32_e32 v79, 16, v28
	v_lshl_add_u32 v78, v78, 7, v150
	v_lshl_add_u32 v79, v79, 7, v151
	s_mov_b32 m0, s98
	s_add_i32 s43, s98, 0x400
	global_load_lds_dwordx4 v78, s[50:51]
	s_mov_b32 m0, s43
	s_nop 0
	global_load_lds_dwordx4 v79, s[50:51]
	s_waitcnt vmcnt(8)
	v_add_u32_e32 v54, s76, v59
	v_add_u32_e32 v55, s76, v60
	v_add_u32_e32 v56, s76, v61
	v_add_u32_e32 v57, s76, v62
	ds_read_b64_tr_b4 v[46:47], v160 offset:768
	ds_read_b64_tr_b4 v[48:49], v160 offset:1792
	ds_read_b64_tr_b4 v[122:123], v54
	ds_read_b64_tr_b4 v[124:125], v55
	ds_read_b64_tr_b4 v[126:127], v56
	ds_read_b64_tr_b4 v[128:129], v57
	s_waitcnt lgkmcnt(7)
	v_dot8c_i32_i4_e32 v38, v130, v52
	v_dot8c_i32_i4_e32 v39, v130, v50
	v_dot8c_i32_i4_e32 v40, v132, v52
	v_dot8c_i32_i4_e32 v41, v132, v50
	v_dot8c_i32_i4_e32 v42, v134, v52
	v_dot8c_i32_i4_e32 v43, v134, v50
	v_dot8c_i32_i4_e32 v44, v136, v52
	v_dot8c_i32_i4_e32 v45, v136, v50
	v_dot8c_i32_i4_e32 v38, v131, v53
	v_dot8c_i32_i4_e32 v39, v131, v51
	v_dot8c_i32_i4_e32 v40, v133, v53
	v_dot8c_i32_i4_e32 v41, v133, v51
	v_dot8c_i32_i4_e32 v42, v135, v53
	v_dot8c_i32_i4_e32 v43, v135, v51
	v_dot8c_i32_i4_e32 v44, v137, v53
	v_dot8c_i32_i4_e32 v45, v137, v51
	v_and_b32_e32 v78, 0xffff, v29
	v_lshrrev_b32_e32 v79, 16, v29
	v_lshl_add_u32 v78, v78, 7, v150
	v_lshl_add_u32 v79, v79, 7, v151
	s_mov_b32 m0, s99
	s_add_i32 s43, s99, 0x400
	global_load_lds_dwordx4 v78, s[50:51]
	s_mov_b32 m0, s43
	s_nop 0
	global_load_lds_dwordx4 v79, s[50:51]
	s_waitcnt vmcnt(8)
	v_add_u32_e32 v54, s77, v59
	v_add_u32_e32 v55, s77, v60
	v_add_u32_e32 v56, s77, v61
	v_add_u32_e32 v57, s77, v62
	ds_read_b64_tr_b4 v[50:51], v160 offset:896
	ds_read_b64_tr_b4 v[52:53], v160 offset:1920
	ds_read_b64_tr_b4 v[130:131], v54
	ds_read_b64_tr_b4 v[132:133], v55
	ds_read_b64_tr_b4 v[134:135], v56
	ds_read_b64_tr_b4 v[136:137], v57
	s_waitcnt lgkmcnt(6)
; __device__ __forceinline__ void peer_v_tokens(int j, const LAS unsigned short* EL, const LAS unsigned char* AL  , const LAS float* ASC  , const LAS int* SAL  , ...
;     ...
; #pragma unroll 1
;     for (int it = 0; it < 8; ++it) {
;         const int tl = it * 8 + wave, t = j * 64 + tl;
;         unsigned E[8];
;         { const LAS v4u* ep = (const LAS v4u*)(EL + tl * 128 + 16 * g); const v4u e0 = ep[0], e1 = ep[1];
;           E[0] = e0.x; E[1] = e0.y; E[2] = e0.z; E[3] = e0.w; E[4] = e1.x; E[5] = e1.y; E[6] = e1.z; E[7] = e1.w; }
;         uint2 hv[4]; float4 gv[4];
;         { unsigned ho = (unsigned)t * (D / 4) + (unsigned)lane; asm volatile("" : "+v"(ho)); const uint2* hp = (const uint2*)HB + ho; const float4* gp = (const float4*)fng + lane;
; #pragma unroll
;           for (int jq = 0; jq < 4; ++jq) { hv[jq] = hp[64 * jq]; gv[jq] = gp[64 * jq]; } }
;         VDMA(0, 0); VDMA(1, 1);
; #pragma unroll
;         for (int m = 0; m < 2; ++m) {
;             const int idx = lane + 64 * m, tau = idx >> 4, sr = idx & 15, k = 16 * (sr & 7) + 2 * tau + (sr >> 3);
;             const int aq = (int)*(const LAS signed char*)(AL + tl * 128 + k); const int tq = aq + 8;
;             const unsigned lo = (((unsigned)tq & 15u) ^ 8u) * 0x11111111u, hi = ((unsigned)(tq >> 4) & 15u) * 0x11111111u;
;             typedef unsigned u2v __attribute__((ext_vector_type(2)));
;             u2v l2; l2.x = lo; l2.y = lo; u2v h2; h2.x = hi; h2.y = hi;
;             *(LAS u2v*)(ATL + 8 * idx) = l2; *(LAS u2v*)(ATL + 1024 + 8 * idx) = h2;
;         }
;         const float asc = ASC[tl]; const int sa = SAL[tl];
;         CFENCE();
;         int accH[4], accL[4];
; #pragma unroll
;         for (int st = 0; st < 16; ++st) {
;             const int p = st >> 2, q = st & 3;
;             if (st < 14) VDMA(st + 2, (st + 2) % 3);
;             if (st < 14) asm volatile("s_waitcnt vmcnt(8)" ::: "memory");
;             else if (st == 14) asm volatile("s_waitcnt vmcnt(4)" ::: "memory");
;             else asm volatile("s_waitcnt vmcnt(0)" ::: "memory");
;             if (q == 0) {
; #pragma unroll
;                 for (int r = 0; r < 4; ++r) { accH[r] = 0; accL[r] = 0; } }
; #pragma unroll
;             for (int tp = 0; tp < 2; ++tp) {
;                 const v2i ao = TR4(ATL + (2 * q + tp) * 128 + 8 * s16), ah = TR4(ATL + 1024 + (2 * q + tp) * 128 + 8 * s16);
; #pragma unroll
	v_dot8c_i32_i4_e32 v38, v122, v48
	v_dot8c_i32_i4_e32 v39, v122, v46
	v_dot8c_i32_i4_e32 v40, v124, v48
	v_dot8c_i32_i4_e32 v41, v124, v46
	v_dot8c_i32_i4_e32 v42, v126, v48
	v_dot8c_i32_i4_e32 v43, v126, v46
	v_dot8c_i32_i4_e32 v44, v128, v48
	v_dot8c_i32_i4_e32 v45, v128, v46
	v_dot8c_i32_i4_e32 v38, v123, v49
	v_dot8c_i32_i4_e32 v39, v123, v47
	v_dot8c_i32_i4_e32 v40, v125, v49
	v_dot8c_i32_i4_e32 v41, v125, v47
	v_dot8c_i32_i4_e32 v42, v127, v49
	v_dot8c_i32_i4_e32 v43, v127, v47
	v_dot8c_i32_i4_e32 v44, v129, v49
	v_dot8c_i32_i4_e32 v45, v129, v47
	v_and_b32_e32 v78, 0xffff, v30
	v_lshrrev_b32_e32 v79, 16, v30
	v_lshl_add_u32 v78, v78, 7, v150
	v_lshl_add_u32 v79, v79, 7, v151
	s_mov_b32 m0, s76
	s_add_i32 s43, s76, 0x400
	global_load_lds_dwordx4 v78, s[50:51]
	s_mov_b32 m0, s43
	s_nop 0
	global_load_lds_dwordx4 v79, s[50:51]
	s_waitcnt vmcnt(8)
	v_add_u32_e32 v54, s78, v59
	v_add_u32_e32 v55, s78, v60
	v_add_u32_e32 v56, s78, v61
	v_add_u32_e32 v57, s78, v62
	ds_read_b64_tr_b4 v[46:47], v160
	ds_read_b64_tr_b4 v[48:49], v160 offset:1024
	ds_read_b64_tr_b4 v[122:123], v54
	ds_read_b64_tr_b4 v[124:125], v55
	ds_read_b64_tr_b4 v[126:127], v56
	ds_read_b64_tr_b4 v[128:129], v57
	s_waitcnt lgkmcnt(6)
	v_dot8c_i32_i4_e32 v38, v130, v52
	v_dot8c_i32_i4_e32 v39, v130, v50
	v_dot8c_i32_i4_e32 v40, v132, v52
	v_dot8c_i32_i4_e32 v41, v132, v50
	v_dot8c_i32_i4_e32 v42, v134, v52
	v_dot8c_i32_i4_e32 v43, v134, v50
	v_dot8c_i32_i4_e32 v44, v136, v52
	v_dot8c_i32_i4_e32 v45, v136, v50
	v_dot8c_i32_i4_e32 v38, v131, v53
	v_dot8c_i32_i4_e32 v39, v131, v51
	v_dot8c_i32_i4_e32 v40, v133, v53
	v_dot8c_i32_i4_e32 v41, v133, v51
	v_dot8c_i32_i4_e32 v42, v135, v53
	v_dot8c_i32_i4_e32 v43, v135, v51
	v_dot8c_i32_i4_e32 v44, v137, v53
	v_dot8c_i32_i4_e32 v45, v137, v51
	s_nop 3
	s_waitcnt lgkmcnt(15)
	v_lshlrev_b32_e32 v38, 5, v38
	v_lshlrev_b32_e32 v39, 1, v39
	v_add3_u32 v38, v39, v229, v38
	v_cvt_f32_i32_e32 v38, v38
	v_mul_f32_e32 v38, v228, v38
	v_lshlrev_b32_e32 v40, 5, v40
	v_lshlrev_b32_e32 v41, 1, v41
	v_add3_u32 v40, v41, v229, v40
	v_cvt_f32_i32_e32 v40, v40
	v_mul_f32_e32 v40, v228, v40
	v_lshlrev_b32_e32 v42, 5, v42
	v_lshlrev_b32_e32 v43, 1, v43
	v_add3_u32 v42, v43, v229, v42
	v_cvt_f32_i32_e32 v42, v42
	v_mul_f32_e32 v42, v228, v42
	v_lshlrev_b32_e32 v44, 5, v44
	v_lshlrev_b32_e32 v45, 1, v45
	v_add3_u32 v44, v45, v229, v44
	v_cvt_f32_i32_e32 v44, v44
	v_mul_f32_e32 v44, v228, v44
	v_cvt_pk_bf16_f32 v178, v38, v40
	v_cvt_pk_bf16_f32 v179, v42, v44
	v_add_u32_e32 v147, 8, v140
	v_and_b32_e32 v146, 15, v147
	v_xor_b32_e32 v146, 8, v146
	v_bfe_u32 v148, v147, 4, 4
	v_mul_lo_u32 v146, v146, s92
	v_mul_lo_u32 v148, v148, s92
	v_mov_b32_e32 v147, v146
	v_mov_b32_e32 v149, v148
	ds_write2st64_b64 v77, v[146:147], v[148:149] offset1:2
	v_add_u32_e32 v138, 0x1800, v74
	ds_read_u8 v139, v138
	v_add_u32_e32 v141, 0x1800, v73
	ds_read_u8 v140, v141
	s_add_i32 s43, s67, 224
	v_mov_b32_e32 v138, s43
	ds_read2st64_b32 v[228:229], v138 offset1:1
	ds_read_b128 v[18:21], v227 offset:12288
	ds_read_b128 v[22:25], v227 offset:12304
	v_add_u32_e32 v152, 0x200000, v63
	v_add_u32_e32 v153, 0x200000, v64
	v_mov_b32_e32 v38, 0
	v_mov_b32_e32 v39, 0
	v_mov_b32_e32 v40, 0
	v_mov_b32_e32 v41, 0
	v_mov_b32_e32 v42, 0
	v_mov_b32_e32 v43, 0
	v_mov_b32_e32 v44, 0
	v_mov_b32_e32 v45, 0
	v_and_b32_e32 v78, 0xffff, v31
	v_lshrrev_b32_e32 v79, 16, v31
	v_lshl_add_u32 v78, v78, 7, v150
	v_lshl_add_u32 v79, v79, 7, v151
	s_mov_b32 m0, s77
	s_add_i32 s43, s77, 0x400
	global_load_lds_dwordx4 v78, s[50:51]
	s_mov_b32 m0, s43
	s_nop 0
	global_load_lds_dwordx4 v79, s[50:51]
	s_waitcnt vmcnt(8)
	v_add_u32_e32 v54, s79, v59
	v_add_u32_e32 v55, s79, v60
	v_add_u32_e32 v56, s79, v61
	v_add_u32_e32 v57, s79, v62
	ds_read_b64_tr_b4 v[50:51], v160 offset:128
	ds_read_b64_tr_b4 v[52:53], v160 offset:1152
	ds_read_b64_tr_b4 v[130:131], v54
	ds_read_b64_tr_b4 v[132:133], v55
	ds_read_b64_tr_b4 v[134:135], v56
	ds_read_b64_tr_b4 v[136:137], v57
	s_waitcnt lgkmcnt(12)
	s_waitcnt vmcnt(35) lgkmcnt(15)
	v_lshlrev_b32_e32 v210, 16, v194
	v_and_b32_e32 v211, 0xffff0000, v194
	v_lshlrev_b32_e32 v142, 16, v202
	v_and_b32_e32 v143, 0xffff0000, v202
	v_add_f32_e32 v210, v210, v142
	v_add_f32_e32 v211, v211, v143
	v_lshlrev_b32_e32 v212, 16, v195
	v_and_b32_e32 v213, 0xffff0000, v195
	v_lshlrev_b32_e32 v142, 16, v203
	v_and_b32_e32 v143, 0xffff0000, v203
	v_add_f32_e32 v212, v212, v142
	v_add_f32_e32 v213, v213, v143
	v_lshlrev_b32_e32 v214, 16, v196
	v_and_b32_e32 v215, 0xffff0000, v196
	v_lshlrev_b32_e32 v142, 16, v204
	v_and_b32_e32 v143, 0xffff0000, v204
	v_add_f32_e32 v214, v214, v142
	v_add_f32_e32 v215, v215, v143
	v_lshlrev_b32_e32 v216, 16, v197
	v_and_b32_e32 v217, 0xffff0000, v197
	v_lshlrev_b32_e32 v142, 16, v205
	v_and_b32_e32 v143, 0xffff0000, v205
	v_add_f32_e32 v216, v216, v142
	v_add_f32_e32 v217, v217, v143
	v_lshlrev_b32_e32 v218, 16, v198
	v_and_b32_e32 v219, 0xffff0000, v198
	v_lshlrev_b32_e32 v142, 16, v206
	v_and_b32_e32 v143, 0xffff0000, v206
	v_add_f32_e32 v218, v218, v142
	v_add_f32_e32 v219, v219, v143
	v_lshlrev_b32_e32 v220, 16, v199
	v_and_b32_e32 v221, 0xffff0000, v199
	v_lshlrev_b32_e32 v142, 16, v207
	v_and_b32_e32 v143, 0xffff0000, v207
	v_add_f32_e32 v220, v220, v142
	v_add_f32_e32 v221, v221, v143
	v_lshlrev_b32_e32 v222, 16, v200
	v_and_b32_e32 v223, 0xffff0000, v200
	v_lshlrev_b32_e32 v142, 16, v208
	v_and_b32_e32 v143, 0xffff0000, v208
	v_add_f32_e32 v222, v222, v142
	v_add_f32_e32 v223, v223, v143
	v_lshlrev_b32_e32 v224, 16, v201
	v_and_b32_e32 v225, 0xffff0000, v201
	v_lshlrev_b32_e32 v142, 16, v209
	v_and_b32_e32 v143, 0xffff0000, v209
	v_add_f32_e32 v224, v224, v142
; #define LAS __attribute__((address_space(3)))
; #define TR4(p_) __builtin_amdgcn_ds_read_tr4_b64_v2i32((LAS v2i*)(p_))
; __device__ __forceinline__ void peer_v_tokens(int j, const LAS unsigned short* EL, const LAS unsigned char* AL  , const LAS float* ASC  , const LAS int* SAL  , ...
;     ...
;         for (int st = 0; st < 16; ++st) {
;             const int p = st >> 2, q = st & 3;
;             if (st < 14) VDMA(st + 2, (st + 2) % 3);
;             if (st < 14) asm volatile("s_waitcnt vmcnt(8)" ::: "memory");
;             else if (st == 14) asm volatile("s_waitcnt vmcnt(4)" ::: "memory");
;             else asm volatile("s_waitcnt vmcnt(0)" ::: "memory");
;             if (q == 0) {
; #pragma unroll
;                 for (int r = 0; r < 4; ++r) { accH[r] = 0; accL[r] = 0; } }
; #pragma unroll
;             for (int tp = 0; tp < 2; ++tp) {
;                 const v2i ao = TR4(ATL + (2 * q + tp) * 128 + 8 * s16), ah = TR4(ATL + 1024 + (2 * q + tp) * 128 + 8 * s16);
; #pragma unroll
;                 for (int r = 0; r < 4; ++r) {
;                     const v2i d = TR4(ldsb + BUF[st % 3] + 2048 * tp + roff[r]);
;                     accH[r] = __builtin_amdgcn_sdot8(d.x, ah.x, accH[r], false); accH[r] = __builtin_amdgcn_sdot8(d.y, ah.y, accH[r], false);
;                     accL[r] = __builtin_amdgcn_sdot8(d.x, ao.x, accL[r], false); accL[r] = __builtin_amdgcn_sdot8(d.y, ao.y, accL[r], false);
;                 }
;             }
;     ...
;         {
;             float4 v[4]; float ss = 0.f;
; #pragma unroll
;             for (int jq = 0; jq < 4; ++jq) { typedef unsigned u2v __attribute__((ext_vector_type(2))); const u2v pw = *(const LAS u2v*)(STASH + 4 * lane + 256 * jq); const uint2 hw = hv[jq];
;                 v[jq] = make_float4(__uint_as_float(hw.x << 16) + __uint_as_float(pw.x << 16), __uint_as_float(hw.x & 0xffff0000u) + __uint_as_float(pw.x & 0xffff0000u),
;                                     __uint_as_float(hw.y << 16) + __uint_as_float(pw.y << 16), __uint_as_float(hw.y & 0xffff0000u) + __uint_as_float(pw.y & 0xffff0000u));
;                 ss += v[jq].x * v[jq].x + v[jq].y * v[jq].y + v[jq].z * v[jq].z + v[jq].w * v[jq].w; }
;             ss = wave_sum(ss);
;             const float r3 = rsqrtf(ss * (1.f / D) + EPS);
	v_add_f32_e32 v225, v225, v143
	v_mov_b32_e32 v144, 0
	v_mul_f32_e32 v145, v210, v210
	v_fmac_f32_e32 v145, v211, v211
	v_fmac_f32_e32 v145, v212, v212
	v_fmac_f32_e32 v145, v213, v213
	v_add_f32_e32 v144, v144, v145
	v_mul_f32_e32 v145, v214, v214
	v_fmac_f32_e32 v145, v215, v215
	v_fmac_f32_e32 v145, v216, v216
	v_fmac_f32_e32 v145, v217, v217
	v_add_f32_e32 v144, v144, v145
	v_mul_f32_e32 v145, v218, v218
	v_fmac_f32_e32 v145, v219, v219
	v_fmac_f32_e32 v145, v220, v220
	v_fmac_f32_e32 v145, v221, v221
	v_add_f32_e32 v144, v144, v145
	v_mul_f32_e32 v145, v222, v222
	v_fmac_f32_e32 v145, v223, v223
	v_fmac_f32_e32 v145, v224, v224
	v_fmac_f32_e32 v145, v225, v225
	v_add_f32_e32 v144, v144, v145
	s_nop 1
	v_add_f32_dpp v144, v144, v144 quad_perm:[1,0,3,2] row_mask:0xf bank_mask:0xf bound_ctrl:1
	s_nop 1
	v_add_f32_dpp v144, v144, v144 quad_perm:[2,3,0,1] row_mask:0xf bank_mask:0xf bound_ctrl:1
	s_nop 1
	v_add_f32_dpp v144, v144, v144 row_half_mirror row_mask:0xf bank_mask:0xf bound_ctrl:1
	s_nop 1
	v_add_f32_dpp v144, v144, v144 row_mirror row_mask:0xf bank_mask:0xf bound_ctrl:1
	s_nop 1
	v_readlane_b32 s10, v144, 0
	v_readlane_b32 s11, v144, 16
	v_readlane_b32 s14, v144, 32
	v_readlane_b32 s15, v144, 48
	s_nop 3
	v_mov_b32_e32 v144, s11
	v_mov_b32_e32 v145, s15
	v_add_f32_e32 v144, s10, v144
	v_add_f32_e32 v145, s14, v145
	v_add_f32_e32 v144, v144, v145
	v_fmamk_f32 v144, v144, 0x3a800000, v111
	v_rsq_f32_e32 v144, v144
	s_nop 0
	v_mul_f32_e32 v210, v210, v144
	v_mul_f32_e32 v211, v211, v144
	v_mul_f32_e32 v212, v212, v144
	v_mul_f32_e32 v213, v213, v144
	v_mul_f32_e32 v214, v214, v144
	v_mul_f32_e32 v215, v215, v144
	v_mul_f32_e32 v216, v216, v144
	v_mul_f32_e32 v217, v217, v144
	v_mul_f32_e32 v218, v218, v144
	v_mul_f32_e32 v219, v219, v144
	v_mul_f32_e32 v220, v220, v144
	v_mul_f32_e32 v221, v221, v144
	v_mul_f32_e32 v222, v222, v144
	v_mul_f32_e32 v223, v223, v144
	v_mul_f32_e32 v224, v224, v144
	v_mul_f32_e32 v225, v225, v144
	v_dot8c_i32_i4_e32 v38, v122, v48
	v_dot8c_i32_i4_e32 v39, v122, v46
	v_dot8c_i32_i4_e32 v40, v124, v48
	v_dot8c_i32_i4_e32 v41, v124, v46
	v_dot8c_i32_i4_e32 v42, v126, v48
	v_dot8c_i32_i4_e32 v43, v126, v46
	v_dot8c_i32_i4_e32 v44, v128, v48
	v_dot8c_i32_i4_e32 v45, v128, v46
	v_dot8c_i32_i4_e32 v38, v123, v49
	v_dot8c_i32_i4_e32 v39, v123, v47
	v_dot8c_i32_i4_e32 v40, v125, v49
	v_dot8c_i32_i4_e32 v41, v125, v47
	v_dot8c_i32_i4_e32 v42, v127, v49
	v_dot8c_i32_i4_e32 v43, v127, v47
	v_dot8c_i32_i4_e32 v44, v129, v49
	v_dot8c_i32_i4_e32 v45, v129, v47
	v_and_b32_e32 v78, 0xffff, v32
	v_lshrrev_b32_e32 v79, 16, v32
	v_lshl_add_u32 v78, v78, 7, v150
	v_lshl_add_u32 v79, v79, 7, v151
	s_mov_b32 m0, s78
	s_add_i32 s43, s78, 0x400
	global_load_lds_dwordx4 v78, s[50:51]
	s_mov_b32 m0, s43
	s_nop 0
	global_load_lds_dwordx4 v79, s[50:51]
	s_waitcnt vmcnt(8)
	v_add_u32_e32 v54, s98, v59
	v_add_u32_e32 v55, s98, v60
	v_add_u32_e32 v56, s98, v61
	v_add_u32_e32 v57, s98, v62
	ds_read_b64_tr_b4 v[46:47], v160 offset:256
	ds_read_b64_tr_b4 v[48:49], v160 offset:1280
	ds_read_b64_tr_b4 v[122:123], v54
	ds_read_b64_tr_b4 v[124:125], v55
	ds_read_b64_tr_b4 v[126:127], v56
	ds_read_b64_tr_b4 v[128:129], v57
	s_waitcnt lgkmcnt(6)
	v_dot8c_i32_i4_e32 v38, v130, v52
	v_dot8c_i32_i4_e32 v39, v130, v50
	v_dot8c_i32_i4_e32 v40, v132, v52
	v_dot8c_i32_i4_e32 v41, v132, v50
	v_dot8c_i32_i4_e32 v42, v134, v52
	v_dot8c_i32_i4_e32 v43, v134, v50
	v_dot8c_i32_i4_e32 v44, v136, v52
	v_dot8c_i32_i4_e32 v45, v136, v50
	v_dot8c_i32_i4_e32 v38, v131, v53
	v_dot8c_i32_i4_e32 v39, v131, v51
	v_dot8c_i32_i4_e32 v40, v133, v53
	v_dot8c_i32_i4_e32 v41, v133, v51
	v_dot8c_i32_i4_e32 v42, v135, v53
	v_dot8c_i32_i4_e32 v43, v135, v51
	v_dot8c_i32_i4_e32 v44, v137, v53
	v_dot8c_i32_i4_e32 v45, v137, v51
	v_and_b32_e32 v78, 0xffff, v33
	v_lshrrev_b32_e32 v79, 16, v33
	v_lshl_add_u32 v78, v78, 7, v150
	v_lshl_add_u32 v79, v79, 7, v151
	s_mov_b32 m0, s79
	s_add_i32 s43, s79, 0x400
	global_load_lds_dwordx4 v78, s[50:51]
	s_mov_b32 m0, s43
	s_nop 0
	global_load_lds_dwordx4 v79, s[50:51]
	s_waitcnt vmcnt(8)
	v_add_u32_e32 v54, s99, v59
	v_add_u32_e32 v55, s99, v60
	v_add_u32_e32 v56, s99, v61
	v_add_u32_e32 v57, s99, v62
	ds_read_b64_tr_b4 v[50:51], v160 offset:384
	ds_read_b64_tr_b4 v[52:53], v160 offset:1408
	ds_read_b64_tr_b4 v[130:131], v54
	ds_read_b64_tr_b4 v[132:133], v55
	ds_read_b64_tr_b4 v[134:135], v56
	ds_read_b64_tr_b4 v[136:137], v57
	s_waitcnt lgkmcnt(6)
	v_dot8c_i32_i4_e32 v38, v122, v48
	v_dot8c_i32_i4_e32 v39, v122, v46
	v_dot8c_i32_i4_e32 v40, v124, v48
	v_dot8c_i32_i4_e32 v41, v124, v46
	v_dot8c_i32_i4_e32 v42, v126, v48
	v_dot8c_i32_i4_e32 v43, v126, v46
	v_dot8c_i32_i4_e32 v44, v128, v48
	v_dot8c_i32_i4_e32 v45, v128, v46
	v_dot8c_i32_i4_e32 v38, v123, v49
	v_dot8c_i32_i4_e32 v39, v123, v47
	v_dot8c_i32_i4_e32 v40, v125, v49
	v_dot8c_i32_i4_e32 v41, v125, v47
	v_dot8c_i32_i4_e32 v42, v127, v49
	v_dot8c_i32_i4_e32 v43, v127, v47
	v_dot8c_i32_i4_e32 v44, v129, v49
	v_dot8c_i32_i4_e32 v45, v129, v47
	s_waitcnt lgkmcnt(15)
	v_and_b32_e32 v78, 0xffff, v18
	v_lshrrev_b32_e32 v79, 16, v18
	v_lshl_add_u32 v78, v78, 7, v152
	v_lshl_add_u32 v79, v79, 7, v153
	s_mov_b32 m0, s98
	s_add_i32 s43, s98, 0x400
	global_load_lds_dwordx4 v78, s[50:51]
	s_mov_b32 m0, s43
	s_nop 0
	global_load_lds_dwordx4 v79, s[50:51]
	s_waitcnt vmcnt(8)
	v_add_u32_e32 v54, s76, v59
	v_add_u32_e32 v55, s76, v60
	v_add_u32_e32 v56, s76, v61
	v_add_u32_e32 v57, s76, v62
	ds_read_b64_tr_b4 v[46:47], v160 offset:512
	ds_read_b64_tr_b4 v[48:49], v160 offset:1536
	ds_read_b64_tr_b4 v[122:123], v54
	ds_read_b64_tr_b4 v[124:125], v55
	ds_read_b64_tr_b4 v[126:127], v56
	ds_read_b64_tr_b4 v[128:129], v57
	s_waitcnt lgkmcnt(6)
; #define LAS __attribute__((address_space(3)))
; #define TR4(p_) __builtin_amdgcn_ds_read_tr4_b64_v2i32((LAS v2i*)(p_))
; #define CFENCE() asm volatile("" ::: "memory")
; __device__ __forceinline__ void peer_v_tokens(int j, const LAS unsigned short* EL, const LAS unsigned char* AL  , const LAS float* ASC  , const LAS int* SAL  , ...
;     ...
;         for (int m = 0; m < 2; ++m) {
;             const int idx = lane + 64 * m, tau = idx >> 4, sr = idx & 15, k = 16 * (sr & 7) + 2 * tau + (sr >> 3);
;             const int aq = (int)*(const LAS signed char*)(AL + tl * 128 + k); const int tq = aq + 8;
;             const unsigned lo = (((unsigned)tq & 15u) ^ 8u) * 0x11111111u, hi = ((unsigned)(tq >> 4) & 15u) * 0x11111111u;
;             typedef unsigned u2v __attribute__((ext_vector_type(2)));
;             u2v l2; l2.x = lo; l2.y = lo; u2v h2; h2.x = hi; h2.y = hi;
;             *(LAS u2v*)(ATL + 8 * idx) = l2; *(LAS u2v*)(ATL + 1024 + 8 * idx) = h2;
;         }
;         const float asc = ASC[tl]; const int sa = SAL[tl];
;         CFENCE();
;         int accH[4], accL[4];
; #pragma unroll
;         for (int st = 0; st < 16; ++st) {
;             const int p = st >> 2, q = st & 3;
;             if (st < 14) VDMA(st + 2, (st + 2) % 3);
;             if (st < 14) asm volatile("s_waitcnt vmcnt(8)" ::: "memory");
;             else if (st == 14) asm volatile("s_waitcnt vmcnt(4)" ::: "memory");
;             else asm volatile("s_waitcnt vmcnt(0)" ::: "memory");
;             if (q == 0) {
; #pragma unroll
;                 for (int r = 0; r < 4; ++r) { accH[r] = 0; accL[r] = 0; } }
; #pragma unroll
;             for (int tp = 0; tp < 2; ++tp) {
;                 const v2i ao = TR4(ATL + (2 * q + tp) * 128 + 8 * s16), ah = TR4(ATL + 1024 + (2 * q + tp) * 128 + 8 * s16);
; #pragma unroll
;                 for (int r = 0; r < 4; ++r) {
;                     const v2i d = TR4(ldsb + BUF[st % 3] + 2048 * tp + roff[r]);
;                     accH[r] = __builtin_amdgcn_sdot8(d.x, ah.x, accH[r], false); accH[r] = __builtin_amdgcn_sdot8(d.y, ah.y, accH[r], false);
;                     accL[r] = __builtin_amdgcn_sdot8(d.x, ao.x, accL[r], false); accL[r] = __builtin_amdgcn_sdot8(d.y, ao.y, accL[r], false);
;                 }
;             }
	v_dot8c_i32_i4_e32 v38, v130, v52
	v_dot8c_i32_i4_e32 v39, v130, v50
	v_dot8c_i32_i4_e32 v40, v132, v52
	v_dot8c_i32_i4_e32 v41, v132, v50
	v_dot8c_i32_i4_e32 v42, v134, v52
	v_dot8c_i32_i4_e32 v43, v134, v50
	v_dot8c_i32_i4_e32 v44, v136, v52
	v_dot8c_i32_i4_e32 v45, v136, v50
	v_dot8c_i32_i4_e32 v38, v131, v53
	v_dot8c_i32_i4_e32 v39, v131, v51
	v_dot8c_i32_i4_e32 v40, v133, v53
	v_dot8c_i32_i4_e32 v41, v133, v51
	v_dot8c_i32_i4_e32 v42, v135, v53
	v_dot8c_i32_i4_e32 v43, v135, v51
	v_dot8c_i32_i4_e32 v44, v137, v53
	v_dot8c_i32_i4_e32 v45, v137, v51
	v_and_b32_e32 v78, 0xffff, v19
	v_lshrrev_b32_e32 v79, 16, v19
	v_lshl_add_u32 v78, v78, 7, v152
	v_lshl_add_u32 v79, v79, 7, v153
	s_mov_b32 m0, s99
	s_add_i32 s43, s99, 0x400
	global_load_lds_dwordx4 v78, s[50:51]
	s_mov_b32 m0, s43
	s_nop 0
	global_load_lds_dwordx4 v79, s[50:51]
	s_waitcnt vmcnt(8)
	v_add_u32_e32 v54, s77, v59
	v_add_u32_e32 v55, s77, v60
	v_add_u32_e32 v56, s77, v61
	v_add_u32_e32 v57, s77, v62
	ds_read_b64_tr_b4 v[50:51], v160 offset:640
	ds_read_b64_tr_b4 v[52:53], v160 offset:1664
	ds_read_b64_tr_b4 v[130:131], v54
	ds_read_b64_tr_b4 v[132:133], v55
	ds_read_b64_tr_b4 v[134:135], v56
	ds_read_b64_tr_b4 v[136:137], v57
	s_waitcnt lgkmcnt(6)
	v_dot8c_i32_i4_e32 v38, v122, v48
	v_dot8c_i32_i4_e32 v39, v122, v46
	v_dot8c_i32_i4_e32 v40, v124, v48
	v_dot8c_i32_i4_e32 v41, v124, v46
	v_dot8c_i32_i4_e32 v42, v126, v48
	v_dot8c_i32_i4_e32 v43, v126, v46
	v_dot8c_i32_i4_e32 v44, v128, v48
	v_dot8c_i32_i4_e32 v45, v128, v46
	v_dot8c_i32_i4_e32 v38, v123, v49
	v_dot8c_i32_i4_e32 v39, v123, v47
	v_dot8c_i32_i4_e32 v40, v125, v49
	v_dot8c_i32_i4_e32 v41, v125, v47
	v_dot8c_i32_i4_e32 v42, v127, v49
	v_dot8c_i32_i4_e32 v43, v127, v47
	v_dot8c_i32_i4_e32 v44, v129, v49
	v_dot8c_i32_i4_e32 v45, v129, v47
	s_waitcnt lgkmcnt(15)
	v_add_u32_e32 v143, 8, v139
	v_and_b32_e32 v142, 15, v143
	v_xor_b32_e32 v142, 8, v142
	v_bfe_u32 v144, v143, 4, 4
	v_mul_lo_u32 v142, v142, s92
	v_mul_lo_u32 v144, v144, s92
	v_mov_b32_e32 v143, v142
	v_mov_b32_e32 v145, v144
	ds_write2st64_b64 v159, v[142:143], v[144:145] offset1:2
	v_and_b32_e32 v78, 0xffff, v20
	v_lshrrev_b32_e32 v79, 16, v20
	v_lshl_add_u32 v78, v78, 7, v152
	v_lshl_add_u32 v79, v79, 7, v153
	s_mov_b32 m0, s76
	s_add_i32 s43, s76, 0x400
	global_load_lds_dwordx4 v78, s[50:51]
	s_mov_b32 m0, s43
	s_nop 0
	global_load_lds_dwordx4 v79, s[50:51]
	s_waitcnt vmcnt(8)
	v_add_u32_e32 v54, s78, v59
	v_add_u32_e32 v55, s78, v60
	v_add_u32_e32 v56, s78, v61
	v_add_u32_e32 v57, s78, v62
	ds_read_b64_tr_b4 v[46:47], v160 offset:768
	ds_read_b64_tr_b4 v[48:49], v160 offset:1792
	ds_read_b64_tr_b4 v[122:123], v54
	ds_read_b64_tr_b4 v[124:125], v55
	ds_read_b64_tr_b4 v[126:127], v56
	ds_read_b64_tr_b4 v[128:129], v57
	s_waitcnt lgkmcnt(7)
	v_dot8c_i32_i4_e32 v38, v130, v52
	v_dot8c_i32_i4_e32 v39, v130, v50
	v_dot8c_i32_i4_e32 v40, v132, v52
	v_dot8c_i32_i4_e32 v41, v132, v50
	v_dot8c_i32_i4_e32 v42, v134, v52
	v_dot8c_i32_i4_e32 v43, v134, v50
	v_dot8c_i32_i4_e32 v44, v136, v52
	v_dot8c_i32_i4_e32 v45, v136, v50
	v_dot8c_i32_i4_e32 v38, v131, v53
	v_dot8c_i32_i4_e32 v39, v131, v51
	v_dot8c_i32_i4_e32 v40, v133, v53
	v_dot8c_i32_i4_e32 v41, v133, v51
	v_dot8c_i32_i4_e32 v42, v135, v53
	v_dot8c_i32_i4_e32 v43, v135, v51
	v_dot8c_i32_i4_e32 v44, v137, v53
	v_dot8c_i32_i4_e32 v45, v137, v51
	v_and_b32_e32 v78, 0xffff, v21
	v_lshrrev_b32_e32 v79, 16, v21
	v_lshl_add_u32 v78, v78, 7, v152
	v_lshl_add_u32 v79, v79, 7, v153
	s_mov_b32 m0, s77
	s_add_i32 s43, s77, 0x400
	global_load_lds_dwordx4 v78, s[50:51]
	s_mov_b32 m0, s43
	s_nop 0
	global_load_lds_dwordx4 v79, s[50:51]
	s_waitcnt vmcnt(8)
	v_add_u32_e32 v54, s79, v59
	v_add_u32_e32 v55, s79, v60
	v_add_u32_e32 v56, s79, v61
	v_add_u32_e32 v57, s79, v62
	ds_read_b64_tr_b4 v[50:51], v160 offset:896
	ds_read_b64_tr_b4 v[52:53], v160 offset:1920
	ds_read_b64_tr_b4 v[130:131], v54
	ds_read_b64_tr_b4 v[132:133], v55
	ds_read_b64_tr_b4 v[134:135], v56
	ds_read_b64_tr_b4 v[136:137], v57
	s_waitcnt lgkmcnt(6)
	v_dot8c_i32_i4_e32 v38, v122, v48
	v_dot8c_i32_i4_e32 v39, v122, v46
	v_dot8c_i32_i4_e32 v40, v124, v48
	v_dot8c_i32_i4_e32 v41, v124, v46
	v_dot8c_i32_i4_e32 v42, v126, v48
	v_dot8c_i32_i4_e32 v43, v126, v46
	v_dot8c_i32_i4_e32 v44, v128, v48
	v_dot8c_i32_i4_e32 v45, v128, v46
	v_dot8c_i32_i4_e32 v38, v123, v49
	v_dot8c_i32_i4_e32 v39, v123, v47
	v_dot8c_i32_i4_e32 v40, v125, v49
	v_dot8c_i32_i4_e32 v41, v125, v47
	v_dot8c_i32_i4_e32 v42, v127, v49
	v_dot8c_i32_i4_e32 v43, v127, v47
	v_dot8c_i32_i4_e32 v44, v129, v49
	v_dot8c_i32_i4_e32 v45, v129, v47
	v_and_b32_e32 v78, 0xffff, v22
	v_lshrrev_b32_e32 v79, 16, v22
	v_lshl_add_u32 v78, v78, 7, v152
	v_lshl_add_u32 v79, v79, 7, v153
	s_mov_b32 m0, s78
	s_add_i32 s43, s78, 0x400
	global_load_lds_dwordx4 v78, s[50:51]
	s_mov_b32 m0, s43
	s_nop 0
	global_load_lds_dwordx4 v79, s[50:51]
	s_waitcnt vmcnt(8)
	v_add_u32_e32 v54, s98, v59
	v_add_u32_e32 v55, s98, v60
	v_add_u32_e32 v56, s98, v61
	v_add_u32_e32 v57, s98, v62
	ds_read_b64_tr_b4 v[46:47], v160
	ds_read_b64_tr_b4 v[48:49], v160 offset:1024
	ds_read_b64_tr_b4 v[122:123], v54
	ds_read_b64_tr_b4 v[124:125], v55
	ds_read_b64_tr_b4 v[126:127], v56
	ds_read_b64_tr_b4 v[128:129], v57
	s_waitcnt lgkmcnt(6)
	v_dot8c_i32_i4_e32 v38, v130, v52
	v_dot8c_i32_i4_e32 v39, v130, v50
	v_dot8c_i32_i4_e32 v40, v132, v52
	v_dot8c_i32_i4_e32 v41, v132, v50
	v_dot8c_i32_i4_e32 v42, v134, v52
	v_dot8c_i32_i4_e32 v43, v134, v50
	v_dot8c_i32_i4_e32 v44, v136, v52
	v_dot8c_i32_i4_e32 v45, v136, v50
	v_dot8c_i32_i4_e32 v38, v131, v53
	v_dot8c_i32_i4_e32 v39, v131, v51
	v_dot8c_i32_i4_e32 v40, v133, v53
	v_dot8c_i32_i4_e32 v41, v133, v51
	v_dot8c_i32_i4_e32 v42, v135, v53
	v_dot8c_i32_i4_e32 v43, v135, v51
	v_dot8c_i32_i4_e32 v44, v137, v53
	v_dot8c_i32_i4_e32 v45, v137, v51
	s_nop 3
	s_waitcnt lgkmcnt(15)
; __device__ __forceinline__ void peer_v_tokens(int j, const LAS unsigned short* EL, const LAS unsigned char* AL  , const LAS float* ASC  , const LAS int* SAL  , ...
;     ...
; #pragma unroll 1
;     for (int it = 0; it < 8; ++it) {
;         const int tl = it * 8 + wave, t = j * 64 + tl;
;         unsigned E[8];
;         { const LAS v4u* ep = (const LAS v4u*)(EL + tl * 128 + 16 * g); const v4u e0 = ep[0], e1 = ep[1];
;           E[0] = e0.x; E[1] = e0.y; E[2] = e0.z; E[3] = e0.w; E[4] = e1.x; E[5] = e1.y; E[6] = e1.z; E[7] = e1.w; }
;         uint2 hv[4]; float4 gv[4];
;         { unsigned ho = (unsigned)t * (D / 4) + (unsigned)lane; asm volatile("" : "+v"(ho)); const uint2* hp = (const uint2*)HB + ho; const float4* gp = (const float4*)fng + lane;
; #pragma unroll
;           for (int jq = 0; jq < 4; ++jq) { hv[jq] = hp[64 * jq]; gv[jq] = gp[64 * jq]; } }
;         VDMA(0, 0); VDMA(1, 1);
; #pragma unroll
;         for (int m = 0; m < 2; ++m) {
;             const int idx = lane + 64 * m, tau = idx >> 4, sr = idx & 15, k = 16 * (sr & 7) + 2 * tau + (sr >> 3);
;             const int aq = (int)*(const LAS signed char*)(AL + tl * 128 + k); const int tq = aq + 8;
;             const unsigned lo = (((unsigned)tq & 15u) ^ 8u) * 0x11111111u, hi = ((unsigned)(tq >> 4) & 15u) * 0x11111111u;
;             typedef unsigned u2v __attribute__((ext_vector_type(2)));
;             u2v l2; l2.x = lo; l2.y = lo; u2v h2; h2.x = hi; h2.y = hi;
;             *(LAS u2v*)(ATL + 8 * idx) = l2; *(LAS u2v*)(ATL + 1024 + 8 * idx) = h2;
;         }
;         const float asc = ASC[tl]; const int sa = SAL[tl];
;         CFENCE();
;         int accH[4], accL[4];
; #pragma unroll
;         for (int st = 0; st < 16; ++st) {
;             const int p = st >> 2, q = st & 3;
;             if (st < 14) VDMA(st + 2, (st + 2) % 3);
;             if (st < 14) asm volatile("s_waitcnt vmcnt(8)" ::: "memory");
;             else if (st == 14) asm volatile("s_waitcnt vmcnt(4)" ::: "memory");
;             else asm volatile("s_waitcnt vmcnt(0)" ::: "memory");
;             if (q == 0) {
; #pragma unroll
;                 for (int r = 0; r < 4; ++r) { accH[r] = 0; accL[r] = 0; } }
; #pragma unroll
;             for (int tp = 0; tp < 2; ++tp) {
;                 const v2i ao = TR4(ATL + (2 * q + tp) * 128 + 8 * s16), ah = TR4(ATL + 1024 + (2 * q + tp) * 128 + 8 * s16);
; #pragma unroll
	v_lshlrev_b32_e32 v38, 5, v38
	v_lshlrev_b32_e32 v39, 1, v39
	v_add3_u32 v38, v39, v229, v38
	v_cvt_f32_i32_e32 v38, v38
	v_mul_f32_e32 v38, v228, v38
	v_lshlrev_b32_e32 v40, 5, v40
	v_lshlrev_b32_e32 v41, 1, v41
	v_add3_u32 v40, v41, v229, v40
	v_cvt_f32_i32_e32 v40, v40
	v_mul_f32_e32 v40, v228, v40
	v_lshlrev_b32_e32 v42, 5, v42
	v_lshlrev_b32_e32 v43, 1, v43
	v_add3_u32 v42, v43, v229, v42
	v_cvt_f32_i32_e32 v42, v42
	v_mul_f32_e32 v42, v228, v42
	v_lshlrev_b32_e32 v44, 5, v44
	v_lshlrev_b32_e32 v45, 1, v45
	v_add3_u32 v44, v45, v229, v44
	v_cvt_f32_i32_e32 v44, v44
	v_mul_f32_e32 v44, v228, v44
	v_cvt_pk_bf16_f32 v186, v38, v40
	v_cvt_pk_bf16_f32 v187, v42, v44
	ds_read_b128 v[252:255], v155
	s_add_i32 s44, s40, 32
	s_ashr_i32 s45, s44, 31
	s_lshl_b64 s[44:45], s[44:45], 12
	v_lshl_add_u64 v[80:81], v[36:37], 0, s[44:45]
	s_waitcnt lgkmcnt(0)
	v_mul_f32_e32 v210, v210, v252
	v_mul_f32_e32 v211, v211, v253
	v_mul_f32_e32 v212, v212, v254
	v_mul_f32_e32 v213, v213, v255
	global_store_dwordx4 v[80:81], v[210:213], off nt
	s_add_i32 s43, s40, 40
	s_lshl_b32 s43, s43, 11
	v_add_u32_e32 v138, s43, v66
	global_load_dwordx2 v[194:195], v138, s[70:71]
	global_load_dwordx2 v[196:197], v138, s[70:71] offset:512
	global_load_dwordx2 v[198:199], v138, s[70:71] offset:1024
	global_load_dwordx2 v[200:201], v138, s[70:71] offset:1536
	v_add_u32_e32 v147, 8, v140
	v_and_b32_e32 v146, 15, v147
	v_xor_b32_e32 v146, 8, v146
	v_bfe_u32 v148, v147, 4, 4
	v_mul_lo_u32 v146, v146, s92
	v_mul_lo_u32 v148, v148, s92
	v_mov_b32_e32 v147, v146
	v_mov_b32_e32 v149, v148
	ds_write2st64_b64 v77, v[146:147], v[148:149] offset1:2
	v_add_u32_e32 v138, 0x1c00, v74
	ds_read_u8 v139, v138
	v_add_u32_e32 v141, 0x1c00, v73
	ds_read_u8 v140, v141
	s_add_i32 s43, s67, 192
	v_mov_b32_e32 v138, s43
	ds_read2st64_b32 v[228:229], v138 offset1:1
	ds_read_b128 v[26:29], v227 offset:14336
	ds_read_b128 v[30:33], v227 offset:14352
	v_mov_b32_e32 v38, 0
	v_mov_b32_e32 v39, 0
	v_mov_b32_e32 v40, 0
	v_mov_b32_e32 v41, 0
	v_mov_b32_e32 v42, 0
	v_mov_b32_e32 v43, 0
	v_mov_b32_e32 v44, 0
	v_mov_b32_e32 v45, 0
	v_and_b32_e32 v78, 0xffff, v23
	v_lshrrev_b32_e32 v79, 16, v23
	v_lshl_add_u32 v78, v78, 7, v152
	v_lshl_add_u32 v79, v79, 7, v153
	s_mov_b32 m0, s79
	s_add_i32 s43, s79, 0x400
	global_load_lds_dwordx4 v78, s[50:51]
	s_mov_b32 m0, s43
	s_nop 0
	global_load_lds_dwordx4 v79, s[50:51]
	s_waitcnt vmcnt(13)
	v_add_u32_e32 v54, s99, v59
	v_add_u32_e32 v55, s99, v60
	v_add_u32_e32 v56, s99, v61
	v_add_u32_e32 v57, s99, v62
	ds_read_b64_tr_b4 v[50:51], v160 offset:128
	ds_read_b64_tr_b4 v[52:53], v160 offset:1152
	ds_read_b64_tr_b4 v[130:131], v54
	ds_read_b64_tr_b4 v[132:133], v55
	ds_read_b64_tr_b4 v[134:135], v56
	ds_read_b64_tr_b4 v[136:137], v57
	s_waitcnt lgkmcnt(13)
	v_dot8c_i32_i4_e32 v38, v122, v48
	v_dot8c_i32_i4_e32 v39, v122, v46
	v_dot8c_i32_i4_e32 v40, v124, v48
	v_dot8c_i32_i4_e32 v41, v124, v46
	v_dot8c_i32_i4_e32 v42, v126, v48
	v_dot8c_i32_i4_e32 v43, v126, v46
	v_dot8c_i32_i4_e32 v44, v128, v48
	v_dot8c_i32_i4_e32 v45, v128, v46
	v_dot8c_i32_i4_e32 v38, v123, v49
	v_dot8c_i32_i4_e32 v39, v123, v47
	v_dot8c_i32_i4_e32 v40, v125, v49
	v_dot8c_i32_i4_e32 v41, v125, v47
	v_dot8c_i32_i4_e32 v42, v127, v49
	v_dot8c_i32_i4_e32 v43, v127, v47
	v_dot8c_i32_i4_e32 v44, v129, v49
	v_dot8c_i32_i4_e32 v45, v129, v47
	v_and_b32_e32 v78, 0xffff, v24
	v_lshrrev_b32_e32 v79, 16, v24
	v_lshl_add_u32 v78, v78, 7, v152
	v_lshl_add_u32 v79, v79, 7, v153
	s_mov_b32 m0, s98
	s_add_i32 s43, s98, 0x400
	global_load_lds_dwordx4 v78, s[50:51]
	s_mov_b32 m0, s43
	s_nop 0
	global_load_lds_dwordx4 v79, s[50:51]
	s_waitcnt vmcnt(13)
	v_add_u32_e32 v54, s76, v59
	v_add_u32_e32 v55, s76, v60
	v_add_u32_e32 v56, s76, v61
	v_add_u32_e32 v57, s76, v62
	ds_read_b64_tr_b4 v[46:47], v160 offset:256
	ds_read_b64_tr_b4 v[48:49], v160 offset:1280
	ds_read_b64_tr_b4 v[122:123], v54
	ds_read_b64_tr_b4 v[124:125], v55
	ds_read_b64_tr_b4 v[126:127], v56
	ds_read_b64_tr_b4 v[128:129], v57
	s_waitcnt lgkmcnt(6)
	v_dot8c_i32_i4_e32 v38, v130, v52
	v_dot8c_i32_i4_e32 v39, v130, v50
	v_dot8c_i32_i4_e32 v40, v132, v52
	v_dot8c_i32_i4_e32 v41, v132, v50
	v_dot8c_i32_i4_e32 v42, v134, v52
	v_dot8c_i32_i4_e32 v43, v134, v50
	v_dot8c_i32_i4_e32 v44, v136, v52
	v_dot8c_i32_i4_e32 v45, v136, v50
	v_dot8c_i32_i4_e32 v38, v131, v53
	v_dot8c_i32_i4_e32 v39, v131, v51
	v_dot8c_i32_i4_e32 v40, v133, v53
	v_dot8c_i32_i4_e32 v41, v133, v51
	v_dot8c_i32_i4_e32 v42, v135, v53
	v_dot8c_i32_i4_e32 v43, v135, v51
	v_dot8c_i32_i4_e32 v44, v137, v53
	v_dot8c_i32_i4_e32 v45, v137, v51
	v_and_b32_e32 v78, 0xffff, v25
	v_lshrrev_b32_e32 v79, 16, v25
	v_lshl_add_u32 v78, v78, 7, v152
	v_lshl_add_u32 v79, v79, 7, v153
	s_mov_b32 m0, s99
	s_add_i32 s43, s99, 0x400
	global_load_lds_dwordx4 v78, s[50:51]
	s_mov_b32 m0, s43
	s_nop 0
	global_load_lds_dwordx4 v79, s[50:51]
	s_waitcnt vmcnt(13)
	v_add_u32_e32 v54, s77, v59
	v_add_u32_e32 v55, s77, v60
	v_add_u32_e32 v56, s77, v61
	v_add_u32_e32 v57, s77, v62
	ds_read_b64_tr_b4 v[50:51], v160 offset:384
	ds_read_b64_tr_b4 v[52:53], v160 offset:1408
	ds_read_b64_tr_b4 v[130:131], v54
	ds_read_b64_tr_b4 v[132:133], v55
	ds_read_b64_tr_b4 v[134:135], v56
	ds_read_b64_tr_b4 v[136:137], v57
	s_waitcnt lgkmcnt(6)
	v_dot8c_i32_i4_e32 v38, v122, v48
	v_dot8c_i32_i4_e32 v39, v122, v46
	v_dot8c_i32_i4_e32 v40, v124, v48
	v_dot8c_i32_i4_e32 v41, v124, v46
	v_dot8c_i32_i4_e32 v42, v126, v48
	v_dot8c_i32_i4_e32 v43, v126, v46
	v_dot8c_i32_i4_e32 v44, v128, v48
	v_dot8c_i32_i4_e32 v45, v128, v46
	v_dot8c_i32_i4_e32 v38, v123, v49
	v_dot8c_i32_i4_e32 v39, v123, v47
	v_dot8c_i32_i4_e32 v40, v125, v49
	v_dot8c_i32_i4_e32 v41, v125, v47
	v_dot8c_i32_i4_e32 v42, v127, v49
	v_dot8c_i32_i4_e32 v43, v127, v47
	v_dot8c_i32_i4_e32 v44, v129, v49
	v_dot8c_i32_i4_e32 v45, v129, v47
	s_waitcnt lgkmcnt(15)
; __device__ __forceinline__ void peer_v_tokens(int j, const LAS unsigned short* EL, const LAS unsigned char* AL  , const LAS float* ASC  , const LAS int* SAL  , ...
;     ...
; #pragma unroll 1
;     for (int it = 0; it < 8; ++it) {
;         const int tl = it * 8 + wave, t = j * 64 + tl;
;         unsigned E[8];
;         { const LAS v4u* ep = (const LAS v4u*)(EL + tl * 128 + 16 * g); const v4u e0 = ep[0], e1 = ep[1];
;           E[0] = e0.x; E[1] = e0.y; E[2] = e0.z; E[3] = e0.w; E[4] = e1.x; E[5] = e1.y; E[6] = e1.z; E[7] = e1.w; }
;         uint2 hv[4]; float4 gv[4];
;         { unsigned ho = (unsigned)t * (D / 4) + (unsigned)lane; asm volatile("" : "+v"(ho)); const uint2* hp = (const uint2*)HB + ho; const float4* gp = (const float4*)fng + lane;
; #pragma unroll
;           for (int jq = 0; jq < 4; ++jq) { hv[jq] = hp[64 * jq]; gv[jq] = gp[64 * jq]; } }
;         VDMA(0, 0); VDMA(1, 1);
; #pragma unroll
;         for (int m = 0; m < 2; ++m) {
;             const int idx = lane + 64 * m, tau = idx >> 4, sr = idx & 15, k = 16 * (sr & 7) + 2 * tau + (sr >> 3);
;             const int aq = (int)*(const LAS signed char*)(AL + tl * 128 + k); const int tq = aq + 8;
;             const unsigned lo = (((unsigned)tq & 15u) ^ 8u) * 0x11111111u, hi = ((unsigned)(tq >> 4) & 15u) * 0x11111111u;
;             typedef unsigned u2v __attribute__((ext_vector_type(2)));
;             u2v l2; l2.x = lo; l2.y = lo; u2v h2; h2.x = hi; h2.y = hi;
;             *(LAS u2v*)(ATL + 8 * idx) = l2; *(LAS u2v*)(ATL + 1024 + 8 * idx) = h2;
;         }
;         const float asc = ASC[tl]; const int sa = SAL[tl];
;         CFENCE();
;         int accH[4], accL[4];
; #pragma unroll
;         for (int st = 0; st < 16; ++st) {
;             const int p = st >> 2, q = st & 3;
;             if (st < 14) VDMA(st + 2, (st + 2) % 3);
;             if (st < 14) asm volatile("s_waitcnt vmcnt(8)" ::: "memory");
;             else if (st == 14) asm volatile("s_waitcnt vmcnt(4)" ::: "memory");
;             else asm volatile("s_waitcnt vmcnt(0)" ::: "memory");
;             if (q == 0) {
; #pragma unroll
;                 for (int r = 0; r < 4; ++r) { accH[r] = 0; accL[r] = 0; } }
; #pragma unroll
;             for (int tp = 0; tp < 2; ++tp) {
;                 const v2i ao = TR4(ATL + (2 * q + tp) * 128 + 8 * s16), ah = TR4(ATL + 1024 + (2 * q + tp) * 128 + 8 * s16);
; #pragma unroll
	v_and_b32_e32 v78, 0xffff, v26
	v_lshrrev_b32_e32 v79, 16, v26
	v_lshl_add_u32 v78, v78, 7, v152
	v_lshl_add_u32 v79, v79, 7, v153
	s_mov_b32 m0, s76
	s_add_i32 s43, s76, 0x400
	global_load_lds_dwordx4 v78, s[50:51]
	s_mov_b32 m0, s43
	s_nop 0
	global_load_lds_dwordx4 v79, s[50:51]
	s_waitcnt vmcnt(13)
	v_add_u32_e32 v54, s78, v59
	v_add_u32_e32 v55, s78, v60
	v_add_u32_e32 v56, s78, v61
	v_add_u32_e32 v57, s78, v62
	ds_read_b64_tr_b4 v[46:47], v160 offset:512
	ds_read_b64_tr_b4 v[48:49], v160 offset:1536
	ds_read_b64_tr_b4 v[122:123], v54
	ds_read_b64_tr_b4 v[124:125], v55
	ds_read_b64_tr_b4 v[126:127], v56
	ds_read_b64_tr_b4 v[128:129], v57
	s_waitcnt lgkmcnt(6)
	v_dot8c_i32_i4_e32 v38, v130, v52
	v_dot8c_i32_i4_e32 v39, v130, v50
	v_dot8c_i32_i4_e32 v40, v132, v52
	v_dot8c_i32_i4_e32 v41, v132, v50
	v_dot8c_i32_i4_e32 v42, v134, v52
	v_dot8c_i32_i4_e32 v43, v134, v50
	v_dot8c_i32_i4_e32 v44, v136, v52
	v_dot8c_i32_i4_e32 v45, v136, v50
	v_dot8c_i32_i4_e32 v38, v131, v53
	v_dot8c_i32_i4_e32 v39, v131, v51
	v_dot8c_i32_i4_e32 v40, v133, v53
	v_dot8c_i32_i4_e32 v41, v133, v51
	v_dot8c_i32_i4_e32 v42, v135, v53
	v_dot8c_i32_i4_e32 v43, v135, v51
	v_dot8c_i32_i4_e32 v44, v137, v53
	v_dot8c_i32_i4_e32 v45, v137, v51
	v_and_b32_e32 v78, 0xffff, v27
	v_lshrrev_b32_e32 v79, 16, v27
	v_lshl_add_u32 v78, v78, 7, v152
	v_lshl_add_u32 v79, v79, 7, v153
	s_mov_b32 m0, s77
	s_add_i32 s43, s77, 0x400
	global_load_lds_dwordx4 v78, s[50:51]
	s_mov_b32 m0, s43
	s_nop 0
	global_load_lds_dwordx4 v79, s[50:51]
	s_waitcnt vmcnt(8)
	v_add_u32_e32 v54, s79, v59
	v_add_u32_e32 v55, s79, v60
	v_add_u32_e32 v56, s79, v61
	v_add_u32_e32 v57, s79, v62
	ds_read_b64_tr_b4 v[50:51], v160 offset:640
	ds_read_b64_tr_b4 v[52:53], v160 offset:1664
	ds_read_b64_tr_b4 v[130:131], v54
	ds_read_b64_tr_b4 v[132:133], v55
	ds_read_b64_tr_b4 v[134:135], v56
	ds_read_b64_tr_b4 v[136:137], v57
	s_waitcnt lgkmcnt(6)
	v_dot8c_i32_i4_e32 v38, v122, v48
	v_dot8c_i32_i4_e32 v39, v122, v46
	v_dot8c_i32_i4_e32 v40, v124, v48
	v_dot8c_i32_i4_e32 v41, v124, v46
	v_dot8c_i32_i4_e32 v42, v126, v48
	v_dot8c_i32_i4_e32 v43, v126, v46
	v_dot8c_i32_i4_e32 v44, v128, v48
	v_dot8c_i32_i4_e32 v45, v128, v46
	v_dot8c_i32_i4_e32 v38, v123, v49
	v_dot8c_i32_i4_e32 v39, v123, v47
	v_dot8c_i32_i4_e32 v40, v125, v49
	v_dot8c_i32_i4_e32 v41, v125, v47
	v_dot8c_i32_i4_e32 v42, v127, v49
	v_dot8c_i32_i4_e32 v43, v127, v47
	v_dot8c_i32_i4_e32 v44, v129, v49
	v_dot8c_i32_i4_e32 v45, v129, v47
	s_waitcnt lgkmcnt(15)
	v_add_u32_e32 v143, 8, v139
	v_and_b32_e32 v142, 15, v143
	v_xor_b32_e32 v142, 8, v142
	v_bfe_u32 v144, v143, 4, 4
	v_mul_lo_u32 v142, v142, s92
	v_mul_lo_u32 v144, v144, s92
	v_mov_b32_e32 v143, v142
	v_mov_b32_e32 v145, v144
	ds_write2st64_b64 v159, v[142:143], v[144:145] offset1:2
	v_and_b32_e32 v78, 0xffff, v28
	v_lshrrev_b32_e32 v79, 16, v28
	v_lshl_add_u32 v78, v78, 7, v152
	v_lshl_add_u32 v79, v79, 7, v153
	s_mov_b32 m0, s78
	s_add_i32 s43, s78, 0x400
	global_load_lds_dwordx4 v78, s[50:51]
	s_mov_b32 m0, s43
	s_nop 0
	global_load_lds_dwordx4 v79, s[50:51]
	s_waitcnt vmcnt(8)
	v_add_u32_e32 v54, s98, v59
	v_add_u32_e32 v55, s98, v60
	v_add_u32_e32 v56, s98, v61
	v_add_u32_e32 v57, s98, v62
	ds_read_b64_tr_b4 v[46:47], v160 offset:768
	ds_read_b64_tr_b4 v[48:49], v160 offset:1792
	ds_read_b64_tr_b4 v[122:123], v54
	ds_read_b64_tr_b4 v[124:125], v55
	ds_read_b64_tr_b4 v[126:127], v56
	ds_read_b64_tr_b4 v[128:129], v57
	s_waitcnt lgkmcnt(7)
	v_dot8c_i32_i4_e32 v38, v130, v52
	v_dot8c_i32_i4_e32 v39, v130, v50
	v_dot8c_i32_i4_e32 v40, v132, v52
	v_dot8c_i32_i4_e32 v41, v132, v50
	v_dot8c_i32_i4_e32 v42, v134, v52
	v_dot8c_i32_i4_e32 v43, v134, v50
	v_dot8c_i32_i4_e32 v44, v136, v52
	v_dot8c_i32_i4_e32 v45, v136, v50
	v_dot8c_i32_i4_e32 v38, v131, v53
	v_dot8c_i32_i4_e32 v39, v131, v51
	v_dot8c_i32_i4_e32 v40, v133, v53
	v_dot8c_i32_i4_e32 v41, v133, v51
	v_dot8c_i32_i4_e32 v42, v135, v53
	v_dot8c_i32_i4_e32 v43, v135, v51
	v_dot8c_i32_i4_e32 v44, v137, v53
	v_dot8c_i32_i4_e32 v45, v137, v51
	v_and_b32_e32 v78, 0xffff, v29
	v_lshrrev_b32_e32 v79, 16, v29
	v_lshl_add_u32 v78, v78, 7, v152
	v_lshl_add_u32 v79, v79, 7, v153
	s_mov_b32 m0, s79
	s_add_i32 s43, s79, 0x400
	global_load_lds_dwordx4 v78, s[50:51]
	s_mov_b32 m0, s43
	s_nop 0
	global_load_lds_dwordx4 v79, s[50:51]
	s_waitcnt vmcnt(8)
	v_add_u32_e32 v54, s99, v59
	v_add_u32_e32 v55, s99, v60
	v_add_u32_e32 v56, s99, v61
	v_add_u32_e32 v57, s99, v62
	ds_read_b64_tr_b4 v[50:51], v160 offset:896
	ds_read_b64_tr_b4 v[52:53], v160 offset:1920
	ds_read_b64_tr_b4 v[130:131], v54
	ds_read_b64_tr_b4 v[132:133], v55
	ds_read_b64_tr_b4 v[134:135], v56
	ds_read_b64_tr_b4 v[136:137], v57
	s_waitcnt lgkmcnt(6)
	v_dot8c_i32_i4_e32 v38, v122, v48
	v_dot8c_i32_i4_e32 v39, v122, v46
	v_dot8c_i32_i4_e32 v40, v124, v48
	v_dot8c_i32_i4_e32 v41, v124, v46
	v_dot8c_i32_i4_e32 v42, v126, v48
	v_dot8c_i32_i4_e32 v43, v126, v46
	v_dot8c_i32_i4_e32 v44, v128, v48
	v_dot8c_i32_i4_e32 v45, v128, v46
	v_dot8c_i32_i4_e32 v38, v123, v49
	v_dot8c_i32_i4_e32 v39, v123, v47
	v_dot8c_i32_i4_e32 v40, v125, v49
	v_dot8c_i32_i4_e32 v41, v125, v47
	v_dot8c_i32_i4_e32 v42, v127, v49
	v_dot8c_i32_i4_e32 v43, v127, v47
	v_dot8c_i32_i4_e32 v44, v129, v49
	v_dot8c_i32_i4_e32 v45, v129, v47
	v_and_b32_e32 v78, 0xffff, v30
	v_lshrrev_b32_e32 v79, 16, v30
	v_lshl_add_u32 v78, v78, 7, v152
	v_lshl_add_u32 v79, v79, 7, v153
	s_mov_b32 m0, s98
	s_add_i32 s43, s98, 0x400
	global_load_lds_dwordx4 v78, s[50:51]
	s_mov_b32 m0, s43
	s_nop 0
	global_load_lds_dwordx4 v79, s[50:51]
	s_waitcnt vmcnt(8)
; __device__ __forceinline__ void peer_v_tokens(int j, const LAS unsigned short* EL, const LAS unsigned char* AL  , const LAS float* ASC  , const LAS int* SAL  , ...
;     ...
;             const int idx = lane + 64 * m, tau = idx >> 4, sr = idx & 15, k = 16 * (sr & 7) + 2 * tau + (sr >> 3);
;             const int aq = (int)*(const LAS signed char*)(AL + tl * 128 + k); const int tq = aq + 8;
;             const unsigned lo = (((unsigned)tq & 15u) ^ 8u) * 0x11111111u, hi = ((unsigned)(tq >> 4) & 15u) * 0x11111111u;
;             typedef unsigned u2v __attribute__((ext_vector_type(2)));
;             u2v l2; l2.x = lo; l2.y = lo; u2v h2; h2.x = hi; h2.y = hi;
;             *(LAS u2v*)(ATL + 8 * idx) = l2; *(LAS u2v*)(ATL + 1024 + 8 * idx) = h2;
;         }
;         const float asc = ASC[tl]; const int sa = SAL[tl];
;         CFENCE();
;         int accH[4], accL[4];
; #pragma unroll
;         for (int st = 0; st < 16; ++st) {
;             const int p = st >> 2, q = st & 3;
;             if (st < 14) VDMA(st + 2, (st + 2) % 3);
;             if (st < 14) asm volatile("s_waitcnt vmcnt(8)" ::: "memory");
;             else if (st == 14) asm volatile("s_waitcnt vmcnt(4)" ::: "memory");
;             else asm volatile("s_waitcnt vmcnt(0)" ::: "memory");
;             if (q == 0) {
; #pragma unroll
;                 for (int r = 0; r < 4; ++r) { accH[r] = 0; accL[r] = 0; } }
; #pragma unroll
;             for (int tp = 0; tp < 2; ++tp) {
;                 const v2i ao = TR4(ATL + (2 * q + tp) * 128 + 8 * s16), ah = TR4(ATL + 1024 + (2 * q + tp) * 128 + 8 * s16);
; #pragma unroll
;                 for (int r = 0; r < 4; ++r) {
;                     const v2i d = TR4(ldsb + BUF[st % 3] + 2048 * tp + roff[r]);
;                     accH[r] = __builtin_amdgcn_sdot8(d.x, ah.x, accH[r], false); accH[r] = __builtin_amdgcn_sdot8(d.y, ah.y, accH[r], false);
;                     accL[r] = __builtin_amdgcn_sdot8(d.x, ao.x, accL[r], false); accL[r] = __builtin_amdgcn_sdot8(d.y, ao.y, accL[r], false);
;                 }
;             }
;             asm volatile("s_waitcnt lgkmcnt(0)" ::: "memory");
;             if (q == 3) {
; #pragma unroll
;                 for (int r = 0; r < 4; ++r) STASH[256 * p + 16 * (grp + 4 * r) + pc] = f2bf(asc * (float)(2 * ((accH[r] << 4) + accL[r]) + sa));
;             }
;         }
;         CFENCE();
;         {
	v_add_u32_e32 v54, s76, v59
	v_add_u32_e32 v55, s76, v60
	v_add_u32_e32 v56, s76, v61
	v_add_u32_e32 v57, s76, v62
	ds_read_b64_tr_b4 v[46:47], v160
	ds_read_b64_tr_b4 v[48:49], v160 offset:1024
	ds_read_b64_tr_b4 v[122:123], v54
	ds_read_b64_tr_b4 v[124:125], v55
	ds_read_b64_tr_b4 v[126:127], v56
	ds_read_b64_tr_b4 v[128:129], v57
	s_waitcnt lgkmcnt(6)
	v_dot8c_i32_i4_e32 v38, v130, v52
	v_dot8c_i32_i4_e32 v39, v130, v50
	v_dot8c_i32_i4_e32 v40, v132, v52
	v_dot8c_i32_i4_e32 v41, v132, v50
	v_dot8c_i32_i4_e32 v42, v134, v52
	v_dot8c_i32_i4_e32 v43, v134, v50
	v_dot8c_i32_i4_e32 v44, v136, v52
	v_dot8c_i32_i4_e32 v45, v136, v50
	v_dot8c_i32_i4_e32 v38, v131, v53
	v_dot8c_i32_i4_e32 v39, v131, v51
	v_dot8c_i32_i4_e32 v40, v133, v53
	v_dot8c_i32_i4_e32 v41, v133, v51
	v_dot8c_i32_i4_e32 v42, v135, v53
	v_dot8c_i32_i4_e32 v43, v135, v51
	v_dot8c_i32_i4_e32 v44, v137, v53
	v_dot8c_i32_i4_e32 v45, v137, v51
	s_nop 3
	s_waitcnt lgkmcnt(15)
	v_lshlrev_b32_e32 v38, 5, v38
	v_lshlrev_b32_e32 v39, 1, v39
	v_add3_u32 v38, v39, v229, v38
	v_cvt_f32_i32_e32 v38, v38
	v_mul_f32_e32 v38, v228, v38
	v_lshlrev_b32_e32 v40, 5, v40
	v_lshlrev_b32_e32 v41, 1, v41
	v_add3_u32 v40, v41, v229, v40
	v_cvt_f32_i32_e32 v40, v40
	v_mul_f32_e32 v40, v228, v40
	v_lshlrev_b32_e32 v42, 5, v42
	v_lshlrev_b32_e32 v43, 1, v43
	v_add3_u32 v42, v43, v229, v42
	v_cvt_f32_i32_e32 v42, v42
	v_mul_f32_e32 v42, v228, v42
	v_lshlrev_b32_e32 v44, 5, v44
	v_lshlrev_b32_e32 v45, 1, v45
	v_add3_u32 v44, v45, v229, v44
	v_cvt_f32_i32_e32 v44, v44
	v_mul_f32_e32 v44, v228, v44
	v_cvt_pk_bf16_f32 v180, v38, v40
	v_cvt_pk_bf16_f32 v181, v42, v44
	ds_read_b128 v[252:255], v155 offset:1024
	s_add_i32 s44, s40, 32
	s_ashr_i32 s45, s44, 31
	s_lshl_b64 s[44:45], s[44:45], 12
	v_lshl_add_u64 v[80:81], v[36:37], 0, s[44:45]
	s_waitcnt lgkmcnt(0)
	v_mul_f32_e32 v214, v214, v252
	v_mul_f32_e32 v215, v215, v253
	v_mul_f32_e32 v216, v216, v254
	v_mul_f32_e32 v217, v217, v255
	global_store_dwordx4 v[80:81], v[214:217], off offset:1024 nt
	v_add_u32_e32 v147, 8, v140
	v_and_b32_e32 v146, 15, v147
	v_xor_b32_e32 v146, 8, v146
	v_bfe_u32 v148, v147, 4, 4
	v_mul_lo_u32 v146, v146, s92
	v_mul_lo_u32 v148, v148, s92
	v_mov_b32_e32 v147, v146
	v_mov_b32_e32 v149, v148
	ds_write2st64_b64 v77, v[146:147], v[148:149] offset1:2
	v_add_u32_e32 v138, 0x1800, v74
	ds_read_u8 v139, v138
	v_add_u32_e32 v141, 0x1800, v73
	ds_read_u8 v140, v141
	s_add_i32 s43, s67, 224
	v_mov_b32_e32 v138, s43
	ds_read2st64_b32 v[228:229], v138 offset1:1
	ds_read_b128 v[18:21], v227 offset:12288
	ds_read_b128 v[22:25], v227 offset:12304
	v_add_u32_e32 v150, 0x400000, v63
	v_add_u32_e32 v151, 0x400000, v64
	v_mov_b32_e32 v38, 0
	v_mov_b32_e32 v39, 0
	v_mov_b32_e32 v40, 0
	v_mov_b32_e32 v41, 0
	v_mov_b32_e32 v42, 0
	v_mov_b32_e32 v43, 0
	v_mov_b32_e32 v44, 0
	v_mov_b32_e32 v45, 0
	v_and_b32_e32 v78, 0xffff, v31
	v_lshrrev_b32_e32 v79, 16, v31
	v_lshl_add_u32 v78, v78, 7, v152
	v_lshl_add_u32 v79, v79, 7, v153
	s_mov_b32 m0, s99
	s_add_i32 s43, s99, 0x400
	global_load_lds_dwordx4 v78, s[50:51]
	s_mov_b32 m0, s43
	s_nop 0
	global_load_lds_dwordx4 v79, s[50:51]
	s_waitcnt vmcnt(9)
	v_add_u32_e32 v54, s77, v59
	v_add_u32_e32 v55, s77, v60
	v_add_u32_e32 v56, s77, v61
	v_add_u32_e32 v57, s77, v62
	ds_read_b64_tr_b4 v[50:51], v160 offset:128
	ds_read_b64_tr_b4 v[52:53], v160 offset:1152
	ds_read_b64_tr_b4 v[130:131], v54
	ds_read_b64_tr_b4 v[132:133], v55
	ds_read_b64_tr_b4 v[134:135], v56
	ds_read_b64_tr_b4 v[136:137], v57
	s_waitcnt lgkmcnt(13)
	v_dot8c_i32_i4_e32 v38, v122, v48
	v_dot8c_i32_i4_e32 v39, v122, v46
	v_dot8c_i32_i4_e32 v40, v124, v48
	v_dot8c_i32_i4_e32 v41, v124, v46
	v_dot8c_i32_i4_e32 v42, v126, v48
	v_dot8c_i32_i4_e32 v43, v126, v46
	v_dot8c_i32_i4_e32 v44, v128, v48
	v_dot8c_i32_i4_e32 v45, v128, v46
	v_dot8c_i32_i4_e32 v38, v123, v49
	v_dot8c_i32_i4_e32 v39, v123, v47
	v_dot8c_i32_i4_e32 v40, v125, v49
	v_dot8c_i32_i4_e32 v41, v125, v47
	v_dot8c_i32_i4_e32 v42, v127, v49
	v_dot8c_i32_i4_e32 v43, v127, v47
	v_dot8c_i32_i4_e32 v44, v129, v49
	v_dot8c_i32_i4_e32 v45, v129, v47
	v_and_b32_e32 v78, 0xffff, v32
	v_lshrrev_b32_e32 v79, 16, v32
	v_lshl_add_u32 v78, v78, 7, v152
	v_lshl_add_u32 v79, v79, 7, v153
	s_mov_b32 m0, s76
	s_add_i32 s43, s76, 0x400
	global_load_lds_dwordx4 v78, s[50:51]
	s_mov_b32 m0, s43
	s_nop 0
	global_load_lds_dwordx4 v79, s[50:51]
	s_waitcnt vmcnt(9)
	v_add_u32_e32 v54, s78, v59
	v_add_u32_e32 v55, s78, v60
	v_add_u32_e32 v56, s78, v61
	v_add_u32_e32 v57, s78, v62
	ds_read_b64_tr_b4 v[46:47], v160 offset:256
	ds_read_b64_tr_b4 v[48:49], v160 offset:1280
	ds_read_b64_tr_b4 v[122:123], v54
	ds_read_b64_tr_b4 v[124:125], v55
	ds_read_b64_tr_b4 v[126:127], v56
	ds_read_b64_tr_b4 v[128:129], v57
	s_waitcnt lgkmcnt(6)
	v_dot8c_i32_i4_e32 v38, v130, v52
	v_dot8c_i32_i4_e32 v39, v130, v50
	v_dot8c_i32_i4_e32 v40, v132, v52
	v_dot8c_i32_i4_e32 v41, v132, v50
	v_dot8c_i32_i4_e32 v42, v134, v52
	v_dot8c_i32_i4_e32 v43, v134, v50
	v_dot8c_i32_i4_e32 v44, v136, v52
	v_dot8c_i32_i4_e32 v45, v136, v50
	v_dot8c_i32_i4_e32 v38, v131, v53
	v_dot8c_i32_i4_e32 v39, v131, v51
	v_dot8c_i32_i4_e32 v40, v133, v53
	v_dot8c_i32_i4_e32 v41, v133, v51
	v_dot8c_i32_i4_e32 v42, v135, v53
	v_dot8c_i32_i4_e32 v43, v135, v51
	v_dot8c_i32_i4_e32 v44, v137, v53
	v_dot8c_i32_i4_e32 v45, v137, v51
	ds_write_b16 v65, v170
	ds_write_b16_d16_hi v65, v170 offset:128
	ds_write_b16 v65, v171 offset:256
	ds_write_b16_d16_hi v65, v171 offset:384
	ds_write_b16 v65, v172 offset:512
	ds_write_b16_d16_hi v65, v172 offset:640
	ds_write_b16 v65, v173 offset:768
	ds_write_b16_d16_hi v65, v173 offset:896
	ds_write_b16 v65, v174 offset:1024
	ds_write_b16_d16_hi v65, v174 offset:1152
	ds_write_b16 v65, v175 offset:1280
	ds_write_b16_d16_hi v65, v175 offset:1408
	ds_write_b16 v65, v176 offset:1536
	ds_write_b16_d16_hi v65, v176 offset:1664
	ds_write_b16 v65, v177 offset:1792
	ds_write_b16_d16_hi v65, v177 offset:1920
	ds_read_b64 v[202:203], v154
	ds_read_b64 v[204:205], v154 offset:512
	ds_read_b64 v[206:207], v154 offset:1024
	ds_read_b64 v[208:209], v154 offset:1536
	v_and_b32_e32 v78, 0xffff, v33
	v_lshrrev_b32_e32 v79, 16, v33
	v_lshl_add_u32 v78, v78, 7, v152
	v_lshl_add_u32 v79, v79, 7, v153
	s_mov_b32 m0, s77
	s_add_i32 s43, s77, 0x400
	global_load_lds_dwordx4 v78, s[50:51]
	s_mov_b32 m0, s43
	s_nop 0
	global_load_lds_dwordx4 v79, s[50:51]
	s_waitcnt vmcnt(9)
; #define LAS __attribute__((address_space(3)))
; #define TR4(p_) __builtin_amdgcn_ds_read_tr4_b64_v2i32((LAS v2i*)(p_))
; #define CFENCE() asm volatile("" ::: "memory")
; __device__ __forceinline__ void peer_v_tokens(int j, const LAS unsigned short* EL, const LAS unsigned char* AL  , const LAS float* ASC  , const LAS int* SAL  , ...
;     ...
;             const int idx = lane + 64 * m, tau = idx >> 4, sr = idx & 15, k = 16 * (sr & 7) + 2 * tau + (sr >> 3);
;             const int aq = (int)*(const LAS signed char*)(AL + tl * 128 + k); const int tq = aq + 8;
;             const unsigned lo = (((unsigned)tq & 15u) ^ 8u) * 0x11111111u, hi = ((unsigned)(tq >> 4) & 15u) * 0x11111111u;
;             typedef unsigned u2v __attribute__((ext_vector_type(2)));
;             u2v l2; l2.x = lo; l2.y = lo; u2v h2; h2.x = hi; h2.y = hi;
;             *(LAS u2v*)(ATL + 8 * idx) = l2; *(LAS u2v*)(ATL + 1024 + 8 * idx) = h2;
;         }
;         const float asc = ASC[tl]; const int sa = SAL[tl];
;         CFENCE();
;         int accH[4], accL[4];
; #pragma unroll
;         for (int st = 0; st < 16; ++st) {
;             const int p = st >> 2, q = st & 3;
;             if (st < 14) VDMA(st + 2, (st + 2) % 3);
;             if (st < 14) asm volatile("s_waitcnt vmcnt(8)" ::: "memory");
;             else if (st == 14) asm volatile("s_waitcnt vmcnt(4)" ::: "memory");
;             else asm volatile("s_waitcnt vmcnt(0)" ::: "memory");
;             if (q == 0) {
; #pragma unroll
;                 for (int r = 0; r < 4; ++r) { accH[r] = 0; accL[r] = 0; } }
; #pragma unroll
;             for (int tp = 0; tp < 2; ++tp) {
;                 const v2i ao = TR4(ATL + (2 * q + tp) * 128 + 8 * s16), ah = TR4(ATL + 1024 + (2 * q + tp) * 128 + 8 * s16);
; #pragma unroll
;                 for (int r = 0; r < 4; ++r) {
;                     const v2i d = TR4(ldsb + BUF[st % 3] + 2048 * tp + roff[r]);
;                     accH[r] = __builtin_amdgcn_sdot8(d.x, ah.x, accH[r], false); accH[r] = __builtin_amdgcn_sdot8(d.y, ah.y, accH[r], false);
;                     accL[r] = __builtin_amdgcn_sdot8(d.x, ao.x, accL[r], false); accL[r] = __builtin_amdgcn_sdot8(d.y, ao.y, accL[r], false);
;                 }
;             }
;             asm volatile("s_waitcnt lgkmcnt(0)" ::: "memory");
	v_add_u32_e32 v54, s79, v59
	v_add_u32_e32 v55, s79, v60
	v_add_u32_e32 v56, s79, v61
	v_add_u32_e32 v57, s79, v62
	ds_read_b64_tr_b4 v[50:51], v160 offset:384
	ds_read_b64_tr_b4 v[52:53], v160 offset:1408
	ds_read_b64_tr_b4 v[130:131], v54
	ds_read_b64_tr_b4 v[132:133], v55
	ds_read_b64_tr_b4 v[134:135], v56
	ds_read_b64_tr_b4 v[136:137], v57
	s_waitcnt lgkmcnt(15)
	v_dot8c_i32_i4_e32 v38, v122, v48
	v_dot8c_i32_i4_e32 v39, v122, v46
	v_dot8c_i32_i4_e32 v40, v124, v48
	v_dot8c_i32_i4_e32 v41, v124, v46
	v_dot8c_i32_i4_e32 v42, v126, v48
	v_dot8c_i32_i4_e32 v43, v126, v46
	v_dot8c_i32_i4_e32 v44, v128, v48
	v_dot8c_i32_i4_e32 v45, v128, v46
	v_dot8c_i32_i4_e32 v38, v123, v49
	v_dot8c_i32_i4_e32 v39, v123, v47
	v_dot8c_i32_i4_e32 v40, v125, v49
	v_dot8c_i32_i4_e32 v41, v125, v47
	v_dot8c_i32_i4_e32 v42, v127, v49
	v_dot8c_i32_i4_e32 v43, v127, v47
	v_dot8c_i32_i4_e32 v44, v129, v49
	v_dot8c_i32_i4_e32 v45, v129, v47
	s_waitcnt lgkmcnt(15)
	v_and_b32_e32 v78, 0xffff, v18
	v_lshrrev_b32_e32 v79, 16, v18
	v_lshl_add_u32 v78, v78, 7, v150
	v_lshl_add_u32 v79, v79, 7, v151
	s_mov_b32 m0, s78
	s_add_i32 s43, s78, 0x400
	global_load_lds_dwordx4 v78, s[50:51]
	s_mov_b32 m0, s43
	s_nop 0
	global_load_lds_dwordx4 v79, s[50:51]
	s_waitcnt vmcnt(9)
	v_add_u32_e32 v54, s98, v59
	v_add_u32_e32 v55, s98, v60
	v_add_u32_e32 v56, s98, v61
	v_add_u32_e32 v57, s98, v62
	ds_read_b64_tr_b4 v[46:47], v160 offset:512
	ds_read_b64_tr_b4 v[48:49], v160 offset:1536
	ds_read_b64_tr_b4 v[122:123], v54
	ds_read_b64_tr_b4 v[124:125], v55
	ds_read_b64_tr_b4 v[126:127], v56
	ds_read_b64_tr_b4 v[128:129], v57
	s_waitcnt lgkmcnt(6)
	v_dot8c_i32_i4_e32 v38, v130, v52
	v_dot8c_i32_i4_e32 v39, v130, v50
	v_dot8c_i32_i4_e32 v40, v132, v52
	v_dot8c_i32_i4_e32 v41, v132, v50
	v_dot8c_i32_i4_e32 v42, v134, v52
	v_dot8c_i32_i4_e32 v43, v134, v50
	v_dot8c_i32_i4_e32 v44, v136, v52
	v_dot8c_i32_i4_e32 v45, v136, v50
	v_dot8c_i32_i4_e32 v38, v131, v53
	v_dot8c_i32_i4_e32 v39, v131, v51
	v_dot8c_i32_i4_e32 v40, v133, v53
	v_dot8c_i32_i4_e32 v41, v133, v51
	v_dot8c_i32_i4_e32 v42, v135, v53
	v_dot8c_i32_i4_e32 v43, v135, v51
	v_dot8c_i32_i4_e32 v44, v137, v53
	v_dot8c_i32_i4_e32 v45, v137, v51
	v_and_b32_e32 v78, 0xffff, v19
	v_lshrrev_b32_e32 v79, 16, v19
	v_lshl_add_u32 v78, v78, 7, v150
	v_lshl_add_u32 v79, v79, 7, v151
	s_mov_b32 m0, s79
	s_add_i32 s43, s79, 0x400
	global_load_lds_dwordx4 v78, s[50:51]
	s_mov_b32 m0, s43
	s_nop 0
	global_load_lds_dwordx4 v79, s[50:51]
	s_waitcnt vmcnt(8)
	v_add_u32_e32 v54, s99, v59
	v_add_u32_e32 v55, s99, v60
	v_add_u32_e32 v56, s99, v61
	v_add_u32_e32 v57, s99, v62
	ds_read_b64_tr_b4 v[50:51], v160 offset:640
	ds_read_b64_tr_b4 v[52:53], v160 offset:1664
	ds_read_b64_tr_b4 v[130:131], v54
	ds_read_b64_tr_b4 v[132:133], v55
	ds_read_b64_tr_b4 v[134:135], v56
	ds_read_b64_tr_b4 v[136:137], v57
	s_waitcnt lgkmcnt(6)
	v_dot8c_i32_i4_e32 v38, v122, v48
	v_dot8c_i32_i4_e32 v39, v122, v46
	v_dot8c_i32_i4_e32 v40, v124, v48
	v_dot8c_i32_i4_e32 v41, v124, v46
	v_dot8c_i32_i4_e32 v42, v126, v48
	v_dot8c_i32_i4_e32 v43, v126, v46
	v_dot8c_i32_i4_e32 v44, v128, v48
	v_dot8c_i32_i4_e32 v45, v128, v46
	v_dot8c_i32_i4_e32 v38, v123, v49
	v_dot8c_i32_i4_e32 v39, v123, v47
	v_dot8c_i32_i4_e32 v40, v125, v49
	v_dot8c_i32_i4_e32 v41, v125, v47
	v_dot8c_i32_i4_e32 v42, v127, v49
	v_dot8c_i32_i4_e32 v43, v127, v47
	v_dot8c_i32_i4_e32 v44, v129, v49
	v_dot8c_i32_i4_e32 v45, v129, v47
	s_waitcnt lgkmcnt(15)
	v_add_u32_e32 v143, 8, v139
	v_and_b32_e32 v142, 15, v143
	v_xor_b32_e32 v142, 8, v142
	v_bfe_u32 v144, v143, 4, 4
	v_mul_lo_u32 v142, v142, s92
	v_mul_lo_u32 v144, v144, s92
	v_mov_b32_e32 v143, v142
	v_mov_b32_e32 v145, v144
	ds_write2st64_b64 v159, v[142:143], v[144:145] offset1:2
	v_and_b32_e32 v78, 0xffff, v20
	v_lshrrev_b32_e32 v79, 16, v20
	v_lshl_add_u32 v78, v78, 7, v150
	v_lshl_add_u32 v79, v79, 7, v151
	s_mov_b32 m0, s98
	s_add_i32 s43, s98, 0x400
	global_load_lds_dwordx4 v78, s[50:51]
	s_mov_b32 m0, s43
	s_nop 0
	global_load_lds_dwordx4 v79, s[50:51]
	s_waitcnt vmcnt(8)
	v_add_u32_e32 v54, s76, v59
	v_add_u32_e32 v55, s76, v60
	v_add_u32_e32 v56, s76, v61
	v_add_u32_e32 v57, s76, v62
	ds_read_b64_tr_b4 v[46:47], v160 offset:768
	ds_read_b64_tr_b4 v[48:49], v160 offset:1792
	ds_read_b64_tr_b4 v[122:123], v54
	ds_read_b64_tr_b4 v[124:125], v55
	ds_read_b64_tr_b4 v[126:127], v56
	ds_read_b64_tr_b4 v[128:129], v57
	s_waitcnt lgkmcnt(7)
	v_dot8c_i32_i4_e32 v38, v130, v52
	v_dot8c_i32_i4_e32 v39, v130, v50
	v_dot8c_i32_i4_e32 v40, v132, v52
	v_dot8c_i32_i4_e32 v41, v132, v50
	v_dot8c_i32_i4_e32 v42, v134, v52
	v_dot8c_i32_i4_e32 v43, v134, v50
	v_dot8c_i32_i4_e32 v44, v136, v52
	v_dot8c_i32_i4_e32 v45, v136, v50
	v_dot8c_i32_i4_e32 v38, v131, v53
	v_dot8c_i32_i4_e32 v39, v131, v51
	v_dot8c_i32_i4_e32 v40, v133, v53
	v_dot8c_i32_i4_e32 v41, v133, v51
	v_dot8c_i32_i4_e32 v42, v135, v53
	v_dot8c_i32_i4_e32 v43, v135, v51
	v_dot8c_i32_i4_e32 v44, v137, v53
	v_dot8c_i32_i4_e32 v45, v137, v51
	v_and_b32_e32 v78, 0xffff, v21
	v_lshrrev_b32_e32 v79, 16, v21
	v_lshl_add_u32 v78, v78, 7, v150
	v_lshl_add_u32 v79, v79, 7, v151
	s_mov_b32 m0, s99
	s_add_i32 s43, s99, 0x400
	global_load_lds_dwordx4 v78, s[50:51]
	s_mov_b32 m0, s43
	s_nop 0
	global_load_lds_dwordx4 v79, s[50:51]
	s_waitcnt vmcnt(8)
	v_add_u32_e32 v54, s77, v59
	v_add_u32_e32 v55, s77, v60
	v_add_u32_e32 v56, s77, v61
	v_add_u32_e32 v57, s77, v62
	ds_read_b64_tr_b4 v[50:51], v160 offset:896
	ds_read_b64_tr_b4 v[52:53], v160 offset:1920
	ds_read_b64_tr_b4 v[130:131], v54
	ds_read_b64_tr_b4 v[132:133], v55
	ds_read_b64_tr_b4 v[134:135], v56
	ds_read_b64_tr_b4 v[136:137], v57
	s_waitcnt lgkmcnt(6)
; __device__ __forceinline__ void peer_v_tokens(int j, const LAS unsigned short* EL, const LAS unsigned char* AL  , const LAS float* ASC  , const LAS int* SAL  , ...
;     ...
;         { const LAS v4u* ep = (const LAS v4u*)(EL + tl * 128 + 16 * g); const v4u e0 = ep[0], e1 = ep[1];
;           E[0] = e0.x; E[1] = e0.y; E[2] = e0.z; E[3] = e0.w; E[4] = e1.x; E[5] = e1.y; E[6] = e1.z; E[7] = e1.w; }
;         uint2 hv[4]; float4 gv[4];
;         { unsigned ho = (unsigned)t * (D / 4) + (unsigned)lane; asm volatile("" : "+v"(ho)); const uint2* hp = (const uint2*)HB + ho; const float4* gp = (const float4*)fng + lane;
; #pragma unroll
;           for (int jq = 0; jq < 4; ++jq) { hv[jq] = hp[64 * jq]; gv[jq] = gp[64 * jq]; } }
;         VDMA(0, 0); VDMA(1, 1);
; #pragma unroll
;         for (int m = 0; m < 2; ++m) {
;             const int idx = lane + 64 * m, tau = idx >> 4, sr = idx & 15, k = 16 * (sr & 7) + 2 * tau + (sr >> 3);
;             const int aq = (int)*(const LAS signed char*)(AL + tl * 128 + k); const int tq = aq + 8;
;             const unsigned lo = (((unsigned)tq & 15u) ^ 8u) * 0x11111111u, hi = ((unsigned)(tq >> 4) & 15u) * 0x11111111u;
;             typedef unsigned u2v __attribute__((ext_vector_type(2)));
;             u2v l2; l2.x = lo; l2.y = lo; u2v h2; h2.x = hi; h2.y = hi;
;             *(LAS u2v*)(ATL + 8 * idx) = l2; *(LAS u2v*)(ATL + 1024 + 8 * idx) = h2;
;         }
;         const float asc = ASC[tl]; const int sa = SAL[tl];
;         CFENCE();
;         int accH[4], accL[4];
; #pragma unroll
;         for (int st = 0; st < 16; ++st) {
;             const int p = st >> 2, q = st & 3;
;             if (st < 14) VDMA(st + 2, (st + 2) % 3);
;             if (st < 14) asm volatile("s_waitcnt vmcnt(8)" ::: "memory");
;             else if (st == 14) asm volatile("s_waitcnt vmcnt(4)" ::: "memory");
;             else asm volatile("s_waitcnt vmcnt(0)" ::: "memory");
;             if (q == 0) {
; #pragma unroll
;                 for (int r = 0; r < 4; ++r) { accH[r] = 0; accL[r] = 0; } }
; #pragma unroll
;             for (int tp = 0; tp < 2; ++tp) {
;                 const v2i ao = TR4(ATL + (2 * q + tp) * 128 + 8 * s16), ah = TR4(ATL + 1024 + (2 * q + tp) * 128 + 8 * s16);
; #pragma unroll
;                 for (int r = 0; r < 4; ++r) {
;                     const v2i d = TR4(ldsb + BUF[st % 3] + 2048 * tp + roff[r]);
	v_dot8c_i32_i4_e32 v38, v122, v48
	v_dot8c_i32_i4_e32 v39, v122, v46
	v_dot8c_i32_i4_e32 v40, v124, v48
	v_dot8c_i32_i4_e32 v41, v124, v46
	v_dot8c_i32_i4_e32 v42, v126, v48
	v_dot8c_i32_i4_e32 v43, v126, v46
	v_dot8c_i32_i4_e32 v44, v128, v48
	v_dot8c_i32_i4_e32 v45, v128, v46
	v_dot8c_i32_i4_e32 v38, v123, v49
	v_dot8c_i32_i4_e32 v39, v123, v47
	v_dot8c_i32_i4_e32 v40, v125, v49
	v_dot8c_i32_i4_e32 v41, v125, v47
	v_dot8c_i32_i4_e32 v42, v127, v49
	v_dot8c_i32_i4_e32 v43, v127, v47
	v_dot8c_i32_i4_e32 v44, v129, v49
	v_dot8c_i32_i4_e32 v45, v129, v47
	v_and_b32_e32 v78, 0xffff, v22
	v_lshrrev_b32_e32 v79, 16, v22
	v_lshl_add_u32 v78, v78, 7, v150
	v_lshl_add_u32 v79, v79, 7, v151
	s_mov_b32 m0, s76
	s_add_i32 s43, s76, 0x400
	global_load_lds_dwordx4 v78, s[50:51]
	s_mov_b32 m0, s43
	s_nop 0
	global_load_lds_dwordx4 v79, s[50:51]
	s_waitcnt vmcnt(8)
	v_add_u32_e32 v54, s78, v59
	v_add_u32_e32 v55, s78, v60
	v_add_u32_e32 v56, s78, v61
	v_add_u32_e32 v57, s78, v62
	ds_read_b64_tr_b4 v[46:47], v160
	ds_read_b64_tr_b4 v[48:49], v160 offset:1024
	ds_read_b64_tr_b4 v[122:123], v54
	ds_read_b64_tr_b4 v[124:125], v55
	ds_read_b64_tr_b4 v[126:127], v56
	ds_read_b64_tr_b4 v[128:129], v57
	s_waitcnt lgkmcnt(6)
	v_dot8c_i32_i4_e32 v38, v130, v52
	v_dot8c_i32_i4_e32 v39, v130, v50
	v_dot8c_i32_i4_e32 v40, v132, v52
	v_dot8c_i32_i4_e32 v41, v132, v50
	v_dot8c_i32_i4_e32 v42, v134, v52
	v_dot8c_i32_i4_e32 v43, v134, v50
	v_dot8c_i32_i4_e32 v44, v136, v52
	v_dot8c_i32_i4_e32 v45, v136, v50
	v_dot8c_i32_i4_e32 v38, v131, v53
	v_dot8c_i32_i4_e32 v39, v131, v51
	v_dot8c_i32_i4_e32 v40, v133, v53
	v_dot8c_i32_i4_e32 v41, v133, v51
	v_dot8c_i32_i4_e32 v42, v135, v53
	v_dot8c_i32_i4_e32 v43, v135, v51
	v_dot8c_i32_i4_e32 v44, v137, v53
	v_dot8c_i32_i4_e32 v45, v137, v51
	s_nop 3
	s_waitcnt lgkmcnt(15)
	v_lshlrev_b32_e32 v38, 5, v38
	v_lshlrev_b32_e32 v39, 1, v39
	v_add3_u32 v38, v39, v229, v38
	v_cvt_f32_i32_e32 v38, v38
	v_mul_f32_e32 v38, v228, v38
	v_lshlrev_b32_e32 v40, 5, v40
	v_lshlrev_b32_e32 v41, 1, v41
	v_add3_u32 v40, v41, v229, v40
	v_cvt_f32_i32_e32 v40, v40
	v_mul_f32_e32 v40, v228, v40
	v_lshlrev_b32_e32 v42, 5, v42
	v_lshlrev_b32_e32 v43, 1, v43
	v_add3_u32 v42, v43, v229, v42
	v_cvt_f32_i32_e32 v42, v42
	v_mul_f32_e32 v42, v228, v42
	v_lshlrev_b32_e32 v44, 5, v44
	v_lshlrev_b32_e32 v45, 1, v45
	v_add3_u32 v44, v45, v229, v44
	v_cvt_f32_i32_e32 v44, v44
	v_mul_f32_e32 v44, v228, v44
	v_cvt_pk_bf16_f32 v188, v38, v40
	v_cvt_pk_bf16_f32 v189, v42, v44
	ds_read_b128 v[252:255], v156
	s_add_i32 s44, s40, 32
	s_ashr_i32 s45, s44, 31
	s_lshl_b64 s[44:45], s[44:45], 12
	v_lshl_add_u64 v[80:81], v[36:37], 0, s[44:45]
	s_waitcnt lgkmcnt(0)
	v_mul_f32_e32 v218, v218, v252
	v_mul_f32_e32 v219, v219, v253
	v_mul_f32_e32 v220, v220, v254
	v_mul_f32_e32 v221, v221, v255
	global_store_dwordx4 v[80:81], v[218:221], off offset:2048 nt
	v_add_u32_e32 v147, 8, v140
	v_and_b32_e32 v146, 15, v147
	v_xor_b32_e32 v146, 8, v146
	v_bfe_u32 v148, v147, 4, 4
	v_mul_lo_u32 v146, v146, s92
	v_mul_lo_u32 v148, v148, s92
	v_mov_b32_e32 v147, v146
	v_mov_b32_e32 v149, v148
	ds_write2st64_b64 v77, v[146:147], v[148:149] offset1:2
	v_add_u32_e32 v138, 0x1c00, v74
	ds_read_u8 v139, v138
	v_add_u32_e32 v141, 0x1c00, v73
	ds_read_u8 v140, v141
	s_add_i32 s43, s67, 192
	v_mov_b32_e32 v138, s43
	ds_read2st64_b32 v[228:229], v138 offset1:1
	ds_read_b128 v[26:29], v227 offset:14336
	ds_read_b128 v[30:33], v227 offset:14352
	v_mov_b32_e32 v38, 0
	v_mov_b32_e32 v39, 0
	v_mov_b32_e32 v40, 0
	v_mov_b32_e32 v41, 0
	v_mov_b32_e32 v42, 0
	v_mov_b32_e32 v43, 0
	v_mov_b32_e32 v44, 0
	v_mov_b32_e32 v45, 0
	v_and_b32_e32 v78, 0xffff, v23
	v_lshrrev_b32_e32 v79, 16, v23
	v_lshl_add_u32 v78, v78, 7, v150
	v_lshl_add_u32 v79, v79, 7, v151
	s_mov_b32 m0, s77
	s_add_i32 s43, s77, 0x400
	global_load_lds_dwordx4 v78, s[50:51]
	s_mov_b32 m0, s43
	s_nop 0
	global_load_lds_dwordx4 v79, s[50:51]
	s_waitcnt vmcnt(9)
	v_add_u32_e32 v54, s79, v59
	v_add_u32_e32 v55, s79, v60
	v_add_u32_e32 v56, s79, v61
	v_add_u32_e32 v57, s79, v62
	ds_read_b64_tr_b4 v[50:51], v160 offset:128
	ds_read_b64_tr_b4 v[52:53], v160 offset:1152
	ds_read_b64_tr_b4 v[130:131], v54
	ds_read_b64_tr_b4 v[132:133], v55
	ds_read_b64_tr_b4 v[134:135], v56
	ds_read_b64_tr_b4 v[136:137], v57
	s_waitcnt lgkmcnt(13)
	s_waitcnt vmcnt(36) lgkmcnt(15)
; #define LAS __attribute__((address_space(3)))
; #define TR4(p_) __builtin_amdgcn_ds_read_tr4_b64_v2i32((LAS v2i*)(p_))
; __device__ __forceinline__ void peer_v_tokens(int j, const LAS unsigned short* EL, const LAS unsigned char* AL  , const LAS float* ASC  , const LAS int* SAL  , ...
;     ...
;         for (int st = 0; st < 16; ++st) {
;             const int p = st >> 2, q = st & 3;
;             if (st < 14) VDMA(st + 2, (st + 2) % 3);
;             if (st < 14) asm volatile("s_waitcnt vmcnt(8)" ::: "memory");
;             else if (st == 14) asm volatile("s_waitcnt vmcnt(4)" ::: "memory");
;             else asm volatile("s_waitcnt vmcnt(0)" ::: "memory");
;             if (q == 0) {
; #pragma unroll
;                 for (int r = 0; r < 4; ++r) { accH[r] = 0; accL[r] = 0; } }
; #pragma unroll
;             for (int tp = 0; tp < 2; ++tp) {
;                 const v2i ao = TR4(ATL + (2 * q + tp) * 128 + 8 * s16), ah = TR4(ATL + 1024 + (2 * q + tp) * 128 + 8 * s16);
; #pragma unroll
;                 for (int r = 0; r < 4; ++r) {
;                     const v2i d = TR4(ldsb + BUF[st % 3] + 2048 * tp + roff[r]);
;                     accH[r] = __builtin_amdgcn_sdot8(d.x, ah.x, accH[r], false); accH[r] = __builtin_amdgcn_sdot8(d.y, ah.y, accH[r], false);
;                     accL[r] = __builtin_amdgcn_sdot8(d.x, ao.x, accL[r], false); accL[r] = __builtin_amdgcn_sdot8(d.y, ao.y, accL[r], false);
;                 }
;     ...
;         {
;             float4 v[4]; float ss = 0.f;
; #pragma unroll
;             for (int jq = 0; jq < 4; ++jq) { typedef unsigned u2v __attribute__((ext_vector_type(2))); const u2v pw = *(const LAS u2v*)(STASH + 4 * lane + 256 * jq); const uint2 hw = hv[jq];
;                 v[jq] = make_float4(__uint_as_float(hw.x << 16) + __uint_as_float(pw.x << 16), __uint_as_float(hw.x & 0xffff0000u) + __uint_as_float(pw.x & 0xffff0000u),
;                                     __uint_as_float(hw.y << 16) + __uint_as_float(pw.y << 16), __uint_as_float(hw.y & 0xffff0000u) + __uint_as_float(pw.y & 0xffff0000u));
;                 ss += v[jq].x * v[jq].x + v[jq].y * v[jq].y + v[jq].z * v[jq].z + v[jq].w * v[jq].w; }
;             ss = wave_sum(ss);
;             const float r3 = rsqrtf(ss * (1.f / D) + EPS);
	v_lshlrev_b32_e32 v236, 16, v194
	v_and_b32_e32 v237, 0xffff0000, v194
	v_lshlrev_b32_e32 v142, 16, v202
	v_and_b32_e32 v143, 0xffff0000, v202
	v_add_f32_e32 v236, v236, v142
	v_add_f32_e32 v237, v237, v143
	v_lshlrev_b32_e32 v238, 16, v195
	v_and_b32_e32 v239, 0xffff0000, v195
	v_lshlrev_b32_e32 v142, 16, v203
	v_and_b32_e32 v143, 0xffff0000, v203
	v_add_f32_e32 v238, v238, v142
	v_add_f32_e32 v239, v239, v143
	v_lshlrev_b32_e32 v240, 16, v196
	v_and_b32_e32 v241, 0xffff0000, v196
	v_lshlrev_b32_e32 v142, 16, v204
	v_and_b32_e32 v143, 0xffff0000, v204
	v_add_f32_e32 v240, v240, v142
	v_add_f32_e32 v241, v241, v143
	v_lshlrev_b32_e32 v242, 16, v197
	v_and_b32_e32 v243, 0xffff0000, v197
	v_lshlrev_b32_e32 v142, 16, v205
	v_and_b32_e32 v143, 0xffff0000, v205
	v_add_f32_e32 v242, v242, v142
	v_add_f32_e32 v243, v243, v143
	v_lshlrev_b32_e32 v244, 16, v198
	v_and_b32_e32 v245, 0xffff0000, v198
	v_lshlrev_b32_e32 v142, 16, v206
	v_and_b32_e32 v143, 0xffff0000, v206
	v_add_f32_e32 v244, v244, v142
	v_add_f32_e32 v245, v245, v143
	v_lshlrev_b32_e32 v246, 16, v199
	v_and_b32_e32 v247, 0xffff0000, v199
	v_lshlrev_b32_e32 v142, 16, v207
	v_and_b32_e32 v143, 0xffff0000, v207
	v_add_f32_e32 v246, v246, v142
	v_add_f32_e32 v247, v247, v143
	v_lshlrev_b32_e32 v248, 16, v200
	v_and_b32_e32 v249, 0xffff0000, v200
	v_lshlrev_b32_e32 v142, 16, v208
	v_and_b32_e32 v143, 0xffff0000, v208
	v_add_f32_e32 v248, v248, v142
	v_add_f32_e32 v249, v249, v143
	v_lshlrev_b32_e32 v250, 16, v201
	v_and_b32_e32 v251, 0xffff0000, v201
	v_lshlrev_b32_e32 v142, 16, v209
	v_and_b32_e32 v143, 0xffff0000, v209
	v_add_f32_e32 v250, v250, v142
	v_add_f32_e32 v251, v251, v143
	v_mov_b32_e32 v144, 0
	v_mul_f32_e32 v145, v236, v236
	v_fmac_f32_e32 v145, v237, v237
	v_fmac_f32_e32 v145, v238, v238
	v_fmac_f32_e32 v145, v239, v239
	v_add_f32_e32 v144, v144, v145
	v_mul_f32_e32 v145, v240, v240
	v_fmac_f32_e32 v145, v241, v241
	v_fmac_f32_e32 v145, v242, v242
	v_fmac_f32_e32 v145, v243, v243
	v_add_f32_e32 v144, v144, v145
	v_mul_f32_e32 v145, v244, v244
	v_fmac_f32_e32 v145, v245, v245
	v_fmac_f32_e32 v145, v246, v246
	v_fmac_f32_e32 v145, v247, v247
	v_add_f32_e32 v144, v144, v145
	v_mul_f32_e32 v145, v248, v248
	v_fmac_f32_e32 v145, v249, v249
	v_fmac_f32_e32 v145, v250, v250
	v_fmac_f32_e32 v145, v251, v251
	v_add_f32_e32 v144, v144, v145
	s_nop 1
	v_add_f32_dpp v144, v144, v144 quad_perm:[1,0,3,2] row_mask:0xf bank_mask:0xf bound_ctrl:1
	s_nop 1
	v_add_f32_dpp v144, v144, v144 quad_perm:[2,3,0,1] row_mask:0xf bank_mask:0xf bound_ctrl:1
	s_nop 1
	v_add_f32_dpp v144, v144, v144 row_half_mirror row_mask:0xf bank_mask:0xf bound_ctrl:1
	s_nop 1
	v_add_f32_dpp v144, v144, v144 row_mirror row_mask:0xf bank_mask:0xf bound_ctrl:1
	s_nop 1
	v_readlane_b32 s10, v144, 0
	v_readlane_b32 s11, v144, 16
	v_readlane_b32 s14, v144, 32
	v_readlane_b32 s15, v144, 48
	s_nop 3
	v_mov_b32_e32 v144, s11
	v_mov_b32_e32 v145, s15
	v_add_f32_e32 v144, s10, v144
	v_add_f32_e32 v145, s14, v145
	v_add_f32_e32 v144, v144, v145
	v_fmamk_f32 v144, v144, 0x3a800000, v111
	v_rsq_f32_e32 v144, v144
	s_nop 0
	v_mul_f32_e32 v236, v236, v144
	v_mul_f32_e32 v237, v237, v144
	v_mul_f32_e32 v238, v238, v144
	v_mul_f32_e32 v239, v239, v144
	v_mul_f32_e32 v240, v240, v144
	v_mul_f32_e32 v241, v241, v144
	v_mul_f32_e32 v242, v242, v144
	v_mul_f32_e32 v243, v243, v144
	v_mul_f32_e32 v244, v244, v144
	v_mul_f32_e32 v245, v245, v144
	v_mul_f32_e32 v246, v246, v144
	v_mul_f32_e32 v247, v247, v144
	v_mul_f32_e32 v248, v248, v144
	v_mul_f32_e32 v249, v249, v144
	v_mul_f32_e32 v250, v250, v144
	v_mul_f32_e32 v251, v251, v144
	v_dot8c_i32_i4_e32 v38, v122, v48
	v_dot8c_i32_i4_e32 v39, v122, v46
	v_dot8c_i32_i4_e32 v40, v124, v48
	v_dot8c_i32_i4_e32 v41, v124, v46
	v_dot8c_i32_i4_e32 v42, v126, v48
	v_dot8c_i32_i4_e32 v43, v126, v46
	v_dot8c_i32_i4_e32 v44, v128, v48
	v_dot8c_i32_i4_e32 v45, v128, v46
	v_dot8c_i32_i4_e32 v38, v123, v49
	v_dot8c_i32_i4_e32 v39, v123, v47
	v_dot8c_i32_i4_e32 v40, v125, v49
	v_dot8c_i32_i4_e32 v41, v125, v47
	v_dot8c_i32_i4_e32 v42, v127, v49
	v_dot8c_i32_i4_e32 v43, v127, v47
	v_dot8c_i32_i4_e32 v44, v129, v49
	v_dot8c_i32_i4_e32 v45, v129, v47
	v_and_b32_e32 v78, 0xffff, v24
	v_lshrrev_b32_e32 v79, 16, v24
	v_lshl_add_u32 v78, v78, 7, v150
	v_lshl_add_u32 v79, v79, 7, v151
	s_mov_b32 m0, s78
	s_add_i32 s43, s78, 0x400
	global_load_lds_dwordx4 v78, s[50:51]
	s_mov_b32 m0, s43
	s_nop 0
	global_load_lds_dwordx4 v79, s[50:51]
	s_waitcnt vmcnt(9)
	v_add_u32_e32 v54, s98, v59
	v_add_u32_e32 v55, s98, v60
	v_add_u32_e32 v56, s98, v61
	v_add_u32_e32 v57, s98, v62
	ds_read_b64_tr_b4 v[46:47], v160 offset:256
	ds_read_b64_tr_b4 v[48:49], v160 offset:1280
	ds_read_b64_tr_b4 v[122:123], v54
	ds_read_b64_tr_b4 v[124:125], v55
	ds_read_b64_tr_b4 v[126:127], v56
	ds_read_b64_tr_b4 v[128:129], v57
	s_waitcnt lgkmcnt(6)
	v_dot8c_i32_i4_e32 v38, v130, v52
	v_dot8c_i32_i4_e32 v39, v130, v50
	v_dot8c_i32_i4_e32 v40, v132, v52
	v_dot8c_i32_i4_e32 v41, v132, v50
	v_dot8c_i32_i4_e32 v42, v134, v52
	v_dot8c_i32_i4_e32 v43, v134, v50
	v_dot8c_i32_i4_e32 v44, v136, v52
	v_dot8c_i32_i4_e32 v45, v136, v50
	v_dot8c_i32_i4_e32 v38, v131, v53
	v_dot8c_i32_i4_e32 v39, v131, v51
	v_dot8c_i32_i4_e32 v40, v133, v53
	v_dot8c_i32_i4_e32 v41, v133, v51
	v_dot8c_i32_i4_e32 v42, v135, v53
	v_dot8c_i32_i4_e32 v43, v135, v51
	v_dot8c_i32_i4_e32 v44, v137, v53
	v_dot8c_i32_i4_e32 v45, v137, v51
	v_and_b32_e32 v78, 0xffff, v25
	v_lshrrev_b32_e32 v79, 16, v25
	v_lshl_add_u32 v78, v78, 7, v150
	v_lshl_add_u32 v79, v79, 7, v151
	s_mov_b32 m0, s79
	s_add_i32 s43, s79, 0x400
	global_load_lds_dwordx4 v78, s[50:51]
	s_mov_b32 m0, s43
	s_nop 0
	global_load_lds_dwordx4 v79, s[50:51]
	s_waitcnt vmcnt(9)
; #define LAS __attribute__((address_space(3)))
; #define TR4(p_) __builtin_amdgcn_ds_read_tr4_b64_v2i32((LAS v2i*)(p_))
; #define CFENCE() asm volatile("" ::: "memory")
; __device__ __forceinline__ void peer_v_tokens(int j, const LAS unsigned short* EL, const LAS unsigned char* AL  , const LAS float* ASC  , const LAS int* SAL  , ...
;     ...
;             const int idx = lane + 64 * m, tau = idx >> 4, sr = idx & 15, k = 16 * (sr & 7) + 2 * tau + (sr >> 3);
;             const int aq = (int)*(const LAS signed char*)(AL + tl * 128 + k); const int tq = aq + 8;
;             const unsigned lo = (((unsigned)tq & 15u) ^ 8u) * 0x11111111u, hi = ((unsigned)(tq >> 4) & 15u) * 0x11111111u;
;             typedef unsigned u2v __attribute__((ext_vector_type(2)));
;             u2v l2; l2.x = lo; l2.y = lo; u2v h2; h2.x = hi; h2.y = hi;
;             *(LAS u2v*)(ATL + 8 * idx) = l2; *(LAS u2v*)(ATL + 1024 + 8 * idx) = h2;
;         }
;         const float asc = ASC[tl]; const int sa = SAL[tl];
;         CFENCE();
;         int accH[4], accL[4];
; #pragma unroll
;         for (int st = 0; st < 16; ++st) {
;             const int p = st >> 2, q = st & 3;
;             if (st < 14) VDMA(st + 2, (st + 2) % 3);
;             if (st < 14) asm volatile("s_waitcnt vmcnt(8)" ::: "memory");
;             else if (st == 14) asm volatile("s_waitcnt vmcnt(4)" ::: "memory");
;             else asm volatile("s_waitcnt vmcnt(0)" ::: "memory");
;             if (q == 0) {
; #pragma unroll
;                 for (int r = 0; r < 4; ++r) { accH[r] = 0; accL[r] = 0; } }
; #pragma unroll
;             for (int tp = 0; tp < 2; ++tp) {
;                 const v2i ao = TR4(ATL + (2 * q + tp) * 128 + 8 * s16), ah = TR4(ATL + 1024 + (2 * q + tp) * 128 + 8 * s16);
; #pragma unroll
;                 for (int r = 0; r < 4; ++r) {
;                     const v2i d = TR4(ldsb + BUF[st % 3] + 2048 * tp + roff[r]);
;                     accH[r] = __builtin_amdgcn_sdot8(d.x, ah.x, accH[r], false); accH[r] = __builtin_amdgcn_sdot8(d.y, ah.y, accH[r], false);
;                     accL[r] = __builtin_amdgcn_sdot8(d.x, ao.x, accL[r], false); accL[r] = __builtin_amdgcn_sdot8(d.y, ao.y, accL[r], false);
;                 }
;             }
;             asm volatile("s_waitcnt lgkmcnt(0)" ::: "memory");
	v_add_u32_e32 v54, s99, v59
	v_add_u32_e32 v55, s99, v60
	v_add_u32_e32 v56, s99, v61
	v_add_u32_e32 v57, s99, v62
	ds_read_b64_tr_b4 v[50:51], v160 offset:384
	ds_read_b64_tr_b4 v[52:53], v160 offset:1408
	ds_read_b64_tr_b4 v[130:131], v54
	ds_read_b64_tr_b4 v[132:133], v55
	ds_read_b64_tr_b4 v[134:135], v56
	ds_read_b64_tr_b4 v[136:137], v57
	s_waitcnt lgkmcnt(6)
	v_dot8c_i32_i4_e32 v38, v122, v48
	v_dot8c_i32_i4_e32 v39, v122, v46
	v_dot8c_i32_i4_e32 v40, v124, v48
	v_dot8c_i32_i4_e32 v41, v124, v46
	v_dot8c_i32_i4_e32 v42, v126, v48
	v_dot8c_i32_i4_e32 v43, v126, v46
	v_dot8c_i32_i4_e32 v44, v128, v48
	v_dot8c_i32_i4_e32 v45, v128, v46
	v_dot8c_i32_i4_e32 v38, v123, v49
	v_dot8c_i32_i4_e32 v39, v123, v47
	v_dot8c_i32_i4_e32 v40, v125, v49
	v_dot8c_i32_i4_e32 v41, v125, v47
	v_dot8c_i32_i4_e32 v42, v127, v49
	v_dot8c_i32_i4_e32 v43, v127, v47
	v_dot8c_i32_i4_e32 v44, v129, v49
	v_dot8c_i32_i4_e32 v45, v129, v47
	s_waitcnt lgkmcnt(15)
	v_and_b32_e32 v78, 0xffff, v26
	v_lshrrev_b32_e32 v79, 16, v26
	v_lshl_add_u32 v78, v78, 7, v150
	v_lshl_add_u32 v79, v79, 7, v151
	s_mov_b32 m0, s98
	s_add_i32 s43, s98, 0x400
	global_load_lds_dwordx4 v78, s[50:51]
	s_mov_b32 m0, s43
	s_nop 0
	global_load_lds_dwordx4 v79, s[50:51]
	s_waitcnt vmcnt(9)
	v_add_u32_e32 v54, s76, v59
	v_add_u32_e32 v55, s76, v60
	v_add_u32_e32 v56, s76, v61
	v_add_u32_e32 v57, s76, v62
	ds_read_b64_tr_b4 v[46:47], v160 offset:512
	ds_read_b64_tr_b4 v[48:49], v160 offset:1536
	ds_read_b64_tr_b4 v[122:123], v54
	ds_read_b64_tr_b4 v[124:125], v55
	ds_read_b64_tr_b4 v[126:127], v56
	ds_read_b64_tr_b4 v[128:129], v57
	s_waitcnt lgkmcnt(6)
	v_dot8c_i32_i4_e32 v38, v130, v52
	v_dot8c_i32_i4_e32 v39, v130, v50
	v_dot8c_i32_i4_e32 v40, v132, v52
	v_dot8c_i32_i4_e32 v41, v132, v50
	v_dot8c_i32_i4_e32 v42, v134, v52
	v_dot8c_i32_i4_e32 v43, v134, v50
	v_dot8c_i32_i4_e32 v44, v136, v52
	v_dot8c_i32_i4_e32 v45, v136, v50
	v_dot8c_i32_i4_e32 v38, v131, v53
	v_dot8c_i32_i4_e32 v39, v131, v51
	v_dot8c_i32_i4_e32 v40, v133, v53
	v_dot8c_i32_i4_e32 v41, v133, v51
	v_dot8c_i32_i4_e32 v42, v135, v53
	v_dot8c_i32_i4_e32 v43, v135, v51
	v_dot8c_i32_i4_e32 v44, v137, v53
	v_dot8c_i32_i4_e32 v45, v137, v51
	v_and_b32_e32 v78, 0xffff, v27
	v_lshrrev_b32_e32 v79, 16, v27
	v_lshl_add_u32 v78, v78, 7, v150
	v_lshl_add_u32 v79, v79, 7, v151
	s_mov_b32 m0, s99
	s_add_i32 s43, s99, 0x400
	global_load_lds_dwordx4 v78, s[50:51]
	s_mov_b32 m0, s43
	s_nop 0
	global_load_lds_dwordx4 v79, s[50:51]
	s_waitcnt vmcnt(8)
	v_add_u32_e32 v54, s77, v59
	v_add_u32_e32 v55, s77, v60
	v_add_u32_e32 v56, s77, v61
	v_add_u32_e32 v57, s77, v62
	ds_read_b64_tr_b4 v[50:51], v160 offset:640
	ds_read_b64_tr_b4 v[52:53], v160 offset:1664
	ds_read_b64_tr_b4 v[130:131], v54
	ds_read_b64_tr_b4 v[132:133], v55
	ds_read_b64_tr_b4 v[134:135], v56
	ds_read_b64_tr_b4 v[136:137], v57
	s_waitcnt lgkmcnt(6)
	v_dot8c_i32_i4_e32 v38, v122, v48
	v_dot8c_i32_i4_e32 v39, v122, v46
	v_dot8c_i32_i4_e32 v40, v124, v48
	v_dot8c_i32_i4_e32 v41, v124, v46
	v_dot8c_i32_i4_e32 v42, v126, v48
	v_dot8c_i32_i4_e32 v43, v126, v46
	v_dot8c_i32_i4_e32 v44, v128, v48
	v_dot8c_i32_i4_e32 v45, v128, v46
	v_dot8c_i32_i4_e32 v38, v123, v49
	v_dot8c_i32_i4_e32 v39, v123, v47
	v_dot8c_i32_i4_e32 v40, v125, v49
	v_dot8c_i32_i4_e32 v41, v125, v47
	v_dot8c_i32_i4_e32 v42, v127, v49
	v_dot8c_i32_i4_e32 v43, v127, v47
	v_dot8c_i32_i4_e32 v44, v129, v49
	v_dot8c_i32_i4_e32 v45, v129, v47
	s_waitcnt lgkmcnt(15)
	v_add_u32_e32 v143, 8, v139
	v_and_b32_e32 v142, 15, v143
	v_xor_b32_e32 v142, 8, v142
	v_bfe_u32 v144, v143, 4, 4
	v_mul_lo_u32 v142, v142, s92
	v_mul_lo_u32 v144, v144, s92
	v_mov_b32_e32 v143, v142
	v_mov_b32_e32 v145, v144
	ds_write2st64_b64 v159, v[142:143], v[144:145] offset1:2
	v_and_b32_e32 v78, 0xffff, v28
	v_lshrrev_b32_e32 v79, 16, v28
	v_lshl_add_u32 v78, v78, 7, v150
	v_lshl_add_u32 v79, v79, 7, v151
	s_mov_b32 m0, s76
	s_add_i32 s43, s76, 0x400
	global_load_lds_dwordx4 v78, s[50:51]
	s_mov_b32 m0, s43
	s_nop 0
	global_load_lds_dwordx4 v79, s[50:51]
	s_waitcnt vmcnt(8)
	v_add_u32_e32 v54, s78, v59
	v_add_u32_e32 v55, s78, v60
	v_add_u32_e32 v56, s78, v61
	v_add_u32_e32 v57, s78, v62
	ds_read_b64_tr_b4 v[46:47], v160 offset:768
	ds_read_b64_tr_b4 v[48:49], v160 offset:1792
	ds_read_b64_tr_b4 v[122:123], v54
	ds_read_b64_tr_b4 v[124:125], v55
	ds_read_b64_tr_b4 v[126:127], v56
	ds_read_b64_tr_b4 v[128:129], v57
	s_waitcnt lgkmcnt(7)
	v_dot8c_i32_i4_e32 v38, v130, v52
	v_dot8c_i32_i4_e32 v39, v130, v50
	v_dot8c_i32_i4_e32 v40, v132, v52
	v_dot8c_i32_i4_e32 v41, v132, v50
	v_dot8c_i32_i4_e32 v42, v134, v52
	v_dot8c_i32_i4_e32 v43, v134, v50
	v_dot8c_i32_i4_e32 v44, v136, v52
	v_dot8c_i32_i4_e32 v45, v136, v50
	v_dot8c_i32_i4_e32 v38, v131, v53
	v_dot8c_i32_i4_e32 v39, v131, v51
	v_dot8c_i32_i4_e32 v40, v133, v53
	v_dot8c_i32_i4_e32 v41, v133, v51
	v_dot8c_i32_i4_e32 v42, v135, v53
	v_dot8c_i32_i4_e32 v43, v135, v51
	v_dot8c_i32_i4_e32 v44, v137, v53
	v_dot8c_i32_i4_e32 v45, v137, v51
	v_and_b32_e32 v78, 0xffff, v29
	v_lshrrev_b32_e32 v79, 16, v29
	v_lshl_add_u32 v78, v78, 7, v150
	v_lshl_add_u32 v79, v79, 7, v151
	s_mov_b32 m0, s77
	s_add_i32 s43, s77, 0x400
	global_load_lds_dwordx4 v78, s[50:51]
	s_mov_b32 m0, s43
	s_nop 0
	global_load_lds_dwordx4 v79, s[50:51]
	s_waitcnt vmcnt(8)
	v_add_u32_e32 v54, s79, v59
	v_add_u32_e32 v55, s79, v60
	v_add_u32_e32 v56, s79, v61
	v_add_u32_e32 v57, s79, v62
	ds_read_b64_tr_b4 v[50:51], v160 offset:896
	ds_read_b64_tr_b4 v[52:53], v160 offset:1920
	ds_read_b64_tr_b4 v[130:131], v54
	ds_read_b64_tr_b4 v[132:133], v55
	ds_read_b64_tr_b4 v[134:135], v56
	ds_read_b64_tr_b4 v[136:137], v57
	s_waitcnt lgkmcnt(6)
; __device__ __forceinline__ void peer_v_tokens(int j, const LAS unsigned short* EL, const LAS unsigned char* AL  , const LAS float* ASC  , const LAS int* SAL  , ...
;     ...
;             const int idx = lane + 64 * m, tau = idx >> 4, sr = idx & 15, k = 16 * (sr & 7) + 2 * tau + (sr >> 3);
;             const int aq = (int)*(const LAS signed char*)(AL + tl * 128 + k); const int tq = aq + 8;
;             const unsigned lo = (((unsigned)tq & 15u) ^ 8u) * 0x11111111u, hi = ((unsigned)(tq >> 4) & 15u) * 0x11111111u;
;             typedef unsigned u2v __attribute__((ext_vector_type(2)));
;             u2v l2; l2.x = lo; l2.y = lo; u2v h2; h2.x = hi; h2.y = hi;
;             *(LAS u2v*)(ATL + 8 * idx) = l2; *(LAS u2v*)(ATL + 1024 + 8 * idx) = h2;
;         }
;         const float asc = ASC[tl]; const int sa = SAL[tl];
;         CFENCE();
;         int accH[4], accL[4];
; #pragma unroll
;         for (int st = 0; st < 16; ++st) {
;             const int p = st >> 2, q = st & 3;
;             if (st < 14) VDMA(st + 2, (st + 2) % 3);
;             if (st < 14) asm volatile("s_waitcnt vmcnt(8)" ::: "memory");
;             else if (st == 14) asm volatile("s_waitcnt vmcnt(4)" ::: "memory");
;             else asm volatile("s_waitcnt vmcnt(0)" ::: "memory");
;             if (q == 0) {
; #pragma unroll
;                 for (int r = 0; r < 4; ++r) { accH[r] = 0; accL[r] = 0; } }
; #pragma unroll
;             for (int tp = 0; tp < 2; ++tp) {
;                 const v2i ao = TR4(ATL + (2 * q + tp) * 128 + 8 * s16), ah = TR4(ATL + 1024 + (2 * q + tp) * 128 + 8 * s16);
; #pragma unroll
;                 for (int r = 0; r < 4; ++r) {
;                     const v2i d = TR4(ldsb + BUF[st % 3] + 2048 * tp + roff[r]);
;                     accH[r] = __builtin_amdgcn_sdot8(d.x, ah.x, accH[r], false); accH[r] = __builtin_amdgcn_sdot8(d.y, ah.y, accH[r], false);
;                     accL[r] = __builtin_amdgcn_sdot8(d.x, ao.x, accL[r], false); accL[r] = __builtin_amdgcn_sdot8(d.y, ao.y, accL[r], false);
;                 }
;             }
;             asm volatile("s_waitcnt lgkmcnt(0)" ::: "memory");
;             if (q == 3) {
; #pragma unroll
;                 for (int r = 0; r < 4; ++r) STASH[256 * p + 16 * (grp + 4 * r) + pc] = f2bf(asc * (float)(2 * ((accH[r] << 4) + accL[r]) + sa));
;             }
;         }
;         CFENCE();
;         {
	v_dot8c_i32_i4_e32 v38, v122, v48
	v_dot8c_i32_i4_e32 v39, v122, v46
	v_dot8c_i32_i4_e32 v40, v124, v48
	v_dot8c_i32_i4_e32 v41, v124, v46
	v_dot8c_i32_i4_e32 v42, v126, v48
	v_dot8c_i32_i4_e32 v43, v126, v46
	v_dot8c_i32_i4_e32 v44, v128, v48
	v_dot8c_i32_i4_e32 v45, v128, v46
	v_dot8c_i32_i4_e32 v38, v123, v49
	v_dot8c_i32_i4_e32 v39, v123, v47
	v_dot8c_i32_i4_e32 v40, v125, v49
	v_dot8c_i32_i4_e32 v41, v125, v47
	v_dot8c_i32_i4_e32 v42, v127, v49
	v_dot8c_i32_i4_e32 v43, v127, v47
	v_dot8c_i32_i4_e32 v44, v129, v49
	v_dot8c_i32_i4_e32 v45, v129, v47
	v_and_b32_e32 v78, 0xffff, v30
	v_lshrrev_b32_e32 v79, 16, v30
	v_lshl_add_u32 v78, v78, 7, v150
	v_lshl_add_u32 v79, v79, 7, v151
	s_mov_b32 m0, s78
	s_add_i32 s43, s78, 0x400
	global_load_lds_dwordx4 v78, s[50:51]
	s_mov_b32 m0, s43
	s_nop 0
	global_load_lds_dwordx4 v79, s[50:51]
	s_waitcnt vmcnt(8)
	v_add_u32_e32 v54, s98, v59
	v_add_u32_e32 v55, s98, v60
	v_add_u32_e32 v56, s98, v61
	v_add_u32_e32 v57, s98, v62
	ds_read_b64_tr_b4 v[46:47], v160
	ds_read_b64_tr_b4 v[48:49], v160 offset:1024
	ds_read_b64_tr_b4 v[122:123], v54
	ds_read_b64_tr_b4 v[124:125], v55
	ds_read_b64_tr_b4 v[126:127], v56
	ds_read_b64_tr_b4 v[128:129], v57
	s_waitcnt lgkmcnt(6)
	v_dot8c_i32_i4_e32 v38, v130, v52
	v_dot8c_i32_i4_e32 v39, v130, v50
	v_dot8c_i32_i4_e32 v40, v132, v52
	v_dot8c_i32_i4_e32 v41, v132, v50
	v_dot8c_i32_i4_e32 v42, v134, v52
	v_dot8c_i32_i4_e32 v43, v134, v50
	v_dot8c_i32_i4_e32 v44, v136, v52
	v_dot8c_i32_i4_e32 v45, v136, v50
	v_dot8c_i32_i4_e32 v38, v131, v53
	v_dot8c_i32_i4_e32 v39, v131, v51
	v_dot8c_i32_i4_e32 v40, v133, v53
	v_dot8c_i32_i4_e32 v41, v133, v51
	v_dot8c_i32_i4_e32 v42, v135, v53
	v_dot8c_i32_i4_e32 v43, v135, v51
	v_dot8c_i32_i4_e32 v44, v137, v53
	v_dot8c_i32_i4_e32 v45, v137, v51
	s_nop 3
	s_waitcnt lgkmcnt(15)
	v_lshlrev_b32_e32 v38, 5, v38
	v_lshlrev_b32_e32 v39, 1, v39
	v_add3_u32 v38, v39, v229, v38
	v_cvt_f32_i32_e32 v38, v38
	v_mul_f32_e32 v38, v228, v38
	v_lshlrev_b32_e32 v40, 5, v40
	v_lshlrev_b32_e32 v41, 1, v41
	v_add3_u32 v40, v41, v229, v40
	v_cvt_f32_i32_e32 v40, v40
	v_mul_f32_e32 v40, v228, v40
	v_lshlrev_b32_e32 v42, 5, v42
	v_lshlrev_b32_e32 v43, 1, v43
	v_add3_u32 v42, v43, v229, v42
	v_cvt_f32_i32_e32 v42, v42
	v_mul_f32_e32 v42, v228, v42
	v_lshlrev_b32_e32 v44, 5, v44
	v_lshlrev_b32_e32 v45, 1, v45
	v_add3_u32 v44, v45, v229, v44
	v_cvt_f32_i32_e32 v44, v44
	v_mul_f32_e32 v44, v228, v44
	v_cvt_pk_bf16_f32 v182, v38, v40
	v_cvt_pk_bf16_f32 v183, v42, v44
	ds_read_b128 v[252:255], v156 offset:1024
	s_add_i32 s44, s40, 32
	s_ashr_i32 s45, s44, 31
	s_lshl_b64 s[44:45], s[44:45], 12
	v_lshl_add_u64 v[80:81], v[36:37], 0, s[44:45]
	s_waitcnt lgkmcnt(0)
	v_mul_f32_e32 v222, v222, v252
	v_mul_f32_e32 v223, v223, v253
	v_mul_f32_e32 v224, v224, v254
	v_mul_f32_e32 v225, v225, v255
	global_store_dwordx4 v[80:81], v[222:225], off offset:3072 nt
	ds_read_b128 v[252:255], v155
	s_add_i32 s44, s40, 40
	s_ashr_i32 s45, s44, 31
	s_lshl_b64 s[44:45], s[44:45], 12
	v_lshl_add_u64 v[80:81], v[36:37], 0, s[44:45]
	s_waitcnt lgkmcnt(0)
	v_mul_f32_e32 v236, v236, v252
	v_mul_f32_e32 v237, v237, v253
	v_mul_f32_e32 v238, v238, v254
	v_mul_f32_e32 v239, v239, v255
	global_store_dwordx4 v[80:81], v[236:239], off nt
	v_add_u32_e32 v147, 8, v140
	v_and_b32_e32 v146, 15, v147
	v_xor_b32_e32 v146, 8, v146
	v_bfe_u32 v148, v147, 4, 4
	v_mul_lo_u32 v146, v146, s92
	v_mul_lo_u32 v148, v148, s92
	v_mov_b32_e32 v147, v146
	v_mov_b32_e32 v149, v148
	ds_write2st64_b64 v77, v[146:147], v[148:149] offset1:2
	v_add_u32_e32 v138, 0x1800, v74
	ds_read_u8 v139, v138
	v_add_u32_e32 v141, 0x1800, v73
	ds_read_u8 v140, v141
	s_add_i32 s43, s67, 224
	v_mov_b32_e32 v138, s43
	ds_read2st64_b32 v[228:229], v138 offset1:1
	ds_read_b128 v[18:21], v227 offset:12288
	ds_read_b128 v[22:25], v227 offset:12304
	v_add_u32_e32 v152, 0x600000, v63
	v_add_u32_e32 v153, 0x600000, v64
	v_mov_b32_e32 v38, 0
	v_mov_b32_e32 v39, 0
	v_mov_b32_e32 v40, 0
	v_mov_b32_e32 v41, 0
	v_mov_b32_e32 v42, 0
	v_mov_b32_e32 v43, 0
	v_mov_b32_e32 v44, 0
	v_mov_b32_e32 v45, 0
	v_and_b32_e32 v78, 0xffff, v31
	v_lshrrev_b32_e32 v79, 16, v31
	v_lshl_add_u32 v78, v78, 7, v150
	v_lshl_add_u32 v79, v79, 7, v151
	s_mov_b32 m0, s79
	s_add_i32 s43, s79, 0x400
	global_load_lds_dwordx4 v78, s[50:51]
	s_mov_b32 m0, s43
	s_nop 0
	global_load_lds_dwordx4 v79, s[50:51]
	s_waitcnt vmcnt(10)
	v_add_u32_e32 v54, s99, v59
	v_add_u32_e32 v55, s99, v60
	v_add_u32_e32 v56, s99, v61
	v_add_u32_e32 v57, s99, v62
	ds_read_b64_tr_b4 v[50:51], v160 offset:128
	ds_read_b64_tr_b4 v[52:53], v160 offset:1152
	ds_read_b64_tr_b4 v[130:131], v54
	ds_read_b64_tr_b4 v[132:133], v55
	ds_read_b64_tr_b4 v[134:135], v56
	ds_read_b64_tr_b4 v[136:137], v57
	s_waitcnt lgkmcnt(14)
	v_dot8c_i32_i4_e32 v38, v122, v48
	v_dot8c_i32_i4_e32 v39, v122, v46
	v_dot8c_i32_i4_e32 v40, v124, v48
	v_dot8c_i32_i4_e32 v41, v124, v46
	v_dot8c_i32_i4_e32 v42, v126, v48
	v_dot8c_i32_i4_e32 v43, v126, v46
	v_dot8c_i32_i4_e32 v44, v128, v48
	v_dot8c_i32_i4_e32 v45, v128, v46
	v_dot8c_i32_i4_e32 v38, v123, v49
	v_dot8c_i32_i4_e32 v39, v123, v47
	v_dot8c_i32_i4_e32 v40, v125, v49
	v_dot8c_i32_i4_e32 v41, v125, v47
	v_dot8c_i32_i4_e32 v42, v127, v49
	v_dot8c_i32_i4_e32 v43, v127, v47
	v_dot8c_i32_i4_e32 v44, v129, v49
	v_dot8c_i32_i4_e32 v45, v129, v47
	v_and_b32_e32 v78, 0xffff, v32
	v_lshrrev_b32_e32 v79, 16, v32
	v_lshl_add_u32 v78, v78, 7, v150
	v_lshl_add_u32 v79, v79, 7, v151
	s_mov_b32 m0, s98
	s_add_i32 s43, s98, 0x400
	global_load_lds_dwordx4 v78, s[50:51]
	s_mov_b32 m0, s43
	s_nop 0
	global_load_lds_dwordx4 v79, s[50:51]
	s_waitcnt vmcnt(10)
; #define LAS __attribute__((address_space(3)))
; #define TR4(p_) __builtin_amdgcn_ds_read_tr4_b64_v2i32((LAS v2i*)(p_))
; #define CFENCE() asm volatile("" ::: "memory")
; __device__ __forceinline__ void peer_v_tokens(int j, const LAS unsigned short* EL, const LAS unsigned char* AL  , const LAS float* ASC  , const LAS int* SAL  , ...
;     ...
;             const int idx = lane + 64 * m, tau = idx >> 4, sr = idx & 15, k = 16 * (sr & 7) + 2 * tau + (sr >> 3);
;             const int aq = (int)*(const LAS signed char*)(AL + tl * 128 + k); const int tq = aq + 8;
;             const unsigned lo = (((unsigned)tq & 15u) ^ 8u) * 0x11111111u, hi = ((unsigned)(tq >> 4) & 15u) * 0x11111111u;
;             typedef unsigned u2v __attribute__((ext_vector_type(2)));
;             u2v l2; l2.x = lo; l2.y = lo; u2v h2; h2.x = hi; h2.y = hi;
;             *(LAS u2v*)(ATL + 8 * idx) = l2; *(LAS u2v*)(ATL + 1024 + 8 * idx) = h2;
;         }
;         const float asc = ASC[tl]; const int sa = SAL[tl];
;         CFENCE();
;         int accH[4], accL[4];
; #pragma unroll
;         for (int st = 0; st < 16; ++st) {
;             const int p = st >> 2, q = st & 3;
;             if (st < 14) VDMA(st + 2, (st + 2) % 3);
;             if (st < 14) asm volatile("s_waitcnt vmcnt(8)" ::: "memory");
;             else if (st == 14) asm volatile("s_waitcnt vmcnt(4)" ::: "memory");
;             else asm volatile("s_waitcnt vmcnt(0)" ::: "memory");
;             if (q == 0) {
; #pragma unroll
;                 for (int r = 0; r < 4; ++r) { accH[r] = 0; accL[r] = 0; } }
; #pragma unroll
;             for (int tp = 0; tp < 2; ++tp) {
;                 const v2i ao = TR4(ATL + (2 * q + tp) * 128 + 8 * s16), ah = TR4(ATL + 1024 + (2 * q + tp) * 128 + 8 * s16);
; #pragma unroll
;                 for (int r = 0; r < 4; ++r) {
;                     const v2i d = TR4(ldsb + BUF[st % 3] + 2048 * tp + roff[r]);
;                     accH[r] = __builtin_amdgcn_sdot8(d.x, ah.x, accH[r], false); accH[r] = __builtin_amdgcn_sdot8(d.y, ah.y, accH[r], false);
;                     accL[r] = __builtin_amdgcn_sdot8(d.x, ao.x, accL[r], false); accL[r] = __builtin_amdgcn_sdot8(d.y, ao.y, accL[r], false);
;                 }
;             }
;             asm volatile("s_waitcnt lgkmcnt(0)" ::: "memory");
	v_add_u32_e32 v54, s76, v59
	v_add_u32_e32 v55, s76, v60
	v_add_u32_e32 v56, s76, v61
	v_add_u32_e32 v57, s76, v62
	ds_read_b64_tr_b4 v[46:47], v160 offset:256
	ds_read_b64_tr_b4 v[48:49], v160 offset:1280
	ds_read_b64_tr_b4 v[122:123], v54
	ds_read_b64_tr_b4 v[124:125], v55
	ds_read_b64_tr_b4 v[126:127], v56
	ds_read_b64_tr_b4 v[128:129], v57
	s_waitcnt lgkmcnt(6)
	v_dot8c_i32_i4_e32 v38, v130, v52
	v_dot8c_i32_i4_e32 v39, v130, v50
	v_dot8c_i32_i4_e32 v40, v132, v52
	v_dot8c_i32_i4_e32 v41, v132, v50
	v_dot8c_i32_i4_e32 v42, v134, v52
	v_dot8c_i32_i4_e32 v43, v134, v50
	v_dot8c_i32_i4_e32 v44, v136, v52
	v_dot8c_i32_i4_e32 v45, v136, v50
	v_dot8c_i32_i4_e32 v38, v131, v53
	v_dot8c_i32_i4_e32 v39, v131, v51
	v_dot8c_i32_i4_e32 v40, v133, v53
	v_dot8c_i32_i4_e32 v41, v133, v51
	v_dot8c_i32_i4_e32 v42, v135, v53
	v_dot8c_i32_i4_e32 v43, v135, v51
	v_dot8c_i32_i4_e32 v44, v137, v53
	v_dot8c_i32_i4_e32 v45, v137, v51
	v_and_b32_e32 v78, 0xffff, v33
	v_lshrrev_b32_e32 v79, 16, v33
	v_lshl_add_u32 v78, v78, 7, v150
	v_lshl_add_u32 v79, v79, 7, v151
	s_mov_b32 m0, s99
	s_add_i32 s43, s99, 0x400
	global_load_lds_dwordx4 v78, s[50:51]
	s_mov_b32 m0, s43
	s_nop 0
	global_load_lds_dwordx4 v79, s[50:51]
	s_waitcnt vmcnt(10)
	v_add_u32_e32 v54, s77, v59
	v_add_u32_e32 v55, s77, v60
	v_add_u32_e32 v56, s77, v61
	v_add_u32_e32 v57, s77, v62
	ds_read_b64_tr_b4 v[50:51], v160 offset:384
	ds_read_b64_tr_b4 v[52:53], v160 offset:1408
	ds_read_b64_tr_b4 v[130:131], v54
	ds_read_b64_tr_b4 v[132:133], v55
	ds_read_b64_tr_b4 v[134:135], v56
	ds_read_b64_tr_b4 v[136:137], v57
	s_waitcnt lgkmcnt(6)
	v_dot8c_i32_i4_e32 v38, v122, v48
	v_dot8c_i32_i4_e32 v39, v122, v46
	v_dot8c_i32_i4_e32 v40, v124, v48
	v_dot8c_i32_i4_e32 v41, v124, v46
	v_dot8c_i32_i4_e32 v42, v126, v48
	v_dot8c_i32_i4_e32 v43, v126, v46
	v_dot8c_i32_i4_e32 v44, v128, v48
	v_dot8c_i32_i4_e32 v45, v128, v46
	v_dot8c_i32_i4_e32 v38, v123, v49
	v_dot8c_i32_i4_e32 v39, v123, v47
	v_dot8c_i32_i4_e32 v40, v125, v49
	v_dot8c_i32_i4_e32 v41, v125, v47
	v_dot8c_i32_i4_e32 v42, v127, v49
	v_dot8c_i32_i4_e32 v43, v127, v47
	v_dot8c_i32_i4_e32 v44, v129, v49
	v_dot8c_i32_i4_e32 v45, v129, v47
	s_waitcnt lgkmcnt(15)
	v_and_b32_e32 v78, 0xffff, v18
	v_lshrrev_b32_e32 v79, 16, v18
	v_lshl_add_u32 v78, v78, 7, v152
	v_lshl_add_u32 v79, v79, 7, v153
	s_mov_b32 m0, s76
	s_add_i32 s43, s76, 0x400
	global_load_lds_dwordx4 v78, s[50:51]
	s_mov_b32 m0, s43
	s_nop 0
	global_load_lds_dwordx4 v79, s[50:51]
	s_waitcnt vmcnt(10)
	v_add_u32_e32 v54, s78, v59
	v_add_u32_e32 v55, s78, v60
	v_add_u32_e32 v56, s78, v61
	v_add_u32_e32 v57, s78, v62
	ds_read_b64_tr_b4 v[46:47], v160 offset:512
	ds_read_b64_tr_b4 v[48:49], v160 offset:1536
	ds_read_b64_tr_b4 v[122:123], v54
	ds_read_b64_tr_b4 v[124:125], v55
	ds_read_b64_tr_b4 v[126:127], v56
	ds_read_b64_tr_b4 v[128:129], v57
	s_waitcnt lgkmcnt(6)
	v_dot8c_i32_i4_e32 v38, v130, v52
	v_dot8c_i32_i4_e32 v39, v130, v50
	v_dot8c_i32_i4_e32 v40, v132, v52
	v_dot8c_i32_i4_e32 v41, v132, v50
	v_dot8c_i32_i4_e32 v42, v134, v52
	v_dot8c_i32_i4_e32 v43, v134, v50
	v_dot8c_i32_i4_e32 v44, v136, v52
	v_dot8c_i32_i4_e32 v45, v136, v50
	v_dot8c_i32_i4_e32 v38, v131, v53
	v_dot8c_i32_i4_e32 v39, v131, v51
	v_dot8c_i32_i4_e32 v40, v133, v53
	v_dot8c_i32_i4_e32 v41, v133, v51
	v_dot8c_i32_i4_e32 v42, v135, v53
	v_dot8c_i32_i4_e32 v43, v135, v51
	v_dot8c_i32_i4_e32 v44, v137, v53
	v_dot8c_i32_i4_e32 v45, v137, v51
	v_and_b32_e32 v78, 0xffff, v19
	v_lshrrev_b32_e32 v79, 16, v19
	v_lshl_add_u32 v78, v78, 7, v152
	v_lshl_add_u32 v79, v79, 7, v153
	s_mov_b32 m0, s77
	s_add_i32 s43, s77, 0x400
	global_load_lds_dwordx4 v78, s[50:51]
	s_mov_b32 m0, s43
	s_nop 0
	global_load_lds_dwordx4 v79, s[50:51]
	s_waitcnt vmcnt(8)
	v_add_u32_e32 v54, s79, v59
	v_add_u32_e32 v55, s79, v60
	v_add_u32_e32 v56, s79, v61
	v_add_u32_e32 v57, s79, v62
	ds_read_b64_tr_b4 v[50:51], v160 offset:640
	ds_read_b64_tr_b4 v[52:53], v160 offset:1664
	ds_read_b64_tr_b4 v[130:131], v54
	ds_read_b64_tr_b4 v[132:133], v55
	ds_read_b64_tr_b4 v[134:135], v56
	ds_read_b64_tr_b4 v[136:137], v57
	s_waitcnt lgkmcnt(6)
	v_dot8c_i32_i4_e32 v38, v122, v48
	v_dot8c_i32_i4_e32 v39, v122, v46
	v_dot8c_i32_i4_e32 v40, v124, v48
	v_dot8c_i32_i4_e32 v41, v124, v46
	v_dot8c_i32_i4_e32 v42, v126, v48
	v_dot8c_i32_i4_e32 v43, v126, v46
	v_dot8c_i32_i4_e32 v44, v128, v48
	v_dot8c_i32_i4_e32 v45, v128, v46
	v_dot8c_i32_i4_e32 v38, v123, v49
	v_dot8c_i32_i4_e32 v39, v123, v47
	v_dot8c_i32_i4_e32 v40, v125, v49
	v_dot8c_i32_i4_e32 v41, v125, v47
	v_dot8c_i32_i4_e32 v42, v127, v49
	v_dot8c_i32_i4_e32 v43, v127, v47
	v_dot8c_i32_i4_e32 v44, v129, v49
	v_dot8c_i32_i4_e32 v45, v129, v47
	s_waitcnt lgkmcnt(15)
	v_add_u32_e32 v143, 8, v139
	v_and_b32_e32 v142, 15, v143
	v_xor_b32_e32 v142, 8, v142
	v_bfe_u32 v144, v143, 4, 4
	v_mul_lo_u32 v142, v142, s92
	v_mul_lo_u32 v144, v144, s92
	v_mov_b32_e32 v143, v142
	v_mov_b32_e32 v145, v144
	ds_write2st64_b64 v159, v[142:143], v[144:145] offset1:2
	v_and_b32_e32 v78, 0xffff, v20
	v_lshrrev_b32_e32 v79, 16, v20
	v_lshl_add_u32 v78, v78, 7, v152
	v_lshl_add_u32 v79, v79, 7, v153
	s_mov_b32 m0, s78
	s_add_i32 s43, s78, 0x400
	global_load_lds_dwordx4 v78, s[50:51]
	s_mov_b32 m0, s43
	s_nop 0
	global_load_lds_dwordx4 v79, s[50:51]
	s_waitcnt vmcnt(8)
	v_add_u32_e32 v54, s98, v59
	v_add_u32_e32 v55, s98, v60
	v_add_u32_e32 v56, s98, v61
	v_add_u32_e32 v57, s98, v62
	ds_read_b64_tr_b4 v[46:47], v160 offset:768
	ds_read_b64_tr_b4 v[48:49], v160 offset:1792
	ds_read_b64_tr_b4 v[122:123], v54
	ds_read_b64_tr_b4 v[124:125], v55
	ds_read_b64_tr_b4 v[126:127], v56
	ds_read_b64_tr_b4 v[128:129], v57
	s_waitcnt lgkmcnt(7)
; __device__ __forceinline__ void peer_v_tokens(int j, const LAS unsigned short* EL, const LAS unsigned char* AL  , const LAS float* ASC  , const LAS int* SAL  , ...
;     ...
;             const int idx = lane + 64 * m, tau = idx >> 4, sr = idx & 15, k = 16 * (sr & 7) + 2 * tau + (sr >> 3);
;             const int aq = (int)*(const LAS signed char*)(AL + tl * 128 + k); const int tq = aq + 8;
;             const unsigned lo = (((unsigned)tq & 15u) ^ 8u) * 0x11111111u, hi = ((unsigned)(tq >> 4) & 15u) * 0x11111111u;
;             typedef unsigned u2v __attribute__((ext_vector_type(2)));
;             u2v l2; l2.x = lo; l2.y = lo; u2v h2; h2.x = hi; h2.y = hi;
;             *(LAS u2v*)(ATL + 8 * idx) = l2; *(LAS u2v*)(ATL + 1024 + 8 * idx) = h2;
;         }
;         const float asc = ASC[tl]; const int sa = SAL[tl];
;         CFENCE();
;         int accH[4], accL[4];
; #pragma unroll
;         for (int st = 0; st < 16; ++st) {
;             const int p = st >> 2, q = st & 3;
;             if (st < 14) VDMA(st + 2, (st + 2) % 3);
;             if (st < 14) asm volatile("s_waitcnt vmcnt(8)" ::: "memory");
;             else if (st == 14) asm volatile("s_waitcnt vmcnt(4)" ::: "memory");
;             else asm volatile("s_waitcnt vmcnt(0)" ::: "memory");
;             if (q == 0) {
; #pragma unroll
;                 for (int r = 0; r < 4; ++r) { accH[r] = 0; accL[r] = 0; } }
; #pragma unroll
;             for (int tp = 0; tp < 2; ++tp) {
;                 const v2i ao = TR4(ATL + (2 * q + tp) * 128 + 8 * s16), ah = TR4(ATL + 1024 + (2 * q + tp) * 128 + 8 * s16);
; #pragma unroll
;                 for (int r = 0; r < 4; ++r) {
;                     const v2i d = TR4(ldsb + BUF[st % 3] + 2048 * tp + roff[r]);
;                     accH[r] = __builtin_amdgcn_sdot8(d.x, ah.x, accH[r], false); accH[r] = __builtin_amdgcn_sdot8(d.y, ah.y, accH[r], false);
;                     accL[r] = __builtin_amdgcn_sdot8(d.x, ao.x, accL[r], false); accL[r] = __builtin_amdgcn_sdot8(d.y, ao.y, accL[r], false);
;                 }
;             }
;             asm volatile("s_waitcnt lgkmcnt(0)" ::: "memory");
;             if (q == 3) {
; #pragma unroll
;                 for (int r = 0; r < 4; ++r) STASH[256 * p + 16 * (grp + 4 * r) + pc] = f2bf(asc * (float)(2 * ((accH[r] << 4) + accL[r]) + sa));
;             }
;         }
;         CFENCE();
;         {
	v_dot8c_i32_i4_e32 v38, v130, v52
	v_dot8c_i32_i4_e32 v39, v130, v50
	v_dot8c_i32_i4_e32 v40, v132, v52
	v_dot8c_i32_i4_e32 v41, v132, v50
	v_dot8c_i32_i4_e32 v42, v134, v52
	v_dot8c_i32_i4_e32 v43, v134, v50
	v_dot8c_i32_i4_e32 v44, v136, v52
	v_dot8c_i32_i4_e32 v45, v136, v50
	v_dot8c_i32_i4_e32 v38, v131, v53
	v_dot8c_i32_i4_e32 v39, v131, v51
	v_dot8c_i32_i4_e32 v40, v133, v53
	v_dot8c_i32_i4_e32 v41, v133, v51
	v_dot8c_i32_i4_e32 v42, v135, v53
	v_dot8c_i32_i4_e32 v43, v135, v51
	v_dot8c_i32_i4_e32 v44, v137, v53
	v_dot8c_i32_i4_e32 v45, v137, v51
	v_and_b32_e32 v78, 0xffff, v21
	v_lshrrev_b32_e32 v79, 16, v21
	v_lshl_add_u32 v78, v78, 7, v152
	v_lshl_add_u32 v79, v79, 7, v153
	s_mov_b32 m0, s79
	s_add_i32 s43, s79, 0x400
	global_load_lds_dwordx4 v78, s[50:51]
	s_mov_b32 m0, s43
	s_nop 0
	global_load_lds_dwordx4 v79, s[50:51]
	s_waitcnt vmcnt(8)
	v_add_u32_e32 v54, s99, v59
	v_add_u32_e32 v55, s99, v60
	v_add_u32_e32 v56, s99, v61
	v_add_u32_e32 v57, s99, v62
	ds_read_b64_tr_b4 v[50:51], v160 offset:896
	ds_read_b64_tr_b4 v[52:53], v160 offset:1920
	ds_read_b64_tr_b4 v[130:131], v54
	ds_read_b64_tr_b4 v[132:133], v55
	ds_read_b64_tr_b4 v[134:135], v56
	ds_read_b64_tr_b4 v[136:137], v57
	s_waitcnt lgkmcnt(6)
	v_dot8c_i32_i4_e32 v38, v122, v48
	v_dot8c_i32_i4_e32 v39, v122, v46
	v_dot8c_i32_i4_e32 v40, v124, v48
	v_dot8c_i32_i4_e32 v41, v124, v46
	v_dot8c_i32_i4_e32 v42, v126, v48
	v_dot8c_i32_i4_e32 v43, v126, v46
	v_dot8c_i32_i4_e32 v44, v128, v48
	v_dot8c_i32_i4_e32 v45, v128, v46
	v_dot8c_i32_i4_e32 v38, v123, v49
	v_dot8c_i32_i4_e32 v39, v123, v47
	v_dot8c_i32_i4_e32 v40, v125, v49
	v_dot8c_i32_i4_e32 v41, v125, v47
	v_dot8c_i32_i4_e32 v42, v127, v49
	v_dot8c_i32_i4_e32 v43, v127, v47
	v_dot8c_i32_i4_e32 v44, v129, v49
	v_dot8c_i32_i4_e32 v45, v129, v47
	v_and_b32_e32 v78, 0xffff, v22
	v_lshrrev_b32_e32 v79, 16, v22
	v_lshl_add_u32 v78, v78, 7, v152
	v_lshl_add_u32 v79, v79, 7, v153
	s_mov_b32 m0, s98
	s_add_i32 s43, s98, 0x400
	global_load_lds_dwordx4 v78, s[50:51]
	s_mov_b32 m0, s43
	s_nop 0
	global_load_lds_dwordx4 v79, s[50:51]
	s_waitcnt vmcnt(8)
	v_add_u32_e32 v54, s76, v59
	v_add_u32_e32 v55, s76, v60
	v_add_u32_e32 v56, s76, v61
	v_add_u32_e32 v57, s76, v62
	ds_read_b64_tr_b4 v[46:47], v160
	ds_read_b64_tr_b4 v[48:49], v160 offset:1024
	ds_read_b64_tr_b4 v[122:123], v54
	ds_read_b64_tr_b4 v[124:125], v55
	ds_read_b64_tr_b4 v[126:127], v56
	ds_read_b64_tr_b4 v[128:129], v57
	s_waitcnt lgkmcnt(6)
	v_dot8c_i32_i4_e32 v38, v130, v52
	v_dot8c_i32_i4_e32 v39, v130, v50
	v_dot8c_i32_i4_e32 v40, v132, v52
	v_dot8c_i32_i4_e32 v41, v132, v50
	v_dot8c_i32_i4_e32 v42, v134, v52
	v_dot8c_i32_i4_e32 v43, v134, v50
	v_dot8c_i32_i4_e32 v44, v136, v52
	v_dot8c_i32_i4_e32 v45, v136, v50
	v_dot8c_i32_i4_e32 v38, v131, v53
	v_dot8c_i32_i4_e32 v39, v131, v51
	v_dot8c_i32_i4_e32 v40, v133, v53
	v_dot8c_i32_i4_e32 v41, v133, v51
	v_dot8c_i32_i4_e32 v42, v135, v53
	v_dot8c_i32_i4_e32 v43, v135, v51
	v_dot8c_i32_i4_e32 v44, v137, v53
	v_dot8c_i32_i4_e32 v45, v137, v51
	s_nop 3
	s_waitcnt lgkmcnt(15)
	v_lshlrev_b32_e32 v38, 5, v38
	v_lshlrev_b32_e32 v39, 1, v39
	v_add3_u32 v38, v39, v229, v38
	v_cvt_f32_i32_e32 v38, v38
	v_mul_f32_e32 v38, v228, v38
	v_lshlrev_b32_e32 v40, 5, v40
	v_lshlrev_b32_e32 v41, 1, v41
	v_add3_u32 v40, v41, v229, v40
	v_cvt_f32_i32_e32 v40, v40
	v_mul_f32_e32 v40, v228, v40
	v_lshlrev_b32_e32 v42, 5, v42
	v_lshlrev_b32_e32 v43, 1, v43
	v_add3_u32 v42, v43, v229, v42
	v_cvt_f32_i32_e32 v42, v42
	v_mul_f32_e32 v42, v228, v42
	v_lshlrev_b32_e32 v44, 5, v44
	v_lshlrev_b32_e32 v45, 1, v45
	v_add3_u32 v44, v45, v229, v44
	v_cvt_f32_i32_e32 v44, v44
	v_mul_f32_e32 v44, v228, v44
	v_cvt_pk_bf16_f32 v190, v38, v40
	v_cvt_pk_bf16_f32 v191, v42, v44
	ds_read_b128 v[252:255], v155 offset:1024
	s_add_i32 s44, s40, 40
	s_ashr_i32 s45, s44, 31
	s_lshl_b64 s[44:45], s[44:45], 12
	v_lshl_add_u64 v[80:81], v[36:37], 0, s[44:45]
	s_waitcnt lgkmcnt(0)
	v_mul_f32_e32 v240, v240, v252
	v_mul_f32_e32 v241, v241, v253
	v_mul_f32_e32 v242, v242, v254
	v_mul_f32_e32 v243, v243, v255
	global_store_dwordx4 v[80:81], v[240:243], off offset:1024 nt
	v_add_u32_e32 v147, 8, v140
	v_and_b32_e32 v146, 15, v147
	v_xor_b32_e32 v146, 8, v146
	v_bfe_u32 v148, v147, 4, 4
	v_mul_lo_u32 v146, v146, s92
	v_mul_lo_u32 v148, v148, s92
	v_mov_b32_e32 v147, v146
	v_mov_b32_e32 v149, v148
	ds_write2st64_b64 v77, v[146:147], v[148:149] offset1:2
	v_add_u32_e32 v138, 0x1c00, v74
	ds_read_u8 v139, v138
	v_add_u32_e32 v141, 0x1c00, v73
	ds_read_u8 v140, v141
	s_add_i32 s43, s67, 192
	v_mov_b32_e32 v138, s43
	ds_read2st64_b32 v[228:229], v138 offset1:1
	ds_read_b128 v[26:29], v227 offset:14336
	ds_read_b128 v[30:33], v227 offset:14352
	v_mov_b32_e32 v38, 0
	v_mov_b32_e32 v39, 0
	v_mov_b32_e32 v40, 0
	v_mov_b32_e32 v41, 0
	v_mov_b32_e32 v42, 0
	v_mov_b32_e32 v43, 0
	v_mov_b32_e32 v44, 0
	v_mov_b32_e32 v45, 0
	v_and_b32_e32 v78, 0xffff, v23
	v_lshrrev_b32_e32 v79, 16, v23
	v_lshl_add_u32 v78, v78, 7, v152
	v_lshl_add_u32 v79, v79, 7, v153
	s_mov_b32 m0, s99
	s_add_i32 s43, s99, 0x400
	global_load_lds_dwordx4 v78, s[50:51]
	s_mov_b32 m0, s43
	s_nop 0
	global_load_lds_dwordx4 v79, s[50:51]
	s_waitcnt vmcnt(9)
	v_add_u32_e32 v54, s77, v59
	v_add_u32_e32 v55, s77, v60
	v_add_u32_e32 v56, s77, v61
	v_add_u32_e32 v57, s77, v62
	ds_read_b64_tr_b4 v[50:51], v160 offset:128
	ds_read_b64_tr_b4 v[52:53], v160 offset:1152
	ds_read_b64_tr_b4 v[130:131], v54
	ds_read_b64_tr_b4 v[132:133], v55
	ds_read_b64_tr_b4 v[134:135], v56
	ds_read_b64_tr_b4 v[136:137], v57
	s_waitcnt lgkmcnt(13)
; #define TR4(p_) __builtin_amdgcn_ds_read_tr4_b64_v2i32((LAS v2i*)(p_))
; #define VDMA(st_, k_) do { _Pragma("unroll") for (int i_ = 0; i_ < 4; ++i_) { \
;         const unsigned off_ = (unsigned)((st_) >> 2) * (16384u * 128u) + (PE_ID(E, 4 * ((st_) & 3) + i_) << 7) + ((i_ & 1) ? cx1 : cx0); \
;         __builtin_amdgcn_global_load_lds((const unsigned*)(V4 + off_), (LAS unsigned*)(ldsb + BUF[k_] + 1024 * i_), 16, 0, 0); } } while (0)
; __device__ __forceinline__ void peer_v_tokens(int j, const LAS unsigned short* EL, const LAS unsigned char* AL  , const LAS float* ASC  , const LAS int* SAL  , ...
;     ...
;         for (int st = 0; st < 16; ++st) {
;             const int p = st >> 2, q = st & 3;
;             if (st < 14) VDMA(st + 2, (st + 2) % 3);
;             if (st < 14) asm volatile("s_waitcnt vmcnt(8)" ::: "memory");
;             else if (st == 14) asm volatile("s_waitcnt vmcnt(4)" ::: "memory");
;             else asm volatile("s_waitcnt vmcnt(0)" ::: "memory");
;             if (q == 0) {
; #pragma unroll
;                 for (int r = 0; r < 4; ++r) { accH[r] = 0; accL[r] = 0; } }
; #pragma unroll
;             for (int tp = 0; tp < 2; ++tp) {
;                 const v2i ao = TR4(ATL + (2 * q + tp) * 128 + 8 * s16), ah = TR4(ATL + 1024 + (2 * q + tp) * 128 + 8 * s16);
; #pragma unroll
;                 for (int r = 0; r < 4; ++r) {
;                     const v2i d = TR4(ldsb + BUF[st % 3] + 2048 * tp + roff[r]);
;                     accH[r] = __builtin_amdgcn_sdot8(d.x, ah.x, accH[r], false); accH[r] = __builtin_amdgcn_sdot8(d.y, ah.y, accH[r], false);
;                     accL[r] = __builtin_amdgcn_sdot8(d.x, ao.x, accL[r], false); accL[r] = __builtin_amdgcn_sdot8(d.y, ao.y, accL[r], false);
;                 }
;             }
;             asm volatile("s_waitcnt lgkmcnt(0)" ::: "memory");
	v_dot8c_i32_i4_e32 v38, v122, v48
	v_dot8c_i32_i4_e32 v39, v122, v46
	v_dot8c_i32_i4_e32 v40, v124, v48
	v_dot8c_i32_i4_e32 v41, v124, v46
	v_dot8c_i32_i4_e32 v42, v126, v48
	v_dot8c_i32_i4_e32 v43, v126, v46
	v_dot8c_i32_i4_e32 v44, v128, v48
	v_dot8c_i32_i4_e32 v45, v128, v46
	v_dot8c_i32_i4_e32 v38, v123, v49
	v_dot8c_i32_i4_e32 v39, v123, v47
	v_dot8c_i32_i4_e32 v40, v125, v49
	v_dot8c_i32_i4_e32 v41, v125, v47
	v_dot8c_i32_i4_e32 v42, v127, v49
	v_dot8c_i32_i4_e32 v43, v127, v47
	v_dot8c_i32_i4_e32 v44, v129, v49
	v_dot8c_i32_i4_e32 v45, v129, v47
	v_and_b32_e32 v78, 0xffff, v24
	v_lshrrev_b32_e32 v79, 16, v24
	v_lshl_add_u32 v78, v78, 7, v152
	v_lshl_add_u32 v79, v79, 7, v153
	s_mov_b32 m0, s76
	s_add_i32 s43, s76, 0x400
	global_load_lds_dwordx4 v78, s[50:51]
	s_mov_b32 m0, s43
	s_nop 0
	global_load_lds_dwordx4 v79, s[50:51]
	s_waitcnt vmcnt(9)
	v_add_u32_e32 v54, s78, v59
	v_add_u32_e32 v55, s78, v60
	v_add_u32_e32 v56, s78, v61
	v_add_u32_e32 v57, s78, v62
	ds_read_b64_tr_b4 v[46:47], v160 offset:256
	ds_read_b64_tr_b4 v[48:49], v160 offset:1280
	ds_read_b64_tr_b4 v[122:123], v54
	ds_read_b64_tr_b4 v[124:125], v55
	ds_read_b64_tr_b4 v[126:127], v56
	ds_read_b64_tr_b4 v[128:129], v57
	s_waitcnt lgkmcnt(6)
	v_dot8c_i32_i4_e32 v38, v130, v52
	v_dot8c_i32_i4_e32 v39, v130, v50
	v_dot8c_i32_i4_e32 v40, v132, v52
	v_dot8c_i32_i4_e32 v41, v132, v50
	v_dot8c_i32_i4_e32 v42, v134, v52
	v_dot8c_i32_i4_e32 v43, v134, v50
	v_dot8c_i32_i4_e32 v44, v136, v52
	v_dot8c_i32_i4_e32 v45, v136, v50
	v_dot8c_i32_i4_e32 v38, v131, v53
	v_dot8c_i32_i4_e32 v39, v131, v51
	v_dot8c_i32_i4_e32 v40, v133, v53
	v_dot8c_i32_i4_e32 v41, v133, v51
	v_dot8c_i32_i4_e32 v42, v135, v53
	v_dot8c_i32_i4_e32 v43, v135, v51
	v_dot8c_i32_i4_e32 v44, v137, v53
	v_dot8c_i32_i4_e32 v45, v137, v51
	v_and_b32_e32 v78, 0xffff, v25
	v_lshrrev_b32_e32 v79, 16, v25
	v_lshl_add_u32 v78, v78, 7, v152
	v_lshl_add_u32 v79, v79, 7, v153
	s_mov_b32 m0, s77
	s_add_i32 s43, s77, 0x400
	global_load_lds_dwordx4 v78, s[50:51]
	s_mov_b32 m0, s43
	s_nop 0
	global_load_lds_dwordx4 v79, s[50:51]
	s_waitcnt vmcnt(9)
	v_add_u32_e32 v54, s79, v59
	v_add_u32_e32 v55, s79, v60
	v_add_u32_e32 v56, s79, v61
	v_add_u32_e32 v57, s79, v62
	ds_read_b64_tr_b4 v[50:51], v160 offset:384
	ds_read_b64_tr_b4 v[52:53], v160 offset:1408
	ds_read_b64_tr_b4 v[130:131], v54
	ds_read_b64_tr_b4 v[132:133], v55
	ds_read_b64_tr_b4 v[134:135], v56
	ds_read_b64_tr_b4 v[136:137], v57
	s_waitcnt lgkmcnt(6)
	v_dot8c_i32_i4_e32 v38, v122, v48
	v_dot8c_i32_i4_e32 v39, v122, v46
	v_dot8c_i32_i4_e32 v40, v124, v48
	v_dot8c_i32_i4_e32 v41, v124, v46
	v_dot8c_i32_i4_e32 v42, v126, v48
	v_dot8c_i32_i4_e32 v43, v126, v46
	v_dot8c_i32_i4_e32 v44, v128, v48
	v_dot8c_i32_i4_e32 v45, v128, v46
	v_dot8c_i32_i4_e32 v38, v123, v49
	v_dot8c_i32_i4_e32 v39, v123, v47
	v_dot8c_i32_i4_e32 v40, v125, v49
	v_dot8c_i32_i4_e32 v41, v125, v47
	v_dot8c_i32_i4_e32 v42, v127, v49
	v_dot8c_i32_i4_e32 v43, v127, v47
	v_dot8c_i32_i4_e32 v44, v129, v49
	v_dot8c_i32_i4_e32 v45, v129, v47
	s_waitcnt lgkmcnt(15)
	v_and_b32_e32 v78, 0xffff, v26
	v_lshrrev_b32_e32 v79, 16, v26
	v_lshl_add_u32 v78, v78, 7, v152
	v_lshl_add_u32 v79, v79, 7, v153
	s_mov_b32 m0, s78
	s_add_i32 s43, s78, 0x400
	global_load_lds_dwordx4 v78, s[50:51]
	s_mov_b32 m0, s43
	s_nop 0
	global_load_lds_dwordx4 v79, s[50:51]
	s_waitcnt vmcnt(9)
	v_add_u32_e32 v54, s98, v59
	v_add_u32_e32 v55, s98, v60
	v_add_u32_e32 v56, s98, v61
	v_add_u32_e32 v57, s98, v62
	ds_read_b64_tr_b4 v[46:47], v160 offset:512
	ds_read_b64_tr_b4 v[48:49], v160 offset:1536
	ds_read_b64_tr_b4 v[122:123], v54
	ds_read_b64_tr_b4 v[124:125], v55
	ds_read_b64_tr_b4 v[126:127], v56
	ds_read_b64_tr_b4 v[128:129], v57
	s_waitcnt lgkmcnt(6)
	v_dot8c_i32_i4_e32 v38, v130, v52
	v_dot8c_i32_i4_e32 v39, v130, v50
	v_dot8c_i32_i4_e32 v40, v132, v52
	v_dot8c_i32_i4_e32 v41, v132, v50
	v_dot8c_i32_i4_e32 v42, v134, v52
	v_dot8c_i32_i4_e32 v43, v134, v50
	v_dot8c_i32_i4_e32 v44, v136, v52
	v_dot8c_i32_i4_e32 v45, v136, v50
	v_dot8c_i32_i4_e32 v38, v131, v53
	v_dot8c_i32_i4_e32 v39, v131, v51
	v_dot8c_i32_i4_e32 v40, v133, v53
	v_dot8c_i32_i4_e32 v41, v133, v51
	v_dot8c_i32_i4_e32 v42, v135, v53
	v_dot8c_i32_i4_e32 v43, v135, v51
	v_dot8c_i32_i4_e32 v44, v137, v53
	v_dot8c_i32_i4_e32 v45, v137, v51
	v_and_b32_e32 v78, 0xffff, v27
	v_lshrrev_b32_e32 v79, 16, v27
	v_lshl_add_u32 v78, v78, 7, v152
	v_lshl_add_u32 v79, v79, 7, v153
	s_mov_b32 m0, s79
	s_add_i32 s43, s79, 0x400
	global_load_lds_dwordx4 v78, s[50:51]
	s_mov_b32 m0, s43
	s_nop 0
	global_load_lds_dwordx4 v79, s[50:51]
	s_waitcnt vmcnt(8)
	v_add_u32_e32 v54, s99, v59
	v_add_u32_e32 v55, s99, v60
	v_add_u32_e32 v56, s99, v61
	v_add_u32_e32 v57, s99, v62
	ds_read_b64_tr_b4 v[50:51], v160 offset:640
	ds_read_b64_tr_b4 v[52:53], v160 offset:1664
	ds_read_b64_tr_b4 v[130:131], v54
	ds_read_b64_tr_b4 v[132:133], v55
	ds_read_b64_tr_b4 v[134:135], v56
	ds_read_b64_tr_b4 v[136:137], v57
	s_waitcnt lgkmcnt(6)
	v_dot8c_i32_i4_e32 v38, v122, v48
	v_dot8c_i32_i4_e32 v39, v122, v46
	v_dot8c_i32_i4_e32 v40, v124, v48
	v_dot8c_i32_i4_e32 v41, v124, v46
	v_dot8c_i32_i4_e32 v42, v126, v48
	v_dot8c_i32_i4_e32 v43, v126, v46
	v_dot8c_i32_i4_e32 v44, v128, v48
	v_dot8c_i32_i4_e32 v45, v128, v46
	v_dot8c_i32_i4_e32 v38, v123, v49
	v_dot8c_i32_i4_e32 v39, v123, v47
	v_dot8c_i32_i4_e32 v40, v125, v49
	v_dot8c_i32_i4_e32 v41, v125, v47
	v_dot8c_i32_i4_e32 v42, v127, v49
	v_dot8c_i32_i4_e32 v43, v127, v47
	v_dot8c_i32_i4_e32 v44, v129, v49
	v_dot8c_i32_i4_e32 v45, v129, v47
	s_waitcnt lgkmcnt(15)
; __device__ __forceinline__ void peer_v_tokens(int j, const LAS unsigned short* EL, const LAS unsigned char* AL  , const LAS float* ASC  , const LAS int* SAL  , ...
;     ...
;             const int idx = lane + 64 * m, tau = idx >> 4, sr = idx & 15, k = 16 * (sr & 7) + 2 * tau + (sr >> 3);
;             const int aq = (int)*(const LAS signed char*)(AL + tl * 128 + k); const int tq = aq + 8;
;             const unsigned lo = (((unsigned)tq & 15u) ^ 8u) * 0x11111111u, hi = ((unsigned)(tq >> 4) & 15u) * 0x11111111u;
;             typedef unsigned u2v __attribute__((ext_vector_type(2)));
;             u2v l2; l2.x = lo; l2.y = lo; u2v h2; h2.x = hi; h2.y = hi;
;             *(LAS u2v*)(ATL + 8 * idx) = l2; *(LAS u2v*)(ATL + 1024 + 8 * idx) = h2;
;         }
;         const float asc = ASC[tl]; const int sa = SAL[tl];
;         CFENCE();
;         int accH[4], accL[4];
; #pragma unroll
;         for (int st = 0; st < 16; ++st) {
;             const int p = st >> 2, q = st & 3;
;             if (st < 14) VDMA(st + 2, (st + 2) % 3);
;             if (st < 14) asm volatile("s_waitcnt vmcnt(8)" ::: "memory");
;             else if (st == 14) asm volatile("s_waitcnt vmcnt(4)" ::: "memory");
;             else asm volatile("s_waitcnt vmcnt(0)" ::: "memory");
;             if (q == 0) {
; #pragma unroll
;                 for (int r = 0; r < 4; ++r) { accH[r] = 0; accL[r] = 0; } }
; #pragma unroll
;             for (int tp = 0; tp < 2; ++tp) {
;                 const v2i ao = TR4(ATL + (2 * q + tp) * 128 + 8 * s16), ah = TR4(ATL + 1024 + (2 * q + tp) * 128 + 8 * s16);
; #pragma unroll
;                 for (int r = 0; r < 4; ++r) {
;                     const v2i d = TR4(ldsb + BUF[st % 3] + 2048 * tp + roff[r]);
;                     accH[r] = __builtin_amdgcn_sdot8(d.x, ah.x, accH[r], false); accH[r] = __builtin_amdgcn_sdot8(d.y, ah.y, accH[r], false);
;                     accL[r] = __builtin_amdgcn_sdot8(d.x, ao.x, accL[r], false); accL[r] = __builtin_amdgcn_sdot8(d.y, ao.y, accL[r], false);
;                 }
;             }
;             asm volatile("s_waitcnt lgkmcnt(0)" ::: "memory");
;             if (q == 3) {
; #pragma unroll
;                 for (int r = 0; r < 4; ++r) STASH[256 * p + 16 * (grp + 4 * r) + pc] = f2bf(asc * (float)(2 * ((accH[r] << 4) + accL[r]) + sa));
;             }
;         }
;         CFENCE();
;         {
	v_add_u32_e32 v143, 8, v139
	v_and_b32_e32 v142, 15, v143
	v_xor_b32_e32 v142, 8, v142
	v_bfe_u32 v144, v143, 4, 4
	v_mul_lo_u32 v142, v142, s92
	v_mul_lo_u32 v144, v144, s92
	v_mov_b32_e32 v143, v142
	v_mov_b32_e32 v145, v144
	ds_write2st64_b64 v159, v[142:143], v[144:145] offset1:2
	v_and_b32_e32 v78, 0xffff, v28
	v_lshrrev_b32_e32 v79, 16, v28
	v_lshl_add_u32 v78, v78, 7, v152
	v_lshl_add_u32 v79, v79, 7, v153
	s_mov_b32 m0, s98
	s_add_i32 s43, s98, 0x400
	global_load_lds_dwordx4 v78, s[50:51]
	s_mov_b32 m0, s43
	s_nop 0
	global_load_lds_dwordx4 v79, s[50:51]
	s_waitcnt vmcnt(8)
	v_add_u32_e32 v54, s76, v59
	v_add_u32_e32 v55, s76, v60
	v_add_u32_e32 v56, s76, v61
	v_add_u32_e32 v57, s76, v62
	ds_read_b64_tr_b4 v[46:47], v160 offset:768
	ds_read_b64_tr_b4 v[48:49], v160 offset:1792
	ds_read_b64_tr_b4 v[122:123], v54
	ds_read_b64_tr_b4 v[124:125], v55
	ds_read_b64_tr_b4 v[126:127], v56
	ds_read_b64_tr_b4 v[128:129], v57
	s_waitcnt lgkmcnt(7)
	v_dot8c_i32_i4_e32 v38, v130, v52
	v_dot8c_i32_i4_e32 v39, v130, v50
	v_dot8c_i32_i4_e32 v40, v132, v52
	v_dot8c_i32_i4_e32 v41, v132, v50
	v_dot8c_i32_i4_e32 v42, v134, v52
	v_dot8c_i32_i4_e32 v43, v134, v50
	v_dot8c_i32_i4_e32 v44, v136, v52
	v_dot8c_i32_i4_e32 v45, v136, v50
	v_dot8c_i32_i4_e32 v38, v131, v53
	v_dot8c_i32_i4_e32 v39, v131, v51
	v_dot8c_i32_i4_e32 v40, v133, v53
	v_dot8c_i32_i4_e32 v41, v133, v51
	v_dot8c_i32_i4_e32 v42, v135, v53
	v_dot8c_i32_i4_e32 v43, v135, v51
	v_dot8c_i32_i4_e32 v44, v137, v53
	v_dot8c_i32_i4_e32 v45, v137, v51
	v_and_b32_e32 v78, 0xffff, v29
	v_lshrrev_b32_e32 v79, 16, v29
	v_lshl_add_u32 v78, v78, 7, v152
	v_lshl_add_u32 v79, v79, 7, v153
	s_mov_b32 m0, s99
	s_add_i32 s43, s99, 0x400
	global_load_lds_dwordx4 v78, s[50:51]
	s_mov_b32 m0, s43
	s_nop 0
	global_load_lds_dwordx4 v79, s[50:51]
	s_waitcnt vmcnt(8)
	v_add_u32_e32 v54, s77, v59
	v_add_u32_e32 v55, s77, v60
	v_add_u32_e32 v56, s77, v61
	v_add_u32_e32 v57, s77, v62
	ds_read_b64_tr_b4 v[50:51], v160 offset:896
	ds_read_b64_tr_b4 v[52:53], v160 offset:1920
	ds_read_b64_tr_b4 v[130:131], v54
	ds_read_b64_tr_b4 v[132:133], v55
	ds_read_b64_tr_b4 v[134:135], v56
	ds_read_b64_tr_b4 v[136:137], v57
	s_waitcnt lgkmcnt(6)
	v_dot8c_i32_i4_e32 v38, v122, v48
	v_dot8c_i32_i4_e32 v39, v122, v46
	v_dot8c_i32_i4_e32 v40, v124, v48
	v_dot8c_i32_i4_e32 v41, v124, v46
	v_dot8c_i32_i4_e32 v42, v126, v48
	v_dot8c_i32_i4_e32 v43, v126, v46
	v_dot8c_i32_i4_e32 v44, v128, v48
	v_dot8c_i32_i4_e32 v45, v128, v46
	v_dot8c_i32_i4_e32 v38, v123, v49
	v_dot8c_i32_i4_e32 v39, v123, v47
	v_dot8c_i32_i4_e32 v40, v125, v49
	v_dot8c_i32_i4_e32 v41, v125, v47
	v_dot8c_i32_i4_e32 v42, v127, v49
	v_dot8c_i32_i4_e32 v43, v127, v47
	v_dot8c_i32_i4_e32 v44, v129, v49
	v_dot8c_i32_i4_e32 v45, v129, v47
	v_and_b32_e32 v78, 0xffff, v30
	v_lshrrev_b32_e32 v79, 16, v30
	v_lshl_add_u32 v78, v78, 7, v152
	v_lshl_add_u32 v79, v79, 7, v153
	s_mov_b32 m0, s76
	s_add_i32 s43, s76, 0x400
	global_load_lds_dwordx4 v78, s[50:51]
	s_mov_b32 m0, s43
	s_nop 0
	global_load_lds_dwordx4 v79, s[50:51]
	s_waitcnt vmcnt(8)
	v_add_u32_e32 v54, s78, v59
	v_add_u32_e32 v55, s78, v60
	v_add_u32_e32 v56, s78, v61
	v_add_u32_e32 v57, s78, v62
	ds_read_b64_tr_b4 v[46:47], v160
	ds_read_b64_tr_b4 v[48:49], v160 offset:1024
	ds_read_b64_tr_b4 v[122:123], v54
	ds_read_b64_tr_b4 v[124:125], v55
	ds_read_b64_tr_b4 v[126:127], v56
	ds_read_b64_tr_b4 v[128:129], v57
	s_waitcnt lgkmcnt(6)
	v_dot8c_i32_i4_e32 v38, v130, v52
	v_dot8c_i32_i4_e32 v39, v130, v50
	v_dot8c_i32_i4_e32 v40, v132, v52
	v_dot8c_i32_i4_e32 v41, v132, v50
	v_dot8c_i32_i4_e32 v42, v134, v52
	v_dot8c_i32_i4_e32 v43, v134, v50
	v_dot8c_i32_i4_e32 v44, v136, v52
	v_dot8c_i32_i4_e32 v45, v136, v50
	v_dot8c_i32_i4_e32 v38, v131, v53
	v_dot8c_i32_i4_e32 v39, v131, v51
	v_dot8c_i32_i4_e32 v40, v133, v53
	v_dot8c_i32_i4_e32 v41, v133, v51
	v_dot8c_i32_i4_e32 v42, v135, v53
	v_dot8c_i32_i4_e32 v43, v135, v51
	v_dot8c_i32_i4_e32 v44, v137, v53
	v_dot8c_i32_i4_e32 v45, v137, v51
	s_nop 3
	s_waitcnt lgkmcnt(15)
	v_lshlrev_b32_e32 v38, 5, v38
	v_lshlrev_b32_e32 v39, 1, v39
	v_add3_u32 v38, v39, v229, v38
	v_cvt_f32_i32_e32 v38, v38
	v_mul_f32_e32 v38, v228, v38
	v_lshlrev_b32_e32 v40, 5, v40
	v_lshlrev_b32_e32 v41, 1, v41
	v_add3_u32 v40, v41, v229, v40
	v_cvt_f32_i32_e32 v40, v40
	v_mul_f32_e32 v40, v228, v40
	v_lshlrev_b32_e32 v42, 5, v42
	v_lshlrev_b32_e32 v43, 1, v43
	v_add3_u32 v42, v43, v229, v42
	v_cvt_f32_i32_e32 v42, v42
	v_mul_f32_e32 v42, v228, v42
	v_lshlrev_b32_e32 v44, 5, v44
	v_lshlrev_b32_e32 v45, 1, v45
	v_add3_u32 v44, v45, v229, v44
	v_cvt_f32_i32_e32 v44, v44
	v_mul_f32_e32 v44, v228, v44
	v_cvt_pk_bf16_f32 v184, v38, v40
	v_cvt_pk_bf16_f32 v185, v42, v44
	ds_read_b128 v[252:255], v156
	s_add_i32 s44, s40, 40
	s_ashr_i32 s45, s44, 31
	s_lshl_b64 s[44:45], s[44:45], 12
	v_lshl_add_u64 v[80:81], v[36:37], 0, s[44:45]
	s_waitcnt lgkmcnt(0)
	v_mul_f32_e32 v244, v244, v252
	v_mul_f32_e32 v245, v245, v253
	v_mul_f32_e32 v246, v246, v254
	v_mul_f32_e32 v247, v247, v255
	global_store_dwordx4 v[80:81], v[244:247], off offset:2048 nt
	v_add_u32_e32 v147, 8, v140
	v_and_b32_e32 v146, 15, v147
	v_xor_b32_e32 v146, 8, v146
	v_bfe_u32 v148, v147, 4, 4
	v_mul_lo_u32 v146, v146, s92
	v_mul_lo_u32 v148, v148, s92
	v_mov_b32_e32 v147, v146
	v_mov_b32_e32 v149, v148
	ds_write2st64_b64 v77, v[146:147], v[148:149] offset1:2
	v_mov_b32_e32 v138, v74
	ds_read_u8 v139, v138
	v_mov_b32_e32 v141, v73
	ds_read_u8 v140, v141
	s_add_i32 s43, s67, 224
	v_mov_b32_e32 v138, s43
	ds_read2st64_b32 v[228:229], v138 offset1:1
	ds_read_b128 v[18:21], v227
	ds_read_b128 v[22:25], v227 offset:16
	v_mov_b32_e32 v150, v63
	v_mov_b32_e32 v151, v64
	v_mov_b32_e32 v38, 0
	v_mov_b32_e32 v39, 0
	v_mov_b32_e32 v40, 0
	v_mov_b32_e32 v41, 0
	v_mov_b32_e32 v42, 0
	v_mov_b32_e32 v43, 0
	v_mov_b32_e32 v44, 0
	v_mov_b32_e32 v45, 0
	v_and_b32_e32 v78, 0xffff, v31
	v_lshrrev_b32_e32 v79, 16, v31
	v_lshl_add_u32 v78, v78, 7, v152
	v_lshl_add_u32 v79, v79, 7, v153
	s_mov_b32 m0, s77
	s_add_i32 s43, s77, 0x400
	global_load_lds_dwordx4 v78, s[50:51]
	s_mov_b32 m0, s43
	s_nop 0
	global_load_lds_dwordx4 v79, s[50:51]
	s_waitcnt vmcnt(9)
; #define LAS __attribute__((address_space(3)))
; #define TR4(p_) __builtin_amdgcn_ds_read_tr4_b64_v2i32((LAS v2i*)(p_))
; #define CFENCE() asm volatile("" ::: "memory")
; __device__ __forceinline__ void peer_v_tokens(int j, const LAS unsigned short* EL, const LAS unsigned char* AL  , const LAS float* ASC  , const LAS int* SAL  , ...
;     ...
;             const int idx = lane + 64 * m, tau = idx >> 4, sr = idx & 15, k = 16 * (sr & 7) + 2 * tau + (sr >> 3);
;             const int aq = (int)*(const LAS signed char*)(AL + tl * 128 + k); const int tq = aq + 8;
;             const unsigned lo = (((unsigned)tq & 15u) ^ 8u) * 0x11111111u, hi = ((unsigned)(tq >> 4) & 15u) * 0x11111111u;
;             typedef unsigned u2v __attribute__((ext_vector_type(2)));
;             u2v l2; l2.x = lo; l2.y = lo; u2v h2; h2.x = hi; h2.y = hi;
;             *(LAS u2v*)(ATL + 8 * idx) = l2; *(LAS u2v*)(ATL + 1024 + 8 * idx) = h2;
;         }
;         const float asc = ASC[tl]; const int sa = SAL[tl];
;         CFENCE();
;         int accH[4], accL[4];
; #pragma unroll
;         for (int st = 0; st < 16; ++st) {
;             const int p = st >> 2, q = st & 3;
;             if (st < 14) VDMA(st + 2, (st + 2) % 3);
;             if (st < 14) asm volatile("s_waitcnt vmcnt(8)" ::: "memory");
;             else if (st == 14) asm volatile("s_waitcnt vmcnt(4)" ::: "memory");
;             else asm volatile("s_waitcnt vmcnt(0)" ::: "memory");
;             if (q == 0) {
; #pragma unroll
;                 for (int r = 0; r < 4; ++r) { accH[r] = 0; accL[r] = 0; } }
; #pragma unroll
;             for (int tp = 0; tp < 2; ++tp) {
;                 const v2i ao = TR4(ATL + (2 * q + tp) * 128 + 8 * s16), ah = TR4(ATL + 1024 + (2 * q + tp) * 128 + 8 * s16);
; #pragma unroll
;                 for (int r = 0; r < 4; ++r) {
;                     const v2i d = TR4(ldsb + BUF[st % 3] + 2048 * tp + roff[r]);
;                     accH[r] = __builtin_amdgcn_sdot8(d.x, ah.x, accH[r], false); accH[r] = __builtin_amdgcn_sdot8(d.y, ah.y, accH[r], false);
;                     accL[r] = __builtin_amdgcn_sdot8(d.x, ao.x, accL[r], false); accL[r] = __builtin_amdgcn_sdot8(d.y, ao.y, accL[r], false);
;                 }
;             }
;             asm volatile("s_waitcnt lgkmcnt(0)" ::: "memory");
	v_add_u32_e32 v54, s79, v59
	v_add_u32_e32 v55, s79, v60
	v_add_u32_e32 v56, s79, v61
	v_add_u32_e32 v57, s79, v62
	ds_read_b64_tr_b4 v[50:51], v160 offset:128
	ds_read_b64_tr_b4 v[52:53], v160 offset:1152
	ds_read_b64_tr_b4 v[130:131], v54
	ds_read_b64_tr_b4 v[132:133], v55
	ds_read_b64_tr_b4 v[134:135], v56
	ds_read_b64_tr_b4 v[136:137], v57
	s_waitcnt lgkmcnt(13)
	v_dot8c_i32_i4_e32 v38, v122, v48
	v_dot8c_i32_i4_e32 v39, v122, v46
	v_dot8c_i32_i4_e32 v40, v124, v48
	v_dot8c_i32_i4_e32 v41, v124, v46
	v_dot8c_i32_i4_e32 v42, v126, v48
	v_dot8c_i32_i4_e32 v43, v126, v46
	v_dot8c_i32_i4_e32 v44, v128, v48
	v_dot8c_i32_i4_e32 v45, v128, v46
	v_dot8c_i32_i4_e32 v38, v123, v49
	v_dot8c_i32_i4_e32 v39, v123, v47
	v_dot8c_i32_i4_e32 v40, v125, v49
	v_dot8c_i32_i4_e32 v41, v125, v47
	v_dot8c_i32_i4_e32 v42, v127, v49
	v_dot8c_i32_i4_e32 v43, v127, v47
	v_dot8c_i32_i4_e32 v44, v129, v49
	v_dot8c_i32_i4_e32 v45, v129, v47
	v_and_b32_e32 v78, 0xffff, v32
	v_lshrrev_b32_e32 v79, 16, v32
	v_lshl_add_u32 v78, v78, 7, v152
	v_lshl_add_u32 v79, v79, 7, v153
	s_mov_b32 m0, s78
	s_add_i32 s43, s78, 0x400
	global_load_lds_dwordx4 v78, s[50:51]
	s_mov_b32 m0, s43
	s_nop 0
	global_load_lds_dwordx4 v79, s[50:51]
	s_waitcnt vmcnt(9)
	v_add_u32_e32 v54, s98, v59
	v_add_u32_e32 v55, s98, v60
	v_add_u32_e32 v56, s98, v61
	v_add_u32_e32 v57, s98, v62
	ds_read_b64_tr_b4 v[46:47], v160 offset:256
	ds_read_b64_tr_b4 v[48:49], v160 offset:1280
	ds_read_b64_tr_b4 v[122:123], v54
	ds_read_b64_tr_b4 v[124:125], v55
	ds_read_b64_tr_b4 v[126:127], v56
	ds_read_b64_tr_b4 v[128:129], v57
	s_waitcnt lgkmcnt(6)
	v_dot8c_i32_i4_e32 v38, v130, v52
	v_dot8c_i32_i4_e32 v39, v130, v50
	v_dot8c_i32_i4_e32 v40, v132, v52
	v_dot8c_i32_i4_e32 v41, v132, v50
	v_dot8c_i32_i4_e32 v42, v134, v52
	v_dot8c_i32_i4_e32 v43, v134, v50
	v_dot8c_i32_i4_e32 v44, v136, v52
	v_dot8c_i32_i4_e32 v45, v136, v50
	v_dot8c_i32_i4_e32 v38, v131, v53
	v_dot8c_i32_i4_e32 v39, v131, v51
	v_dot8c_i32_i4_e32 v40, v133, v53
	v_dot8c_i32_i4_e32 v41, v133, v51
	v_dot8c_i32_i4_e32 v42, v135, v53
	v_dot8c_i32_i4_e32 v43, v135, v51
	v_dot8c_i32_i4_e32 v44, v137, v53
	v_dot8c_i32_i4_e32 v45, v137, v51
	v_and_b32_e32 v78, 0xffff, v33
	v_lshrrev_b32_e32 v79, 16, v33
	v_lshl_add_u32 v78, v78, 7, v152
	v_lshl_add_u32 v79, v79, 7, v153
	s_mov_b32 m0, s79
	s_add_i32 s43, s79, 0x400
	global_load_lds_dwordx4 v78, s[50:51]
	s_mov_b32 m0, s43
	s_nop 0
	global_load_lds_dwordx4 v79, s[50:51]
	s_waitcnt vmcnt(9)
	v_add_u32_e32 v54, s99, v59
	v_add_u32_e32 v55, s99, v60
	v_add_u32_e32 v56, s99, v61
	v_add_u32_e32 v57, s99, v62
	ds_read_b64_tr_b4 v[50:51], v160 offset:384
	ds_read_b64_tr_b4 v[52:53], v160 offset:1408
	ds_read_b64_tr_b4 v[130:131], v54
	ds_read_b64_tr_b4 v[132:133], v55
	ds_read_b64_tr_b4 v[134:135], v56
	ds_read_b64_tr_b4 v[136:137], v57
	s_waitcnt lgkmcnt(6)
	v_dot8c_i32_i4_e32 v38, v122, v48
	v_dot8c_i32_i4_e32 v39, v122, v46
	v_dot8c_i32_i4_e32 v40, v124, v48
	v_dot8c_i32_i4_e32 v41, v124, v46
	v_dot8c_i32_i4_e32 v42, v126, v48
	v_dot8c_i32_i4_e32 v43, v126, v46
	v_dot8c_i32_i4_e32 v44, v128, v48
	v_dot8c_i32_i4_e32 v45, v128, v46
	v_dot8c_i32_i4_e32 v38, v123, v49
	v_dot8c_i32_i4_e32 v39, v123, v47
	v_dot8c_i32_i4_e32 v40, v125, v49
	v_dot8c_i32_i4_e32 v41, v125, v47
	v_dot8c_i32_i4_e32 v42, v127, v49
	v_dot8c_i32_i4_e32 v43, v127, v47
	v_dot8c_i32_i4_e32 v44, v129, v49
	v_dot8c_i32_i4_e32 v45, v129, v47
	s_waitcnt lgkmcnt(15)
	v_and_b32_e32 v78, 0xffff, v18
	v_lshrrev_b32_e32 v79, 16, v18
	v_lshl_add_u32 v78, v78, 7, v150
	v_lshl_add_u32 v79, v79, 7, v151
	s_mov_b32 m0, s98
	s_add_i32 s43, s98, 0x400
	global_load_lds_dwordx4 v78, s[50:51]
	s_mov_b32 m0, s43
	s_nop 0
	global_load_lds_dwordx4 v79, s[50:51]
	s_waitcnt vmcnt(9)
	v_add_u32_e32 v54, s76, v59
	v_add_u32_e32 v55, s76, v60
	v_add_u32_e32 v56, s76, v61
	v_add_u32_e32 v57, s76, v62
	ds_read_b64_tr_b4 v[46:47], v160 offset:512
	ds_read_b64_tr_b4 v[48:49], v160 offset:1536
	ds_read_b64_tr_b4 v[122:123], v54
	ds_read_b64_tr_b4 v[124:125], v55
	ds_read_b64_tr_b4 v[126:127], v56
	ds_read_b64_tr_b4 v[128:129], v57
	s_waitcnt lgkmcnt(6)
	v_dot8c_i32_i4_e32 v38, v130, v52
	v_dot8c_i32_i4_e32 v39, v130, v50
	v_dot8c_i32_i4_e32 v40, v132, v52
	v_dot8c_i32_i4_e32 v41, v132, v50
	v_dot8c_i32_i4_e32 v42, v134, v52
	v_dot8c_i32_i4_e32 v43, v134, v50
	v_dot8c_i32_i4_e32 v44, v136, v52
	v_dot8c_i32_i4_e32 v45, v136, v50
	v_dot8c_i32_i4_e32 v38, v131, v53
	v_dot8c_i32_i4_e32 v39, v131, v51
	v_dot8c_i32_i4_e32 v40, v133, v53
	v_dot8c_i32_i4_e32 v41, v133, v51
	v_dot8c_i32_i4_e32 v42, v135, v53
	v_dot8c_i32_i4_e32 v43, v135, v51
	v_dot8c_i32_i4_e32 v44, v137, v53
	v_dot8c_i32_i4_e32 v45, v137, v51
	v_and_b32_e32 v78, 0xffff, v19
	v_lshrrev_b32_e32 v79, 16, v19
	v_lshl_add_u32 v78, v78, 7, v150
	v_lshl_add_u32 v79, v79, 7, v151
	s_mov_b32 m0, s99
	s_add_i32 s43, s99, 0x400
	global_load_lds_dwordx4 v78, s[50:51]
	s_mov_b32 m0, s43
	s_nop 0
	global_load_lds_dwordx4 v79, s[50:51]
	s_waitcnt vmcnt(8)
	v_add_u32_e32 v54, s77, v59
	v_add_u32_e32 v55, s77, v60
	v_add_u32_e32 v56, s77, v61
	v_add_u32_e32 v57, s77, v62
	ds_read_b64_tr_b4 v[50:51], v160 offset:640
	ds_read_b64_tr_b4 v[52:53], v160 offset:1664
	ds_read_b64_tr_b4 v[130:131], v54
	ds_read_b64_tr_b4 v[132:133], v55
	ds_read_b64_tr_b4 v[134:135], v56
	ds_read_b64_tr_b4 v[136:137], v57
	s_waitcnt lgkmcnt(6)
	v_dot8c_i32_i4_e32 v38, v122, v48
	v_dot8c_i32_i4_e32 v39, v122, v46
	v_dot8c_i32_i4_e32 v40, v124, v48
	v_dot8c_i32_i4_e32 v41, v124, v46
	v_dot8c_i32_i4_e32 v42, v126, v48
	v_dot8c_i32_i4_e32 v43, v126, v46
	v_dot8c_i32_i4_e32 v44, v128, v48
	v_dot8c_i32_i4_e32 v45, v128, v46
	v_dot8c_i32_i4_e32 v38, v123, v49
	v_dot8c_i32_i4_e32 v39, v123, v47
	v_dot8c_i32_i4_e32 v40, v125, v49
	v_dot8c_i32_i4_e32 v41, v125, v47
	v_dot8c_i32_i4_e32 v42, v127, v49
	v_dot8c_i32_i4_e32 v43, v127, v47
	v_dot8c_i32_i4_e32 v44, v129, v49
	v_dot8c_i32_i4_e32 v45, v129, v47
	s_waitcnt lgkmcnt(15)
; __device__ __forceinline__ void peer_v_tokens(int j, const LAS unsigned short* EL, const LAS unsigned char* AL  , const LAS float* ASC  , const LAS int* SAL  , ...
;     ...
;         { unsigned ho = (unsigned)t * (D / 4) + (unsigned)lane; asm volatile("" : "+v"(ho)); const uint2* hp = (const uint2*)HB + ho; const float4* gp = (const float4*)fng + lane;
; #pragma unroll
;           for (int jq = 0; jq < 4; ++jq) { hv[jq] = hp[64 * jq]; gv[jq] = gp[64 * jq]; } }
;         VDMA(0, 0); VDMA(1, 1);
; #pragma unroll
;         for (int m = 0; m < 2; ++m) {
;             const int idx = lane + 64 * m, tau = idx >> 4, sr = idx & 15, k = 16 * (sr & 7) + 2 * tau + (sr >> 3);
;             const int aq = (int)*(const LAS signed char*)(AL + tl * 128 + k); const int tq = aq + 8;
;             const unsigned lo = (((unsigned)tq & 15u) ^ 8u) * 0x11111111u, hi = ((unsigned)(tq >> 4) & 15u) * 0x11111111u;
;             typedef unsigned u2v __attribute__((ext_vector_type(2)));
;             u2v l2; l2.x = lo; l2.y = lo; u2v h2; h2.x = hi; h2.y = hi;
;             *(LAS u2v*)(ATL + 8 * idx) = l2; *(LAS u2v*)(ATL + 1024 + 8 * idx) = h2;
;         }
;         const float asc = ASC[tl]; const int sa = SAL[tl];
;         CFENCE();
;         int accH[4], accL[4];
; #pragma unroll
;         for (int st = 0; st < 16; ++st) {
;             const int p = st >> 2, q = st & 3;
;             if (st < 14) VDMA(st + 2, (st + 2) % 3);
;             if (st < 14) asm volatile("s_waitcnt vmcnt(8)" ::: "memory");
;             else if (st == 14) asm volatile("s_waitcnt vmcnt(4)" ::: "memory");
;             else asm volatile("s_waitcnt vmcnt(0)" ::: "memory");
;             if (q == 0) {
; #pragma unroll
;                 for (int r = 0; r < 4; ++r) { accH[r] = 0; accL[r] = 0; } }
; #pragma unroll
;             for (int tp = 0; tp < 2; ++tp) {
;                 const v2i ao = TR4(ATL + (2 * q + tp) * 128 + 8 * s16), ah = TR4(ATL + 1024 + (2 * q + tp) * 128 + 8 * s16);
; #pragma unroll
;                 for (int r = 0; r < 4; ++r) {
;                     const v2i d = TR4(ldsb + BUF[st % 3] + 2048 * tp + roff[r]);
;                     accH[r] = __builtin_amdgcn_sdot8(d.x, ah.x, accH[r], false); accH[r] = __builtin_amdgcn_sdot8(d.y, ah.y, accH[r], false);
;                     accL[r] = __builtin_amdgcn_sdot8(d.x, ao.x, accL[r], false); accL[r] = __builtin_amdgcn_sdot8(d.y, ao.y, accL[r], false);
	v_add_u32_e32 v143, 8, v139
	v_and_b32_e32 v142, 15, v143
	v_xor_b32_e32 v142, 8, v142
	v_bfe_u32 v144, v143, 4, 4
	v_mul_lo_u32 v142, v142, s92
	v_mul_lo_u32 v144, v144, s92
	v_mov_b32_e32 v143, v142
	v_mov_b32_e32 v145, v144
	ds_write2st64_b64 v159, v[142:143], v[144:145] offset1:2
	v_and_b32_e32 v78, 0xffff, v20
	v_lshrrev_b32_e32 v79, 16, v20
	v_lshl_add_u32 v78, v78, 7, v150
	v_lshl_add_u32 v79, v79, 7, v151
	s_mov_b32 m0, s76
	s_add_i32 s43, s76, 0x400
	global_load_lds_dwordx4 v78, s[50:51]
	s_mov_b32 m0, s43
	s_nop 0
	global_load_lds_dwordx4 v79, s[50:51]
	s_waitcnt vmcnt(8)
	v_add_u32_e32 v54, s78, v59
	v_add_u32_e32 v55, s78, v60
	v_add_u32_e32 v56, s78, v61
	v_add_u32_e32 v57, s78, v62
	ds_read_b64_tr_b4 v[46:47], v160 offset:768
	ds_read_b64_tr_b4 v[48:49], v160 offset:1792
	ds_read_b64_tr_b4 v[122:123], v54
	ds_read_b64_tr_b4 v[124:125], v55
	ds_read_b64_tr_b4 v[126:127], v56
	ds_read_b64_tr_b4 v[128:129], v57
	s_waitcnt lgkmcnt(7)
	v_dot8c_i32_i4_e32 v38, v130, v52
	v_dot8c_i32_i4_e32 v39, v130, v50
	v_dot8c_i32_i4_e32 v40, v132, v52
	v_dot8c_i32_i4_e32 v41, v132, v50
	v_dot8c_i32_i4_e32 v42, v134, v52
	v_dot8c_i32_i4_e32 v43, v134, v50
	v_dot8c_i32_i4_e32 v44, v136, v52
	v_dot8c_i32_i4_e32 v45, v136, v50
	v_dot8c_i32_i4_e32 v38, v131, v53
	v_dot8c_i32_i4_e32 v39, v131, v51
	v_dot8c_i32_i4_e32 v40, v133, v53
	v_dot8c_i32_i4_e32 v41, v133, v51
	v_dot8c_i32_i4_e32 v42, v135, v53
	v_dot8c_i32_i4_e32 v43, v135, v51
	v_dot8c_i32_i4_e32 v44, v137, v53
	v_dot8c_i32_i4_e32 v45, v137, v51
	v_and_b32_e32 v78, 0xffff, v21
	v_lshrrev_b32_e32 v79, 16, v21
	v_lshl_add_u32 v78, v78, 7, v150
	v_lshl_add_u32 v79, v79, 7, v151
	s_mov_b32 m0, s77
	s_add_i32 s43, s77, 0x400
	global_load_lds_dwordx4 v78, s[50:51]
	s_mov_b32 m0, s43
	s_nop 0
	global_load_lds_dwordx4 v79, s[50:51]
	s_waitcnt vmcnt(8)
	v_add_u32_e32 v54, s79, v59
	v_add_u32_e32 v55, s79, v60
	v_add_u32_e32 v56, s79, v61
	v_add_u32_e32 v57, s79, v62
	ds_read_b64_tr_b4 v[50:51], v160 offset:896
	ds_read_b64_tr_b4 v[52:53], v160 offset:1920
	ds_read_b64_tr_b4 v[130:131], v54
	ds_read_b64_tr_b4 v[132:133], v55
	ds_read_b64_tr_b4 v[134:135], v56
	ds_read_b64_tr_b4 v[136:137], v57
	s_waitcnt lgkmcnt(6)
	v_dot8c_i32_i4_e32 v38, v122, v48
	v_dot8c_i32_i4_e32 v39, v122, v46
	v_dot8c_i32_i4_e32 v40, v124, v48
	v_dot8c_i32_i4_e32 v41, v124, v46
	v_dot8c_i32_i4_e32 v42, v126, v48
	v_dot8c_i32_i4_e32 v43, v126, v46
	v_dot8c_i32_i4_e32 v44, v128, v48
	v_dot8c_i32_i4_e32 v45, v128, v46
	v_dot8c_i32_i4_e32 v38, v123, v49
	v_dot8c_i32_i4_e32 v39, v123, v47
	v_dot8c_i32_i4_e32 v40, v125, v49
	v_dot8c_i32_i4_e32 v41, v125, v47
	v_dot8c_i32_i4_e32 v42, v127, v49
	v_dot8c_i32_i4_e32 v43, v127, v47
	v_dot8c_i32_i4_e32 v44, v129, v49
	v_dot8c_i32_i4_e32 v45, v129, v47
	v_and_b32_e32 v78, 0xffff, v22
	v_lshrrev_b32_e32 v79, 16, v22
	v_lshl_add_u32 v78, v78, 7, v150
	v_lshl_add_u32 v79, v79, 7, v151
	s_mov_b32 m0, s78
	s_add_i32 s43, s78, 0x400
	global_load_lds_dwordx4 v78, s[50:51]
	s_mov_b32 m0, s43
	s_nop 0
	global_load_lds_dwordx4 v79, s[50:51]
	s_waitcnt vmcnt(8)
	v_add_u32_e32 v54, s98, v59
	v_add_u32_e32 v55, s98, v60
	v_add_u32_e32 v56, s98, v61
	v_add_u32_e32 v57, s98, v62
	ds_read_b64_tr_b4 v[46:47], v160
	ds_read_b64_tr_b4 v[48:49], v160 offset:1024
	ds_read_b64_tr_b4 v[122:123], v54
	ds_read_b64_tr_b4 v[124:125], v55
	ds_read_b64_tr_b4 v[126:127], v56
	ds_read_b64_tr_b4 v[128:129], v57
	s_waitcnt lgkmcnt(6)
	v_dot8c_i32_i4_e32 v38, v130, v52
	v_dot8c_i32_i4_e32 v39, v130, v50
	v_dot8c_i32_i4_e32 v40, v132, v52
	v_dot8c_i32_i4_e32 v41, v132, v50
	v_dot8c_i32_i4_e32 v42, v134, v52
	v_dot8c_i32_i4_e32 v43, v134, v50
	v_dot8c_i32_i4_e32 v44, v136, v52
	v_dot8c_i32_i4_e32 v45, v136, v50
	v_dot8c_i32_i4_e32 v38, v131, v53
	v_dot8c_i32_i4_e32 v39, v131, v51
	v_dot8c_i32_i4_e32 v40, v133, v53
	v_dot8c_i32_i4_e32 v41, v133, v51
	v_dot8c_i32_i4_e32 v42, v135, v53
	v_dot8c_i32_i4_e32 v43, v135, v51
	v_dot8c_i32_i4_e32 v44, v137, v53
	v_dot8c_i32_i4_e32 v45, v137, v51
	s_nop 3
	s_waitcnt lgkmcnt(15)
	v_lshlrev_b32_e32 v38, 5, v38
	v_lshlrev_b32_e32 v39, 1, v39
	v_add3_u32 v38, v39, v229, v38
	v_cvt_f32_i32_e32 v38, v38
	v_mul_f32_e32 v38, v228, v38
	v_lshlrev_b32_e32 v40, 5, v40
	v_lshlrev_b32_e32 v41, 1, v41
	v_add3_u32 v40, v41, v229, v40
	v_cvt_f32_i32_e32 v40, v40
	v_mul_f32_e32 v40, v228, v40
	v_lshlrev_b32_e32 v42, 5, v42
	v_lshlrev_b32_e32 v43, 1, v43
	v_add3_u32 v42, v43, v229, v42
	v_cvt_f32_i32_e32 v42, v42
	v_mul_f32_e32 v42, v228, v42
	v_lshlrev_b32_e32 v44, 5, v44
	v_lshlrev_b32_e32 v45, 1, v45
	v_add3_u32 v44, v45, v229, v44
	v_cvt_f32_i32_e32 v44, v44
	v_mul_f32_e32 v44, v228, v44
	v_cvt_pk_bf16_f32 v192, v38, v40
	v_cvt_pk_bf16_f32 v193, v42, v44
	s_waitcnt vmcnt(0) lgkmcnt(0)
	ds_read_b128 v[252:255], v156 offset:1024
	s_add_i32 s44, s40, 40
	s_ashr_i32 s45, s44, 31
	s_lshl_b64 s[44:45], s[44:45], 12
	v_lshl_add_u64 v[80:81], v[36:37], 0, s[44:45]
	s_waitcnt lgkmcnt(0)
	v_mul_f32_e32 v248, v248, v252
	v_mul_f32_e32 v249, v249, v253
	v_mul_f32_e32 v250, v250, v254
	v_mul_f32_e32 v251, v251, v255
	global_store_dwordx4 v[80:81], v[248:251], off offset:3072 nt
	s_add_i32 s43, s40, 48
	s_lshl_b32 s43, s43, 11
	v_add_u32_e32 v138, s43, v66
	global_load_dwordx2 v[194:195], v138, s[70:71]
	global_load_dwordx2 v[196:197], v138, s[70:71] offset:512
	global_load_dwordx2 v[198:199], v138, s[70:71] offset:1024
	global_load_dwordx2 v[200:201], v138, s[70:71] offset:1536
	ds_write_b16 v65, v178
	ds_write_b16_d16_hi v65, v178 offset:128
	ds_write_b16 v65, v179 offset:256
	ds_write_b16_d16_hi v65, v179 offset:384
	ds_write_b16 v65, v180 offset:512
	ds_write_b16_d16_hi v65, v180 offset:640
	ds_write_b16 v65, v181 offset:768
	ds_write_b16_d16_hi v65, v181 offset:896
	ds_write_b16 v65, v182 offset:1024
	ds_write_b16_d16_hi v65, v182 offset:1152
	ds_write_b16 v65, v183 offset:1280
	ds_write_b16_d16_hi v65, v183 offset:1408
	ds_write_b16 v65, v184 offset:1536
	ds_write_b16_d16_hi v65, v184 offset:1664
	ds_write_b16 v65, v185 offset:1792
	ds_write_b16_d16_hi v65, v185 offset:1920
	ds_read_b64 v[202:203], v154
	ds_read_b64 v[204:205], v154 offset:512
	ds_read_b64 v[206:207], v154 offset:1024
	ds_read_b64 v[208:209], v154 offset:1536
	s_waitcnt vmcnt(0) lgkmcnt(0)
; #define LAS __attribute__((address_space(3)))
; __device__ __forceinline__ void peer_v_tokens(int j, const LAS unsigned short* EL, const LAS unsigned char* AL  , const LAS float* ASC  , const LAS int* SAL  , ...
;     ...
;         { unsigned ho = (unsigned)t * (D / 4) + (unsigned)lane; asm volatile("" : "+v"(ho)); const uint2* hp = (const uint2*)HB + ho; const float4* gp = (const float4*)fng + lane;
; #pragma unroll
;           for (int jq = 0; jq < 4; ++jq) { hv[jq] = hp[64 * jq]; gv[jq] = gp[64 * jq]; } }
;     ...
;         {
;             float4 v[4]; float ss = 0.f;
; #pragma unroll
;             for (int jq = 0; jq < 4; ++jq) { typedef unsigned u2v __attribute__((ext_vector_type(2))); const u2v pw = *(const LAS u2v*)(STASH + 4 * lane + 256 * jq); const uint2 hw = hv[jq];
;                 v[jq] = make_float4(__uint_as_float(hw.x << 16) + __uint_as_float(pw.x << 16), __uint_as_float(hw.x & 0xffff0000u) + __uint_as_float(pw.x & 0xffff0000u),
;                                     __uint_as_float(hw.y << 16) + __uint_as_float(pw.y << 16), __uint_as_float(hw.y & 0xffff0000u) + __uint_as_float(pw.y & 0xffff0000u));
;                 ss += v[jq].x * v[jq].x + v[jq].y * v[jq].y + v[jq].z * v[jq].z + v[jq].w * v[jq].w; }
;             ss = wave_sum(ss);
;             const float r3 = rsqrtf(ss * (1.f / D) + EPS);
;             float4* op = (float4*)(outp + (size_t)t * D) + lane;
; #pragma unroll
;             for (int jq = 0; jq < 4; ++jq) { typedef float f4v __attribute__((ext_vector_type(4))); f4v o4; o4.x = v[jq].x * r3 * gv[jq].x; o4.y = v[jq].y * r3 * gv[jq].y; o4.z = v[jq].z * r3 * gv[jq].z; o4.w = v[jq].w * r3 * gv[jq].w;
;                 __builtin_nontemporal_store(o4, (f4v*)op + 64 * jq); }
;         }
	v_lshlrev_b32_e32 v210, 16, v194
	v_and_b32_e32 v211, 0xffff0000, v194
	v_lshlrev_b32_e32 v142, 16, v202
	v_and_b32_e32 v143, 0xffff0000, v202
	v_add_f32_e32 v210, v210, v142
	v_add_f32_e32 v211, v211, v143
	v_lshlrev_b32_e32 v212, 16, v195
	v_and_b32_e32 v213, 0xffff0000, v195
	v_lshlrev_b32_e32 v142, 16, v203
	v_and_b32_e32 v143, 0xffff0000, v203
	v_add_f32_e32 v212, v212, v142
	v_add_f32_e32 v213, v213, v143
	v_lshlrev_b32_e32 v214, 16, v196
	v_and_b32_e32 v215, 0xffff0000, v196
	v_lshlrev_b32_e32 v142, 16, v204
	v_and_b32_e32 v143, 0xffff0000, v204
	v_add_f32_e32 v214, v214, v142
	v_add_f32_e32 v215, v215, v143
	v_lshlrev_b32_e32 v216, 16, v197
	v_and_b32_e32 v217, 0xffff0000, v197
	v_lshlrev_b32_e32 v142, 16, v205
	v_and_b32_e32 v143, 0xffff0000, v205
	v_add_f32_e32 v216, v216, v142
	v_add_f32_e32 v217, v217, v143
	v_lshlrev_b32_e32 v218, 16, v198
	v_and_b32_e32 v219, 0xffff0000, v198
	v_lshlrev_b32_e32 v142, 16, v206
	v_and_b32_e32 v143, 0xffff0000, v206
	v_add_f32_e32 v218, v218, v142
	v_add_f32_e32 v219, v219, v143
	v_lshlrev_b32_e32 v220, 16, v199
	v_and_b32_e32 v221, 0xffff0000, v199
	v_lshlrev_b32_e32 v142, 16, v207
	v_and_b32_e32 v143, 0xffff0000, v207
	v_add_f32_e32 v220, v220, v142
	v_add_f32_e32 v221, v221, v143
	v_lshlrev_b32_e32 v222, 16, v200
	v_and_b32_e32 v223, 0xffff0000, v200
	v_lshlrev_b32_e32 v142, 16, v208
	v_and_b32_e32 v143, 0xffff0000, v208
	v_add_f32_e32 v222, v222, v142
	v_add_f32_e32 v223, v223, v143
	v_lshlrev_b32_e32 v224, 16, v201
	v_and_b32_e32 v225, 0xffff0000, v201
	v_lshlrev_b32_e32 v142, 16, v209
	v_and_b32_e32 v143, 0xffff0000, v209
	v_add_f32_e32 v224, v224, v142
	v_add_f32_e32 v225, v225, v143
	v_mov_b32_e32 v144, 0
	v_mul_f32_e32 v145, v210, v210
	v_fmac_f32_e32 v145, v211, v211
	v_fmac_f32_e32 v145, v212, v212
	v_fmac_f32_e32 v145, v213, v213
	v_add_f32_e32 v144, v144, v145
	v_mul_f32_e32 v145, v214, v214
	v_fmac_f32_e32 v145, v215, v215
	v_fmac_f32_e32 v145, v216, v216
	v_fmac_f32_e32 v145, v217, v217
	v_add_f32_e32 v144, v144, v145
	v_mul_f32_e32 v145, v218, v218
	v_fmac_f32_e32 v145, v219, v219
	v_fmac_f32_e32 v145, v220, v220
	v_fmac_f32_e32 v145, v221, v221
	v_add_f32_e32 v144, v144, v145
	v_mul_f32_e32 v145, v222, v222
	v_fmac_f32_e32 v145, v223, v223
	v_fmac_f32_e32 v145, v224, v224
	v_fmac_f32_e32 v145, v225, v225
	v_add_f32_e32 v144, v144, v145
	s_nop 1
	v_add_f32_dpp v144, v144, v144 quad_perm:[1,0,3,2] row_mask:0xf bank_mask:0xf bound_ctrl:1
	s_nop 1
	v_add_f32_dpp v144, v144, v144 quad_perm:[2,3,0,1] row_mask:0xf bank_mask:0xf bound_ctrl:1
	s_nop 1
	v_add_f32_dpp v144, v144, v144 row_half_mirror row_mask:0xf bank_mask:0xf bound_ctrl:1
	s_nop 1
	v_add_f32_dpp v144, v144, v144 row_mirror row_mask:0xf bank_mask:0xf bound_ctrl:1
	s_nop 1
	v_readlane_b32 s10, v144, 0
	v_readlane_b32 s11, v144, 16
	v_readlane_b32 s14, v144, 32
	v_readlane_b32 s15, v144, 48
	s_nop 3
	v_mov_b32_e32 v144, s11
	v_mov_b32_e32 v145, s15
	v_add_f32_e32 v144, s10, v144
	v_add_f32_e32 v145, s14, v145
	v_add_f32_e32 v144, v144, v145
	v_fmamk_f32 v144, v144, 0x3a800000, v111
	v_rsq_f32_e32 v144, v144
	s_nop 0
	v_mul_f32_e32 v210, v210, v144
	v_mul_f32_e32 v211, v211, v144
	v_mul_f32_e32 v212, v212, v144
	v_mul_f32_e32 v213, v213, v144
	v_mul_f32_e32 v214, v214, v144
	v_mul_f32_e32 v215, v215, v144
	v_mul_f32_e32 v216, v216, v144
	v_mul_f32_e32 v217, v217, v144
	v_mul_f32_e32 v218, v218, v144
	v_mul_f32_e32 v219, v219, v144
	v_mul_f32_e32 v220, v220, v144
	v_mul_f32_e32 v221, v221, v144
	v_mul_f32_e32 v222, v222, v144
	v_mul_f32_e32 v223, v223, v144
	v_mul_f32_e32 v224, v224, v144
	v_mul_f32_e32 v225, v225, v144
	ds_read_b128 v[252:255], v155
	s_add_i32 s44, s40, 48
	s_ashr_i32 s45, s44, 31
	s_lshl_b64 s[44:45], s[44:45], 12
	v_lshl_add_u64 v[80:81], v[36:37], 0, s[44:45]
	s_waitcnt lgkmcnt(0)
	v_mul_f32_e32 v210, v210, v252
	v_mul_f32_e32 v211, v211, v253
	v_mul_f32_e32 v212, v212, v254
	v_mul_f32_e32 v213, v213, v255
	global_store_dwordx4 v[80:81], v[210:213], off nt
	ds_read_b128 v[252:255], v155 offset:1024
	s_add_i32 s44, s40, 48
	s_ashr_i32 s45, s44, 31
	s_lshl_b64 s[44:45], s[44:45], 12
	v_lshl_add_u64 v[80:81], v[36:37], 0, s[44:45]
	s_waitcnt lgkmcnt(0)
	v_mul_f32_e32 v214, v214, v252
	v_mul_f32_e32 v215, v215, v253
	v_mul_f32_e32 v216, v216, v254
	v_mul_f32_e32 v217, v217, v255
	global_store_dwordx4 v[80:81], v[214:217], off offset:1024 nt
	ds_read_b128 v[252:255], v156
	s_add_i32 s44, s40, 48
	s_ashr_i32 s45, s44, 31
	s_lshl_b64 s[44:45], s[44:45], 12
	v_lshl_add_u64 v[80:81], v[36:37], 0, s[44:45]
	s_waitcnt lgkmcnt(0)
	v_mul_f32_e32 v218, v218, v252
	v_mul_f32_e32 v219, v219, v253
	v_mul_f32_e32 v220, v220, v254
	v_mul_f32_e32 v221, v221, v255
	global_store_dwordx4 v[80:81], v[218:221], off offset:2048 nt
	ds_read_b128 v[252:255], v156 offset:1024
	s_add_i32 s44, s40, 48
	s_ashr_i32 s45, s44, 31
	s_lshl_b64 s[44:45], s[44:45], 12
	v_lshl_add_u64 v[80:81], v[36:37], 0, s[44:45]
	s_waitcnt lgkmcnt(0)
	v_mul_f32_e32 v222, v222, v252
	v_mul_f32_e32 v223, v223, v253
	v_mul_f32_e32 v224, v224, v254
	v_mul_f32_e32 v225, v225, v255
	global_store_dwordx4 v[80:81], v[222:225], off offset:3072 nt
	s_add_i32 s43, s40, 56
	s_lshl_b32 s43, s43, 11
	v_add_u32_e32 v138, s43, v66
	global_load_dwordx2 v[194:195], v138, s[70:71]
	global_load_dwordx2 v[196:197], v138, s[70:71] offset:512
	global_load_dwordx2 v[198:199], v138, s[70:71] offset:1024
	global_load_dwordx2 v[200:201], v138, s[70:71] offset:1536
	ds_write_b16 v65, v186
	ds_write_b16_d16_hi v65, v186 offset:128
	ds_write_b16 v65, v187 offset:256
	ds_write_b16_d16_hi v65, v187 offset:384
	ds_write_b16 v65, v188 offset:512
	ds_write_b16_d16_hi v65, v188 offset:640
	ds_write_b16 v65, v189 offset:768
	ds_write_b16_d16_hi v65, v189 offset:896
	ds_write_b16 v65, v190 offset:1024
	ds_write_b16_d16_hi v65, v190 offset:1152
	ds_write_b16 v65, v191 offset:1280
	ds_write_b16_d16_hi v65, v191 offset:1408
	ds_write_b16 v65, v192 offset:1536
	ds_write_b16_d16_hi v65, v192 offset:1664
	ds_write_b16 v65, v193 offset:1792
	ds_write_b16_d16_hi v65, v193 offset:1920
	ds_read_b64 v[202:203], v154
	ds_read_b64 v[204:205], v154 offset:512
	ds_read_b64 v[206:207], v154 offset:1024
	ds_read_b64 v[208:209], v154 offset:1536
	s_waitcnt vmcnt(0) lgkmcnt(0)
; #define LAS __attribute__((address_space(3)))
; __device__ __forceinline__ void peer_v_tokens(int j, const LAS unsigned short* EL, const LAS unsigned char* AL  , const LAS float* ASC  , const LAS int* SAL  , ...
;     ...
;         {
;             float4 v[4]; float ss = 0.f;
; #pragma unroll
;             for (int jq = 0; jq < 4; ++jq) { typedef unsigned u2v __attribute__((ext_vector_type(2))); const u2v pw = *(const LAS u2v*)(STASH + 4 * lane + 256 * jq); const uint2 hw = hv[jq];
;                 v[jq] = make_float4(__uint_as_float(hw.x << 16) + __uint_as_float(pw.x << 16), __uint_as_float(hw.x & 0xffff0000u) + __uint_as_float(pw.x & 0xffff0000u),
;                                     __uint_as_float(hw.y << 16) + __uint_as_float(pw.y << 16), __uint_as_float(hw.y & 0xffff0000u) + __uint_as_float(pw.y & 0xffff0000u));
;                 ss += v[jq].x * v[jq].x + v[jq].y * v[jq].y + v[jq].z * v[jq].z + v[jq].w * v[jq].w; }
;             ss = wave_sum(ss);
;             const float r3 = rsqrtf(ss * (1.f / D) + EPS);
;             float4* op = (float4*)(outp + (size_t)t * D) + lane;
; #pragma unroll
;             for (int jq = 0; jq < 4; ++jq) { typedef float f4v __attribute__((ext_vector_type(4))); f4v o4; o4.x = v[jq].x * r3 * gv[jq].x; o4.y = v[jq].y * r3 * gv[jq].y; o4.z = v[jq].z * r3 * gv[jq].z; o4.w = v[jq].w * r3 * gv[jq].w;
;                 __builtin_nontemporal_store(o4, (f4v*)op + 64 * jq); }
;         }
	v_lshlrev_b32_e32 v236, 16, v194
	v_and_b32_e32 v237, 0xffff0000, v194
	v_lshlrev_b32_e32 v142, 16, v202
	v_and_b32_e32 v143, 0xffff0000, v202
	v_add_f32_e32 v236, v236, v142
	v_add_f32_e32 v237, v237, v143
	v_lshlrev_b32_e32 v238, 16, v195
	v_and_b32_e32 v239, 0xffff0000, v195
	v_lshlrev_b32_e32 v142, 16, v203
	v_and_b32_e32 v143, 0xffff0000, v203
	v_add_f32_e32 v238, v238, v142
	v_add_f32_e32 v239, v239, v143
	v_lshlrev_b32_e32 v240, 16, v196
	v_and_b32_e32 v241, 0xffff0000, v196
	v_lshlrev_b32_e32 v142, 16, v204
	v_and_b32_e32 v143, 0xffff0000, v204
	v_add_f32_e32 v240, v240, v142
	v_add_f32_e32 v241, v241, v143
	v_lshlrev_b32_e32 v242, 16, v197
	v_and_b32_e32 v243, 0xffff0000, v197
	v_lshlrev_b32_e32 v142, 16, v205
	v_and_b32_e32 v143, 0xffff0000, v205
	v_add_f32_e32 v242, v242, v142
	v_add_f32_e32 v243, v243, v143
	v_lshlrev_b32_e32 v244, 16, v198
	v_and_b32_e32 v245, 0xffff0000, v198
	v_lshlrev_b32_e32 v142, 16, v206
	v_and_b32_e32 v143, 0xffff0000, v206
	v_add_f32_e32 v244, v244, v142
	v_add_f32_e32 v245, v245, v143
	v_lshlrev_b32_e32 v246, 16, v199
	v_and_b32_e32 v247, 0xffff0000, v199
	v_lshlrev_b32_e32 v142, 16, v207
	v_and_b32_e32 v143, 0xffff0000, v207
	v_add_f32_e32 v246, v246, v142
	v_add_f32_e32 v247, v247, v143
	v_lshlrev_b32_e32 v248, 16, v200
	v_and_b32_e32 v249, 0xffff0000, v200
	v_lshlrev_b32_e32 v142, 16, v208
	v_and_b32_e32 v143, 0xffff0000, v208
	v_add_f32_e32 v248, v248, v142
	v_add_f32_e32 v249, v249, v143
	v_lshlrev_b32_e32 v250, 16, v201
	v_and_b32_e32 v251, 0xffff0000, v201
	v_lshlrev_b32_e32 v142, 16, v209
	v_and_b32_e32 v143, 0xffff0000, v209
	v_add_f32_e32 v250, v250, v142
	v_add_f32_e32 v251, v251, v143
	v_mov_b32_e32 v144, 0
	v_mul_f32_e32 v145, v236, v236
	v_fmac_f32_e32 v145, v237, v237
	v_fmac_f32_e32 v145, v238, v238
	v_fmac_f32_e32 v145, v239, v239
	v_add_f32_e32 v144, v144, v145
	v_mul_f32_e32 v145, v240, v240
	v_fmac_f32_e32 v145, v241, v241
	v_fmac_f32_e32 v145, v242, v242
	v_fmac_f32_e32 v145, v243, v243
	v_add_f32_e32 v144, v144, v145
	v_mul_f32_e32 v145, v244, v244
	v_fmac_f32_e32 v145, v245, v245
	v_fmac_f32_e32 v145, v246, v246
	v_fmac_f32_e32 v145, v247, v247
	v_add_f32_e32 v144, v144, v145
	v_mul_f32_e32 v145, v248, v248
	v_fmac_f32_e32 v145, v249, v249
	v_fmac_f32_e32 v145, v250, v250
	v_fmac_f32_e32 v145, v251, v251
	v_add_f32_e32 v144, v144, v145
	s_nop 1
	v_add_f32_dpp v144, v144, v144 quad_perm:[1,0,3,2] row_mask:0xf bank_mask:0xf bound_ctrl:1
	s_nop 1
	v_add_f32_dpp v144, v144, v144 quad_perm:[2,3,0,1] row_mask:0xf bank_mask:0xf bound_ctrl:1
	s_nop 1
	v_add_f32_dpp v144, v144, v144 row_half_mirror row_mask:0xf bank_mask:0xf bound_ctrl:1
	s_nop 1
	v_add_f32_dpp v144, v144, v144 row_mirror row_mask:0xf bank_mask:0xf bound_ctrl:1
	s_nop 1
	v_readlane_b32 s10, v144, 0
	v_readlane_b32 s11, v144, 16
	v_readlane_b32 s14, v144, 32
	v_readlane_b32 s15, v144, 48
	s_nop 3
	v_mov_b32_e32 v144, s11
	v_mov_b32_e32 v145, s15
	v_add_f32_e32 v144, s10, v144
	v_add_f32_e32 v145, s14, v145
	v_add_f32_e32 v144, v144, v145
	v_fmamk_f32 v144, v144, 0x3a800000, v111
	v_rsq_f32_e32 v144, v144
	s_nop 0
	v_mul_f32_e32 v236, v236, v144
	v_mul_f32_e32 v237, v237, v144
	v_mul_f32_e32 v238, v238, v144
	v_mul_f32_e32 v239, v239, v144
	v_mul_f32_e32 v240, v240, v144
	v_mul_f32_e32 v241, v241, v144
	v_mul_f32_e32 v242, v242, v144
	v_mul_f32_e32 v243, v243, v144
	v_mul_f32_e32 v244, v244, v144
	v_mul_f32_e32 v245, v245, v144
	v_mul_f32_e32 v246, v246, v144
	v_mul_f32_e32 v247, v247, v144
	v_mul_f32_e32 v248, v248, v144
	v_mul_f32_e32 v249, v249, v144
	v_mul_f32_e32 v250, v250, v144
	v_mul_f32_e32 v251, v251, v144
	ds_read_b128 v[252:255], v155
	s_add_i32 s44, s40, 56
	s_ashr_i32 s45, s44, 31
	s_lshl_b64 s[44:45], s[44:45], 12
	v_lshl_add_u64 v[80:81], v[36:37], 0, s[44:45]
	s_waitcnt lgkmcnt(0)
	v_mul_f32_e32 v236, v236, v252
	v_mul_f32_e32 v237, v237, v253
	v_mul_f32_e32 v238, v238, v254
	v_mul_f32_e32 v239, v239, v255
	global_store_dwordx4 v[80:81], v[236:239], off nt
	ds_read_b128 v[252:255], v155 offset:1024
	s_add_i32 s44, s40, 56
	s_ashr_i32 s45, s44, 31
	s_lshl_b64 s[44:45], s[44:45], 12
	v_lshl_add_u64 v[80:81], v[36:37], 0, s[44:45]
	s_waitcnt lgkmcnt(0)
	v_mul_f32_e32 v240, v240, v252
	v_mul_f32_e32 v241, v241, v253
	v_mul_f32_e32 v242, v242, v254
	v_mul_f32_e32 v243, v243, v255
	global_store_dwordx4 v[80:81], v[240:243], off offset:1024 nt
	ds_read_b128 v[252:255], v156
	s_add_i32 s44, s40, 56
	s_ashr_i32 s45, s44, 31
	s_lshl_b64 s[44:45], s[44:45], 12
	v_lshl_add_u64 v[80:81], v[36:37], 0, s[44:45]
	s_waitcnt lgkmcnt(0)
	v_mul_f32_e32 v244, v244, v252
	v_mul_f32_e32 v245, v245, v253
	v_mul_f32_e32 v246, v246, v254
	v_mul_f32_e32 v247, v247, v255
	global_store_dwordx4 v[80:81], v[244:247], off offset:2048 nt
	ds_read_b128 v[252:255], v156 offset:1024
	s_add_i32 s44, s40, 56
	s_ashr_i32 s45, s44, 31
	s_lshl_b64 s[44:45], s[44:45], 12
	v_lshl_add_u64 v[80:81], v[36:37], 0, s[44:45]
	s_waitcnt lgkmcnt(0)
	v_mul_f32_e32 v248, v248, v252
	v_mul_f32_e32 v249, v249, v253
	v_mul_f32_e32 v250, v250, v254
	v_mul_f32_e32 v251, v251, v255
	global_store_dwordx4 v[80:81], v[248:251], off offset:3072 nt
	s_add_i32 s2, s2, s33
	s_add_i32 s40, s40, s63
	s_add_i32 s73, s73, s74
	s_cmpk_lt_i32 s2, 0x100
	s_cbranch_scc1 .LBB0_648

; __global__ void __launch_bounds__(NTHR, 2) k_main(Args a) {
	.amdhsa_kernel _ZN12_GLOBAL__N_16k_mainENS_4ArgsE
		.amdhsa_group_segment_fixed_size 0
		.amdhsa_private_segment_fixed_size 0
		.amdhsa_kernarg_size 424
		.amdhsa_user_sgpr_count 2
		.amdhsa_user_sgpr_dispatch_ptr 0
		.amdhsa_user_sgpr_queue_ptr 0
		.amdhsa_user_sgpr_kernarg_segment_ptr 1
		.amdhsa_user_sgpr_dispatch_id 0
		.amdhsa_user_sgpr_kernarg_preload_length 0
		.amdhsa_user_sgpr_kernarg_preload_offset 0
		.amdhsa_user_sgpr_private_segment_size 0
		.amdhsa_uses_dynamic_stack 0
		.amdhsa_enable_private_segment 0
		.amdhsa_system_sgpr_workgroup_id_x 1
		.amdhsa_system_sgpr_workgroup_id_y 0
		.amdhsa_system_sgpr_workgroup_id_z 0
		.amdhsa_system_sgpr_workgroup_info 0
		.amdhsa_system_vgpr_workitem_id 0
		.amdhsa_next_free_vgpr 256
		.amdhsa_next_free_sgpr 102
		.amdhsa_accum_offset 256
		.amdhsa_reserve_vcc 1
		.amdhsa_float_round_mode_32 0
		.amdhsa_float_round_mode_16_64 0
		.amdhsa_float_denorm_mode_32 3
		.amdhsa_float_denorm_mode_16_64 3
		.amdhsa_dx10_clamp 1
		.amdhsa_ieee_mode 1
		.amdhsa_fp16_overflow 0
		.amdhsa_tg_split 0
		.amdhsa_exception_fp_ieee_invalid_op 0
		.amdhsa_exception_fp_denorm_src 0
		.amdhsa_exception_fp_ieee_div_zero 0
		.amdhsa_exception_fp_ieee_overflow 0
		.amdhsa_exception_fp_ieee_underflow 0
		.amdhsa_exception_fp_ieee_inexact 0
		.amdhsa_exception_int_div_zero 0
	.end_amdhsa_kernel

; __global__ void __launch_bounds__(NTHR, 2) k_main(Args a) {
amdhsa.kernels:
  - .agpr_count:     0
    .args:
      - .offset:         0
        .size:           168
        .value_kind:     by_value
      - .offset:         168
        .size:           4
        .value_kind:     hidden_block_count_x
      - .offset:         172
        .size:           4
        .value_kind:     hidden_block_count_y
      - .offset:         176
        .size:           4
        .value_kind:     hidden_block_count_z
      - .offset:         180
        .size:           2
        .value_kind:     hidden_group_size_x
      - .offset:         182
        .size:           2
        .value_kind:     hidden_group_size_y
      - .offset:         184
        .size:           2
        .value_kind:     hidden_group_size_z
      - .offset:         186
        .size:           2
        .value_kind:     hidden_remainder_x
      - .offset:         188
        .size:           2
        .value_kind:     hidden_remainder_y
      - .offset:         190
        .size:           2
        .value_kind:     hidden_remainder_z
      - .offset:         208
        .size:           8
        .value_kind:     hidden_global_offset_x
      - .offset:         216
        .size:           8
        .value_kind:     hidden_global_offset_y
      - .offset:         224
        .size:           8
        .value_kind:     hidden_global_offset_z
      - .offset:         232
        .size:           2
        .value_kind:     hidden_grid_dims
      - .offset:         288
        .size:           4
        .value_kind:     hidden_dynamic_lds_size
    .group_segment_fixed_size: 0
    .kernarg_segment_align: 8
    .kernarg_segment_size: 424
    .language:       OpenCL C
    .language_version:
      - 2
      - 0
    .max_flat_workgroup_size: 512
    .name:           _ZN12_GLOBAL__N_16k_mainENS_4ArgsE
    .private_segment_fixed_size: 0
    .sgpr_count:     108
    .sgpr_spill_count: 93
    .symbol:         _ZN12_GLOBAL__N_16k_mainENS_4ArgsE.kd
    .uniform_work_group_size: 1
    .uses_dynamic_stack: false
    .vgpr_count:     256
    .vgpr_spill_count: 0
    .wavefront_size: 64
